# epilogues: every blocked-image load/store address rewritten to base+immediate (integer address chains removed by DCE), dead m0 save/restore removed; numerics unchanged
# speedup vs baseline: 1.0133x; 1.0133x over previous
.LBB0_254:
	s_xor_b64 s[38:39], s[26:27], -1
	s_add_u32 s93, s6, 0x20000
	s_addc_u32 s94, s7, 0
	s_ashr_i32 s31, s30, 31
	s_lshl_b64 s[46:47], s[30:31], 19
	s_add_u32 s46, s34, s46
	s_addc_u32 s47, s35, s47
	s_and_b64 s[48:49], s[26:27], exec
	s_cselect_b32 s31, s47, s13
	s_cselect_b32 s95, s46, s12
	s_ashr_i32 s29, s28, 31
	s_lshl_b64 s[48:49], s[28:29], 19
	ds_read_b128 v[2:5], v137
	ds_read_b128 v[6:9], v137 offset:1024
	ds_read_b128 v[10:13], v137 offset:2048
	ds_read_b128 v[14:17], v137 offset:3072
	ds_read_b128 v[18:21], v138
	ds_read_b128 v[22:25], v138 offset:1024
	ds_read_b128 v[26:29], v138 offset:2048
	ds_read_b128 v[30:33], v138 offset:3072
	s_add_u32 s48, s33, s48
	s_addc_u32 s49, s64, s49
	s_and_b64 s[50:51], s[26:27], exec
	s_cselect_b32 s29, s49, s7
	s_cselect_b32 s96, s48, s6
	s_add_u32 s54, s12, 0x10000
	s_addc_u32 s55, s13, 0
	s_add_u32 s0, s6, 0x10000
	s_addc_u32 s1, s7, 0
	s_add_u32 s50, s12, 0x18000
	s_addc_u32 s51, s13, 0
	s_add_u32 s52, s6, 0x18000
	s_addc_u32 s53, s7, 0
	ds_read_b128 v[34:37], v139
	ds_read_b128 v[38:41], v139 offset:1024
	ds_read_b128 v[42:45], v139 offset:2048
	ds_read_b128 v[46:49], v139 offset:3072
	ds_read_b128 v[50:53], v139 offset:4096
	ds_read_b128 v[54:57], v139 offset:5120
	ds_read_b128 v[58:61], v139 offset:6144
	ds_read_b128 v[62:65], v139 offset:7168
	s_add_u32 s88, s12, 0xc000
	s_addc_u32 s89, s13, 0
	s_mov_b32 m0, s78
	s_nop 0
	global_load_lds_dwordx4 v134, s[88:89]
	s_add_u32 m0, s78, 0x2000
	s_nop 0
	global_load_lds_dwordx4 v135, s[88:89]
	s_waitcnt vmcnt(8)
	s_waitcnt lgkmcnt(0)
	s_barrier
	s_setprio 1
	s_waitcnt lgkmcnt(1)
	v_mfma_f32_16x16x32_bf16 v[90:93], v[2:5], v[58:61], 0
	v_mfma_f32_16x16x32_bf16 v[66:69], v[2:5], v[34:37], 0
	v_mfma_f32_16x16x32_bf16 v[70:73], v[10:13], v[34:37], 0
	v_mfma_f32_16x16x32_bf16 v[74:77], v[2:5], v[42:45], 0
	v_mfma_f32_16x16x32_bf16 v[78:81], v[10:13], v[42:45], 0
	v_mfma_f32_16x16x32_bf16 v[82:85], v[2:5], v[50:53], 0
	v_mfma_f32_16x16x32_bf16 v[86:89], v[10:13], v[50:53], 0
	s_waitcnt lgkmcnt(0)
	v_mfma_f32_16x16x32_bf16 v[94:97], v[6:9], v[62:65], v[90:93]
	v_mfma_f32_16x16x32_bf16 v[90:93], v[10:13], v[58:61], 0
	v_mfma_f32_16x16x32_bf16 v[66:69], v[6:9], v[38:41], v[66:69]
	v_mfma_f32_16x16x32_bf16 v[70:73], v[14:17], v[38:41], v[70:73]
	v_mfma_f32_16x16x32_bf16 v[74:77], v[6:9], v[46:49], v[74:77]
	v_mfma_f32_16x16x32_bf16 v[78:81], v[14:17], v[46:49], v[78:81]
	v_mfma_f32_16x16x32_bf16 v[82:85], v[6:9], v[54:57], v[82:85]
	v_mfma_f32_16x16x32_bf16 v[86:89], v[14:17], v[54:57], v[86:89]
	v_mfma_f32_16x16x32_bf16 v[102:105], v[14:17], v[62:65], v[90:93]
	s_setprio 0
	s_setprio 1
	v_mfma_f32_16x16x32_bf16 v[90:93], v[18:21], v[34:37], 0
	v_mfma_f32_16x16x32_bf16 v[34:37], v[26:29], v[34:37], 0
	v_mfma_f32_16x16x32_bf16 v[110:113], v[22:25], v[38:41], v[90:93]
	v_mfma_f32_16x16x32_bf16 v[34:37], v[30:33], v[38:41], v[34:37]
	v_mfma_f32_16x16x32_bf16 v[38:41], v[18:21], v[42:45], 0
	v_mfma_f32_16x16x32_bf16 v[42:45], v[26:29], v[42:45], 0
	v_mfma_f32_16x16x32_bf16 v[38:41], v[22:25], v[46:49], v[38:41]
	v_mfma_f32_16x16x32_bf16 v[42:45], v[30:33], v[46:49], v[42:45]
	v_mfma_f32_16x16x32_bf16 v[46:49], v[18:21], v[50:53], 0
	v_mfma_f32_16x16x32_bf16 v[50:53], v[26:29], v[50:53], 0
	v_mfma_f32_16x16x32_bf16 v[46:49], v[22:25], v[54:57], v[46:49]
	v_mfma_f32_16x16x32_bf16 v[50:53], v[30:33], v[54:57], v[50:53]
	v_mfma_f32_16x16x32_bf16 v[54:57], v[18:21], v[58:61], 0
	v_mfma_f32_16x16x32_bf16 v[58:61], v[26:29], v[58:61], 0
	v_mfma_f32_16x16x32_bf16 v[54:57], v[22:25], v[62:65], v[54:57]
	v_mfma_f32_16x16x32_bf16 v[58:61], v[30:33], v[62:65], v[58:61]
	s_setprio 0
	s_barrier
	ds_read_b128 v[62:65], v139 offset:16384
	ds_read_b128 v[90:93], v139 offset:17408
	ds_read_b128 v[98:101], v139 offset:18432
	ds_read_b128 v[106:109], v139 offset:19456
	ds_read_b128 v[114:117], v139 offset:20480
	ds_read_b128 v[118:121], v139 offset:21504
	ds_read_b128 v[122:125], v139 offset:22528
	ds_read_b128 v[126:129], v139 offset:23552
	s_mov_b32 m0, s11
	s_nop 0
	global_load_lds_dwordx4 v134, s[0:1]
	s_add_u32 m0, s11, 0x2000
	s_nop 0
	global_load_lds_dwordx4 v135, s[0:1]
	s_add_u32 s0, s6, 0x14000
	s_addc_u32 s1, s7, 0
	s_mov_b32 m0, s68
	s_nop 0
	global_load_lds_dwordx4 v134, s[0:1]
	s_add_u32 m0, s68, 0x2000
	s_nop 0
	global_load_lds_dwordx4 v135, s[0:1]
	s_nop 0
	s_mov_b32 m0, s65
	s_nop 0
	global_load_lds_dwordx4 v134, s[54:55]
	s_add_u32 m0, s65, 0x2000
	s_nop 0
	global_load_lds_dwordx4 v135, s[54:55]
	s_waitcnt vmcnt(8)
	s_waitcnt lgkmcnt(0)
	s_barrier
	s_setprio 1
	s_waitcnt lgkmcnt(7)
	v_mfma_f32_16x16x32_bf16 v[146:149], v[2:5], v[62:65], 0
	s_waitcnt lgkmcnt(5)
	v_mfma_f32_16x16x32_bf16 v[154:157], v[2:5], v[98:101], 0
	s_waitcnt lgkmcnt(3)
	v_mfma_f32_16x16x32_bf16 v[162:165], v[2:5], v[114:117], 0
	s_waitcnt lgkmcnt(1)
	v_mfma_f32_16x16x32_bf16 v[2:5], v[2:5], v[122:125], 0
	v_mfma_f32_16x16x32_bf16 v[146:149], v[6:9], v[90:93], v[146:149]
	v_mfma_f32_16x16x32_bf16 v[154:157], v[6:9], v[106:109], v[154:157]
	v_mfma_f32_16x16x32_bf16 v[162:165], v[6:9], v[118:121], v[162:165]
	s_waitcnt lgkmcnt(0)
	v_mfma_f32_16x16x32_bf16 v[2:5], v[6:9], v[126:129], v[2:5]
	v_mfma_f32_16x16x32_bf16 v[6:9], v[10:13], v[122:125], 0
	v_mfma_f32_16x16x32_bf16 v[150:153], v[10:13], v[62:65], 0
	v_mfma_f32_16x16x32_bf16 v[158:161], v[10:13], v[98:101], 0
	v_mfma_f32_16x16x32_bf16 v[166:169], v[10:13], v[114:117], 0
	v_mfma_f32_16x16x32_bf16 v[6:9], v[14:17], v[126:129], v[6:9]
	v_mfma_f32_16x16x32_bf16 v[150:153], v[14:17], v[90:93], v[150:153]
	v_mfma_f32_16x16x32_bf16 v[158:161], v[14:17], v[106:109], v[158:161]
	v_mfma_f32_16x16x32_bf16 v[166:169], v[14:17], v[118:121], v[166:169]
	s_setprio 0
	s_setprio 1
	v_mfma_f32_16x16x32_bf16 v[10:13], v[18:21], v[62:65], 0
	v_mfma_f32_16x16x32_bf16 v[14:17], v[22:25], v[90:93], v[10:13]
	v_mfma_f32_16x16x32_bf16 v[10:13], v[26:29], v[62:65], 0
	v_mfma_f32_16x16x32_bf16 v[170:173], v[30:33], v[90:93], v[10:13]
	v_mfma_f32_16x16x32_bf16 v[10:13], v[18:21], v[98:101], 0
	v_mfma_f32_16x16x32_bf16 v[174:177], v[22:25], v[106:109], v[10:13]
	v_mfma_f32_16x16x32_bf16 v[10:13], v[26:29], v[98:101], 0
	v_mfma_f32_16x16x32_bf16 v[178:181], v[30:33], v[106:109], v[10:13]
	v_mfma_f32_16x16x32_bf16 v[10:13], v[18:21], v[114:117], 0
	v_mfma_f32_16x16x32_bf16 v[182:185], v[22:25], v[118:121], v[10:13]
	v_mfma_f32_16x16x32_bf16 v[10:13], v[26:29], v[114:117], 0
	v_mfma_f32_16x16x32_bf16 v[186:189], v[30:33], v[118:121], v[10:13]
	v_mfma_f32_16x16x32_bf16 v[10:13], v[18:21], v[122:125], 0
	v_mfma_f32_16x16x32_bf16 v[190:193], v[22:25], v[126:129], v[10:13]
	v_mfma_f32_16x16x32_bf16 v[10:13], v[26:29], v[122:125], 0
	v_mfma_f32_16x16x32_bf16 v[198:201], v[30:33], v[126:129], v[10:13]
	s_setprio 0
	s_barrier
	s_nop 4
	ds_read_b128 v[10:13], v140
	ds_read_b128 v[22:25], v140 offset:1024
	ds_read_b128 v[30:33], v140 offset:2048
	ds_read_b128 v[62:65], v140 offset:3072
	ds_read_b128 v[202:205], v141
	ds_read_b128 v[206:209], v141 offset:1024
	ds_read_b128 v[212:215], v141 offset:2048
	ds_read_b128 v[216:219], v141 offset:3072
	ds_read_b128 v[18:21], v139 offset:32768
	ds_read_b128 v[26:29], v139 offset:33792
	ds_read_b128 v[220:223], v139 offset:34816
	ds_read_b128 v[224:227], v139 offset:35840
	ds_read_b128 v[228:231], v139 offset:36864
	ds_read_b128 v[232:235], v139 offset:37888
	ds_read_b128 v[236:239], v139 offset:38912
	ds_read_b128 v[240:243], v139 offset:39936
	s_add_u32 s0, s12, 0x14000
	s_addc_u32 s1, s13, 0
	s_mov_b32 m0, s69
	s_nop 0
	global_load_lds_dwordx4 v134, s[0:1]
	s_add_u32 m0, s69, 0x2000
	s_nop 0
	global_load_lds_dwordx4 v135, s[0:1]
	s_waitcnt vmcnt(8)
	s_waitcnt lgkmcnt(0)
	s_barrier
	s_setprio 1
	s_waitcnt lgkmcnt(7)
	v_mfma_f32_16x16x32_bf16 v[66:69], v[10:13], v[18:21], v[66:69]
	s_waitcnt lgkmcnt(6)
	v_mfma_f32_16x16x32_bf16 v[122:125], v[22:25], v[26:29], v[66:69]
	v_mfma_f32_16x16x32_bf16 v[66:69], v[30:33], v[18:21], v[70:73]
	v_mfma_f32_16x16x32_bf16 v[114:117], v[62:65], v[26:29], v[66:69]
	s_waitcnt lgkmcnt(5)
	v_mfma_f32_16x16x32_bf16 v[66:69], v[10:13], v[220:223], v[74:77]
	s_waitcnt lgkmcnt(4)
	v_mfma_f32_16x16x32_bf16 v[106:109], v[22:25], v[224:227], v[66:69]
	v_mfma_f32_16x16x32_bf16 v[66:69], v[30:33], v[220:223], v[78:81]
	v_mfma_f32_16x16x32_bf16 v[98:101], v[62:65], v[224:227], v[66:69]
	s_waitcnt lgkmcnt(3)
	v_mfma_f32_16x16x32_bf16 v[66:69], v[10:13], v[228:231], v[82:85]
	s_waitcnt lgkmcnt(2)
	v_mfma_f32_16x16x32_bf16 v[90:93], v[22:25], v[232:235], v[66:69]
	v_mfma_f32_16x16x32_bf16 v[66:69], v[30:33], v[228:231], v[86:89]
	v_mfma_f32_16x16x32_bf16 v[82:85], v[62:65], v[232:235], v[66:69]
	s_waitcnt lgkmcnt(1)
	v_mfma_f32_16x16x32_bf16 v[66:69], v[10:13], v[236:239], v[94:97]
	s_waitcnt lgkmcnt(0)
	v_mfma_f32_16x16x32_bf16 v[74:77], v[22:25], v[240:243], v[66:69]
	v_mfma_f32_16x16x32_bf16 v[66:69], v[30:33], v[236:239], v[102:105]
	v_mfma_f32_16x16x32_bf16 v[66:69], v[62:65], v[240:243], v[66:69]
	s_setprio 0
	s_setprio 1
	v_mfma_f32_16x16x32_bf16 v[70:73], v[202:205], v[18:21], v[110:113]
	v_mfma_f32_16x16x32_bf16 v[18:21], v[212:215], v[18:21], v[34:37]
	v_mfma_f32_16x16x32_bf16 v[118:121], v[216:219], v[26:29], v[18:21]
	v_mfma_f32_16x16x32_bf16 v[18:21], v[202:205], v[220:223], v[38:41]
	v_mfma_f32_16x16x32_bf16 v[110:113], v[206:209], v[224:227], v[18:21]
	v_mfma_f32_16x16x32_bf16 v[18:21], v[212:215], v[220:223], v[42:45]
	v_mfma_f32_16x16x32_bf16 v[102:105], v[216:219], v[224:227], v[18:21]
	v_mfma_f32_16x16x32_bf16 v[18:21], v[202:205], v[228:231], v[46:49]
	v_mfma_f32_16x16x32_bf16 v[94:97], v[206:209], v[232:235], v[18:21]
	v_mfma_f32_16x16x32_bf16 v[18:21], v[212:215], v[228:231], v[50:53]
	v_mfma_f32_16x16x32_bf16 v[86:89], v[216:219], v[232:235], v[18:21]
	v_mfma_f32_16x16x32_bf16 v[18:21], v[202:205], v[236:239], v[54:57]
	v_mfma_f32_16x16x32_bf16 v[78:81], v[206:209], v[240:243], v[18:21]
	v_mfma_f32_16x16x32_bf16 v[18:21], v[212:215], v[236:239], v[58:61]
	v_mfma_f32_16x16x32_bf16 v[126:129], v[206:209], v[26:29], v[70:73]
	v_mfma_f32_16x16x32_bf16 v[70:73], v[216:219], v[240:243], v[18:21]
	s_setprio 0
	s_barrier
	ds_read_b128 v[38:41], v139 offset:49152
	ds_read_b128 v[46:49], v139 offset:50176
	ds_read_b128 v[220:223], v139 offset:51200
	ds_read_b128 v[224:227], v139 offset:52224
	ds_read_b128 v[228:231], v139 offset:53248
	ds_read_b128 v[232:235], v139 offset:54272
	ds_read_b128 v[236:239], v139 offset:55296
	ds_read_b128 v[240:243], v139 offset:56320
	s_mov_b32 m0, s74
	s_nop 0
	global_load_lds_dwordx4 v134, s[52:53]
	s_add_u32 m0, s74, 0x2000
	s_nop 0
	global_load_lds_dwordx4 v135, s[52:53]
	s_add_u32 s0, s6, 0x1c000
	s_addc_u32 s1, s7, 0
	s_mov_b32 m0, s77
	s_nop 0
	global_load_lds_dwordx4 v134, s[0:1]
	s_add_u32 m0, s77, 0x2000
	s_nop 0
	global_load_lds_dwordx4 v135, s[0:1]
	s_nop 0
	s_mov_b32 m0, s76
	s_nop 0
	global_load_lds_dwordx4 v134, s[50:51]
	s_add_u32 m0, s76, 0x2000
	s_nop 0
	global_load_lds_dwordx4 v135, s[50:51]
	s_waitcnt vmcnt(8)
	s_waitcnt lgkmcnt(0)
	s_barrier
	s_setprio 1
	s_waitcnt lgkmcnt(7)
	v_mfma_f32_16x16x32_bf16 v[18:21], v[10:13], v[38:41], v[146:149]
	s_waitcnt lgkmcnt(6)
	v_mfma_f32_16x16x32_bf16 v[58:61], v[22:25], v[46:49], v[18:21]
	v_mfma_f32_16x16x32_bf16 v[18:21], v[30:33], v[38:41], v[150:153]
	v_mfma_f32_16x16x32_bf16 v[50:53], v[62:65], v[46:49], v[18:21]
	s_waitcnt lgkmcnt(5)
	v_mfma_f32_16x16x32_bf16 v[18:21], v[10:13], v[220:223], v[154:157]
	s_waitcnt lgkmcnt(4)
	v_mfma_f32_16x16x32_bf16 v[42:45], v[22:25], v[224:227], v[18:21]
	v_mfma_f32_16x16x32_bf16 v[18:21], v[30:33], v[220:223], v[158:161]
	v_mfma_f32_16x16x32_bf16 v[34:37], v[62:65], v[224:227], v[18:21]
	s_waitcnt lgkmcnt(3)
	v_mfma_f32_16x16x32_bf16 v[18:21], v[10:13], v[228:231], v[162:165]
	s_waitcnt lgkmcnt(1)
	v_mfma_f32_16x16x32_bf16 v[2:5], v[10:13], v[236:239], v[2:5]
	v_mfma_f32_16x16x32_bf16 v[26:29], v[22:25], v[232:235], v[18:21]
	v_mfma_f32_16x16x32_bf16 v[18:21], v[30:33], v[228:231], v[166:169]
	s_waitcnt lgkmcnt(0)
	v_mfma_f32_16x16x32_bf16 v[10:13], v[22:25], v[240:243], v[2:5]
	v_mfma_f32_16x16x32_bf16 v[2:5], v[30:33], v[236:239], v[6:9]
	v_mfma_f32_16x16x32_bf16 v[18:21], v[62:65], v[232:235], v[18:21]
	v_mfma_f32_16x16x32_bf16 v[2:5], v[62:65], v[240:243], v[2:5]
	s_setprio 0
	s_setprio 1
	v_mfma_f32_16x16x32_bf16 v[6:9], v[202:205], v[38:41], v[14:17]
	v_mfma_f32_16x16x32_bf16 v[62:65], v[206:209], v[46:49], v[6:9]
	v_mfma_f32_16x16x32_bf16 v[6:9], v[212:215], v[38:41], v[170:173]
	v_mfma_f32_16x16x32_bf16 v[54:57], v[216:219], v[46:49], v[6:9]
	v_mfma_f32_16x16x32_bf16 v[6:9], v[202:205], v[220:223], v[174:177]
	v_mfma_f32_16x16x32_bf16 v[46:49], v[206:209], v[224:227], v[6:9]
	v_mfma_f32_16x16x32_bf16 v[6:9], v[212:215], v[220:223], v[178:181]
	v_mfma_f32_16x16x32_bf16 v[38:41], v[216:219], v[224:227], v[6:9]
	v_mfma_f32_16x16x32_bf16 v[6:9], v[202:205], v[228:231], v[182:185]
	v_mfma_f32_16x16x32_bf16 v[30:33], v[206:209], v[232:235], v[6:9]
	v_mfma_f32_16x16x32_bf16 v[6:9], v[212:215], v[228:231], v[186:189]
	v_mfma_f32_16x16x32_bf16 v[22:25], v[216:219], v[232:235], v[6:9]
	v_mfma_f32_16x16x32_bf16 v[6:9], v[202:205], v[236:239], v[190:193]
	v_mfma_f32_16x16x32_bf16 v[14:17], v[206:209], v[240:243], v[6:9]
	v_mfma_f32_16x16x32_bf16 v[6:9], v[212:215], v[236:239], v[198:201]
	v_mfma_f32_16x16x32_bf16 v[6:9], v[216:219], v[240:243], v[6:9]
	s_setprio 0
	s_barrier
	s_mov_b32 s97, 0
	s_mov_b64 s[6:7], 0
	v_mov_b32_e32 v145, s62

.LBB0_257:
	s_or_b64 exec, exec, s[50:51]
	s_add_u32 s0, s12, s6
	ds_read_b128 v[146:149], v137
	ds_read_b128 v[150:153], v137 offset:1024
	ds_read_b128 v[154:157], v137 offset:2048
	ds_read_b128 v[158:161], v137 offset:3072
	ds_read_b128 v[162:165], v138
	ds_read_b128 v[166:169], v138 offset:1024
	ds_read_b128 v[170:173], v138 offset:2048
	ds_read_b128 v[174:177], v138 offset:3072
	s_addc_u32 s1, s13, s7
	s_add_u32 s50, s0, 0x20000
	s_addc_u32 s51, s1, 0
	s_add_u32 s52, s93, s6
	s_addc_u32 s53, s94, s7
	s_cmp_eq_u32 s6, 0x60000
	s_cselect_b32 s62, s95, s50
	s_cselect_b32 s63, s31, s51
	s_cselect_b32 s51, s29, s53
	s_cselect_b32 s50, s96, s52
	s_add_u32 s52, s62, 0x8000
	s_addc_u32 s53, s63, 0
	s_add_u32 s54, s50, 0x8000
	s_addc_u32 s55, s51, 0
	ds_read_b128 v[178:181], v139
	ds_read_b128 v[182:185], v139 offset:1024
	ds_read_b128 v[186:189], v139 offset:2048
	ds_read_b128 v[190:193], v139 offset:3072
	ds_read_b128 v[198:201], v139 offset:4096
	ds_read_b128 v[202:205], v139 offset:5120
	ds_read_b128 v[206:209], v139 offset:6144
	ds_read_b128 v[212:215], v139 offset:7168
	s_add_u32 s0, s0, 0x1c000
	s_addc_u32 s1, s1, 0
	s_mov_b32 m0, s78
	s_nop 0
	global_load_lds_dwordx4 v134, s[0:1]
	s_add_u32 m0, s78, 0x2000
	s_nop 0
	global_load_lds_dwordx4 v135, s[0:1]
	s_waitcnt vmcnt(8)
	s_waitcnt lgkmcnt(0)
	s_barrier
	s_setprio 1
	s_waitcnt lgkmcnt(7)
	v_mfma_f32_16x16x32_bf16 v[122:125], v[146:149], v[178:181], v[122:125]
	v_mfma_f32_16x16x32_bf16 v[114:117], v[154:157], v[178:181], v[114:117]
	s_waitcnt lgkmcnt(5)
	v_mfma_f32_16x16x32_bf16 v[106:109], v[146:149], v[186:189], v[106:109]
	v_mfma_f32_16x16x32_bf16 v[98:101], v[154:157], v[186:189], v[98:101]
	s_waitcnt lgkmcnt(3)
	v_mfma_f32_16x16x32_bf16 v[90:93], v[146:149], v[198:201], v[90:93]
	v_mfma_f32_16x16x32_bf16 v[82:85], v[154:157], v[198:201], v[82:85]
	s_waitcnt lgkmcnt(1)
	v_mfma_f32_16x16x32_bf16 v[74:77], v[146:149], v[206:209], v[74:77]
	v_mfma_f32_16x16x32_bf16 v[66:69], v[154:157], v[206:209], v[66:69]
	v_mfma_f32_16x16x32_bf16 v[122:125], v[150:153], v[182:185], v[122:125]
	v_mfma_f32_16x16x32_bf16 v[114:117], v[158:161], v[182:185], v[114:117]
	v_mfma_f32_16x16x32_bf16 v[106:109], v[150:153], v[190:193], v[106:109]
	v_mfma_f32_16x16x32_bf16 v[98:101], v[158:161], v[190:193], v[98:101]
	v_mfma_f32_16x16x32_bf16 v[90:93], v[150:153], v[202:205], v[90:93]
	v_mfma_f32_16x16x32_bf16 v[82:85], v[158:161], v[202:205], v[82:85]
	s_waitcnt lgkmcnt(0)
	v_mfma_f32_16x16x32_bf16 v[74:77], v[150:153], v[212:215], v[74:77]
	v_mfma_f32_16x16x32_bf16 v[66:69], v[158:161], v[212:215], v[66:69]
	s_setprio 0
	s_setprio 1
	v_mfma_f32_16x16x32_bf16 v[126:129], v[162:165], v[178:181], v[126:129]
	v_mfma_f32_16x16x32_bf16 v[118:121], v[170:173], v[178:181], v[118:121]
	v_mfma_f32_16x16x32_bf16 v[110:113], v[162:165], v[186:189], v[110:113]
	v_mfma_f32_16x16x32_bf16 v[102:105], v[170:173], v[186:189], v[102:105]
	v_mfma_f32_16x16x32_bf16 v[94:97], v[162:165], v[198:201], v[94:97]
	v_mfma_f32_16x16x32_bf16 v[86:89], v[170:173], v[198:201], v[86:89]
	v_mfma_f32_16x16x32_bf16 v[78:81], v[162:165], v[206:209], v[78:81]
	v_mfma_f32_16x16x32_bf16 v[70:73], v[170:173], v[206:209], v[70:73]
	v_mfma_f32_16x16x32_bf16 v[126:129], v[166:169], v[182:185], v[126:129]
	v_mfma_f32_16x16x32_bf16 v[118:121], v[174:177], v[182:185], v[118:121]
	v_mfma_f32_16x16x32_bf16 v[110:113], v[166:169], v[190:193], v[110:113]
	v_mfma_f32_16x16x32_bf16 v[102:105], v[174:177], v[190:193], v[102:105]
	v_mfma_f32_16x16x32_bf16 v[94:97], v[166:169], v[202:205], v[94:97]
	v_mfma_f32_16x16x32_bf16 v[86:89], v[174:177], v[202:205], v[86:89]
	v_mfma_f32_16x16x32_bf16 v[78:81], v[166:169], v[212:215], v[78:81]
	v_mfma_f32_16x16x32_bf16 v[70:73], v[174:177], v[212:215], v[70:73]
	s_setprio 0
	s_barrier
	ds_read_b128 v[178:181], v139 offset:16384
	ds_read_b128 v[182:185], v139 offset:17408
	ds_read_b128 v[186:189], v139 offset:18432
	ds_read_b128 v[190:193], v139 offset:19456
	ds_read_b128 v[198:201], v139 offset:20480
	ds_read_b128 v[202:205], v139 offset:21504
	ds_read_b128 v[206:209], v139 offset:22528
	ds_read_b128 v[212:215], v139 offset:23552
	s_mov_b32 m0, s11
	s_nop 0
	global_load_lds_dwordx4 v134, s[50:51]
	s_add_u32 m0, s11, 0x2000
	s_nop 0
	global_load_lds_dwordx4 v135, s[50:51]
	s_add_u32 s0, s50, 0x4000
	s_addc_u32 s1, s51, 0
	s_mov_b32 m0, s68
	s_nop 0
	global_load_lds_dwordx4 v134, s[0:1]
	s_add_u32 m0, s68, 0x2000
	s_nop 0
	global_load_lds_dwordx4 v135, s[0:1]
	s_nop 0
	s_mov_b32 m0, s65
	s_nop 0
	global_load_lds_dwordx4 v134, s[62:63]
	s_add_u32 m0, s65, 0x2000
	s_nop 0
	global_load_lds_dwordx4 v135, s[62:63]
	s_waitcnt vmcnt(8)
	s_waitcnt lgkmcnt(0)
	s_barrier
	s_setprio 1
	s_waitcnt lgkmcnt(7)
	v_mfma_f32_16x16x32_bf16 v[58:61], v[146:149], v[178:181], v[58:61]
	v_mfma_f32_16x16x32_bf16 v[50:53], v[154:157], v[178:181], v[50:53]
	s_waitcnt lgkmcnt(5)
	v_mfma_f32_16x16x32_bf16 v[42:45], v[146:149], v[186:189], v[42:45]
	v_mfma_f32_16x16x32_bf16 v[34:37], v[154:157], v[186:189], v[34:37]
	s_waitcnt lgkmcnt(3)
	v_mfma_f32_16x16x32_bf16 v[26:29], v[146:149], v[198:201], v[26:29]
	v_mfma_f32_16x16x32_bf16 v[18:21], v[154:157], v[198:201], v[18:21]
	s_waitcnt lgkmcnt(1)
	v_mfma_f32_16x16x32_bf16 v[10:13], v[146:149], v[206:209], v[10:13]
	v_mfma_f32_16x16x32_bf16 v[2:5], v[154:157], v[206:209], v[2:5]
	v_mfma_f32_16x16x32_bf16 v[58:61], v[150:153], v[182:185], v[58:61]
	v_mfma_f32_16x16x32_bf16 v[50:53], v[158:161], v[182:185], v[50:53]
	v_mfma_f32_16x16x32_bf16 v[42:45], v[150:153], v[190:193], v[42:45]
	v_mfma_f32_16x16x32_bf16 v[34:37], v[158:161], v[190:193], v[34:37]
	v_mfma_f32_16x16x32_bf16 v[26:29], v[150:153], v[202:205], v[26:29]
	v_mfma_f32_16x16x32_bf16 v[18:21], v[158:161], v[202:205], v[18:21]
	s_waitcnt lgkmcnt(0)
	v_mfma_f32_16x16x32_bf16 v[10:13], v[150:153], v[212:215], v[10:13]
	v_mfma_f32_16x16x32_bf16 v[2:5], v[158:161], v[212:215], v[2:5]
	s_setprio 0
	s_setprio 1
	v_mfma_f32_16x16x32_bf16 v[62:65], v[162:165], v[178:181], v[62:65]
	v_mfma_f32_16x16x32_bf16 v[54:57], v[170:173], v[178:181], v[54:57]
	v_mfma_f32_16x16x32_bf16 v[46:49], v[162:165], v[186:189], v[46:49]
	v_mfma_f32_16x16x32_bf16 v[38:41], v[170:173], v[186:189], v[38:41]
	v_mfma_f32_16x16x32_bf16 v[30:33], v[162:165], v[198:201], v[30:33]
	v_mfma_f32_16x16x32_bf16 v[22:25], v[170:173], v[198:201], v[22:25]
	v_mfma_f32_16x16x32_bf16 v[14:17], v[162:165], v[206:209], v[14:17]
	v_mfma_f32_16x16x32_bf16 v[6:9], v[170:173], v[206:209], v[6:9]
	v_mfma_f32_16x16x32_bf16 v[62:65], v[166:169], v[182:185], v[62:65]
	v_mfma_f32_16x16x32_bf16 v[54:57], v[174:177], v[182:185], v[54:57]
	v_mfma_f32_16x16x32_bf16 v[46:49], v[166:169], v[190:193], v[46:49]
	v_mfma_f32_16x16x32_bf16 v[38:41], v[174:177], v[190:193], v[38:41]
	v_mfma_f32_16x16x32_bf16 v[30:33], v[166:169], v[202:205], v[30:33]
	v_mfma_f32_16x16x32_bf16 v[22:25], v[174:177], v[202:205], v[22:25]
	v_mfma_f32_16x16x32_bf16 v[14:17], v[166:169], v[212:215], v[14:17]
	v_mfma_f32_16x16x32_bf16 v[6:9], v[174:177], v[212:215], v[6:9]
	s_setprio 0
	s_barrier
	ds_read_b128 v[146:149], v140
	ds_read_b128 v[150:153], v140 offset:1024
	ds_read_b128 v[154:157], v140 offset:2048
	ds_read_b128 v[158:161], v140 offset:3072
	ds_read_b128 v[162:165], v141
	ds_read_b128 v[166:169], v141 offset:1024
	ds_read_b128 v[170:173], v141 offset:2048
	ds_read_b128 v[174:177], v141 offset:3072
	ds_read_b128 v[178:181], v139 offset:32768
	ds_read_b128 v[182:185], v139 offset:33792
	ds_read_b128 v[186:189], v139 offset:34816
	ds_read_b128 v[190:193], v139 offset:35840
	ds_read_b128 v[198:201], v139 offset:36864
	ds_read_b128 v[202:205], v139 offset:37888
	ds_read_b128 v[206:209], v139 offset:38912
	ds_read_b128 v[212:215], v139 offset:39936
	s_add_u32 s0, s62, 0x4000
	s_addc_u32 s1, s63, 0
	s_mov_b32 m0, s69
	s_nop 0
	global_load_lds_dwordx4 v134, s[0:1]
	s_add_u32 m0, s69, 0x2000
	s_nop 0
	global_load_lds_dwordx4 v135, s[0:1]
	s_waitcnt vmcnt(8)
	s_waitcnt lgkmcnt(0)
	s_barrier
	s_setprio 1
	s_waitcnt lgkmcnt(7)
	v_mfma_f32_16x16x32_bf16 v[122:125], v[146:149], v[178:181], v[122:125]
	v_mfma_f32_16x16x32_bf16 v[114:117], v[154:157], v[178:181], v[114:117]
	s_waitcnt lgkmcnt(5)
	v_mfma_f32_16x16x32_bf16 v[106:109], v[146:149], v[186:189], v[106:109]
	v_mfma_f32_16x16x32_bf16 v[98:101], v[154:157], v[186:189], v[98:101]
	s_waitcnt lgkmcnt(3)
	v_mfma_f32_16x16x32_bf16 v[90:93], v[146:149], v[198:201], v[90:93]
	v_mfma_f32_16x16x32_bf16 v[82:85], v[154:157], v[198:201], v[82:85]
	s_waitcnt lgkmcnt(1)
	v_mfma_f32_16x16x32_bf16 v[74:77], v[146:149], v[206:209], v[74:77]
	v_mfma_f32_16x16x32_bf16 v[66:69], v[154:157], v[206:209], v[66:69]
	v_mfma_f32_16x16x32_bf16 v[122:125], v[150:153], v[182:185], v[122:125]
	v_mfma_f32_16x16x32_bf16 v[114:117], v[158:161], v[182:185], v[114:117]
	v_mfma_f32_16x16x32_bf16 v[106:109], v[150:153], v[190:193], v[106:109]
	v_mfma_f32_16x16x32_bf16 v[98:101], v[158:161], v[190:193], v[98:101]
	v_mfma_f32_16x16x32_bf16 v[90:93], v[150:153], v[202:205], v[90:93]
	v_mfma_f32_16x16x32_bf16 v[82:85], v[158:161], v[202:205], v[82:85]
	s_waitcnt lgkmcnt(0)
	v_mfma_f32_16x16x32_bf16 v[74:77], v[150:153], v[212:215], v[74:77]
	v_mfma_f32_16x16x32_bf16 v[66:69], v[158:161], v[212:215], v[66:69]
	s_setprio 0
	s_setprio 1
	v_mfma_f32_16x16x32_bf16 v[126:129], v[162:165], v[178:181], v[126:129]
	v_mfma_f32_16x16x32_bf16 v[118:121], v[170:173], v[178:181], v[118:121]
	v_mfma_f32_16x16x32_bf16 v[110:113], v[162:165], v[186:189], v[110:113]
	v_mfma_f32_16x16x32_bf16 v[102:105], v[170:173], v[186:189], v[102:105]
	v_mfma_f32_16x16x32_bf16 v[94:97], v[162:165], v[198:201], v[94:97]
	v_mfma_f32_16x16x32_bf16 v[86:89], v[170:173], v[198:201], v[86:89]
	v_mfma_f32_16x16x32_bf16 v[78:81], v[162:165], v[206:209], v[78:81]
	v_mfma_f32_16x16x32_bf16 v[70:73], v[170:173], v[206:209], v[70:73]
	v_mfma_f32_16x16x32_bf16 v[126:129], v[166:169], v[182:185], v[126:129]
	v_mfma_f32_16x16x32_bf16 v[118:121], v[174:177], v[182:185], v[118:121]
	v_mfma_f32_16x16x32_bf16 v[110:113], v[166:169], v[190:193], v[110:113]
	v_mfma_f32_16x16x32_bf16 v[102:105], v[174:177], v[190:193], v[102:105]
	v_mfma_f32_16x16x32_bf16 v[94:97], v[166:169], v[202:205], v[94:97]
	v_mfma_f32_16x16x32_bf16 v[86:89], v[174:177], v[202:205], v[86:89]
	v_mfma_f32_16x16x32_bf16 v[78:81], v[166:169], v[212:215], v[78:81]
	v_mfma_f32_16x16x32_bf16 v[70:73], v[174:177], v[212:215], v[70:73]
	s_setprio 0
	s_barrier
	ds_read_b128 v[178:181], v139 offset:49152
	ds_read_b128 v[182:185], v139 offset:50176
	ds_read_b128 v[186:189], v139 offset:51200
	ds_read_b128 v[190:193], v139 offset:52224
	ds_read_b128 v[198:201], v139 offset:53248
	ds_read_b128 v[202:205], v139 offset:54272
	ds_read_b128 v[206:209], v139 offset:55296
	ds_read_b128 v[212:215], v139 offset:56320
	s_mov_b32 m0, s74
	s_nop 0
	global_load_lds_dwordx4 v134, s[54:55]
	s_add_u32 m0, s74, 0x2000
	s_nop 0
	global_load_lds_dwordx4 v135, s[54:55]
	s_add_u32 s0, s50, 0xc000
	s_addc_u32 s1, s51, 0
	s_mov_b32 m0, s77
	s_nop 0
	global_load_lds_dwordx4 v134, s[0:1]
	s_add_u32 m0, s77, 0x2000
	s_nop 0
	global_load_lds_dwordx4 v135, s[0:1]
	s_nop 0
	s_mov_b32 m0, s76
	s_nop 0
	global_load_lds_dwordx4 v134, s[52:53]
	s_add_u32 m0, s76, 0x2000
	s_nop 0
	global_load_lds_dwordx4 v135, s[52:53]
	s_waitcnt vmcnt(8)
	s_waitcnt lgkmcnt(0)
	s_barrier
	s_setprio 1
	s_waitcnt lgkmcnt(7)
	v_mfma_f32_16x16x32_bf16 v[58:61], v[146:149], v[178:181], v[58:61]
	v_mfma_f32_16x16x32_bf16 v[50:53], v[154:157], v[178:181], v[50:53]
	s_waitcnt lgkmcnt(5)
	v_mfma_f32_16x16x32_bf16 v[42:45], v[146:149], v[186:189], v[42:45]
	v_mfma_f32_16x16x32_bf16 v[34:37], v[154:157], v[186:189], v[34:37]
	s_waitcnt lgkmcnt(3)
	v_mfma_f32_16x16x32_bf16 v[26:29], v[146:149], v[198:201], v[26:29]
	v_mfma_f32_16x16x32_bf16 v[18:21], v[154:157], v[198:201], v[18:21]
	s_waitcnt lgkmcnt(1)
	v_mfma_f32_16x16x32_bf16 v[10:13], v[146:149], v[206:209], v[10:13]
	v_mfma_f32_16x16x32_bf16 v[2:5], v[154:157], v[206:209], v[2:5]
	v_mfma_f32_16x16x32_bf16 v[58:61], v[150:153], v[182:185], v[58:61]
	v_mfma_f32_16x16x32_bf16 v[50:53], v[158:161], v[182:185], v[50:53]
	v_mfma_f32_16x16x32_bf16 v[42:45], v[150:153], v[190:193], v[42:45]
	v_mfma_f32_16x16x32_bf16 v[34:37], v[158:161], v[190:193], v[34:37]
	v_mfma_f32_16x16x32_bf16 v[26:29], v[150:153], v[202:205], v[26:29]
	v_mfma_f32_16x16x32_bf16 v[18:21], v[158:161], v[202:205], v[18:21]
	s_waitcnt lgkmcnt(0)
	v_mfma_f32_16x16x32_bf16 v[10:13], v[150:153], v[212:215], v[10:13]
	v_mfma_f32_16x16x32_bf16 v[2:5], v[158:161], v[212:215], v[2:5]
	s_setprio 0
	s_setprio 1
	v_mfma_f32_16x16x32_bf16 v[62:65], v[162:165], v[178:181], v[62:65]
	v_mfma_f32_16x16x32_bf16 v[54:57], v[170:173], v[178:181], v[54:57]
	v_mfma_f32_16x16x32_bf16 v[46:49], v[162:165], v[186:189], v[46:49]
	v_mfma_f32_16x16x32_bf16 v[38:41], v[170:173], v[186:189], v[38:41]
	v_mfma_f32_16x16x32_bf16 v[30:33], v[162:165], v[198:201], v[30:33]
	v_mfma_f32_16x16x32_bf16 v[22:25], v[170:173], v[198:201], v[22:25]
	v_mfma_f32_16x16x32_bf16 v[14:17], v[162:165], v[206:209], v[14:17]
	v_mfma_f32_16x16x32_bf16 v[6:9], v[170:173], v[206:209], v[6:9]
	v_mfma_f32_16x16x32_bf16 v[62:65], v[166:169], v[182:185], v[62:65]
	v_mfma_f32_16x16x32_bf16 v[54:57], v[174:177], v[182:185], v[54:57]
	v_mfma_f32_16x16x32_bf16 v[46:49], v[166:169], v[190:193], v[46:49]
	v_mfma_f32_16x16x32_bf16 v[38:41], v[174:177], v[190:193], v[38:41]
	v_mfma_f32_16x16x32_bf16 v[30:33], v[166:169], v[202:205], v[30:33]
	v_mfma_f32_16x16x32_bf16 v[22:25], v[174:177], v[202:205], v[22:25]
	v_mfma_f32_16x16x32_bf16 v[14:17], v[166:169], v[212:215], v[14:17]
	v_mfma_f32_16x16x32_bf16 v[6:9], v[174:177], v[212:215], v[6:9]
	s_setprio 0
	s_barrier
	s_add_i32 s97, s97, 2
	s_add_u32 s6, s6, 0x10000
	s_addc_u32 s7, s7, 0
	s_cmp_gt_u32 s97, 13
	s_cbranch_scc1 .LBB0_259
	v_mov_b32_e32 v145, v130
	s_branch .LBB0_255

.LBB0_261:
	v_mov_b32_e32 v130, v136
	v_mov_b32_e32 v145, v210
	v_readlane_b32 s0, v248, 15
	v_add_u32_e32 v130, s72, v130
	v_lshl_add_u32 v146, s91, 8, v130
	v_lshlrev_b32_e32 v148, 2, v145
	v_ashrrev_i32_e32 v149, 31, v148
	v_readlane_b32 s1, v248, 16
	v_ashrrev_i32_e32 v147, 31, v146
	v_lshlrev_b64 v[146:147], 6, v[146:147]
	v_lshl_add_u64 v[148:149], v[148:149], 2, s[0:1]
	v_lshl_add_u64 v[146:147], v[148:149], 0, v[146:147]
	v_lshl_add_u64 v[184:185], v[146:147], 0, 0
	global_load_dwordx4 v[148:151], v[146:147], off
	s_mov_b32 s98, 0x1000
	s_mov_b32 s99, 0x0
	v_lshl_add_u64 v[186:187], v[184:185], 0, s[98:99]
	global_load_dwordx4 v[152:155], v[186:187], off offset:-3072
	global_load_dwordx4 v[156:159], v[186:187], off offset:-2048
	global_load_dwordx4 v[160:163], v[186:187], off offset:-1024
	s_movk_i32 s0, 0x2000
	v_add_co_u32_e32 v146, vcc, s0, v146
	v_xor_b32_e32 v180, 32, v143
	s_nop 0
	v_addc_co_u32_e32 v147, vcc, 0, v147, vcc
	s_mov_b32 s98, 0x3000
	s_mov_b32 s99, 0x0
	v_lshl_add_u64 v[186:187], v[184:185], 0, s[98:99]
	global_load_dwordx4 v[164:167], v[186:187], off offset:-4096
	global_load_dwordx4 v[168:171], v[186:187], off offset:-3072
	global_load_dwordx4 v[172:175], v[186:187], off offset:-2048
	global_load_dwordx4 v[176:179], v[186:187], off offset:-1024
	v_and_b32_e32 v147, 64, v143
	v_xor_b32_e32 v146, 16, v143
	v_add_u32_e32 v147, 64, v147
	v_cmp_lt_i32_e32 vcc, v146, v147
	s_mul_i32 s0, s91, 44
	s_lshl_b32 s1, s10, 1
	v_cndmask_b32_e32 v146, v143, v146, vcc
	v_cmp_lt_i32_e32 vcc, v180, v147
	v_lshlrev_b32_e32 v182, 2, v146
	s_add_i32 s0, s0, s1
	v_cndmask_b32_e32 v147, v143, v180, vcc
	v_lshl_add_u32 v180, v145, 3, s80
	v_ashrrev_i32_e32 v146, 5, v180
	v_lshlrev_b32_e32 v183, 2, v147
	s_or_b32 s0, s0, s79
	s_ashr_i32 s1, s0, 31
	s_lshl_b64 s[0:1], s[0:1], 15
	v_lshlrev_b32_e32 v145, 4, v145
	s_add_u32 s50, s70, s0
	v_and_b32_e32 v145, 48, v145
	s_addc_u32 s51, s71, s1
	s_cmpk_lt_i32 s91, 0x80
	s_cselect_b64 s[0:1], -1, 0
	s_xor_b64 s[52:53], s[36:37], -1
	s_and_b64 s[52:53], s[52:53], s[0:1]
	s_mov_b64 s[6:7], -1
	s_and_b64 vcc, exec, s[52:53]
	s_waitcnt vmcnt(7)
	v_mov_b32_e32 v180, v149
	v_mov_b32_e32 v181, v150
	v_mov_b32_e32 v149, v151
	s_waitcnt vmcnt(6)
	v_add_f32_e32 v147, v152, v153
	v_add_f32_e32 v150, v154, v155
	s_waitcnt vmcnt(5)
	v_add_f32_e32 v151, v156, v157
	v_add_f32_e32 v152, v158, v159
	s_waitcnt vmcnt(4)
	v_add_f32_e32 v153, v160, v161
	v_add_f32_e32 v154, v162, v163
	v_pk_add_f32 v[148:149], v[180:181], v[148:149]
	v_add_f32_e32 v147, v147, v150
	v_add_f32_e32 v150, v151, v152
	v_add_f32_e32 v151, v153, v154
	s_waitcnt vmcnt(3)
	v_add_f32_e32 v152, v164, v165
	v_add_f32_e32 v153, v166, v167
	v_add_f32_e32 v148, v148, v149
	v_add_f32_e32 v152, v152, v153
	ds_bpermute_b32 v153, v182, v148
	ds_bpermute_b32 v160, v182, v150
	s_waitcnt vmcnt(1)
	v_add_f32_e32 v156, v172, v173
	v_add_f32_e32 v157, v174, v175
	v_add_f32_e32 v162, v156, v157
	s_waitcnt lgkmcnt(1)
	v_add_f32_e32 v148, v148, v153
	s_waitcnt lgkmcnt(0)
	v_add_f32_e32 v157, v150, v160
	ds_bpermute_b32 v150, v183, v148
	ds_bpermute_b32 v149, v182, v147
	ds_bpermute_b32 v166, v182, v162
	v_add_f32_e32 v154, v168, v169
	v_add_f32_e32 v155, v170, v171
	s_waitcnt lgkmcnt(2)
	v_add_f32_e32 v148, v148, v150
	s_waitcnt vmcnt(0)
	v_add_f32_e32 v158, v176, v177
	v_add_f32_e32 v159, v178, v179
	v_add_f32_e32 v154, v154, v155
	v_fmamk_f32 v148, v148, 0x3a800000, v144
	ds_bpermute_b32 v161, v182, v151
	v_add_f32_e32 v163, v158, v159
	ds_bpermute_b32 v164, v182, v152
	ds_bpermute_b32 v165, v182, v154
	s_waitcnt lgkmcnt(4)
	v_add_f32_e32 v159, v147, v149
	s_waitcnt lgkmcnt(3)
	v_add_f32_e32 v149, v162, v166
	v_rsq_f32_e32 v162, v148
	ds_bpermute_b32 v167, v182, v163
	s_waitcnt lgkmcnt(3)
	v_add_f32_e32 v155, v151, v161
	s_waitcnt lgkmcnt(2)
	v_add_f32_e32 v153, v152, v164
	v_pk_mul_f32 v[122:123], v[122:123], v[162:163] op_sel_hi:[1,0]
	s_waitcnt lgkmcnt(1)
	v_add_f32_e32 v151, v154, v165
	v_pk_mul_f32 v[124:125], v[124:125], v[162:163] op_sel_hi:[1,0]
	v_pk_mul_f32 v[164:165], v[122:123], s[24:25] op_sel_hi:[1,0]
	s_waitcnt lgkmcnt(0)
	v_add_f32_e32 v147, v163, v167
	v_pk_mul_f32 v[166:167], v[124:125], s[24:25] op_sel_hi:[1,0]
	v_exp_f32_e32 v164, v164
	v_exp_f32_e32 v165, v165
	v_exp_f32_e32 v166, v166
	v_exp_f32_e32 v167, v167
	v_pk_mul_f32 v[126:127], v[126:127], v[162:163] op_sel_hi:[1,0]
	v_pk_add_f32 v[164:165], v[164:165], 1.0 op_sel_hi:[1,0]
	v_pk_mul_f32 v[114:115], v[114:115], v[162:163] op_sel_hi:[1,0]
	v_pk_add_f32 v[166:167], v[166:167], 1.0 op_sel_hi:[1,0]
	v_rcp_f32_e32 v164, v164
	v_rcp_f32_e32 v165, v165
	v_rcp_f32_e32 v166, v166
	v_rcp_f32_e32 v167, v167
	v_pk_mul_f32 v[128:129], v[128:129], v[162:163] op_sel_hi:[1,0]
	v_pk_mul_f32 v[122:123], v[122:123], v[164:165]
	v_pk_mul_f32 v[116:117], v[116:117], v[162:163] op_sel_hi:[1,0]
	v_pk_mul_f32 v[124:125], v[124:125], v[166:167]
	v_pk_mul_f32 v[122:123], v[126:127], v[122:123]
	v_pk_mul_f32 v[126:127], v[114:115], s[24:25] op_sel_hi:[1,0]
	v_pk_mul_f32 v[124:125], v[128:129], v[124:125]
	v_exp_f32_e32 v126, v126
	v_exp_f32_e32 v127, v127
	v_pk_mul_f32 v[128:129], v[116:117], s[24:25] op_sel_hi:[1,0]
	v_pk_mul_f32 v[118:119], v[118:119], v[162:163] op_sel_hi:[1,0]
	v_exp_f32_e32 v128, v128
	v_exp_f32_e32 v129, v129
	v_pk_add_f32 v[126:127], v[126:127], 1.0 op_sel_hi:[1,0]
	ds_bpermute_b32 v160, v183, v159
	v_rcp_f32_e32 v126, v126
	v_rcp_f32_e32 v127, v127
	v_pk_add_f32 v[128:129], v[128:129], 1.0 op_sel_hi:[1,0]
	ds_bpermute_b32 v158, v183, v157
	v_rcp_f32_e32 v128, v128
	v_rcp_f32_e32 v129, v129
	v_pk_mul_f32 v[114:115], v[114:115], v[126:127]
	ds_bpermute_b32 v156, v183, v155
	v_pk_mul_f32 v[126:127], v[118:119], v[114:115]
	v_pk_mul_f32 v[114:115], v[120:121], v[162:163] op_sel_hi:[1,0]
	v_pk_mul_f32 v[116:117], v[116:117], v[128:129]
	ds_bpermute_b32 v154, v183, v153
	v_pk_mul_f32 v[128:129], v[114:115], v[116:117]
	v_lshrrev_b32_e32 v115, 3, v130
	v_lshlrev_b32_e32 v114, 7, v130
	v_and_b32_e32 v115, 14, v115
	ds_bpermute_b32 v152, v183, v151
	ds_bpermute_b32 v150, v183, v149
	ds_bpermute_b32 v148, v183, v147
	v_and_b32_e32 v114, 0xffffc000, v114
	v_lshlrev_b32_e32 v116, 6, v130
	v_add_lshl_u32 v120, v115, v146, 10
	v_lshlrev_b32_e32 v115, 2, v130
	v_and_or_b32 v116, v116, s73, v145
	v_and_b32_e32 v115, 32, v115
	v_add_u32_e32 v114, v120, v114
	v_bitop3_b32 v114, v114, v116, v115 bitop3:0xf6
	v_ashrrev_i32_e32 v115, 31, v114
	v_lshl_add_u64 v[118:119], s[50:51], 0, v[114:115]
	v_cvt_pk_bf16_f32 v114, v122, v123
	v_cvt_pk_bf16_f32 v115, v124, v125
	v_cvt_pk_bf16_f32 v116, v126, v127
	v_cvt_pk_bf16_f32 v117, v128, v129
	v_lshl_add_u64 v[184:185], v[118:119], 0, 0
	s_cbranch_vccz .LBB0_263
	global_store_dwordx4 v[118:119], v[114:117], off
	s_mov_b64 s[6:7], 0
.LBB0_263:
	s_mov_b32 s98, 0x1000
	s_mov_b32 s99, 0x0
	v_lshl_add_u64 v[186:187], v[184:185], 0, s[98:99]
	s_andn2_b64 vcc, exec, s[6:7]
	s_cbranch_vccnz .LBB0_265
	global_store_dwordx4 v[186:187], v[114:117], off offset:-4096 sc1
	s_nop 1
.LBB0_265:
	s_waitcnt lgkmcnt(6)
	v_add_f32_e32 v114, v159, v160
	v_fmamk_f32 v114, v114, 0x3a800000, v144
	v_rsq_f32_e32 v114, v114
	s_mov_b64 s[54:55], -1
	s_andn2_b64 vcc, exec, s[52:53]
	v_pk_mul_f32 v[106:107], v[106:107], v[114:115] op_sel_hi:[1,0]
	v_pk_mul_f32 v[110:111], v[110:111], v[114:115] op_sel_hi:[1,0]
	v_pk_mul_f32 v[116:117], v[106:107], s[24:25] op_sel_hi:[1,0]
	v_pk_mul_f32 v[108:109], v[108:109], v[114:115] op_sel_hi:[1,0]
	v_exp_f32_e32 v116, v116
	v_exp_f32_e32 v117, v117
	v_pk_mul_f32 v[98:99], v[98:99], v[114:115] op_sel_hi:[1,0]
	v_pk_mul_f32 v[102:103], v[102:103], v[114:115] op_sel_hi:[1,0]
	v_pk_add_f32 v[116:117], v[116:117], 1.0 op_sel_hi:[1,0]
	s_nop 0
	v_rcp_f32_e32 v116, v116
	v_rcp_f32_e32 v117, v117
	s_nop 0
	v_pk_mul_f32 v[106:107], v[106:107], v[116:117]
	s_nop 0
	v_pk_mul_f32 v[106:107], v[110:111], v[106:107]
	v_pk_mul_f32 v[110:111], v[112:113], v[114:115] op_sel_hi:[1,0]
	v_pk_mul_f32 v[112:113], v[108:109], s[24:25] op_sel_hi:[1,0]
	s_nop 0
	v_exp_f32_e32 v112, v112
	v_exp_f32_e32 v113, v113
	s_nop 0
	v_pk_add_f32 v[112:113], v[112:113], 1.0 op_sel_hi:[1,0]
	s_nop 0
	v_rcp_f32_e32 v112, v112
	v_rcp_f32_e32 v113, v113
	s_nop 0
	v_pk_mul_f32 v[108:109], v[108:109], v[112:113]
	s_nop 0
	v_pk_mul_f32 v[108:109], v[110:111], v[108:109]
	v_pk_mul_f32 v[110:111], v[98:99], s[24:25] op_sel_hi:[1,0]
	s_nop 0
	v_exp_f32_e32 v110, v110
	v_exp_f32_e32 v111, v111
	s_nop 0
	v_pk_add_f32 v[110:111], v[110:111], 1.0 op_sel_hi:[1,0]
	s_nop 0
	v_rcp_f32_e32 v110, v110
	v_rcp_f32_e32 v111, v111
	s_nop 0
	v_pk_mul_f32 v[98:99], v[98:99], v[110:111]
	s_nop 0
	v_pk_mul_f32 v[110:111], v[102:103], v[98:99]
	v_pk_mul_f32 v[98:99], v[100:101], v[114:115] op_sel_hi:[1,0]
	v_pk_mul_f32 v[100:101], v[104:105], v[114:115] op_sel_hi:[1,0]
	v_pk_mul_f32 v[102:103], v[98:99], s[24:25] op_sel_hi:[1,0]
	s_nop 0
	v_exp_f32_e32 v102, v102
	v_exp_f32_e32 v103, v103
	s_nop 0
	v_pk_add_f32 v[102:103], v[102:103], 1.0 op_sel_hi:[1,0]
	s_nop 0
	v_rcp_f32_e32 v102, v102
	v_rcp_f32_e32 v103, v103
	s_nop 0
	v_pk_mul_f32 v[98:99], v[98:99], v[102:103]
	s_nop 0
	v_pk_mul_f32 v[104:105], v[100:101], v[98:99]
	s_nop 0
	s_nop 0
	s_nop 0
	s_nop 0
	s_nop 0
	v_cvt_pk_bf16_f32 v101, v104, v105
	v_cndmask_b32_e64 v104, 0, 1, s[52:53]
	v_cvt_pk_bf16_f32 v98, v106, v107
	v_cvt_pk_bf16_f32 v99, v108, v109
	v_cvt_pk_bf16_f32 v100, v110, v111
	v_cmp_ne_u32_e64 s[6:7], 1, v104
	s_cbranch_vccnz .LBB0_267
	s_mov_b64 s[54:55], 0
	global_store_dwordx4 v[186:187], v[98:101], off offset:-2048
.LBB0_267:
	s_andn2_b64 vcc, exec, s[54:55]
	s_cbranch_vccnz .LBB0_269
	global_store_dwordx4 v[186:187], v[98:101], off offset:-2048 sc1
	s_nop 1
.LBB0_269:
	s_waitcnt lgkmcnt(5)
	v_add_f32_e32 v98, v157, v158
	v_fmamk_f32 v98, v98, 0x3a800000, v144
	v_rsq_f32_e32 v98, v98
	s_mov_b64 s[52:53], -1
	s_and_b64 vcc, exec, s[6:7]
	v_pk_mul_f32 v[90:91], v[90:91], v[98:99] op_sel_hi:[1,0]
	v_pk_mul_f32 v[94:95], v[94:95], v[98:99] op_sel_hi:[1,0]
	v_pk_mul_f32 v[100:101], v[90:91], s[24:25] op_sel_hi:[1,0]
	v_pk_mul_f32 v[92:93], v[92:93], v[98:99] op_sel_hi:[1,0]
	v_exp_f32_e32 v100, v100
	v_exp_f32_e32 v101, v101
	v_pk_mul_f32 v[82:83], v[82:83], v[98:99] op_sel_hi:[1,0]
	v_pk_mul_f32 v[86:87], v[86:87], v[98:99] op_sel_hi:[1,0]
	v_pk_add_f32 v[100:101], v[100:101], 1.0 op_sel_hi:[1,0]
	s_nop 0
	v_rcp_f32_e32 v100, v100
	v_rcp_f32_e32 v101, v101
	s_nop 0
	v_pk_mul_f32 v[90:91], v[90:91], v[100:101]
	s_nop 0
	v_pk_mul_f32 v[90:91], v[94:95], v[90:91]
	v_pk_mul_f32 v[94:95], v[96:97], v[98:99] op_sel_hi:[1,0]
	v_pk_mul_f32 v[96:97], v[92:93], s[24:25] op_sel_hi:[1,0]
	s_nop 0
	v_exp_f32_e32 v96, v96
	v_exp_f32_e32 v97, v97
	s_nop 0
	v_pk_add_f32 v[96:97], v[96:97], 1.0 op_sel_hi:[1,0]
	s_nop 0
	v_rcp_f32_e32 v96, v96
	v_rcp_f32_e32 v97, v97
	s_nop 0
	v_pk_mul_f32 v[92:93], v[92:93], v[96:97]
	s_nop 0
	v_pk_mul_f32 v[92:93], v[94:95], v[92:93]
	v_pk_mul_f32 v[94:95], v[82:83], s[24:25] op_sel_hi:[1,0]
	s_nop 0
	v_exp_f32_e32 v94, v94
	v_exp_f32_e32 v95, v95
	s_nop 0
	v_pk_add_f32 v[94:95], v[94:95], 1.0 op_sel_hi:[1,0]
	s_nop 0
	v_rcp_f32_e32 v94, v94
	v_rcp_f32_e32 v95, v95
	s_nop 0
	v_pk_mul_f32 v[82:83], v[82:83], v[94:95]
	s_nop 0
	v_pk_mul_f32 v[94:95], v[86:87], v[82:83]
	v_pk_mul_f32 v[82:83], v[84:85], v[98:99] op_sel_hi:[1,0]
	v_pk_mul_f32 v[84:85], v[88:89], v[98:99] op_sel_hi:[1,0]
	v_pk_mul_f32 v[86:87], v[82:83], s[24:25] op_sel_hi:[1,0]
	s_nop 0
	v_exp_f32_e32 v86, v86
	v_exp_f32_e32 v87, v87
	s_nop 0
	v_pk_add_f32 v[86:87], v[86:87], 1.0 op_sel_hi:[1,0]
	s_nop 0
	v_rcp_f32_e32 v86, v86
	v_rcp_f32_e32 v87, v87
	s_nop 0
	v_pk_mul_f32 v[82:83], v[82:83], v[86:87]
	s_nop 0
	v_pk_mul_f32 v[88:89], v[84:85], v[82:83]
	s_nop 0
	v_cvt_pk_bf16_f32 v82, v90, v91
	v_cvt_pk_bf16_f32 v83, v92, v93
	v_cvt_pk_bf16_f32 v84, v94, v95
	v_cvt_pk_bf16_f32 v85, v88, v89
	s_cbranch_vccnz .LBB0_271
	s_mov_b64 s[52:53], 0
	global_store_dwordx4 v[186:187], v[82:85], off
.LBB0_271:
	s_andn2_b64 vcc, exec, s[52:53]
	s_cbranch_vccnz .LBB0_273
	global_store_dwordx4 v[186:187], v[82:85], off sc1
	s_nop 1
.LBB0_273:
	s_waitcnt lgkmcnt(4)
	v_add_f32_e32 v82, v155, v156
	v_fmamk_f32 v82, v82, 0x3a800000, v144
	v_rsq_f32_e32 v82, v82
	s_mov_b64 s[52:53], -1
	s_and_b64 vcc, exec, s[6:7]
	v_pk_mul_f32 v[74:75], v[74:75], v[82:83] op_sel_hi:[1,0]
	v_pk_mul_f32 v[78:79], v[78:79], v[82:83] op_sel_hi:[1,0]
	v_pk_mul_f32 v[84:85], v[74:75], s[24:25] op_sel_hi:[1,0]
	v_pk_mul_f32 v[76:77], v[76:77], v[82:83] op_sel_hi:[1,0]
	v_exp_f32_e32 v84, v84
	v_exp_f32_e32 v85, v85
	v_pk_mul_f32 v[66:67], v[66:67], v[82:83] op_sel_hi:[1,0]
	v_pk_mul_f32 v[70:71], v[70:71], v[82:83] op_sel_hi:[1,0]
	v_pk_add_f32 v[84:85], v[84:85], 1.0 op_sel_hi:[1,0]
	s_nop 0
	v_rcp_f32_e32 v84, v84
	v_rcp_f32_e32 v85, v85
	s_nop 0
	v_pk_mul_f32 v[74:75], v[74:75], v[84:85]
	s_nop 0
	v_pk_mul_f32 v[74:75], v[78:79], v[74:75]
	v_pk_mul_f32 v[78:79], v[80:81], v[82:83] op_sel_hi:[1,0]
	v_pk_mul_f32 v[80:81], v[76:77], s[24:25] op_sel_hi:[1,0]
	s_nop 0
	v_exp_f32_e32 v80, v80
	v_exp_f32_e32 v81, v81
	s_nop 0
	v_pk_add_f32 v[80:81], v[80:81], 1.0 op_sel_hi:[1,0]
	s_nop 0
	v_rcp_f32_e32 v80, v80
	v_rcp_f32_e32 v81, v81
	s_nop 0
	v_pk_mul_f32 v[76:77], v[76:77], v[80:81]
	s_nop 0
	v_pk_mul_f32 v[76:77], v[78:79], v[76:77]
	v_pk_mul_f32 v[78:79], v[66:67], s[24:25] op_sel_hi:[1,0]
	s_nop 0
	v_exp_f32_e32 v78, v78
	v_exp_f32_e32 v79, v79
	s_nop 0
	v_pk_add_f32 v[78:79], v[78:79], 1.0 op_sel_hi:[1,0]
	s_nop 0
	v_rcp_f32_e32 v78, v78
	v_rcp_f32_e32 v79, v79
	s_nop 0
	v_pk_mul_f32 v[66:67], v[66:67], v[78:79]
	s_nop 0
	v_pk_mul_f32 v[78:79], v[70:71], v[66:67]
	v_pk_mul_f32 v[66:67], v[68:69], v[82:83] op_sel_hi:[1,0]
	v_pk_mul_f32 v[68:69], v[72:73], v[82:83] op_sel_hi:[1,0]
	v_pk_mul_f32 v[70:71], v[66:67], s[24:25] op_sel_hi:[1,0]
	s_nop 0
	v_exp_f32_e32 v70, v70
	v_exp_f32_e32 v71, v71
	s_nop 0
	v_pk_add_f32 v[70:71], v[70:71], 1.0 op_sel_hi:[1,0]
	s_nop 0
	v_rcp_f32_e32 v70, v70
	v_rcp_f32_e32 v71, v71
	s_nop 0
	v_pk_mul_f32 v[66:67], v[66:67], v[70:71]
	s_nop 0
	v_pk_mul_f32 v[72:73], v[68:69], v[66:67]
	s_nop 0
	v_cvt_pk_bf16_f32 v66, v74, v75
	v_cvt_pk_bf16_f32 v67, v76, v77
	v_cvt_pk_bf16_f32 v68, v78, v79
	v_cvt_pk_bf16_f32 v69, v72, v73
	s_cbranch_vccnz .LBB0_275
	s_mov_b64 s[52:53], 0
	global_store_dwordx4 v[186:187], v[66:69], off offset:2048
.LBB0_275:
	s_andn2_b64 vcc, exec, s[52:53]
	s_cbranch_vccnz .LBB0_277
	global_store_dwordx4 v[186:187], v[66:69], off offset:2048 sc1
	s_nop 1
.LBB0_277:
	s_waitcnt lgkmcnt(3)
	v_add_f32_e32 v66, v153, v154
	v_fmamk_f32 v66, v66, 0x3a800000, v144
	v_rsq_f32_e32 v66, v66
	v_add_u32_e32 v67, 0x80, v130
	s_mov_b64 s[52:53], -1
	v_pk_mul_f32 v[58:59], v[58:59], v[66:67] op_sel_hi:[1,0]
	v_pk_mul_f32 v[62:63], v[62:63], v[66:67] op_sel_hi:[1,0]
	v_pk_mul_f32 v[68:69], v[58:59], s[24:25] op_sel_hi:[1,0]
	v_pk_mul_f32 v[60:61], v[60:61], v[66:67] op_sel_hi:[1,0]
	v_exp_f32_e32 v68, v68
	v_exp_f32_e32 v69, v69
	v_pk_mul_f32 v[50:51], v[50:51], v[66:67] op_sel_hi:[1,0]
	v_pk_mul_f32 v[54:55], v[54:55], v[66:67] op_sel_hi:[1,0]
	s_and_b64 vcc, exec, s[6:7]
	v_pk_add_f32 v[68:69], v[68:69], 1.0 op_sel_hi:[1,0]
	s_nop 0
	v_rcp_f32_e32 v68, v68
	v_rcp_f32_e32 v69, v69
	s_nop 0
	v_pk_mul_f32 v[58:59], v[58:59], v[68:69]
	s_nop 0
	v_pk_mul_f32 v[58:59], v[62:63], v[58:59]
	v_pk_mul_f32 v[62:63], v[64:65], v[66:67] op_sel_hi:[1,0]
	v_pk_mul_f32 v[64:65], v[60:61], s[24:25] op_sel_hi:[1,0]
	s_nop 0
	v_exp_f32_e32 v64, v64
	v_exp_f32_e32 v65, v65
	s_nop 0
	v_pk_add_f32 v[64:65], v[64:65], 1.0 op_sel_hi:[1,0]
	s_nop 0
	v_rcp_f32_e32 v64, v64
	v_rcp_f32_e32 v65, v65
	s_nop 0
	v_pk_mul_f32 v[60:61], v[60:61], v[64:65]
	s_nop 0
	v_pk_mul_f32 v[60:61], v[62:63], v[60:61]
	v_pk_mul_f32 v[62:63], v[50:51], s[24:25] op_sel_hi:[1,0]
	s_nop 0
	v_exp_f32_e32 v62, v62
	v_exp_f32_e32 v63, v63
	s_nop 0
	v_pk_add_f32 v[62:63], v[62:63], 1.0 op_sel_hi:[1,0]
	s_nop 0
	v_rcp_f32_e32 v62, v62
	v_rcp_f32_e32 v63, v63
	s_nop 0
	v_pk_mul_f32 v[50:51], v[50:51], v[62:63]
	s_nop 0
	v_pk_mul_f32 v[62:63], v[54:55], v[50:51]
	v_pk_mul_f32 v[50:51], v[52:53], v[66:67] op_sel_hi:[1,0]
	v_pk_mul_f32 v[52:53], v[56:57], v[66:67] op_sel_hi:[1,0]
	v_pk_mul_f32 v[54:55], v[50:51], s[24:25] op_sel_hi:[1,0]
	s_nop 0
	v_exp_f32_e32 v54, v54
	v_exp_f32_e32 v55, v55
	s_nop 0
	v_pk_add_f32 v[54:55], v[54:55], 1.0 op_sel_hi:[1,0]
	s_nop 0
	v_rcp_f32_e32 v54, v54
	v_rcp_f32_e32 v55, v55
	s_nop 0
	v_pk_mul_f32 v[50:51], v[50:51], v[54:55]
	s_nop 0
	v_pk_mul_f32 v[56:57], v[52:53], v[50:51]
	s_nop 0
	v_cvt_pk_bf16_f32 v50, v58, v59
	v_cvt_pk_bf16_f32 v51, v60, v61
	v_cvt_pk_bf16_f32 v52, v62, v63
	v_cvt_pk_bf16_f32 v53, v56, v57
	s_mov_b32 s98, 0x5000
	s_mov_b32 s99, 0x0
	v_lshl_add_u64 v[186:187], v[184:185], 0, s[98:99]
	s_cbranch_vccnz .LBB0_279
	s_mov_b64 s[52:53], 0
	global_store_dwordx4 v[186:187], v[50:53], off offset:-4096
.LBB0_279:
	s_andn2_b64 vcc, exec, s[52:53]
	s_cbranch_vccnz .LBB0_281
	global_store_dwordx4 v[186:187], v[50:53], off offset:-4096 sc1
	s_nop 1
.LBB0_281:
	s_waitcnt lgkmcnt(2)
	v_add_f32_e32 v50, v151, v152
	v_fmamk_f32 v50, v50, 0x3a800000, v144
	v_rsq_f32_e32 v50, v50
	s_mov_b64 s[52:53], -1
	s_and_b64 vcc, exec, s[6:7]
	v_pk_mul_f32 v[42:43], v[42:43], v[50:51] op_sel_hi:[1,0]
	v_pk_mul_f32 v[46:47], v[46:47], v[50:51] op_sel_hi:[1,0]
	v_pk_mul_f32 v[52:53], v[42:43], s[24:25] op_sel_hi:[1,0]
	v_pk_mul_f32 v[44:45], v[44:45], v[50:51] op_sel_hi:[1,0]
	v_exp_f32_e32 v52, v52
	v_exp_f32_e32 v53, v53
	v_pk_mul_f32 v[34:35], v[34:35], v[50:51] op_sel_hi:[1,0]
	v_pk_mul_f32 v[38:39], v[38:39], v[50:51] op_sel_hi:[1,0]
	v_pk_add_f32 v[52:53], v[52:53], 1.0 op_sel_hi:[1,0]
	s_nop 0
	v_rcp_f32_e32 v52, v52
	v_rcp_f32_e32 v53, v53
	s_nop 0
	v_pk_mul_f32 v[42:43], v[42:43], v[52:53]
	s_nop 0
	v_pk_mul_f32 v[42:43], v[46:47], v[42:43]
	v_pk_mul_f32 v[46:47], v[48:49], v[50:51] op_sel_hi:[1,0]
	v_pk_mul_f32 v[48:49], v[44:45], s[24:25] op_sel_hi:[1,0]
	s_nop 0
	v_exp_f32_e32 v48, v48
	v_exp_f32_e32 v49, v49
	s_nop 0
	v_pk_add_f32 v[48:49], v[48:49], 1.0 op_sel_hi:[1,0]
	s_nop 0
	v_rcp_f32_e32 v48, v48
	v_rcp_f32_e32 v49, v49
	s_nop 0
	v_pk_mul_f32 v[44:45], v[44:45], v[48:49]
	s_nop 0
	v_pk_mul_f32 v[44:45], v[46:47], v[44:45]
	v_pk_mul_f32 v[46:47], v[34:35], s[24:25] op_sel_hi:[1,0]
	s_nop 0
	v_exp_f32_e32 v46, v46
	v_exp_f32_e32 v47, v47
	s_nop 0
	v_pk_add_f32 v[46:47], v[46:47], 1.0 op_sel_hi:[1,0]
	s_nop 0
	v_rcp_f32_e32 v46, v46
	v_rcp_f32_e32 v47, v47
	s_nop 0
	v_pk_mul_f32 v[34:35], v[34:35], v[46:47]
	s_nop 0
	v_pk_mul_f32 v[46:47], v[38:39], v[34:35]
	v_pk_mul_f32 v[34:35], v[36:37], v[50:51] op_sel_hi:[1,0]
	v_pk_mul_f32 v[36:37], v[40:41], v[50:51] op_sel_hi:[1,0]
	v_pk_mul_f32 v[38:39], v[34:35], s[24:25] op_sel_hi:[1,0]
	s_nop 0
	v_exp_f32_e32 v38, v38
	v_exp_f32_e32 v39, v39
	s_nop 0
	v_pk_add_f32 v[38:39], v[38:39], 1.0 op_sel_hi:[1,0]
	s_nop 0
	v_rcp_f32_e32 v38, v38
	v_rcp_f32_e32 v39, v39
	s_nop 0
	v_pk_mul_f32 v[34:35], v[34:35], v[38:39]
	s_nop 0
	v_pk_mul_f32 v[40:41], v[36:37], v[34:35]
	s_nop 0
	v_cvt_pk_bf16_f32 v34, v42, v43
	v_cvt_pk_bf16_f32 v35, v44, v45
	v_cvt_pk_bf16_f32 v36, v46, v47
	v_cvt_pk_bf16_f32 v37, v40, v41
	s_cbranch_vccnz .LBB0_283
	s_mov_b64 s[52:53], 0
	global_store_dwordx4 v[186:187], v[34:37], off offset:-2048
.LBB0_283:
	s_andn2_b64 vcc, exec, s[52:53]
	s_cbranch_vccnz .LBB0_285
	global_store_dwordx4 v[186:187], v[34:37], off offset:-2048 sc1
	s_nop 1
.LBB0_285:
	s_waitcnt lgkmcnt(1)
	v_add_f32_e32 v34, v149, v150
	v_fmamk_f32 v34, v34, 0x3a800000, v144
	v_rsq_f32_e32 v34, v34
	s_mov_b64 s[52:53], -1
	s_and_b64 vcc, exec, s[6:7]
	v_pk_mul_f32 v[26:27], v[26:27], v[34:35] op_sel_hi:[1,0]
	v_pk_mul_f32 v[30:31], v[30:31], v[34:35] op_sel_hi:[1,0]
	v_pk_mul_f32 v[36:37], v[26:27], s[24:25] op_sel_hi:[1,0]
	v_pk_mul_f32 v[28:29], v[28:29], v[34:35] op_sel_hi:[1,0]
	v_exp_f32_e32 v36, v36
	v_exp_f32_e32 v37, v37
	v_pk_mul_f32 v[18:19], v[18:19], v[34:35] op_sel_hi:[1,0]
	v_pk_mul_f32 v[22:23], v[22:23], v[34:35] op_sel_hi:[1,0]
	v_pk_add_f32 v[36:37], v[36:37], 1.0 op_sel_hi:[1,0]
	s_nop 0
	v_rcp_f32_e32 v36, v36
	v_rcp_f32_e32 v37, v37
	s_nop 0
	v_pk_mul_f32 v[26:27], v[26:27], v[36:37]
	s_nop 0
	v_pk_mul_f32 v[26:27], v[30:31], v[26:27]
	v_pk_mul_f32 v[30:31], v[32:33], v[34:35] op_sel_hi:[1,0]
	v_pk_mul_f32 v[32:33], v[28:29], s[24:25] op_sel_hi:[1,0]
	s_nop 0
	v_exp_f32_e32 v32, v32
	v_exp_f32_e32 v33, v33
	s_nop 0
	v_pk_add_f32 v[32:33], v[32:33], 1.0 op_sel_hi:[1,0]
	s_nop 0
	v_rcp_f32_e32 v32, v32
	v_rcp_f32_e32 v33, v33
	s_nop 0
	v_pk_mul_f32 v[28:29], v[28:29], v[32:33]
	s_nop 0
	v_pk_mul_f32 v[28:29], v[30:31], v[28:29]
	v_pk_mul_f32 v[30:31], v[18:19], s[24:25] op_sel_hi:[1,0]
	s_nop 0
	v_exp_f32_e32 v30, v30
	v_exp_f32_e32 v31, v31
	s_nop 0
	v_pk_add_f32 v[30:31], v[30:31], 1.0 op_sel_hi:[1,0]
	s_nop 0
	v_rcp_f32_e32 v30, v30
	v_rcp_f32_e32 v31, v31
	s_nop 0
	v_pk_mul_f32 v[18:19], v[18:19], v[30:31]
	s_nop 0
	v_pk_mul_f32 v[30:31], v[22:23], v[18:19]
	v_pk_mul_f32 v[18:19], v[20:21], v[34:35] op_sel_hi:[1,0]
	v_pk_mul_f32 v[20:21], v[24:25], v[34:35] op_sel_hi:[1,0]
	v_pk_mul_f32 v[22:23], v[18:19], s[24:25] op_sel_hi:[1,0]
	s_nop 0
	v_exp_f32_e32 v22, v22
	v_exp_f32_e32 v23, v23
	s_nop 0
	v_pk_add_f32 v[22:23], v[22:23], 1.0 op_sel_hi:[1,0]
	s_nop 0
	v_rcp_f32_e32 v22, v22
	v_rcp_f32_e32 v23, v23
	s_nop 0
	v_pk_mul_f32 v[18:19], v[18:19], v[22:23]
	s_nop 0
	v_pk_mul_f32 v[24:25], v[20:21], v[18:19]
	s_nop 0
	v_cvt_pk_bf16_f32 v18, v26, v27
	v_cvt_pk_bf16_f32 v19, v28, v29
	v_cvt_pk_bf16_f32 v20, v30, v31
	v_cvt_pk_bf16_f32 v21, v24, v25
	s_cbranch_vccnz .LBB0_287
	s_mov_b64 s[52:53], 0
	global_store_dwordx4 v[186:187], v[18:21], off
.LBB0_287:
	s_andn2_b64 vcc, exec, s[52:53]
	s_cbranch_vccnz .LBB0_289
	global_store_dwordx4 v[186:187], v[18:21], off sc1
	s_nop 1
.LBB0_289:
	s_waitcnt lgkmcnt(0)
	v_add_f32_e32 v18, v147, v148
	v_fmamk_f32 v18, v18, 0x3a800000, v144
	v_rsq_f32_e32 v18, v18
	s_and_b64 vcc, exec, s[6:7]
	v_pk_mul_f32 v[10:11], v[10:11], v[18:19] op_sel_hi:[1,0]
	s_nop 0
	v_pk_mul_f32 v[20:21], v[10:11], s[24:25] op_sel_hi:[1,0]
	v_pk_mul_f32 v[14:15], v[14:15], v[18:19] op_sel_hi:[1,0]
	v_exp_f32_e32 v20, v20
	v_exp_f32_e32 v21, v21
	v_pk_mul_f32 v[12:13], v[12:13], v[18:19] op_sel_hi:[1,0]
	v_pk_mul_f32 v[2:3], v[2:3], v[18:19] op_sel_hi:[1,0]
	v_pk_mul_f32 v[6:7], v[6:7], v[18:19] op_sel_hi:[1,0]
	v_pk_add_f32 v[20:21], v[20:21], 1.0 op_sel_hi:[1,0]
	s_nop 0
	v_rcp_f32_e32 v20, v20
	v_rcp_f32_e32 v21, v21
	s_nop 0
	v_pk_mul_f32 v[10:11], v[10:11], v[20:21]
	s_nop 0
	v_pk_mul_f32 v[10:11], v[14:15], v[10:11]
	v_pk_mul_f32 v[14:15], v[16:17], v[18:19] op_sel_hi:[1,0]
	v_pk_mul_f32 v[16:17], v[12:13], s[24:25] op_sel_hi:[1,0]
	s_nop 0
	v_exp_f32_e32 v16, v16
	v_exp_f32_e32 v17, v17
	s_nop 0
	v_pk_add_f32 v[16:17], v[16:17], 1.0 op_sel_hi:[1,0]
	s_nop 0
	v_rcp_f32_e32 v16, v16
	v_rcp_f32_e32 v17, v17
	s_nop 0
	v_pk_mul_f32 v[12:13], v[12:13], v[16:17]
	s_nop 0
	v_pk_mul_f32 v[12:13], v[14:15], v[12:13]
	v_pk_mul_f32 v[14:15], v[2:3], s[24:25] op_sel_hi:[1,0]
	s_nop 0
	v_exp_f32_e32 v14, v14
	v_exp_f32_e32 v15, v15
	s_nop 0
	v_pk_add_f32 v[14:15], v[14:15], 1.0 op_sel_hi:[1,0]
	s_nop 0
	v_rcp_f32_e32 v14, v14
	v_rcp_f32_e32 v15, v15
	s_nop 0
	v_pk_mul_f32 v[2:3], v[2:3], v[14:15]
	s_nop 0
	v_pk_mul_f32 v[14:15], v[6:7], v[2:3]
	v_pk_mul_f32 v[2:3], v[4:5], v[18:19] op_sel_hi:[1,0]
	v_pk_mul_f32 v[4:5], v[8:9], v[18:19] op_sel_hi:[1,0]
	v_pk_mul_f32 v[6:7], v[2:3], s[24:25] op_sel_hi:[1,0]
	s_nop 0
	v_exp_f32_e32 v6, v6
	v_exp_f32_e32 v7, v7
	s_nop 0
	v_pk_add_f32 v[6:7], v[6:7], 1.0 op_sel_hi:[1,0]
	s_nop 0
	v_rcp_f32_e32 v6, v6
	v_rcp_f32_e32 v7, v7
	s_nop 0
	v_pk_mul_f32 v[2:3], v[2:3], v[6:7]
	s_nop 0
	v_pk_mul_f32 v[8:9], v[4:5], v[2:3]
	s_nop 0
	v_cvt_pk_bf16_f32 v2, v10, v11
	v_cvt_pk_bf16_f32 v3, v12, v13
	v_cvt_pk_bf16_f32 v4, v14, v15
	v_cvt_pk_bf16_f32 v5, v8, v9
	s_mov_b64 s[50:51], -1
	s_cbranch_vccnz .LBB0_291
	s_mov_b64 s[50:51], 0
	global_store_dwordx4 v[186:187], v[2:5], off offset:2048
.LBB0_291:
	s_andn2_b64 vcc, exec, s[50:51]
	s_cbranch_vccnz .LBB0_293
	global_store_dwordx4 v[186:187], v[2:5], off offset:2048 sc1
	s_nop 1

.LBB0_364:
	s_add_i32 s26, s93, 2
	s_lshl_b64 s[62:63], s[26:27], 15
	s_add_u32 s64, s18, s62
	s_addc_u32 s65, s19, s63
	s_and_b64 s[52:53], s[50:51], exec
	s_cselect_b32 s53, s65, s39
	s_cselect_b32 s52, s64, s38
	s_add_u32 s62, s20, s62
	s_waitcnt vmcnt(8)
	s_addc_u32 s63, s21, s63
	s_waitcnt lgkmcnt(0)
	s_and_b64 s[50:51], s[50:51], exec
	s_cselect_b32 s51, s63, s49
	s_cselect_b32 s50, s62, s48
	s_barrier
	s_setprio 1
	s_waitcnt lgkmcnt(7)
	v_mfma_f32_16x16x32_bf16 v[126:129], v[146:149], v[186:189], v[126:129]
	v_mfma_f32_16x16x32_bf16 v[122:125], v[154:157], v[186:189], v[122:125]
	s_waitcnt lgkmcnt(5)
	v_mfma_f32_16x16x32_bf16 v[118:121], v[146:149], v[178:181], v[118:121]
	v_mfma_f32_16x16x32_bf16 v[114:117], v[154:157], v[178:181], v[114:117]
	s_waitcnt lgkmcnt(3)
	v_mfma_f32_16x16x32_bf16 v[110:113], v[146:149], v[170:173], v[110:113]
	v_mfma_f32_16x16x32_bf16 v[106:109], v[154:157], v[170:173], v[106:109]
	s_waitcnt lgkmcnt(1)
	v_mfma_f32_16x16x32_bf16 v[102:105], v[146:149], v[162:165], v[102:105]
	v_mfma_f32_16x16x32_bf16 v[98:101], v[154:157], v[162:165], v[98:101]
	v_mfma_f32_16x16x32_bf16 v[126:129], v[150:153], v[190:193], v[126:129]
	v_mfma_f32_16x16x32_bf16 v[122:125], v[158:161], v[190:193], v[122:125]
	v_mfma_f32_16x16x32_bf16 v[118:121], v[150:153], v[182:185], v[118:121]
	v_mfma_f32_16x16x32_bf16 v[114:117], v[158:161], v[182:185], v[114:117]
	v_mfma_f32_16x16x32_bf16 v[110:113], v[150:153], v[174:177], v[110:113]
	v_mfma_f32_16x16x32_bf16 v[106:109], v[158:161], v[174:177], v[106:109]
	s_waitcnt lgkmcnt(0)
	v_mfma_f32_16x16x32_bf16 v[102:105], v[150:153], v[166:169], v[102:105]
	v_mfma_f32_16x16x32_bf16 v[98:101], v[158:161], v[166:169], v[98:101]
	s_setprio 0
	s_setprio 1
	v_mfma_f32_16x16x32_bf16 v[94:97], v[130:133], v[186:189], v[94:97]
	v_mfma_f32_16x16x32_bf16 v[90:93], v[138:141], v[186:189], v[90:93]
	v_mfma_f32_16x16x32_bf16 v[86:89], v[130:133], v[178:181], v[86:89]
	v_mfma_f32_16x16x32_bf16 v[82:85], v[138:141], v[178:181], v[82:85]
	v_mfma_f32_16x16x32_bf16 v[78:81], v[130:133], v[170:173], v[78:81]
	v_mfma_f32_16x16x32_bf16 v[74:77], v[138:141], v[170:173], v[74:77]
	v_mfma_f32_16x16x32_bf16 v[70:73], v[130:133], v[162:165], v[70:73]
	v_mfma_f32_16x16x32_bf16 v[66:69], v[138:141], v[162:165], v[66:69]
	v_mfma_f32_16x16x32_bf16 v[94:97], v[134:137], v[190:193], v[94:97]
	v_mfma_f32_16x16x32_bf16 v[90:93], v[142:145], v[190:193], v[90:93]
	v_mfma_f32_16x16x32_bf16 v[86:89], v[134:137], v[182:185], v[86:89]
	v_mfma_f32_16x16x32_bf16 v[82:85], v[142:145], v[182:185], v[82:85]
	v_mfma_f32_16x16x32_bf16 v[78:81], v[134:137], v[174:177], v[78:81]
	v_mfma_f32_16x16x32_bf16 v[74:77], v[142:145], v[174:177], v[74:77]
	v_mfma_f32_16x16x32_bf16 v[70:73], v[134:137], v[166:169], v[70:73]
	v_mfma_f32_16x16x32_bf16 v[66:69], v[142:145], v[166:169], v[66:69]
	s_setprio 0
	s_barrier
	ds_read_b128 v[186:189], v219 offset:16384
	ds_read_b128 v[190:193], v219 offset:17408
	ds_read_b128 v[178:181], v219 offset:18432
	ds_read_b128 v[182:185], v219 offset:19456
	ds_read_b128 v[170:173], v219 offset:20480
	ds_read_b128 v[174:177], v219 offset:21504
	ds_read_b128 v[162:165], v219 offset:22528
	ds_read_b128 v[166:169], v219 offset:23552
	s_mov_b32 m0, s74
	s_nop 0
	global_load_lds_dwordx4 v195, s[50:51]
	s_add_u32 m0, s74, 0x2000
	s_nop 0
	global_load_lds_dwordx4 v212, s[50:51]
	s_add_u32 s62, s50, 0x4000
	s_addc_u32 s63, s51, 0
	s_mov_b32 m0, s75
	s_nop 0
	global_load_lds_dwordx4 v195, s[62:63]
	s_add_u32 m0, s75, 0x2000
	s_nop 0
	global_load_lds_dwordx4 v212, s[62:63]
	s_andn2_b64 vcc, exec, s[54:55]
	s_mov_b32 m0, s73
	s_nop 0
	global_load_lds_dwordx4 v195, s[52:53]
	s_add_u32 m0, s73, 0x2000
	s_nop 0
	global_load_lds_dwordx4 v212, s[52:53]
	s_cbranch_vccnz .LBB0_366
	v_mov_b32_e32 v2, 0
	v_mov_b32_e32 v3, v2
	v_mov_b32_e32 v4, v2
	v_mov_b32_e32 v5, v2
	v_mov_b32_e32 v6, v2
	v_mov_b32_e32 v7, v2
	v_mov_b32_e32 v8, v2
	v_mov_b32_e32 v9, v2
	v_mov_b32_e32 v10, v2
	v_mov_b32_e32 v11, v2
	v_mov_b32_e32 v12, v2
	v_mov_b32_e32 v13, v2
	v_mov_b32_e32 v14, v2
	v_mov_b32_e32 v15, v2
	v_mov_b32_e32 v16, v2
	v_mov_b32_e32 v17, v2
	v_mov_b32_e32 v18, v2
	v_mov_b32_e32 v19, v2
	v_mov_b32_e32 v20, v2
	v_mov_b32_e32 v21, v2
	v_mov_b32_e32 v22, v2
	v_mov_b32_e32 v23, v2
	v_mov_b32_e32 v24, v2
	v_mov_b32_e32 v25, v2
	v_mov_b32_e32 v26, v2
	v_mov_b32_e32 v27, v2
	v_mov_b32_e32 v28, v2
	v_mov_b32_e32 v29, v2
	v_mov_b32_e32 v30, v2
	v_mov_b32_e32 v31, v2
	v_mov_b32_e32 v32, v2
	v_mov_b32_e32 v33, v2
	v_mov_b32_e32 v34, v2
	v_mov_b32_e32 v35, v2
	v_mov_b32_e32 v36, v2
	v_mov_b32_e32 v37, v2
	v_mov_b32_e32 v38, v2
	v_mov_b32_e32 v39, v2
	v_mov_b32_e32 v40, v2
	v_mov_b32_e32 v41, v2
	v_mov_b32_e32 v42, v2
	v_mov_b32_e32 v43, v2
	v_mov_b32_e32 v44, v2
	v_mov_b32_e32 v45, v2
	v_mov_b32_e32 v46, v2
	v_mov_b32_e32 v47, v2
	v_mov_b32_e32 v48, v2
	v_mov_b32_e32 v49, v2
	v_mov_b32_e32 v50, v2
	v_mov_b32_e32 v51, v2
	v_mov_b32_e32 v52, v2
	v_mov_b32_e32 v53, v2
	v_mov_b32_e32 v54, v2
	v_mov_b32_e32 v55, v2
	v_mov_b32_e32 v56, v2
	v_mov_b32_e32 v57, v2
	v_mov_b32_e32 v58, v2
	v_mov_b32_e32 v59, v2
	v_mov_b32_e32 v60, v2
	v_mov_b32_e32 v61, v2
	v_mov_b32_e32 v62, v2
	v_mov_b32_e32 v63, v2
	v_mov_b32_e32 v64, v2
	v_mov_b32_e32 v65, v2
.LBB0_366:
	s_waitcnt vmcnt(8)
	s_add_u32 s54, s52, 0x8000
	s_waitcnt lgkmcnt(0)
	s_addc_u32 s55, s53, 0
	s_add_u32 s62, s50, 0x8000
	s_addc_u32 s63, s51, 0
	s_barrier
	s_setprio 1
	s_waitcnt lgkmcnt(7)
	v_mfma_f32_16x16x32_bf16 v[62:65], v[146:149], v[186:189], v[62:65]
	v_mfma_f32_16x16x32_bf16 v[58:61], v[154:157], v[186:189], v[58:61]
	s_waitcnt lgkmcnt(5)
	v_mfma_f32_16x16x32_bf16 v[54:57], v[146:149], v[178:181], v[54:57]
	v_mfma_f32_16x16x32_bf16 v[50:53], v[154:157], v[178:181], v[50:53]
	s_waitcnt lgkmcnt(3)
	v_mfma_f32_16x16x32_bf16 v[46:49], v[146:149], v[170:173], v[46:49]
	v_mfma_f32_16x16x32_bf16 v[42:45], v[154:157], v[170:173], v[42:45]
	s_waitcnt lgkmcnt(1)
	v_mfma_f32_16x16x32_bf16 v[38:41], v[146:149], v[162:165], v[38:41]
	v_mfma_f32_16x16x32_bf16 v[34:37], v[154:157], v[162:165], v[34:37]
	v_mfma_f32_16x16x32_bf16 v[62:65], v[150:153], v[190:193], v[62:65]
	v_mfma_f32_16x16x32_bf16 v[58:61], v[158:161], v[190:193], v[58:61]
	v_mfma_f32_16x16x32_bf16 v[54:57], v[150:153], v[182:185], v[54:57]
	v_mfma_f32_16x16x32_bf16 v[50:53], v[158:161], v[182:185], v[50:53]
	v_mfma_f32_16x16x32_bf16 v[46:49], v[150:153], v[174:177], v[46:49]
	v_mfma_f32_16x16x32_bf16 v[42:45], v[158:161], v[174:177], v[42:45]
	s_waitcnt lgkmcnt(0)
	v_mfma_f32_16x16x32_bf16 v[38:41], v[150:153], v[166:169], v[38:41]
	v_mfma_f32_16x16x32_bf16 v[34:37], v[158:161], v[166:169], v[34:37]
	s_setprio 0
	s_setprio 1
	v_mfma_f32_16x16x32_bf16 v[30:33], v[130:133], v[186:189], v[30:33]
	v_mfma_f32_16x16x32_bf16 v[26:29], v[138:141], v[186:189], v[26:29]
	v_mfma_f32_16x16x32_bf16 v[22:25], v[130:133], v[178:181], v[22:25]
	v_mfma_f32_16x16x32_bf16 v[18:21], v[138:141], v[178:181], v[18:21]
	v_mfma_f32_16x16x32_bf16 v[14:17], v[130:133], v[170:173], v[14:17]
	v_mfma_f32_16x16x32_bf16 v[10:13], v[138:141], v[170:173], v[10:13]
	v_mfma_f32_16x16x32_bf16 v[6:9], v[130:133], v[162:165], v[6:9]
	v_mfma_f32_16x16x32_bf16 v[2:5], v[138:141], v[162:165], v[2:5]
	v_mfma_f32_16x16x32_bf16 v[30:33], v[134:137], v[190:193], v[30:33]
	v_mfma_f32_16x16x32_bf16 v[26:29], v[142:145], v[190:193], v[26:29]
	v_mfma_f32_16x16x32_bf16 v[22:25], v[134:137], v[182:185], v[22:25]
	v_mfma_f32_16x16x32_bf16 v[18:21], v[142:145], v[182:185], v[18:21]
	v_mfma_f32_16x16x32_bf16 v[14:17], v[134:137], v[174:177], v[14:17]
	v_mfma_f32_16x16x32_bf16 v[10:13], v[142:145], v[174:177], v[10:13]
	v_mfma_f32_16x16x32_bf16 v[6:9], v[134:137], v[166:169], v[6:9]
	v_mfma_f32_16x16x32_bf16 v[2:5], v[142:145], v[166:169], v[2:5]
	s_setprio 0
	s_barrier
	v_add_u32_e32 v142, 0x18000, v218
	v_add_u32_e32 v158, 0x1c000, v218
	ds_read_b128 v[130:133], v142
	ds_read_b128 v[134:137], v142 offset:1024
	ds_read_b128 v[138:141], v142 offset:2048
	ds_read_b128 v[142:145], v142 offset:3072
	ds_read_b128 v[146:149], v158
	ds_read_b128 v[150:153], v158 offset:1024
	ds_read_b128 v[154:157], v158 offset:2048
	ds_read_b128 v[158:161], v158 offset:3072
	ds_read_b128 v[162:165], v219 offset:32768
	ds_read_b128 v[166:169], v219 offset:33792
	ds_read_b128 v[170:173], v219 offset:34816
	ds_read_b128 v[174:177], v219 offset:35840
	ds_read_b128 v[178:181], v219 offset:36864
	ds_read_b128 v[182:185], v219 offset:37888
	ds_read_b128 v[186:189], v219 offset:38912
	ds_read_b128 v[190:193], v219 offset:39936
	s_add_u32 s52, s52, 0x4000
	s_addc_u32 s53, s53, 0
	s_mov_b32 m0, s76
	s_nop 0
	global_load_lds_dwordx4 v195, s[52:53]
	s_add_u32 m0, s76, 0x2000
	s_nop 0
	global_load_lds_dwordx4 v212, s[52:53]
	s_waitcnt vmcnt(8)
	s_waitcnt lgkmcnt(0)
	s_barrier
	s_setprio 1
	s_waitcnt lgkmcnt(7)
	v_mfma_f32_16x16x32_bf16 v[126:129], v[130:133], v[162:165], v[126:129]
	v_mfma_f32_16x16x32_bf16 v[122:125], v[138:141], v[162:165], v[122:125]
	s_waitcnt lgkmcnt(5)
	v_mfma_f32_16x16x32_bf16 v[118:121], v[130:133], v[170:173], v[118:121]
	v_mfma_f32_16x16x32_bf16 v[114:117], v[138:141], v[170:173], v[114:117]
	s_waitcnt lgkmcnt(3)
	v_mfma_f32_16x16x32_bf16 v[110:113], v[130:133], v[178:181], v[110:113]
	v_mfma_f32_16x16x32_bf16 v[106:109], v[138:141], v[178:181], v[106:109]
	s_waitcnt lgkmcnt(1)
	v_mfma_f32_16x16x32_bf16 v[102:105], v[130:133], v[186:189], v[102:105]
	v_mfma_f32_16x16x32_bf16 v[98:101], v[138:141], v[186:189], v[98:101]
	v_mfma_f32_16x16x32_bf16 v[126:129], v[134:137], v[166:169], v[126:129]
	v_mfma_f32_16x16x32_bf16 v[122:125], v[142:145], v[166:169], v[122:125]
	v_mfma_f32_16x16x32_bf16 v[118:121], v[134:137], v[174:177], v[118:121]
	v_mfma_f32_16x16x32_bf16 v[114:117], v[142:145], v[174:177], v[114:117]
	v_mfma_f32_16x16x32_bf16 v[110:113], v[134:137], v[182:185], v[110:113]
	v_mfma_f32_16x16x32_bf16 v[106:109], v[142:145], v[182:185], v[106:109]
	s_waitcnt lgkmcnt(0)
	v_mfma_f32_16x16x32_bf16 v[102:105], v[134:137], v[190:193], v[102:105]
	v_mfma_f32_16x16x32_bf16 v[98:101], v[142:145], v[190:193], v[98:101]
	s_setprio 0
	s_setprio 1
	v_mfma_f32_16x16x32_bf16 v[94:97], v[146:149], v[162:165], v[94:97]
	v_mfma_f32_16x16x32_bf16 v[90:93], v[154:157], v[162:165], v[90:93]
	v_mfma_f32_16x16x32_bf16 v[86:89], v[146:149], v[170:173], v[86:89]
	v_mfma_f32_16x16x32_bf16 v[82:85], v[154:157], v[170:173], v[82:85]
	v_mfma_f32_16x16x32_bf16 v[78:81], v[146:149], v[178:181], v[78:81]
	v_mfma_f32_16x16x32_bf16 v[74:77], v[154:157], v[178:181], v[74:77]
	v_mfma_f32_16x16x32_bf16 v[70:73], v[146:149], v[186:189], v[70:73]
	v_mfma_f32_16x16x32_bf16 v[66:69], v[154:157], v[186:189], v[66:69]
	v_mfma_f32_16x16x32_bf16 v[94:97], v[150:153], v[166:169], v[94:97]
	v_mfma_f32_16x16x32_bf16 v[90:93], v[158:161], v[166:169], v[90:93]
	v_mfma_f32_16x16x32_bf16 v[86:89], v[150:153], v[174:177], v[86:89]
	v_mfma_f32_16x16x32_bf16 v[82:85], v[158:161], v[174:177], v[82:85]
	v_mfma_f32_16x16x32_bf16 v[78:81], v[150:153], v[182:185], v[78:81]
	v_mfma_f32_16x16x32_bf16 v[74:77], v[158:161], v[182:185], v[74:77]
	v_mfma_f32_16x16x32_bf16 v[70:73], v[150:153], v[190:193], v[70:73]
	v_mfma_f32_16x16x32_bf16 v[66:69], v[158:161], v[190:193], v[66:69]
	s_setprio 0
	s_barrier
	ds_read_b128 v[162:165], v219 offset:49152
	ds_read_b128 v[166:169], v219 offset:50176
	ds_read_b128 v[170:173], v219 offset:51200
	ds_read_b128 v[174:177], v219 offset:52224
	ds_read_b128 v[178:181], v219 offset:53248
	ds_read_b128 v[182:185], v219 offset:54272
	ds_read_b128 v[186:189], v219 offset:55296
	ds_read_b128 v[190:193], v219 offset:56320
	s_mov_b32 m0, s80
	s_nop 0
	global_load_lds_dwordx4 v195, s[62:63]
	s_add_u32 m0, s80, 0x2000
	s_nop 0
	global_load_lds_dwordx4 v212, s[62:63]
	s_add_u32 s50, s50, 0xc000
	s_addc_u32 s51, s51, 0
	s_mov_b32 m0, s82
	s_nop 0
	global_load_lds_dwordx4 v195, s[50:51]
	s_add_u32 m0, s82, 0x2000
	s_nop 0
	global_load_lds_dwordx4 v212, s[50:51]
	s_nop 0
	s_mov_b32 m0, s81
	s_nop 0
	global_load_lds_dwordx4 v195, s[54:55]
	s_add_u32 m0, s81, 0x2000
	s_nop 0
	global_load_lds_dwordx4 v212, s[54:55]
	s_waitcnt vmcnt(8)
	s_waitcnt lgkmcnt(0)
	s_barrier
	s_setprio 1
	s_waitcnt lgkmcnt(7)
	v_mfma_f32_16x16x32_bf16 v[62:65], v[130:133], v[162:165], v[62:65]
	v_mfma_f32_16x16x32_bf16 v[58:61], v[138:141], v[162:165], v[58:61]
	s_waitcnt lgkmcnt(5)
	v_mfma_f32_16x16x32_bf16 v[54:57], v[130:133], v[170:173], v[54:57]
	v_mfma_f32_16x16x32_bf16 v[50:53], v[138:141], v[170:173], v[50:53]
	s_waitcnt lgkmcnt(3)
	v_mfma_f32_16x16x32_bf16 v[46:49], v[130:133], v[178:181], v[46:49]
	v_mfma_f32_16x16x32_bf16 v[42:45], v[138:141], v[178:181], v[42:45]
	s_waitcnt lgkmcnt(1)
	v_mfma_f32_16x16x32_bf16 v[38:41], v[130:133], v[186:189], v[38:41]
	v_mfma_f32_16x16x32_bf16 v[34:37], v[138:141], v[186:189], v[34:37]
	v_mfma_f32_16x16x32_bf16 v[62:65], v[134:137], v[166:169], v[62:65]
	v_mfma_f32_16x16x32_bf16 v[58:61], v[142:145], v[166:169], v[58:61]
	v_mfma_f32_16x16x32_bf16 v[54:57], v[134:137], v[174:177], v[54:57]
	v_mfma_f32_16x16x32_bf16 v[50:53], v[142:145], v[174:177], v[50:53]
	v_mfma_f32_16x16x32_bf16 v[46:49], v[134:137], v[182:185], v[46:49]
	v_mfma_f32_16x16x32_bf16 v[42:45], v[142:145], v[182:185], v[42:45]
	s_waitcnt lgkmcnt(0)
	v_mfma_f32_16x16x32_bf16 v[38:41], v[134:137], v[190:193], v[38:41]
	v_mfma_f32_16x16x32_bf16 v[34:37], v[142:145], v[190:193], v[34:37]
	s_setprio 0
	s_setprio 1
	v_mfma_f32_16x16x32_bf16 v[30:33], v[146:149], v[162:165], v[30:33]
	v_mfma_f32_16x16x32_bf16 v[26:29], v[154:157], v[162:165], v[26:29]
	v_mfma_f32_16x16x32_bf16 v[22:25], v[146:149], v[170:173], v[22:25]
	v_mfma_f32_16x16x32_bf16 v[18:21], v[154:157], v[170:173], v[18:21]
	v_mfma_f32_16x16x32_bf16 v[14:17], v[146:149], v[178:181], v[14:17]
	v_mfma_f32_16x16x32_bf16 v[10:13], v[154:157], v[178:181], v[10:13]
	v_mfma_f32_16x16x32_bf16 v[6:9], v[146:149], v[186:189], v[6:9]
	v_mfma_f32_16x16x32_bf16 v[2:5], v[154:157], v[186:189], v[2:5]
	v_mfma_f32_16x16x32_bf16 v[30:33], v[150:153], v[166:169], v[30:33]
	v_mfma_f32_16x16x32_bf16 v[26:29], v[158:161], v[166:169], v[26:29]
	v_mfma_f32_16x16x32_bf16 v[22:25], v[150:153], v[174:177], v[22:25]
	v_mfma_f32_16x16x32_bf16 v[18:21], v[158:161], v[174:177], v[18:21]
	v_mfma_f32_16x16x32_bf16 v[14:17], v[150:153], v[182:185], v[14:17]
	v_mfma_f32_16x16x32_bf16 v[10:13], v[158:161], v[182:185], v[10:13]
	v_mfma_f32_16x16x32_bf16 v[6:9], v[150:153], v[190:193], v[6:9]
	v_mfma_f32_16x16x32_bf16 v[2:5], v[158:161], v[190:193], v[2:5]
	s_setprio 0
	s_barrier
	s_cmp_gt_u32 s93, 41
	s_cbranch_scc1 .LBB0_368
	v_mov_b32_e32 v130, v198
	s_mov_b32 s93, s26
	s_branch .LBB0_343

.LBB0_370:
	s_lshl_b32 s12, s95, 8
	v_mov_b32_e32 v130, v213
	v_mov_b32_e32 v163, v210
	s_add_i32 s12, s12, s78
	v_add_u32_e32 v162, s12, v130
	s_lshl_b32 s12, s68, 8
	s_or_b32 s12, s12, s79
	v_lshl_add_u32 v134, v163, 3, s12
	v_bfe_u32 v224, v134, 5, 1
	v_lshrrev_b32_e32 v131, 3, v162
	v_lshlrev_b32_e32 v130, 1, v134
	v_and_or_b32 v131, v131, 14, v224
	v_and_b32_e32 v223, 48, v130
	v_ashrrev_i32_e32 v222, 6, v134
	v_ashrrev_i32_e32 v130, 4, v162
	v_lshlrev_b32_e32 v132, 6, v162
	v_lshlrev_b32_e32 v226, 10, v131
	v_lshlrev_b32_e32 v131, 2, v162
	v_add_u32_e32 v134, 0x80, v134
	v_and_b32_e32 v135, -16, v130
	v_lshlrev_b32_e32 v130, 7, v162
	v_and_b32_e32 v132, 0x3c0, v132
	v_and_b32_e32 v131, 32, v131
	v_ashrrev_i32_e32 v225, 6, v134
	v_and_b32_e32 v130, 0x4000, v130
	v_bitop3_b32 v131, v223, v131, v132 bitop3:0x36
	v_add_u32_e32 v132, v222, v135
	v_or3_b32 v198, v130, v131, v226
	v_ashrrev_i32_e32 v133, 31, v132
	v_lshl_add_u64 v[130:131], s[34:35], 0, v[198:199]
	v_lshlrev_b64 v[190:191], 15, v[132:133]
	v_lshl_add_u64 v[132:133], v[130:131], 0, v[190:191]
	v_add_u32_e32 v178, 16, v162
	v_lshl_add_u64 v[166:167], v[132:133], 0, 0
	global_load_dwordx4 v[158:161], v[132:133], off
	s_mov_b32 s98, 0x11000
	s_mov_b32 s99, 0x0
	v_lshl_add_u64 v[172:173], v[166:167], 0, s[98:99]
	global_load_dwordx4 v[154:157], v[172:173], off offset:-4096
	v_add_u32_e32 v170, 32, v162
	s_mov_b32 s98, 0x1000
	s_mov_b32 s99, 0x0
	v_lshl_add_u64 v[174:175], v[166:167], 0, s[98:99]
	global_load_dwordx4 v[150:153], v[174:175], off offset:-2048
	global_load_dwordx4 v[146:149], v[172:173], off offset:-2048
	v_ashrrev_i32_e32 v130, 4, v170
	v_and_b32_e32 v134, -16, v130
	v_add_u32_e32 v134, v225, v134
	v_ashrrev_i32_e32 v135, 31, v134
	v_lshlrev_b64 v[176:177], 15, v[134:135]
	v_add_u32_e32 v164, 48, v162
	global_load_dwordx4 v[142:145], v[174:175], off
	global_load_dwordx4 v[138:141], v[172:173], off
	global_load_dwordx4 v[134:137], v[174:175], off offset:2048
	s_nop 0
	global_load_dwordx4 v[130:133], v[172:173], off offset:2048
	s_cmpk_gt_i32 s95, 0x7f
	s_cselect_b64 s[50:51], -1, 0
	s_nor_b64 s[54:55], s[36:37], s[50:51]
	s_waitcnt vmcnt(7)
	v_lshlrev_b32_e32 v190, 16, v158
	v_and_b32_e32 v191, 0xffff0000, v158
	v_lshlrev_b32_e32 v158, 16, v159
	v_and_b32_e32 v159, 0xffff0000, v159
	v_pk_fma_f32 v[192:193], v[128:129], 0.5, v[158:159] op_sel_hi:[1,0,1]
	v_lshlrev_b32_e32 v158, 16, v160
	v_and_b32_e32 v159, 0xffff0000, v160
	v_pk_fma_f32 v[202:203], v[122:123], 0.5, v[158:159] op_sel_hi:[1,0,1]
	v_lshlrev_b32_e32 v158, 16, v161
	v_and_b32_e32 v159, 0xffff0000, v161
	v_pk_fma_f32 v[190:191], v[126:127], 0.5, v[190:191] op_sel_hi:[1,0,1]
	v_pk_fma_f32 v[204:205], v[124:125], 0.5, v[158:159] op_sel_hi:[1,0,1]
	v_cvt_pk_bf16_f32 v158, v190, v191
	v_cvt_pk_bf16_f32 v159, v192, v193
	v_cvt_pk_bf16_f32 v160, v202, v203
	v_cvt_pk_bf16_f32 v161, v204, v205
	s_mov_b64 s[12:13], -1
	s_and_b64 vcc, exec, s[54:55]
	s_cbranch_vccz .LBB0_372
	global_store_dwordx4 v[174:175], v[158:161], off offset:-4096
	s_mov_b64 s[12:13], 0
.LBB0_372:
	s_andn2_b64 vcc, exec, s[12:13]
	s_cbranch_vccnz .LBB0_374
	global_store_dwordx4 v[174:175], v[158:161], off offset:-4096 sc1
	s_nop 1
.LBB0_374:
	s_nop 0
	s_nop 0
	s_waitcnt vmcnt(6)
	v_lshlrev_b32_e32 v158, 16, v154
	v_and_b32_e32 v159, 0xffff0000, v154
	v_lshlrev_b32_e32 v154, 16, v155
	v_and_b32_e32 v155, 0xffff0000, v155
	v_pk_fma_f32 v[188:189], v[96:97], 0.5, v[154:155] op_sel_hi:[1,0,1]
	v_lshlrev_b32_e32 v154, 16, v156
	v_and_b32_e32 v155, 0xffff0000, v156
	v_pk_fma_f32 v[206:207], v[90:91], 0.5, v[154:155] op_sel_hi:[1,0,1]
	v_lshlrev_b32_e32 v154, 16, v157
	v_and_b32_e32 v155, 0xffff0000, v157
	v_pk_fma_f32 v[158:159], v[94:95], 0.5, v[158:159] op_sel_hi:[1,0,1]
	v_pk_fma_f32 v[208:209], v[92:93], 0.5, v[154:155] op_sel_hi:[1,0,1]
	v_cndmask_b32_e64 v165, 0, 1, s[54:55]
	v_cvt_pk_bf16_f32 v154, v158, v159
	v_cvt_pk_bf16_f32 v155, v188, v189
	v_cvt_pk_bf16_f32 v156, v206, v207
	v_cvt_pk_bf16_f32 v157, v208, v209
	v_cmp_ne_u32_e64 s[12:13], 1, v165
	s_andn2_b64 vcc, exec, s[54:55]
	s_mov_b64 s[14:15], -1
	s_cbranch_vccnz .LBB0_376
	s_mov_b64 s[14:15], 0
	global_store_dwordx4 v[172:173], v[154:157], off offset:-4096
.LBB0_376:
	s_andn2_b64 vcc, exec, s[14:15]
	s_cbranch_vccnz .LBB0_378
	global_store_dwordx4 v[172:173], v[154:157], off offset:-4096 sc1
	s_nop 1

.LBB0_384:
	s_or_b64 exec, exec, s[62:63]
	s_waitcnt lgkmcnt(0)
	s_waitcnt vmcnt(5)
	v_lshlrev_b32_e32 v154, 16, v150
	v_and_b32_e32 v155, 0xffff0000, v150
	v_lshlrev_b32_e32 v150, 16, v151
	v_and_b32_e32 v151, 0xffff0000, v151
	v_pk_fma_f32 v[156:157], v[120:121], 0.5, v[150:151] op_sel_hi:[1,0,1]
	v_lshlrev_b32_e32 v150, 16, v152
	v_and_b32_e32 v151, 0xffff0000, v152
	v_pk_fma_f32 v[158:159], v[114:115], 0.5, v[150:151] op_sel_hi:[1,0,1]
	v_lshlrev_b32_e32 v150, 16, v153
	v_and_b32_e32 v151, 0xffff0000, v153
	v_pk_fma_f32 v[154:155], v[118:119], 0.5, v[154:155] op_sel_hi:[1,0,1]
	v_pk_fma_f32 v[160:161], v[116:117], 0.5, v[150:151] op_sel_hi:[1,0,1]
	v_cvt_pk_bf16_f32 v150, v154, v155
	v_cvt_pk_bf16_f32 v151, v156, v157
	v_cvt_pk_bf16_f32 v152, v158, v159
	v_cvt_pk_bf16_f32 v153, v160, v161
	s_nor_b64 s[54:55], s[64:65], s[50:51]
	s_and_saveexec_b64 s[62:63], s[54:55]
	s_xor_b64 s[54:55], exec, s[62:63]
	s_cbranch_execz .LBB0_386
	global_store_dwordx4 v[174:175], v[150:153], off offset:-2048
.LBB0_386:
	s_andn2_saveexec_b64 s[54:55], s[54:55]
	s_cbranch_execz .LBB0_388
	global_store_dwordx4 v[174:175], v[150:153], off offset:-2048 sc1
	s_nop 1
.LBB0_388:
	s_or_b64 exec, exec, s[54:55]
	s_nop 0
	s_waitcnt vmcnt(4)
	v_lshlrev_b32_e32 v152, 16, v146
	v_and_b32_e32 v153, 0xffff0000, v146
	v_lshlrev_b32_e32 v146, 16, v147
	v_and_b32_e32 v147, 0xffff0000, v147
	v_pk_fma_f32 v[182:183], v[88:89], 0.5, v[146:147] op_sel_hi:[1,0,1]
	v_lshlrev_b32_e32 v146, 16, v148
	v_and_b32_e32 v147, 0xffff0000, v148
	v_pk_fma_f32 v[184:185], v[82:83], 0.5, v[146:147] op_sel_hi:[1,0,1]
	v_lshlrev_b32_e32 v146, 16, v149
	v_and_b32_e32 v147, 0xffff0000, v149
	v_pk_fma_f32 v[152:153], v[86:87], 0.5, v[152:153] op_sel_hi:[1,0,1]
	v_pk_fma_f32 v[186:187], v[84:85], 0.5, v[146:147] op_sel_hi:[1,0,1]
	v_cvt_pk_bf16_f32 v146, v152, v153
	v_cvt_pk_bf16_f32 v147, v182, v183
	v_cvt_pk_bf16_f32 v148, v184, v185
	v_cvt_pk_bf16_f32 v149, v186, v187
	s_and_b64 vcc, exec, s[12:13]
	s_mov_b64 s[54:55], -1
	s_cbranch_vccnz .LBB0_390
	s_mov_b64 s[54:55], 0
	global_store_dwordx4 v[172:173], v[146:149], off offset:-2048
.LBB0_390:
	s_andn2_b64 vcc, exec, s[54:55]
	s_cbranch_vccnz .LBB0_392
	global_store_dwordx4 v[172:173], v[146:149], off offset:-2048 sc1
	s_nop 1

.LBB0_398:
	s_or_b64 exec, exec, s[54:55]
	s_waitcnt lgkmcnt(0)
	s_waitcnt vmcnt(3)
	v_lshlrev_b32_e32 v146, 16, v142
	v_and_b32_e32 v147, 0xffff0000, v142
	v_lshlrev_b32_e32 v142, 16, v143
	v_and_b32_e32 v143, 0xffff0000, v143
	v_pk_fma_f32 v[148:149], v[112:113], 0.5, v[142:143] op_sel_hi:[1,0,1]
	v_lshlrev_b32_e32 v142, 16, v144
	v_and_b32_e32 v143, 0xffff0000, v144
	v_pk_fma_f32 v[150:151], v[106:107], 0.5, v[142:143] op_sel_hi:[1,0,1]
	v_lshlrev_b32_e32 v142, 16, v145
	v_and_b32_e32 v143, 0xffff0000, v145
	v_pk_fma_f32 v[146:147], v[110:111], 0.5, v[146:147] op_sel_hi:[1,0,1]
	v_pk_fma_f32 v[152:153], v[108:109], 0.5, v[142:143] op_sel_hi:[1,0,1]
	v_cvt_pk_bf16_f32 v142, v146, v147
	v_cvt_pk_bf16_f32 v143, v148, v149
	v_cvt_pk_bf16_f32 v144, v150, v151
	v_cvt_pk_bf16_f32 v145, v152, v153
	s_nor_b64 s[54:55], s[62:63], s[50:51]
	s_and_saveexec_b64 s[62:63], s[54:55]
	s_xor_b64 s[54:55], exec, s[62:63]
	s_cbranch_execz .LBB0_400
	global_store_dwordx4 v[174:175], v[142:145], off
.LBB0_400:
	s_andn2_saveexec_b64 s[54:55], s[54:55]
	s_cbranch_execz .LBB0_402
	global_store_dwordx4 v[174:175], v[142:145], off sc1
	s_nop 1
.LBB0_402:
	s_or_b64 exec, exec, s[54:55]
	s_waitcnt vmcnt(2)
	v_lshlrev_b32_e32 v144, 16, v138
	v_and_b32_e32 v145, 0xffff0000, v138
	v_lshlrev_b32_e32 v138, 16, v139
	v_and_b32_e32 v139, 0xffff0000, v139
	v_pk_fma_f32 v[154:155], v[80:81], 0.5, v[138:139] op_sel_hi:[1,0,1]
	v_lshlrev_b32_e32 v138, 16, v140
	v_and_b32_e32 v139, 0xffff0000, v140
	v_pk_fma_f32 v[156:157], v[74:75], 0.5, v[138:139] op_sel_hi:[1,0,1]
	v_lshlrev_b32_e32 v138, 16, v141
	v_and_b32_e32 v139, 0xffff0000, v141
	v_pk_fma_f32 v[144:145], v[78:79], 0.5, v[144:145] op_sel_hi:[1,0,1]
	v_pk_fma_f32 v[158:159], v[76:77], 0.5, v[138:139] op_sel_hi:[1,0,1]
	v_cvt_pk_bf16_f32 v138, v144, v145
	v_cvt_pk_bf16_f32 v139, v154, v155
	v_cvt_pk_bf16_f32 v140, v156, v157
	v_cvt_pk_bf16_f32 v141, v158, v159
	s_and_b64 vcc, exec, s[12:13]
	s_mov_b64 s[54:55], -1
	s_cbranch_vccnz .LBB0_404
	s_mov_b64 s[54:55], 0
	global_store_dwordx4 v[172:173], v[138:141], off
.LBB0_404:
	s_andn2_b64 vcc, exec, s[54:55]
	s_cbranch_vccnz .LBB0_406
	global_store_dwordx4 v[172:173], v[138:141], off sc1
	s_nop 1

.LBB0_412:
	s_or_b64 exec, exec, s[54:55]
	s_waitcnt lgkmcnt(0)
	s_waitcnt vmcnt(1)
	v_lshlrev_b32_e32 v138, 16, v134
	v_and_b32_e32 v139, 0xffff0000, v134
	v_lshlrev_b32_e32 v134, 16, v135
	v_and_b32_e32 v135, 0xffff0000, v135
	v_pk_fma_f32 v[140:141], v[104:105], 0.5, v[134:135] op_sel_hi:[1,0,1]
	v_lshlrev_b32_e32 v134, 16, v136
	v_and_b32_e32 v135, 0xffff0000, v136
	v_pk_fma_f32 v[142:143], v[98:99], 0.5, v[134:135] op_sel_hi:[1,0,1]
	v_lshlrev_b32_e32 v134, 16, v137
	v_and_b32_e32 v135, 0xffff0000, v137
	v_pk_fma_f32 v[138:139], v[102:103], 0.5, v[138:139] op_sel_hi:[1,0,1]
	v_pk_fma_f32 v[144:145], v[100:101], 0.5, v[134:135] op_sel_hi:[1,0,1]
	v_cvt_pk_bf16_f32 v134, v138, v139
	v_cvt_pk_bf16_f32 v135, v140, v141
	v_cvt_pk_bf16_f32 v136, v142, v143
	v_cvt_pk_bf16_f32 v137, v144, v145
	s_nor_b64 s[54:55], s[62:63], s[50:51]
	s_and_saveexec_b64 s[62:63], s[54:55]
	s_xor_b64 s[54:55], exec, s[62:63]
	s_cbranch_execz .LBB0_414
	global_store_dwordx4 v[174:175], v[134:137], off offset:2048
.LBB0_414:
	s_andn2_saveexec_b64 s[54:55], s[54:55]
	s_cbranch_execz .LBB0_416
	global_store_dwordx4 v[174:175], v[134:137], off offset:2048 sc1
	s_nop 1
.LBB0_416:
	s_or_b64 exec, exec, s[54:55]
	s_waitcnt vmcnt(0)
	v_lshlrev_b32_e32 v136, 16, v130
	v_and_b32_e32 v137, 0xffff0000, v130
	v_lshlrev_b32_e32 v130, 16, v131
	v_and_b32_e32 v131, 0xffff0000, v131
	v_pk_fma_f32 v[146:147], v[72:73], 0.5, v[130:131] op_sel_hi:[1,0,1]
	v_lshlrev_b32_e32 v130, 16, v132
	v_and_b32_e32 v131, 0xffff0000, v132
	v_pk_fma_f32 v[148:149], v[66:67], 0.5, v[130:131] op_sel_hi:[1,0,1]
	v_lshlrev_b32_e32 v130, 16, v133
	v_and_b32_e32 v131, 0xffff0000, v133
	v_pk_fma_f32 v[136:137], v[70:71], 0.5, v[136:137] op_sel_hi:[1,0,1]
	v_pk_fma_f32 v[150:151], v[68:69], 0.5, v[130:131] op_sel_hi:[1,0,1]
	v_cvt_pk_bf16_f32 v130, v136, v137
	v_cvt_pk_bf16_f32 v131, v146, v147
	v_cvt_pk_bf16_f32 v132, v148, v149
	v_cvt_pk_bf16_f32 v133, v150, v151
	s_and_b64 vcc, exec, s[12:13]
	s_mov_b64 s[54:55], -1
	s_cbranch_vccnz .LBB0_418
	s_mov_b64 s[54:55], 0
	global_store_dwordx4 v[172:173], v[130:133], off offset:2048
.LBB0_418:
	s_andn2_b64 vcc, exec, s[54:55]
	s_cbranch_vccnz .LBB0_420
	global_store_dwordx4 v[172:173], v[130:133], off offset:2048 sc1
	s_nop 1

.LBB0_425:
	s_or_b64 exec, exec, s[54:55]
	v_add_u32_e32 v184, 0x80, v162
	s_waitcnt lgkmcnt(0)
	v_lshlrev_b32_e32 v131, 6, v184
	v_lshlrev_b32_e32 v132, 2, v184
	v_lshlrev_b32_e32 v130, 7, v184
	v_and_b32_e32 v131, 0x3c0, v131
	v_and_b32_e32 v132, 32, v132
	v_and_b32_e32 v130, 0x4000, v130
	v_bitop3_b32 v131, v131, v132, v223 bitop3:0x36
	v_or3_b32 v198, v130, v131, v226
	v_add_u32_e32 v176, 0x90, v162
	s_mov_b32 s98, 0x5000
	s_mov_b32 s99, 0x0
	v_lshl_add_u64 v[172:173], v[166:167], 0, s[98:99]
	global_load_dwordx4 v[158:161], v[172:173], off offset:-4096
	s_mov_b32 s98, 0x15000
	s_mov_b32 s99, 0x0
	v_lshl_add_u64 v[174:175], v[166:167], 0, s[98:99]
	global_load_dwordx4 v[154:157], v[174:175], off offset:-4096
	v_add_u32_e32 v168, 0xa0, v162
	global_load_dwordx4 v[150:153], v[172:173], off offset:-2048
	global_load_dwordx4 v[146:149], v[174:175], off offset:-2048
	v_add_u32_e32 v162, 0xb0, v162
	global_load_dwordx4 v[142:145], v[172:173], off
	global_load_dwordx4 v[138:141], v[174:175], off
	global_load_dwordx4 v[134:137], v[172:173], off offset:2048
	s_nop 0
	global_load_dwordx4 v[130:133], v[174:175], off offset:2048
	s_and_b64 vcc, exec, s[12:13]
	s_mov_b64 s[54:55], -1
	s_waitcnt vmcnt(7)
	v_lshlrev_b32_e32 v190, 16, v158
	v_and_b32_e32 v191, 0xffff0000, v158
	v_lshlrev_b32_e32 v158, 16, v159
	v_and_b32_e32 v159, 0xffff0000, v159
	v_pk_fma_f32 v[192:193], v[64:65], 0.5, v[158:159] op_sel_hi:[1,0,1]
	v_lshlrev_b32_e32 v158, 16, v160
	v_and_b32_e32 v159, 0xffff0000, v160
	v_pk_fma_f32 v[202:203], v[58:59], 0.5, v[158:159] op_sel_hi:[1,0,1]
	v_lshlrev_b32_e32 v158, 16, v161
	v_and_b32_e32 v159, 0xffff0000, v161
	v_pk_fma_f32 v[190:191], v[62:63], 0.5, v[190:191] op_sel_hi:[1,0,1]
	v_pk_fma_f32 v[204:205], v[60:61], 0.5, v[158:159] op_sel_hi:[1,0,1]
	v_cvt_pk_bf16_f32 v158, v190, v191
	v_cvt_pk_bf16_f32 v159, v192, v193
	v_cvt_pk_bf16_f32 v160, v202, v203
	v_cvt_pk_bf16_f32 v161, v204, v205
	s_cbranch_vccnz .LBB0_427
	s_mov_b64 s[54:55], 0
	global_store_dwordx4 v[172:173], v[158:161], off offset:-4096
.LBB0_427:
	s_andn2_b64 vcc, exec, s[54:55]
	s_cbranch_vccnz .LBB0_429
	global_store_dwordx4 v[172:173], v[158:161], off offset:-4096 sc1
	s_nop 1
.LBB0_429:
	s_waitcnt vmcnt(6)
	v_lshlrev_b32_e32 v160, 16, v154
	v_and_b32_e32 v161, 0xffff0000, v154
	v_lshlrev_b32_e32 v154, 16, v155
	v_and_b32_e32 v155, 0xffff0000, v155
	v_pk_fma_f32 v[188:189], v[32:33], 0.5, v[154:155] op_sel_hi:[1,0,1]
	v_lshlrev_b32_e32 v154, 16, v156
	v_and_b32_e32 v155, 0xffff0000, v156
	v_pk_fma_f32 v[206:207], v[26:27], 0.5, v[154:155] op_sel_hi:[1,0,1]
	v_lshlrev_b32_e32 v154, 16, v157
	v_and_b32_e32 v155, 0xffff0000, v157
	v_pk_fma_f32 v[160:161], v[30:31], 0.5, v[160:161] op_sel_hi:[1,0,1]
	v_pk_fma_f32 v[208:209], v[28:29], 0.5, v[154:155] op_sel_hi:[1,0,1]
	v_cvt_pk_bf16_f32 v154, v160, v161
	v_cvt_pk_bf16_f32 v155, v188, v189
	v_cvt_pk_bf16_f32 v156, v206, v207
	v_cvt_pk_bf16_f32 v157, v208, v209
	s_and_b64 vcc, exec, s[12:13]
	s_mov_b64 s[54:55], -1
	s_cbranch_vccnz .LBB0_431
	s_mov_b64 s[54:55], 0
	global_store_dwordx4 v[174:175], v[154:157], off offset:-4096
.LBB0_431:
	s_andn2_b64 vcc, exec, s[54:55]
	s_cbranch_vccnz .LBB0_433
	global_store_dwordx4 v[174:175], v[154:157], off offset:-4096 sc1
	s_nop 1

.LBB0_439:
	s_or_b64 exec, exec, s[54:55]
	s_waitcnt lgkmcnt(0)
	s_waitcnt vmcnt(5)
	v_lshlrev_b32_e32 v154, 16, v150
	v_and_b32_e32 v155, 0xffff0000, v150
	v_lshlrev_b32_e32 v150, 16, v151
	v_and_b32_e32 v151, 0xffff0000, v151
	v_pk_fma_f32 v[156:157], v[56:57], 0.5, v[150:151] op_sel_hi:[1,0,1]
	v_lshlrev_b32_e32 v150, 16, v152
	v_and_b32_e32 v151, 0xffff0000, v152
	v_pk_fma_f32 v[158:159], v[50:51], 0.5, v[150:151] op_sel_hi:[1,0,1]
	v_lshlrev_b32_e32 v150, 16, v153
	v_and_b32_e32 v151, 0xffff0000, v153
	v_pk_fma_f32 v[154:155], v[54:55], 0.5, v[154:155] op_sel_hi:[1,0,1]
	v_pk_fma_f32 v[160:161], v[52:53], 0.5, v[150:151] op_sel_hi:[1,0,1]
	v_cvt_pk_bf16_f32 v150, v154, v155
	v_cvt_pk_bf16_f32 v151, v156, v157
	v_cvt_pk_bf16_f32 v152, v158, v159
	v_cvt_pk_bf16_f32 v153, v160, v161
	s_nor_b64 s[54:55], s[62:63], s[50:51]
	s_and_saveexec_b64 s[62:63], s[54:55]
	s_xor_b64 s[54:55], exec, s[62:63]
	s_cbranch_execz .LBB0_441
	global_store_dwordx4 v[172:173], v[150:153], off offset:-2048
.LBB0_441:
	s_andn2_saveexec_b64 s[54:55], s[54:55]
	s_cbranch_execz .LBB0_443
	global_store_dwordx4 v[172:173], v[150:153], off offset:-2048 sc1
	s_nop 1
.LBB0_443:
	s_or_b64 exec, exec, s[54:55]
	s_nop 0
	s_waitcnt vmcnt(4)
	v_lshlrev_b32_e32 v152, 16, v146
	v_and_b32_e32 v153, 0xffff0000, v146
	v_lshlrev_b32_e32 v146, 16, v147
	v_and_b32_e32 v147, 0xffff0000, v147
	v_pk_fma_f32 v[180:181], v[24:25], 0.5, v[146:147] op_sel_hi:[1,0,1]
	v_lshlrev_b32_e32 v146, 16, v148
	v_and_b32_e32 v147, 0xffff0000, v148
	v_pk_fma_f32 v[182:183], v[18:19], 0.5, v[146:147] op_sel_hi:[1,0,1]
	v_lshlrev_b32_e32 v146, 16, v149
	v_and_b32_e32 v147, 0xffff0000, v149
	v_pk_fma_f32 v[152:153], v[22:23], 0.5, v[152:153] op_sel_hi:[1,0,1]
	v_pk_fma_f32 v[184:185], v[20:21], 0.5, v[146:147] op_sel_hi:[1,0,1]
	v_cvt_pk_bf16_f32 v146, v152, v153
	v_cvt_pk_bf16_f32 v147, v180, v181
	v_cvt_pk_bf16_f32 v148, v182, v183
	v_cvt_pk_bf16_f32 v149, v184, v185
	s_and_b64 vcc, exec, s[12:13]
	s_mov_b64 s[54:55], -1
	s_cbranch_vccnz .LBB0_445
	s_mov_b64 s[54:55], 0
	global_store_dwordx4 v[174:175], v[146:149], off offset:-2048
.LBB0_445:
	s_andn2_b64 vcc, exec, s[54:55]
	s_cbranch_vccnz .LBB0_447
	global_store_dwordx4 v[174:175], v[146:149], off offset:-2048 sc1
	s_nop 1

.LBB0_453:
	s_or_b64 exec, exec, s[54:55]
	s_waitcnt lgkmcnt(0)
	s_waitcnt vmcnt(3)
	v_lshlrev_b32_e32 v146, 16, v142
	v_and_b32_e32 v147, 0xffff0000, v142
	v_lshlrev_b32_e32 v142, 16, v143
	v_and_b32_e32 v143, 0xffff0000, v143
	v_pk_fma_f32 v[148:149], v[48:49], 0.5, v[142:143] op_sel_hi:[1,0,1]
	v_lshlrev_b32_e32 v142, 16, v144
	v_and_b32_e32 v143, 0xffff0000, v144
	v_pk_fma_f32 v[150:151], v[42:43], 0.5, v[142:143] op_sel_hi:[1,0,1]
	v_lshlrev_b32_e32 v142, 16, v145
	v_and_b32_e32 v143, 0xffff0000, v145
	v_pk_fma_f32 v[146:147], v[46:47], 0.5, v[146:147] op_sel_hi:[1,0,1]
	v_pk_fma_f32 v[152:153], v[44:45], 0.5, v[142:143] op_sel_hi:[1,0,1]
	v_cvt_pk_bf16_f32 v142, v146, v147
	v_cvt_pk_bf16_f32 v143, v148, v149
	v_cvt_pk_bf16_f32 v144, v150, v151
	v_cvt_pk_bf16_f32 v145, v152, v153
	s_nor_b64 s[54:55], s[62:63], s[50:51]
	s_and_saveexec_b64 s[62:63], s[54:55]
	s_xor_b64 s[54:55], exec, s[62:63]
	s_cbranch_execz .LBB0_455
	global_store_dwordx4 v[172:173], v[142:145], off
.LBB0_455:
	s_andn2_saveexec_b64 s[54:55], s[54:55]
	s_cbranch_execz .LBB0_457
	global_store_dwordx4 v[172:173], v[142:145], off sc1
	s_nop 1
.LBB0_457:
	s_or_b64 exec, exec, s[54:55]
	s_waitcnt vmcnt(2)
	v_lshlrev_b32_e32 v144, 16, v138
	v_and_b32_e32 v145, 0xffff0000, v138
	v_lshlrev_b32_e32 v138, 16, v139
	v_and_b32_e32 v139, 0xffff0000, v139
	v_pk_fma_f32 v[154:155], v[16:17], 0.5, v[138:139] op_sel_hi:[1,0,1]
	v_lshlrev_b32_e32 v138, 16, v140
	v_and_b32_e32 v139, 0xffff0000, v140
	v_pk_fma_f32 v[156:157], v[10:11], 0.5, v[138:139] op_sel_hi:[1,0,1]
	v_lshlrev_b32_e32 v138, 16, v141
	v_and_b32_e32 v139, 0xffff0000, v141
	v_pk_fma_f32 v[144:145], v[14:15], 0.5, v[144:145] op_sel_hi:[1,0,1]
	v_pk_fma_f32 v[158:159], v[12:13], 0.5, v[138:139] op_sel_hi:[1,0,1]
	v_cvt_pk_bf16_f32 v138, v144, v145
	v_cvt_pk_bf16_f32 v139, v154, v155
	v_cvt_pk_bf16_f32 v140, v156, v157
	v_cvt_pk_bf16_f32 v141, v158, v159
	s_and_b64 vcc, exec, s[12:13]
	s_mov_b64 s[54:55], -1
	s_cbranch_vccnz .LBB0_459
	s_mov_b64 s[54:55], 0
	global_store_dwordx4 v[174:175], v[138:141], off
.LBB0_459:
	s_andn2_b64 vcc, exec, s[54:55]
	s_cbranch_vccnz .LBB0_461
	global_store_dwordx4 v[174:175], v[138:141], off sc1
	s_nop 1

.LBB0_467:
	s_or_b64 exec, exec, s[54:55]
	s_waitcnt lgkmcnt(0)
	s_waitcnt vmcnt(1)
	v_lshlrev_b32_e32 v138, 16, v134
	v_and_b32_e32 v139, 0xffff0000, v134
	v_lshlrev_b32_e32 v134, 16, v135
	v_and_b32_e32 v135, 0xffff0000, v135
	v_pk_fma_f32 v[140:141], v[40:41], 0.5, v[134:135] op_sel_hi:[1,0,1]
	v_lshlrev_b32_e32 v134, 16, v136
	v_and_b32_e32 v135, 0xffff0000, v136
	v_pk_fma_f32 v[142:143], v[34:35], 0.5, v[134:135] op_sel_hi:[1,0,1]
	v_lshlrev_b32_e32 v134, 16, v137
	v_and_b32_e32 v135, 0xffff0000, v137
	v_pk_fma_f32 v[138:139], v[38:39], 0.5, v[138:139] op_sel_hi:[1,0,1]
	v_pk_fma_f32 v[144:145], v[36:37], 0.5, v[134:135] op_sel_hi:[1,0,1]
	v_cvt_pk_bf16_f32 v134, v138, v139
	v_cvt_pk_bf16_f32 v135, v140, v141
	v_cvt_pk_bf16_f32 v136, v142, v143
	v_cvt_pk_bf16_f32 v137, v144, v145
	s_nor_b64 s[50:51], s[62:63], s[50:51]
	s_and_saveexec_b64 s[54:55], s[50:51]
	s_xor_b64 s[50:51], exec, s[54:55]
	s_cbranch_execz .LBB0_469
	global_store_dwordx4 v[172:173], v[134:137], off offset:2048
.LBB0_469:
	s_andn2_saveexec_b64 s[50:51], s[50:51]
	s_cbranch_execz .LBB0_471
	global_store_dwordx4 v[172:173], v[134:137], off offset:2048 sc1
	s_nop 1
.LBB0_471:
	s_or_b64 exec, exec, s[50:51]
	s_waitcnt vmcnt(0)
	v_lshlrev_b32_e32 v136, 16, v130
	v_and_b32_e32 v137, 0xffff0000, v130
	v_lshlrev_b32_e32 v130, 16, v131
	v_and_b32_e32 v131, 0xffff0000, v131
	v_pk_fma_f32 v[146:147], v[8:9], 0.5, v[130:131] op_sel_hi:[1,0,1]
	v_lshlrev_b32_e32 v130, 16, v132
	v_and_b32_e32 v131, 0xffff0000, v132
	v_pk_fma_f32 v[148:149], v[2:3], 0.5, v[130:131] op_sel_hi:[1,0,1]
	v_lshlrev_b32_e32 v130, 16, v133
	v_and_b32_e32 v131, 0xffff0000, v133
	v_pk_fma_f32 v[136:137], v[6:7], 0.5, v[136:137] op_sel_hi:[1,0,1]
	v_pk_fma_f32 v[150:151], v[4:5], 0.5, v[130:131] op_sel_hi:[1,0,1]
	v_cvt_pk_bf16_f32 v130, v136, v137
	v_cvt_pk_bf16_f32 v131, v146, v147
	v_cvt_pk_bf16_f32 v132, v148, v149
	v_cvt_pk_bf16_f32 v133, v150, v151
	s_and_b64 vcc, exec, s[12:13]
	s_mov_b64 s[50:51], -1
	s_cbranch_vccnz .LBB0_473
	s_mov_b64 s[50:51], 0
	global_store_dwordx4 v[174:175], v[130:133], off offset:2048
.LBB0_473:
	s_andn2_b64 vcc, exec, s[50:51]
	s_cbranch_vccnz .LBB0_475
	global_store_dwordx4 v[174:175], v[130:133], off offset:2048 sc1
	s_nop 1

.LBB0_518:
	s_ashr_i32 s17, s16, 31
	s_lshl_b64 s[18:19], s[16:17], 19
	s_add_u32 s18, s50, s18
	s_addc_u32 s19, s51, s19
	s_and_b64 s[20:21], s[12:13], exec
	ds_read_b128 v[2:5], v141
	ds_read_b128 v[6:9], v141 offset:1024
	ds_read_b128 v[10:13], v141 offset:2048
	ds_read_b128 v[14:17], v141 offset:3072
	ds_read_b128 v[18:21], v142
	ds_read_b128 v[22:25], v142 offset:1024
	ds_read_b128 v[26:29], v142 offset:2048
	ds_read_b128 v[30:33], v142 offset:3072
	s_cselect_b32 s1, s19, s29
	s_cselect_b32 s17, s18, s28
	s_ashr_i32 s15, s14, 31
	s_lshl_b64 s[20:21], s[14:15], 19
	s_add_u32 s20, s52, s20
	s_addc_u32 s21, s53, s21
	s_and_b64 s[26:27], s[12:13], exec
	s_cselect_b32 s15, s21, s25
	s_cselect_b32 s23, s20, s24
	s_add_u32 s26, s28, 0x10000
	s_addc_u32 s27, s29, 0
	s_add_u32 s48, s24, 0x10000
	s_addc_u32 s49, s25, 0
	s_add_u32 s30, s28, 0x18000
	s_addc_u32 s31, s29, 0
	ds_read_b128 v[34:37], v143
	ds_read_b128 v[38:41], v143 offset:1024
	ds_read_b128 v[42:45], v143 offset:2048
	ds_read_b128 v[46:49], v143 offset:3072
	ds_read_b128 v[50:53], v143 offset:4096
	ds_read_b128 v[54:57], v143 offset:5120
	ds_read_b128 v[58:61], v143 offset:6144
	ds_read_b128 v[62:65], v143 offset:7168
	s_add_u32 s38, s24, 0x18000
	s_addc_u32 s39, s25, 0
	s_add_u32 s76, s28, 0xc000
	s_addc_u32 s77, s29, 0
	s_mov_b32 m0, s72
	s_nop 0
	global_load_lds_dwordx4 v195, s[76:77]
	s_add_u32 m0, s72, 0x2000
	s_nop 0
	global_load_lds_dwordx4 v212, s[76:77]
	s_waitcnt vmcnt(8)
	s_waitcnt lgkmcnt(0)
	s_barrier
	s_setprio 1
	s_waitcnt lgkmcnt(1)
	v_mfma_f32_16x16x32_bf16 v[90:93], v[2:5], v[58:61], 0
	v_mfma_f32_16x16x32_bf16 v[66:69], v[2:5], v[34:37], 0
	v_mfma_f32_16x16x32_bf16 v[70:73], v[10:13], v[34:37], 0
	v_mfma_f32_16x16x32_bf16 v[74:77], v[2:5], v[42:45], 0
	v_mfma_f32_16x16x32_bf16 v[78:81], v[10:13], v[42:45], 0
	v_mfma_f32_16x16x32_bf16 v[82:85], v[2:5], v[50:53], 0
	v_mfma_f32_16x16x32_bf16 v[86:89], v[10:13], v[50:53], 0
	s_waitcnt lgkmcnt(0)
	v_mfma_f32_16x16x32_bf16 v[98:101], v[6:9], v[62:65], v[90:93]
	v_mfma_f32_16x16x32_bf16 v[90:93], v[10:13], v[58:61], 0
	v_mfma_f32_16x16x32_bf16 v[66:69], v[6:9], v[38:41], v[66:69]
	v_mfma_f32_16x16x32_bf16 v[70:73], v[14:17], v[38:41], v[70:73]
	v_mfma_f32_16x16x32_bf16 v[74:77], v[6:9], v[46:49], v[74:77]
	v_mfma_f32_16x16x32_bf16 v[78:81], v[14:17], v[46:49], v[78:81]
	v_mfma_f32_16x16x32_bf16 v[82:85], v[6:9], v[54:57], v[82:85]
	v_mfma_f32_16x16x32_bf16 v[86:89], v[14:17], v[54:57], v[86:89]
	v_mfma_f32_16x16x32_bf16 v[102:105], v[14:17], v[62:65], v[90:93]
	s_setprio 0
	s_setprio 1
	v_mfma_f32_16x16x32_bf16 v[90:93], v[18:21], v[34:37], 0
	v_mfma_f32_16x16x32_bf16 v[34:37], v[26:29], v[34:37], 0
	v_mfma_f32_16x16x32_bf16 v[114:117], v[22:25], v[38:41], v[90:93]
	v_mfma_f32_16x16x32_bf16 v[34:37], v[30:33], v[38:41], v[34:37]
	v_mfma_f32_16x16x32_bf16 v[38:41], v[18:21], v[42:45], 0
	v_mfma_f32_16x16x32_bf16 v[42:45], v[26:29], v[42:45], 0
	v_mfma_f32_16x16x32_bf16 v[38:41], v[22:25], v[46:49], v[38:41]
	v_mfma_f32_16x16x32_bf16 v[42:45], v[30:33], v[46:49], v[42:45]
	v_mfma_f32_16x16x32_bf16 v[46:49], v[18:21], v[50:53], 0
	v_mfma_f32_16x16x32_bf16 v[50:53], v[26:29], v[50:53], 0
	v_mfma_f32_16x16x32_bf16 v[46:49], v[22:25], v[54:57], v[46:49]
	v_mfma_f32_16x16x32_bf16 v[50:53], v[30:33], v[54:57], v[50:53]
	v_mfma_f32_16x16x32_bf16 v[54:57], v[18:21], v[58:61], 0
	v_mfma_f32_16x16x32_bf16 v[58:61], v[26:29], v[58:61], 0
	v_mfma_f32_16x16x32_bf16 v[54:57], v[22:25], v[62:65], v[54:57]
	v_mfma_f32_16x16x32_bf16 v[58:61], v[30:33], v[62:65], v[58:61]
	s_setprio 0
	s_barrier
	ds_read_b128 v[62:65], v143 offset:16384
	ds_read_b128 v[90:93], v143 offset:17408
	ds_read_b128 v[94:97], v143 offset:18432
	ds_read_b128 v[106:109], v143 offset:19456
	ds_read_b128 v[110:113], v143 offset:20480
	ds_read_b128 v[118:121], v143 offset:21504
	ds_read_b128 v[122:125], v143 offset:22528
	ds_read_b128 v[126:129], v143 offset:23552
	s_mov_b32 m0, s55
	s_nop 0
	global_load_lds_dwordx4 v195, s[48:49]
	s_add_u32 m0, s55, 0x2000
	s_nop 0
	global_load_lds_dwordx4 v212, s[48:49]
	s_add_u32 s48, s24, 0x14000
	s_addc_u32 s49, s25, 0
	s_mov_b32 m0, s62
	s_nop 0
	global_load_lds_dwordx4 v195, s[48:49]
	s_add_u32 m0, s62, 0x2000
	s_nop 0
	global_load_lds_dwordx4 v212, s[48:49]
	s_nop 0
	s_mov_b32 m0, s54
	s_nop 0
	global_load_lds_dwordx4 v195, s[26:27]
	s_add_u32 m0, s54, 0x2000
	s_nop 0
	global_load_lds_dwordx4 v212, s[26:27]
	s_waitcnt vmcnt(8)
	s_waitcnt lgkmcnt(0)
	s_barrier
	s_setprio 1
	s_waitcnt lgkmcnt(7)
	v_mfma_f32_16x16x32_bf16 v[130:133], v[2:5], v[62:65], 0
	s_waitcnt lgkmcnt(5)
	v_mfma_f32_16x16x32_bf16 v[146:149], v[2:5], v[94:97], 0
	s_waitcnt lgkmcnt(3)
	v_mfma_f32_16x16x32_bf16 v[154:157], v[2:5], v[110:113], 0
	s_waitcnt lgkmcnt(1)
	v_mfma_f32_16x16x32_bf16 v[2:5], v[2:5], v[122:125], 0
	v_mfma_f32_16x16x32_bf16 v[130:133], v[6:9], v[90:93], v[130:133]
	v_mfma_f32_16x16x32_bf16 v[146:149], v[6:9], v[106:109], v[146:149]
	v_mfma_f32_16x16x32_bf16 v[154:157], v[6:9], v[118:121], v[154:157]
	s_waitcnt lgkmcnt(0)
	v_mfma_f32_16x16x32_bf16 v[2:5], v[6:9], v[126:129], v[2:5]
	v_mfma_f32_16x16x32_bf16 v[6:9], v[10:13], v[122:125], 0
	v_mfma_f32_16x16x32_bf16 v[134:137], v[10:13], v[62:65], 0
	v_mfma_f32_16x16x32_bf16 v[150:153], v[10:13], v[94:97], 0
	v_mfma_f32_16x16x32_bf16 v[158:161], v[10:13], v[110:113], 0
	v_mfma_f32_16x16x32_bf16 v[6:9], v[14:17], v[126:129], v[6:9]
	v_mfma_f32_16x16x32_bf16 v[134:137], v[14:17], v[90:93], v[134:137]
	v_mfma_f32_16x16x32_bf16 v[150:153], v[14:17], v[106:109], v[150:153]
	v_mfma_f32_16x16x32_bf16 v[158:161], v[14:17], v[118:121], v[158:161]
	s_setprio 0
	s_setprio 1
	v_mfma_f32_16x16x32_bf16 v[10:13], v[18:21], v[62:65], 0
	v_mfma_f32_16x16x32_bf16 v[162:165], v[22:25], v[90:93], v[10:13]
	v_mfma_f32_16x16x32_bf16 v[10:13], v[26:29], v[62:65], 0
	v_mfma_f32_16x16x32_bf16 v[166:169], v[30:33], v[90:93], v[10:13]
	v_mfma_f32_16x16x32_bf16 v[10:13], v[18:21], v[94:97], 0
	v_mfma_f32_16x16x32_bf16 v[170:173], v[22:25], v[106:109], v[10:13]
	v_mfma_f32_16x16x32_bf16 v[10:13], v[26:29], v[94:97], 0
	v_mfma_f32_16x16x32_bf16 v[174:177], v[30:33], v[106:109], v[10:13]
	v_mfma_f32_16x16x32_bf16 v[10:13], v[18:21], v[110:113], 0
	v_mfma_f32_16x16x32_bf16 v[178:181], v[22:25], v[118:121], v[10:13]
	v_mfma_f32_16x16x32_bf16 v[10:13], v[26:29], v[110:113], 0
	v_mfma_f32_16x16x32_bf16 v[182:185], v[30:33], v[118:121], v[10:13]
	v_mfma_f32_16x16x32_bf16 v[10:13], v[18:21], v[122:125], 0
	v_mfma_f32_16x16x32_bf16 v[186:189], v[22:25], v[126:129], v[10:13]
	v_mfma_f32_16x16x32_bf16 v[10:13], v[26:29], v[122:125], 0
	v_mfma_f32_16x16x32_bf16 v[190:193], v[30:33], v[126:129], v[10:13]
	s_setprio 0
	s_barrier
	s_nop 4
	ds_read_b128 v[10:13], v144
	ds_read_b128 v[14:17], v144 offset:1024
	ds_read_b128 v[18:21], v144 offset:2048
	ds_read_b128 v[22:25], v144 offset:3072
	ds_read_b128 v[198:201], v145
	ds_read_b128 v[202:205], v145 offset:1024
	ds_read_b128 v[206:209], v145 offset:2048
	ds_read_b128 v[214:217], v145 offset:3072
	ds_read_b128 v[26:29], v143 offset:32768
	ds_read_b128 v[30:33], v143 offset:33792
	ds_read_b128 v[62:65], v143 offset:34816
	ds_read_b128 v[218:221], v143 offset:35840
	ds_read_b128 v[222:225], v143 offset:36864
	ds_read_b128 v[226:229], v143 offset:37888
	ds_read_b128 v[230:233], v143 offset:38912
	ds_read_b128 v[234:237], v143 offset:39936
	s_add_u32 s28, s28, 0x14000
	s_addc_u32 s29, s29, 0
	s_mov_b32 m0, s63
	s_nop 0
	global_load_lds_dwordx4 v195, s[28:29]
	s_add_u32 m0, s63, 0x2000
	s_nop 0
	global_load_lds_dwordx4 v212, s[28:29]
	s_waitcnt vmcnt(8)
	s_waitcnt lgkmcnt(0)
	s_barrier
	s_setprio 1
	s_waitcnt lgkmcnt(7)
	v_mfma_f32_16x16x32_bf16 v[66:69], v[10:13], v[26:29], v[66:69]
	s_waitcnt lgkmcnt(6)
	v_mfma_f32_16x16x32_bf16 v[122:125], v[14:17], v[30:33], v[66:69]
	v_mfma_f32_16x16x32_bf16 v[66:69], v[18:21], v[26:29], v[70:73]
	v_mfma_f32_16x16x32_bf16 v[126:129], v[22:25], v[30:33], v[66:69]
	s_waitcnt lgkmcnt(5)
	v_mfma_f32_16x16x32_bf16 v[66:69], v[10:13], v[62:65], v[74:77]
	s_waitcnt lgkmcnt(4)
	v_mfma_f32_16x16x32_bf16 v[110:113], v[14:17], v[218:221], v[66:69]
	v_mfma_f32_16x16x32_bf16 v[66:69], v[18:21], v[62:65], v[78:81]
	v_mfma_f32_16x16x32_bf16 v[106:109], v[22:25], v[218:221], v[66:69]
	s_waitcnt lgkmcnt(3)
	v_mfma_f32_16x16x32_bf16 v[66:69], v[10:13], v[222:225], v[82:85]
	s_waitcnt lgkmcnt(2)
	v_mfma_f32_16x16x32_bf16 v[94:97], v[14:17], v[226:229], v[66:69]
	v_mfma_f32_16x16x32_bf16 v[66:69], v[18:21], v[222:225], v[86:89]
	v_mfma_f32_16x16x32_bf16 v[90:93], v[22:25], v[226:229], v[66:69]
	s_waitcnt lgkmcnt(1)
	v_mfma_f32_16x16x32_bf16 v[66:69], v[10:13], v[230:233], v[98:101]
	s_waitcnt lgkmcnt(0)
	v_mfma_f32_16x16x32_bf16 v[78:81], v[14:17], v[234:237], v[66:69]
	v_mfma_f32_16x16x32_bf16 v[66:69], v[18:21], v[230:233], v[102:105]
	v_mfma_f32_16x16x32_bf16 v[74:77], v[22:25], v[234:237], v[66:69]
	s_setprio 0
	s_setprio 1
	v_mfma_f32_16x16x32_bf16 v[66:69], v[198:201], v[26:29], v[114:117]
	v_mfma_f32_16x16x32_bf16 v[26:29], v[206:209], v[26:29], v[34:37]
	v_mfma_f32_16x16x32_bf16 v[118:121], v[214:217], v[30:33], v[26:29]
	v_mfma_f32_16x16x32_bf16 v[26:29], v[198:201], v[62:65], v[38:41]
	v_mfma_f32_16x16x32_bf16 v[98:101], v[202:205], v[218:221], v[26:29]
	v_mfma_f32_16x16x32_bf16 v[26:29], v[206:209], v[62:65], v[42:45]
	v_mfma_f32_16x16x32_bf16 v[102:105], v[214:217], v[218:221], v[26:29]
	v_mfma_f32_16x16x32_bf16 v[26:29], v[198:201], v[222:225], v[46:49]
	v_mfma_f32_16x16x32_bf16 v[82:85], v[202:205], v[226:229], v[26:29]
	v_mfma_f32_16x16x32_bf16 v[26:29], v[206:209], v[222:225], v[50:53]
	v_mfma_f32_16x16x32_bf16 v[86:89], v[214:217], v[226:229], v[26:29]
	v_mfma_f32_16x16x32_bf16 v[26:29], v[198:201], v[230:233], v[54:57]
	v_mfma_f32_16x16x32_bf16 v[114:117], v[202:205], v[30:33], v[66:69]
	v_mfma_f32_16x16x32_bf16 v[66:69], v[202:205], v[234:237], v[26:29]
	v_mfma_f32_16x16x32_bf16 v[26:29], v[206:209], v[230:233], v[58:61]
	v_mfma_f32_16x16x32_bf16 v[70:73], v[214:217], v[234:237], v[26:29]
	s_setprio 0
	s_barrier
	ds_read_b128 v[34:37], v143 offset:49152
	ds_read_b128 v[38:41], v143 offset:50176
	ds_read_b128 v[218:221], v143 offset:51200
	ds_read_b128 v[222:225], v143 offset:52224
	ds_read_b128 v[226:229], v143 offset:53248
	ds_read_b128 v[230:233], v143 offset:54272
	ds_read_b128 v[234:237], v143 offset:55296
	ds_read_b128 v[238:241], v143 offset:56320
	s_mov_b32 m0, s69
	s_nop 0
	global_load_lds_dwordx4 v195, s[38:39]
	s_add_u32 m0, s69, 0x2000
	s_nop 0
	global_load_lds_dwordx4 v212, s[38:39]
	s_add_u32 s28, s24, 0x1c000
	s_addc_u32 s29, s25, 0
	s_mov_b32 m0, s71
	s_nop 0
	global_load_lds_dwordx4 v195, s[28:29]
	s_add_u32 m0, s71, 0x2000
	s_nop 0
	global_load_lds_dwordx4 v212, s[28:29]
	s_nop 0
	s_mov_b32 m0, s70
	s_nop 0
	global_load_lds_dwordx4 v195, s[30:31]
	s_add_u32 m0, s70, 0x2000
	s_nop 0
	global_load_lds_dwordx4 v212, s[30:31]
	s_waitcnt vmcnt(8)
	s_waitcnt lgkmcnt(0)
	s_barrier
	s_setprio 1
	s_waitcnt lgkmcnt(7)
	v_mfma_f32_16x16x32_bf16 v[26:29], v[10:13], v[34:37], v[130:133]
	s_waitcnt lgkmcnt(6)
	v_mfma_f32_16x16x32_bf16 v[62:65], v[14:17], v[38:41], v[26:29]
	v_mfma_f32_16x16x32_bf16 v[26:29], v[18:21], v[34:37], v[134:137]
	v_mfma_f32_16x16x32_bf16 v[58:61], v[22:25], v[38:41], v[26:29]
	s_waitcnt lgkmcnt(5)
	v_mfma_f32_16x16x32_bf16 v[26:29], v[10:13], v[218:221], v[146:149]
	s_waitcnt lgkmcnt(4)
	v_mfma_f32_16x16x32_bf16 v[46:49], v[14:17], v[222:225], v[26:29]
	v_mfma_f32_16x16x32_bf16 v[26:29], v[18:21], v[218:221], v[150:153]
	v_mfma_f32_16x16x32_bf16 v[42:45], v[22:25], v[222:225], v[26:29]
	s_waitcnt lgkmcnt(3)
	v_mfma_f32_16x16x32_bf16 v[26:29], v[10:13], v[226:229], v[154:157]
	s_waitcnt lgkmcnt(1)
	v_mfma_f32_16x16x32_bf16 v[2:5], v[10:13], v[234:237], v[2:5]
	v_mfma_f32_16x16x32_bf16 v[30:33], v[14:17], v[230:233], v[26:29]
	v_mfma_f32_16x16x32_bf16 v[26:29], v[18:21], v[226:229], v[158:161]
	s_waitcnt lgkmcnt(0)
	v_mfma_f32_16x16x32_bf16 v[14:17], v[14:17], v[238:241], v[2:5]
	v_mfma_f32_16x16x32_bf16 v[2:5], v[18:21], v[234:237], v[6:9]
	v_mfma_f32_16x16x32_bf16 v[26:29], v[22:25], v[230:233], v[26:29]
	v_mfma_f32_16x16x32_bf16 v[10:13], v[22:25], v[238:241], v[2:5]
	s_setprio 0
	s_setprio 1
	v_mfma_f32_16x16x32_bf16 v[2:5], v[198:201], v[34:37], v[162:165]
	v_mfma_f32_16x16x32_bf16 v[50:53], v[202:205], v[38:41], v[2:5]
	v_mfma_f32_16x16x32_bf16 v[2:5], v[206:209], v[34:37], v[166:169]
	v_mfma_f32_16x16x32_bf16 v[54:57], v[214:217], v[38:41], v[2:5]
	v_mfma_f32_16x16x32_bf16 v[2:5], v[198:201], v[218:221], v[170:173]
	v_mfma_f32_16x16x32_bf16 v[34:37], v[202:205], v[222:225], v[2:5]
	v_mfma_f32_16x16x32_bf16 v[2:5], v[206:209], v[218:221], v[174:177]
	v_mfma_f32_16x16x32_bf16 v[38:41], v[214:217], v[222:225], v[2:5]
	v_mfma_f32_16x16x32_bf16 v[2:5], v[198:201], v[226:229], v[178:181]
	v_mfma_f32_16x16x32_bf16 v[18:21], v[202:205], v[230:233], v[2:5]
	v_mfma_f32_16x16x32_bf16 v[2:5], v[206:209], v[226:229], v[182:185]
	v_mfma_f32_16x16x32_bf16 v[22:25], v[214:217], v[230:233], v[2:5]
	v_mfma_f32_16x16x32_bf16 v[2:5], v[198:201], v[234:237], v[186:189]
	v_mfma_f32_16x16x32_bf16 v[6:9], v[206:209], v[234:237], v[190:193]
	v_mfma_f32_16x16x32_bf16 v[2:5], v[202:205], v[238:241], v[2:5]
	v_mfma_f32_16x16x32_bf16 v[6:9], v[214:217], v[238:241], v[6:9]
	s_setprio 0
	s_barrier
	s_add_u32 s75, s24, 0x20000
	s_addc_u32 s76, s25, 0
	s_mov_b32 s77, 0
.LBB0_519:
	ds_read_b128 v[130:133], v141
	ds_read_b128 v[134:137], v141 offset:1024
	ds_read_b128 v[146:149], v141 offset:2048
	ds_read_b128 v[150:153], v141 offset:3072
	ds_read_b128 v[154:157], v142
	ds_read_b128 v[158:161], v142 offset:1024
	ds_read_b128 v[162:165], v142 offset:2048
	ds_read_b128 v[166:169], v142 offset:3072
	s_add_u32 s24, s26, 0x10000
	s_addc_u32 s25, s27, 0
	s_cmp_eq_u32 s77, 12
	s_cselect_b32 s48, s17, s24
	s_cselect_b32 s49, s1, s25
	s_cselect_b32 s30, s23, s75
	s_cselect_b32 s31, s15, s76
	s_add_u32 s28, s48, 0x8000
	s_addc_u32 s29, s49, 0
	ds_read_b128 v[170:173], v143
	ds_read_b128 v[174:177], v143 offset:1024
	ds_read_b128 v[178:181], v143 offset:2048
	ds_read_b128 v[182:185], v143 offset:3072
	ds_read_b128 v[186:189], v143 offset:4096
	ds_read_b128 v[190:193], v143 offset:5120
	ds_read_b128 v[198:201], v143 offset:6144
	ds_read_b128 v[202:205], v143 offset:7168
	s_add_u32 s38, s30, 0x8000
	s_addc_u32 s39, s31, 0
	s_add_u32 s26, s26, 0xc000
	s_addc_u32 s27, s27, 0
	s_mov_b32 m0, s72
	s_nop 0
	global_load_lds_dwordx4 v195, s[26:27]
	s_add_u32 m0, s72, 0x2000
	s_nop 0
	global_load_lds_dwordx4 v212, s[26:27]
	s_waitcnt vmcnt(8)
	s_waitcnt lgkmcnt(0)
	s_barrier
	s_setprio 1
	s_waitcnt lgkmcnt(7)
	v_mfma_f32_16x16x32_bf16 v[122:125], v[130:133], v[170:173], v[122:125]
	v_mfma_f32_16x16x32_bf16 v[126:129], v[146:149], v[170:173], v[126:129]
	s_waitcnt lgkmcnt(5)
	v_mfma_f32_16x16x32_bf16 v[110:113], v[130:133], v[178:181], v[110:113]
	v_mfma_f32_16x16x32_bf16 v[106:109], v[146:149], v[178:181], v[106:109]
	s_waitcnt lgkmcnt(3)
	v_mfma_f32_16x16x32_bf16 v[94:97], v[130:133], v[186:189], v[94:97]
	v_mfma_f32_16x16x32_bf16 v[90:93], v[146:149], v[186:189], v[90:93]
	s_waitcnt lgkmcnt(1)
	v_mfma_f32_16x16x32_bf16 v[78:81], v[130:133], v[198:201], v[78:81]
	v_mfma_f32_16x16x32_bf16 v[74:77], v[146:149], v[198:201], v[74:77]
	v_mfma_f32_16x16x32_bf16 v[122:125], v[134:137], v[174:177], v[122:125]
	v_mfma_f32_16x16x32_bf16 v[126:129], v[150:153], v[174:177], v[126:129]
	v_mfma_f32_16x16x32_bf16 v[110:113], v[134:137], v[182:185], v[110:113]
	v_mfma_f32_16x16x32_bf16 v[106:109], v[150:153], v[182:185], v[106:109]
	v_mfma_f32_16x16x32_bf16 v[94:97], v[134:137], v[190:193], v[94:97]
	v_mfma_f32_16x16x32_bf16 v[90:93], v[150:153], v[190:193], v[90:93]
	s_waitcnt lgkmcnt(0)
	v_mfma_f32_16x16x32_bf16 v[78:81], v[134:137], v[202:205], v[78:81]
	v_mfma_f32_16x16x32_bf16 v[74:77], v[150:153], v[202:205], v[74:77]
	s_setprio 0
	s_setprio 1
	v_mfma_f32_16x16x32_bf16 v[114:117], v[154:157], v[170:173], v[114:117]
	v_mfma_f32_16x16x32_bf16 v[118:121], v[162:165], v[170:173], v[118:121]
	v_mfma_f32_16x16x32_bf16 v[98:101], v[154:157], v[178:181], v[98:101]
	v_mfma_f32_16x16x32_bf16 v[102:105], v[162:165], v[178:181], v[102:105]
	v_mfma_f32_16x16x32_bf16 v[82:85], v[154:157], v[186:189], v[82:85]
	v_mfma_f32_16x16x32_bf16 v[86:89], v[162:165], v[186:189], v[86:89]
	v_mfma_f32_16x16x32_bf16 v[66:69], v[154:157], v[198:201], v[66:69]
	v_mfma_f32_16x16x32_bf16 v[70:73], v[162:165], v[198:201], v[70:73]
	v_mfma_f32_16x16x32_bf16 v[114:117], v[158:161], v[174:177], v[114:117]
	v_mfma_f32_16x16x32_bf16 v[118:121], v[166:169], v[174:177], v[118:121]
	v_mfma_f32_16x16x32_bf16 v[98:101], v[158:161], v[182:185], v[98:101]
	v_mfma_f32_16x16x32_bf16 v[102:105], v[166:169], v[182:185], v[102:105]
	v_mfma_f32_16x16x32_bf16 v[82:85], v[158:161], v[190:193], v[82:85]
	v_mfma_f32_16x16x32_bf16 v[86:89], v[166:169], v[190:193], v[86:89]
	v_mfma_f32_16x16x32_bf16 v[66:69], v[158:161], v[202:205], v[66:69]
	v_mfma_f32_16x16x32_bf16 v[70:73], v[166:169], v[202:205], v[70:73]
	s_setprio 0
	s_barrier
	ds_read_b128 v[170:173], v143 offset:16384
	ds_read_b128 v[174:177], v143 offset:17408
	ds_read_b128 v[178:181], v143 offset:18432
	ds_read_b128 v[182:185], v143 offset:19456
	ds_read_b128 v[186:189], v143 offset:20480
	ds_read_b128 v[190:193], v143 offset:21504
	ds_read_b128 v[198:201], v143 offset:22528
	ds_read_b128 v[202:205], v143 offset:23552
	s_mov_b32 m0, s55
	s_nop 0
	global_load_lds_dwordx4 v195, s[30:31]
	s_add_u32 m0, s55, 0x2000
	s_nop 0
	global_load_lds_dwordx4 v212, s[30:31]
	s_add_u32 s26, s30, 0x4000
	s_addc_u32 s27, s31, 0
	s_mov_b32 m0, s62
	s_nop 0
	global_load_lds_dwordx4 v195, s[26:27]
	s_add_u32 m0, s62, 0x2000
	s_nop 0
	global_load_lds_dwordx4 v212, s[26:27]
	s_nop 0
	s_mov_b32 m0, s54
	s_nop 0
	global_load_lds_dwordx4 v195, s[48:49]
	s_add_u32 m0, s54, 0x2000
	s_nop 0
	global_load_lds_dwordx4 v212, s[48:49]
	s_waitcnt vmcnt(8)
	s_waitcnt lgkmcnt(0)
	s_barrier
	s_setprio 1
	s_waitcnt lgkmcnt(7)
	v_mfma_f32_16x16x32_bf16 v[62:65], v[130:133], v[170:173], v[62:65]
	v_mfma_f32_16x16x32_bf16 v[58:61], v[146:149], v[170:173], v[58:61]
	s_waitcnt lgkmcnt(5)
	v_mfma_f32_16x16x32_bf16 v[46:49], v[130:133], v[178:181], v[46:49]
	v_mfma_f32_16x16x32_bf16 v[42:45], v[146:149], v[178:181], v[42:45]
	s_waitcnt lgkmcnt(3)
	v_mfma_f32_16x16x32_bf16 v[30:33], v[130:133], v[186:189], v[30:33]
	v_mfma_f32_16x16x32_bf16 v[26:29], v[146:149], v[186:189], v[26:29]
	s_waitcnt lgkmcnt(1)
	v_mfma_f32_16x16x32_bf16 v[14:17], v[130:133], v[198:201], v[14:17]
	v_mfma_f32_16x16x32_bf16 v[10:13], v[146:149], v[198:201], v[10:13]
	v_mfma_f32_16x16x32_bf16 v[62:65], v[134:137], v[174:177], v[62:65]
	v_mfma_f32_16x16x32_bf16 v[58:61], v[150:153], v[174:177], v[58:61]
	v_mfma_f32_16x16x32_bf16 v[46:49], v[134:137], v[182:185], v[46:49]
	v_mfma_f32_16x16x32_bf16 v[42:45], v[150:153], v[182:185], v[42:45]
	v_mfma_f32_16x16x32_bf16 v[30:33], v[134:137], v[190:193], v[30:33]
	v_mfma_f32_16x16x32_bf16 v[26:29], v[150:153], v[190:193], v[26:29]
	s_waitcnt lgkmcnt(0)
	v_mfma_f32_16x16x32_bf16 v[14:17], v[134:137], v[202:205], v[14:17]
	v_mfma_f32_16x16x32_bf16 v[10:13], v[150:153], v[202:205], v[10:13]
	s_setprio 0
	s_setprio 1
	v_mfma_f32_16x16x32_bf16 v[50:53], v[154:157], v[170:173], v[50:53]
	v_mfma_f32_16x16x32_bf16 v[54:57], v[162:165], v[170:173], v[54:57]
	v_mfma_f32_16x16x32_bf16 v[34:37], v[154:157], v[178:181], v[34:37]
	v_mfma_f32_16x16x32_bf16 v[38:41], v[162:165], v[178:181], v[38:41]
	v_mfma_f32_16x16x32_bf16 v[18:21], v[154:157], v[186:189], v[18:21]
	v_mfma_f32_16x16x32_bf16 v[22:25], v[162:165], v[186:189], v[22:25]
	v_mfma_f32_16x16x32_bf16 v[2:5], v[154:157], v[198:201], v[2:5]
	v_mfma_f32_16x16x32_bf16 v[6:9], v[162:165], v[198:201], v[6:9]
	v_mfma_f32_16x16x32_bf16 v[50:53], v[158:161], v[174:177], v[50:53]
	v_mfma_f32_16x16x32_bf16 v[54:57], v[166:169], v[174:177], v[54:57]
	v_mfma_f32_16x16x32_bf16 v[34:37], v[158:161], v[182:185], v[34:37]
	v_mfma_f32_16x16x32_bf16 v[38:41], v[166:169], v[182:185], v[38:41]
	v_mfma_f32_16x16x32_bf16 v[18:21], v[158:161], v[190:193], v[18:21]
	v_mfma_f32_16x16x32_bf16 v[22:25], v[166:169], v[190:193], v[22:25]
	v_mfma_f32_16x16x32_bf16 v[2:5], v[158:161], v[202:205], v[2:5]
	v_mfma_f32_16x16x32_bf16 v[6:9], v[166:169], v[202:205], v[6:9]
	s_setprio 0
	s_barrier
	ds_read_b128 v[130:133], v144
	ds_read_b128 v[134:137], v144 offset:1024
	ds_read_b128 v[146:149], v144 offset:2048
	ds_read_b128 v[150:153], v144 offset:3072
	ds_read_b128 v[154:157], v145
	ds_read_b128 v[158:161], v145 offset:1024
	ds_read_b128 v[162:165], v145 offset:2048
	ds_read_b128 v[166:169], v145 offset:3072
	ds_read_b128 v[170:173], v143 offset:32768
	ds_read_b128 v[174:177], v143 offset:33792
	ds_read_b128 v[178:181], v143 offset:34816
	ds_read_b128 v[182:185], v143 offset:35840
	ds_read_b128 v[186:189], v143 offset:36864
	ds_read_b128 v[190:193], v143 offset:37888
	ds_read_b128 v[198:201], v143 offset:38912
	ds_read_b128 v[202:205], v143 offset:39936
	s_add_u32 s26, s48, 0x4000
	s_addc_u32 s27, s49, 0
	s_mov_b32 m0, s63
	s_nop 0
	global_load_lds_dwordx4 v195, s[26:27]
	s_add_u32 m0, s63, 0x2000
	s_nop 0
	global_load_lds_dwordx4 v212, s[26:27]
	s_waitcnt vmcnt(8)
	s_waitcnt lgkmcnt(0)
	s_barrier
	s_setprio 1
	s_waitcnt lgkmcnt(7)
	v_mfma_f32_16x16x32_bf16 v[122:125], v[130:133], v[170:173], v[122:125]
	v_mfma_f32_16x16x32_bf16 v[126:129], v[146:149], v[170:173], v[126:129]
	s_waitcnt lgkmcnt(5)
	v_mfma_f32_16x16x32_bf16 v[110:113], v[130:133], v[178:181], v[110:113]
	v_mfma_f32_16x16x32_bf16 v[106:109], v[146:149], v[178:181], v[106:109]
	s_waitcnt lgkmcnt(3)
	v_mfma_f32_16x16x32_bf16 v[94:97], v[130:133], v[186:189], v[94:97]
	v_mfma_f32_16x16x32_bf16 v[90:93], v[146:149], v[186:189], v[90:93]
	s_waitcnt lgkmcnt(1)
	v_mfma_f32_16x16x32_bf16 v[78:81], v[130:133], v[198:201], v[78:81]
	v_mfma_f32_16x16x32_bf16 v[74:77], v[146:149], v[198:201], v[74:77]
	v_mfma_f32_16x16x32_bf16 v[122:125], v[134:137], v[174:177], v[122:125]
	v_mfma_f32_16x16x32_bf16 v[126:129], v[150:153], v[174:177], v[126:129]
	v_mfma_f32_16x16x32_bf16 v[110:113], v[134:137], v[182:185], v[110:113]
	v_mfma_f32_16x16x32_bf16 v[106:109], v[150:153], v[182:185], v[106:109]
	v_mfma_f32_16x16x32_bf16 v[94:97], v[134:137], v[190:193], v[94:97]
	v_mfma_f32_16x16x32_bf16 v[90:93], v[150:153], v[190:193], v[90:93]
	s_waitcnt lgkmcnt(0)
	v_mfma_f32_16x16x32_bf16 v[78:81], v[134:137], v[202:205], v[78:81]
	v_mfma_f32_16x16x32_bf16 v[74:77], v[150:153], v[202:205], v[74:77]
	s_setprio 0
	s_setprio 1
	v_mfma_f32_16x16x32_bf16 v[114:117], v[154:157], v[170:173], v[114:117]
	v_mfma_f32_16x16x32_bf16 v[118:121], v[162:165], v[170:173], v[118:121]
	v_mfma_f32_16x16x32_bf16 v[98:101], v[154:157], v[178:181], v[98:101]
	v_mfma_f32_16x16x32_bf16 v[102:105], v[162:165], v[178:181], v[102:105]
	v_mfma_f32_16x16x32_bf16 v[82:85], v[154:157], v[186:189], v[82:85]
	v_mfma_f32_16x16x32_bf16 v[86:89], v[162:165], v[186:189], v[86:89]
	v_mfma_f32_16x16x32_bf16 v[66:69], v[154:157], v[198:201], v[66:69]
	v_mfma_f32_16x16x32_bf16 v[70:73], v[162:165], v[198:201], v[70:73]
	v_mfma_f32_16x16x32_bf16 v[114:117], v[158:161], v[174:177], v[114:117]
	v_mfma_f32_16x16x32_bf16 v[118:121], v[166:169], v[174:177], v[118:121]
	v_mfma_f32_16x16x32_bf16 v[98:101], v[158:161], v[182:185], v[98:101]
	v_mfma_f32_16x16x32_bf16 v[102:105], v[166:169], v[182:185], v[102:105]
	v_mfma_f32_16x16x32_bf16 v[82:85], v[158:161], v[190:193], v[82:85]
	v_mfma_f32_16x16x32_bf16 v[86:89], v[166:169], v[190:193], v[86:89]
	v_mfma_f32_16x16x32_bf16 v[66:69], v[158:161], v[202:205], v[66:69]
	v_mfma_f32_16x16x32_bf16 v[70:73], v[166:169], v[202:205], v[70:73]
	s_setprio 0
	s_barrier
	ds_read_b128 v[170:173], v143 offset:49152
	ds_read_b128 v[174:177], v143 offset:50176
	ds_read_b128 v[178:181], v143 offset:51200
	ds_read_b128 v[182:185], v143 offset:52224
	ds_read_b128 v[186:189], v143 offset:53248
	ds_read_b128 v[190:193], v143 offset:54272
	ds_read_b128 v[198:201], v143 offset:55296
	ds_read_b128 v[202:205], v143 offset:56320
	s_mov_b32 m0, s69
	s_nop 0
	global_load_lds_dwordx4 v195, s[38:39]
	s_add_u32 m0, s69, 0x2000
	s_nop 0
	global_load_lds_dwordx4 v212, s[38:39]
	s_add_u32 s26, s30, 0xc000
	s_addc_u32 s27, s31, 0
	s_mov_b32 m0, s71
	s_nop 0
	global_load_lds_dwordx4 v195, s[26:27]
	s_add_u32 m0, s71, 0x2000
	s_nop 0
	global_load_lds_dwordx4 v212, s[26:27]
	s_nop 0
	s_mov_b32 m0, s70
	s_nop 0
	global_load_lds_dwordx4 v195, s[28:29]
	s_add_u32 m0, s70, 0x2000
	s_nop 0
	global_load_lds_dwordx4 v212, s[28:29]
	s_waitcnt vmcnt(8)
	s_waitcnt lgkmcnt(0)
	s_barrier
	s_setprio 1
	s_waitcnt lgkmcnt(7)
	v_mfma_f32_16x16x32_bf16 v[62:65], v[130:133], v[170:173], v[62:65]
	v_mfma_f32_16x16x32_bf16 v[58:61], v[146:149], v[170:173], v[58:61]
	s_waitcnt lgkmcnt(5)
	v_mfma_f32_16x16x32_bf16 v[46:49], v[130:133], v[178:181], v[46:49]
	v_mfma_f32_16x16x32_bf16 v[42:45], v[146:149], v[178:181], v[42:45]
	s_waitcnt lgkmcnt(3)
	v_mfma_f32_16x16x32_bf16 v[30:33], v[130:133], v[186:189], v[30:33]
	v_mfma_f32_16x16x32_bf16 v[26:29], v[146:149], v[186:189], v[26:29]
	s_waitcnt lgkmcnt(1)
	v_mfma_f32_16x16x32_bf16 v[14:17], v[130:133], v[198:201], v[14:17]
	v_mfma_f32_16x16x32_bf16 v[10:13], v[146:149], v[198:201], v[10:13]
	v_mfma_f32_16x16x32_bf16 v[62:65], v[134:137], v[174:177], v[62:65]
	v_mfma_f32_16x16x32_bf16 v[58:61], v[150:153], v[174:177], v[58:61]
	v_mfma_f32_16x16x32_bf16 v[46:49], v[134:137], v[182:185], v[46:49]
	v_mfma_f32_16x16x32_bf16 v[42:45], v[150:153], v[182:185], v[42:45]
	v_mfma_f32_16x16x32_bf16 v[30:33], v[134:137], v[190:193], v[30:33]
	v_mfma_f32_16x16x32_bf16 v[26:29], v[150:153], v[190:193], v[26:29]
	s_waitcnt lgkmcnt(0)
	v_mfma_f32_16x16x32_bf16 v[14:17], v[134:137], v[202:205], v[14:17]
	v_mfma_f32_16x16x32_bf16 v[10:13], v[150:153], v[202:205], v[10:13]
	s_setprio 0
	s_setprio 1
	v_mfma_f32_16x16x32_bf16 v[50:53], v[154:157], v[170:173], v[50:53]
	v_mfma_f32_16x16x32_bf16 v[54:57], v[162:165], v[170:173], v[54:57]
	v_mfma_f32_16x16x32_bf16 v[34:37], v[154:157], v[178:181], v[34:37]
	v_mfma_f32_16x16x32_bf16 v[38:41], v[162:165], v[178:181], v[38:41]
	v_mfma_f32_16x16x32_bf16 v[18:21], v[154:157], v[186:189], v[18:21]
	v_mfma_f32_16x16x32_bf16 v[22:25], v[162:165], v[186:189], v[22:25]
	v_mfma_f32_16x16x32_bf16 v[2:5], v[154:157], v[198:201], v[2:5]
	v_mfma_f32_16x16x32_bf16 v[6:9], v[162:165], v[198:201], v[6:9]
	v_mfma_f32_16x16x32_bf16 v[50:53], v[158:161], v[174:177], v[50:53]
	v_mfma_f32_16x16x32_bf16 v[54:57], v[166:169], v[174:177], v[54:57]
	v_mfma_f32_16x16x32_bf16 v[34:37], v[158:161], v[182:185], v[34:37]
	v_mfma_f32_16x16x32_bf16 v[38:41], v[166:169], v[182:185], v[38:41]
	v_mfma_f32_16x16x32_bf16 v[18:21], v[158:161], v[190:193], v[18:21]
	v_mfma_f32_16x16x32_bf16 v[22:25], v[166:169], v[190:193], v[22:25]
	v_mfma_f32_16x16x32_bf16 v[2:5], v[158:161], v[202:205], v[2:5]
	v_mfma_f32_16x16x32_bf16 v[6:9], v[166:169], v[202:205], v[6:9]
	s_setprio 0
	s_barrier
	s_add_i32 s77, s77, 2
	s_add_u32 s75, s75, 0x10000
	s_addc_u32 s76, s76, 0
	s_cmp_gt_u32 s77, 13
	s_mov_b64 s[26:27], s[24:25]
	s_cbranch_scc0 .LBB0_519
	s_and_b64 vcc, exec, s[10:11]
	s_cbranch_vccz .LBB0_522
	s_barrier

.LBB0_524:
	s_and_b64 s[0:1], s[24:25], exec
	s_mov_b32 s0, 0x842c000
	s_cselect_b32 s0, s0, 0x8c2c000
	s_add_u32 s0, s84, s0
	v_lshlrev_b32_e32 v134, 2, v134
	s_addc_u32 s1, s85, 0
	v_ashrrev_i32_e32 v135, 31, v134
	v_lshl_add_u64 v[134:135], v[134:135], 2, s[0:1]
	v_lshlrev_b64 v[136:137], 12, v[130:131]
	v_lshl_add_u64 v[136:137], v[134:135], 0, v[136:137]
	v_permlane16_swap_b32_e32 v122, v126
	v_permlane16_swap_b32_e32 v123, v127
	v_permlane16_swap_b32_e32 v124, v128
	v_permlane16_swap_b32_e32 v125, v129
	s_ashr_i32 s23, s22, 31
	v_permlane32_swap_b32_e32 v122, v126
	v_permlane32_swap_b32_e32 v123, v127
	v_permlane32_swap_b32_e32 v124, v128
	v_permlane32_swap_b32_e32 v125, v129
	v_lshl_add_u64 v[148:149], s[22:23], 2, v[136:137]
	v_lshl_add_u64 v[152:153], v[148:149], 0, 0
	s_andn2_b64 vcc, exec, s[26:27]
	s_mov_b64 s[0:1], -1
	global_store_dwordx4 v[148:149], v[122:125], off
	s_mov_b32 s98, 0x1000
	s_mov_b32 s99, 0x0
	v_lshl_add_u64 v[154:155], v[152:153], 0, s[98:99]
	global_store_dwordx4 v[154:155], v[126:129], off offset:-4032
	s_cbranch_vccnz .LBB0_526
	s_mov_b64 s[0:1], 0
.LBB0_526:
	s_andn2_b64 vcc, exec, s[0:1]
	s_cbranch_vccnz .LBB0_528
	v_cvt_pk_bf16_f32 v122, v114, v115
	v_cvt_pk_bf16_f32 v123, v116, v117
	v_cvt_pk_bf16_f32 v124, v118, v119
	v_cvt_pk_bf16_f32 v125, v120, v121
	v_lshl_add_u64 v[126:127], v[132:133], 1, v[138:139]
	s_mov_b32 s98, 0x100
	s_mov_b32 s99, 0x0
	s_nop 0
	global_store_dwordx4 v[126:127], v[122:125], off offset:256
.LBB0_528:
	s_nop 1
	v_ashrrev_i32_e32 v123, 31, v146
	v_sub_co_u32_e32 v122, vcc, v132, v146
	v_permlane16_swap_b32_e32 v114, v118
	v_permlane16_swap_b32_e32 v115, v119
	v_permlane16_swap_b32_e32 v116, v120
	v_permlane16_swap_b32_e32 v117, v121
	v_subb_co_u32_e32 v123, vcc, v133, v123, vcc
	v_permlane32_swap_b32_e32 v114, v118
	v_permlane32_swap_b32_e32 v115, v119
	v_permlane32_swap_b32_e32 v116, v120
	v_permlane32_swap_b32_e32 v117, v121
	v_lshl_add_u64 v[124:125], v[122:123], 2, v[136:137]
	global_store_dwordx4 v[124:125], v[114:117], off offset:512
	global_store_dwordx4 v[124:125], v[118:121], off offset:576
	s_andn2_b64 vcc, exec, s[24:25]
	v_add_u32_e32 v114, 16, v130
	v_ashrrev_i32_e32 v115, 31, v114
	v_lshlrev_b64 v[116:117], 11, v[114:115]
	v_cndmask_b32_e64 v118, 0, 1, s[24:25]
	v_lshl_add_u64 v[116:117], s[6:7], 0, v[116:117]
	v_cmp_ne_u32_e64 s[0:1], 1, v118
	v_lshl_add_u64 v[116:117], v[132:133], 1, v[116:117]
	s_cbranch_vccnz .LBB0_530
	v_cvt_pk_bf16_f32 v118, v110, v111
	v_cvt_pk_bf16_f32 v119, v112, v113
	v_cvt_pk_bf16_f32 v120, v106, v107
	v_cvt_pk_bf16_f32 v121, v108, v109
	s_nop 0
	global_store_dwordx4 v[116:117], v[118:121], off
.LBB0_530:
	v_lshlrev_b64 v[114:115], 12, v[114:115]
	v_lshl_add_u64 v[114:115], v[134:135], 0, v[114:115]
	v_permlane16_swap_b32_e32 v110, v106
	v_permlane16_swap_b32_e32 v111, v107
	v_permlane16_swap_b32_e32 v112, v108
	v_permlane16_swap_b32_e32 v113, v109
	v_permlane32_swap_b32_e32 v110, v106
	v_permlane32_swap_b32_e32 v111, v107
	v_permlane32_swap_b32_e32 v112, v108
	v_permlane32_swap_b32_e32 v113, v109
	v_lshl_add_u64 v[118:119], s[22:23], 2, v[114:115]
	s_mov_b32 s98, 0x11000
	s_mov_b32 s99, 0x0
	v_lshl_add_u64 v[154:155], v[152:153], 0, s[98:99]
	s_and_b64 vcc, exec, s[0:1]
	global_store_dwordx4 v[154:155], v[110:113], off offset:-4096
	global_store_dwordx4 v[154:155], v[106:109], off offset:-4032
	s_cbranch_vccnz .LBB0_532
	s_nop 0
	v_cvt_pk_bf16_f32 v106, v98, v99
	v_cvt_pk_bf16_f32 v107, v100, v101
	v_cvt_pk_bf16_f32 v108, v102, v103
	v_cvt_pk_bf16_f32 v109, v104, v105
	s_mov_b32 s98, 0x100
	s_mov_b32 s99, 0x0
	v_lshl_add_u64 v[154:155], v[116:117], 0, s[98:99]
	global_store_dwordx4 v[116:117], v[106:109], off offset:256
.LBB0_532:
	v_permlane16_swap_b32_e32 v98, v102
	v_permlane16_swap_b32_e32 v99, v103
	v_permlane16_swap_b32_e32 v100, v104
	v_permlane16_swap_b32_e32 v101, v105
	v_permlane32_swap_b32_e32 v98, v102
	v_permlane32_swap_b32_e32 v99, v103
	v_permlane32_swap_b32_e32 v100, v104
	v_permlane32_swap_b32_e32 v101, v105
	v_lshl_add_u64 v[106:107], v[122:123], 2, v[114:115]
	global_store_dwordx4 v[106:107], v[98:101], off offset:512
	global_store_dwordx4 v[106:107], v[102:105], off offset:576
	s_and_b64 vcc, exec, s[0:1]
	v_add_u32_e32 v98, 32, v130
	v_ashrrev_i32_e32 v99, 31, v98
	v_lshlrev_b64 v[100:101], 11, v[98:99]
	v_lshl_add_u64 v[100:101], s[6:7], 0, v[100:101]
	v_lshl_add_u64 v[100:101], v[132:133], 1, v[100:101]
	s_cbranch_vccnz .LBB0_534
	v_cvt_pk_bf16_f32 v102, v94, v95
	v_cvt_pk_bf16_f32 v103, v96, v97
	v_cvt_pk_bf16_f32 v104, v90, v91
	v_cvt_pk_bf16_f32 v105, v92, v93
	v_lshl_add_u64 v[154:155], v[100:101], 0, 0
	global_store_dwordx4 v[100:101], v[102:105], off
.LBB0_534:
	v_lshlrev_b64 v[98:99], 12, v[98:99]
	v_lshl_add_u64 v[98:99], v[134:135], 0, v[98:99]
	v_permlane16_swap_b32_e32 v94, v90
	v_permlane16_swap_b32_e32 v95, v91
	v_permlane16_swap_b32_e32 v96, v92
	v_permlane16_swap_b32_e32 v97, v93
	v_permlane32_swap_b32_e32 v94, v90
	v_permlane32_swap_b32_e32 v95, v91
	v_permlane32_swap_b32_e32 v96, v92
	v_permlane32_swap_b32_e32 v97, v93
	v_lshl_add_u64 v[102:103], s[22:23], 2, v[98:99]
	s_mov_b32 s98, 0x21000
	s_mov_b32 s99, 0x0
	v_lshl_add_u64 v[154:155], v[152:153], 0, s[98:99]
	s_and_b64 vcc, exec, s[0:1]
	global_store_dwordx4 v[154:155], v[94:97], off offset:-4096
	global_store_dwordx4 v[154:155], v[90:93], off offset:-4032
	s_cbranch_vccnz .LBB0_536
	s_nop 0
	v_cvt_pk_bf16_f32 v90, v82, v83
	v_cvt_pk_bf16_f32 v91, v84, v85
	v_cvt_pk_bf16_f32 v92, v86, v87
	v_cvt_pk_bf16_f32 v93, v88, v89
	s_mov_b32 s98, 0x100
	s_mov_b32 s99, 0x0
	v_lshl_add_u64 v[154:155], v[100:101], 0, s[98:99]
	global_store_dwordx4 v[100:101], v[90:93], off offset:256
.LBB0_536:
	v_permlane16_swap_b32_e32 v82, v86
	v_permlane16_swap_b32_e32 v83, v87
	v_permlane16_swap_b32_e32 v84, v88
	v_permlane16_swap_b32_e32 v85, v89
	v_permlane32_swap_b32_e32 v82, v86
	v_permlane32_swap_b32_e32 v83, v87
	v_permlane32_swap_b32_e32 v84, v88
	v_permlane32_swap_b32_e32 v85, v89
	v_lshl_add_u64 v[90:91], v[122:123], 2, v[98:99]
	global_store_dwordx4 v[90:91], v[82:85], off offset:512
	global_store_dwordx4 v[90:91], v[86:89], off offset:576
	s_and_b64 vcc, exec, s[0:1]
	v_add_u32_e32 v82, 48, v130
	v_ashrrev_i32_e32 v83, 31, v82
	v_lshlrev_b64 v[84:85], 11, v[82:83]
	v_lshl_add_u64 v[84:85], s[6:7], 0, v[84:85]
	v_lshl_add_u64 v[84:85], v[132:133], 1, v[84:85]
	s_cbranch_vccnz .LBB0_538
	v_cvt_pk_bf16_f32 v86, v78, v79
	v_cvt_pk_bf16_f32 v87, v80, v81
	v_cvt_pk_bf16_f32 v88, v74, v75
	v_cvt_pk_bf16_f32 v89, v76, v77
	v_lshl_add_u64 v[154:155], v[84:85], 0, 0
	global_store_dwordx4 v[84:85], v[86:89], off
.LBB0_538:
	v_lshlrev_b64 v[82:83], 12, v[82:83]
	v_lshl_add_u64 v[82:83], v[134:135], 0, v[82:83]
	v_permlane16_swap_b32_e32 v78, v74
	v_permlane16_swap_b32_e32 v79, v75
	v_permlane16_swap_b32_e32 v80, v76
	v_permlane16_swap_b32_e32 v81, v77
	v_permlane32_swap_b32_e32 v78, v74
	v_permlane32_swap_b32_e32 v79, v75
	v_permlane32_swap_b32_e32 v80, v76
	v_permlane32_swap_b32_e32 v81, v77
	v_lshl_add_u64 v[86:87], s[22:23], 2, v[82:83]
	s_mov_b32 s98, 0x31000
	s_mov_b32 s99, 0x0
	v_lshl_add_u64 v[154:155], v[152:153], 0, s[98:99]
	s_and_b64 vcc, exec, s[0:1]
	global_store_dwordx4 v[154:155], v[78:81], off offset:-4096
	global_store_dwordx4 v[154:155], v[74:77], off offset:-4032
	s_cbranch_vccnz .LBB0_540
	s_nop 0
	v_cvt_pk_bf16_f32 v74, v66, v67
	v_cvt_pk_bf16_f32 v75, v68, v69
	v_cvt_pk_bf16_f32 v76, v70, v71
	v_cvt_pk_bf16_f32 v77, v72, v73
	s_mov_b32 s98, 0x100
	s_mov_b32 s99, 0x0
	v_lshl_add_u64 v[154:155], v[84:85], 0, s[98:99]
	global_store_dwordx4 v[84:85], v[74:77], off offset:256
.LBB0_540:
	v_permlane16_swap_b32_e32 v66, v70
	v_permlane16_swap_b32_e32 v67, v71
	v_permlane16_swap_b32_e32 v68, v72
	v_permlane16_swap_b32_e32 v69, v73
	v_permlane32_swap_b32_e32 v66, v70
	v_permlane32_swap_b32_e32 v67, v71
	v_permlane32_swap_b32_e32 v68, v72
	v_permlane32_swap_b32_e32 v69, v73
	v_lshl_add_u64 v[74:75], v[122:123], 2, v[82:83]
	global_store_dwordx4 v[74:75], v[66:69], off offset:512
	global_store_dwordx4 v[74:75], v[70:73], off offset:576
	s_and_b64 vcc, exec, s[0:1]
	v_add_u32_e32 v66, 0x80, v130
	v_ashrrev_i32_e32 v67, 31, v66
	v_lshlrev_b64 v[68:69], 11, v[66:67]
	v_lshl_add_u64 v[68:69], s[6:7], 0, v[68:69]
	v_lshl_add_u64 v[68:69], v[132:133], 1, v[68:69]
	s_cbranch_vccnz .LBB0_542
	v_cvt_pk_bf16_f32 v70, v62, v63
	v_cvt_pk_bf16_f32 v71, v64, v65
	v_cvt_pk_bf16_f32 v72, v58, v59
	v_cvt_pk_bf16_f32 v73, v60, v61
	v_lshl_add_u64 v[154:155], v[68:69], 0, 0
	global_store_dwordx4 v[68:69], v[70:73], off
.LBB0_542:
	v_lshlrev_b64 v[66:67], 12, v[66:67]
	v_lshl_add_u64 v[66:67], v[134:135], 0, v[66:67]
	v_permlane16_swap_b32_e32 v62, v58
	v_permlane16_swap_b32_e32 v63, v59
	v_permlane16_swap_b32_e32 v64, v60
	v_permlane16_swap_b32_e32 v65, v61
	v_permlane32_swap_b32_e32 v62, v58
	v_permlane32_swap_b32_e32 v63, v59
	v_permlane32_swap_b32_e32 v64, v60
	v_permlane32_swap_b32_e32 v65, v61
	v_lshl_add_u64 v[70:71], s[22:23], 2, v[66:67]
	s_mov_b32 s98, 0x81000
	s_mov_b32 s99, 0x0
	v_lshl_add_u64 v[154:155], v[152:153], 0, s[98:99]
	s_and_b64 vcc, exec, s[0:1]
	global_store_dwordx4 v[154:155], v[62:65], off offset:-4096
	global_store_dwordx4 v[154:155], v[58:61], off offset:-4032
	s_cbranch_vccnz .LBB0_544
	s_nop 0
	v_cvt_pk_bf16_f32 v58, v50, v51
	v_cvt_pk_bf16_f32 v59, v52, v53
	v_cvt_pk_bf16_f32 v60, v54, v55
	v_cvt_pk_bf16_f32 v61, v56, v57
	s_mov_b32 s98, 0x100
	s_mov_b32 s99, 0x0
	v_lshl_add_u64 v[154:155], v[68:69], 0, s[98:99]
	global_store_dwordx4 v[68:69], v[58:61], off offset:256
.LBB0_544:
	v_permlane16_swap_b32_e32 v50, v54
	v_permlane16_swap_b32_e32 v51, v55
	v_permlane16_swap_b32_e32 v52, v56
	v_permlane16_swap_b32_e32 v53, v57
	v_permlane32_swap_b32_e32 v50, v54
	v_permlane32_swap_b32_e32 v51, v55
	v_permlane32_swap_b32_e32 v52, v56
	v_permlane32_swap_b32_e32 v53, v57
	v_lshl_add_u64 v[58:59], v[122:123], 2, v[66:67]
	global_store_dwordx4 v[58:59], v[50:53], off offset:512
	global_store_dwordx4 v[58:59], v[54:57], off offset:576
	s_and_b64 vcc, exec, s[0:1]
	v_add_u32_e32 v50, 0x90, v130
	v_ashrrev_i32_e32 v51, 31, v50
	v_lshlrev_b64 v[52:53], 11, v[50:51]
	v_lshl_add_u64 v[52:53], s[6:7], 0, v[52:53]
	v_lshl_add_u64 v[52:53], v[132:133], 1, v[52:53]
	s_cbranch_vccnz .LBB0_546
	v_cvt_pk_bf16_f32 v54, v46, v47
	v_cvt_pk_bf16_f32 v55, v48, v49
	v_cvt_pk_bf16_f32 v56, v42, v43
	v_cvt_pk_bf16_f32 v57, v44, v45
	v_lshl_add_u64 v[154:155], v[52:53], 0, 0
	global_store_dwordx4 v[52:53], v[54:57], off
.LBB0_546:
	v_lshlrev_b64 v[50:51], 12, v[50:51]
	v_lshl_add_u64 v[50:51], v[134:135], 0, v[50:51]
	v_permlane16_swap_b32_e32 v46, v42
	v_permlane16_swap_b32_e32 v47, v43
	v_permlane16_swap_b32_e32 v48, v44
	v_permlane16_swap_b32_e32 v49, v45
	v_permlane32_swap_b32_e32 v46, v42
	v_permlane32_swap_b32_e32 v47, v43
	v_permlane32_swap_b32_e32 v48, v44
	v_permlane32_swap_b32_e32 v49, v45
	v_lshl_add_u64 v[54:55], s[22:23], 2, v[50:51]
	s_mov_b32 s98, 0x91000
	s_mov_b32 s99, 0x0
	v_lshl_add_u64 v[154:155], v[152:153], 0, s[98:99]
	s_and_b64 vcc, exec, s[0:1]
	global_store_dwordx4 v[154:155], v[46:49], off offset:-4096
	global_store_dwordx4 v[154:155], v[42:45], off offset:-4032
	s_cbranch_vccnz .LBB0_548
	s_nop 0
	v_cvt_pk_bf16_f32 v42, v34, v35
	v_cvt_pk_bf16_f32 v43, v36, v37
	v_cvt_pk_bf16_f32 v44, v38, v39
	v_cvt_pk_bf16_f32 v45, v40, v41
	s_mov_b32 s98, 0x100
	s_mov_b32 s99, 0x0
	v_lshl_add_u64 v[154:155], v[52:53], 0, s[98:99]
	global_store_dwordx4 v[52:53], v[42:45], off offset:256
.LBB0_548:
	v_permlane16_swap_b32_e32 v34, v38
	v_permlane16_swap_b32_e32 v35, v39
	v_permlane16_swap_b32_e32 v36, v40
	v_permlane16_swap_b32_e32 v37, v41
	v_permlane32_swap_b32_e32 v34, v38
	v_permlane32_swap_b32_e32 v35, v39
	v_permlane32_swap_b32_e32 v36, v40
	v_permlane32_swap_b32_e32 v37, v41
	v_lshl_add_u64 v[42:43], v[122:123], 2, v[50:51]
	global_store_dwordx4 v[42:43], v[34:37], off offset:512
	global_store_dwordx4 v[42:43], v[38:41], off offset:576
	s_and_b64 vcc, exec, s[0:1]
	v_add_u32_e32 v34, 0xa0, v130
	v_ashrrev_i32_e32 v35, 31, v34
	v_lshlrev_b64 v[36:37], 11, v[34:35]
	v_lshl_add_u64 v[36:37], s[6:7], 0, v[36:37]
	v_lshl_add_u64 v[36:37], v[132:133], 1, v[36:37]
	s_cbranch_vccnz .LBB0_550
	v_cvt_pk_bf16_f32 v38, v30, v31
	v_cvt_pk_bf16_f32 v39, v32, v33
	v_cvt_pk_bf16_f32 v40, v26, v27
	v_cvt_pk_bf16_f32 v41, v28, v29
	v_lshl_add_u64 v[154:155], v[36:37], 0, 0
	global_store_dwordx4 v[36:37], v[38:41], off
.LBB0_550:
	v_lshlrev_b64 v[34:35], 12, v[34:35]
	v_lshl_add_u64 v[34:35], v[134:135], 0, v[34:35]
	v_permlane16_swap_b32_e32 v30, v26
	v_permlane16_swap_b32_e32 v31, v27
	v_permlane16_swap_b32_e32 v32, v28
	v_permlane16_swap_b32_e32 v33, v29
	v_permlane32_swap_b32_e32 v30, v26
	v_permlane32_swap_b32_e32 v31, v27
	v_permlane32_swap_b32_e32 v32, v28
	v_permlane32_swap_b32_e32 v33, v29
	v_lshl_add_u64 v[38:39], s[22:23], 2, v[34:35]
	s_mov_b32 s98, 0xa1000
	s_mov_b32 s99, 0x0
	v_lshl_add_u64 v[154:155], v[152:153], 0, s[98:99]
	s_and_b64 vcc, exec, s[0:1]
	global_store_dwordx4 v[154:155], v[30:33], off offset:-4096
	global_store_dwordx4 v[154:155], v[26:29], off offset:-4032
	s_cbranch_vccnz .LBB0_552
	s_nop 0
	v_cvt_pk_bf16_f32 v26, v18, v19
	v_cvt_pk_bf16_f32 v27, v20, v21
	v_cvt_pk_bf16_f32 v28, v22, v23
	v_cvt_pk_bf16_f32 v29, v24, v25
	s_mov_b32 s98, 0x100
	s_mov_b32 s99, 0x0
	v_lshl_add_u64 v[154:155], v[36:37], 0, s[98:99]
	global_store_dwordx4 v[36:37], v[26:29], off offset:256

.LBB0_554:
	v_lshlrev_b64 v[18:19], 12, v[18:19]
	v_lshl_add_u64 v[18:19], v[134:135], 0, v[18:19]
	v_permlane16_swap_b32_e32 v14, v10
	v_permlane16_swap_b32_e32 v15, v11
	v_permlane16_swap_b32_e32 v16, v12
	v_permlane16_swap_b32_e32 v17, v13
	v_permlane32_swap_b32_e32 v14, v10
	v_permlane32_swap_b32_e32 v15, v11
	v_permlane32_swap_b32_e32 v16, v12
	v_permlane32_swap_b32_e32 v17, v13
	v_lshl_add_u64 v[22:23], s[22:23], 2, v[18:19]
	s_mov_b32 s98, 0xb1000
	s_mov_b32 s99, 0x0
	v_lshl_add_u64 v[154:155], v[152:153], 0, s[98:99]
	s_and_b64 vcc, exec, s[0:1]
	global_store_dwordx4 v[154:155], v[14:17], off offset:-4096
	global_store_dwordx4 v[154:155], v[10:13], off offset:-4032
	s_cbranch_vccnz .LBB0_556
	s_nop 0
	v_cvt_pk_bf16_f32 v10, v2, v3
	v_cvt_pk_bf16_f32 v11, v4, v5
	v_cvt_pk_bf16_f32 v12, v6, v7
	v_cvt_pk_bf16_f32 v13, v8, v9
	global_store_dwordx4 v[20:21], v[10:13], off offset:256

.LBB0_635:
	s_add_u32 s28, s24, 0x10000
	s_addc_u32 s29, s25, 0
	s_and_b64 s[24:25], s[22:23], exec
	s_cselect_b32 s25, s29, s15
	s_cselect_b32 s24, s28, s33
	s_add_u32 s3, s52, s3
	s_addc_u32 s28, s53, 0
	s_add_u32 s3, s3, 0x10000
	s_waitcnt vmcnt(8)
	s_addc_u32 s28, s28, 0
	s_waitcnt lgkmcnt(0)
	s_and_b64 s[22:23], s[22:23], exec
	s_cselect_b32 s23, s28, s13
	s_cselect_b32 s22, s3, s70
	s_barrier
	s_setprio 1
	s_waitcnt lgkmcnt(7)
	v_mfma_f32_16x16x32_bf16 v[126:129], v[146:149], v[186:189], v[126:129]
	v_mfma_f32_16x16x32_bf16 v[122:125], v[154:157], v[186:189], v[122:125]
	s_waitcnt lgkmcnt(5)
	v_mfma_f32_16x16x32_bf16 v[118:121], v[146:149], v[178:181], v[118:121]
	v_mfma_f32_16x16x32_bf16 v[114:117], v[154:157], v[178:181], v[114:117]
	s_waitcnt lgkmcnt(3)
	v_mfma_f32_16x16x32_bf16 v[110:113], v[146:149], v[170:173], v[110:113]
	v_mfma_f32_16x16x32_bf16 v[106:109], v[154:157], v[170:173], v[106:109]
	s_waitcnt lgkmcnt(1)
	v_mfma_f32_16x16x32_bf16 v[102:105], v[146:149], v[162:165], v[102:105]
	v_mfma_f32_16x16x32_bf16 v[98:101], v[154:157], v[162:165], v[98:101]
	v_mfma_f32_16x16x32_bf16 v[126:129], v[150:153], v[190:193], v[126:129]
	v_mfma_f32_16x16x32_bf16 v[122:125], v[158:161], v[190:193], v[122:125]
	v_mfma_f32_16x16x32_bf16 v[118:121], v[150:153], v[182:185], v[118:121]
	v_mfma_f32_16x16x32_bf16 v[114:117], v[158:161], v[182:185], v[114:117]
	v_mfma_f32_16x16x32_bf16 v[110:113], v[150:153], v[174:177], v[110:113]
	v_mfma_f32_16x16x32_bf16 v[106:109], v[158:161], v[174:177], v[106:109]
	s_waitcnt lgkmcnt(0)
	v_mfma_f32_16x16x32_bf16 v[102:105], v[150:153], v[166:169], v[102:105]
	v_mfma_f32_16x16x32_bf16 v[98:101], v[158:161], v[166:169], v[98:101]
	s_setprio 0
	s_setprio 1
	v_mfma_f32_16x16x32_bf16 v[94:97], v[130:133], v[186:189], v[94:97]
	v_mfma_f32_16x16x32_bf16 v[90:93], v[138:141], v[186:189], v[90:93]
	v_mfma_f32_16x16x32_bf16 v[86:89], v[130:133], v[178:181], v[86:89]
	v_mfma_f32_16x16x32_bf16 v[82:85], v[138:141], v[178:181], v[82:85]
	v_mfma_f32_16x16x32_bf16 v[78:81], v[130:133], v[170:173], v[78:81]
	v_mfma_f32_16x16x32_bf16 v[74:77], v[138:141], v[170:173], v[74:77]
	v_mfma_f32_16x16x32_bf16 v[70:73], v[130:133], v[162:165], v[70:73]
	v_mfma_f32_16x16x32_bf16 v[66:69], v[138:141], v[162:165], v[66:69]
	v_mfma_f32_16x16x32_bf16 v[94:97], v[134:137], v[190:193], v[94:97]
	v_mfma_f32_16x16x32_bf16 v[90:93], v[142:145], v[190:193], v[90:93]
	v_mfma_f32_16x16x32_bf16 v[86:89], v[134:137], v[182:185], v[86:89]
	v_mfma_f32_16x16x32_bf16 v[82:85], v[142:145], v[182:185], v[82:85]
	v_mfma_f32_16x16x32_bf16 v[78:81], v[134:137], v[174:177], v[78:81]
	v_mfma_f32_16x16x32_bf16 v[74:77], v[142:145], v[174:177], v[74:77]
	v_mfma_f32_16x16x32_bf16 v[70:73], v[134:137], v[166:169], v[70:73]
	v_mfma_f32_16x16x32_bf16 v[66:69], v[142:145], v[166:169], v[66:69]
	s_setprio 0
	s_barrier
	ds_read_b128 v[186:189], v219 offset:16384
	ds_read_b128 v[190:193], v219 offset:17408
	ds_read_b128 v[178:181], v219 offset:18432
	ds_read_b128 v[182:185], v219 offset:19456
	ds_read_b128 v[170:173], v219 offset:20480
	ds_read_b128 v[174:177], v219 offset:21504
	ds_read_b128 v[162:165], v219 offset:22528
	ds_read_b128 v[166:169], v219 offset:23552
	s_mov_b32 m0, s89
	s_nop 0
	global_load_lds_dwordx4 v195, s[22:23]
	s_add_u32 m0, s89, 0x2000
	s_nop 0
	global_load_lds_dwordx4 v213, s[22:23]
	s_add_u32 s28, s22, 0x4000
	s_addc_u32 s29, s23, 0
	s_mov_b32 m0, s54
	s_nop 0
	global_load_lds_dwordx4 v195, s[28:29]
	s_add_u32 m0, s54, 0x2000
	s_nop 0
	global_load_lds_dwordx4 v213, s[28:29]
	s_andn2_b64 vcc, exec, s[26:27]
	s_mov_b32 m0, s39
	s_nop 0
	global_load_lds_dwordx4 v195, s[24:25]
	s_add_u32 m0, s39, 0x2000
	s_nop 0
	global_load_lds_dwordx4 v213, s[24:25]
	s_cbranch_vccnz .LBB0_637
	v_mov_b32_e32 v2, 0
	v_mov_b32_e32 v3, v2
	v_mov_b32_e32 v4, v2
	v_mov_b32_e32 v5, v2
	v_mov_b32_e32 v6, v2
	v_mov_b32_e32 v7, v2
	v_mov_b32_e32 v8, v2
	v_mov_b32_e32 v9, v2
	v_mov_b32_e32 v10, v2
	v_mov_b32_e32 v11, v2
	v_mov_b32_e32 v12, v2
	v_mov_b32_e32 v13, v2
	v_mov_b32_e32 v14, v2
	v_mov_b32_e32 v15, v2
	v_mov_b32_e32 v16, v2
	v_mov_b32_e32 v17, v2
	v_mov_b32_e32 v18, v2
	v_mov_b32_e32 v19, v2
	v_mov_b32_e32 v20, v2
	v_mov_b32_e32 v21, v2
	v_mov_b32_e32 v22, v2
	v_mov_b32_e32 v23, v2
	v_mov_b32_e32 v24, v2
	v_mov_b32_e32 v25, v2
	v_mov_b32_e32 v26, v2
	v_mov_b32_e32 v27, v2
	v_mov_b32_e32 v28, v2
	v_mov_b32_e32 v29, v2
	v_mov_b32_e32 v30, v2
	v_mov_b32_e32 v31, v2
	v_mov_b32_e32 v32, v2
	v_mov_b32_e32 v33, v2
	v_mov_b32_e32 v34, v2
	v_mov_b32_e32 v35, v2
	v_mov_b32_e32 v36, v2
	v_mov_b32_e32 v37, v2
	v_mov_b32_e32 v38, v2
	v_mov_b32_e32 v39, v2
	v_mov_b32_e32 v40, v2
	v_mov_b32_e32 v41, v2
	v_mov_b32_e32 v42, v2
	v_mov_b32_e32 v43, v2
	v_mov_b32_e32 v44, v2
	v_mov_b32_e32 v45, v2
	v_mov_b32_e32 v46, v2
	v_mov_b32_e32 v47, v2
	v_mov_b32_e32 v48, v2
	v_mov_b32_e32 v49, v2
	v_mov_b32_e32 v50, v2
	v_mov_b32_e32 v51, v2
	v_mov_b32_e32 v52, v2
	v_mov_b32_e32 v53, v2
	v_mov_b32_e32 v54, v2
	v_mov_b32_e32 v55, v2
	v_mov_b32_e32 v56, v2
	v_mov_b32_e32 v57, v2
	v_mov_b32_e32 v58, v2
	v_mov_b32_e32 v59, v2
	v_mov_b32_e32 v60, v2
	v_mov_b32_e32 v61, v2
	v_mov_b32_e32 v62, v2
	v_mov_b32_e32 v63, v2
	v_mov_b32_e32 v64, v2
	v_mov_b32_e32 v65, v2
.LBB0_637:
	s_waitcnt vmcnt(8)
	s_add_u32 s26, s24, 0x8000
	s_waitcnt lgkmcnt(0)
	s_addc_u32 s27, s25, 0
	s_add_u32 s28, s22, 0x8000
	s_addc_u32 s29, s23, 0
	s_barrier
	s_setprio 1
	s_waitcnt lgkmcnt(7)
	v_mfma_f32_16x16x32_bf16 v[62:65], v[146:149], v[186:189], v[62:65]
	v_mfma_f32_16x16x32_bf16 v[58:61], v[154:157], v[186:189], v[58:61]
	s_waitcnt lgkmcnt(5)
	v_mfma_f32_16x16x32_bf16 v[54:57], v[146:149], v[178:181], v[54:57]
	v_mfma_f32_16x16x32_bf16 v[50:53], v[154:157], v[178:181], v[50:53]
	s_waitcnt lgkmcnt(3)
	v_mfma_f32_16x16x32_bf16 v[46:49], v[146:149], v[170:173], v[46:49]
	v_mfma_f32_16x16x32_bf16 v[42:45], v[154:157], v[170:173], v[42:45]
	s_waitcnt lgkmcnt(1)
	v_mfma_f32_16x16x32_bf16 v[38:41], v[146:149], v[162:165], v[38:41]
	v_mfma_f32_16x16x32_bf16 v[34:37], v[154:157], v[162:165], v[34:37]
	v_mfma_f32_16x16x32_bf16 v[62:65], v[150:153], v[190:193], v[62:65]
	v_mfma_f32_16x16x32_bf16 v[58:61], v[158:161], v[190:193], v[58:61]
	v_mfma_f32_16x16x32_bf16 v[54:57], v[150:153], v[182:185], v[54:57]
	v_mfma_f32_16x16x32_bf16 v[50:53], v[158:161], v[182:185], v[50:53]
	v_mfma_f32_16x16x32_bf16 v[46:49], v[150:153], v[174:177], v[46:49]
	v_mfma_f32_16x16x32_bf16 v[42:45], v[158:161], v[174:177], v[42:45]
	s_waitcnt lgkmcnt(0)
	v_mfma_f32_16x16x32_bf16 v[38:41], v[150:153], v[166:169], v[38:41]
	v_mfma_f32_16x16x32_bf16 v[34:37], v[158:161], v[166:169], v[34:37]
	s_setprio 0
	s_setprio 1
	v_mfma_f32_16x16x32_bf16 v[30:33], v[130:133], v[186:189], v[30:33]
	v_mfma_f32_16x16x32_bf16 v[26:29], v[138:141], v[186:189], v[26:29]
	v_mfma_f32_16x16x32_bf16 v[22:25], v[130:133], v[178:181], v[22:25]
	v_mfma_f32_16x16x32_bf16 v[18:21], v[138:141], v[178:181], v[18:21]
	v_mfma_f32_16x16x32_bf16 v[14:17], v[130:133], v[170:173], v[14:17]
	v_mfma_f32_16x16x32_bf16 v[10:13], v[138:141], v[170:173], v[10:13]
	v_mfma_f32_16x16x32_bf16 v[6:9], v[130:133], v[162:165], v[6:9]
	v_mfma_f32_16x16x32_bf16 v[2:5], v[138:141], v[162:165], v[2:5]
	v_mfma_f32_16x16x32_bf16 v[30:33], v[134:137], v[190:193], v[30:33]
	v_mfma_f32_16x16x32_bf16 v[26:29], v[142:145], v[190:193], v[26:29]
	v_mfma_f32_16x16x32_bf16 v[22:25], v[134:137], v[182:185], v[22:25]
	v_mfma_f32_16x16x32_bf16 v[18:21], v[142:145], v[182:185], v[18:21]
	v_mfma_f32_16x16x32_bf16 v[14:17], v[134:137], v[174:177], v[14:17]
	v_mfma_f32_16x16x32_bf16 v[10:13], v[142:145], v[174:177], v[10:13]
	v_mfma_f32_16x16x32_bf16 v[6:9], v[134:137], v[166:169], v[6:9]
	v_mfma_f32_16x16x32_bf16 v[2:5], v[142:145], v[166:169], v[2:5]
	s_setprio 0
	s_barrier
	v_add_u32_e32 v142, 0x18000, v218
	v_add_u32_e32 v158, 0x1c000, v218
	ds_read_b128 v[130:133], v142
	ds_read_b128 v[134:137], v142 offset:1024
	ds_read_b128 v[138:141], v142 offset:2048
	ds_read_b128 v[142:145], v142 offset:3072
	ds_read_b128 v[146:149], v158
	ds_read_b128 v[150:153], v158 offset:1024
	ds_read_b128 v[154:157], v158 offset:2048
	ds_read_b128 v[158:161], v158 offset:3072
	ds_read_b128 v[162:165], v219 offset:32768
	ds_read_b128 v[166:169], v219 offset:33792
	ds_read_b128 v[170:173], v219 offset:34816
	ds_read_b128 v[174:177], v219 offset:35840
	ds_read_b128 v[178:181], v219 offset:36864
	ds_read_b128 v[182:185], v219 offset:37888
	ds_read_b128 v[186:189], v219 offset:38912
	ds_read_b128 v[190:193], v219 offset:39936
	s_add_u32 s24, s24, 0x4000
	s_addc_u32 s25, s25, 0
	s_mov_b32 m0, s55
	s_nop 0
	global_load_lds_dwordx4 v195, s[24:25]
	s_add_u32 m0, s55, 0x2000
	s_nop 0
	global_load_lds_dwordx4 v213, s[24:25]
	s_waitcnt vmcnt(8)
	s_waitcnt lgkmcnt(0)
	s_barrier
	s_setprio 1
	s_waitcnt lgkmcnt(7)
	v_mfma_f32_16x16x32_bf16 v[126:129], v[130:133], v[162:165], v[126:129]
	v_mfma_f32_16x16x32_bf16 v[122:125], v[138:141], v[162:165], v[122:125]
	s_waitcnt lgkmcnt(5)
	v_mfma_f32_16x16x32_bf16 v[118:121], v[130:133], v[170:173], v[118:121]
	v_mfma_f32_16x16x32_bf16 v[114:117], v[138:141], v[170:173], v[114:117]
	s_waitcnt lgkmcnt(3)
	v_mfma_f32_16x16x32_bf16 v[110:113], v[130:133], v[178:181], v[110:113]
	v_mfma_f32_16x16x32_bf16 v[106:109], v[138:141], v[178:181], v[106:109]
	s_waitcnt lgkmcnt(1)
	v_mfma_f32_16x16x32_bf16 v[102:105], v[130:133], v[186:189], v[102:105]
	v_mfma_f32_16x16x32_bf16 v[98:101], v[138:141], v[186:189], v[98:101]
	v_mfma_f32_16x16x32_bf16 v[126:129], v[134:137], v[166:169], v[126:129]
	v_mfma_f32_16x16x32_bf16 v[122:125], v[142:145], v[166:169], v[122:125]
	v_mfma_f32_16x16x32_bf16 v[118:121], v[134:137], v[174:177], v[118:121]
	v_mfma_f32_16x16x32_bf16 v[114:117], v[142:145], v[174:177], v[114:117]
	v_mfma_f32_16x16x32_bf16 v[110:113], v[134:137], v[182:185], v[110:113]
	v_mfma_f32_16x16x32_bf16 v[106:109], v[142:145], v[182:185], v[106:109]
	s_waitcnt lgkmcnt(0)
	v_mfma_f32_16x16x32_bf16 v[102:105], v[134:137], v[190:193], v[102:105]
	v_mfma_f32_16x16x32_bf16 v[98:101], v[142:145], v[190:193], v[98:101]
	s_setprio 0
	s_setprio 1
	v_mfma_f32_16x16x32_bf16 v[94:97], v[146:149], v[162:165], v[94:97]
	v_mfma_f32_16x16x32_bf16 v[90:93], v[154:157], v[162:165], v[90:93]
	v_mfma_f32_16x16x32_bf16 v[86:89], v[146:149], v[170:173], v[86:89]
	v_mfma_f32_16x16x32_bf16 v[82:85], v[154:157], v[170:173], v[82:85]
	v_mfma_f32_16x16x32_bf16 v[78:81], v[146:149], v[178:181], v[78:81]
	v_mfma_f32_16x16x32_bf16 v[74:77], v[154:157], v[178:181], v[74:77]
	v_mfma_f32_16x16x32_bf16 v[70:73], v[146:149], v[186:189], v[70:73]
	v_mfma_f32_16x16x32_bf16 v[66:69], v[154:157], v[186:189], v[66:69]
	v_mfma_f32_16x16x32_bf16 v[94:97], v[150:153], v[166:169], v[94:97]
	v_mfma_f32_16x16x32_bf16 v[90:93], v[158:161], v[166:169], v[90:93]
	v_mfma_f32_16x16x32_bf16 v[86:89], v[150:153], v[174:177], v[86:89]
	v_mfma_f32_16x16x32_bf16 v[82:85], v[158:161], v[174:177], v[82:85]
	v_mfma_f32_16x16x32_bf16 v[78:81], v[150:153], v[182:185], v[78:81]
	v_mfma_f32_16x16x32_bf16 v[74:77], v[158:161], v[182:185], v[74:77]
	v_mfma_f32_16x16x32_bf16 v[70:73], v[150:153], v[190:193], v[70:73]
	v_mfma_f32_16x16x32_bf16 v[66:69], v[158:161], v[190:193], v[66:69]
	s_setprio 0
	s_barrier
	ds_read_b128 v[162:165], v219 offset:49152
	ds_read_b128 v[166:169], v219 offset:50176
	ds_read_b128 v[170:173], v219 offset:51200
	ds_read_b128 v[174:177], v219 offset:52224
	ds_read_b128 v[178:181], v219 offset:53248
	ds_read_b128 v[182:185], v219 offset:54272
	ds_read_b128 v[186:189], v219 offset:55296
	ds_read_b128 v[190:193], v219 offset:56320
	s_mov_b32 m0, s83
	s_nop 0
	global_load_lds_dwordx4 v195, s[28:29]
	s_add_u32 m0, s83, 0x2000
	s_nop 0
	global_load_lds_dwordx4 v213, s[28:29]
	s_add_u32 s22, s22, 0xc000
	s_addc_u32 s23, s23, 0
	s_mov_b32 m0, s91
	s_nop 0
	global_load_lds_dwordx4 v195, s[22:23]
	s_add_u32 m0, s91, 0x2000
	s_nop 0
	global_load_lds_dwordx4 v213, s[22:23]
	s_nop 0
	s_mov_b32 m0, s90
	s_nop 0
	global_load_lds_dwordx4 v195, s[26:27]
	s_add_u32 m0, s90, 0x2000
	s_nop 0
	global_load_lds_dwordx4 v213, s[26:27]
	s_waitcnt vmcnt(8)
	s_waitcnt lgkmcnt(0)
	s_barrier
	s_setprio 1
	s_waitcnt lgkmcnt(7)
	v_mfma_f32_16x16x32_bf16 v[62:65], v[130:133], v[162:165], v[62:65]
	v_mfma_f32_16x16x32_bf16 v[58:61], v[138:141], v[162:165], v[58:61]
	s_waitcnt lgkmcnt(5)
	v_mfma_f32_16x16x32_bf16 v[54:57], v[130:133], v[170:173], v[54:57]
	v_mfma_f32_16x16x32_bf16 v[50:53], v[138:141], v[170:173], v[50:53]
	s_waitcnt lgkmcnt(3)
	v_mfma_f32_16x16x32_bf16 v[46:49], v[130:133], v[178:181], v[46:49]
	v_mfma_f32_16x16x32_bf16 v[42:45], v[138:141], v[178:181], v[42:45]
	s_waitcnt lgkmcnt(1)
	v_mfma_f32_16x16x32_bf16 v[38:41], v[130:133], v[186:189], v[38:41]
	v_mfma_f32_16x16x32_bf16 v[34:37], v[138:141], v[186:189], v[34:37]
	v_mfma_f32_16x16x32_bf16 v[62:65], v[134:137], v[166:169], v[62:65]
	v_mfma_f32_16x16x32_bf16 v[58:61], v[142:145], v[166:169], v[58:61]
	v_mfma_f32_16x16x32_bf16 v[54:57], v[134:137], v[174:177], v[54:57]
	v_mfma_f32_16x16x32_bf16 v[50:53], v[142:145], v[174:177], v[50:53]
	v_mfma_f32_16x16x32_bf16 v[46:49], v[134:137], v[182:185], v[46:49]
	v_mfma_f32_16x16x32_bf16 v[42:45], v[142:145], v[182:185], v[42:45]
	s_waitcnt lgkmcnt(0)
	v_mfma_f32_16x16x32_bf16 v[38:41], v[134:137], v[190:193], v[38:41]
	v_mfma_f32_16x16x32_bf16 v[34:37], v[142:145], v[190:193], v[34:37]
	s_setprio 0
	s_setprio 1
	v_mfma_f32_16x16x32_bf16 v[30:33], v[146:149], v[162:165], v[30:33]
	v_mfma_f32_16x16x32_bf16 v[26:29], v[154:157], v[162:165], v[26:29]
	v_mfma_f32_16x16x32_bf16 v[22:25], v[146:149], v[170:173], v[22:25]
	v_mfma_f32_16x16x32_bf16 v[18:21], v[154:157], v[170:173], v[18:21]
	v_mfma_f32_16x16x32_bf16 v[14:17], v[146:149], v[178:181], v[14:17]
	v_mfma_f32_16x16x32_bf16 v[10:13], v[154:157], v[178:181], v[10:13]
	v_mfma_f32_16x16x32_bf16 v[6:9], v[146:149], v[186:189], v[6:9]
	v_mfma_f32_16x16x32_bf16 v[2:5], v[154:157], v[186:189], v[2:5]
	v_mfma_f32_16x16x32_bf16 v[30:33], v[150:153], v[166:169], v[30:33]
	v_mfma_f32_16x16x32_bf16 v[26:29], v[158:161], v[166:169], v[26:29]
	v_mfma_f32_16x16x32_bf16 v[22:25], v[150:153], v[174:177], v[22:25]
	v_mfma_f32_16x16x32_bf16 v[18:21], v[158:161], v[174:177], v[18:21]
	v_mfma_f32_16x16x32_bf16 v[14:17], v[150:153], v[182:185], v[14:17]
	v_mfma_f32_16x16x32_bf16 v[10:13], v[158:161], v[182:185], v[10:13]
	v_mfma_f32_16x16x32_bf16 v[6:9], v[150:153], v[190:193], v[6:9]
	v_mfma_f32_16x16x32_bf16 v[2:5], v[158:161], v[190:193], v[2:5]
	s_setprio 0
	s_barrier
	s_add_i32 s3, s71, 2
	s_cmp_gt_u32 s71, 13
	s_cbranch_scc1 .LBB0_639
	s_mov_b32 s71, s3
	s_branch .LBB0_616

.LBB0_641:
	s_lshl_b32 s0, s31, 8
	v_mov_b32_e32 v223, v210
	v_mov_b32_e32 v220, v214
	s_add_i32 s0, s0, s81
	v_and_b32_e32 v153, 64, v216
	v_add_u32_e32 v178, s0, v220
	v_lshlrev_b32_e32 v130, 2, v223
	v_ashrrev_i32_e32 v131, 31, v130
	v_ashrrev_i32_e32 v179, 31, v178
	v_lshl_add_u64 v[130:131], v[130:131], 2, s[46:47]
	v_lshlrev_b64 v[206:207], 6, v[178:179]
	v_add_u32_e32 v174, 16, v178
	v_lshl_add_u64 v[132:133], v[130:131], 0, v[206:207]
	v_ashrrev_i32_e32 v175, 31, v174
	v_lshl_add_u64 v[250:251], v[132:133], 0, 0
	global_load_dwordx4 v[134:137], v[132:133], off
	v_lshlrev_b64 v[204:205], 6, v[174:175]
	v_add_u32_e32 v170, 32, v178
	v_ashrrev_i32_e32 v171, 31, v170
	s_mov_b32 s98, 0x1000
	s_mov_b32 s99, 0x0
	v_lshl_add_u64 v[252:253], v[250:251], 0, s[98:99]
	global_load_dwordx4 v[138:141], v[252:253], off offset:-3072
	v_lshlrev_b64 v[202:203], 6, v[170:171]
	v_add_u32_e32 v166, 48, v178
	v_ashrrev_i32_e32 v167, 31, v166
	global_load_dwordx4 v[142:145], v[252:253], off offset:-2048
	v_lshlrev_b64 v[192:193], 6, v[166:167]
	v_add_u32_e32 v162, 0x80, v178
	v_ashrrev_i32_e32 v163, 31, v162
	global_load_dwordx4 v[146:149], v[252:253], off offset:-1024
	v_lshlrev_b64 v[190:191], 6, v[162:163]
	v_add_u32_e32 v158, 0x90, v178
	v_ashrrev_i32_e32 v159, 31, v158
	s_mov_b32 s98, 0x3000
	s_mov_b32 s99, 0x0
	v_lshl_add_u64 v[252:253], v[250:251], 0, s[98:99]
	global_load_dwordx4 v[180:183], v[252:253], off offset:-4096
	v_lshlrev_b64 v[188:189], 6, v[158:159]
	v_add_u32_e32 v154, 0xa0, v178
	v_add_u32_e32 v150, 0xb0, v178
	v_ashrrev_i32_e32 v155, 31, v154
	v_ashrrev_i32_e32 v151, 31, v150
	global_load_dwordx4 v[224:227], v[252:253], off offset:-3072
	v_lshlrev_b64 v[186:187], 6, v[154:155]
	v_lshlrev_b64 v[184:185], 6, v[150:151]
	global_load_dwordx4 v[228:231], v[252:253], off offset:-2048
	v_xor_b32_e32 v152, 16, v216
	global_load_dwordx4 v[130:133], v[252:253], off offset:-1024
	v_add_u32_e32 v153, 64, v153
	v_cmp_lt_i32_e32 vcc, v152, v153
	s_cmp_lt_u32 s38, 6
	s_cselect_b32 s0, 2, 3
	v_cndmask_b32_e32 v152, v216, v152, vcc
	v_lshlrev_b32_e32 v221, 2, v152
	v_xor_b32_e32 v152, 32, v216
	v_cmp_lt_i32_e32 vcc, v152, v153
	s_cselect_b32 s1, -4, -6
	s_cmp_lt_u32 s38, 4
	v_cndmask_b32_e32 v152, v216, v152, vcc
	v_lshlrev_b32_e32 v222, 2, v152
	s_cselect_b32 s0, 1, s0
	s_cselect_b32 s1, -2, s1
	s_cmp_lt_i32 s38, 2
	s_cselect_b32 s3, 0, s0
	s_cselect_b32 s0, 0, s1
	s_add_i32 s0, s0, s38
	s_cmp_lt_i32 s3, 2
	s_waitcnt vmcnt(7)
	v_add_f32_e32 v134, v134, v135
	v_add_f32_e32 v135, v136, v137
	v_add_f32_e32 v134, v134, v135
	ds_bpermute_b32 v135, v221, v134
	s_waitcnt vmcnt(6)
	v_add_f32_e32 v136, v138, v139
	v_add_f32_e32 v137, v140, v141
	v_add_f32_e32 v136, v136, v137
	ds_bpermute_b32 v137, v221, v136
	s_waitcnt lgkmcnt(1)
	v_add_f32_e32 v134, v134, v135
	s_waitcnt vmcnt(5)
	v_add_f32_e32 v138, v142, v143
	v_add_f32_e32 v139, v144, v145
	v_add_f32_e32 v138, v138, v139
	ds_bpermute_b32 v139, v221, v138
	ds_bpermute_b32 v135, v222, v134
	s_waitcnt vmcnt(4)
	v_add_f32_e32 v140, v146, v147
	v_add_f32_e32 v141, v148, v149
	v_add_f32_e32 v140, v140, v141
	ds_bpermute_b32 v141, v221, v140
	s_waitcnt lgkmcnt(3)
	v_add_f32_e32 v136, v136, v137
	s_waitcnt vmcnt(3)
	v_add_f32_e32 v142, v180, v181
	v_add_f32_e32 v143, v182, v183
	v_add_f32_e32 v142, v142, v143
	ds_bpermute_b32 v137, v222, v136
	ds_bpermute_b32 v143, v221, v142
	s_waitcnt lgkmcnt(4)
	v_add_f32_e32 v138, v138, v139
	ds_bpermute_b32 v139, v222, v138
	s_waitcnt vmcnt(2)
	v_add_f32_e32 v144, v224, v225
	v_add_f32_e32 v145, v226, v227
	v_add_f32_e32 v144, v144, v145
	ds_bpermute_b32 v145, v221, v144
	s_waitcnt lgkmcnt(4)
	v_add_f32_e32 v140, v140, v141
	s_waitcnt vmcnt(1)
	v_add_f32_e32 v146, v228, v229
	v_add_f32_e32 v147, v230, v231
	s_waitcnt vmcnt(0)
	v_add_f32_e32 v130, v130, v131
	v_add_f32_e32 v131, v132, v133
	v_add_f32_e32 v146, v146, v147
	v_add_f32_e32 v130, v130, v131
	v_add_f32_e32 v132, v134, v135
	ds_bpermute_b32 v141, v222, v140
	ds_bpermute_b32 v147, v221, v146
	ds_bpermute_b32 v131, v221, v130
	v_fmamk_f32 v132, v132, 0x3a800000, v217
	s_waitcnt lgkmcnt(5)
	v_add_f32_e32 v142, v142, v143
	v_rsq_f32_e32 v180, v132
	v_add_f32_e32 v132, v136, v137
	ds_bpermute_b32 v143, v222, v142
	v_fmamk_f32 v132, v132, 0x3a800000, v217
	s_waitcnt lgkmcnt(4)
	v_add_f32_e32 v144, v144, v145
	v_rsq_f32_e32 v176, v132
	v_add_f32_e32 v132, v138, v139
	ds_bpermute_b32 v145, v222, v144
	v_fmamk_f32 v132, v132, 0x3a800000, v217
	s_waitcnt lgkmcnt(3)
	v_add_f32_e32 v146, v146, v147
	s_waitcnt lgkmcnt(2)
	v_add_f32_e32 v130, v130, v131
	v_rsq_f32_e32 v172, v132
	v_add_f32_e32 v132, v140, v141
	ds_bpermute_b32 v147, v222, v146
	ds_bpermute_b32 v131, v222, v130
	v_fmamk_f32 v132, v132, 0x3a800000, v217
	v_rsq_f32_e32 v168, v132
	s_waitcnt lgkmcnt(3)
	v_add_f32_e32 v132, v142, v143
	v_fmamk_f32 v132, v132, 0x3a800000, v217
	v_rsq_f32_e32 v164, v132
	s_waitcnt lgkmcnt(2)
	v_add_f32_e32 v132, v144, v145
	v_fmamk_f32 v132, v132, 0x3a800000, v217
	v_rsq_f32_e32 v160, v132
	s_waitcnt lgkmcnt(1)
	v_add_f32_e32 v132, v146, v147
	s_waitcnt lgkmcnt(0)
	v_add_f32_e32 v130, v130, v131
	v_fmamk_f32 v132, v132, 0x3a800000, v217
	v_fmamk_f32 v130, v130, 0x3a800000, v217
	v_rsq_f32_e32 v156, v132
	v_rsq_f32_e32 v152, v130
	v_lshl_add_u32 v148, v223, 3, s82
	v_lshl_add_u32 v182, s0, 8, v148
	s_mov_b64 s[0:1], -1
	s_cbranch_scc1 .LBB0_727
	s_cmp_gt_i32 s3, 2
	s_cbranch_scc0 .LBB0_708
	s_mov_b32 s33, s64
	s_mov_b32 s15, s62
	s_mov_b64 s[28:29], s[58:59]
	s_mov_b64 s[26:27], s[56:57]
	s_mov_b32 s13, s63
	v_readlane_b32 s56, v249, 6
	v_ashrrev_i32_e32 v183, 31, v182
	v_readlane_b32 s64, v249, 14
	v_readlane_b32 s65, v249, 15
	v_lshrrev_b32_e32 v147, 3, v178
	v_lshlrev_b32_e32 v146, 1, v148
	v_lshl_add_u64 v[134:135], v[182:183], 2, s[64:65]
	s_mov_b32 s98, 0x10
	s_mov_b32 s99, 0x0
	v_lshl_add_u64 v[250:251], v[134:135], 0, s[98:99]
	global_load_dwordx4 v[138:141], v[134:135], off offset:16
	s_mov_b32 s98, 0xfffff000
	s_mov_b32 s99, 0xffffffff
	v_lshl_add_u64 v[252:253], v[250:251], 0, s[98:99]
	global_load_dwordx4 v[142:145], v[252:253], off offset:4080
	s_mov_b32 s98, 0x1000
	s_mov_b32 s99, 0x0
	v_lshl_add_u64 v[252:253], v[250:251], 0, s[98:99]
	global_load_dwordx4 v[130:133], v[252:253], off offset:-3584
	s_nop 0
	global_load_dwordx4 v[134:137], v[252:253], off offset:-3600
	v_bfe_u32 v183, v148, 5, 1
	v_and_or_b32 v147, v147, 14, v183
	v_and_b32_e32 v153, 48, v146
	v_ashrrev_i32_e32 v146, 3, v178
	v_lshlrev_b32_e32 v148, 6, v178
	v_lshlrev_b32_e32 v157, 10, v147
	v_lshlrev_b32_e32 v147, 2, v178
	v_and_b32_e32 v161, 0xffffffe0, v146
	v_lshlrev_b32_e32 v146, 7, v178
	v_and_b32_e32 v148, 0x3c0, v148
	v_and_b32_e32 v147, 32, v147
	v_and_b32_e32 v146, 0x4000, v146
	v_bitop3_b32 v147, v153, v147, v148 bitop3:0x36
	v_or3_b32 v198, v146, v147, v157
	v_ashrrev_i32_e32 v224, 6, v182
	s_cmpk_lt_i32 s31, 0x80
	s_cselect_b64 s[0:1], -1, 0
	s_xor_b64 s[22:23], s[36:37], -1
	s_and_b64 s[22:23], s[22:23], s[0:1]
	s_mov_b64 s[24:25], -1
	s_and_b64 vcc, exec, s[22:23]
	v_readlane_b32 s57, v249, 7
	v_readlane_b32 s58, v249, 8
	v_readlane_b32 s59, v249, 9
	v_readlane_b32 s60, v249, 10
	v_readlane_b32 s61, v249, 11
	v_readlane_b32 s62, v249, 12
	v_readlane_b32 s63, v249, 13
	v_readlane_b32 s66, v249, 16
	v_readlane_b32 s67, v249, 17
	v_readlane_b32 s68, v249, 18
	v_readlane_b32 s69, v249, 19
	v_readlane_b32 s70, v249, 20
	v_readlane_b32 s71, v249, 21
	s_waitcnt vmcnt(2)
	v_pk_fma_f32 v[146:147], v[126:127], v[180:181], v[142:143] op_sel_hi:[1,0,1]
	s_nop 0
	v_pk_mul_f32 v[146:147], v[146:147], s[94:95] op_sel_hi:[1,0]
	s_nop 0
	v_exp_f32_e32 v146, v146
	v_exp_f32_e32 v147, v147
	s_nop 0
	v_pk_add_f32 v[146:147], v[146:147], 1.0 op_sel_hi:[1,0]
	s_nop 0
	v_rcp_f32_e32 v148, v146
	v_rcp_f32_e32 v149, v147
	v_pk_fma_f32 v[146:147], v[128:129], v[180:181], v[144:145] op_sel_hi:[1,0,1]
	s_nop 0
	v_pk_mul_f32 v[146:147], v[146:147], s[94:95] op_sel_hi:[1,0]
	s_nop 0
	v_exp_f32_e32 v146, v146
	v_exp_f32_e32 v147, v147
	s_nop 0
	v_pk_add_f32 v[146:147], v[146:147], 1.0 op_sel_hi:[1,0]
	s_nop 0
	v_rcp_f32_e32 v165, v146
	v_rcp_f32_e32 v169, v147
	v_pk_fma_f32 v[146:147], v[122:123], v[180:181], v[138:139] op_sel_hi:[1,0,1]
	s_nop 0
	v_pk_mul_f32 v[146:147], v[146:147], s[94:95] op_sel_hi:[1,0]
	s_nop 0
	v_exp_f32_e32 v146, v146
	v_exp_f32_e32 v147, v147
	s_nop 0
	v_pk_add_f32 v[146:147], v[146:147], 1.0 op_sel_hi:[1,0]
	s_nop 0
	v_rcp_f32_e32 v173, v146
	v_rcp_f32_e32 v177, v147
	v_pk_fma_f32 v[146:147], v[124:125], v[180:181], v[140:141] op_sel_hi:[1,0,1]
	s_nop 0
	v_pk_mul_f32 v[146:147], v[146:147], s[94:95] op_sel_hi:[1,0]
	s_nop 0
	v_exp_f32_e32 v146, v146
	v_exp_f32_e32 v147, v147
	s_nop 0
	v_pk_add_f32 v[146:147], v[146:147], 1.0 op_sel_hi:[1,0]
	s_nop 0
	v_rcp_f32_e32 v181, v146
	v_rcp_f32_e32 v225, v147
	v_add_u32_e32 v146, v224, v161
	v_ashrrev_i32_e32 v147, 31, v146
	v_lshlrev_b64 v[146:147], 15, v[146:147]
	v_lshl_add_u64 v[146:147], s[72:73], 0, v[146:147]
	v_lshl_add_u64 v[208:209], v[146:147], 0, v[198:199]
	v_cvt_pk_bf16_f32 v146, v148, v149
	v_cvt_pk_bf16_f32 v147, v165, v169
	v_cvt_pk_bf16_f32 v148, v173, v177
	v_cvt_pk_bf16_f32 v149, v181, v225
	v_lshl_add_u64 v[250:251], v[208:209], 0, 0
	s_cbranch_vccz .LBB0_645
	global_store_dwordx4 v[208:209], v[146:149], off
	s_mov_b64 s[24:25], 0
.LBB0_645:
	s_mov_b32 s98, 0x1000
	s_mov_b32 s99, 0x0
	v_lshl_add_u64 v[252:253], v[250:251], 0, s[98:99]
	s_andn2_b64 vcc, exec, s[24:25]
	s_cbranch_vccnz .LBB0_647
	global_store_dwordx4 v[252:253], v[146:149], off offset:-4096 sc1
	s_nop 1
.LBB0_647:
	v_mov_b32_e32 v181, v180
	s_waitcnt vmcnt(0)
	v_pk_fma_f32 v[146:147], v[94:95], v[180:181], v[134:135]
	v_pk_fma_f32 v[148:149], v[96:97], v[180:181], v[136:137]
	v_pk_mul_f32 v[146:147], v[146:147], s[94:95] op_sel_hi:[1,0]
	v_pk_mul_f32 v[148:149], v[148:149], s[94:95] op_sel_hi:[1,0]
	v_exp_f32_e32 v146, v146
	v_exp_f32_e32 v147, v147
	v_exp_f32_e32 v148, v148
	v_exp_f32_e32 v149, v149
	s_andn2_b64 vcc, exec, s[22:23]
	v_pk_add_f32 v[146:147], v[146:147], 1.0 op_sel_hi:[1,0]
	s_mov_b32 s63, s13
	v_rcp_f32_e32 v165, v146
	v_rcp_f32_e32 v169, v147
	v_pk_add_f32 v[146:147], v[148:149], 1.0 op_sel_hi:[1,0]
	v_pk_fma_f32 v[148:149], v[92:93], v[180:181], v[132:133]
	v_rcp_f32_e32 v173, v146
	v_rcp_f32_e32 v177, v147
	v_pk_fma_f32 v[146:147], v[90:91], v[180:181], v[130:131]
	v_pk_mul_f32 v[148:149], v[148:149], s[94:95] op_sel_hi:[1,0]
	v_pk_mul_f32 v[146:147], v[146:147], s[94:95] op_sel_hi:[1,0]
	v_exp_f32_e32 v148, v148
	v_exp_f32_e32 v146, v146
	v_exp_f32_e32 v147, v147
	v_exp_f32_e32 v149, v149
	s_mov_b64 s[56:57], s[26:27]
	s_mov_b64 s[58:59], s[28:29]
	v_pk_add_f32 v[146:147], v[146:147], 1.0 op_sel_hi:[1,0]
	s_mov_b32 s62, s15
	v_rcp_f32_e32 v225, v146
	v_rcp_f32_e32 v226, v147
	v_pk_add_f32 v[146:147], v[148:149], 1.0 op_sel_hi:[1,0]
	s_mov_b32 s64, s33
	v_rcp_f32_e32 v149, v146
	v_add_u32_e32 v146, 0x80, v182
	v_ashrrev_i32_e32 v181, 6, v146
	v_rcp_f32_e32 v227, v147
	s_nop 0
	s_nop 0
	s_nop 0
	s_nop 0
	v_cndmask_b32_e64 v161, 0, 1, s[22:23]
	v_cvt_pk_bf16_f32 v146, v165, v169
	v_cvt_pk_bf16_f32 v147, v173, v177
	v_cvt_pk_bf16_f32 v148, v225, v226
	v_cvt_pk_bf16_f32 v149, v149, v227
	v_cmp_ne_u32_e64 s[0:1], 1, v161
	s_mov_b32 s98, 0x11000
	s_mov_b32 s99, 0x0
	v_lshl_add_u64 v[254:255], v[250:251], 0, s[98:99]
	s_mov_b64 s[22:23], -1
	s_movk_i32 s65, 0xff0
	s_movk_i32 s66, 0xf00f
	s_cbranch_vccnz .LBB0_649
	s_mov_b64 s[22:23], 0
	global_store_dwordx4 v[254:255], v[146:149], off offset:-4096
.LBB0_649:
	s_andn2_b64 vcc, exec, s[22:23]
	s_cbranch_vccnz .LBB0_651
	global_store_dwordx4 v[254:255], v[146:149], off offset:-4096 sc1
	s_nop 1
.LBB0_651:
	s_nop 0
	s_nop 0
	s_nop 0
	s_nop 0
	v_pk_fma_f32 v[146:147], v[118:119], v[176:177], v[142:143] op_sel_hi:[1,0,1]
	v_pk_fma_f32 v[148:149], v[120:121], v[176:177], v[144:145] op_sel_hi:[1,0,1]
	v_pk_mul_f32 v[146:147], v[146:147], s[94:95] op_sel_hi:[1,0]
	v_pk_mul_f32 v[148:149], v[148:149], s[94:95] op_sel_hi:[1,0]
	v_exp_f32_e32 v146, v146
	v_exp_f32_e32 v147, v147
	v_exp_f32_e32 v148, v148
	v_exp_f32_e32 v149, v149
	s_and_b64 vcc, exec, s[0:1]
	v_pk_add_f32 v[146:147], v[146:147], 1.0 op_sel_hi:[1,0]
	s_mov_b64 s[22:23], -1
	v_rcp_f32_e32 v165, v146
	v_rcp_f32_e32 v169, v147
	v_pk_add_f32 v[146:147], v[148:149], 1.0 op_sel_hi:[1,0]
	s_nop 0
	v_rcp_f32_e32 v177, v147
	v_rcp_f32_e32 v173, v146
	v_pk_fma_f32 v[146:147], v[114:115], v[176:177], v[138:139] op_sel_hi:[1,0,1]
	s_nop 0
	v_pk_mul_f32 v[146:147], v[146:147], s[94:95] op_sel_hi:[1,0]
	v_pk_fma_f32 v[148:149], v[116:117], v[176:177], v[140:141] op_sel_hi:[1,0,1]
	v_exp_f32_e32 v146, v146
	v_exp_f32_e32 v147, v147
	v_pk_mul_f32 v[148:149], v[148:149], s[94:95] op_sel_hi:[1,0]
	v_pk_add_f32 v[146:147], v[146:147], 1.0 op_sel_hi:[1,0]
	v_exp_f32_e32 v148, v148
	v_exp_f32_e32 v149, v149
	v_rcp_f32_e32 v225, v146
	v_rcp_f32_e32 v226, v147
	v_pk_add_f32 v[146:147], v[148:149], 1.0 op_sel_hi:[1,0]
	s_nop 0
	v_rcp_f32_e32 v149, v146
	v_rcp_f32_e32 v227, v147
	s_nop 0
	s_nop 0
	s_nop 0
	s_nop 0
	s_nop 0
	v_cvt_pk_bf16_f32 v146, v165, v169
	v_cvt_pk_bf16_f32 v147, v173, v177
	v_cvt_pk_bf16_f32 v148, v225, v226
	v_cvt_pk_bf16_f32 v149, v149, v227
	s_cbranch_vccnz .LBB0_653
	s_mov_b64 s[22:23], 0
	global_store_dwordx4 v[252:253], v[146:149], off offset:-2048
.LBB0_653:
	s_andn2_b64 vcc, exec, s[22:23]
	s_cbranch_vccnz .LBB0_655
	global_store_dwordx4 v[252:253], v[146:149], off offset:-2048 sc1
	s_nop 1
.LBB0_655:
	v_mov_b32_e32 v177, v176
	v_pk_fma_f32 v[146:147], v[86:87], v[176:177], v[134:135]
	v_pk_fma_f32 v[148:149], v[88:89], v[176:177], v[136:137]
	v_pk_mul_f32 v[146:147], v[146:147], s[94:95] op_sel_hi:[1,0]
	v_pk_mul_f32 v[148:149], v[148:149], s[94:95] op_sel_hi:[1,0]
	v_exp_f32_e32 v146, v146
	v_exp_f32_e32 v147, v147
	v_exp_f32_e32 v148, v148
	v_exp_f32_e32 v149, v149
	s_and_b64 vcc, exec, s[0:1]
	v_pk_add_f32 v[146:147], v[146:147], 1.0 op_sel_hi:[1,0]
	s_mov_b64 s[22:23], -1
	v_rcp_f32_e32 v165, v146
	v_rcp_f32_e32 v169, v147
	v_pk_add_f32 v[146:147], v[148:149], 1.0 op_sel_hi:[1,0]
	v_pk_fma_f32 v[148:149], v[84:85], v[176:177], v[132:133]
	v_rcp_f32_e32 v173, v146
	v_rcp_f32_e32 v225, v147
	v_pk_fma_f32 v[146:147], v[82:83], v[176:177], v[130:131]
	v_pk_mul_f32 v[148:149], v[148:149], s[94:95] op_sel_hi:[1,0]
	v_pk_mul_f32 v[146:147], v[146:147], s[94:95] op_sel_hi:[1,0]
	v_exp_f32_e32 v148, v148
	v_exp_f32_e32 v146, v146
	v_exp_f32_e32 v147, v147
	v_exp_f32_e32 v149, v149
	v_pk_add_f32 v[146:147], v[146:147], 1.0 op_sel_hi:[1,0]
	s_nop 0
	v_rcp_f32_e32 v177, v146
	v_rcp_f32_e32 v226, v147
	v_pk_add_f32 v[146:147], v[148:149], 1.0 op_sel_hi:[1,0]
	v_cvt_pk_bf16_f32 v148, v177, v226
	v_rcp_f32_e32 v149, v146
	v_rcp_f32_e32 v227, v147
	s_nop 0
	s_nop 0
	s_nop 0
	s_nop 0
	s_nop 0
	v_cvt_pk_bf16_f32 v146, v165, v169
	v_cvt_pk_bf16_f32 v147, v173, v225
	v_cvt_pk_bf16_f32 v149, v149, v227
	s_cbranch_vccnz .LBB0_657
	s_mov_b64 s[22:23], 0
	global_store_dwordx4 v[254:255], v[146:149], off offset:-2048
.LBB0_657:
	s_andn2_b64 vcc, exec, s[22:23]
	s_cbranch_vccnz .LBB0_659
	global_store_dwordx4 v[254:255], v[146:149], off offset:-2048 sc1
	s_nop 1
.LBB0_659:
	s_nop 0
	s_nop 0
	s_nop 0
	s_nop 0
	v_pk_fma_f32 v[146:147], v[110:111], v[172:173], v[142:143] op_sel_hi:[1,0,1]
	v_pk_fma_f32 v[148:149], v[112:113], v[172:173], v[144:145] op_sel_hi:[1,0,1]
	v_pk_mul_f32 v[146:147], v[146:147], s[94:95] op_sel_hi:[1,0]
	v_pk_mul_f32 v[148:149], v[148:149], s[94:95] op_sel_hi:[1,0]
	v_exp_f32_e32 v146, v146
	v_exp_f32_e32 v147, v147
	v_exp_f32_e32 v148, v148
	v_exp_f32_e32 v149, v149
	s_and_b64 vcc, exec, s[0:1]
	v_pk_add_f32 v[146:147], v[146:147], 1.0 op_sel_hi:[1,0]
	s_mov_b64 s[22:23], -1
	v_rcp_f32_e32 v165, v146
	v_rcp_f32_e32 v169, v147
	v_pk_add_f32 v[146:147], v[148:149], 1.0 op_sel_hi:[1,0]
	s_nop 0
	v_rcp_f32_e32 v173, v146
	v_rcp_f32_e32 v177, v147
	v_pk_fma_f32 v[146:147], v[106:107], v[172:173], v[138:139] op_sel_hi:[1,0,1]
	s_nop 0
	v_pk_mul_f32 v[146:147], v[146:147], s[94:95] op_sel_hi:[1,0]
	v_pk_fma_f32 v[148:149], v[108:109], v[172:173], v[140:141] op_sel_hi:[1,0,1]
	v_exp_f32_e32 v146, v146
	v_exp_f32_e32 v147, v147
	v_pk_mul_f32 v[148:149], v[148:149], s[94:95] op_sel_hi:[1,0]
	v_pk_add_f32 v[146:147], v[146:147], 1.0 op_sel_hi:[1,0]
	v_exp_f32_e32 v148, v148
	v_exp_f32_e32 v149, v149
	v_rcp_f32_e32 v225, v146
	v_rcp_f32_e32 v226, v147
	v_pk_add_f32 v[146:147], v[148:149], 1.0 op_sel_hi:[1,0]
	s_nop 0
	v_rcp_f32_e32 v149, v146
	v_rcp_f32_e32 v227, v147
	s_nop 0
	s_nop 0
	s_nop 0
	s_nop 0
	s_nop 0
	v_cvt_pk_bf16_f32 v146, v165, v169
	v_cvt_pk_bf16_f32 v147, v173, v177
	v_cvt_pk_bf16_f32 v148, v225, v226
	v_cvt_pk_bf16_f32 v149, v149, v227
	s_cbranch_vccnz .LBB0_661
	s_mov_b64 s[22:23], 0
	global_store_dwordx4 v[252:253], v[146:149], off
.LBB0_661:
	s_andn2_b64 vcc, exec, s[22:23]
	s_cbranch_vccnz .LBB0_663
	global_store_dwordx4 v[252:253], v[146:149], off sc1
	s_nop 1
.LBB0_663:
	v_mov_b32_e32 v173, v172
	v_pk_fma_f32 v[146:147], v[78:79], v[172:173], v[134:135]
	v_pk_fma_f32 v[148:149], v[80:81], v[172:173], v[136:137]
	v_pk_mul_f32 v[146:147], v[146:147], s[94:95] op_sel_hi:[1,0]
	v_pk_mul_f32 v[148:149], v[148:149], s[94:95] op_sel_hi:[1,0]
	v_exp_f32_e32 v146, v146
	v_exp_f32_e32 v147, v147
	v_exp_f32_e32 v148, v148
	v_exp_f32_e32 v149, v149
	s_and_b64 vcc, exec, s[0:1]
	v_pk_add_f32 v[146:147], v[146:147], 1.0 op_sel_hi:[1,0]
	s_mov_b64 s[22:23], -1
	v_rcp_f32_e32 v165, v146
	v_rcp_f32_e32 v169, v147
	v_pk_add_f32 v[146:147], v[148:149], 1.0 op_sel_hi:[1,0]
	v_pk_fma_f32 v[148:149], v[76:77], v[172:173], v[132:133]
	v_rcp_f32_e32 v177, v146
	v_rcp_f32_e32 v225, v147
	v_pk_fma_f32 v[146:147], v[74:75], v[172:173], v[130:131]
	v_pk_mul_f32 v[148:149], v[148:149], s[94:95] op_sel_hi:[1,0]
	v_pk_mul_f32 v[146:147], v[146:147], s[94:95] op_sel_hi:[1,0]
	v_exp_f32_e32 v148, v148
	v_exp_f32_e32 v146, v146
	v_exp_f32_e32 v147, v147
	v_exp_f32_e32 v149, v149
	v_pk_add_f32 v[146:147], v[146:147], 1.0 op_sel_hi:[1,0]
	s_nop 0
	v_rcp_f32_e32 v173, v146
	v_rcp_f32_e32 v226, v147
	v_pk_add_f32 v[146:147], v[148:149], 1.0 op_sel_hi:[1,0]
	v_cvt_pk_bf16_f32 v148, v173, v226
	v_rcp_f32_e32 v149, v146
	v_rcp_f32_e32 v227, v147
	s_nop 0
	s_nop 0
	s_nop 0
	s_nop 0
	s_nop 0
	v_cvt_pk_bf16_f32 v146, v165, v169
	v_cvt_pk_bf16_f32 v147, v177, v225
	v_cvt_pk_bf16_f32 v149, v149, v227
	s_cbranch_vccnz .LBB0_665
	s_mov_b64 s[22:23], 0
	global_store_dwordx4 v[254:255], v[146:149], off
.LBB0_665:
	s_andn2_b64 vcc, exec, s[22:23]
	s_cbranch_vccnz .LBB0_667
	global_store_dwordx4 v[254:255], v[146:149], off sc1
	s_nop 1
.LBB0_667:
	s_nop 0
	s_nop 0
	s_nop 0
	s_nop 0
	v_pk_fma_f32 v[146:147], v[102:103], v[168:169], v[142:143] op_sel_hi:[1,0,1]
	v_pk_fma_f32 v[148:149], v[104:105], v[168:169], v[144:145] op_sel_hi:[1,0,1]
	v_pk_mul_f32 v[146:147], v[146:147], s[94:95] op_sel_hi:[1,0]
	v_pk_mul_f32 v[148:149], v[148:149], s[94:95] op_sel_hi:[1,0]
	v_exp_f32_e32 v146, v146
	v_exp_f32_e32 v147, v147
	v_exp_f32_e32 v148, v148
	v_exp_f32_e32 v149, v149
	s_and_b64 vcc, exec, s[0:1]
	v_pk_add_f32 v[146:147], v[146:147], 1.0 op_sel_hi:[1,0]
	s_mov_b64 s[22:23], -1
	v_rcp_f32_e32 v169, v147
	v_rcp_f32_e32 v165, v146
	v_pk_add_f32 v[146:147], v[148:149], 1.0 op_sel_hi:[1,0]
	v_pk_fma_f32 v[148:149], v[100:101], v[168:169], v[140:141] op_sel_hi:[1,0,1]
	v_rcp_f32_e32 v173, v146
	v_rcp_f32_e32 v177, v147
	v_pk_fma_f32 v[146:147], v[98:99], v[168:169], v[138:139] op_sel_hi:[1,0,1]
	v_pk_mul_f32 v[148:149], v[148:149], s[94:95] op_sel_hi:[1,0]
	v_pk_mul_f32 v[146:147], v[146:147], s[94:95] op_sel_hi:[1,0]
	v_exp_f32_e32 v148, v148
	v_exp_f32_e32 v146, v146
	v_exp_f32_e32 v147, v147
	v_exp_f32_e32 v149, v149
	v_pk_add_f32 v[146:147], v[146:147], 1.0 op_sel_hi:[1,0]
	s_nop 0
	v_rcp_f32_e32 v225, v146
	v_rcp_f32_e32 v226, v147
	v_pk_add_f32 v[146:147], v[148:149], 1.0 op_sel_hi:[1,0]
	v_cvt_pk_bf16_f32 v148, v225, v226
	v_rcp_f32_e32 v149, v146
	v_rcp_f32_e32 v227, v147
	s_nop 0
	s_nop 0
	s_nop 0
	s_nop 0
	s_nop 0
	v_cvt_pk_bf16_f32 v146, v165, v169
	v_cvt_pk_bf16_f32 v147, v173, v177
	v_cvt_pk_bf16_f32 v149, v149, v227
	s_cbranch_vccnz .LBB0_669
	s_mov_b64 s[22:23], 0
	global_store_dwordx4 v[252:253], v[146:149], off offset:2048
.LBB0_669:
	s_andn2_b64 vcc, exec, s[22:23]
	s_cbranch_vccnz .LBB0_671
	global_store_dwordx4 v[252:253], v[146:149], off offset:2048 sc1
	s_nop 1
.LBB0_671:
	v_mov_b32_e32 v169, v168
	v_pk_fma_f32 v[146:147], v[70:71], v[168:169], v[134:135]
	v_pk_fma_f32 v[148:149], v[72:73], v[168:169], v[136:137]
	v_pk_mul_f32 v[146:147], v[146:147], s[94:95] op_sel_hi:[1,0]
	v_pk_mul_f32 v[148:149], v[148:149], s[94:95] op_sel_hi:[1,0]
	v_exp_f32_e32 v146, v146
	v_exp_f32_e32 v147, v147
	v_exp_f32_e32 v148, v148
	v_exp_f32_e32 v149, v149
	s_and_b64 vcc, exec, s[0:1]
	v_pk_add_f32 v[146:147], v[146:147], 1.0 op_sel_hi:[1,0]
	s_mov_b64 s[22:23], -1
	v_rcp_f32_e32 v165, v146
	v_rcp_f32_e32 v173, v147
	v_pk_add_f32 v[146:147], v[148:149], 1.0 op_sel_hi:[1,0]
	v_pk_fma_f32 v[148:149], v[68:69], v[168:169], v[132:133]
	v_rcp_f32_e32 v177, v146
	v_rcp_f32_e32 v225, v147
	v_pk_fma_f32 v[146:147], v[66:67], v[168:169], v[130:131]
	v_pk_mul_f32 v[148:149], v[148:149], s[94:95] op_sel_hi:[1,0]
	v_pk_mul_f32 v[146:147], v[146:147], s[94:95] op_sel_hi:[1,0]
	v_exp_f32_e32 v148, v148
	v_exp_f32_e32 v146, v146
	v_exp_f32_e32 v147, v147
	v_exp_f32_e32 v149, v149
	v_pk_add_f32 v[146:147], v[146:147], 1.0 op_sel_hi:[1,0]
	s_nop 0
	v_rcp_f32_e32 v169, v146
	v_rcp_f32_e32 v226, v147
	v_pk_add_f32 v[146:147], v[148:149], 1.0 op_sel_hi:[1,0]
	v_cvt_pk_bf16_f32 v148, v169, v226
	v_rcp_f32_e32 v149, v146
	v_rcp_f32_e32 v227, v147
	s_nop 0
	s_nop 0
	s_nop 0
	s_nop 0
	s_nop 0
	v_cvt_pk_bf16_f32 v146, v165, v173
	v_cvt_pk_bf16_f32 v147, v177, v225
	v_cvt_pk_bf16_f32 v149, v149, v227
	s_cbranch_vccnz .LBB0_673
	s_mov_b64 s[22:23], 0
	global_store_dwordx4 v[254:255], v[146:149], off offset:2048
.LBB0_673:
	s_andn2_b64 vcc, exec, s[22:23]
	s_cbranch_vccnz .LBB0_675
	global_store_dwordx4 v[254:255], v[146:149], off offset:2048 sc1
	s_nop 1
.LBB0_675:
	v_ashrrev_i32_e32 v146, 3, v162
	s_nop 0
	s_nop 0
	v_and_b32_e32 v161, 0xffffffe0, v146
	v_pk_fma_f32 v[146:147], v[62:63], v[164:165], v[142:143] op_sel_hi:[1,0,1]
	v_pk_fma_f32 v[148:149], v[64:65], v[164:165], v[144:145] op_sel_hi:[1,0,1]
	v_pk_mul_f32 v[146:147], v[146:147], s[94:95] op_sel_hi:[1,0]
	v_pk_mul_f32 v[148:149], v[148:149], s[94:95] op_sel_hi:[1,0]
	v_exp_f32_e32 v146, v146
	v_exp_f32_e32 v147, v147
	v_exp_f32_e32 v148, v148
	v_exp_f32_e32 v149, v149
	s_and_b64 vcc, exec, s[0:1]
	v_pk_add_f32 v[146:147], v[146:147], 1.0 op_sel_hi:[1,0]
	s_mov_b64 s[22:23], -1
	v_rcp_f32_e32 v165, v147
	v_rcp_f32_e32 v157, v146
	v_pk_add_f32 v[146:147], v[148:149], 1.0 op_sel_hi:[1,0]
	v_pk_fma_f32 v[148:149], v[60:61], v[164:165], v[140:141] op_sel_hi:[1,0,1]
	v_rcp_f32_e32 v169, v146
	v_rcp_f32_e32 v173, v147
	v_pk_fma_f32 v[146:147], v[58:59], v[164:165], v[138:139] op_sel_hi:[1,0,1]
	v_pk_mul_f32 v[148:149], v[148:149], s[94:95] op_sel_hi:[1,0]
	v_pk_mul_f32 v[146:147], v[146:147], s[94:95] op_sel_hi:[1,0]
	v_exp_f32_e32 v148, v148
	v_exp_f32_e32 v146, v146
	v_exp_f32_e32 v147, v147
	v_exp_f32_e32 v149, v149
	v_pk_add_f32 v[146:147], v[146:147], 1.0 op_sel_hi:[1,0]
	s_nop 0
	v_rcp_f32_e32 v177, v146
	v_rcp_f32_e32 v225, v147
	v_pk_add_f32 v[146:147], v[148:149], 1.0 op_sel_hi:[1,0]
	v_cvt_pk_bf16_f32 v148, v177, v225
	v_rcp_f32_e32 v149, v146
	v_rcp_f32_e32 v226, v147
	s_nop 0
	s_nop 0
	s_nop 0
	s_nop 0
	s_nop 0
	v_cvt_pk_bf16_f32 v146, v157, v165
	v_cvt_pk_bf16_f32 v147, v169, v173
	v_cvt_pk_bf16_f32 v149, v149, v226
	s_mov_b32 s98, 0x5000
	s_mov_b32 s99, 0x0
	v_lshl_add_u64 v[252:253], v[250:251], 0, s[98:99]
	s_cbranch_vccnz .LBB0_677
	s_mov_b64 s[22:23], 0
	global_store_dwordx4 v[252:253], v[146:149], off offset:-4096
.LBB0_677:
	s_andn2_b64 vcc, exec, s[22:23]
	s_cbranch_vccnz .LBB0_679
	global_store_dwordx4 v[252:253], v[146:149], off offset:-4096 sc1
	s_nop 1
.LBB0_679:
	v_mov_b32_e32 v165, v164
	v_pk_fma_f32 v[146:147], v[30:31], v[164:165], v[134:135]
	v_pk_fma_f32 v[148:149], v[32:33], v[164:165], v[136:137]
	v_pk_mul_f32 v[146:147], v[146:147], s[94:95] op_sel_hi:[1,0]
	v_pk_mul_f32 v[148:149], v[148:149], s[94:95] op_sel_hi:[1,0]
	v_exp_f32_e32 v146, v146
	v_exp_f32_e32 v147, v147
	v_exp_f32_e32 v148, v148
	v_exp_f32_e32 v149, v149
	s_and_b64 vcc, exec, s[0:1]
	v_pk_add_f32 v[146:147], v[146:147], 1.0 op_sel_hi:[1,0]
	s_mov_b64 s[22:23], -1
	v_rcp_f32_e32 v157, v146
	v_rcp_f32_e32 v169, v147
	v_pk_add_f32 v[146:147], v[148:149], 1.0 op_sel_hi:[1,0]
	v_pk_fma_f32 v[148:149], v[28:29], v[164:165], v[132:133]
	v_rcp_f32_e32 v173, v146
	v_rcp_f32_e32 v177, v147
	v_pk_fma_f32 v[146:147], v[26:27], v[164:165], v[130:131]
	v_pk_mul_f32 v[148:149], v[148:149], s[94:95] op_sel_hi:[1,0]
	v_pk_mul_f32 v[146:147], v[146:147], s[94:95] op_sel_hi:[1,0]
	v_exp_f32_e32 v148, v148
	v_exp_f32_e32 v146, v146
	v_exp_f32_e32 v147, v147
	v_exp_f32_e32 v149, v149
	v_pk_add_f32 v[146:147], v[146:147], 1.0 op_sel_hi:[1,0]
	s_nop 0
	v_rcp_f32_e32 v165, v146
	v_rcp_f32_e32 v225, v147
	v_pk_add_f32 v[146:147], v[148:149], 1.0 op_sel_hi:[1,0]
	v_cvt_pk_bf16_f32 v148, v165, v225
	v_rcp_f32_e32 v149, v146
	v_rcp_f32_e32 v226, v147
	s_nop 0
	s_nop 0
	s_nop 0
	s_nop 0
	s_nop 0
	v_cvt_pk_bf16_f32 v146, v157, v169
	v_cvt_pk_bf16_f32 v147, v173, v177
	v_cvt_pk_bf16_f32 v149, v149, v226
	s_mov_b32 s98, 0x15000
	s_mov_b32 s99, 0x0
	v_lshl_add_u64 v[254:255], v[250:251], 0, s[98:99]
	s_cbranch_vccnz .LBB0_681
	s_mov_b64 s[22:23], 0
	global_store_dwordx4 v[254:255], v[146:149], off offset:-4096

.LBB0_683:
	v_ashrrev_i32_e32 v146, 3, v158
	s_nop 0
	s_nop 0
	s_nop 0
	v_and_b32_e32 v157, 0xffffffe0, v146
	v_pk_fma_f32 v[146:147], v[54:55], v[160:161], v[142:143] op_sel_hi:[1,0,1]
	v_pk_fma_f32 v[148:149], v[56:57], v[160:161], v[144:145] op_sel_hi:[1,0,1]
	v_pk_mul_f32 v[146:147], v[146:147], s[94:95] op_sel_hi:[1,0]
	v_pk_mul_f32 v[148:149], v[148:149], s[94:95] op_sel_hi:[1,0]
	v_exp_f32_e32 v146, v146
	v_exp_f32_e32 v147, v147
	v_exp_f32_e32 v148, v148
	v_exp_f32_e32 v149, v149
	s_and_b64 vcc, exec, s[0:1]
	v_pk_add_f32 v[146:147], v[146:147], 1.0 op_sel_hi:[1,0]
	s_mov_b64 s[22:23], -1
	v_rcp_f32_e32 v161, v146
	v_rcp_f32_e32 v165, v147
	v_pk_add_f32 v[146:147], v[148:149], 1.0 op_sel_hi:[1,0]
	v_pk_fma_f32 v[148:149], v[52:53], v[160:161], v[140:141] op_sel_hi:[1,0,1]
	v_rcp_f32_e32 v169, v146
	v_rcp_f32_e32 v173, v147
	v_pk_fma_f32 v[146:147], v[50:51], v[160:161], v[138:139] op_sel_hi:[1,0,1]
	v_pk_mul_f32 v[148:149], v[148:149], s[94:95] op_sel_hi:[1,0]
	v_pk_mul_f32 v[146:147], v[146:147], s[94:95] op_sel_hi:[1,0]
	v_exp_f32_e32 v148, v148
	v_exp_f32_e32 v146, v146
	v_exp_f32_e32 v147, v147
	v_exp_f32_e32 v149, v149
	v_pk_add_f32 v[146:147], v[146:147], 1.0 op_sel_hi:[1,0]
	s_nop 0
	v_rcp_f32_e32 v177, v146
	v_rcp_f32_e32 v225, v147
	v_pk_add_f32 v[146:147], v[148:149], 1.0 op_sel_hi:[1,0]
	v_cvt_pk_bf16_f32 v148, v177, v225
	v_rcp_f32_e32 v149, v146
	v_rcp_f32_e32 v226, v147
	s_nop 0
	s_nop 0
	s_nop 0
	s_nop 0
	s_nop 0
	v_cvt_pk_bf16_f32 v146, v161, v165
	v_cvt_pk_bf16_f32 v147, v169, v173
	v_cvt_pk_bf16_f32 v149, v149, v226
	s_cbranch_vccnz .LBB0_685
	s_mov_b64 s[22:23], 0
	global_store_dwordx4 v[252:253], v[146:149], off offset:-2048

.LBB0_687:
	v_mov_b32_e32 v161, v160
	v_pk_fma_f32 v[146:147], v[22:23], v[160:161], v[134:135]
	v_pk_fma_f32 v[148:149], v[24:25], v[160:161], v[136:137]
	v_pk_mul_f32 v[146:147], v[146:147], s[94:95] op_sel_hi:[1,0]
	v_pk_mul_f32 v[148:149], v[148:149], s[94:95] op_sel_hi:[1,0]
	v_exp_f32_e32 v146, v146
	v_exp_f32_e32 v147, v147
	v_exp_f32_e32 v148, v148
	v_exp_f32_e32 v149, v149
	s_and_b64 vcc, exec, s[0:1]
	v_pk_add_f32 v[146:147], v[146:147], 1.0 op_sel_hi:[1,0]
	s_mov_b64 s[22:23], -1
	v_rcp_f32_e32 v165, v146
	v_rcp_f32_e32 v169, v147
	v_pk_add_f32 v[146:147], v[148:149], 1.0 op_sel_hi:[1,0]
	v_pk_fma_f32 v[148:149], v[20:21], v[160:161], v[132:133]
	v_rcp_f32_e32 v173, v146
	v_rcp_f32_e32 v177, v147
	v_pk_fma_f32 v[146:147], v[18:19], v[160:161], v[130:131]
	v_pk_mul_f32 v[148:149], v[148:149], s[94:95] op_sel_hi:[1,0]
	v_pk_mul_f32 v[146:147], v[146:147], s[94:95] op_sel_hi:[1,0]
	v_exp_f32_e32 v148, v148
	v_exp_f32_e32 v146, v146
	v_exp_f32_e32 v147, v147
	v_exp_f32_e32 v149, v149
	v_pk_add_f32 v[146:147], v[146:147], 1.0 op_sel_hi:[1,0]
	s_nop 0
	v_rcp_f32_e32 v161, v146
	v_rcp_f32_e32 v225, v147
	v_pk_add_f32 v[146:147], v[148:149], 1.0 op_sel_hi:[1,0]
	v_cvt_pk_bf16_f32 v148, v161, v225
	v_rcp_f32_e32 v149, v146
	v_rcp_f32_e32 v226, v147
	s_nop 0
	s_nop 0
	s_nop 0
	s_nop 0
	s_nop 0
	v_cvt_pk_bf16_f32 v146, v165, v169
	v_cvt_pk_bf16_f32 v147, v173, v177
	v_cvt_pk_bf16_f32 v149, v149, v226
	s_cbranch_vccnz .LBB0_689
	s_mov_b64 s[22:23], 0
	global_store_dwordx4 v[254:255], v[146:149], off offset:-2048

.LBB0_691:
	v_ashrrev_i32_e32 v146, 3, v154
	v_lshrrev_b32_e32 v147, 3, v154
	v_lshlrev_b32_e32 v148, 6, v154
	v_lshlrev_b32_e32 v149, 2, v154
	v_and_b32_e32 v161, 0xffffffe0, v146
	v_lshlrev_b32_e32 v146, 7, v154
	v_and_or_b32 v147, v147, 14, v183
	v_and_b32_e32 v148, 0x3c0, v148
	v_and_b32_e32 v149, 32, v149
	v_and_b32_e32 v146, 0x4000, v146
	v_lshlrev_b32_e32 v147, 10, v147
	v_bitop3_b32 v148, v148, v149, v153 bitop3:0x36
	v_or3_b32 v198, v147, v146, v148
	v_pk_fma_f32 v[146:147], v[46:47], v[156:157], v[142:143] op_sel_hi:[1,0,1]
	v_pk_fma_f32 v[148:149], v[48:49], v[156:157], v[144:145] op_sel_hi:[1,0,1]
	v_pk_mul_f32 v[146:147], v[146:147], s[94:95] op_sel_hi:[1,0]
	v_pk_mul_f32 v[148:149], v[148:149], s[94:95] op_sel_hi:[1,0]
	v_exp_f32_e32 v146, v146
	v_exp_f32_e32 v147, v147
	v_exp_f32_e32 v148, v148
	v_exp_f32_e32 v149, v149
	s_and_b64 vcc, exec, s[0:1]
	v_pk_add_f32 v[146:147], v[146:147], 1.0 op_sel_hi:[1,0]
	s_mov_b64 s[22:23], -1
	v_rcp_f32_e32 v157, v146
	v_rcp_f32_e32 v165, v147
	v_pk_add_f32 v[146:147], v[148:149], 1.0 op_sel_hi:[1,0]
	v_pk_fma_f32 v[148:149], v[44:45], v[156:157], v[140:141] op_sel_hi:[1,0,1]
	v_rcp_f32_e32 v169, v146
	v_rcp_f32_e32 v173, v147
	v_pk_fma_f32 v[146:147], v[42:43], v[156:157], v[138:139] op_sel_hi:[1,0,1]
	v_pk_mul_f32 v[148:149], v[148:149], s[94:95] op_sel_hi:[1,0]
	v_pk_mul_f32 v[146:147], v[146:147], s[94:95] op_sel_hi:[1,0]
	v_exp_f32_e32 v148, v148
	v_exp_f32_e32 v146, v146
	v_exp_f32_e32 v147, v147
	v_exp_f32_e32 v149, v149
	v_pk_add_f32 v[146:147], v[146:147], 1.0 op_sel_hi:[1,0]
	s_nop 0
	v_rcp_f32_e32 v177, v146
	v_rcp_f32_e32 v225, v147
	v_pk_add_f32 v[146:147], v[148:149], 1.0 op_sel_hi:[1,0]
	v_cvt_pk_bf16_f32 v148, v177, v225
	v_rcp_f32_e32 v149, v146
	v_rcp_f32_e32 v226, v147
	s_nop 0
	s_nop 0
	s_nop 0
	s_nop 0
	s_nop 0
	v_cvt_pk_bf16_f32 v146, v157, v165
	v_cvt_pk_bf16_f32 v147, v169, v173
	v_cvt_pk_bf16_f32 v149, v149, v226
	s_cbranch_vccnz .LBB0_693
	s_mov_b64 s[22:23], 0
	global_store_dwordx4 v[252:253], v[146:149], off

.LBB0_695:
	v_mov_b32_e32 v157, v156
	v_pk_fma_f32 v[146:147], v[14:15], v[156:157], v[134:135]
	v_pk_fma_f32 v[148:149], v[16:17], v[156:157], v[136:137]
	v_pk_mul_f32 v[146:147], v[146:147], s[94:95] op_sel_hi:[1,0]
	v_pk_mul_f32 v[148:149], v[148:149], s[94:95] op_sel_hi:[1,0]
	v_exp_f32_e32 v146, v146
	v_exp_f32_e32 v147, v147
	v_exp_f32_e32 v148, v148
	v_exp_f32_e32 v149, v149
	s_and_b64 vcc, exec, s[0:1]
	v_pk_add_f32 v[146:147], v[146:147], 1.0 op_sel_hi:[1,0]
	s_mov_b64 s[22:23], -1
	v_rcp_f32_e32 v165, v146
	v_rcp_f32_e32 v169, v147
	v_pk_add_f32 v[146:147], v[148:149], 1.0 op_sel_hi:[1,0]
	v_pk_fma_f32 v[148:149], v[12:13], v[156:157], v[132:133]
	v_rcp_f32_e32 v173, v146
	v_rcp_f32_e32 v177, v147
	v_pk_fma_f32 v[146:147], v[10:11], v[156:157], v[130:131]
	v_pk_mul_f32 v[148:149], v[148:149], s[94:95] op_sel_hi:[1,0]
	v_pk_mul_f32 v[146:147], v[146:147], s[94:95] op_sel_hi:[1,0]
	v_exp_f32_e32 v148, v148
	v_exp_f32_e32 v146, v146
	v_exp_f32_e32 v147, v147
	v_exp_f32_e32 v149, v149
	v_pk_add_f32 v[146:147], v[146:147], 1.0 op_sel_hi:[1,0]
	s_nop 0
	v_rcp_f32_e32 v157, v146
	v_rcp_f32_e32 v225, v147
	v_pk_add_f32 v[146:147], v[148:149], 1.0 op_sel_hi:[1,0]
	v_cvt_pk_bf16_f32 v148, v157, v225
	v_rcp_f32_e32 v149, v146
	v_rcp_f32_e32 v226, v147
	v_add_u32_e32 v146, v181, v161
	v_ashrrev_i32_e32 v147, 31, v146
	v_lshlrev_b64 v[146:147], 15, v[146:147]
	v_lshl_add_u64 v[146:147], s[72:73], 0, v[146:147]
	v_lshl_add_u64 v[208:209], v[146:147], 0, v[198:199]
	v_cvt_pk_bf16_f32 v146, v165, v169
	v_cvt_pk_bf16_f32 v147, v173, v177
	v_cvt_pk_bf16_f32 v149, v149, v226
	s_cbranch_vccnz .LBB0_697
	s_mov_b64 s[22:23], 0
	global_store_dwordx4 v[254:255], v[146:149], off

.LBB0_699:
	v_pk_fma_f32 v[142:143], v[38:39], v[152:153], v[142:143] op_sel_hi:[1,0,1]
	v_pk_fma_f32 v[138:139], v[34:35], v[152:153], v[138:139] op_sel_hi:[1,0,1]
	v_pk_mul_f32 v[142:143], v[142:143], s[94:95] op_sel_hi:[1,0]
	v_pk_fma_f32 v[144:145], v[40:41], v[152:153], v[144:145] op_sel_hi:[1,0,1]
	v_pk_mul_f32 v[138:139], v[138:139], s[94:95] op_sel_hi:[1,0]
	v_pk_fma_f32 v[140:141], v[36:37], v[152:153], v[140:141] op_sel_hi:[1,0,1]
	v_exp_f32_e32 v142, v142
	v_exp_f32_e32 v143, v143
	v_pk_mul_f32 v[144:145], v[144:145], s[94:95] op_sel_hi:[1,0]
	v_exp_f32_e32 v138, v138
	v_exp_f32_e32 v139, v139
	v_pk_mul_f32 v[140:141], v[140:141], s[94:95] op_sel_hi:[1,0]
	v_exp_f32_e32 v144, v144
	v_exp_f32_e32 v145, v145
	v_exp_f32_e32 v140, v140
	v_exp_f32_e32 v141, v141
	v_lshrrev_b32_e32 v148, 3, v150
	v_lshlrev_b32_e32 v149, 6, v150
	v_lshlrev_b32_e32 v157, 2, v150
	v_lshlrev_b32_e32 v147, 7, v150
	v_and_or_b32 v148, v148, 14, v183
	v_and_b32_e32 v149, 0x3c0, v149
	v_and_b32_e32 v157, 32, v157
	v_and_b32_e32 v147, 0x4000, v147
	v_lshlrev_b32_e32 v148, 10, v148
	v_bitop3_b32 v149, v149, v157, v153 bitop3:0x36
	v_pk_add_f32 v[142:143], v[142:143], 1.0 op_sel_hi:[1,0]
	v_pk_add_f32 v[138:139], v[138:139], 1.0 op_sel_hi:[1,0]
	v_or3_b32 v198, v148, v147, v149
	v_rcp_f32_e32 v147, v142
	v_rcp_f32_e32 v148, v143
	v_pk_add_f32 v[142:143], v[144:145], 1.0 op_sel_hi:[1,0]
	v_rcp_f32_e32 v149, v138
	v_rcp_f32_e32 v153, v139
	v_pk_add_f32 v[138:139], v[140:141], 1.0 op_sel_hi:[1,0]
	v_rcp_f32_e32 v144, v142
	v_rcp_f32_e32 v145, v143
	v_rcp_f32_e32 v141, v138
	v_rcp_f32_e32 v157, v139
	s_nop 0
	s_nop 0
	s_nop 0
	s_nop 0
	s_nop 0
	v_cvt_pk_bf16_f32 v138, v147, v148
	v_cvt_pk_bf16_f32 v139, v144, v145
	v_cvt_pk_bf16_f32 v140, v149, v153
	v_cvt_pk_bf16_f32 v141, v141, v157
	s_and_b64 vcc, exec, s[0:1]
	s_mov_b64 s[22:23], -1
	s_cbranch_vccnz .LBB0_701
	s_mov_b64 s[22:23], 0
	global_store_dwordx4 v[252:253], v[138:141], off offset:2048
.LBB0_701:
	s_andn2_b64 vcc, exec, s[22:23]
	s_cbranch_vccnz .LBB0_703
	global_store_dwordx4 v[252:253], v[138:141], off offset:2048 sc1
	s_nop 1
.LBB0_703:
	v_mov_b32_e32 v153, v152
	v_pk_fma_f32 v[134:135], v[6:7], v[152:153], v[134:135]
	v_pk_fma_f32 v[130:131], v[2:3], v[152:153], v[130:131]
	v_pk_mul_f32 v[134:135], v[134:135], s[94:95] op_sel_hi:[1,0]
	v_pk_fma_f32 v[136:137], v[8:9], v[152:153], v[136:137]
	v_pk_mul_f32 v[130:131], v[130:131], s[94:95] op_sel_hi:[1,0]
	v_pk_fma_f32 v[132:133], v[4:5], v[152:153], v[132:133]
	v_exp_f32_e32 v134, v134
	v_exp_f32_e32 v135, v135
	v_pk_mul_f32 v[136:137], v[136:137], s[94:95] op_sel_hi:[1,0]
	v_exp_f32_e32 v130, v130
	v_exp_f32_e32 v131, v131
	v_pk_mul_f32 v[132:133], v[132:133], s[94:95] op_sel_hi:[1,0]
	v_exp_f32_e32 v136, v136
	v_exp_f32_e32 v137, v137
	v_exp_f32_e32 v132, v132
	v_exp_f32_e32 v133, v133
	v_pk_add_f32 v[134:135], v[134:135], 1.0 op_sel_hi:[1,0]
	v_pk_add_f32 v[130:131], v[130:131], 1.0 op_sel_hi:[1,0]
	v_rcp_f32_e32 v138, v134
	v_rcp_f32_e32 v139, v135
	v_pk_add_f32 v[134:135], v[136:137], 1.0 op_sel_hi:[1,0]
	v_rcp_f32_e32 v140, v130
	v_rcp_f32_e32 v141, v131
	v_pk_add_f32 v[130:131], v[132:133], 1.0 op_sel_hi:[1,0]
	v_rcp_f32_e32 v136, v134
	v_rcp_f32_e32 v137, v135
	v_rcp_f32_e32 v133, v130
	v_rcp_f32_e32 v142, v131
	s_nop 0
	s_nop 0
	s_nop 0
	s_nop 0
	s_nop 0
	v_cvt_pk_bf16_f32 v130, v138, v139
	v_cvt_pk_bf16_f32 v131, v136, v137
	v_cvt_pk_bf16_f32 v132, v140, v141
	v_cvt_pk_bf16_f32 v133, v133, v142
	s_and_b64 vcc, exec, s[0:1]
	s_mov_b64 s[0:1], -1
	s_cbranch_vccnz .LBB0_705
	s_mov_b64 s[0:1], 0
	global_store_dwordx4 v[254:255], v[130:133], off offset:2048
.LBB0_705:
	s_andn2_b64 vcc, exec, s[0:1]
	s_cbranch_vccnz .LBB0_707
	global_store_dwordx4 v[254:255], v[130:133], off offset:2048 sc1
	s_nop 1

.LBB0_708:
	s_and_b64 vcc, exec, s[0:1]
	s_cbranch_vccz .LBB0_726
	v_pk_mul_f32 v[130:131], v[126:127], v[180:181] op_sel_hi:[1,0]
	v_lshlrev_b64 v[134:135], 10, v[178:179]
	v_pk_mul_f32 v[132:133], v[130:131], v[130:131]
	v_ashrrev_i32_e32 v183, 31, v182
	v_pk_fma_f32 v[132:133], v[132:133], s[92:93], 1.0 op_sel_hi:[1,0,0]
	v_lshl_add_u64 v[134:135], s[44:45], 0, v[134:135]
	v_pk_mul_f32 v[132:133], v[130:131], v[132:133]
	v_lshl_add_u64 v[134:135], v[182:183], 1, v[134:135]
	v_pk_mul_f32 v[132:133], v[132:133], s[48:49] op_sel_hi:[1,0]
	s_lshl_b32 s0, s38, 3
	v_pk_mul_f32 v[132:133], v[132:133], s[94:95] op_sel_hi:[1,0]
	v_readlane_b32 s1, v249, 22
	v_exp_f32_e32 v132, v132
	v_exp_f32_e32 v133, v133
	s_add_i32 s0, s1, s0
	v_cmp_eq_u32_e32 vcc, 0, v223
	s_ashr_i32 s1, s0, 31
	v_pk_add_f32 v[132:133], v[132:133], 1.0 op_sel_hi:[1,0]
	s_nop 0
	v_rcp_f32_e32 v132, v132
	v_rcp_f32_e32 v133, v133
	s_nop 0
	v_pk_mul_f32 v[130:131], v[130:131], v[132:133]
	v_pk_mul_f32 v[132:133], v[128:129], v[180:181] op_sel_hi:[1,0]
	v_mov_b32_e32 v139, v131
	v_pk_mul_f32 v[136:137], v[132:133], v[132:133]
	s_nop 0
	v_pk_fma_f32 v[136:137], v[136:137], s[92:93], 1.0 op_sel_hi:[1,0,0]
	s_nop 0
	v_pk_mul_f32 v[136:137], v[132:133], v[136:137]
	s_nop 0
	v_pk_mul_f32 v[136:137], v[136:137], s[48:49] op_sel_hi:[1,0]
	s_nop 0
	v_pk_mul_f32 v[136:137], v[136:137], s[94:95] op_sel_hi:[1,0]
	s_nop 0
	v_exp_f32_e32 v136, v136
	v_exp_f32_e32 v137, v137
	s_nop 0
	v_pk_add_f32 v[136:137], v[136:137], 1.0 op_sel_hi:[1,0]
	s_nop 0
	v_rcp_f32_e32 v136, v136
	v_rcp_f32_e32 v137, v137
	s_nop 0
	v_pk_mul_f32 v[132:133], v[132:133], v[136:137]
	s_nop 0
	v_mov_b32_e32 v136, v132
	v_mov_b32_e32 v137, v130
	v_mov_b32_e32 v138, v133
	v_pk_add_f32 v[136:137], v[136:137], v[138:139]
	v_mov_b32_e32 v138, v131
	v_add_f32_e32 v137, 0, v137
	v_mov_b32_e32 v139, v133
	v_add_f32_e32 v148, v136, v137
	v_mov_b32_e32 v136, v130
	v_mov_b32_e32 v137, v132
	v_pk_mul_f32 v[138:139], v[138:139], v[138:139]
	v_cvt_pk_bf16_f32 v130, v130, v131
	v_pk_fma_f32 v[136:137], v[136:137], v[136:137], v[138:139]
	v_pk_mul_f32 v[138:139], v[122:123], v[180:181] op_sel_hi:[1,0]
	v_cvt_pk_bf16_f32 v131, v132, v133
	v_pk_mul_f32 v[140:141], v[138:139], v[138:139]
	v_pk_add_f32 v[136:137], v[136:137], v[136:137] op_sel:[0,1] op_sel_hi:[1,0]
	v_pk_fma_f32 v[140:141], v[140:141], s[92:93], 1.0 op_sel_hi:[1,0,0]
	s_nop 0
	v_pk_mul_f32 v[140:141], v[138:139], v[140:141]
	s_nop 0
	v_pk_mul_f32 v[140:141], v[140:141], s[48:49] op_sel_hi:[1,0]
	s_nop 0
	v_pk_mul_f32 v[140:141], v[140:141], s[94:95] op_sel_hi:[1,0]
	s_nop 0
	v_exp_f32_e32 v140, v140
	v_exp_f32_e32 v141, v141
	s_nop 0
	v_pk_add_f32 v[140:141], v[140:141], 1.0 op_sel_hi:[1,0]
	s_nop 0
	v_rcp_f32_e32 v140, v140
	v_rcp_f32_e32 v141, v141
	s_nop 0
	v_pk_mul_f32 v[138:139], v[138:139], v[140:141]
	v_pk_mul_f32 v[140:141], v[124:125], v[180:181] op_sel_hi:[1,0]
	v_cvt_pk_bf16_f32 v132, v138, v139
	v_pk_mul_f32 v[142:143], v[140:141], v[140:141]
	v_mov_b32_e32 v145, v139
	v_pk_fma_f32 v[142:143], v[142:143], s[92:93], 1.0 op_sel_hi:[1,0,0]
	s_nop 0
	v_pk_mul_f32 v[142:143], v[140:141], v[142:143]
	s_nop 0
	v_pk_mul_f32 v[142:143], v[142:143], s[48:49] op_sel_hi:[1,0]
	s_nop 0
	v_pk_mul_f32 v[142:143], v[142:143], s[94:95] op_sel_hi:[1,0]
	s_nop 0
	v_exp_f32_e32 v142, v142
	v_exp_f32_e32 v143, v143
	s_nop 0
	v_pk_add_f32 v[142:143], v[142:143], 1.0 op_sel_hi:[1,0]
	s_nop 0
	v_rcp_f32_e32 v142, v142
	v_rcp_f32_e32 v143, v143
	s_nop 0
	v_pk_mul_f32 v[140:141], v[140:141], v[142:143]
	s_nop 0
	v_cvt_pk_bf16_f32 v133, v140, v141
	v_lshl_add_u64 v[250:251], v[134:135], 0, 0
	global_store_dwordx4 v[134:135], v[130:133], off
	v_mov_b32_e32 v143, v138
	v_mov_b32_e32 v142, v140
	v_pk_mul_f32 v[130:131], v[94:95], v[180:181] op_sel_hi:[1,0]
	v_mov_b32_e32 v144, v141
	v_pk_mul_f32 v[132:133], v[130:131], v[130:131]
	v_pk_add_f32 v[146:147], v[142:143], v[144:145]
	v_pk_fma_f32 v[132:133], v[132:133], s[92:93], 1.0 op_sel_hi:[1,0,0]
	v_pk_mul_f32 v[144:145], v[144:145], v[144:145]
	v_pk_mul_f32 v[132:133], v[130:131], v[132:133]
	v_pk_fma_f32 v[142:143], v[142:143], v[142:143], v[144:145]
	v_pk_mul_f32 v[132:133], v[132:133], s[48:49] op_sel_hi:[1,0]
	v_pk_add_f32 v[136:137], v[142:143], v[136:137] op_sel:[1,0] op_sel_hi:[0,1]
	v_pk_mul_f32 v[132:133], v[132:133], s[94:95] op_sel_hi:[1,0]
	v_pk_add_f32 v[136:137], v[142:143], v[136:137]
	v_exp_f32_e32 v132, v132
	v_exp_f32_e32 v133, v133
	v_add_f32_e32 v147, v147, v148
	v_add_f32_e32 v146, v146, v147
	v_pk_add_f32 v[132:133], v[132:133], 1.0 op_sel_hi:[1,0]
	s_nop 0
	v_rcp_f32_e32 v132, v132
	v_rcp_f32_e32 v133, v133
	s_nop 0
	v_pk_mul_f32 v[130:131], v[130:131], v[132:133]
	v_pk_mul_f32 v[132:133], v[96:97], v[180:181] op_sel_hi:[1,0]
	v_mov_b32_e32 v141, v131
	v_pk_mul_f32 v[138:139], v[132:133], v[132:133]
	s_nop 0
	v_pk_fma_f32 v[138:139], v[138:139], s[92:93], 1.0 op_sel_hi:[1,0,0]
	s_nop 0
	v_pk_mul_f32 v[138:139], v[132:133], v[138:139]
	s_nop 0
	v_pk_mul_f32 v[138:139], v[138:139], s[48:49] op_sel_hi:[1,0]
	s_nop 0
	v_pk_mul_f32 v[138:139], v[138:139], s[94:95] op_sel_hi:[1,0]
	s_nop 0
	v_exp_f32_e32 v138, v138
	v_exp_f32_e32 v139, v139
	s_nop 0
	v_pk_add_f32 v[138:139], v[138:139], 1.0 op_sel_hi:[1,0]
	s_nop 0
	v_rcp_f32_e32 v138, v138
	v_rcp_f32_e32 v139, v139
	s_nop 0
	v_pk_mul_f32 v[132:133], v[132:133], v[138:139]
	s_nop 0
	v_mov_b32_e32 v138, v132
	v_mov_b32_e32 v139, v130
	v_mov_b32_e32 v140, v133
	v_pk_add_f32 v[142:143], v[138:139], v[140:141]
	v_pk_mul_f32 v[140:141], v[140:141], v[140:141]
	v_add_f32_e32 v143, v143, v146
	v_pk_fma_f32 v[138:139], v[138:139], v[138:139], v[140:141]
	v_pk_mul_f32 v[146:147], v[92:93], v[180:181] op_sel_hi:[1,0]
	v_pk_add_f32 v[136:137], v[138:139], v[136:137] op_sel:[1,0] op_sel_hi:[0,1]
	v_pk_add_f32 v[136:137], v[138:139], v[136:137]
	v_pk_mul_f32 v[138:139], v[90:91], v[180:181] op_sel_hi:[1,0]
	v_pk_mul_f32 v[148:149], v[146:147], v[146:147]
	v_pk_mul_f32 v[140:141], v[138:139], v[138:139]
	v_pk_fma_f32 v[148:149], v[148:149], s[92:93], 1.0 op_sel_hi:[1,0,0]
	v_pk_fma_f32 v[140:141], v[140:141], s[92:93], 1.0 op_sel_hi:[1,0,0]
	v_pk_mul_f32 v[148:149], v[146:147], v[148:149]
	v_pk_mul_f32 v[140:141], v[138:139], v[140:141]
	v_pk_mul_f32 v[148:149], v[148:149], s[48:49] op_sel_hi:[1,0]
	v_pk_mul_f32 v[140:141], v[140:141], s[48:49] op_sel_hi:[1,0]
	v_pk_mul_f32 v[148:149], v[148:149], s[94:95] op_sel_hi:[1,0]
	v_pk_mul_f32 v[140:141], v[140:141], s[94:95] op_sel_hi:[1,0]
	v_exp_f32_e32 v148, v148
	v_exp_f32_e32 v140, v140
	v_exp_f32_e32 v141, v141
	v_exp_f32_e32 v149, v149
	v_cvt_pk_bf16_f32 v130, v130, v131
	v_cvt_pk_bf16_f32 v131, v132, v133
	v_pk_add_f32 v[140:141], v[140:141], 1.0 op_sel_hi:[1,0]
	v_pk_add_f32 v[148:149], v[148:149], 1.0 op_sel_hi:[1,0]
	v_rcp_f32_e32 v140, v140
	v_rcp_f32_e32 v141, v141
	v_rcp_f32_e32 v148, v148
	v_rcp_f32_e32 v149, v149
	v_add_f32_e32 v142, v142, v143
	v_pk_mul_f32 v[144:145], v[138:139], v[140:141]
	v_pk_mul_f32 v[146:147], v[146:147], v[148:149]
	v_pk_fma_f32 v[138:139], v[138:139], v[140:141], v[144:145] op_sel:[0,0,1] op_sel_hi:[1,1,0]
	v_mul_f32_e32 v140, v144, v144
	v_pk_fma_f32 v[140:141], v[144:145], v[144:145], v[140:141] op_sel_hi:[1,1,0]
	v_pk_mul_f32 v[148:149], v[146:147], v[146:147]
	v_cvt_pk_bf16_f32 v132, v144, v145
	v_cvt_pk_bf16_f32 v133, v146, v147
	s_mov_b32 s98, 0x1000
	s_mov_b32 s99, 0x0
	v_lshl_add_u64 v[252:253], v[250:251], 0, s[98:99]
	global_store_dwordx4 v[252:253], v[130:133], off offset:-3840
	v_mov_b32_e32 v140, v146
	v_mov_b32_e32 v139, v148
	v_pk_mov_b32 v[130:131], v[146:147], v[136:137] op_sel:[1,0]
	v_mov_b32_e32 v143, v149
	v_pk_add_f32 v[130:131], v[140:141], v[130:131]
	v_pk_add_f32 v[132:133], v[138:139], v[142:143]
	s_nop 0
	v_pk_add_f32 v[130:131], v[132:133], v[130:131]
	ds_bpermute_b32 v132, v221, v130
	ds_bpermute_b32 v133, v221, v131
	s_waitcnt lgkmcnt(0)
	v_pk_add_f32 v[130:131], v[130:131], v[132:133]
	ds_bpermute_b32 v132, v222, v130
	ds_bpermute_b32 v133, v222, v131
	s_and_saveexec_b64 s[22:23], vcc
	s_cbranch_execz .LBB0_711
	v_lshl_add_u64 v[134:135], s[78:79], 0, v[206:207]
	v_lshl_add_u64 v[134:135], s[0:1], 2, v[134:135]
	s_waitcnt lgkmcnt(0)
	v_pk_add_f32 v[130:131], v[130:131], v[132:133]
	global_store_dwordx2 v[134:135], v[130:131], off
.LBB0_711:
	s_or_b64 exec, exec, s[22:23]
	v_pk_mul_f32 v[130:131], v[118:119], v[176:177] op_sel_hi:[1,0]
	v_lshlrev_b64 v[134:135], 10, v[174:175]
	s_waitcnt lgkmcnt(0)
	v_pk_mul_f32 v[132:133], v[130:131], v[130:131]
	v_lshl_add_u64 v[134:135], s[44:45], 0, v[134:135]
	v_pk_fma_f32 v[132:133], v[132:133], s[92:93], 1.0 op_sel_hi:[1,0,0]
	v_lshl_add_u64 v[134:135], v[182:183], 1, v[134:135]
	v_pk_mul_f32 v[132:133], v[130:131], v[132:133]
	s_nop 0
	v_pk_mul_f32 v[132:133], v[132:133], s[48:49] op_sel_hi:[1,0]
	s_nop 0
	v_pk_mul_f32 v[132:133], v[132:133], s[94:95] op_sel_hi:[1,0]
	s_nop 0
	v_exp_f32_e32 v132, v132
	v_exp_f32_e32 v133, v133
	s_nop 0
	v_pk_add_f32 v[132:133], v[132:133], 1.0 op_sel_hi:[1,0]
	s_nop 0
	v_rcp_f32_e32 v132, v132
	v_rcp_f32_e32 v133, v133
	s_nop 0
	v_pk_mul_f32 v[130:131], v[130:131], v[132:133]
	v_pk_mul_f32 v[132:133], v[120:121], v[176:177] op_sel_hi:[1,0]
	v_mov_b32_e32 v139, v131
	v_pk_mul_f32 v[136:137], v[132:133], v[132:133]
	s_nop 0
	v_pk_fma_f32 v[136:137], v[136:137], s[92:93], 1.0 op_sel_hi:[1,0,0]
	s_nop 0
	v_pk_mul_f32 v[136:137], v[132:133], v[136:137]
	s_nop 0
	v_pk_mul_f32 v[136:137], v[136:137], s[48:49] op_sel_hi:[1,0]
	s_nop 0
	v_pk_mul_f32 v[136:137], v[136:137], s[94:95] op_sel_hi:[1,0]
	s_nop 0
	v_exp_f32_e32 v136, v136
	v_exp_f32_e32 v137, v137
	s_nop 0
	v_pk_add_f32 v[136:137], v[136:137], 1.0 op_sel_hi:[1,0]
	s_nop 0
	v_rcp_f32_e32 v136, v136
	v_rcp_f32_e32 v137, v137
	s_nop 0
	v_pk_mul_f32 v[132:133], v[132:133], v[136:137]
	s_nop 0
	v_mov_b32_e32 v136, v132
	v_mov_b32_e32 v137, v130
	v_mov_b32_e32 v138, v133
	v_pk_add_f32 v[136:137], v[136:137], v[138:139]
	v_mov_b32_e32 v138, v131
	v_add_f32_e32 v137, 0, v137
	v_mov_b32_e32 v139, v133
	v_add_f32_e32 v148, v136, v137
	v_mov_b32_e32 v136, v130
	v_mov_b32_e32 v137, v132
	v_pk_mul_f32 v[138:139], v[138:139], v[138:139]
	v_cvt_pk_bf16_f32 v130, v130, v131
	v_pk_fma_f32 v[136:137], v[136:137], v[136:137], v[138:139]
	v_pk_mul_f32 v[138:139], v[114:115], v[176:177] op_sel_hi:[1,0]
	v_cvt_pk_bf16_f32 v131, v132, v133
	v_pk_mul_f32 v[140:141], v[138:139], v[138:139]
	v_pk_add_f32 v[136:137], v[136:137], v[136:137] op_sel:[0,1] op_sel_hi:[1,0]
	v_pk_fma_f32 v[140:141], v[140:141], s[92:93], 1.0 op_sel_hi:[1,0,0]
	s_nop 0
	v_pk_mul_f32 v[140:141], v[138:139], v[140:141]
	s_nop 0
	v_pk_mul_f32 v[140:141], v[140:141], s[48:49] op_sel_hi:[1,0]
	s_nop 0
	v_pk_mul_f32 v[140:141], v[140:141], s[94:95] op_sel_hi:[1,0]
	s_nop 0
	v_exp_f32_e32 v140, v140
	v_exp_f32_e32 v141, v141
	s_nop 0
	v_pk_add_f32 v[140:141], v[140:141], 1.0 op_sel_hi:[1,0]
	s_nop 0
	v_rcp_f32_e32 v140, v140
	v_rcp_f32_e32 v141, v141
	s_nop 0
	v_pk_mul_f32 v[138:139], v[138:139], v[140:141]
	v_pk_mul_f32 v[140:141], v[116:117], v[176:177] op_sel_hi:[1,0]
	v_cvt_pk_bf16_f32 v132, v138, v139
	v_pk_mul_f32 v[142:143], v[140:141], v[140:141]
	v_mov_b32_e32 v145, v139
	v_pk_fma_f32 v[142:143], v[142:143], s[92:93], 1.0 op_sel_hi:[1,0,0]
	s_nop 0
	v_pk_mul_f32 v[142:143], v[140:141], v[142:143]
	s_nop 0
	v_pk_mul_f32 v[142:143], v[142:143], s[48:49] op_sel_hi:[1,0]
	s_nop 0
	v_pk_mul_f32 v[142:143], v[142:143], s[94:95] op_sel_hi:[1,0]
	s_nop 0
	v_exp_f32_e32 v142, v142
	v_exp_f32_e32 v143, v143
	s_nop 0
	v_pk_add_f32 v[142:143], v[142:143], 1.0 op_sel_hi:[1,0]
	s_nop 0
	v_rcp_f32_e32 v142, v142
	v_rcp_f32_e32 v143, v143
	s_nop 0
	v_pk_mul_f32 v[140:141], v[140:141], v[142:143]
	s_nop 0
	v_cvt_pk_bf16_f32 v133, v140, v141
	s_mov_b32 s98, 0x5000
	s_mov_b32 s99, 0x0
	v_lshl_add_u64 v[252:253], v[250:251], 0, s[98:99]
	global_store_dwordx4 v[252:253], v[130:133], off offset:-4096
	v_mov_b32_e32 v143, v138
	v_mov_b32_e32 v142, v140
	v_pk_mul_f32 v[130:131], v[86:87], v[176:177] op_sel_hi:[1,0]
	v_mov_b32_e32 v144, v141
	v_pk_mul_f32 v[132:133], v[130:131], v[130:131]
	v_pk_add_f32 v[146:147], v[142:143], v[144:145]
	v_pk_fma_f32 v[132:133], v[132:133], s[92:93], 1.0 op_sel_hi:[1,0,0]
	v_pk_mul_f32 v[144:145], v[144:145], v[144:145]
	v_pk_mul_f32 v[132:133], v[130:131], v[132:133]
	v_pk_fma_f32 v[142:143], v[142:143], v[142:143], v[144:145]
	v_pk_mul_f32 v[132:133], v[132:133], s[48:49] op_sel_hi:[1,0]
	v_pk_add_f32 v[136:137], v[142:143], v[136:137] op_sel:[1,0] op_sel_hi:[0,1]
	v_pk_mul_f32 v[132:133], v[132:133], s[94:95] op_sel_hi:[1,0]
	v_pk_add_f32 v[136:137], v[142:143], v[136:137]
	v_exp_f32_e32 v132, v132
	v_exp_f32_e32 v133, v133
	v_add_f32_e32 v147, v147, v148
	v_add_f32_e32 v146, v146, v147
	v_pk_add_f32 v[132:133], v[132:133], 1.0 op_sel_hi:[1,0]
	s_nop 0
	v_rcp_f32_e32 v132, v132
	v_rcp_f32_e32 v133, v133
	s_nop 0
	v_pk_mul_f32 v[130:131], v[130:131], v[132:133]
	v_pk_mul_f32 v[132:133], v[88:89], v[176:177] op_sel_hi:[1,0]
	v_mov_b32_e32 v141, v131
	v_pk_mul_f32 v[138:139], v[132:133], v[132:133]
	s_nop 0
	v_pk_fma_f32 v[138:139], v[138:139], s[92:93], 1.0 op_sel_hi:[1,0,0]
	s_nop 0
	v_pk_mul_f32 v[138:139], v[132:133], v[138:139]
	s_nop 0
	v_pk_mul_f32 v[138:139], v[138:139], s[48:49] op_sel_hi:[1,0]
	s_nop 0
	v_pk_mul_f32 v[138:139], v[138:139], s[94:95] op_sel_hi:[1,0]
	s_nop 0
	v_exp_f32_e32 v138, v138
	v_exp_f32_e32 v139, v139
	s_nop 0
	v_pk_add_f32 v[138:139], v[138:139], 1.0 op_sel_hi:[1,0]
	s_nop 0
	v_rcp_f32_e32 v138, v138
	v_rcp_f32_e32 v139, v139
	s_nop 0
	v_pk_mul_f32 v[132:133], v[132:133], v[138:139]
	s_nop 0
	v_mov_b32_e32 v138, v132
	v_mov_b32_e32 v139, v130
	v_mov_b32_e32 v140, v133
	v_pk_add_f32 v[142:143], v[138:139], v[140:141]
	v_pk_mul_f32 v[140:141], v[140:141], v[140:141]
	v_add_f32_e32 v143, v143, v146
	v_pk_fma_f32 v[138:139], v[138:139], v[138:139], v[140:141]
	v_pk_mul_f32 v[146:147], v[84:85], v[176:177] op_sel_hi:[1,0]
	v_pk_add_f32 v[136:137], v[138:139], v[136:137] op_sel:[1,0] op_sel_hi:[0,1]
	v_pk_add_f32 v[136:137], v[138:139], v[136:137]
	v_pk_mul_f32 v[138:139], v[82:83], v[176:177] op_sel_hi:[1,0]
	v_pk_mul_f32 v[148:149], v[146:147], v[146:147]
	v_pk_mul_f32 v[140:141], v[138:139], v[138:139]
	v_pk_fma_f32 v[148:149], v[148:149], s[92:93], 1.0 op_sel_hi:[1,0,0]
	v_pk_fma_f32 v[140:141], v[140:141], s[92:93], 1.0 op_sel_hi:[1,0,0]
	v_pk_mul_f32 v[148:149], v[146:147], v[148:149]
	v_pk_mul_f32 v[140:141], v[138:139], v[140:141]
	v_pk_mul_f32 v[148:149], v[148:149], s[48:49] op_sel_hi:[1,0]
	v_pk_mul_f32 v[140:141], v[140:141], s[48:49] op_sel_hi:[1,0]
	v_pk_mul_f32 v[148:149], v[148:149], s[94:95] op_sel_hi:[1,0]
	v_pk_mul_f32 v[140:141], v[140:141], s[94:95] op_sel_hi:[1,0]
	v_exp_f32_e32 v148, v148
	v_exp_f32_e32 v140, v140
	v_exp_f32_e32 v141, v141
	v_exp_f32_e32 v149, v149
	v_cvt_pk_bf16_f32 v130, v130, v131
	v_cvt_pk_bf16_f32 v131, v132, v133
	v_pk_add_f32 v[140:141], v[140:141], 1.0 op_sel_hi:[1,0]
	v_pk_add_f32 v[148:149], v[148:149], 1.0 op_sel_hi:[1,0]
	v_rcp_f32_e32 v140, v140
	v_rcp_f32_e32 v141, v141
	v_rcp_f32_e32 v148, v148
	v_rcp_f32_e32 v149, v149
	v_add_f32_e32 v142, v142, v143
	v_pk_mul_f32 v[144:145], v[138:139], v[140:141]
	v_pk_mul_f32 v[146:147], v[146:147], v[148:149]
	v_pk_fma_f32 v[138:139], v[138:139], v[140:141], v[144:145] op_sel:[0,0,1] op_sel_hi:[1,1,0]
	v_mul_f32_e32 v140, v144, v144
	v_pk_fma_f32 v[140:141], v[144:145], v[144:145], v[140:141] op_sel_hi:[1,1,0]
	v_pk_mul_f32 v[148:149], v[146:147], v[146:147]
	v_cvt_pk_bf16_f32 v132, v144, v145
	v_cvt_pk_bf16_f32 v133, v146, v147
	global_store_dwordx4 v[252:253], v[130:133], off offset:-3840
	v_mov_b32_e32 v140, v146
	v_mov_b32_e32 v139, v148
	v_pk_mov_b32 v[130:131], v[146:147], v[136:137] op_sel:[1,0]
	v_mov_b32_e32 v143, v149
	v_pk_add_f32 v[130:131], v[140:141], v[130:131]
	v_pk_add_f32 v[132:133], v[138:139], v[142:143]
	s_nop 0
	v_pk_add_f32 v[130:131], v[132:133], v[130:131]
	ds_bpermute_b32 v132, v221, v130
	ds_bpermute_b32 v133, v221, v131
	s_waitcnt lgkmcnt(0)
	v_pk_add_f32 v[130:131], v[130:131], v[132:133]
	ds_bpermute_b32 v132, v222, v130
	ds_bpermute_b32 v133, v222, v131
	s_and_saveexec_b64 s[22:23], vcc
	s_cbranch_execz .LBB0_713
	v_lshl_add_u64 v[134:135], s[78:79], 0, v[204:205]
	v_lshl_add_u64 v[134:135], s[0:1], 2, v[134:135]
	s_waitcnt lgkmcnt(0)
	v_pk_add_f32 v[130:131], v[130:131], v[132:133]
	global_store_dwordx2 v[134:135], v[130:131], off
.LBB0_713:
	s_or_b64 exec, exec, s[22:23]
	v_pk_mul_f32 v[130:131], v[110:111], v[172:173] op_sel_hi:[1,0]
	v_lshlrev_b64 v[134:135], 10, v[170:171]
	s_waitcnt lgkmcnt(0)
	v_pk_mul_f32 v[132:133], v[130:131], v[130:131]
	v_lshl_add_u64 v[134:135], s[44:45], 0, v[134:135]
	v_pk_fma_f32 v[132:133], v[132:133], s[92:93], 1.0 op_sel_hi:[1,0,0]
	v_lshl_add_u64 v[134:135], v[182:183], 1, v[134:135]
	v_pk_mul_f32 v[132:133], v[130:131], v[132:133]
	s_nop 0
	v_pk_mul_f32 v[132:133], v[132:133], s[48:49] op_sel_hi:[1,0]
	s_nop 0
	v_pk_mul_f32 v[132:133], v[132:133], s[94:95] op_sel_hi:[1,0]
	s_nop 0
	v_exp_f32_e32 v132, v132
	v_exp_f32_e32 v133, v133
	s_nop 0
	v_pk_add_f32 v[132:133], v[132:133], 1.0 op_sel_hi:[1,0]
	s_nop 0
	v_rcp_f32_e32 v132, v132
	v_rcp_f32_e32 v133, v133
	s_nop 0
	v_pk_mul_f32 v[130:131], v[130:131], v[132:133]
	v_pk_mul_f32 v[132:133], v[112:113], v[172:173] op_sel_hi:[1,0]
	v_mov_b32_e32 v139, v131
	v_pk_mul_f32 v[136:137], v[132:133], v[132:133]
	s_nop 0
	v_pk_fma_f32 v[136:137], v[136:137], s[92:93], 1.0 op_sel_hi:[1,0,0]
	s_nop 0
	v_pk_mul_f32 v[136:137], v[132:133], v[136:137]
	s_nop 0
	v_pk_mul_f32 v[136:137], v[136:137], s[48:49] op_sel_hi:[1,0]
	s_nop 0
	v_pk_mul_f32 v[136:137], v[136:137], s[94:95] op_sel_hi:[1,0]
	s_nop 0
	v_exp_f32_e32 v136, v136
	v_exp_f32_e32 v137, v137
	s_nop 0
	v_pk_add_f32 v[136:137], v[136:137], 1.0 op_sel_hi:[1,0]
	s_nop 0
	v_rcp_f32_e32 v136, v136
	v_rcp_f32_e32 v137, v137
	s_nop 0
	v_pk_mul_f32 v[132:133], v[132:133], v[136:137]
	s_nop 0
	v_mov_b32_e32 v136, v132
	v_mov_b32_e32 v137, v130
	v_mov_b32_e32 v138, v133
	v_pk_add_f32 v[136:137], v[136:137], v[138:139]
	v_mov_b32_e32 v138, v131
	v_add_f32_e32 v137, 0, v137
	v_mov_b32_e32 v139, v133
	v_add_f32_e32 v148, v136, v137
	v_mov_b32_e32 v136, v130
	v_mov_b32_e32 v137, v132
	v_pk_mul_f32 v[138:139], v[138:139], v[138:139]
	v_cvt_pk_bf16_f32 v130, v130, v131
	v_pk_fma_f32 v[136:137], v[136:137], v[136:137], v[138:139]
	v_pk_mul_f32 v[138:139], v[106:107], v[172:173] op_sel_hi:[1,0]
	v_cvt_pk_bf16_f32 v131, v132, v133
	v_pk_mul_f32 v[140:141], v[138:139], v[138:139]
	v_pk_add_f32 v[136:137], v[136:137], v[136:137] op_sel:[0,1] op_sel_hi:[1,0]
	v_pk_fma_f32 v[140:141], v[140:141], s[92:93], 1.0 op_sel_hi:[1,0,0]
	s_nop 0
	v_pk_mul_f32 v[140:141], v[138:139], v[140:141]
	s_nop 0
	v_pk_mul_f32 v[140:141], v[140:141], s[48:49] op_sel_hi:[1,0]
	s_nop 0
	v_pk_mul_f32 v[140:141], v[140:141], s[94:95] op_sel_hi:[1,0]
	s_nop 0
	v_exp_f32_e32 v140, v140
	v_exp_f32_e32 v141, v141
	s_nop 0
	v_pk_add_f32 v[140:141], v[140:141], 1.0 op_sel_hi:[1,0]
	s_nop 0
	v_rcp_f32_e32 v140, v140
	v_rcp_f32_e32 v141, v141
	s_nop 0
	v_pk_mul_f32 v[138:139], v[138:139], v[140:141]
	v_pk_mul_f32 v[140:141], v[108:109], v[172:173] op_sel_hi:[1,0]
	v_cvt_pk_bf16_f32 v132, v138, v139
	v_pk_mul_f32 v[142:143], v[140:141], v[140:141]
	v_mov_b32_e32 v145, v139
	v_pk_fma_f32 v[142:143], v[142:143], s[92:93], 1.0 op_sel_hi:[1,0,0]
	s_nop 0
	v_pk_mul_f32 v[142:143], v[140:141], v[142:143]
	s_nop 0
	v_pk_mul_f32 v[142:143], v[142:143], s[48:49] op_sel_hi:[1,0]
	s_nop 0
	v_pk_mul_f32 v[142:143], v[142:143], s[94:95] op_sel_hi:[1,0]
	s_nop 0
	v_exp_f32_e32 v142, v142
	v_exp_f32_e32 v143, v143
	s_nop 0
	v_pk_add_f32 v[142:143], v[142:143], 1.0 op_sel_hi:[1,0]
	s_nop 0
	v_rcp_f32_e32 v142, v142
	v_rcp_f32_e32 v143, v143
	s_nop 0
	v_pk_mul_f32 v[140:141], v[140:141], v[142:143]
	s_nop 0
	v_cvt_pk_bf16_f32 v133, v140, v141
	s_mov_b32 s98, 0x9000
	s_mov_b32 s99, 0x0
	v_lshl_add_u64 v[252:253], v[250:251], 0, s[98:99]
	global_store_dwordx4 v[252:253], v[130:133], off offset:-4096
	v_mov_b32_e32 v143, v138
	v_mov_b32_e32 v142, v140
	v_pk_mul_f32 v[130:131], v[78:79], v[172:173] op_sel_hi:[1,0]
	v_mov_b32_e32 v144, v141
	v_pk_mul_f32 v[132:133], v[130:131], v[130:131]
	v_pk_add_f32 v[146:147], v[142:143], v[144:145]
	v_pk_fma_f32 v[132:133], v[132:133], s[92:93], 1.0 op_sel_hi:[1,0,0]
	v_pk_mul_f32 v[144:145], v[144:145], v[144:145]
	v_pk_mul_f32 v[132:133], v[130:131], v[132:133]
	v_pk_fma_f32 v[142:143], v[142:143], v[142:143], v[144:145]
	v_pk_mul_f32 v[132:133], v[132:133], s[48:49] op_sel_hi:[1,0]
	v_pk_add_f32 v[136:137], v[142:143], v[136:137] op_sel:[1,0] op_sel_hi:[0,1]
	v_pk_mul_f32 v[132:133], v[132:133], s[94:95] op_sel_hi:[1,0]
	v_pk_add_f32 v[136:137], v[142:143], v[136:137]
	v_exp_f32_e32 v132, v132
	v_exp_f32_e32 v133, v133
	v_add_f32_e32 v147, v147, v148
	v_add_f32_e32 v146, v146, v147
	v_pk_add_f32 v[132:133], v[132:133], 1.0 op_sel_hi:[1,0]
	s_nop 0
	v_rcp_f32_e32 v132, v132
	v_rcp_f32_e32 v133, v133
	s_nop 0
	v_pk_mul_f32 v[130:131], v[130:131], v[132:133]
	v_pk_mul_f32 v[132:133], v[80:81], v[172:173] op_sel_hi:[1,0]
	v_mov_b32_e32 v141, v131
	v_pk_mul_f32 v[138:139], v[132:133], v[132:133]
	s_nop 0
	v_pk_fma_f32 v[138:139], v[138:139], s[92:93], 1.0 op_sel_hi:[1,0,0]
	s_nop 0
	v_pk_mul_f32 v[138:139], v[132:133], v[138:139]
	s_nop 0
	v_pk_mul_f32 v[138:139], v[138:139], s[48:49] op_sel_hi:[1,0]
	s_nop 0
	v_pk_mul_f32 v[138:139], v[138:139], s[94:95] op_sel_hi:[1,0]
	s_nop 0
	v_exp_f32_e32 v138, v138
	v_exp_f32_e32 v139, v139
	s_nop 0
	v_pk_add_f32 v[138:139], v[138:139], 1.0 op_sel_hi:[1,0]
	s_nop 0
	v_rcp_f32_e32 v138, v138
	v_rcp_f32_e32 v139, v139
	s_nop 0
	v_pk_mul_f32 v[132:133], v[132:133], v[138:139]
	s_nop 0
	v_mov_b32_e32 v138, v132
	v_mov_b32_e32 v139, v130
	v_mov_b32_e32 v140, v133
	v_pk_add_f32 v[142:143], v[138:139], v[140:141]
	v_pk_mul_f32 v[140:141], v[140:141], v[140:141]
	v_add_f32_e32 v143, v143, v146
	v_pk_fma_f32 v[138:139], v[138:139], v[138:139], v[140:141]
	v_pk_mul_f32 v[146:147], v[76:77], v[172:173] op_sel_hi:[1,0]
	v_pk_add_f32 v[136:137], v[138:139], v[136:137] op_sel:[1,0] op_sel_hi:[0,1]
	v_pk_add_f32 v[136:137], v[138:139], v[136:137]
	v_pk_mul_f32 v[138:139], v[74:75], v[172:173] op_sel_hi:[1,0]
	v_pk_mul_f32 v[148:149], v[146:147], v[146:147]
	v_pk_mul_f32 v[140:141], v[138:139], v[138:139]
	v_pk_fma_f32 v[148:149], v[148:149], s[92:93], 1.0 op_sel_hi:[1,0,0]
	v_pk_fma_f32 v[140:141], v[140:141], s[92:93], 1.0 op_sel_hi:[1,0,0]
	v_pk_mul_f32 v[148:149], v[146:147], v[148:149]
	v_pk_mul_f32 v[140:141], v[138:139], v[140:141]
	v_pk_mul_f32 v[148:149], v[148:149], s[48:49] op_sel_hi:[1,0]
	v_pk_mul_f32 v[140:141], v[140:141], s[48:49] op_sel_hi:[1,0]
	v_pk_mul_f32 v[148:149], v[148:149], s[94:95] op_sel_hi:[1,0]
	v_pk_mul_f32 v[140:141], v[140:141], s[94:95] op_sel_hi:[1,0]
	v_exp_f32_e32 v148, v148
	v_exp_f32_e32 v140, v140
	v_exp_f32_e32 v141, v141
	v_exp_f32_e32 v149, v149
	v_cvt_pk_bf16_f32 v130, v130, v131
	v_cvt_pk_bf16_f32 v131, v132, v133
	v_pk_add_f32 v[140:141], v[140:141], 1.0 op_sel_hi:[1,0]
	v_pk_add_f32 v[148:149], v[148:149], 1.0 op_sel_hi:[1,0]
	v_rcp_f32_e32 v140, v140
	v_rcp_f32_e32 v141, v141
	v_rcp_f32_e32 v148, v148
	v_rcp_f32_e32 v149, v149
	v_add_f32_e32 v142, v142, v143
	v_pk_mul_f32 v[144:145], v[138:139], v[140:141]
	v_pk_mul_f32 v[146:147], v[146:147], v[148:149]
	v_pk_fma_f32 v[138:139], v[138:139], v[140:141], v[144:145] op_sel:[0,0,1] op_sel_hi:[1,1,0]
	v_mul_f32_e32 v140, v144, v144
	v_pk_fma_f32 v[140:141], v[144:145], v[144:145], v[140:141] op_sel_hi:[1,1,0]
	v_pk_mul_f32 v[148:149], v[146:147], v[146:147]
	v_cvt_pk_bf16_f32 v132, v144, v145
	v_cvt_pk_bf16_f32 v133, v146, v147
	global_store_dwordx4 v[252:253], v[130:133], off offset:-3840
	v_mov_b32_e32 v140, v146
	v_mov_b32_e32 v139, v148
	v_pk_mov_b32 v[130:131], v[146:147], v[136:137] op_sel:[1,0]
	v_mov_b32_e32 v143, v149
	v_pk_add_f32 v[130:131], v[140:141], v[130:131]
	v_pk_add_f32 v[132:133], v[138:139], v[142:143]
	s_nop 0
	v_pk_add_f32 v[130:131], v[132:133], v[130:131]
	ds_bpermute_b32 v132, v221, v130
	ds_bpermute_b32 v133, v221, v131
	s_waitcnt lgkmcnt(0)
	v_pk_add_f32 v[130:131], v[130:131], v[132:133]
	ds_bpermute_b32 v132, v222, v130
	ds_bpermute_b32 v133, v222, v131
	s_and_saveexec_b64 s[22:23], vcc
	s_cbranch_execz .LBB0_715
	v_lshl_add_u64 v[134:135], s[78:79], 0, v[202:203]
	v_lshl_add_u64 v[134:135], s[0:1], 2, v[134:135]
	s_waitcnt lgkmcnt(0)
	v_pk_add_f32 v[130:131], v[130:131], v[132:133]
	global_store_dwordx2 v[134:135], v[130:131], off
.LBB0_715:
	s_or_b64 exec, exec, s[22:23]
	v_pk_mul_f32 v[130:131], v[102:103], v[168:169] op_sel_hi:[1,0]
	v_lshlrev_b64 v[134:135], 10, v[166:167]
	s_waitcnt lgkmcnt(0)
	v_pk_mul_f32 v[132:133], v[130:131], v[130:131]
	v_lshl_add_u64 v[134:135], s[44:45], 0, v[134:135]
	v_pk_fma_f32 v[132:133], v[132:133], s[92:93], 1.0 op_sel_hi:[1,0,0]
	v_lshl_add_u64 v[134:135], v[182:183], 1, v[134:135]
	v_pk_mul_f32 v[132:133], v[130:131], v[132:133]
	s_nop 0
	v_pk_mul_f32 v[132:133], v[132:133], s[48:49] op_sel_hi:[1,0]
	s_nop 0
	v_pk_mul_f32 v[132:133], v[132:133], s[94:95] op_sel_hi:[1,0]
	s_nop 0
	v_exp_f32_e32 v132, v132
	v_exp_f32_e32 v133, v133
	s_nop 0
	v_pk_add_f32 v[132:133], v[132:133], 1.0 op_sel_hi:[1,0]
	s_nop 0
	v_rcp_f32_e32 v132, v132
	v_rcp_f32_e32 v133, v133
	s_nop 0
	v_pk_mul_f32 v[130:131], v[130:131], v[132:133]
	v_pk_mul_f32 v[132:133], v[104:105], v[168:169] op_sel_hi:[1,0]
	v_mov_b32_e32 v139, v131
	v_pk_mul_f32 v[136:137], v[132:133], v[132:133]
	s_nop 0
	v_pk_fma_f32 v[136:137], v[136:137], s[92:93], 1.0 op_sel_hi:[1,0,0]
	s_nop 0
	v_pk_mul_f32 v[136:137], v[132:133], v[136:137]
	s_nop 0
	v_pk_mul_f32 v[136:137], v[136:137], s[48:49] op_sel_hi:[1,0]
	s_nop 0
	v_pk_mul_f32 v[136:137], v[136:137], s[94:95] op_sel_hi:[1,0]
	s_nop 0
	v_exp_f32_e32 v136, v136
	v_exp_f32_e32 v137, v137
	s_nop 0
	v_pk_add_f32 v[136:137], v[136:137], 1.0 op_sel_hi:[1,0]
	s_nop 0
	v_rcp_f32_e32 v136, v136
	v_rcp_f32_e32 v137, v137
	s_nop 0
	v_pk_mul_f32 v[132:133], v[132:133], v[136:137]
	s_nop 0
	v_mov_b32_e32 v136, v132
	v_mov_b32_e32 v137, v130
	v_mov_b32_e32 v138, v133
	v_pk_add_f32 v[136:137], v[136:137], v[138:139]
	v_mov_b32_e32 v138, v131
	v_add_f32_e32 v137, 0, v137
	v_mov_b32_e32 v139, v133
	v_add_f32_e32 v148, v136, v137
	v_mov_b32_e32 v136, v130
	v_mov_b32_e32 v137, v132
	v_pk_mul_f32 v[138:139], v[138:139], v[138:139]
	v_cvt_pk_bf16_f32 v130, v130, v131
	v_pk_fma_f32 v[136:137], v[136:137], v[136:137], v[138:139]
	v_pk_mul_f32 v[138:139], v[98:99], v[168:169] op_sel_hi:[1,0]
	v_cvt_pk_bf16_f32 v131, v132, v133
	v_pk_mul_f32 v[140:141], v[138:139], v[138:139]
	v_pk_add_f32 v[136:137], v[136:137], v[136:137] op_sel:[0,1] op_sel_hi:[1,0]
	v_pk_fma_f32 v[140:141], v[140:141], s[92:93], 1.0 op_sel_hi:[1,0,0]
	s_nop 0
	v_pk_mul_f32 v[140:141], v[138:139], v[140:141]
	s_nop 0
	v_pk_mul_f32 v[140:141], v[140:141], s[48:49] op_sel_hi:[1,0]
	s_nop 0
	v_pk_mul_f32 v[140:141], v[140:141], s[94:95] op_sel_hi:[1,0]
	s_nop 0
	v_exp_f32_e32 v140, v140
	v_exp_f32_e32 v141, v141
	s_nop 0
	v_pk_add_f32 v[140:141], v[140:141], 1.0 op_sel_hi:[1,0]
	s_nop 0
	v_rcp_f32_e32 v140, v140
	v_rcp_f32_e32 v141, v141
	s_nop 0
	v_pk_mul_f32 v[138:139], v[138:139], v[140:141]
	v_pk_mul_f32 v[140:141], v[100:101], v[168:169] op_sel_hi:[1,0]
	v_cvt_pk_bf16_f32 v132, v138, v139
	v_pk_mul_f32 v[142:143], v[140:141], v[140:141]
	v_mov_b32_e32 v145, v139
	v_pk_fma_f32 v[142:143], v[142:143], s[92:93], 1.0 op_sel_hi:[1,0,0]
	s_nop 0
	v_pk_mul_f32 v[142:143], v[140:141], v[142:143]
	s_nop 0
	v_pk_mul_f32 v[142:143], v[142:143], s[48:49] op_sel_hi:[1,0]
	s_nop 0
	v_pk_mul_f32 v[142:143], v[142:143], s[94:95] op_sel_hi:[1,0]
	s_nop 0
	v_exp_f32_e32 v142, v142
	v_exp_f32_e32 v143, v143
	s_nop 0
	v_pk_add_f32 v[142:143], v[142:143], 1.0 op_sel_hi:[1,0]
	s_nop 0
	v_rcp_f32_e32 v142, v142
	v_rcp_f32_e32 v143, v143
	s_nop 0
	v_pk_mul_f32 v[140:141], v[140:141], v[142:143]
	s_nop 0
	v_cvt_pk_bf16_f32 v133, v140, v141
	s_mov_b32 s98, 0xd000
	s_mov_b32 s99, 0x0
	v_lshl_add_u64 v[252:253], v[250:251], 0, s[98:99]
	global_store_dwordx4 v[252:253], v[130:133], off offset:-4096
	v_mov_b32_e32 v143, v138
	v_mov_b32_e32 v142, v140
	v_pk_mul_f32 v[130:131], v[70:71], v[168:169] op_sel_hi:[1,0]
	v_mov_b32_e32 v144, v141
	v_pk_mul_f32 v[132:133], v[130:131], v[130:131]
	v_pk_add_f32 v[146:147], v[142:143], v[144:145]
	v_pk_fma_f32 v[132:133], v[132:133], s[92:93], 1.0 op_sel_hi:[1,0,0]
	v_pk_mul_f32 v[144:145], v[144:145], v[144:145]
	v_pk_mul_f32 v[132:133], v[130:131], v[132:133]
	v_pk_fma_f32 v[142:143], v[142:143], v[142:143], v[144:145]
	v_pk_mul_f32 v[132:133], v[132:133], s[48:49] op_sel_hi:[1,0]
	v_pk_add_f32 v[136:137], v[142:143], v[136:137] op_sel:[1,0] op_sel_hi:[0,1]
	v_pk_mul_f32 v[132:133], v[132:133], s[94:95] op_sel_hi:[1,0]
	v_pk_add_f32 v[136:137], v[142:143], v[136:137]
	v_exp_f32_e32 v132, v132
	v_exp_f32_e32 v133, v133
	v_add_f32_e32 v147, v147, v148
	v_add_f32_e32 v146, v146, v147
	v_pk_add_f32 v[132:133], v[132:133], 1.0 op_sel_hi:[1,0]
	s_nop 0
	v_rcp_f32_e32 v132, v132
	v_rcp_f32_e32 v133, v133
	s_nop 0
	v_pk_mul_f32 v[130:131], v[130:131], v[132:133]
	v_pk_mul_f32 v[132:133], v[72:73], v[168:169] op_sel_hi:[1,0]
	v_mov_b32_e32 v141, v131
	v_pk_mul_f32 v[138:139], v[132:133], v[132:133]
	s_nop 0
	v_pk_fma_f32 v[138:139], v[138:139], s[92:93], 1.0 op_sel_hi:[1,0,0]
	s_nop 0
	v_pk_mul_f32 v[138:139], v[132:133], v[138:139]
	s_nop 0
	v_pk_mul_f32 v[138:139], v[138:139], s[48:49] op_sel_hi:[1,0]
	s_nop 0
	v_pk_mul_f32 v[138:139], v[138:139], s[94:95] op_sel_hi:[1,0]
	s_nop 0
	v_exp_f32_e32 v138, v138
	v_exp_f32_e32 v139, v139
	s_nop 0
	v_pk_add_f32 v[138:139], v[138:139], 1.0 op_sel_hi:[1,0]
	s_nop 0
	v_rcp_f32_e32 v138, v138
	v_rcp_f32_e32 v139, v139
	s_nop 0
	v_pk_mul_f32 v[132:133], v[132:133], v[138:139]
	s_nop 0
	v_mov_b32_e32 v138, v132
	v_mov_b32_e32 v139, v130
	v_mov_b32_e32 v140, v133
	v_pk_add_f32 v[142:143], v[138:139], v[140:141]
	v_pk_mul_f32 v[140:141], v[140:141], v[140:141]
	v_add_f32_e32 v143, v143, v146
	v_pk_fma_f32 v[138:139], v[138:139], v[138:139], v[140:141]
	v_pk_mul_f32 v[146:147], v[68:69], v[168:169] op_sel_hi:[1,0]
	v_pk_add_f32 v[136:137], v[138:139], v[136:137] op_sel:[1,0] op_sel_hi:[0,1]
	v_pk_add_f32 v[136:137], v[138:139], v[136:137]
	v_pk_mul_f32 v[138:139], v[66:67], v[168:169] op_sel_hi:[1,0]
	v_pk_mul_f32 v[148:149], v[146:147], v[146:147]
	v_pk_mul_f32 v[140:141], v[138:139], v[138:139]
	v_pk_fma_f32 v[148:149], v[148:149], s[92:93], 1.0 op_sel_hi:[1,0,0]
	v_pk_fma_f32 v[140:141], v[140:141], s[92:93], 1.0 op_sel_hi:[1,0,0]
	v_pk_mul_f32 v[148:149], v[146:147], v[148:149]
	v_pk_mul_f32 v[140:141], v[138:139], v[140:141]
	v_pk_mul_f32 v[148:149], v[148:149], s[48:49] op_sel_hi:[1,0]
	v_pk_mul_f32 v[140:141], v[140:141], s[48:49] op_sel_hi:[1,0]
	v_pk_mul_f32 v[148:149], v[148:149], s[94:95] op_sel_hi:[1,0]
	v_pk_mul_f32 v[140:141], v[140:141], s[94:95] op_sel_hi:[1,0]
	v_exp_f32_e32 v148, v148
	v_exp_f32_e32 v140, v140
	v_exp_f32_e32 v141, v141
	v_exp_f32_e32 v149, v149
	v_cvt_pk_bf16_f32 v130, v130, v131
	v_cvt_pk_bf16_f32 v131, v132, v133
	v_pk_add_f32 v[140:141], v[140:141], 1.0 op_sel_hi:[1,0]
	v_pk_add_f32 v[148:149], v[148:149], 1.0 op_sel_hi:[1,0]
	v_rcp_f32_e32 v140, v140
	v_rcp_f32_e32 v141, v141
	v_rcp_f32_e32 v148, v148
	v_rcp_f32_e32 v149, v149
	v_add_f32_e32 v142, v142, v143
	v_pk_mul_f32 v[144:145], v[138:139], v[140:141]
	v_pk_mul_f32 v[146:147], v[146:147], v[148:149]
	v_pk_fma_f32 v[138:139], v[138:139], v[140:141], v[144:145] op_sel:[0,0,1] op_sel_hi:[1,1,0]
	v_mul_f32_e32 v140, v144, v144
	v_pk_fma_f32 v[140:141], v[144:145], v[144:145], v[140:141] op_sel_hi:[1,1,0]
	v_pk_mul_f32 v[148:149], v[146:147], v[146:147]
	v_cvt_pk_bf16_f32 v132, v144, v145
	v_cvt_pk_bf16_f32 v133, v146, v147
	global_store_dwordx4 v[252:253], v[130:133], off offset:-3840
	v_mov_b32_e32 v140, v146
	v_mov_b32_e32 v139, v148
	v_pk_mov_b32 v[130:131], v[146:147], v[136:137] op_sel:[1,0]
	v_mov_b32_e32 v143, v149
	v_pk_add_f32 v[130:131], v[140:141], v[130:131]
	v_pk_add_f32 v[132:133], v[138:139], v[142:143]
	s_nop 0
	v_pk_add_f32 v[130:131], v[132:133], v[130:131]
	ds_bpermute_b32 v132, v221, v130
	ds_bpermute_b32 v133, v221, v131
	s_waitcnt lgkmcnt(0)
	v_pk_add_f32 v[130:131], v[130:131], v[132:133]
	ds_bpermute_b32 v132, v222, v130
	ds_bpermute_b32 v133, v222, v131
	s_and_saveexec_b64 s[22:23], vcc
	s_cbranch_execz .LBB0_717
	v_lshl_add_u64 v[134:135], s[78:79], 0, v[192:193]
	v_lshl_add_u64 v[134:135], s[0:1], 2, v[134:135]
	s_waitcnt lgkmcnt(0)
	v_pk_add_f32 v[130:131], v[130:131], v[132:133]
	global_store_dwordx2 v[134:135], v[130:131], off
.LBB0_717:
	s_or_b64 exec, exec, s[22:23]
	v_pk_mul_f32 v[130:131], v[62:63], v[164:165] op_sel_hi:[1,0]
	v_lshlrev_b64 v[134:135], 10, v[162:163]
	s_waitcnt lgkmcnt(0)
	v_pk_mul_f32 v[132:133], v[130:131], v[130:131]
	v_lshl_add_u64 v[134:135], s[44:45], 0, v[134:135]
	v_pk_fma_f32 v[132:133], v[132:133], s[92:93], 1.0 op_sel_hi:[1,0,0]
	v_lshl_add_u64 v[134:135], v[182:183], 1, v[134:135]
	v_pk_mul_f32 v[132:133], v[130:131], v[132:133]
	s_nop 0
	v_pk_mul_f32 v[132:133], v[132:133], s[48:49] op_sel_hi:[1,0]
	s_nop 0
	v_pk_mul_f32 v[132:133], v[132:133], s[94:95] op_sel_hi:[1,0]
	s_nop 0
	v_exp_f32_e32 v132, v132
	v_exp_f32_e32 v133, v133
	s_nop 0
	v_pk_add_f32 v[132:133], v[132:133], 1.0 op_sel_hi:[1,0]
	s_nop 0
	v_rcp_f32_e32 v132, v132
	v_rcp_f32_e32 v133, v133
	s_nop 0
	v_pk_mul_f32 v[130:131], v[130:131], v[132:133]
	v_pk_mul_f32 v[132:133], v[64:65], v[164:165] op_sel_hi:[1,0]
	v_mov_b32_e32 v139, v131
	v_pk_mul_f32 v[136:137], v[132:133], v[132:133]
	s_nop 0
	v_pk_fma_f32 v[136:137], v[136:137], s[92:93], 1.0 op_sel_hi:[1,0,0]
	s_nop 0
	v_pk_mul_f32 v[136:137], v[132:133], v[136:137]
	s_nop 0
	v_pk_mul_f32 v[136:137], v[136:137], s[48:49] op_sel_hi:[1,0]
	s_nop 0
	v_pk_mul_f32 v[136:137], v[136:137], s[94:95] op_sel_hi:[1,0]
	s_nop 0
	v_exp_f32_e32 v136, v136
	v_exp_f32_e32 v137, v137
	s_nop 0
	v_pk_add_f32 v[136:137], v[136:137], 1.0 op_sel_hi:[1,0]
	s_nop 0
	v_rcp_f32_e32 v136, v136
	v_rcp_f32_e32 v137, v137
	s_nop 0
	v_pk_mul_f32 v[132:133], v[132:133], v[136:137]
	s_nop 0
	v_mov_b32_e32 v136, v132
	v_mov_b32_e32 v137, v130
	v_mov_b32_e32 v138, v133
	v_pk_add_f32 v[136:137], v[136:137], v[138:139]
	v_mov_b32_e32 v138, v131
	v_add_f32_e32 v137, 0, v137
	v_mov_b32_e32 v139, v133
	v_add_f32_e32 v148, v136, v137
	v_mov_b32_e32 v136, v130
	v_mov_b32_e32 v137, v132
	v_pk_mul_f32 v[138:139], v[138:139], v[138:139]
	v_cvt_pk_bf16_f32 v130, v130, v131
	v_pk_fma_f32 v[136:137], v[136:137], v[136:137], v[138:139]
	v_pk_mul_f32 v[138:139], v[58:59], v[164:165] op_sel_hi:[1,0]
	v_cvt_pk_bf16_f32 v131, v132, v133
	v_pk_mul_f32 v[140:141], v[138:139], v[138:139]
	v_pk_add_f32 v[136:137], v[136:137], v[136:137] op_sel:[0,1] op_sel_hi:[1,0]
	v_pk_fma_f32 v[140:141], v[140:141], s[92:93], 1.0 op_sel_hi:[1,0,0]
	s_nop 0
	v_pk_mul_f32 v[140:141], v[138:139], v[140:141]
	s_nop 0
	v_pk_mul_f32 v[140:141], v[140:141], s[48:49] op_sel_hi:[1,0]
	s_nop 0
	v_pk_mul_f32 v[140:141], v[140:141], s[94:95] op_sel_hi:[1,0]
	s_nop 0
	v_exp_f32_e32 v140, v140
	v_exp_f32_e32 v141, v141
	s_nop 0
	v_pk_add_f32 v[140:141], v[140:141], 1.0 op_sel_hi:[1,0]
	s_nop 0
	v_rcp_f32_e32 v140, v140
	v_rcp_f32_e32 v141, v141
	s_nop 0
	v_pk_mul_f32 v[138:139], v[138:139], v[140:141]
	v_pk_mul_f32 v[140:141], v[60:61], v[164:165] op_sel_hi:[1,0]
	v_cvt_pk_bf16_f32 v132, v138, v139
	v_pk_mul_f32 v[142:143], v[140:141], v[140:141]
	v_mov_b32_e32 v145, v139
	v_pk_fma_f32 v[142:143], v[142:143], s[92:93], 1.0 op_sel_hi:[1,0,0]
	s_nop 0
	v_pk_mul_f32 v[142:143], v[140:141], v[142:143]
	s_nop 0
	v_pk_mul_f32 v[142:143], v[142:143], s[48:49] op_sel_hi:[1,0]
	s_nop 0
	v_pk_mul_f32 v[142:143], v[142:143], s[94:95] op_sel_hi:[1,0]
	s_nop 0
	v_exp_f32_e32 v142, v142
	v_exp_f32_e32 v143, v143
	s_nop 0
	v_pk_add_f32 v[142:143], v[142:143], 1.0 op_sel_hi:[1,0]
	s_nop 0
	v_rcp_f32_e32 v142, v142
	v_rcp_f32_e32 v143, v143
	s_nop 0
	v_pk_mul_f32 v[140:141], v[140:141], v[142:143]
	s_nop 0
	v_cvt_pk_bf16_f32 v133, v140, v141
	s_mov_b32 s98, 0x21000
	s_mov_b32 s99, 0x0
	v_lshl_add_u64 v[252:253], v[250:251], 0, s[98:99]
	global_store_dwordx4 v[252:253], v[130:133], off offset:-4096
	v_mov_b32_e32 v143, v138
	v_mov_b32_e32 v142, v140
	v_pk_mul_f32 v[130:131], v[30:31], v[164:165] op_sel_hi:[1,0]
	v_mov_b32_e32 v144, v141
	v_pk_mul_f32 v[132:133], v[130:131], v[130:131]
	v_pk_add_f32 v[146:147], v[142:143], v[144:145]
	v_pk_fma_f32 v[132:133], v[132:133], s[92:93], 1.0 op_sel_hi:[1,0,0]
	v_pk_mul_f32 v[144:145], v[144:145], v[144:145]
	v_pk_mul_f32 v[132:133], v[130:131], v[132:133]
	v_pk_fma_f32 v[142:143], v[142:143], v[142:143], v[144:145]
	v_pk_mul_f32 v[132:133], v[132:133], s[48:49] op_sel_hi:[1,0]
	v_pk_add_f32 v[136:137], v[142:143], v[136:137] op_sel:[1,0] op_sel_hi:[0,1]
	v_pk_mul_f32 v[132:133], v[132:133], s[94:95] op_sel_hi:[1,0]
	v_pk_add_f32 v[136:137], v[142:143], v[136:137]
	v_exp_f32_e32 v132, v132
	v_exp_f32_e32 v133, v133
	v_add_f32_e32 v147, v147, v148
	v_add_f32_e32 v146, v146, v147
	v_pk_add_f32 v[132:133], v[132:133], 1.0 op_sel_hi:[1,0]
	s_nop 0
	v_rcp_f32_e32 v132, v132
	v_rcp_f32_e32 v133, v133
	s_nop 0
	v_pk_mul_f32 v[130:131], v[130:131], v[132:133]
	v_pk_mul_f32 v[132:133], v[32:33], v[164:165] op_sel_hi:[1,0]
	v_mov_b32_e32 v141, v131
	v_pk_mul_f32 v[138:139], v[132:133], v[132:133]
	s_nop 0
	v_pk_fma_f32 v[138:139], v[138:139], s[92:93], 1.0 op_sel_hi:[1,0,0]
	s_nop 0
	v_pk_mul_f32 v[138:139], v[132:133], v[138:139]
	s_nop 0
	v_pk_mul_f32 v[138:139], v[138:139], s[48:49] op_sel_hi:[1,0]
	s_nop 0
	v_pk_mul_f32 v[138:139], v[138:139], s[94:95] op_sel_hi:[1,0]
	s_nop 0
	v_exp_f32_e32 v138, v138
	v_exp_f32_e32 v139, v139
	s_nop 0
	v_pk_add_f32 v[138:139], v[138:139], 1.0 op_sel_hi:[1,0]
	s_nop 0
	v_rcp_f32_e32 v138, v138
	v_rcp_f32_e32 v139, v139
	s_nop 0
	v_pk_mul_f32 v[132:133], v[132:133], v[138:139]
	s_nop 0
	v_mov_b32_e32 v138, v132
	v_mov_b32_e32 v139, v130
	v_mov_b32_e32 v140, v133
	v_pk_add_f32 v[142:143], v[138:139], v[140:141]
	v_pk_mul_f32 v[140:141], v[140:141], v[140:141]
	v_add_f32_e32 v143, v143, v146
	v_pk_fma_f32 v[138:139], v[138:139], v[138:139], v[140:141]
	v_pk_mul_f32 v[146:147], v[28:29], v[164:165] op_sel_hi:[1,0]
	v_pk_add_f32 v[136:137], v[138:139], v[136:137] op_sel:[1,0] op_sel_hi:[0,1]
	v_pk_add_f32 v[136:137], v[138:139], v[136:137]
	v_pk_mul_f32 v[138:139], v[26:27], v[164:165] op_sel_hi:[1,0]
	v_pk_mul_f32 v[148:149], v[146:147], v[146:147]
	v_pk_mul_f32 v[140:141], v[138:139], v[138:139]
	v_pk_fma_f32 v[148:149], v[148:149], s[92:93], 1.0 op_sel_hi:[1,0,0]
	v_pk_fma_f32 v[140:141], v[140:141], s[92:93], 1.0 op_sel_hi:[1,0,0]
	v_pk_mul_f32 v[148:149], v[146:147], v[148:149]
	v_pk_mul_f32 v[140:141], v[138:139], v[140:141]
	v_pk_mul_f32 v[148:149], v[148:149], s[48:49] op_sel_hi:[1,0]
	v_pk_mul_f32 v[140:141], v[140:141], s[48:49] op_sel_hi:[1,0]
	v_pk_mul_f32 v[148:149], v[148:149], s[94:95] op_sel_hi:[1,0]
	v_pk_mul_f32 v[140:141], v[140:141], s[94:95] op_sel_hi:[1,0]
	v_exp_f32_e32 v148, v148
	v_exp_f32_e32 v140, v140
	v_exp_f32_e32 v141, v141
	v_exp_f32_e32 v149, v149
	v_cvt_pk_bf16_f32 v130, v130, v131
	v_cvt_pk_bf16_f32 v131, v132, v133
	v_pk_add_f32 v[140:141], v[140:141], 1.0 op_sel_hi:[1,0]
	v_pk_add_f32 v[148:149], v[148:149], 1.0 op_sel_hi:[1,0]
	v_rcp_f32_e32 v140, v140
	v_rcp_f32_e32 v141, v141
	v_rcp_f32_e32 v148, v148
	v_rcp_f32_e32 v149, v149
	v_add_f32_e32 v142, v142, v143
	v_pk_mul_f32 v[144:145], v[138:139], v[140:141]
	v_pk_mul_f32 v[146:147], v[146:147], v[148:149]
	v_pk_fma_f32 v[138:139], v[138:139], v[140:141], v[144:145] op_sel:[0,0,1] op_sel_hi:[1,1,0]
	v_mul_f32_e32 v140, v144, v144
	v_pk_fma_f32 v[140:141], v[144:145], v[144:145], v[140:141] op_sel_hi:[1,1,0]
	v_pk_mul_f32 v[148:149], v[146:147], v[146:147]
	v_cvt_pk_bf16_f32 v132, v144, v145
	v_cvt_pk_bf16_f32 v133, v146, v147
	global_store_dwordx4 v[252:253], v[130:133], off offset:-3840
	v_mov_b32_e32 v140, v146
	v_mov_b32_e32 v139, v148
	v_pk_mov_b32 v[130:131], v[146:147], v[136:137] op_sel:[1,0]
	v_mov_b32_e32 v143, v149
	v_pk_add_f32 v[130:131], v[140:141], v[130:131]
	v_pk_add_f32 v[132:133], v[138:139], v[142:143]
	s_nop 0
	v_pk_add_f32 v[130:131], v[132:133], v[130:131]
	ds_bpermute_b32 v132, v221, v130
	ds_bpermute_b32 v133, v221, v131
	s_waitcnt lgkmcnt(0)
	v_pk_add_f32 v[130:131], v[130:131], v[132:133]
	ds_bpermute_b32 v132, v222, v130
	ds_bpermute_b32 v133, v222, v131
	s_and_saveexec_b64 s[22:23], vcc
	s_cbranch_execz .LBB0_719
	v_lshl_add_u64 v[134:135], s[78:79], 0, v[190:191]
	v_lshl_add_u64 v[134:135], s[0:1], 2, v[134:135]
	s_waitcnt lgkmcnt(0)
	v_pk_add_f32 v[130:131], v[130:131], v[132:133]
	global_store_dwordx2 v[134:135], v[130:131], off
.LBB0_719:
	s_or_b64 exec, exec, s[22:23]
	v_pk_mul_f32 v[130:131], v[54:55], v[160:161] op_sel_hi:[1,0]
	v_lshlrev_b64 v[134:135], 10, v[158:159]
	s_waitcnt lgkmcnt(0)
	v_pk_mul_f32 v[132:133], v[130:131], v[130:131]
	v_lshl_add_u64 v[134:135], s[44:45], 0, v[134:135]
	v_pk_fma_f32 v[132:133], v[132:133], s[92:93], 1.0 op_sel_hi:[1,0,0]
	v_lshl_add_u64 v[134:135], v[182:183], 1, v[134:135]
	v_pk_mul_f32 v[132:133], v[130:131], v[132:133]
	s_nop 0
	v_pk_mul_f32 v[132:133], v[132:133], s[48:49] op_sel_hi:[1,0]
	s_nop 0
	v_pk_mul_f32 v[132:133], v[132:133], s[94:95] op_sel_hi:[1,0]
	s_nop 0
	v_exp_f32_e32 v132, v132
	v_exp_f32_e32 v133, v133
	s_nop 0
	v_pk_add_f32 v[132:133], v[132:133], 1.0 op_sel_hi:[1,0]
	s_nop 0
	v_rcp_f32_e32 v132, v132
	v_rcp_f32_e32 v133, v133
	s_nop 0
	v_pk_mul_f32 v[130:131], v[130:131], v[132:133]
	v_pk_mul_f32 v[132:133], v[56:57], v[160:161] op_sel_hi:[1,0]
	v_mov_b32_e32 v139, v131
	v_pk_mul_f32 v[136:137], v[132:133], v[132:133]
	s_nop 0
	v_pk_fma_f32 v[136:137], v[136:137], s[92:93], 1.0 op_sel_hi:[1,0,0]
	s_nop 0
	v_pk_mul_f32 v[136:137], v[132:133], v[136:137]
	s_nop 0
	v_pk_mul_f32 v[136:137], v[136:137], s[48:49] op_sel_hi:[1,0]
	s_nop 0
	v_pk_mul_f32 v[136:137], v[136:137], s[94:95] op_sel_hi:[1,0]
	s_nop 0
	v_exp_f32_e32 v136, v136
	v_exp_f32_e32 v137, v137
	s_nop 0
	v_pk_add_f32 v[136:137], v[136:137], 1.0 op_sel_hi:[1,0]
	s_nop 0
	v_rcp_f32_e32 v136, v136
	v_rcp_f32_e32 v137, v137
	s_nop 0
	v_pk_mul_f32 v[132:133], v[132:133], v[136:137]
	s_nop 0
	v_mov_b32_e32 v136, v132
	v_mov_b32_e32 v137, v130
	v_mov_b32_e32 v138, v133
	v_pk_add_f32 v[136:137], v[136:137], v[138:139]
	v_mov_b32_e32 v138, v131
	v_add_f32_e32 v137, 0, v137
	v_mov_b32_e32 v139, v133
	v_add_f32_e32 v148, v136, v137
	v_mov_b32_e32 v136, v130
	v_mov_b32_e32 v137, v132
	v_pk_mul_f32 v[138:139], v[138:139], v[138:139]
	v_cvt_pk_bf16_f32 v130, v130, v131
	v_pk_fma_f32 v[136:137], v[136:137], v[136:137], v[138:139]
	v_pk_mul_f32 v[138:139], v[50:51], v[160:161] op_sel_hi:[1,0]
	v_cvt_pk_bf16_f32 v131, v132, v133
	v_pk_mul_f32 v[140:141], v[138:139], v[138:139]
	v_pk_add_f32 v[136:137], v[136:137], v[136:137] op_sel:[0,1] op_sel_hi:[1,0]
	v_pk_fma_f32 v[140:141], v[140:141], s[92:93], 1.0 op_sel_hi:[1,0,0]
	s_nop 0
	v_pk_mul_f32 v[140:141], v[138:139], v[140:141]
	s_nop 0
	v_pk_mul_f32 v[140:141], v[140:141], s[48:49] op_sel_hi:[1,0]
	s_nop 0
	v_pk_mul_f32 v[140:141], v[140:141], s[94:95] op_sel_hi:[1,0]
	s_nop 0
	v_exp_f32_e32 v140, v140
	v_exp_f32_e32 v141, v141
	s_nop 0
	v_pk_add_f32 v[140:141], v[140:141], 1.0 op_sel_hi:[1,0]
	s_nop 0
	v_rcp_f32_e32 v140, v140
	v_rcp_f32_e32 v141, v141
	s_nop 0
	v_pk_mul_f32 v[138:139], v[138:139], v[140:141]
	v_pk_mul_f32 v[140:141], v[52:53], v[160:161] op_sel_hi:[1,0]
	v_cvt_pk_bf16_f32 v132, v138, v139
	v_pk_mul_f32 v[142:143], v[140:141], v[140:141]
	v_mov_b32_e32 v145, v139
	v_pk_fma_f32 v[142:143], v[142:143], s[92:93], 1.0 op_sel_hi:[1,0,0]
	s_nop 0
	v_pk_mul_f32 v[142:143], v[140:141], v[142:143]
	s_nop 0
	v_pk_mul_f32 v[142:143], v[142:143], s[48:49] op_sel_hi:[1,0]
	s_nop 0
	v_pk_mul_f32 v[142:143], v[142:143], s[94:95] op_sel_hi:[1,0]
	s_nop 0
	v_exp_f32_e32 v142, v142
	v_exp_f32_e32 v143, v143
	s_nop 0
	v_pk_add_f32 v[142:143], v[142:143], 1.0 op_sel_hi:[1,0]
	s_nop 0
	v_rcp_f32_e32 v142, v142
	v_rcp_f32_e32 v143, v143
	s_nop 0
	v_pk_mul_f32 v[140:141], v[140:141], v[142:143]
	s_nop 0
	v_cvt_pk_bf16_f32 v133, v140, v141
	s_mov_b32 s98, 0x25000
	s_mov_b32 s99, 0x0
	v_lshl_add_u64 v[252:253], v[250:251], 0, s[98:99]
	global_store_dwordx4 v[252:253], v[130:133], off offset:-4096
	v_mov_b32_e32 v143, v138
	v_mov_b32_e32 v142, v140
	v_pk_mul_f32 v[130:131], v[22:23], v[160:161] op_sel_hi:[1,0]
	v_mov_b32_e32 v144, v141
	v_pk_mul_f32 v[132:133], v[130:131], v[130:131]
	v_pk_add_f32 v[146:147], v[142:143], v[144:145]
	v_pk_fma_f32 v[132:133], v[132:133], s[92:93], 1.0 op_sel_hi:[1,0,0]
	v_pk_mul_f32 v[144:145], v[144:145], v[144:145]
	v_pk_mul_f32 v[132:133], v[130:131], v[132:133]
	v_pk_fma_f32 v[142:143], v[142:143], v[142:143], v[144:145]
	v_pk_mul_f32 v[132:133], v[132:133], s[48:49] op_sel_hi:[1,0]
	v_pk_add_f32 v[136:137], v[142:143], v[136:137] op_sel:[1,0] op_sel_hi:[0,1]
	v_pk_mul_f32 v[132:133], v[132:133], s[94:95] op_sel_hi:[1,0]
	v_pk_add_f32 v[136:137], v[142:143], v[136:137]
	v_exp_f32_e32 v132, v132
	v_exp_f32_e32 v133, v133
	v_add_f32_e32 v147, v147, v148
	v_add_f32_e32 v146, v146, v147
	v_pk_add_f32 v[132:133], v[132:133], 1.0 op_sel_hi:[1,0]
	s_nop 0
	v_rcp_f32_e32 v132, v132
	v_rcp_f32_e32 v133, v133
	s_nop 0
	v_pk_mul_f32 v[130:131], v[130:131], v[132:133]
	v_pk_mul_f32 v[132:133], v[24:25], v[160:161] op_sel_hi:[1,0]
	v_mov_b32_e32 v141, v131
	v_pk_mul_f32 v[138:139], v[132:133], v[132:133]
	s_nop 0
	v_pk_fma_f32 v[138:139], v[138:139], s[92:93], 1.0 op_sel_hi:[1,0,0]
	s_nop 0
	v_pk_mul_f32 v[138:139], v[132:133], v[138:139]
	s_nop 0
	v_pk_mul_f32 v[138:139], v[138:139], s[48:49] op_sel_hi:[1,0]
	s_nop 0
	v_pk_mul_f32 v[138:139], v[138:139], s[94:95] op_sel_hi:[1,0]
	s_nop 0
	v_exp_f32_e32 v138, v138
	v_exp_f32_e32 v139, v139
	s_nop 0
	v_pk_add_f32 v[138:139], v[138:139], 1.0 op_sel_hi:[1,0]
	s_nop 0
	v_rcp_f32_e32 v138, v138
	v_rcp_f32_e32 v139, v139
	s_nop 0
	v_pk_mul_f32 v[132:133], v[132:133], v[138:139]
	s_nop 0
	v_mov_b32_e32 v138, v132
	v_mov_b32_e32 v139, v130
	v_mov_b32_e32 v140, v133
	v_pk_add_f32 v[142:143], v[138:139], v[140:141]
	v_pk_mul_f32 v[140:141], v[140:141], v[140:141]
	v_add_f32_e32 v143, v143, v146
	v_pk_fma_f32 v[138:139], v[138:139], v[138:139], v[140:141]
	v_pk_mul_f32 v[146:147], v[20:21], v[160:161] op_sel_hi:[1,0]
	v_pk_add_f32 v[136:137], v[138:139], v[136:137] op_sel:[1,0] op_sel_hi:[0,1]
	v_pk_add_f32 v[136:137], v[138:139], v[136:137]
	v_pk_mul_f32 v[138:139], v[18:19], v[160:161] op_sel_hi:[1,0]
	v_pk_mul_f32 v[148:149], v[146:147], v[146:147]
	v_pk_mul_f32 v[140:141], v[138:139], v[138:139]
	v_pk_fma_f32 v[148:149], v[148:149], s[92:93], 1.0 op_sel_hi:[1,0,0]
	v_pk_fma_f32 v[140:141], v[140:141], s[92:93], 1.0 op_sel_hi:[1,0,0]
	v_pk_mul_f32 v[148:149], v[146:147], v[148:149]
	v_pk_mul_f32 v[140:141], v[138:139], v[140:141]
	v_pk_mul_f32 v[148:149], v[148:149], s[48:49] op_sel_hi:[1,0]
	v_pk_mul_f32 v[140:141], v[140:141], s[48:49] op_sel_hi:[1,0]
	v_pk_mul_f32 v[148:149], v[148:149], s[94:95] op_sel_hi:[1,0]
	v_pk_mul_f32 v[140:141], v[140:141], s[94:95] op_sel_hi:[1,0]
	v_exp_f32_e32 v148, v148
	v_exp_f32_e32 v140, v140
	v_exp_f32_e32 v141, v141
	v_exp_f32_e32 v149, v149
	v_cvt_pk_bf16_f32 v130, v130, v131
	v_cvt_pk_bf16_f32 v131, v132, v133
	v_pk_add_f32 v[140:141], v[140:141], 1.0 op_sel_hi:[1,0]
	v_pk_add_f32 v[148:149], v[148:149], 1.0 op_sel_hi:[1,0]
	v_rcp_f32_e32 v140, v140
	v_rcp_f32_e32 v141, v141
	v_rcp_f32_e32 v148, v148
	v_rcp_f32_e32 v149, v149
	v_add_f32_e32 v142, v142, v143
	v_pk_mul_f32 v[144:145], v[138:139], v[140:141]
	v_pk_mul_f32 v[146:147], v[146:147], v[148:149]
	v_pk_fma_f32 v[138:139], v[138:139], v[140:141], v[144:145] op_sel:[0,0,1] op_sel_hi:[1,1,0]
	v_mul_f32_e32 v140, v144, v144
	v_pk_fma_f32 v[140:141], v[144:145], v[144:145], v[140:141] op_sel_hi:[1,1,0]
	v_pk_mul_f32 v[148:149], v[146:147], v[146:147]
	v_cvt_pk_bf16_f32 v132, v144, v145
	v_cvt_pk_bf16_f32 v133, v146, v147
	global_store_dwordx4 v[252:253], v[130:133], off offset:-3840
	v_mov_b32_e32 v140, v146
	v_mov_b32_e32 v139, v148
	v_pk_mov_b32 v[130:131], v[146:147], v[136:137] op_sel:[1,0]
	v_mov_b32_e32 v143, v149
	v_pk_add_f32 v[130:131], v[140:141], v[130:131]
	v_pk_add_f32 v[132:133], v[138:139], v[142:143]
	s_nop 0
	v_pk_add_f32 v[130:131], v[132:133], v[130:131]
	ds_bpermute_b32 v132, v221, v130
	ds_bpermute_b32 v133, v221, v131
	s_waitcnt lgkmcnt(0)
	v_pk_add_f32 v[130:131], v[130:131], v[132:133]
	ds_bpermute_b32 v132, v222, v130
	ds_bpermute_b32 v133, v222, v131
	s_and_saveexec_b64 s[22:23], vcc
	s_cbranch_execz .LBB0_721
	v_lshl_add_u64 v[134:135], s[78:79], 0, v[188:189]
	v_lshl_add_u64 v[134:135], s[0:1], 2, v[134:135]
	s_waitcnt lgkmcnt(0)
	v_pk_add_f32 v[130:131], v[130:131], v[132:133]
	global_store_dwordx2 v[134:135], v[130:131], off
.LBB0_721:
	s_or_b64 exec, exec, s[22:23]
	v_pk_mul_f32 v[130:131], v[46:47], v[156:157] op_sel_hi:[1,0]
	v_lshlrev_b64 v[134:135], 10, v[154:155]
	s_waitcnt lgkmcnt(0)
	v_pk_mul_f32 v[132:133], v[130:131], v[130:131]
	v_lshl_add_u64 v[134:135], s[44:45], 0, v[134:135]
	v_pk_fma_f32 v[132:133], v[132:133], s[92:93], 1.0 op_sel_hi:[1,0,0]
	v_lshl_add_u64 v[134:135], v[182:183], 1, v[134:135]
	v_pk_mul_f32 v[132:133], v[130:131], v[132:133]
	s_nop 0
	v_pk_mul_f32 v[132:133], v[132:133], s[48:49] op_sel_hi:[1,0]
	s_nop 0
	v_pk_mul_f32 v[132:133], v[132:133], s[94:95] op_sel_hi:[1,0]
	s_nop 0
	v_exp_f32_e32 v132, v132
	v_exp_f32_e32 v133, v133
	s_nop 0
	v_pk_add_f32 v[132:133], v[132:133], 1.0 op_sel_hi:[1,0]
	s_nop 0
	v_rcp_f32_e32 v132, v132
	v_rcp_f32_e32 v133, v133
	s_nop 0
	v_pk_mul_f32 v[130:131], v[130:131], v[132:133]
	v_pk_mul_f32 v[132:133], v[48:49], v[156:157] op_sel_hi:[1,0]
	v_mov_b32_e32 v139, v131
	v_pk_mul_f32 v[136:137], v[132:133], v[132:133]
	s_nop 0
	v_pk_fma_f32 v[136:137], v[136:137], s[92:93], 1.0 op_sel_hi:[1,0,0]
	s_nop 0
	v_pk_mul_f32 v[136:137], v[132:133], v[136:137]
	s_nop 0
	v_pk_mul_f32 v[136:137], v[136:137], s[48:49] op_sel_hi:[1,0]
	s_nop 0
	v_pk_mul_f32 v[136:137], v[136:137], s[94:95] op_sel_hi:[1,0]
	s_nop 0
	v_exp_f32_e32 v136, v136
	v_exp_f32_e32 v137, v137
	s_nop 0
	v_pk_add_f32 v[136:137], v[136:137], 1.0 op_sel_hi:[1,0]
	s_nop 0
	v_rcp_f32_e32 v136, v136
	v_rcp_f32_e32 v137, v137
	s_nop 0
	v_pk_mul_f32 v[132:133], v[132:133], v[136:137]
	s_nop 0
	v_mov_b32_e32 v136, v132
	v_mov_b32_e32 v137, v130
	v_mov_b32_e32 v138, v133
	v_pk_add_f32 v[136:137], v[136:137], v[138:139]
	v_mov_b32_e32 v138, v131
	v_add_f32_e32 v137, 0, v137
	v_mov_b32_e32 v139, v133
	v_add_f32_e32 v148, v136, v137
	v_mov_b32_e32 v136, v130
	v_mov_b32_e32 v137, v132
	v_pk_mul_f32 v[138:139], v[138:139], v[138:139]
	v_cvt_pk_bf16_f32 v130, v130, v131
	v_pk_fma_f32 v[136:137], v[136:137], v[136:137], v[138:139]
	v_pk_mul_f32 v[138:139], v[42:43], v[156:157] op_sel_hi:[1,0]
	v_cvt_pk_bf16_f32 v131, v132, v133
	v_pk_mul_f32 v[140:141], v[138:139], v[138:139]
	v_pk_add_f32 v[136:137], v[136:137], v[136:137] op_sel:[0,1] op_sel_hi:[1,0]
	v_pk_fma_f32 v[140:141], v[140:141], s[92:93], 1.0 op_sel_hi:[1,0,0]
	s_nop 0
	v_pk_mul_f32 v[140:141], v[138:139], v[140:141]
	s_nop 0
	v_pk_mul_f32 v[140:141], v[140:141], s[48:49] op_sel_hi:[1,0]
	s_nop 0
	v_pk_mul_f32 v[140:141], v[140:141], s[94:95] op_sel_hi:[1,0]
	s_nop 0
	v_exp_f32_e32 v140, v140
	v_exp_f32_e32 v141, v141
	s_nop 0
	v_pk_add_f32 v[140:141], v[140:141], 1.0 op_sel_hi:[1,0]
	s_nop 0
	v_rcp_f32_e32 v140, v140
	v_rcp_f32_e32 v141, v141
	s_nop 0
	v_pk_mul_f32 v[138:139], v[138:139], v[140:141]
	v_pk_mul_f32 v[140:141], v[44:45], v[156:157] op_sel_hi:[1,0]
	v_cvt_pk_bf16_f32 v132, v138, v139
	v_pk_mul_f32 v[142:143], v[140:141], v[140:141]
	v_mov_b32_e32 v145, v139
	v_pk_fma_f32 v[142:143], v[142:143], s[92:93], 1.0 op_sel_hi:[1,0,0]
	s_nop 0
	v_pk_mul_f32 v[142:143], v[140:141], v[142:143]
	s_nop 0
	v_pk_mul_f32 v[142:143], v[142:143], s[48:49] op_sel_hi:[1,0]
	s_nop 0
	v_pk_mul_f32 v[142:143], v[142:143], s[94:95] op_sel_hi:[1,0]
	s_nop 0
	v_exp_f32_e32 v142, v142
	v_exp_f32_e32 v143, v143
	s_nop 0
	v_pk_add_f32 v[142:143], v[142:143], 1.0 op_sel_hi:[1,0]
	s_nop 0
	v_rcp_f32_e32 v142, v142
	v_rcp_f32_e32 v143, v143
	s_nop 0
	v_pk_mul_f32 v[140:141], v[140:141], v[142:143]
	s_nop 0
	v_cvt_pk_bf16_f32 v133, v140, v141
	s_mov_b32 s98, 0x29000
	s_mov_b32 s99, 0x0
	v_lshl_add_u64 v[252:253], v[250:251], 0, s[98:99]
	global_store_dwordx4 v[252:253], v[130:133], off offset:-4096
	v_mov_b32_e32 v143, v138
	v_mov_b32_e32 v142, v140
	v_pk_mul_f32 v[130:131], v[14:15], v[156:157] op_sel_hi:[1,0]
	v_mov_b32_e32 v144, v141
	v_pk_mul_f32 v[132:133], v[130:131], v[130:131]
	v_pk_add_f32 v[146:147], v[142:143], v[144:145]
	v_pk_fma_f32 v[132:133], v[132:133], s[92:93], 1.0 op_sel_hi:[1,0,0]
	v_pk_mul_f32 v[144:145], v[144:145], v[144:145]
	v_pk_mul_f32 v[132:133], v[130:131], v[132:133]
	v_pk_fma_f32 v[142:143], v[142:143], v[142:143], v[144:145]
	v_pk_mul_f32 v[132:133], v[132:133], s[48:49] op_sel_hi:[1,0]
	v_pk_add_f32 v[136:137], v[142:143], v[136:137] op_sel:[1,0] op_sel_hi:[0,1]
	v_pk_mul_f32 v[132:133], v[132:133], s[94:95] op_sel_hi:[1,0]
	v_pk_add_f32 v[136:137], v[142:143], v[136:137]
	v_exp_f32_e32 v132, v132
	v_exp_f32_e32 v133, v133
	v_add_f32_e32 v147, v147, v148
	v_add_f32_e32 v146, v146, v147
	v_pk_add_f32 v[132:133], v[132:133], 1.0 op_sel_hi:[1,0]
	s_nop 0
	v_rcp_f32_e32 v132, v132
	v_rcp_f32_e32 v133, v133
	s_nop 0
	v_pk_mul_f32 v[130:131], v[130:131], v[132:133]
	v_pk_mul_f32 v[132:133], v[16:17], v[156:157] op_sel_hi:[1,0]
	v_mov_b32_e32 v141, v131
	v_pk_mul_f32 v[138:139], v[132:133], v[132:133]
	s_nop 0
	v_pk_fma_f32 v[138:139], v[138:139], s[92:93], 1.0 op_sel_hi:[1,0,0]
	s_nop 0
	v_pk_mul_f32 v[138:139], v[132:133], v[138:139]
	s_nop 0
	v_pk_mul_f32 v[138:139], v[138:139], s[48:49] op_sel_hi:[1,0]
	s_nop 0
	v_pk_mul_f32 v[138:139], v[138:139], s[94:95] op_sel_hi:[1,0]
	s_nop 0
	v_exp_f32_e32 v138, v138
	v_exp_f32_e32 v139, v139
	s_nop 0
	v_pk_add_f32 v[138:139], v[138:139], 1.0 op_sel_hi:[1,0]
	s_nop 0
	v_rcp_f32_e32 v138, v138
	v_rcp_f32_e32 v139, v139
	s_nop 0
	v_pk_mul_f32 v[132:133], v[132:133], v[138:139]
	s_nop 0
	v_mov_b32_e32 v138, v132
	v_mov_b32_e32 v139, v130
	v_mov_b32_e32 v140, v133
	v_pk_add_f32 v[142:143], v[138:139], v[140:141]
	v_pk_mul_f32 v[140:141], v[140:141], v[140:141]
	v_add_f32_e32 v143, v143, v146
	v_pk_fma_f32 v[138:139], v[138:139], v[138:139], v[140:141]
	v_pk_mul_f32 v[146:147], v[12:13], v[156:157] op_sel_hi:[1,0]
	v_pk_add_f32 v[136:137], v[138:139], v[136:137] op_sel:[1,0] op_sel_hi:[0,1]
	v_pk_add_f32 v[136:137], v[138:139], v[136:137]
	v_pk_mul_f32 v[138:139], v[10:11], v[156:157] op_sel_hi:[1,0]
	v_pk_mul_f32 v[148:149], v[146:147], v[146:147]
	v_pk_mul_f32 v[140:141], v[138:139], v[138:139]
	v_pk_fma_f32 v[148:149], v[148:149], s[92:93], 1.0 op_sel_hi:[1,0,0]
	v_pk_fma_f32 v[140:141], v[140:141], s[92:93], 1.0 op_sel_hi:[1,0,0]
	v_pk_mul_f32 v[148:149], v[146:147], v[148:149]
	v_pk_mul_f32 v[140:141], v[138:139], v[140:141]
	v_pk_mul_f32 v[148:149], v[148:149], s[48:49] op_sel_hi:[1,0]
	v_pk_mul_f32 v[140:141], v[140:141], s[48:49] op_sel_hi:[1,0]
	v_pk_mul_f32 v[148:149], v[148:149], s[94:95] op_sel_hi:[1,0]
	v_pk_mul_f32 v[140:141], v[140:141], s[94:95] op_sel_hi:[1,0]
	v_exp_f32_e32 v148, v148
	v_exp_f32_e32 v140, v140
	v_exp_f32_e32 v141, v141
	v_exp_f32_e32 v149, v149
	v_cvt_pk_bf16_f32 v130, v130, v131
	v_cvt_pk_bf16_f32 v131, v132, v133
	v_pk_add_f32 v[140:141], v[140:141], 1.0 op_sel_hi:[1,0]
	v_pk_add_f32 v[148:149], v[148:149], 1.0 op_sel_hi:[1,0]
	v_rcp_f32_e32 v140, v140
	v_rcp_f32_e32 v141, v141
	v_rcp_f32_e32 v148, v148
	v_rcp_f32_e32 v149, v149
	v_add_f32_e32 v142, v142, v143
	v_pk_mul_f32 v[144:145], v[138:139], v[140:141]
	v_pk_mul_f32 v[146:147], v[146:147], v[148:149]
	v_pk_fma_f32 v[138:139], v[138:139], v[140:141], v[144:145] op_sel:[0,0,1] op_sel_hi:[1,1,0]
	v_mul_f32_e32 v140, v144, v144
	v_pk_fma_f32 v[140:141], v[144:145], v[144:145], v[140:141] op_sel_hi:[1,1,0]
	v_pk_mul_f32 v[148:149], v[146:147], v[146:147]
	v_cvt_pk_bf16_f32 v132, v144, v145
	v_cvt_pk_bf16_f32 v133, v146, v147
	global_store_dwordx4 v[252:253], v[130:133], off offset:-3840
	v_mov_b32_e32 v140, v146
	v_mov_b32_e32 v139, v148
	v_pk_mov_b32 v[130:131], v[146:147], v[136:137] op_sel:[1,0]
	v_mov_b32_e32 v143, v149
	v_pk_add_f32 v[130:131], v[140:141], v[130:131]
	v_pk_add_f32 v[132:133], v[138:139], v[142:143]
	s_nop 0
	v_pk_add_f32 v[130:131], v[132:133], v[130:131]
	ds_bpermute_b32 v132, v221, v130
	ds_bpermute_b32 v133, v221, v131
	s_waitcnt lgkmcnt(0)
	v_pk_add_f32 v[130:131], v[130:131], v[132:133]
	ds_bpermute_b32 v132, v222, v130
	ds_bpermute_b32 v133, v222, v131
	s_and_saveexec_b64 s[22:23], vcc
	s_cbranch_execz .LBB0_723
	v_lshl_add_u64 v[134:135], s[78:79], 0, v[186:187]
	v_lshl_add_u64 v[134:135], s[0:1], 2, v[134:135]
	s_waitcnt lgkmcnt(0)
	v_pk_add_f32 v[130:131], v[130:131], v[132:133]
	global_store_dwordx2 v[134:135], v[130:131], off
.LBB0_723:
	s_or_b64 exec, exec, s[22:23]
	v_pk_mul_f32 v[130:131], v[38:39], v[152:153] op_sel_hi:[1,0]
	v_lshlrev_b64 v[134:135], 10, v[150:151]
	s_waitcnt lgkmcnt(0)
	v_pk_mul_f32 v[132:133], v[130:131], v[130:131]
	v_lshl_add_u64 v[134:135], s[44:45], 0, v[134:135]
	v_pk_fma_f32 v[132:133], v[132:133], s[92:93], 1.0 op_sel_hi:[1,0,0]
	v_lshl_add_u64 v[134:135], v[182:183], 1, v[134:135]
	v_pk_mul_f32 v[132:133], v[130:131], v[132:133]
	s_nop 0
	v_pk_mul_f32 v[132:133], v[132:133], s[48:49] op_sel_hi:[1,0]
	s_nop 0
	v_pk_mul_f32 v[132:133], v[132:133], s[94:95] op_sel_hi:[1,0]
	s_nop 0
	v_exp_f32_e32 v132, v132
	v_exp_f32_e32 v133, v133
	s_nop 0
	v_pk_add_f32 v[132:133], v[132:133], 1.0 op_sel_hi:[1,0]
	s_nop 0
	v_rcp_f32_e32 v132, v132
	v_rcp_f32_e32 v133, v133
	s_nop 0
	v_pk_mul_f32 v[130:131], v[130:131], v[132:133]
	v_pk_mul_f32 v[132:133], v[40:41], v[152:153] op_sel_hi:[1,0]
	v_mov_b32_e32 v139, v131
	v_pk_mul_f32 v[136:137], v[132:133], v[132:133]
	s_nop 0
	v_pk_fma_f32 v[136:137], v[136:137], s[92:93], 1.0 op_sel_hi:[1,0,0]
	s_nop 0
	v_pk_mul_f32 v[136:137], v[132:133], v[136:137]
	s_nop 0
	v_pk_mul_f32 v[136:137], v[136:137], s[48:49] op_sel_hi:[1,0]
	s_nop 0
	v_pk_mul_f32 v[136:137], v[136:137], s[94:95] op_sel_hi:[1,0]
	s_nop 0
	v_exp_f32_e32 v136, v136
	v_exp_f32_e32 v137, v137
	s_nop 0
	v_pk_add_f32 v[136:137], v[136:137], 1.0 op_sel_hi:[1,0]
	s_nop 0
	v_rcp_f32_e32 v136, v136
	v_rcp_f32_e32 v137, v137
	s_nop 0
	v_pk_mul_f32 v[132:133], v[132:133], v[136:137]
	s_nop 0
	v_mov_b32_e32 v136, v132
	v_mov_b32_e32 v137, v130
	v_mov_b32_e32 v138, v133
	v_pk_add_f32 v[136:137], v[136:137], v[138:139]
	v_mov_b32_e32 v138, v131
	v_add_f32_e32 v137, 0, v137
	v_mov_b32_e32 v139, v133
	v_add_f32_e32 v148, v136, v137
	v_mov_b32_e32 v136, v130
	v_mov_b32_e32 v137, v132
	v_pk_mul_f32 v[138:139], v[138:139], v[138:139]
	v_cvt_pk_bf16_f32 v130, v130, v131
	v_pk_fma_f32 v[136:137], v[136:137], v[136:137], v[138:139]
	v_pk_mul_f32 v[138:139], v[34:35], v[152:153] op_sel_hi:[1,0]
	v_cvt_pk_bf16_f32 v131, v132, v133
	v_pk_mul_f32 v[140:141], v[138:139], v[138:139]
	v_pk_add_f32 v[136:137], v[136:137], v[136:137] op_sel:[0,1] op_sel_hi:[1,0]
	v_pk_fma_f32 v[140:141], v[140:141], s[92:93], 1.0 op_sel_hi:[1,0,0]
	s_nop 0
	v_pk_mul_f32 v[140:141], v[138:139], v[140:141]
	s_nop 0
	v_pk_mul_f32 v[140:141], v[140:141], s[48:49] op_sel_hi:[1,0]
	s_nop 0
	v_pk_mul_f32 v[140:141], v[140:141], s[94:95] op_sel_hi:[1,0]
	s_nop 0
	v_exp_f32_e32 v140, v140
	v_exp_f32_e32 v141, v141
	s_nop 0
	v_pk_add_f32 v[140:141], v[140:141], 1.0 op_sel_hi:[1,0]
	s_nop 0
	v_rcp_f32_e32 v140, v140
	v_rcp_f32_e32 v141, v141
	s_nop 0
	v_pk_mul_f32 v[138:139], v[138:139], v[140:141]
	v_pk_mul_f32 v[140:141], v[36:37], v[152:153] op_sel_hi:[1,0]
	v_cvt_pk_bf16_f32 v132, v138, v139
	v_pk_mul_f32 v[142:143], v[140:141], v[140:141]
	v_mov_b32_e32 v145, v139
	v_pk_fma_f32 v[142:143], v[142:143], s[92:93], 1.0 op_sel_hi:[1,0,0]
	s_nop 0
	v_pk_mul_f32 v[142:143], v[140:141], v[142:143]
	s_nop 0
	v_pk_mul_f32 v[142:143], v[142:143], s[48:49] op_sel_hi:[1,0]
	s_nop 0
	v_pk_mul_f32 v[142:143], v[142:143], s[94:95] op_sel_hi:[1,0]
	s_nop 0
	v_exp_f32_e32 v142, v142
	v_exp_f32_e32 v143, v143
	s_nop 0
	v_pk_add_f32 v[142:143], v[142:143], 1.0 op_sel_hi:[1,0]
	s_nop 0
	v_rcp_f32_e32 v142, v142
	v_rcp_f32_e32 v143, v143
	s_nop 0
	v_pk_mul_f32 v[140:141], v[140:141], v[142:143]
	s_nop 0
	v_cvt_pk_bf16_f32 v133, v140, v141
	s_mov_b32 s98, 0x2d000
	s_mov_b32 s99, 0x0
	v_lshl_add_u64 v[252:253], v[250:251], 0, s[98:99]
	global_store_dwordx4 v[252:253], v[130:133], off offset:-4096
	v_mov_b32_e32 v143, v138
	v_mov_b32_e32 v142, v140
	v_pk_mul_f32 v[130:131], v[6:7], v[152:153] op_sel_hi:[1,0]
	v_mov_b32_e32 v144, v141
	v_pk_mul_f32 v[132:133], v[130:131], v[130:131]
	v_pk_add_f32 v[146:147], v[142:143], v[144:145]
	v_pk_fma_f32 v[132:133], v[132:133], s[92:93], 1.0 op_sel_hi:[1,0,0]
	v_pk_mul_f32 v[144:145], v[144:145], v[144:145]
	v_pk_mul_f32 v[132:133], v[130:131], v[132:133]
	v_pk_fma_f32 v[142:143], v[142:143], v[142:143], v[144:145]
	v_pk_mul_f32 v[132:133], v[132:133], s[48:49] op_sel_hi:[1,0]
	v_pk_add_f32 v[136:137], v[142:143], v[136:137] op_sel:[1,0] op_sel_hi:[0,1]
	v_pk_mul_f32 v[132:133], v[132:133], s[94:95] op_sel_hi:[1,0]
	v_pk_add_f32 v[136:137], v[142:143], v[136:137]
	v_exp_f32_e32 v132, v132
	v_exp_f32_e32 v133, v133
	v_add_f32_e32 v147, v147, v148
	v_add_f32_e32 v146, v146, v147
	v_pk_add_f32 v[132:133], v[132:133], 1.0 op_sel_hi:[1,0]
	s_nop 0
	v_rcp_f32_e32 v132, v132
	v_rcp_f32_e32 v133, v133
	s_nop 0
	v_pk_mul_f32 v[130:131], v[130:131], v[132:133]
	v_pk_mul_f32 v[132:133], v[8:9], v[152:153] op_sel_hi:[1,0]
	v_mov_b32_e32 v141, v131
	v_pk_mul_f32 v[138:139], v[132:133], v[132:133]
	s_nop 0
	v_pk_fma_f32 v[138:139], v[138:139], s[92:93], 1.0 op_sel_hi:[1,0,0]
	s_nop 0
	v_pk_mul_f32 v[138:139], v[132:133], v[138:139]
	s_nop 0
	v_pk_mul_f32 v[138:139], v[138:139], s[48:49] op_sel_hi:[1,0]
	s_nop 0
	v_pk_mul_f32 v[138:139], v[138:139], s[94:95] op_sel_hi:[1,0]
	s_nop 0
	v_exp_f32_e32 v138, v138
	v_exp_f32_e32 v139, v139
	s_nop 0
	v_pk_add_f32 v[138:139], v[138:139], 1.0 op_sel_hi:[1,0]
	s_nop 0
	v_rcp_f32_e32 v138, v138
	v_rcp_f32_e32 v139, v139
	s_nop 0
	v_pk_mul_f32 v[132:133], v[132:133], v[138:139]
	s_nop 0
	v_mov_b32_e32 v138, v132
	v_mov_b32_e32 v139, v130
	v_mov_b32_e32 v140, v133
	v_pk_add_f32 v[142:143], v[138:139], v[140:141]
	v_pk_mul_f32 v[140:141], v[140:141], v[140:141]
	v_add_f32_e32 v143, v143, v146
	v_pk_fma_f32 v[138:139], v[138:139], v[138:139], v[140:141]
	v_pk_mul_f32 v[146:147], v[4:5], v[152:153] op_sel_hi:[1,0]
	v_pk_add_f32 v[136:137], v[138:139], v[136:137] op_sel:[1,0] op_sel_hi:[0,1]
	v_pk_add_f32 v[136:137], v[138:139], v[136:137]
	v_pk_mul_f32 v[138:139], v[2:3], v[152:153] op_sel_hi:[1,0]
	v_pk_mul_f32 v[148:149], v[146:147], v[146:147]
	v_pk_mul_f32 v[140:141], v[138:139], v[138:139]
	v_pk_fma_f32 v[148:149], v[148:149], s[92:93], 1.0 op_sel_hi:[1,0,0]
	v_pk_fma_f32 v[140:141], v[140:141], s[92:93], 1.0 op_sel_hi:[1,0,0]
	v_pk_mul_f32 v[148:149], v[146:147], v[148:149]
	v_pk_mul_f32 v[140:141], v[138:139], v[140:141]
	v_pk_mul_f32 v[148:149], v[148:149], s[48:49] op_sel_hi:[1,0]
	v_pk_mul_f32 v[140:141], v[140:141], s[48:49] op_sel_hi:[1,0]
	v_pk_mul_f32 v[148:149], v[148:149], s[94:95] op_sel_hi:[1,0]
	v_pk_mul_f32 v[140:141], v[140:141], s[94:95] op_sel_hi:[1,0]
	v_exp_f32_e32 v148, v148
	v_exp_f32_e32 v140, v140
	v_exp_f32_e32 v141, v141
	v_exp_f32_e32 v149, v149
	v_cvt_pk_bf16_f32 v130, v130, v131
	v_cvt_pk_bf16_f32 v131, v132, v133
	v_pk_add_f32 v[140:141], v[140:141], 1.0 op_sel_hi:[1,0]
	v_pk_add_f32 v[148:149], v[148:149], 1.0 op_sel_hi:[1,0]
	v_rcp_f32_e32 v140, v140
	v_rcp_f32_e32 v141, v141
	v_rcp_f32_e32 v148, v148
	v_rcp_f32_e32 v149, v149
	v_add_f32_e32 v142, v142, v143
	v_pk_mul_f32 v[144:145], v[138:139], v[140:141]
	v_pk_mul_f32 v[146:147], v[146:147], v[148:149]
	v_pk_fma_f32 v[138:139], v[138:139], v[140:141], v[144:145] op_sel:[0,0,1] op_sel_hi:[1,1,0]
	v_mul_f32_e32 v140, v144, v144
	v_pk_fma_f32 v[140:141], v[144:145], v[144:145], v[140:141] op_sel_hi:[1,1,0]
	v_pk_mul_f32 v[148:149], v[146:147], v[146:147]
	v_cvt_pk_bf16_f32 v132, v144, v145
	v_cvt_pk_bf16_f32 v133, v146, v147
	global_store_dwordx4 v[252:253], v[130:133], off offset:-3840
	v_mov_b32_e32 v140, v146
	v_mov_b32_e32 v139, v148
	v_pk_mov_b32 v[130:131], v[146:147], v[136:137] op_sel:[1,0]
	v_mov_b32_e32 v143, v149
	v_pk_add_f32 v[130:131], v[140:141], v[130:131]
	v_pk_add_f32 v[132:133], v[138:139], v[142:143]
	s_nop 0
	v_pk_add_f32 v[130:131], v[132:133], v[130:131]
	ds_bpermute_b32 v132, v221, v130
	ds_bpermute_b32 v133, v221, v131
	s_waitcnt lgkmcnt(0)
	v_pk_add_f32 v[130:131], v[130:131], v[132:133]
	ds_bpermute_b32 v132, v222, v130
	ds_bpermute_b32 v133, v222, v131
	s_and_saveexec_b64 s[22:23], vcc
	s_cbranch_execz .LBB0_725
	v_lshl_add_u64 v[134:135], s[78:79], 0, v[184:185]
	v_lshl_add_u64 v[134:135], s[0:1], 2, v[134:135]
	s_waitcnt lgkmcnt(0)
	v_pk_add_f32 v[130:131], v[130:131], v[132:133]
	global_store_dwordx2 v[134:135], v[130:131], off

.LBB0_737:
	s_or_b64 exec, exec, s[22:23]
	v_lshlrev_b64 v[142:143], 10, v[178:179]
	s_waitcnt lgkmcnt(0)
	v_pk_mul_f32 v[132:133], v[128:129], v[180:181] op_sel_hi:[1,0]
	v_pk_mul_f32 v[130:131], v[126:127], v[180:181] op_sel_hi:[1,0]
	v_pk_mul_f32 v[136:137], v[124:125], v[180:181] op_sel_hi:[1,0]
	v_pk_mul_f32 v[134:135], v[122:123], v[180:181] op_sel_hi:[1,0]
	v_lshl_add_u64 v[142:143], s[40:41], 0, v[142:143]
	v_ashrrev_i32_e32 v183, 31, v182
	v_cmp_ne_u64_e32 vcc, 0, v[140:141]
	v_cvt_pk_bf16_f32 v144, v130, v131
	v_cvt_pk_bf16_f32 v145, v132, v133
	v_cvt_pk_bf16_f32 v146, v134, v135
	v_cvt_pk_bf16_f32 v147, v136, v137
	v_lshl_add_u64 v[142:143], v[182:183], 1, v[142:143]
	v_lshl_add_u64 v[140:141], v[182:183], 2, v[140:141]
	v_lshl_add_u64 v[148:149], v[142:143], 0, 0
	global_store_dwordx4 v[142:143], v[144:147], off
	s_and_saveexec_b64 s[22:23], vcc
	s_cbranch_execz .LBB0_739
	global_store_dwordx4 v[140:141], v[130:133], off
	global_store_dwordx4 v[140:141], v[134:137], off offset:16
.LBB0_739:
	s_or_b64 exec, exec, s[22:23]
	v_mov_b32_e32 v181, v180
	v_mov_b32_e32 v134, v180
	v_mov_b32_e32 v135, v180
	v_pk_mul_f32 v[132:133], v[96:97], v[134:135]
	v_pk_mul_f32 v[130:131], v[94:95], v[180:181]
	v_pk_mul_f32 v[136:137], v[92:93], v[134:135]
	v_pk_mul_f32 v[134:135], v[90:91], v[180:181]
	v_cvt_pk_bf16_f32 v144, v130, v131
	v_cvt_pk_bf16_f32 v145, v132, v133
	v_cvt_pk_bf16_f32 v146, v134, v135
	v_cvt_pk_bf16_f32 v147, v136, v137
	s_mov_b32 s98, 0x1000
	s_mov_b32 s99, 0x0
	v_lshl_add_u64 v[184:185], v[148:149], 0, s[98:99]
	global_store_dwordx4 v[184:185], v[144:147], off offset:-3840
	s_and_saveexec_b64 s[22:23], vcc
	s_cbranch_execz .LBB0_741
	global_store_dwordx4 v[140:141], v[130:133], off offset:512
	global_store_dwordx4 v[140:141], v[134:137], off offset:528

.LBB0_749:
	s_or_b64 exec, exec, s[22:23]
	v_pk_mul_f32 v[132:133], v[120:121], v[176:177] op_sel_hi:[1,0]
	v_pk_mul_f32 v[130:131], v[118:119], v[176:177] op_sel_hi:[1,0]
	v_pk_mul_f32 v[136:137], v[116:117], v[176:177] op_sel_hi:[1,0]
	v_pk_mul_f32 v[134:135], v[114:115], v[176:177] op_sel_hi:[1,0]
	v_cmp_ne_u64_e32 vcc, 0, v[140:141]
	v_cvt_pk_bf16_f32 v144, v130, v131
	v_cvt_pk_bf16_f32 v145, v132, v133
	v_cvt_pk_bf16_f32 v146, v134, v135
	v_cvt_pk_bf16_f32 v147, v136, v137
	s_nop 0
	v_lshl_add_u64 v[140:141], v[182:183], 2, v[140:141]
	s_mov_b32 s98, 0x5000
	s_mov_b32 s99, 0x0
	v_lshl_add_u64 v[184:185], v[148:149], 0, s[98:99]
	global_store_dwordx4 v[184:185], v[144:147], off offset:-4096
	s_and_saveexec_b64 s[22:23], vcc
	s_cbranch_execz .LBB0_751
	global_store_dwordx4 v[140:141], v[130:133], off
	global_store_dwordx4 v[140:141], v[134:137], off offset:16
.LBB0_751:
	s_or_b64 exec, exec, s[22:23]
	v_mov_b32_e32 v177, v176
	v_mov_b32_e32 v134, v176
	v_mov_b32_e32 v135, v176
	v_pk_mul_f32 v[132:133], v[88:89], v[134:135]
	v_pk_mul_f32 v[130:131], v[86:87], v[176:177]
	v_pk_mul_f32 v[136:137], v[84:85], v[134:135]
	v_pk_mul_f32 v[134:135], v[82:83], v[176:177]
	v_cvt_pk_bf16_f32 v144, v130, v131
	v_cvt_pk_bf16_f32 v145, v132, v133
	v_cvt_pk_bf16_f32 v146, v134, v135
	v_cvt_pk_bf16_f32 v147, v136, v137
	global_store_dwordx4 v[184:185], v[144:147], off offset:-3840
	s_and_saveexec_b64 s[22:23], vcc
	s_cbranch_execz .LBB0_753
	global_store_dwordx4 v[140:141], v[130:133], off offset:512
	global_store_dwordx4 v[140:141], v[134:137], off offset:528

.LBB0_761:
	s_or_b64 exec, exec, s[22:23]
	v_pk_mul_f32 v[132:133], v[112:113], v[172:173] op_sel_hi:[1,0]
	v_pk_mul_f32 v[130:131], v[110:111], v[172:173] op_sel_hi:[1,0]
	v_pk_mul_f32 v[136:137], v[108:109], v[172:173] op_sel_hi:[1,0]
	v_pk_mul_f32 v[134:135], v[106:107], v[172:173] op_sel_hi:[1,0]
	v_cmp_ne_u64_e32 vcc, 0, v[140:141]
	v_cvt_pk_bf16_f32 v144, v130, v131
	v_cvt_pk_bf16_f32 v145, v132, v133
	v_cvt_pk_bf16_f32 v146, v134, v135
	v_cvt_pk_bf16_f32 v147, v136, v137
	s_nop 0
	v_lshl_add_u64 v[140:141], v[182:183], 2, v[140:141]
	s_mov_b32 s98, 0x9000
	s_mov_b32 s99, 0x0
	v_lshl_add_u64 v[184:185], v[148:149], 0, s[98:99]
	global_store_dwordx4 v[184:185], v[144:147], off offset:-4096
	s_and_saveexec_b64 s[22:23], vcc
	s_cbranch_execz .LBB0_763
	global_store_dwordx4 v[140:141], v[130:133], off
	global_store_dwordx4 v[140:141], v[134:137], off offset:16
.LBB0_763:
	s_or_b64 exec, exec, s[22:23]
	v_mov_b32_e32 v173, v172
	v_mov_b32_e32 v134, v172
	v_mov_b32_e32 v135, v172
	v_pk_mul_f32 v[132:133], v[80:81], v[134:135]
	v_pk_mul_f32 v[130:131], v[78:79], v[172:173]
	v_pk_mul_f32 v[136:137], v[76:77], v[134:135]
	v_pk_mul_f32 v[134:135], v[74:75], v[172:173]
	v_cvt_pk_bf16_f32 v144, v130, v131
	v_cvt_pk_bf16_f32 v145, v132, v133
	v_cvt_pk_bf16_f32 v146, v134, v135
	v_cvt_pk_bf16_f32 v147, v136, v137
	global_store_dwordx4 v[184:185], v[144:147], off offset:-3840
	s_and_saveexec_b64 s[22:23], vcc
	s_cbranch_execz .LBB0_765
	global_store_dwordx4 v[140:141], v[130:133], off offset:512
	global_store_dwordx4 v[140:141], v[134:137], off offset:528

.LBB0_773:
	s_or_b64 exec, exec, s[22:23]
	v_pk_mul_f32 v[132:133], v[104:105], v[168:169] op_sel_hi:[1,0]
	v_pk_mul_f32 v[130:131], v[102:103], v[168:169] op_sel_hi:[1,0]
	v_pk_mul_f32 v[136:137], v[100:101], v[168:169] op_sel_hi:[1,0]
	v_pk_mul_f32 v[134:135], v[98:99], v[168:169] op_sel_hi:[1,0]
	v_cmp_ne_u64_e32 vcc, 0, v[140:141]
	v_cvt_pk_bf16_f32 v144, v130, v131
	v_cvt_pk_bf16_f32 v145, v132, v133
	v_cvt_pk_bf16_f32 v146, v134, v135
	v_cvt_pk_bf16_f32 v147, v136, v137
	s_nop 0
	v_lshl_add_u64 v[140:141], v[182:183], 2, v[140:141]
	s_mov_b32 s98, 0xd000
	s_mov_b32 s99, 0x0
	v_lshl_add_u64 v[184:185], v[148:149], 0, s[98:99]
	global_store_dwordx4 v[184:185], v[144:147], off offset:-4096
	s_and_saveexec_b64 s[22:23], vcc
	s_cbranch_execz .LBB0_775
	global_store_dwordx4 v[140:141], v[130:133], off
	global_store_dwordx4 v[140:141], v[134:137], off offset:16
.LBB0_775:
	s_or_b64 exec, exec, s[22:23]
	v_mov_b32_e32 v169, v168
	v_mov_b32_e32 v134, v168
	v_mov_b32_e32 v135, v168
	v_pk_mul_f32 v[132:133], v[72:73], v[134:135]
	v_pk_mul_f32 v[130:131], v[70:71], v[168:169]
	v_pk_mul_f32 v[136:137], v[68:69], v[134:135]
	v_pk_mul_f32 v[134:135], v[66:67], v[168:169]
	v_cvt_pk_bf16_f32 v144, v130, v131
	v_cvt_pk_bf16_f32 v145, v132, v133
	v_cvt_pk_bf16_f32 v146, v134, v135
	v_cvt_pk_bf16_f32 v147, v136, v137
	global_store_dwordx4 v[184:185], v[144:147], off offset:-3840
	s_and_saveexec_b64 s[22:23], vcc
	s_cbranch_execz .LBB0_777
	global_store_dwordx4 v[140:141], v[130:133], off offset:512
	global_store_dwordx4 v[140:141], v[134:137], off offset:528

.LBB0_785:
	s_or_b64 exec, exec, s[22:23]
	v_pk_mul_f32 v[132:133], v[64:65], v[164:165] op_sel_hi:[1,0]
	v_pk_mul_f32 v[130:131], v[62:63], v[164:165] op_sel_hi:[1,0]
	v_pk_mul_f32 v[136:137], v[60:61], v[164:165] op_sel_hi:[1,0]
	v_pk_mul_f32 v[134:135], v[58:59], v[164:165] op_sel_hi:[1,0]
	v_cmp_ne_u64_e32 vcc, 0, v[140:141]
	v_cvt_pk_bf16_f32 v144, v130, v131
	v_cvt_pk_bf16_f32 v145, v132, v133
	v_cvt_pk_bf16_f32 v146, v134, v135
	v_cvt_pk_bf16_f32 v147, v136, v137
	s_nop 0
	v_lshl_add_u64 v[140:141], v[182:183], 2, v[140:141]
	s_mov_b32 s98, 0x21000
	s_mov_b32 s99, 0x0
	v_lshl_add_u64 v[184:185], v[148:149], 0, s[98:99]
	global_store_dwordx4 v[184:185], v[144:147], off offset:-4096
	s_and_saveexec_b64 s[22:23], vcc
	s_cbranch_execz .LBB0_787
	global_store_dwordx4 v[140:141], v[130:133], off
	global_store_dwordx4 v[140:141], v[134:137], off offset:16
.LBB0_787:
	s_or_b64 exec, exec, s[22:23]
	v_mov_b32_e32 v165, v164
	v_mov_b32_e32 v134, v164
	v_mov_b32_e32 v135, v164
	v_pk_mul_f32 v[132:133], v[32:33], v[134:135]
	v_pk_mul_f32 v[130:131], v[30:31], v[164:165]
	v_pk_mul_f32 v[136:137], v[28:29], v[134:135]
	v_pk_mul_f32 v[134:135], v[26:27], v[164:165]
	v_cvt_pk_bf16_f32 v144, v130, v131
	v_cvt_pk_bf16_f32 v145, v132, v133
	v_cvt_pk_bf16_f32 v146, v134, v135
	v_cvt_pk_bf16_f32 v147, v136, v137
	global_store_dwordx4 v[184:185], v[144:147], off offset:-3840
	s_and_saveexec_b64 s[22:23], vcc
	s_cbranch_execz .LBB0_789
	global_store_dwordx4 v[140:141], v[130:133], off offset:512
	global_store_dwordx4 v[140:141], v[134:137], off offset:528

.LBB0_797:
	s_or_b64 exec, exec, s[22:23]
	v_pk_mul_f32 v[132:133], v[56:57], v[160:161] op_sel_hi:[1,0]
	v_pk_mul_f32 v[130:131], v[54:55], v[160:161] op_sel_hi:[1,0]
	v_pk_mul_f32 v[136:137], v[52:53], v[160:161] op_sel_hi:[1,0]
	v_pk_mul_f32 v[134:135], v[50:51], v[160:161] op_sel_hi:[1,0]
	v_cmp_ne_u64_e32 vcc, 0, v[140:141]
	v_cvt_pk_bf16_f32 v144, v130, v131
	v_cvt_pk_bf16_f32 v145, v132, v133
	v_cvt_pk_bf16_f32 v146, v134, v135
	v_cvt_pk_bf16_f32 v147, v136, v137
	s_nop 0
	v_lshl_add_u64 v[140:141], v[182:183], 2, v[140:141]
	s_mov_b32 s98, 0x25000
	s_mov_b32 s99, 0x0
	v_lshl_add_u64 v[184:185], v[148:149], 0, s[98:99]
	global_store_dwordx4 v[184:185], v[144:147], off offset:-4096
	s_and_saveexec_b64 s[22:23], vcc
	s_cbranch_execz .LBB0_799
	global_store_dwordx4 v[140:141], v[130:133], off
	global_store_dwordx4 v[140:141], v[134:137], off offset:16
.LBB0_799:
	s_or_b64 exec, exec, s[22:23]
	v_mov_b32_e32 v161, v160
	v_mov_b32_e32 v134, v160
	v_mov_b32_e32 v135, v160
	v_pk_mul_f32 v[132:133], v[24:25], v[134:135]
	v_pk_mul_f32 v[130:131], v[22:23], v[160:161]
	v_pk_mul_f32 v[136:137], v[20:21], v[134:135]
	v_pk_mul_f32 v[134:135], v[18:19], v[160:161]
	v_cvt_pk_bf16_f32 v144, v130, v131
	v_cvt_pk_bf16_f32 v145, v132, v133
	v_cvt_pk_bf16_f32 v146, v134, v135
	v_cvt_pk_bf16_f32 v147, v136, v137
	global_store_dwordx4 v[184:185], v[144:147], off offset:-3840
	s_and_saveexec_b64 s[22:23], vcc
	s_cbranch_execz .LBB0_801
	global_store_dwordx4 v[140:141], v[130:133], off offset:512
	global_store_dwordx4 v[140:141], v[134:137], off offset:528

.LBB0_809:
	s_or_b64 exec, exec, s[22:23]
	v_pk_mul_f32 v[132:133], v[48:49], v[156:157] op_sel_hi:[1,0]
	v_pk_mul_f32 v[130:131], v[46:47], v[156:157] op_sel_hi:[1,0]
	v_pk_mul_f32 v[136:137], v[44:45], v[156:157] op_sel_hi:[1,0]
	v_pk_mul_f32 v[134:135], v[42:43], v[156:157] op_sel_hi:[1,0]
	v_cmp_ne_u64_e32 vcc, 0, v[140:141]
	v_cvt_pk_bf16_f32 v144, v130, v131
	v_cvt_pk_bf16_f32 v145, v132, v133
	v_cvt_pk_bf16_f32 v146, v134, v135
	v_cvt_pk_bf16_f32 v147, v136, v137
	s_nop 0
	v_lshl_add_u64 v[140:141], v[182:183], 2, v[140:141]
	s_mov_b32 s98, 0x29000
	s_mov_b32 s99, 0x0
	v_lshl_add_u64 v[184:185], v[148:149], 0, s[98:99]
	global_store_dwordx4 v[184:185], v[144:147], off offset:-4096
	s_and_saveexec_b64 s[22:23], vcc
	s_cbranch_execz .LBB0_811
	global_store_dwordx4 v[140:141], v[130:133], off
	global_store_dwordx4 v[140:141], v[134:137], off offset:16
.LBB0_811:
	s_or_b64 exec, exec, s[22:23]
	v_mov_b32_e32 v157, v156
	v_mov_b32_e32 v134, v156
	v_mov_b32_e32 v135, v156
	v_pk_mul_f32 v[132:133], v[16:17], v[134:135]
	v_pk_mul_f32 v[130:131], v[14:15], v[156:157]
	v_pk_mul_f32 v[136:137], v[12:13], v[134:135]
	v_pk_mul_f32 v[134:135], v[10:11], v[156:157]
	v_cvt_pk_bf16_f32 v144, v130, v131
	v_cvt_pk_bf16_f32 v145, v132, v133
	v_cvt_pk_bf16_f32 v146, v134, v135
	v_cvt_pk_bf16_f32 v147, v136, v137
	global_store_dwordx4 v[184:185], v[144:147], off offset:-3840
	s_and_saveexec_b64 s[22:23], vcc
	s_cbranch_execz .LBB0_813
	global_store_dwordx4 v[140:141], v[130:133], off offset:512
	global_store_dwordx4 v[140:141], v[134:137], off offset:528

.LBB0_821:
	s_or_b64 exec, exec, s[0:1]
	v_pk_mul_f32 v[132:133], v[40:41], v[152:153] op_sel_hi:[1,0]
	v_pk_mul_f32 v[130:131], v[38:39], v[152:153] op_sel_hi:[1,0]
	v_pk_mul_f32 v[136:137], v[36:37], v[152:153] op_sel_hi:[1,0]
	v_pk_mul_f32 v[134:135], v[34:35], v[152:153] op_sel_hi:[1,0]
	v_cmp_ne_u64_e32 vcc, 0, v[140:141]
	v_cvt_pk_bf16_f32 v144, v130, v131
	v_cvt_pk_bf16_f32 v145, v132, v133
	v_cvt_pk_bf16_f32 v146, v134, v135
	v_cvt_pk_bf16_f32 v147, v136, v137
	s_nop 0
	v_lshl_add_u64 v[138:139], v[182:183], 2, v[140:141]
	s_mov_b32 s98, 0x2d000
	s_mov_b32 s99, 0x0
	v_lshl_add_u64 v[184:185], v[148:149], 0, s[98:99]
	global_store_dwordx4 v[184:185], v[144:147], off offset:-4096
	s_and_saveexec_b64 s[0:1], vcc
	s_cbranch_execz .LBB0_823
	global_store_dwordx4 v[138:139], v[130:133], off
	global_store_dwordx4 v[138:139], v[134:137], off offset:16
.LBB0_823:
	s_or_b64 exec, exec, s[0:1]
	v_mov_b32_e32 v153, v152
	v_mov_b32_e32 v134, v152
	v_mov_b32_e32 v135, v152
	v_pk_mul_f32 v[132:133], v[8:9], v[134:135]
	v_pk_mul_f32 v[130:131], v[6:7], v[152:153]
	v_pk_mul_f32 v[136:137], v[4:5], v[134:135]
	v_pk_mul_f32 v[134:135], v[2:3], v[152:153]
	v_cvt_pk_bf16_f32 v144, v130, v131
	v_cvt_pk_bf16_f32 v145, v132, v133
	v_cvt_pk_bf16_f32 v146, v134, v135
	v_cvt_pk_bf16_f32 v147, v136, v137
	global_store_dwordx4 v[184:185], v[144:147], off offset:-3840
	s_and_saveexec_b64 s[0:1], vcc
	s_cbranch_execz .LBB0_825
	global_store_dwordx4 v[138:139], v[130:133], off offset:512
	global_store_dwordx4 v[138:139], v[134:137], off offset:528

.LBB0_826:
	s_and_b64 vcc, exec, s[0:1]
	s_cbranch_vccz .LBB0_828
	s_waitcnt lgkmcnt(0)
	v_pk_mul_f32 v[132:133], v[126:127], v[180:181] op_sel_hi:[1,0]
	v_ashrrev_i32_e32 v183, 31, v182
	v_pk_mul_f32 v[134:135], v[132:133], v[132:133]
	v_lshlrev_b64 v[130:131], 10, v[178:179]
	v_pk_fma_f32 v[134:135], v[134:135], s[92:93], 1.0 op_sel_hi:[1,0,0]
	s_nop 0
	v_pk_mul_f32 v[134:135], v[132:133], v[134:135]
	s_nop 0
	v_pk_mul_f32 v[134:135], v[134:135], s[48:49] op_sel_hi:[1,0]
	s_nop 0
	v_pk_mul_f32 v[134:135], v[134:135], s[94:95] op_sel_hi:[1,0]
	s_nop 0
	v_exp_f32_e32 v134, v134
	v_exp_f32_e32 v135, v135
	s_nop 0
	v_pk_add_f32 v[134:135], v[134:135], 1.0 op_sel_hi:[1,0]
	s_nop 0
	v_rcp_f32_e32 v134, v134
	v_rcp_f32_e32 v135, v135
	s_nop 0
	v_pk_mul_f32 v[132:133], v[132:133], v[134:135]
	v_pk_mul_f32 v[134:135], v[128:129], v[180:181] op_sel_hi:[1,0]
	v_cvt_pk_bf16_f32 v132, v132, v133
	v_pk_mul_f32 v[136:137], v[134:135], v[134:135]
	s_nop 0
	v_pk_fma_f32 v[136:137], v[136:137], s[92:93], 1.0 op_sel_hi:[1,0,0]
	s_nop 0
	v_pk_mul_f32 v[136:137], v[134:135], v[136:137]
	s_nop 0
	v_pk_mul_f32 v[136:137], v[136:137], s[48:49] op_sel_hi:[1,0]
	s_nop 0
	v_pk_mul_f32 v[136:137], v[136:137], s[94:95] op_sel_hi:[1,0]
	s_nop 0
	v_exp_f32_e32 v136, v136
	v_exp_f32_e32 v137, v137
	s_nop 0
	v_pk_add_f32 v[136:137], v[136:137], 1.0 op_sel_hi:[1,0]
	s_nop 0
	v_rcp_f32_e32 v136, v136
	v_rcp_f32_e32 v137, v137
	s_nop 0
	v_pk_mul_f32 v[134:135], v[134:135], v[136:137]
	v_pk_mul_f32 v[136:137], v[122:123], v[180:181] op_sel_hi:[1,0]
	v_cvt_pk_bf16_f32 v133, v134, v135
	v_pk_mul_f32 v[138:139], v[136:137], v[136:137]
	s_nop 0
	v_pk_fma_f32 v[138:139], v[138:139], s[92:93], 1.0 op_sel_hi:[1,0,0]
	s_nop 0
	v_pk_mul_f32 v[138:139], v[136:137], v[138:139]
	s_nop 0
	v_pk_mul_f32 v[138:139], v[138:139], s[48:49] op_sel_hi:[1,0]
	s_nop 0
	v_pk_mul_f32 v[138:139], v[138:139], s[94:95] op_sel_hi:[1,0]
	s_nop 0
	v_exp_f32_e32 v138, v138
	v_exp_f32_e32 v139, v139
	s_nop 0
	v_pk_add_f32 v[138:139], v[138:139], 1.0 op_sel_hi:[1,0]
	s_nop 0
	v_rcp_f32_e32 v138, v138
	v_rcp_f32_e32 v139, v139
	s_nop 0
	v_pk_mul_f32 v[136:137], v[136:137], v[138:139]
	v_pk_mul_f32 v[138:139], v[124:125], v[180:181] op_sel_hi:[1,0]
	v_cvt_pk_bf16_f32 v134, v136, v137
	v_pk_mul_f32 v[140:141], v[138:139], v[138:139]
	v_lshl_add_u64 v[136:137], s[42:43], 0, v[130:131]
	v_pk_fma_f32 v[140:141], v[140:141], s[92:93], 1.0 op_sel_hi:[1,0,0]
	v_lshlrev_b64 v[130:131], 1, v[182:183]
	v_pk_mul_f32 v[140:141], v[138:139], v[140:141]
	v_lshl_add_u64 v[136:137], v[136:137], 0, v[130:131]
	v_pk_mul_f32 v[140:141], v[140:141], s[48:49] op_sel_hi:[1,0]
	s_nop 0
	v_pk_mul_f32 v[140:141], v[140:141], s[94:95] op_sel_hi:[1,0]
	s_nop 0
	v_exp_f32_e32 v140, v140
	v_exp_f32_e32 v141, v141
	s_nop 0
	v_pk_add_f32 v[140:141], v[140:141], 1.0 op_sel_hi:[1,0]
	s_nop 0
	v_rcp_f32_e32 v140, v140
	v_rcp_f32_e32 v141, v141
	s_nop 0
	v_pk_mul_f32 v[138:139], v[138:139], v[140:141]
	s_nop 0
	v_cvt_pk_bf16_f32 v135, v138, v139
	v_lshl_add_u64 v[144:145], v[136:137], 0, 0
	global_store_dwordx4 v[136:137], v[132:135], off
	s_nop 1
	v_pk_mul_f32 v[132:133], v[94:95], v[180:181] op_sel_hi:[1,0]
	s_nop 0
	v_pk_mul_f32 v[134:135], v[132:133], v[132:133]
	s_nop 0
	v_pk_fma_f32 v[134:135], v[134:135], s[92:93], 1.0 op_sel_hi:[1,0,0]
	s_nop 0
	v_pk_mul_f32 v[134:135], v[132:133], v[134:135]
	s_nop 0
	v_pk_mul_f32 v[134:135], v[134:135], s[48:49] op_sel_hi:[1,0]
	s_nop 0
	v_pk_mul_f32 v[134:135], v[134:135], s[94:95] op_sel_hi:[1,0]
	s_nop 0
	v_exp_f32_e32 v134, v134
	v_exp_f32_e32 v135, v135
	s_nop 0
	v_pk_add_f32 v[134:135], v[134:135], 1.0 op_sel_hi:[1,0]
	s_nop 0
	v_rcp_f32_e32 v134, v134
	v_rcp_f32_e32 v135, v135
	s_nop 0
	v_pk_mul_f32 v[132:133], v[132:133], v[134:135]
	v_pk_mul_f32 v[134:135], v[96:97], v[180:181] op_sel_hi:[1,0]
	v_cvt_pk_bf16_f32 v132, v132, v133
	v_pk_mul_f32 v[138:139], v[134:135], v[134:135]
	s_nop 0
	v_pk_fma_f32 v[138:139], v[138:139], s[92:93], 1.0 op_sel_hi:[1,0,0]
	s_nop 0
	v_pk_mul_f32 v[138:139], v[134:135], v[138:139]
	s_nop 0
	v_pk_mul_f32 v[138:139], v[138:139], s[48:49] op_sel_hi:[1,0]
	s_nop 0
	v_pk_mul_f32 v[138:139], v[138:139], s[94:95] op_sel_hi:[1,0]
	s_nop 0
	v_exp_f32_e32 v138, v138
	v_exp_f32_e32 v139, v139
	s_nop 0
	v_pk_add_f32 v[138:139], v[138:139], 1.0 op_sel_hi:[1,0]
	s_nop 0
	v_rcp_f32_e32 v138, v138
	v_rcp_f32_e32 v139, v139
	s_nop 0
	v_pk_mul_f32 v[134:135], v[134:135], v[138:139]
	v_pk_mul_f32 v[138:139], v[90:91], v[180:181] op_sel_hi:[1,0]
	v_cvt_pk_bf16_f32 v133, v134, v135
	v_pk_mul_f32 v[140:141], v[138:139], v[138:139]
	s_nop 0
	v_pk_fma_f32 v[140:141], v[140:141], s[92:93], 1.0 op_sel_hi:[1,0,0]
	s_nop 0
	v_pk_mul_f32 v[140:141], v[138:139], v[140:141]
	s_nop 0
	v_pk_mul_f32 v[140:141], v[140:141], s[48:49] op_sel_hi:[1,0]
	s_nop 0
	v_pk_mul_f32 v[140:141], v[140:141], s[94:95] op_sel_hi:[1,0]
	s_nop 0
	v_exp_f32_e32 v140, v140
	v_exp_f32_e32 v141, v141
	s_nop 0
	v_pk_add_f32 v[140:141], v[140:141], 1.0 op_sel_hi:[1,0]
	s_nop 0
	v_rcp_f32_e32 v140, v140
	v_rcp_f32_e32 v141, v141
	s_nop 0
	v_pk_mul_f32 v[138:139], v[138:139], v[140:141]
	v_pk_mul_f32 v[140:141], v[92:93], v[180:181] op_sel_hi:[1,0]
	v_cvt_pk_bf16_f32 v134, v138, v139
	v_pk_mul_f32 v[142:143], v[140:141], v[140:141]
	s_nop 0
	v_pk_fma_f32 v[142:143], v[142:143], s[92:93], 1.0 op_sel_hi:[1,0,0]
	s_nop 0
	v_pk_mul_f32 v[142:143], v[140:141], v[142:143]
	s_nop 0
	v_pk_mul_f32 v[142:143], v[142:143], s[48:49] op_sel_hi:[1,0]
	s_nop 0
	v_pk_mul_f32 v[142:143], v[142:143], s[94:95] op_sel_hi:[1,0]
	s_nop 0
	v_exp_f32_e32 v142, v142
	v_exp_f32_e32 v143, v143
	s_nop 0
	v_pk_add_f32 v[142:143], v[142:143], 1.0 op_sel_hi:[1,0]
	s_nop 0
	v_rcp_f32_e32 v142, v142
	v_rcp_f32_e32 v143, v143
	s_nop 0
	v_pk_mul_f32 v[140:141], v[140:141], v[142:143]
	s_nop 0
	v_cvt_pk_bf16_f32 v135, v140, v141
	s_mov_b32 s98, 0x1000
	s_mov_b32 s99, 0x0
	v_lshl_add_u64 v[146:147], v[144:145], 0, s[98:99]
	global_store_dwordx4 v[146:147], v[132:135], off offset:-3840
	s_nop 0
	s_nop 0
	v_pk_mul_f32 v[132:133], v[118:119], v[176:177] op_sel_hi:[1,0]
	s_nop 0
	v_pk_mul_f32 v[134:135], v[132:133], v[132:133]
	s_nop 0
	v_pk_fma_f32 v[134:135], v[134:135], s[92:93], 1.0 op_sel_hi:[1,0,0]
	s_nop 0
	v_pk_mul_f32 v[134:135], v[132:133], v[134:135]
	s_nop 0
	v_pk_mul_f32 v[134:135], v[134:135], s[48:49] op_sel_hi:[1,0]
	s_nop 0
	v_pk_mul_f32 v[134:135], v[134:135], s[94:95] op_sel_hi:[1,0]
	s_nop 0
	v_exp_f32_e32 v134, v134
	v_exp_f32_e32 v135, v135
	s_nop 0
	v_pk_add_f32 v[134:135], v[134:135], 1.0 op_sel_hi:[1,0]
	s_nop 0
	v_rcp_f32_e32 v134, v134
	v_rcp_f32_e32 v135, v135
	s_nop 0
	v_pk_mul_f32 v[132:133], v[132:133], v[134:135]
	v_pk_mul_f32 v[134:135], v[120:121], v[176:177] op_sel_hi:[1,0]
	v_cvt_pk_bf16_f32 v132, v132, v133
	v_pk_mul_f32 v[138:139], v[134:135], v[134:135]
	s_nop 0
	v_pk_fma_f32 v[138:139], v[138:139], s[92:93], 1.0 op_sel_hi:[1,0,0]
	s_nop 0
	v_pk_mul_f32 v[138:139], v[134:135], v[138:139]
	s_nop 0
	v_pk_mul_f32 v[138:139], v[138:139], s[48:49] op_sel_hi:[1,0]
	s_nop 0
	v_pk_mul_f32 v[138:139], v[138:139], s[94:95] op_sel_hi:[1,0]
	s_nop 0
	v_exp_f32_e32 v138, v138
	v_exp_f32_e32 v139, v139
	s_nop 0
	v_pk_add_f32 v[138:139], v[138:139], 1.0 op_sel_hi:[1,0]
	s_nop 0
	v_rcp_f32_e32 v138, v138
	v_rcp_f32_e32 v139, v139
	s_nop 0
	v_pk_mul_f32 v[134:135], v[134:135], v[138:139]
	v_pk_mul_f32 v[138:139], v[114:115], v[176:177] op_sel_hi:[1,0]
	v_cvt_pk_bf16_f32 v133, v134, v135
	v_pk_mul_f32 v[140:141], v[138:139], v[138:139]
	s_nop 0
	v_pk_fma_f32 v[140:141], v[140:141], s[92:93], 1.0 op_sel_hi:[1,0,0]
	s_nop 0
	v_pk_mul_f32 v[140:141], v[138:139], v[140:141]
	s_nop 0
	v_pk_mul_f32 v[140:141], v[140:141], s[48:49] op_sel_hi:[1,0]
	s_nop 0
	v_pk_mul_f32 v[140:141], v[140:141], s[94:95] op_sel_hi:[1,0]
	s_nop 0
	v_exp_f32_e32 v140, v140
	v_exp_f32_e32 v141, v141
	s_nop 0
	v_pk_add_f32 v[140:141], v[140:141], 1.0 op_sel_hi:[1,0]
	s_nop 0
	v_rcp_f32_e32 v140, v140
	v_rcp_f32_e32 v141, v141
	s_nop 0
	v_pk_mul_f32 v[138:139], v[138:139], v[140:141]
	v_pk_mul_f32 v[140:141], v[116:117], v[176:177] op_sel_hi:[1,0]
	v_cvt_pk_bf16_f32 v134, v138, v139
	v_pk_mul_f32 v[142:143], v[140:141], v[140:141]
	s_nop 0
	v_pk_fma_f32 v[142:143], v[142:143], s[92:93], 1.0 op_sel_hi:[1,0,0]
	s_nop 0
	v_pk_mul_f32 v[142:143], v[140:141], v[142:143]
	s_nop 0
	v_pk_mul_f32 v[142:143], v[142:143], s[48:49] op_sel_hi:[1,0]
	s_nop 0
	v_pk_mul_f32 v[142:143], v[142:143], s[94:95] op_sel_hi:[1,0]
	s_nop 0
	v_exp_f32_e32 v142, v142
	v_exp_f32_e32 v143, v143
	s_nop 0
	v_pk_add_f32 v[142:143], v[142:143], 1.0 op_sel_hi:[1,0]
	s_nop 0
	v_rcp_f32_e32 v142, v142
	v_rcp_f32_e32 v143, v143
	s_nop 0
	v_pk_mul_f32 v[140:141], v[140:141], v[142:143]
	s_nop 0
	v_cvt_pk_bf16_f32 v135, v140, v141
	s_mov_b32 s98, 0x5000
	s_mov_b32 s99, 0x0
	v_lshl_add_u64 v[146:147], v[144:145], 0, s[98:99]
	global_store_dwordx4 v[146:147], v[132:135], off offset:-4096
	s_nop 1
	v_pk_mul_f32 v[132:133], v[86:87], v[176:177] op_sel_hi:[1,0]
	s_nop 0
	v_pk_mul_f32 v[134:135], v[132:133], v[132:133]
	s_nop 0
	v_pk_fma_f32 v[134:135], v[134:135], s[92:93], 1.0 op_sel_hi:[1,0,0]
	s_nop 0
	v_pk_mul_f32 v[134:135], v[132:133], v[134:135]
	s_nop 0
	v_pk_mul_f32 v[134:135], v[134:135], s[48:49] op_sel_hi:[1,0]
	s_nop 0
	v_pk_mul_f32 v[134:135], v[134:135], s[94:95] op_sel_hi:[1,0]
	s_nop 0
	v_exp_f32_e32 v134, v134
	v_exp_f32_e32 v135, v135
	s_nop 0
	v_pk_add_f32 v[134:135], v[134:135], 1.0 op_sel_hi:[1,0]
	s_nop 0
	v_rcp_f32_e32 v134, v134
	v_rcp_f32_e32 v135, v135
	s_nop 0
	v_pk_mul_f32 v[132:133], v[132:133], v[134:135]
	v_pk_mul_f32 v[134:135], v[88:89], v[176:177] op_sel_hi:[1,0]
	v_cvt_pk_bf16_f32 v132, v132, v133
	v_pk_mul_f32 v[138:139], v[134:135], v[134:135]
	s_nop 0
	v_pk_fma_f32 v[138:139], v[138:139], s[92:93], 1.0 op_sel_hi:[1,0,0]
	s_nop 0
	v_pk_mul_f32 v[138:139], v[134:135], v[138:139]
	s_nop 0
	v_pk_mul_f32 v[138:139], v[138:139], s[48:49] op_sel_hi:[1,0]
	s_nop 0
	v_pk_mul_f32 v[138:139], v[138:139], s[94:95] op_sel_hi:[1,0]
	s_nop 0
	v_exp_f32_e32 v138, v138
	v_exp_f32_e32 v139, v139
	s_nop 0
	v_pk_add_f32 v[138:139], v[138:139], 1.0 op_sel_hi:[1,0]
	s_nop 0
	v_rcp_f32_e32 v138, v138
	v_rcp_f32_e32 v139, v139
	s_nop 0
	v_pk_mul_f32 v[134:135], v[134:135], v[138:139]
	v_pk_mul_f32 v[138:139], v[82:83], v[176:177] op_sel_hi:[1,0]
	v_cvt_pk_bf16_f32 v133, v134, v135
	v_pk_mul_f32 v[140:141], v[138:139], v[138:139]
	s_nop 0
	v_pk_fma_f32 v[140:141], v[140:141], s[92:93], 1.0 op_sel_hi:[1,0,0]
	s_nop 0
	v_pk_mul_f32 v[140:141], v[138:139], v[140:141]
	s_nop 0
	v_pk_mul_f32 v[140:141], v[140:141], s[48:49] op_sel_hi:[1,0]
	s_nop 0
	v_pk_mul_f32 v[140:141], v[140:141], s[94:95] op_sel_hi:[1,0]
	s_nop 0
	v_exp_f32_e32 v140, v140
	v_exp_f32_e32 v141, v141
	s_nop 0
	v_pk_add_f32 v[140:141], v[140:141], 1.0 op_sel_hi:[1,0]
	s_nop 0
	v_rcp_f32_e32 v140, v140
	v_rcp_f32_e32 v141, v141
	s_nop 0
	v_pk_mul_f32 v[138:139], v[138:139], v[140:141]
	v_pk_mul_f32 v[140:141], v[84:85], v[176:177] op_sel_hi:[1,0]
	v_cvt_pk_bf16_f32 v134, v138, v139
	v_pk_mul_f32 v[142:143], v[140:141], v[140:141]
	s_nop 0
	v_pk_fma_f32 v[142:143], v[142:143], s[92:93], 1.0 op_sel_hi:[1,0,0]
	s_nop 0
	v_pk_mul_f32 v[142:143], v[140:141], v[142:143]
	s_nop 0
	v_pk_mul_f32 v[142:143], v[142:143], s[48:49] op_sel_hi:[1,0]
	s_nop 0
	v_pk_mul_f32 v[142:143], v[142:143], s[94:95] op_sel_hi:[1,0]
	s_nop 0
	v_exp_f32_e32 v142, v142
	v_exp_f32_e32 v143, v143
	s_nop 0
	v_pk_add_f32 v[142:143], v[142:143], 1.0 op_sel_hi:[1,0]
	s_nop 0
	v_rcp_f32_e32 v142, v142
	v_rcp_f32_e32 v143, v143
	s_nop 0
	v_pk_mul_f32 v[140:141], v[140:141], v[142:143]
	s_nop 0
	v_cvt_pk_bf16_f32 v135, v140, v141
	global_store_dwordx4 v[146:147], v[132:135], off offset:-3840
	s_nop 0
	s_nop 0
	v_pk_mul_f32 v[132:133], v[110:111], v[172:173] op_sel_hi:[1,0]
	s_nop 0
	v_pk_mul_f32 v[134:135], v[132:133], v[132:133]
	s_nop 0
	v_pk_fma_f32 v[134:135], v[134:135], s[92:93], 1.0 op_sel_hi:[1,0,0]
	s_nop 0
	v_pk_mul_f32 v[134:135], v[132:133], v[134:135]
	s_nop 0
	v_pk_mul_f32 v[134:135], v[134:135], s[48:49] op_sel_hi:[1,0]
	s_nop 0
	v_pk_mul_f32 v[134:135], v[134:135], s[94:95] op_sel_hi:[1,0]
	s_nop 0
	v_exp_f32_e32 v134, v134
	v_exp_f32_e32 v135, v135
	s_nop 0
	v_pk_add_f32 v[134:135], v[134:135], 1.0 op_sel_hi:[1,0]
	s_nop 0
	v_rcp_f32_e32 v134, v134
	v_rcp_f32_e32 v135, v135
	s_nop 0
	v_pk_mul_f32 v[132:133], v[132:133], v[134:135]
	v_pk_mul_f32 v[134:135], v[112:113], v[172:173] op_sel_hi:[1,0]
	v_cvt_pk_bf16_f32 v132, v132, v133
	v_pk_mul_f32 v[138:139], v[134:135], v[134:135]
	s_nop 0
	v_pk_fma_f32 v[138:139], v[138:139], s[92:93], 1.0 op_sel_hi:[1,0,0]
	s_nop 0
	v_pk_mul_f32 v[138:139], v[134:135], v[138:139]
	s_nop 0
	v_pk_mul_f32 v[138:139], v[138:139], s[48:49] op_sel_hi:[1,0]
	s_nop 0
	v_pk_mul_f32 v[138:139], v[138:139], s[94:95] op_sel_hi:[1,0]
	s_nop 0
	v_exp_f32_e32 v138, v138
	v_exp_f32_e32 v139, v139
	s_nop 0
	v_pk_add_f32 v[138:139], v[138:139], 1.0 op_sel_hi:[1,0]
	s_nop 0
	v_rcp_f32_e32 v138, v138
	v_rcp_f32_e32 v139, v139
	s_nop 0
	v_pk_mul_f32 v[134:135], v[134:135], v[138:139]
	v_pk_mul_f32 v[138:139], v[106:107], v[172:173] op_sel_hi:[1,0]
	v_cvt_pk_bf16_f32 v133, v134, v135
	v_pk_mul_f32 v[140:141], v[138:139], v[138:139]
	s_nop 0
	v_pk_fma_f32 v[140:141], v[140:141], s[92:93], 1.0 op_sel_hi:[1,0,0]
	s_nop 0
	v_pk_mul_f32 v[140:141], v[138:139], v[140:141]
	s_nop 0
	v_pk_mul_f32 v[140:141], v[140:141], s[48:49] op_sel_hi:[1,0]
	s_nop 0
	v_pk_mul_f32 v[140:141], v[140:141], s[94:95] op_sel_hi:[1,0]
	s_nop 0
	v_exp_f32_e32 v140, v140
	v_exp_f32_e32 v141, v141
	s_nop 0
	v_pk_add_f32 v[140:141], v[140:141], 1.0 op_sel_hi:[1,0]
	s_nop 0
	v_rcp_f32_e32 v140, v140
	v_rcp_f32_e32 v141, v141
	s_nop 0
	v_pk_mul_f32 v[138:139], v[138:139], v[140:141]
	v_pk_mul_f32 v[140:141], v[108:109], v[172:173] op_sel_hi:[1,0]
	v_cvt_pk_bf16_f32 v134, v138, v139
	v_pk_mul_f32 v[142:143], v[140:141], v[140:141]
	s_nop 0
	v_pk_fma_f32 v[142:143], v[142:143], s[92:93], 1.0 op_sel_hi:[1,0,0]
	s_nop 0
	v_pk_mul_f32 v[142:143], v[140:141], v[142:143]
	s_nop 0
	v_pk_mul_f32 v[142:143], v[142:143], s[48:49] op_sel_hi:[1,0]
	s_nop 0
	v_pk_mul_f32 v[142:143], v[142:143], s[94:95] op_sel_hi:[1,0]
	s_nop 0
	v_exp_f32_e32 v142, v142
	v_exp_f32_e32 v143, v143
	s_nop 0
	v_pk_add_f32 v[142:143], v[142:143], 1.0 op_sel_hi:[1,0]
	s_nop 0
	v_rcp_f32_e32 v142, v142
	v_rcp_f32_e32 v143, v143
	s_nop 0
	v_pk_mul_f32 v[140:141], v[140:141], v[142:143]
	s_nop 0
	v_cvt_pk_bf16_f32 v135, v140, v141
	s_mov_b32 s98, 0x9000
	s_mov_b32 s99, 0x0
	v_lshl_add_u64 v[146:147], v[144:145], 0, s[98:99]
	global_store_dwordx4 v[146:147], v[132:135], off offset:-4096
	s_nop 1
	v_pk_mul_f32 v[132:133], v[78:79], v[172:173] op_sel_hi:[1,0]
	s_nop 0
	v_pk_mul_f32 v[134:135], v[132:133], v[132:133]
	s_nop 0
	v_pk_fma_f32 v[134:135], v[134:135], s[92:93], 1.0 op_sel_hi:[1,0,0]
	s_nop 0
	v_pk_mul_f32 v[134:135], v[132:133], v[134:135]
	s_nop 0
	v_pk_mul_f32 v[134:135], v[134:135], s[48:49] op_sel_hi:[1,0]
	s_nop 0
	v_pk_mul_f32 v[134:135], v[134:135], s[94:95] op_sel_hi:[1,0]
	s_nop 0
	v_exp_f32_e32 v134, v134
	v_exp_f32_e32 v135, v135
	s_nop 0
	v_pk_add_f32 v[134:135], v[134:135], 1.0 op_sel_hi:[1,0]
	s_nop 0
	v_rcp_f32_e32 v134, v134
	v_rcp_f32_e32 v135, v135
	s_nop 0
	v_pk_mul_f32 v[132:133], v[132:133], v[134:135]
	v_pk_mul_f32 v[134:135], v[80:81], v[172:173] op_sel_hi:[1,0]
	v_cvt_pk_bf16_f32 v132, v132, v133
	v_pk_mul_f32 v[138:139], v[134:135], v[134:135]
	s_nop 0
	v_pk_fma_f32 v[138:139], v[138:139], s[92:93], 1.0 op_sel_hi:[1,0,0]
	s_nop 0
	v_pk_mul_f32 v[138:139], v[134:135], v[138:139]
	s_nop 0
	v_pk_mul_f32 v[138:139], v[138:139], s[48:49] op_sel_hi:[1,0]
	s_nop 0
	v_pk_mul_f32 v[138:139], v[138:139], s[94:95] op_sel_hi:[1,0]
	s_nop 0
	v_exp_f32_e32 v138, v138
	v_exp_f32_e32 v139, v139
	s_nop 0
	v_pk_add_f32 v[138:139], v[138:139], 1.0 op_sel_hi:[1,0]
	s_nop 0
	v_rcp_f32_e32 v138, v138
	v_rcp_f32_e32 v139, v139
	s_nop 0
	v_pk_mul_f32 v[134:135], v[134:135], v[138:139]
	v_pk_mul_f32 v[138:139], v[74:75], v[172:173] op_sel_hi:[1,0]
	v_cvt_pk_bf16_f32 v133, v134, v135
	v_pk_mul_f32 v[140:141], v[138:139], v[138:139]
	s_nop 0
	v_pk_fma_f32 v[140:141], v[140:141], s[92:93], 1.0 op_sel_hi:[1,0,0]
	s_nop 0
	v_pk_mul_f32 v[140:141], v[138:139], v[140:141]
	s_nop 0
	v_pk_mul_f32 v[140:141], v[140:141], s[48:49] op_sel_hi:[1,0]
	s_nop 0
	v_pk_mul_f32 v[140:141], v[140:141], s[94:95] op_sel_hi:[1,0]
	s_nop 0
	v_exp_f32_e32 v140, v140
	v_exp_f32_e32 v141, v141
	s_nop 0
	v_pk_add_f32 v[140:141], v[140:141], 1.0 op_sel_hi:[1,0]
	s_nop 0
	v_rcp_f32_e32 v140, v140
	v_rcp_f32_e32 v141, v141
	s_nop 0
	v_pk_mul_f32 v[138:139], v[138:139], v[140:141]
	v_pk_mul_f32 v[140:141], v[76:77], v[172:173] op_sel_hi:[1,0]
	v_cvt_pk_bf16_f32 v134, v138, v139
	v_pk_mul_f32 v[142:143], v[140:141], v[140:141]
	s_nop 0
	v_pk_fma_f32 v[142:143], v[142:143], s[92:93], 1.0 op_sel_hi:[1,0,0]
	s_nop 0
	v_pk_mul_f32 v[142:143], v[140:141], v[142:143]
	s_nop 0
	v_pk_mul_f32 v[142:143], v[142:143], s[48:49] op_sel_hi:[1,0]
	s_nop 0
	v_pk_mul_f32 v[142:143], v[142:143], s[94:95] op_sel_hi:[1,0]
	s_nop 0
	v_exp_f32_e32 v142, v142
	v_exp_f32_e32 v143, v143
	s_nop 0
	v_pk_add_f32 v[142:143], v[142:143], 1.0 op_sel_hi:[1,0]
	s_nop 0
	v_rcp_f32_e32 v142, v142
	v_rcp_f32_e32 v143, v143
	s_nop 0
	v_pk_mul_f32 v[140:141], v[140:141], v[142:143]
	s_nop 0
	v_cvt_pk_bf16_f32 v135, v140, v141
	global_store_dwordx4 v[146:147], v[132:135], off offset:-3840
	s_nop 0
	s_nop 0
	v_pk_mul_f32 v[132:133], v[102:103], v[168:169] op_sel_hi:[1,0]
	s_nop 0
	v_pk_mul_f32 v[134:135], v[132:133], v[132:133]
	s_nop 0
	v_pk_fma_f32 v[134:135], v[134:135], s[92:93], 1.0 op_sel_hi:[1,0,0]
	s_nop 0
	v_pk_mul_f32 v[134:135], v[132:133], v[134:135]
	s_nop 0
	v_pk_mul_f32 v[134:135], v[134:135], s[48:49] op_sel_hi:[1,0]
	s_nop 0
	v_pk_mul_f32 v[134:135], v[134:135], s[94:95] op_sel_hi:[1,0]
	s_nop 0
	v_exp_f32_e32 v134, v134
	v_exp_f32_e32 v135, v135
	s_nop 0
	v_pk_add_f32 v[134:135], v[134:135], 1.0 op_sel_hi:[1,0]
	s_nop 0
	v_rcp_f32_e32 v134, v134
	v_rcp_f32_e32 v135, v135
	s_nop 0
	v_pk_mul_f32 v[132:133], v[132:133], v[134:135]
	v_pk_mul_f32 v[134:135], v[104:105], v[168:169] op_sel_hi:[1,0]
	v_cvt_pk_bf16_f32 v132, v132, v133
	v_pk_mul_f32 v[138:139], v[134:135], v[134:135]
	s_nop 0
	v_pk_fma_f32 v[138:139], v[138:139], s[92:93], 1.0 op_sel_hi:[1,0,0]
	s_nop 0
	v_pk_mul_f32 v[138:139], v[134:135], v[138:139]
	s_nop 0
	v_pk_mul_f32 v[138:139], v[138:139], s[48:49] op_sel_hi:[1,0]
	s_nop 0
	v_pk_mul_f32 v[138:139], v[138:139], s[94:95] op_sel_hi:[1,0]
	s_nop 0
	v_exp_f32_e32 v138, v138
	v_exp_f32_e32 v139, v139
	s_nop 0
	v_pk_add_f32 v[138:139], v[138:139], 1.0 op_sel_hi:[1,0]
	s_nop 0
	v_rcp_f32_e32 v138, v138
	v_rcp_f32_e32 v139, v139
	s_nop 0
	v_pk_mul_f32 v[134:135], v[134:135], v[138:139]
	v_pk_mul_f32 v[138:139], v[98:99], v[168:169] op_sel_hi:[1,0]
	v_cvt_pk_bf16_f32 v133, v134, v135
	v_pk_mul_f32 v[140:141], v[138:139], v[138:139]
	s_nop 0
	v_pk_fma_f32 v[140:141], v[140:141], s[92:93], 1.0 op_sel_hi:[1,0,0]
	s_nop 0
	v_pk_mul_f32 v[140:141], v[138:139], v[140:141]
	s_nop 0
	v_pk_mul_f32 v[140:141], v[140:141], s[48:49] op_sel_hi:[1,0]
	s_nop 0
	v_pk_mul_f32 v[140:141], v[140:141], s[94:95] op_sel_hi:[1,0]
	s_nop 0
	v_exp_f32_e32 v140, v140
	v_exp_f32_e32 v141, v141
	s_nop 0
	v_pk_add_f32 v[140:141], v[140:141], 1.0 op_sel_hi:[1,0]
	s_nop 0
	v_rcp_f32_e32 v140, v140
	v_rcp_f32_e32 v141, v141
	s_nop 0
	v_pk_mul_f32 v[138:139], v[138:139], v[140:141]
	v_pk_mul_f32 v[140:141], v[100:101], v[168:169] op_sel_hi:[1,0]
	v_cvt_pk_bf16_f32 v134, v138, v139
	v_pk_mul_f32 v[142:143], v[140:141], v[140:141]
	s_nop 0
	v_pk_fma_f32 v[142:143], v[142:143], s[92:93], 1.0 op_sel_hi:[1,0,0]
	s_nop 0
	v_pk_mul_f32 v[142:143], v[140:141], v[142:143]
	s_nop 0
	v_pk_mul_f32 v[142:143], v[142:143], s[48:49] op_sel_hi:[1,0]
	s_nop 0
	v_pk_mul_f32 v[142:143], v[142:143], s[94:95] op_sel_hi:[1,0]
	s_nop 0
	v_exp_f32_e32 v142, v142
	v_exp_f32_e32 v143, v143
	s_nop 0
	v_pk_add_f32 v[142:143], v[142:143], 1.0 op_sel_hi:[1,0]
	s_nop 0
	v_rcp_f32_e32 v142, v142
	v_rcp_f32_e32 v143, v143
	s_nop 0
	v_pk_mul_f32 v[140:141], v[140:141], v[142:143]
	s_nop 0
	v_cvt_pk_bf16_f32 v135, v140, v141
	s_mov_b32 s98, 0xd000
	s_mov_b32 s99, 0x0
	v_lshl_add_u64 v[146:147], v[144:145], 0, s[98:99]
	global_store_dwordx4 v[146:147], v[132:135], off offset:-4096
	s_nop 1
	v_pk_mul_f32 v[132:133], v[70:71], v[168:169] op_sel_hi:[1,0]
	s_nop 0
	v_pk_mul_f32 v[134:135], v[132:133], v[132:133]
	s_nop 0
	v_pk_fma_f32 v[134:135], v[134:135], s[92:93], 1.0 op_sel_hi:[1,0,0]
	s_nop 0
	v_pk_mul_f32 v[134:135], v[132:133], v[134:135]
	s_nop 0
	v_pk_mul_f32 v[134:135], v[134:135], s[48:49] op_sel_hi:[1,0]
	s_nop 0
	v_pk_mul_f32 v[134:135], v[134:135], s[94:95] op_sel_hi:[1,0]
	s_nop 0
	v_exp_f32_e32 v134, v134
	v_exp_f32_e32 v135, v135
	s_nop 0
	v_pk_add_f32 v[134:135], v[134:135], 1.0 op_sel_hi:[1,0]
	s_nop 0
	v_rcp_f32_e32 v134, v134
	v_rcp_f32_e32 v135, v135
	s_nop 0
	v_pk_mul_f32 v[132:133], v[132:133], v[134:135]
	v_pk_mul_f32 v[134:135], v[72:73], v[168:169] op_sel_hi:[1,0]
	v_cvt_pk_bf16_f32 v132, v132, v133
	v_pk_mul_f32 v[138:139], v[134:135], v[134:135]
	s_nop 0
	v_pk_fma_f32 v[138:139], v[138:139], s[92:93], 1.0 op_sel_hi:[1,0,0]
	s_nop 0
	v_pk_mul_f32 v[138:139], v[134:135], v[138:139]
	s_nop 0
	v_pk_mul_f32 v[138:139], v[138:139], s[48:49] op_sel_hi:[1,0]
	s_nop 0
	v_pk_mul_f32 v[138:139], v[138:139], s[94:95] op_sel_hi:[1,0]
	s_nop 0
	v_exp_f32_e32 v138, v138
	v_exp_f32_e32 v139, v139
	s_nop 0
	v_pk_add_f32 v[138:139], v[138:139], 1.0 op_sel_hi:[1,0]
	s_nop 0
	v_rcp_f32_e32 v138, v138
	v_rcp_f32_e32 v139, v139
	s_nop 0
	v_pk_mul_f32 v[134:135], v[134:135], v[138:139]
	v_pk_mul_f32 v[138:139], v[66:67], v[168:169] op_sel_hi:[1,0]
	v_cvt_pk_bf16_f32 v133, v134, v135
	v_pk_mul_f32 v[140:141], v[138:139], v[138:139]
	s_nop 0
	v_pk_fma_f32 v[140:141], v[140:141], s[92:93], 1.0 op_sel_hi:[1,0,0]
	s_nop 0
	v_pk_mul_f32 v[140:141], v[138:139], v[140:141]
	s_nop 0
	v_pk_mul_f32 v[140:141], v[140:141], s[48:49] op_sel_hi:[1,0]
	s_nop 0
	v_pk_mul_f32 v[140:141], v[140:141], s[94:95] op_sel_hi:[1,0]
	s_nop 0
	v_exp_f32_e32 v140, v140
	v_exp_f32_e32 v141, v141
	s_nop 0
	v_pk_add_f32 v[140:141], v[140:141], 1.0 op_sel_hi:[1,0]
	s_nop 0
	v_rcp_f32_e32 v140, v140
	v_rcp_f32_e32 v141, v141
	s_nop 0
	v_pk_mul_f32 v[138:139], v[138:139], v[140:141]
	v_pk_mul_f32 v[140:141], v[68:69], v[168:169] op_sel_hi:[1,0]
	v_cvt_pk_bf16_f32 v134, v138, v139
	v_pk_mul_f32 v[142:143], v[140:141], v[140:141]
	s_nop 0
	v_pk_fma_f32 v[142:143], v[142:143], s[92:93], 1.0 op_sel_hi:[1,0,0]
	s_nop 0
	v_pk_mul_f32 v[142:143], v[140:141], v[142:143]
	s_nop 0
	v_pk_mul_f32 v[142:143], v[142:143], s[48:49] op_sel_hi:[1,0]
	s_nop 0
	v_pk_mul_f32 v[142:143], v[142:143], s[94:95] op_sel_hi:[1,0]
	s_nop 0
	v_exp_f32_e32 v142, v142
	v_exp_f32_e32 v143, v143
	s_nop 0
	v_pk_add_f32 v[142:143], v[142:143], 1.0 op_sel_hi:[1,0]
	s_nop 0
	v_rcp_f32_e32 v142, v142
	v_rcp_f32_e32 v143, v143
	s_nop 0
	v_pk_mul_f32 v[140:141], v[140:141], v[142:143]
	s_nop 0
	v_cvt_pk_bf16_f32 v135, v140, v141
	global_store_dwordx4 v[146:147], v[132:135], off offset:-3840
	s_nop 0
	s_nop 0
	v_pk_mul_f32 v[132:133], v[62:63], v[164:165] op_sel_hi:[1,0]
	s_nop 0
	v_pk_mul_f32 v[134:135], v[132:133], v[132:133]
	s_nop 0
	v_pk_fma_f32 v[134:135], v[134:135], s[92:93], 1.0 op_sel_hi:[1,0,0]
	s_nop 0
	v_pk_mul_f32 v[134:135], v[132:133], v[134:135]
	s_nop 0
	v_pk_mul_f32 v[134:135], v[134:135], s[48:49] op_sel_hi:[1,0]
	s_nop 0
	v_pk_mul_f32 v[134:135], v[134:135], s[94:95] op_sel_hi:[1,0]
	s_nop 0
	v_exp_f32_e32 v134, v134
	v_exp_f32_e32 v135, v135
	s_nop 0
	v_pk_add_f32 v[134:135], v[134:135], 1.0 op_sel_hi:[1,0]
	s_nop 0
	v_rcp_f32_e32 v134, v134
	v_rcp_f32_e32 v135, v135
	s_nop 0
	v_pk_mul_f32 v[132:133], v[132:133], v[134:135]
	v_pk_mul_f32 v[134:135], v[64:65], v[164:165] op_sel_hi:[1,0]
	v_cvt_pk_bf16_f32 v132, v132, v133
	v_pk_mul_f32 v[138:139], v[134:135], v[134:135]
	s_nop 0
	v_pk_fma_f32 v[138:139], v[138:139], s[92:93], 1.0 op_sel_hi:[1,0,0]
	s_nop 0
	v_pk_mul_f32 v[138:139], v[134:135], v[138:139]
	s_nop 0
	v_pk_mul_f32 v[138:139], v[138:139], s[48:49] op_sel_hi:[1,0]
	s_nop 0
	v_pk_mul_f32 v[138:139], v[138:139], s[94:95] op_sel_hi:[1,0]
	s_nop 0
	v_exp_f32_e32 v138, v138
	v_exp_f32_e32 v139, v139
	s_nop 0
	v_pk_add_f32 v[138:139], v[138:139], 1.0 op_sel_hi:[1,0]
	s_nop 0
	v_rcp_f32_e32 v138, v138
	v_rcp_f32_e32 v139, v139
	s_nop 0
	v_pk_mul_f32 v[134:135], v[134:135], v[138:139]
	v_pk_mul_f32 v[138:139], v[58:59], v[164:165] op_sel_hi:[1,0]
	v_cvt_pk_bf16_f32 v133, v134, v135
	v_pk_mul_f32 v[140:141], v[138:139], v[138:139]
	s_nop 0
	v_pk_fma_f32 v[140:141], v[140:141], s[92:93], 1.0 op_sel_hi:[1,0,0]
	s_nop 0
	v_pk_mul_f32 v[140:141], v[138:139], v[140:141]
	s_nop 0
	v_pk_mul_f32 v[140:141], v[140:141], s[48:49] op_sel_hi:[1,0]
	s_nop 0
	v_pk_mul_f32 v[140:141], v[140:141], s[94:95] op_sel_hi:[1,0]
	s_nop 0
	v_exp_f32_e32 v140, v140
	v_exp_f32_e32 v141, v141
	s_nop 0
	v_pk_add_f32 v[140:141], v[140:141], 1.0 op_sel_hi:[1,0]
	s_nop 0
	v_rcp_f32_e32 v140, v140
	v_rcp_f32_e32 v141, v141
	s_nop 0
	v_pk_mul_f32 v[138:139], v[138:139], v[140:141]
	v_pk_mul_f32 v[140:141], v[60:61], v[164:165] op_sel_hi:[1,0]
	v_cvt_pk_bf16_f32 v134, v138, v139
	v_pk_mul_f32 v[142:143], v[140:141], v[140:141]
	s_nop 0
	v_pk_fma_f32 v[142:143], v[142:143], s[92:93], 1.0 op_sel_hi:[1,0,0]
	s_nop 0
	v_pk_mul_f32 v[142:143], v[140:141], v[142:143]
	s_nop 0
	v_pk_mul_f32 v[142:143], v[142:143], s[48:49] op_sel_hi:[1,0]
	s_nop 0
	v_pk_mul_f32 v[142:143], v[142:143], s[94:95] op_sel_hi:[1,0]
	s_nop 0
	v_exp_f32_e32 v142, v142
	v_exp_f32_e32 v143, v143
	s_nop 0
	v_pk_add_f32 v[142:143], v[142:143], 1.0 op_sel_hi:[1,0]
	s_nop 0
	v_rcp_f32_e32 v142, v142
	v_rcp_f32_e32 v143, v143
	s_nop 0
	v_pk_mul_f32 v[140:141], v[140:141], v[142:143]
	s_nop 0
	v_cvt_pk_bf16_f32 v135, v140, v141
	s_mov_b32 s98, 0x21000
	s_mov_b32 s99, 0x0
	v_lshl_add_u64 v[146:147], v[144:145], 0, s[98:99]
	global_store_dwordx4 v[146:147], v[132:135], off offset:-4096
	s_nop 1
	v_pk_mul_f32 v[132:133], v[30:31], v[164:165] op_sel_hi:[1,0]
	s_nop 0
	v_pk_mul_f32 v[134:135], v[132:133], v[132:133]
	s_nop 0
	v_pk_fma_f32 v[134:135], v[134:135], s[92:93], 1.0 op_sel_hi:[1,0,0]
	s_nop 0
	v_pk_mul_f32 v[134:135], v[132:133], v[134:135]
	s_nop 0
	v_pk_mul_f32 v[134:135], v[134:135], s[48:49] op_sel_hi:[1,0]
	s_nop 0
	v_pk_mul_f32 v[134:135], v[134:135], s[94:95] op_sel_hi:[1,0]
	s_nop 0
	v_exp_f32_e32 v134, v134
	v_exp_f32_e32 v135, v135
	s_nop 0
	v_pk_add_f32 v[134:135], v[134:135], 1.0 op_sel_hi:[1,0]
	s_nop 0
	v_rcp_f32_e32 v134, v134
	v_rcp_f32_e32 v135, v135
	s_nop 0
	v_pk_mul_f32 v[132:133], v[132:133], v[134:135]
	v_pk_mul_f32 v[134:135], v[32:33], v[164:165] op_sel_hi:[1,0]
	v_cvt_pk_bf16_f32 v132, v132, v133
	v_pk_mul_f32 v[138:139], v[134:135], v[134:135]
	s_nop 0
	v_pk_fma_f32 v[138:139], v[138:139], s[92:93], 1.0 op_sel_hi:[1,0,0]
	s_nop 0
	v_pk_mul_f32 v[138:139], v[134:135], v[138:139]
	s_nop 0
	v_pk_mul_f32 v[138:139], v[138:139], s[48:49] op_sel_hi:[1,0]
	s_nop 0
	v_pk_mul_f32 v[138:139], v[138:139], s[94:95] op_sel_hi:[1,0]
	s_nop 0
	v_exp_f32_e32 v138, v138
	v_exp_f32_e32 v139, v139
	s_nop 0
	v_pk_add_f32 v[138:139], v[138:139], 1.0 op_sel_hi:[1,0]
	s_nop 0
	v_rcp_f32_e32 v138, v138
	v_rcp_f32_e32 v139, v139
	s_nop 0
	v_pk_mul_f32 v[134:135], v[134:135], v[138:139]
	v_pk_mul_f32 v[138:139], v[26:27], v[164:165] op_sel_hi:[1,0]
	v_cvt_pk_bf16_f32 v133, v134, v135
	v_pk_mul_f32 v[140:141], v[138:139], v[138:139]
	s_nop 0
	v_pk_fma_f32 v[140:141], v[140:141], s[92:93], 1.0 op_sel_hi:[1,0,0]
	s_nop 0
	v_pk_mul_f32 v[140:141], v[138:139], v[140:141]
	s_nop 0
	v_pk_mul_f32 v[140:141], v[140:141], s[48:49] op_sel_hi:[1,0]
	s_nop 0
	v_pk_mul_f32 v[140:141], v[140:141], s[94:95] op_sel_hi:[1,0]
	s_nop 0
	v_exp_f32_e32 v140, v140
	v_exp_f32_e32 v141, v141
	s_nop 0
	v_pk_add_f32 v[140:141], v[140:141], 1.0 op_sel_hi:[1,0]
	s_nop 0
	v_rcp_f32_e32 v140, v140
	v_rcp_f32_e32 v141, v141
	s_nop 0
	v_pk_mul_f32 v[138:139], v[138:139], v[140:141]
	v_pk_mul_f32 v[140:141], v[28:29], v[164:165] op_sel_hi:[1,0]
	v_cvt_pk_bf16_f32 v134, v138, v139
	v_pk_mul_f32 v[142:143], v[140:141], v[140:141]
	s_nop 0
	v_pk_fma_f32 v[142:143], v[142:143], s[92:93], 1.0 op_sel_hi:[1,0,0]
	s_nop 0
	v_pk_mul_f32 v[142:143], v[140:141], v[142:143]
	s_nop 0
	v_pk_mul_f32 v[142:143], v[142:143], s[48:49] op_sel_hi:[1,0]
	s_nop 0
	v_pk_mul_f32 v[142:143], v[142:143], s[94:95] op_sel_hi:[1,0]
	s_nop 0
	v_exp_f32_e32 v142, v142
	v_exp_f32_e32 v143, v143
	s_nop 0
	v_pk_add_f32 v[142:143], v[142:143], 1.0 op_sel_hi:[1,0]
	s_nop 0
	v_rcp_f32_e32 v142, v142
	v_rcp_f32_e32 v143, v143
	s_nop 0
	v_pk_mul_f32 v[140:141], v[140:141], v[142:143]
	s_nop 0
	v_cvt_pk_bf16_f32 v135, v140, v141
	global_store_dwordx4 v[146:147], v[132:135], off offset:-3840
	s_nop 0
	s_nop 0
	v_pk_mul_f32 v[132:133], v[54:55], v[160:161] op_sel_hi:[1,0]
	s_nop 0
	v_pk_mul_f32 v[134:135], v[132:133], v[132:133]
	s_nop 0
	v_pk_fma_f32 v[134:135], v[134:135], s[92:93], 1.0 op_sel_hi:[1,0,0]
	s_nop 0
	v_pk_mul_f32 v[134:135], v[132:133], v[134:135]
	s_nop 0
	v_pk_mul_f32 v[134:135], v[134:135], s[48:49] op_sel_hi:[1,0]
	s_nop 0
	v_pk_mul_f32 v[134:135], v[134:135], s[94:95] op_sel_hi:[1,0]
	s_nop 0
	v_exp_f32_e32 v134, v134
	v_exp_f32_e32 v135, v135
	s_nop 0
	v_pk_add_f32 v[134:135], v[134:135], 1.0 op_sel_hi:[1,0]
	s_nop 0
	v_rcp_f32_e32 v134, v134
	v_rcp_f32_e32 v135, v135
	s_nop 0
	v_pk_mul_f32 v[132:133], v[132:133], v[134:135]
	v_pk_mul_f32 v[134:135], v[56:57], v[160:161] op_sel_hi:[1,0]
	v_cvt_pk_bf16_f32 v132, v132, v133
	v_pk_mul_f32 v[138:139], v[134:135], v[134:135]
	s_nop 0
	v_pk_fma_f32 v[138:139], v[138:139], s[92:93], 1.0 op_sel_hi:[1,0,0]
	s_nop 0
	v_pk_mul_f32 v[138:139], v[134:135], v[138:139]
	s_nop 0
	v_pk_mul_f32 v[138:139], v[138:139], s[48:49] op_sel_hi:[1,0]
	s_nop 0
	v_pk_mul_f32 v[138:139], v[138:139], s[94:95] op_sel_hi:[1,0]
	s_nop 0
	v_exp_f32_e32 v138, v138
	v_exp_f32_e32 v139, v139
	s_nop 0
	v_pk_add_f32 v[138:139], v[138:139], 1.0 op_sel_hi:[1,0]
	s_nop 0
	v_rcp_f32_e32 v138, v138
	v_rcp_f32_e32 v139, v139
	s_nop 0
	v_pk_mul_f32 v[134:135], v[134:135], v[138:139]
	v_pk_mul_f32 v[138:139], v[50:51], v[160:161] op_sel_hi:[1,0]
	v_cvt_pk_bf16_f32 v133, v134, v135
	v_pk_mul_f32 v[140:141], v[138:139], v[138:139]
	s_nop 0
	v_pk_fma_f32 v[140:141], v[140:141], s[92:93], 1.0 op_sel_hi:[1,0,0]
	s_nop 0
	v_pk_mul_f32 v[140:141], v[138:139], v[140:141]
	s_nop 0
	v_pk_mul_f32 v[140:141], v[140:141], s[48:49] op_sel_hi:[1,0]
	s_nop 0
	v_pk_mul_f32 v[140:141], v[140:141], s[94:95] op_sel_hi:[1,0]
	s_nop 0
	v_exp_f32_e32 v140, v140
	v_exp_f32_e32 v141, v141
	s_nop 0
	v_pk_add_f32 v[140:141], v[140:141], 1.0 op_sel_hi:[1,0]
	s_nop 0
	v_rcp_f32_e32 v140, v140
	v_rcp_f32_e32 v141, v141
	s_nop 0
	v_pk_mul_f32 v[138:139], v[138:139], v[140:141]
	v_pk_mul_f32 v[140:141], v[52:53], v[160:161] op_sel_hi:[1,0]
	v_cvt_pk_bf16_f32 v134, v138, v139
	v_pk_mul_f32 v[142:143], v[140:141], v[140:141]
	s_nop 0
	v_pk_fma_f32 v[142:143], v[142:143], s[92:93], 1.0 op_sel_hi:[1,0,0]
	s_nop 0
	v_pk_mul_f32 v[142:143], v[140:141], v[142:143]
	s_nop 0
	v_pk_mul_f32 v[142:143], v[142:143], s[48:49] op_sel_hi:[1,0]
	s_nop 0
	v_pk_mul_f32 v[142:143], v[142:143], s[94:95] op_sel_hi:[1,0]
	s_nop 0
	v_exp_f32_e32 v142, v142
	v_exp_f32_e32 v143, v143
	s_nop 0
	v_pk_add_f32 v[142:143], v[142:143], 1.0 op_sel_hi:[1,0]
	s_nop 0
	v_rcp_f32_e32 v142, v142
	v_rcp_f32_e32 v143, v143
	s_nop 0
	v_pk_mul_f32 v[140:141], v[140:141], v[142:143]
	s_nop 0
	v_cvt_pk_bf16_f32 v135, v140, v141
	s_mov_b32 s98, 0x25000
	s_mov_b32 s99, 0x0
	v_lshl_add_u64 v[146:147], v[144:145], 0, s[98:99]
	global_store_dwordx4 v[146:147], v[132:135], off offset:-4096
	s_nop 1
	v_pk_mul_f32 v[132:133], v[22:23], v[160:161] op_sel_hi:[1,0]
	s_nop 0
	v_pk_mul_f32 v[134:135], v[132:133], v[132:133]
	s_nop 0
	v_pk_fma_f32 v[134:135], v[134:135], s[92:93], 1.0 op_sel_hi:[1,0,0]
	s_nop 0
	v_pk_mul_f32 v[134:135], v[132:133], v[134:135]
	s_nop 0
	v_pk_mul_f32 v[134:135], v[134:135], s[48:49] op_sel_hi:[1,0]
	s_nop 0
	v_pk_mul_f32 v[134:135], v[134:135], s[94:95] op_sel_hi:[1,0]
	s_nop 0
	v_exp_f32_e32 v134, v134
	v_exp_f32_e32 v135, v135
	s_nop 0
	v_pk_add_f32 v[134:135], v[134:135], 1.0 op_sel_hi:[1,0]
	s_nop 0
	v_rcp_f32_e32 v134, v134
	v_rcp_f32_e32 v135, v135
	s_nop 0
	v_pk_mul_f32 v[132:133], v[132:133], v[134:135]
	v_pk_mul_f32 v[134:135], v[24:25], v[160:161] op_sel_hi:[1,0]
	v_cvt_pk_bf16_f32 v132, v132, v133
	v_pk_mul_f32 v[138:139], v[134:135], v[134:135]
	s_nop 0
	v_pk_fma_f32 v[138:139], v[138:139], s[92:93], 1.0 op_sel_hi:[1,0,0]
	s_nop 0
	v_pk_mul_f32 v[138:139], v[134:135], v[138:139]
	s_nop 0
	v_pk_mul_f32 v[138:139], v[138:139], s[48:49] op_sel_hi:[1,0]
	s_nop 0
	v_pk_mul_f32 v[138:139], v[138:139], s[94:95] op_sel_hi:[1,0]
	s_nop 0
	v_exp_f32_e32 v138, v138
	v_exp_f32_e32 v139, v139
	s_nop 0
	v_pk_add_f32 v[138:139], v[138:139], 1.0 op_sel_hi:[1,0]
	s_nop 0
	v_rcp_f32_e32 v138, v138
	v_rcp_f32_e32 v139, v139
	s_nop 0
	v_pk_mul_f32 v[134:135], v[134:135], v[138:139]
	v_pk_mul_f32 v[138:139], v[18:19], v[160:161] op_sel_hi:[1,0]
	v_cvt_pk_bf16_f32 v133, v134, v135
	v_pk_mul_f32 v[140:141], v[138:139], v[138:139]
	s_nop 0
	v_pk_fma_f32 v[140:141], v[140:141], s[92:93], 1.0 op_sel_hi:[1,0,0]
	s_nop 0
	v_pk_mul_f32 v[140:141], v[138:139], v[140:141]
	s_nop 0
	v_pk_mul_f32 v[140:141], v[140:141], s[48:49] op_sel_hi:[1,0]
	s_nop 0
	v_pk_mul_f32 v[140:141], v[140:141], s[94:95] op_sel_hi:[1,0]
	s_nop 0
	v_exp_f32_e32 v140, v140
	v_exp_f32_e32 v141, v141
	s_nop 0
	v_pk_add_f32 v[140:141], v[140:141], 1.0 op_sel_hi:[1,0]
	s_nop 0
	v_rcp_f32_e32 v140, v140
	v_rcp_f32_e32 v141, v141
	s_nop 0
	v_pk_mul_f32 v[138:139], v[138:139], v[140:141]
	v_pk_mul_f32 v[140:141], v[20:21], v[160:161] op_sel_hi:[1,0]
	v_cvt_pk_bf16_f32 v134, v138, v139
	v_pk_mul_f32 v[142:143], v[140:141], v[140:141]
	s_nop 0
	v_pk_fma_f32 v[142:143], v[142:143], s[92:93], 1.0 op_sel_hi:[1,0,0]
	s_nop 0
	v_pk_mul_f32 v[142:143], v[140:141], v[142:143]
	s_nop 0
	v_pk_mul_f32 v[142:143], v[142:143], s[48:49] op_sel_hi:[1,0]
	s_nop 0
	v_pk_mul_f32 v[142:143], v[142:143], s[94:95] op_sel_hi:[1,0]
	s_nop 0
	v_exp_f32_e32 v142, v142
	v_exp_f32_e32 v143, v143
	s_nop 0
	v_pk_add_f32 v[142:143], v[142:143], 1.0 op_sel_hi:[1,0]
	s_nop 0
	v_rcp_f32_e32 v142, v142
	v_rcp_f32_e32 v143, v143
	s_nop 0
	v_pk_mul_f32 v[140:141], v[140:141], v[142:143]
	s_nop 0
	v_cvt_pk_bf16_f32 v135, v140, v141
	global_store_dwordx4 v[146:147], v[132:135], off offset:-3840
	s_nop 0
	s_nop 0
	v_pk_mul_f32 v[132:133], v[46:47], v[156:157] op_sel_hi:[1,0]
	s_nop 0
	v_pk_mul_f32 v[134:135], v[132:133], v[132:133]
	s_nop 0
	v_pk_fma_f32 v[134:135], v[134:135], s[92:93], 1.0 op_sel_hi:[1,0,0]
	s_nop 0
	v_pk_mul_f32 v[134:135], v[132:133], v[134:135]
	s_nop 0
	v_pk_mul_f32 v[134:135], v[134:135], s[48:49] op_sel_hi:[1,0]
	s_nop 0
	v_pk_mul_f32 v[134:135], v[134:135], s[94:95] op_sel_hi:[1,0]
	s_nop 0
	v_exp_f32_e32 v134, v134
	v_exp_f32_e32 v135, v135
	s_nop 0
	v_pk_add_f32 v[134:135], v[134:135], 1.0 op_sel_hi:[1,0]
	s_nop 0
	v_rcp_f32_e32 v134, v134
	v_rcp_f32_e32 v135, v135
	s_nop 0
	v_pk_mul_f32 v[132:133], v[132:133], v[134:135]
	v_pk_mul_f32 v[134:135], v[48:49], v[156:157] op_sel_hi:[1,0]
	v_cvt_pk_bf16_f32 v132, v132, v133
	v_pk_mul_f32 v[138:139], v[134:135], v[134:135]
	s_nop 0
	v_pk_fma_f32 v[138:139], v[138:139], s[92:93], 1.0 op_sel_hi:[1,0,0]
	s_nop 0
	v_pk_mul_f32 v[138:139], v[134:135], v[138:139]
	s_nop 0
	v_pk_mul_f32 v[138:139], v[138:139], s[48:49] op_sel_hi:[1,0]
	s_nop 0
	v_pk_mul_f32 v[138:139], v[138:139], s[94:95] op_sel_hi:[1,0]
	s_nop 0
	v_exp_f32_e32 v138, v138
	v_exp_f32_e32 v139, v139
	s_nop 0
	v_pk_add_f32 v[138:139], v[138:139], 1.0 op_sel_hi:[1,0]
	s_nop 0
	v_rcp_f32_e32 v138, v138
	v_rcp_f32_e32 v139, v139
	s_nop 0
	v_pk_mul_f32 v[134:135], v[134:135], v[138:139]
	v_pk_mul_f32 v[138:139], v[42:43], v[156:157] op_sel_hi:[1,0]
	v_cvt_pk_bf16_f32 v133, v134, v135
	v_pk_mul_f32 v[140:141], v[138:139], v[138:139]
	s_nop 0
	v_pk_fma_f32 v[140:141], v[140:141], s[92:93], 1.0 op_sel_hi:[1,0,0]
	s_nop 0
	v_pk_mul_f32 v[140:141], v[138:139], v[140:141]
	s_nop 0
	v_pk_mul_f32 v[140:141], v[140:141], s[48:49] op_sel_hi:[1,0]
	s_nop 0
	v_pk_mul_f32 v[140:141], v[140:141], s[94:95] op_sel_hi:[1,0]
	s_nop 0
	v_exp_f32_e32 v140, v140
	v_exp_f32_e32 v141, v141
	s_nop 0
	v_pk_add_f32 v[140:141], v[140:141], 1.0 op_sel_hi:[1,0]
	s_nop 0
	v_rcp_f32_e32 v140, v140
	v_rcp_f32_e32 v141, v141
	s_nop 0
	v_pk_mul_f32 v[138:139], v[138:139], v[140:141]
	v_pk_mul_f32 v[140:141], v[44:45], v[156:157] op_sel_hi:[1,0]
	v_cvt_pk_bf16_f32 v134, v138, v139
	v_pk_mul_f32 v[142:143], v[140:141], v[140:141]
	s_nop 0
	v_pk_fma_f32 v[142:143], v[142:143], s[92:93], 1.0 op_sel_hi:[1,0,0]
	s_nop 0
	v_pk_mul_f32 v[142:143], v[140:141], v[142:143]
	s_nop 0
	v_pk_mul_f32 v[142:143], v[142:143], s[48:49] op_sel_hi:[1,0]
	s_nop 0
	v_pk_mul_f32 v[142:143], v[142:143], s[94:95] op_sel_hi:[1,0]
	s_nop 0
	v_exp_f32_e32 v142, v142
	v_exp_f32_e32 v143, v143
	s_nop 0
	v_pk_add_f32 v[142:143], v[142:143], 1.0 op_sel_hi:[1,0]
	s_nop 0
	v_rcp_f32_e32 v142, v142
	v_rcp_f32_e32 v143, v143
	s_nop 0
	v_pk_mul_f32 v[140:141], v[140:141], v[142:143]
	s_nop 0
	v_cvt_pk_bf16_f32 v135, v140, v141
	s_mov_b32 s98, 0x29000
	s_mov_b32 s99, 0x0
	v_lshl_add_u64 v[146:147], v[144:145], 0, s[98:99]
	global_store_dwordx4 v[146:147], v[132:135], off offset:-4096
	s_nop 1
	v_pk_mul_f32 v[132:133], v[14:15], v[156:157] op_sel_hi:[1,0]
	s_nop 0
	v_pk_mul_f32 v[134:135], v[132:133], v[132:133]
	s_nop 0
	v_pk_fma_f32 v[134:135], v[134:135], s[92:93], 1.0 op_sel_hi:[1,0,0]
	s_nop 0
	v_pk_mul_f32 v[134:135], v[132:133], v[134:135]
	s_nop 0
	v_pk_mul_f32 v[134:135], v[134:135], s[48:49] op_sel_hi:[1,0]
	s_nop 0
	v_pk_mul_f32 v[134:135], v[134:135], s[94:95] op_sel_hi:[1,0]
	s_nop 0
	v_exp_f32_e32 v134, v134
	v_exp_f32_e32 v135, v135
	s_nop 0
	v_pk_add_f32 v[134:135], v[134:135], 1.0 op_sel_hi:[1,0]
	s_nop 0
	v_rcp_f32_e32 v134, v134
	v_rcp_f32_e32 v135, v135
	s_nop 0
	v_pk_mul_f32 v[132:133], v[132:133], v[134:135]
	v_pk_mul_f32 v[134:135], v[16:17], v[156:157] op_sel_hi:[1,0]
	v_cvt_pk_bf16_f32 v132, v132, v133
	v_pk_mul_f32 v[138:139], v[134:135], v[134:135]
	s_nop 0
	v_pk_fma_f32 v[138:139], v[138:139], s[92:93], 1.0 op_sel_hi:[1,0,0]
	s_nop 0
	v_pk_mul_f32 v[138:139], v[134:135], v[138:139]
	s_nop 0
	v_pk_mul_f32 v[138:139], v[138:139], s[48:49] op_sel_hi:[1,0]
	s_nop 0
	v_pk_mul_f32 v[138:139], v[138:139], s[94:95] op_sel_hi:[1,0]
	s_nop 0
	v_exp_f32_e32 v138, v138
	v_exp_f32_e32 v139, v139
	s_nop 0
	v_pk_add_f32 v[138:139], v[138:139], 1.0 op_sel_hi:[1,0]
	s_nop 0
	v_rcp_f32_e32 v138, v138
	v_rcp_f32_e32 v139, v139
	s_nop 0
	v_pk_mul_f32 v[134:135], v[134:135], v[138:139]
	v_pk_mul_f32 v[138:139], v[10:11], v[156:157] op_sel_hi:[1,0]
	v_cvt_pk_bf16_f32 v133, v134, v135
	v_pk_mul_f32 v[140:141], v[138:139], v[138:139]
	s_nop 0
	v_pk_fma_f32 v[140:141], v[140:141], s[92:93], 1.0 op_sel_hi:[1,0,0]
	s_nop 0
	v_pk_mul_f32 v[140:141], v[138:139], v[140:141]
	s_nop 0
	v_pk_mul_f32 v[140:141], v[140:141], s[48:49] op_sel_hi:[1,0]
	s_nop 0
	v_pk_mul_f32 v[140:141], v[140:141], s[94:95] op_sel_hi:[1,0]
	s_nop 0
	v_exp_f32_e32 v140, v140
	v_exp_f32_e32 v141, v141
	s_nop 0
	v_pk_add_f32 v[140:141], v[140:141], 1.0 op_sel_hi:[1,0]
	s_nop 0
	v_rcp_f32_e32 v140, v140
	v_rcp_f32_e32 v141, v141
	s_nop 0
	v_pk_mul_f32 v[138:139], v[138:139], v[140:141]
	v_pk_mul_f32 v[140:141], v[12:13], v[156:157] op_sel_hi:[1,0]
	v_cvt_pk_bf16_f32 v134, v138, v139
	v_pk_mul_f32 v[142:143], v[140:141], v[140:141]
	s_nop 0
	v_pk_fma_f32 v[142:143], v[142:143], s[92:93], 1.0 op_sel_hi:[1,0,0]
	s_nop 0
	v_pk_mul_f32 v[142:143], v[140:141], v[142:143]
	s_nop 0
	v_pk_mul_f32 v[142:143], v[142:143], s[48:49] op_sel_hi:[1,0]
	s_nop 0
	v_pk_mul_f32 v[142:143], v[142:143], s[94:95] op_sel_hi:[1,0]
	s_nop 0
	v_exp_f32_e32 v142, v142
	v_exp_f32_e32 v143, v143
	s_nop 0
	v_pk_add_f32 v[142:143], v[142:143], 1.0 op_sel_hi:[1,0]
	s_nop 0
	v_rcp_f32_e32 v142, v142
	v_rcp_f32_e32 v143, v143
	s_nop 0
	v_pk_mul_f32 v[140:141], v[140:141], v[142:143]
	s_nop 0
	v_cvt_pk_bf16_f32 v135, v140, v141
	global_store_dwordx4 v[146:147], v[132:135], off offset:-3840
	s_nop 0
	s_nop 0
	v_pk_mul_f32 v[132:133], v[38:39], v[152:153] op_sel_hi:[1,0]
	s_nop 0
	v_pk_mul_f32 v[134:135], v[132:133], v[132:133]
	v_pk_mul_f32 v[130:131], v[6:7], v[152:153] op_sel_hi:[1,0]
	v_pk_fma_f32 v[134:135], v[134:135], s[92:93], 1.0 op_sel_hi:[1,0,0]
	s_nop 0
	v_pk_mul_f32 v[134:135], v[132:133], v[134:135]
	s_nop 0
	v_pk_mul_f32 v[134:135], v[134:135], s[48:49] op_sel_hi:[1,0]
	s_nop 0
	v_pk_mul_f32 v[134:135], v[134:135], s[94:95] op_sel_hi:[1,0]
	s_nop 0
	v_exp_f32_e32 v134, v134
	v_exp_f32_e32 v135, v135
	s_nop 0
	v_pk_add_f32 v[134:135], v[134:135], 1.0 op_sel_hi:[1,0]
	s_nop 0
	v_rcp_f32_e32 v134, v134
	v_rcp_f32_e32 v135, v135
	s_nop 0
	v_pk_mul_f32 v[132:133], v[132:133], v[134:135]
	v_pk_mul_f32 v[134:135], v[40:41], v[152:153] op_sel_hi:[1,0]
	v_cvt_pk_bf16_f32 v132, v132, v133
	v_pk_mul_f32 v[138:139], v[134:135], v[134:135]
	s_nop 0
	v_pk_fma_f32 v[138:139], v[138:139], s[92:93], 1.0 op_sel_hi:[1,0,0]
	s_nop 0
	v_pk_mul_f32 v[138:139], v[134:135], v[138:139]
	s_nop 0
	v_pk_mul_f32 v[138:139], v[138:139], s[48:49] op_sel_hi:[1,0]
	s_nop 0
	v_pk_mul_f32 v[138:139], v[138:139], s[94:95] op_sel_hi:[1,0]
	s_nop 0
	v_exp_f32_e32 v138, v138
	v_exp_f32_e32 v139, v139
	s_nop 0
	v_pk_add_f32 v[138:139], v[138:139], 1.0 op_sel_hi:[1,0]
	s_nop 0
	v_rcp_f32_e32 v138, v138
	v_rcp_f32_e32 v139, v139
	s_nop 0
	v_pk_mul_f32 v[134:135], v[134:135], v[138:139]
	v_pk_mul_f32 v[138:139], v[34:35], v[152:153] op_sel_hi:[1,0]
	v_cvt_pk_bf16_f32 v133, v134, v135
	v_pk_mul_f32 v[140:141], v[138:139], v[138:139]
	s_nop 0
	v_pk_fma_f32 v[140:141], v[140:141], s[92:93], 1.0 op_sel_hi:[1,0,0]
	s_nop 0
	v_pk_mul_f32 v[140:141], v[138:139], v[140:141]
	s_nop 0
	v_pk_mul_f32 v[140:141], v[140:141], s[48:49] op_sel_hi:[1,0]
	s_nop 0
	v_pk_mul_f32 v[140:141], v[140:141], s[94:95] op_sel_hi:[1,0]
	s_nop 0
	v_exp_f32_e32 v140, v140
	v_exp_f32_e32 v141, v141
	s_nop 0
	v_pk_add_f32 v[140:141], v[140:141], 1.0 op_sel_hi:[1,0]
	s_nop 0
	v_rcp_f32_e32 v140, v140
	v_rcp_f32_e32 v141, v141
	s_nop 0
	v_pk_mul_f32 v[138:139], v[138:139], v[140:141]
	v_pk_mul_f32 v[140:141], v[36:37], v[152:153] op_sel_hi:[1,0]
	v_cvt_pk_bf16_f32 v134, v138, v139
	v_pk_mul_f32 v[142:143], v[140:141], v[140:141]
	s_nop 0
	v_pk_fma_f32 v[142:143], v[142:143], s[92:93], 1.0 op_sel_hi:[1,0,0]
	s_nop 0
	v_pk_mul_f32 v[142:143], v[140:141], v[142:143]
	s_nop 0
	v_pk_mul_f32 v[142:143], v[142:143], s[48:49] op_sel_hi:[1,0]
	s_nop 0
	v_pk_mul_f32 v[142:143], v[142:143], s[94:95] op_sel_hi:[1,0]
	s_nop 0
	v_exp_f32_e32 v142, v142
	v_exp_f32_e32 v143, v143
	s_nop 0
	v_pk_add_f32 v[142:143], v[142:143], 1.0 op_sel_hi:[1,0]
	s_nop 0
	v_rcp_f32_e32 v142, v142
	v_rcp_f32_e32 v143, v143
	s_nop 0
	v_pk_mul_f32 v[140:141], v[140:141], v[142:143]
	s_nop 0
	v_cvt_pk_bf16_f32 v135, v140, v141
	s_mov_b32 s98, 0x2d000
	s_mov_b32 s99, 0x0
	v_lshl_add_u64 v[146:147], v[144:145], 0, s[98:99]
	global_store_dwordx4 v[146:147], v[132:135], off offset:-4096
	s_nop 1
	v_pk_mul_f32 v[132:133], v[130:131], v[130:131]
	s_nop 0
	v_pk_fma_f32 v[132:133], v[132:133], s[92:93], 1.0 op_sel_hi:[1,0,0]
	s_nop 0
	v_pk_mul_f32 v[132:133], v[130:131], v[132:133]
	s_nop 0
	v_pk_mul_f32 v[132:133], v[132:133], s[48:49] op_sel_hi:[1,0]
	s_nop 0
	v_pk_mul_f32 v[132:133], v[132:133], s[94:95] op_sel_hi:[1,0]
	s_nop 0
	v_exp_f32_e32 v132, v132
	v_exp_f32_e32 v133, v133
	s_nop 0
	v_pk_add_f32 v[132:133], v[132:133], 1.0 op_sel_hi:[1,0]
	s_nop 0
	v_rcp_f32_e32 v132, v132
	v_rcp_f32_e32 v133, v133
	s_nop 0
	v_pk_mul_f32 v[130:131], v[130:131], v[132:133]
	v_pk_mul_f32 v[132:133], v[8:9], v[152:153] op_sel_hi:[1,0]
	v_cvt_pk_bf16_f32 v130, v130, v131
	v_pk_mul_f32 v[134:135], v[132:133], v[132:133]
	s_nop 0
	v_pk_fma_f32 v[134:135], v[134:135], s[92:93], 1.0 op_sel_hi:[1,0,0]
	s_nop 0
	v_pk_mul_f32 v[134:135], v[132:133], v[134:135]
	s_nop 0
	v_pk_mul_f32 v[134:135], v[134:135], s[48:49] op_sel_hi:[1,0]
	s_nop 0
	v_pk_mul_f32 v[134:135], v[134:135], s[94:95] op_sel_hi:[1,0]
	s_nop 0
	v_exp_f32_e32 v134, v134
	v_exp_f32_e32 v135, v135
	s_nop 0
	v_pk_add_f32 v[134:135], v[134:135], 1.0 op_sel_hi:[1,0]
	s_nop 0
	v_rcp_f32_e32 v134, v134
	v_rcp_f32_e32 v135, v135
	s_nop 0
	v_pk_mul_f32 v[132:133], v[132:133], v[134:135]
	v_pk_mul_f32 v[134:135], v[2:3], v[152:153] op_sel_hi:[1,0]
	v_cvt_pk_bf16_f32 v131, v132, v133
	v_pk_mul_f32 v[138:139], v[134:135], v[134:135]
	s_nop 0
	v_pk_fma_f32 v[138:139], v[138:139], s[92:93], 1.0 op_sel_hi:[1,0,0]
	s_nop 0
	v_pk_mul_f32 v[138:139], v[134:135], v[138:139]
	s_nop 0
	v_pk_mul_f32 v[138:139], v[138:139], s[48:49] op_sel_hi:[1,0]
	s_nop 0
	v_pk_mul_f32 v[138:139], v[138:139], s[94:95] op_sel_hi:[1,0]
	s_nop 0
	v_exp_f32_e32 v138, v138
	v_exp_f32_e32 v139, v139
	s_nop 0
	v_pk_add_f32 v[138:139], v[138:139], 1.0 op_sel_hi:[1,0]
	s_nop 0
	v_rcp_f32_e32 v138, v138
	v_rcp_f32_e32 v139, v139
	s_nop 0
	v_pk_mul_f32 v[134:135], v[134:135], v[138:139]
	v_pk_mul_f32 v[138:139], v[4:5], v[152:153] op_sel_hi:[1,0]
	v_cvt_pk_bf16_f32 v132, v134, v135
	v_pk_mul_f32 v[140:141], v[138:139], v[138:139]
	s_nop 0
	v_pk_fma_f32 v[140:141], v[140:141], s[92:93], 1.0 op_sel_hi:[1,0,0]
	s_nop 0
	v_pk_mul_f32 v[140:141], v[138:139], v[140:141]
	s_nop 0
	v_pk_mul_f32 v[140:141], v[140:141], s[48:49] op_sel_hi:[1,0]
	s_nop 0
	v_pk_mul_f32 v[140:141], v[140:141], s[94:95] op_sel_hi:[1,0]
	s_nop 0
	v_exp_f32_e32 v140, v140
	v_exp_f32_e32 v141, v141
	s_nop 0
	v_pk_add_f32 v[140:141], v[140:141], 1.0 op_sel_hi:[1,0]
	s_nop 0
	v_rcp_f32_e32 v140, v140
	v_rcp_f32_e32 v141, v141
	s_nop 0
	v_pk_mul_f32 v[138:139], v[138:139], v[140:141]
	s_nop 0
	v_cvt_pk_bf16_f32 v133, v138, v139
	global_store_dwordx4 v[146:147], v[130:133], off offset:-3840

.LBB0_1065:
	s_xor_b64 s[54:55], s[48:49], -1
	s_add_u32 s94, s0, 0x20000
	s_addc_u32 s96, s1, 0
	s_ashr_i32 s53, s52, 31
	s_lshl_b64 s[56:57], s[52:53], 19
	s_add_u32 s56, s34, s56
	s_addc_u32 s57, s35, s57
	s_and_b64 s[58:59], s[48:49], exec
	s_cselect_b32 s33, s57, s13
	s_cselect_b32 s53, s56, s12
	s_ashr_i32 s51, s50, 31
	s_lshl_b64 s[58:59], s[50:51], 19
	ds_read_b128 v[2:5], v214
	ds_read_b128 v[6:9], v214 offset:1024
	ds_read_b128 v[10:13], v214 offset:2048
	ds_read_b128 v[14:17], v214 offset:3072
	ds_read_b128 v[18:21], v215
	ds_read_b128 v[22:25], v215 offset:1024
	ds_read_b128 v[26:29], v215 offset:2048
	ds_read_b128 v[30:33], v215 offset:3072
	s_add_u32 s58, s41, s58
	s_addc_u32 s59, s43, s59
	s_and_b64 s[62:63], s[48:49], exec
	s_cselect_b32 s51, s59, s1
	s_cselect_b32 s95, s58, s0
	s_add_u32 s66, s12, 0x10000
	s_addc_u32 s67, s13, 0
	s_add_u32 s88, s0, 0x10000
	s_addc_u32 s89, s1, 0
	s_add_u32 s62, s12, 0x18000
	s_addc_u32 s63, s13, 0
	s_add_u32 s64, s0, 0x18000
	s_addc_u32 s65, s1, 0
	ds_read_b128 v[34:37], v216
	ds_read_b128 v[38:41], v216 offset:1024
	ds_read_b128 v[42:45], v216 offset:2048
	ds_read_b128 v[46:49], v216 offset:3072
	ds_read_b128 v[50:53], v216 offset:4096
	ds_read_b128 v[54:57], v216 offset:5120
	ds_read_b128 v[58:61], v216 offset:6144
	ds_read_b128 v[62:65], v216 offset:7168
	s_add_u32 s90, s12, 0xc000
	s_addc_u32 s91, s13, 0
	s_mov_b32 m0, s79
	s_nop 0
	global_load_lds_dwordx4 v195, s[90:91]
	s_add_u32 m0, s79, 0x2000
	s_nop 0
	global_load_lds_dwordx4 v212, s[90:91]
	s_waitcnt vmcnt(8)
	s_waitcnt lgkmcnt(0)
	s_barrier
	s_setprio 1
	s_waitcnt lgkmcnt(1)
	v_mfma_f32_16x16x32_bf16 v[90:93], v[2:5], v[58:61], 0
	v_mfma_f32_16x16x32_bf16 v[66:69], v[2:5], v[34:37], 0
	v_mfma_f32_16x16x32_bf16 v[70:73], v[10:13], v[34:37], 0
	v_mfma_f32_16x16x32_bf16 v[74:77], v[2:5], v[42:45], 0
	v_mfma_f32_16x16x32_bf16 v[78:81], v[10:13], v[42:45], 0
	v_mfma_f32_16x16x32_bf16 v[82:85], v[2:5], v[50:53], 0
	v_mfma_f32_16x16x32_bf16 v[86:89], v[10:13], v[50:53], 0
	s_waitcnt lgkmcnt(0)
	v_mfma_f32_16x16x32_bf16 v[98:101], v[6:9], v[62:65], v[90:93]
	v_mfma_f32_16x16x32_bf16 v[90:93], v[10:13], v[58:61], 0
	v_mfma_f32_16x16x32_bf16 v[66:69], v[6:9], v[38:41], v[66:69]
	v_mfma_f32_16x16x32_bf16 v[70:73], v[14:17], v[38:41], v[70:73]
	v_mfma_f32_16x16x32_bf16 v[74:77], v[6:9], v[46:49], v[74:77]
	v_mfma_f32_16x16x32_bf16 v[78:81], v[14:17], v[46:49], v[78:81]
	v_mfma_f32_16x16x32_bf16 v[82:85], v[6:9], v[54:57], v[82:85]
	v_mfma_f32_16x16x32_bf16 v[86:89], v[14:17], v[54:57], v[86:89]
	v_mfma_f32_16x16x32_bf16 v[102:105], v[14:17], v[62:65], v[90:93]
	s_setprio 0
	s_setprio 1
	v_mfma_f32_16x16x32_bf16 v[90:93], v[18:21], v[34:37], 0
	v_mfma_f32_16x16x32_bf16 v[34:37], v[26:29], v[34:37], 0
	v_mfma_f32_16x16x32_bf16 v[114:117], v[22:25], v[38:41], v[90:93]
	v_mfma_f32_16x16x32_bf16 v[34:37], v[30:33], v[38:41], v[34:37]
	v_mfma_f32_16x16x32_bf16 v[38:41], v[18:21], v[42:45], 0
	v_mfma_f32_16x16x32_bf16 v[42:45], v[26:29], v[42:45], 0
	v_mfma_f32_16x16x32_bf16 v[38:41], v[22:25], v[46:49], v[38:41]
	v_mfma_f32_16x16x32_bf16 v[42:45], v[30:33], v[46:49], v[42:45]
	v_mfma_f32_16x16x32_bf16 v[46:49], v[18:21], v[50:53], 0
	v_mfma_f32_16x16x32_bf16 v[50:53], v[26:29], v[50:53], 0
	v_mfma_f32_16x16x32_bf16 v[46:49], v[22:25], v[54:57], v[46:49]
	v_mfma_f32_16x16x32_bf16 v[50:53], v[30:33], v[54:57], v[50:53]
	v_mfma_f32_16x16x32_bf16 v[54:57], v[18:21], v[58:61], 0
	v_mfma_f32_16x16x32_bf16 v[58:61], v[26:29], v[58:61], 0
	v_mfma_f32_16x16x32_bf16 v[54:57], v[22:25], v[62:65], v[54:57]
	v_mfma_f32_16x16x32_bf16 v[58:61], v[30:33], v[62:65], v[58:61]
	s_setprio 0
	s_barrier
	ds_read_b128 v[62:65], v216 offset:16384
	ds_read_b128 v[90:93], v216 offset:17408
	ds_read_b128 v[94:97], v216 offset:18432
	ds_read_b128 v[106:109], v216 offset:19456
	ds_read_b128 v[110:113], v216 offset:20480
	ds_read_b128 v[118:121], v216 offset:21504
	ds_read_b128 v[122:125], v216 offset:22528
	ds_read_b128 v[126:129], v216 offset:23552
	s_mov_b32 m0, s3
	s_nop 0
	global_load_lds_dwordx4 v195, s[88:89]
	s_add_u32 m0, s3, 0x2000
	s_nop 0
	global_load_lds_dwordx4 v212, s[88:89]
	s_add_u32 s88, s0, 0x14000
	s_addc_u32 s89, s1, 0
	s_mov_b32 m0, s71
	s_nop 0
	global_load_lds_dwordx4 v195, s[88:89]
	s_add_u32 m0, s71, 0x2000
	s_nop 0
	global_load_lds_dwordx4 v212, s[88:89]
	s_nop 0
	s_mov_b32 m0, s70
	s_nop 0
	global_load_lds_dwordx4 v195, s[66:67]
	s_add_u32 m0, s70, 0x2000
	s_nop 0
	global_load_lds_dwordx4 v212, s[66:67]
	s_waitcnt vmcnt(8)
	s_waitcnt lgkmcnt(0)
	s_barrier
	s_setprio 1
	s_waitcnt lgkmcnt(7)
	v_mfma_f32_16x16x32_bf16 v[130:133], v[2:5], v[62:65], 0
	s_waitcnt lgkmcnt(5)
	v_mfma_f32_16x16x32_bf16 v[138:141], v[2:5], v[94:97], 0
	s_waitcnt lgkmcnt(3)
	v_mfma_f32_16x16x32_bf16 v[146:149], v[2:5], v[110:113], 0
	s_waitcnt lgkmcnt(1)
	v_mfma_f32_16x16x32_bf16 v[2:5], v[2:5], v[122:125], 0
	v_mfma_f32_16x16x32_bf16 v[130:133], v[6:9], v[90:93], v[130:133]
	v_mfma_f32_16x16x32_bf16 v[138:141], v[6:9], v[106:109], v[138:141]
	v_mfma_f32_16x16x32_bf16 v[146:149], v[6:9], v[118:121], v[146:149]
	s_waitcnt lgkmcnt(0)
	v_mfma_f32_16x16x32_bf16 v[2:5], v[6:9], v[126:129], v[2:5]
	v_mfma_f32_16x16x32_bf16 v[6:9], v[10:13], v[122:125], 0
	v_mfma_f32_16x16x32_bf16 v[134:137], v[10:13], v[62:65], 0
	v_mfma_f32_16x16x32_bf16 v[142:145], v[10:13], v[94:97], 0
	v_mfma_f32_16x16x32_bf16 v[154:157], v[10:13], v[110:113], 0
	v_mfma_f32_16x16x32_bf16 v[6:9], v[14:17], v[126:129], v[6:9]
	v_mfma_f32_16x16x32_bf16 v[134:137], v[14:17], v[90:93], v[134:137]
	v_mfma_f32_16x16x32_bf16 v[142:145], v[14:17], v[106:109], v[142:145]
	v_mfma_f32_16x16x32_bf16 v[154:157], v[14:17], v[118:121], v[154:157]
	s_setprio 0
	s_setprio 1
	v_mfma_f32_16x16x32_bf16 v[10:13], v[18:21], v[62:65], 0
	v_mfma_f32_16x16x32_bf16 v[158:161], v[22:25], v[90:93], v[10:13]
	v_mfma_f32_16x16x32_bf16 v[10:13], v[26:29], v[62:65], 0
	v_mfma_f32_16x16x32_bf16 v[162:165], v[30:33], v[90:93], v[10:13]
	v_mfma_f32_16x16x32_bf16 v[10:13], v[18:21], v[94:97], 0
	v_mfma_f32_16x16x32_bf16 v[166:169], v[22:25], v[106:109], v[10:13]
	v_mfma_f32_16x16x32_bf16 v[10:13], v[26:29], v[94:97], 0
	v_mfma_f32_16x16x32_bf16 v[170:173], v[30:33], v[106:109], v[10:13]
	v_mfma_f32_16x16x32_bf16 v[10:13], v[18:21], v[110:113], 0
	v_mfma_f32_16x16x32_bf16 v[174:177], v[22:25], v[118:121], v[10:13]
	v_mfma_f32_16x16x32_bf16 v[10:13], v[26:29], v[110:113], 0
	v_mfma_f32_16x16x32_bf16 v[178:181], v[30:33], v[118:121], v[10:13]
	v_mfma_f32_16x16x32_bf16 v[10:13], v[18:21], v[122:125], 0
	v_mfma_f32_16x16x32_bf16 v[182:185], v[22:25], v[126:129], v[10:13]
	v_mfma_f32_16x16x32_bf16 v[10:13], v[26:29], v[122:125], 0
	v_mfma_f32_16x16x32_bf16 v[186:189], v[30:33], v[126:129], v[10:13]
	s_setprio 0
	s_barrier
	s_nop 4
	ds_read_b128 v[10:13], v217
	ds_read_b128 v[14:17], v217 offset:1024
	ds_read_b128 v[18:21], v217 offset:2048
	ds_read_b128 v[22:25], v217 offset:3072
	ds_read_b128 v[190:193], v218
	ds_read_b128 v[198:201], v218 offset:1024
	ds_read_b128 v[202:205], v218 offset:2048
	ds_read_b128 v[206:209], v218 offset:3072
	ds_read_b128 v[26:29], v216 offset:32768
	ds_read_b128 v[30:33], v216 offset:33792
	ds_read_b128 v[62:65], v216 offset:34816
	ds_read_b128 v[222:225], v216 offset:35840
	ds_read_b128 v[226:229], v216 offset:36864
	ds_read_b128 v[230:233], v216 offset:37888
	ds_read_b128 v[234:237], v216 offset:38912
	ds_read_b128 v[238:241], v216 offset:39936
	s_add_u32 s66, s12, 0x14000
	s_addc_u32 s67, s13, 0
	s_mov_b32 m0, s72
	s_nop 0
	global_load_lds_dwordx4 v195, s[66:67]
	s_add_u32 m0, s72, 0x2000
	s_nop 0
	global_load_lds_dwordx4 v212, s[66:67]
	s_waitcnt vmcnt(8)
	s_waitcnt lgkmcnt(0)
	s_barrier
	s_setprio 1
	s_waitcnt lgkmcnt(7)
	v_mfma_f32_16x16x32_bf16 v[66:69], v[10:13], v[26:29], v[66:69]
	s_waitcnt lgkmcnt(6)
	v_mfma_f32_16x16x32_bf16 v[126:129], v[14:17], v[30:33], v[66:69]
	v_mfma_f32_16x16x32_bf16 v[66:69], v[18:21], v[26:29], v[70:73]
	v_mfma_f32_16x16x32_bf16 v[122:125], v[22:25], v[30:33], v[66:69]
	s_waitcnt lgkmcnt(5)
	v_mfma_f32_16x16x32_bf16 v[66:69], v[10:13], v[62:65], v[74:77]
	s_waitcnt lgkmcnt(4)
	v_mfma_f32_16x16x32_bf16 v[110:113], v[14:17], v[222:225], v[66:69]
	v_mfma_f32_16x16x32_bf16 v[66:69], v[18:21], v[62:65], v[78:81]
	v_mfma_f32_16x16x32_bf16 v[106:109], v[22:25], v[222:225], v[66:69]
	s_waitcnt lgkmcnt(3)
	v_mfma_f32_16x16x32_bf16 v[66:69], v[10:13], v[226:229], v[82:85]
	s_waitcnt lgkmcnt(2)
	v_mfma_f32_16x16x32_bf16 v[94:97], v[14:17], v[230:233], v[66:69]
	v_mfma_f32_16x16x32_bf16 v[66:69], v[18:21], v[226:229], v[86:89]
	v_mfma_f32_16x16x32_bf16 v[90:93], v[22:25], v[230:233], v[66:69]
	s_waitcnt lgkmcnt(1)
	v_mfma_f32_16x16x32_bf16 v[66:69], v[10:13], v[234:237], v[98:101]
	s_waitcnt lgkmcnt(0)
	v_mfma_f32_16x16x32_bf16 v[78:81], v[14:17], v[238:241], v[66:69]
	v_mfma_f32_16x16x32_bf16 v[66:69], v[18:21], v[234:237], v[102:105]
	v_mfma_f32_16x16x32_bf16 v[74:77], v[22:25], v[238:241], v[66:69]
	s_setprio 0
	s_setprio 1
	v_mfma_f32_16x16x32_bf16 v[66:69], v[190:193], v[26:29], v[114:117]
	v_mfma_f32_16x16x32_bf16 v[26:29], v[202:205], v[26:29], v[34:37]
	v_mfma_f32_16x16x32_bf16 v[114:117], v[206:209], v[30:33], v[26:29]
	v_mfma_f32_16x16x32_bf16 v[26:29], v[190:193], v[62:65], v[38:41]
	v_mfma_f32_16x16x32_bf16 v[102:105], v[198:201], v[222:225], v[26:29]
	v_mfma_f32_16x16x32_bf16 v[26:29], v[202:205], v[62:65], v[42:45]
	v_mfma_f32_16x16x32_bf16 v[98:101], v[206:209], v[222:225], v[26:29]
	v_mfma_f32_16x16x32_bf16 v[26:29], v[190:193], v[226:229], v[46:49]
	v_mfma_f32_16x16x32_bf16 v[86:89], v[198:201], v[230:233], v[26:29]
	v_mfma_f32_16x16x32_bf16 v[26:29], v[202:205], v[226:229], v[50:53]
	v_mfma_f32_16x16x32_bf16 v[82:85], v[206:209], v[230:233], v[26:29]
	v_mfma_f32_16x16x32_bf16 v[26:29], v[190:193], v[234:237], v[54:57]
	v_mfma_f32_16x16x32_bf16 v[70:73], v[198:201], v[238:241], v[26:29]
	v_mfma_f32_16x16x32_bf16 v[26:29], v[202:205], v[234:237], v[58:61]
	v_mfma_f32_16x16x32_bf16 v[118:121], v[198:201], v[30:33], v[66:69]
	v_mfma_f32_16x16x32_bf16 v[66:69], v[206:209], v[238:241], v[26:29]
	s_setprio 0
	s_barrier
	ds_read_b128 v[34:37], v216 offset:49152
	ds_read_b128 v[38:41], v216 offset:50176
	ds_read_b128 v[222:225], v216 offset:51200
	ds_read_b128 v[226:229], v216 offset:52224
	ds_read_b128 v[230:233], v216 offset:53248
	ds_read_b128 v[234:237], v216 offset:54272
	ds_read_b128 v[238:241], v216 offset:55296
	ds_read_b128 v[242:245], v216 offset:56320
	s_mov_b32 m0, s76
	s_nop 0
	global_load_lds_dwordx4 v195, s[64:65]
	s_add_u32 m0, s76, 0x2000
	s_nop 0
	global_load_lds_dwordx4 v212, s[64:65]
	s_add_u32 s0, s0, 0x1c000
	s_addc_u32 s1, s1, 0
	s_mov_b32 m0, s78
	s_nop 0
	global_load_lds_dwordx4 v195, s[0:1]
	s_add_u32 m0, s78, 0x2000
	s_nop 0
	global_load_lds_dwordx4 v212, s[0:1]
	s_nop 0
	s_mov_b32 m0, s77
	s_nop 0
	global_load_lds_dwordx4 v195, s[62:63]
	s_add_u32 m0, s77, 0x2000
	s_nop 0
	global_load_lds_dwordx4 v212, s[62:63]
	s_waitcnt vmcnt(8)
	s_waitcnt lgkmcnt(0)
	s_barrier
	s_setprio 1
	s_waitcnt lgkmcnt(7)
	v_mfma_f32_16x16x32_bf16 v[26:29], v[10:13], v[34:37], v[130:133]
	s_waitcnt lgkmcnt(6)
	v_mfma_f32_16x16x32_bf16 v[62:65], v[14:17], v[38:41], v[26:29]
	v_mfma_f32_16x16x32_bf16 v[26:29], v[18:21], v[34:37], v[134:137]
	v_mfma_f32_16x16x32_bf16 v[58:61], v[22:25], v[38:41], v[26:29]
	s_waitcnt lgkmcnt(5)
	v_mfma_f32_16x16x32_bf16 v[26:29], v[10:13], v[222:225], v[138:141]
	s_waitcnt lgkmcnt(4)
	v_mfma_f32_16x16x32_bf16 v[46:49], v[14:17], v[226:229], v[26:29]
	v_mfma_f32_16x16x32_bf16 v[26:29], v[18:21], v[222:225], v[142:145]
	v_mfma_f32_16x16x32_bf16 v[42:45], v[22:25], v[226:229], v[26:29]
	s_waitcnt lgkmcnt(3)
	v_mfma_f32_16x16x32_bf16 v[26:29], v[10:13], v[230:233], v[146:149]
	s_waitcnt lgkmcnt(1)
	v_mfma_f32_16x16x32_bf16 v[2:5], v[10:13], v[238:241], v[2:5]
	v_mfma_f32_16x16x32_bf16 v[30:33], v[14:17], v[234:237], v[26:29]
	v_mfma_f32_16x16x32_bf16 v[26:29], v[18:21], v[230:233], v[154:157]
	s_waitcnt lgkmcnt(0)
	v_mfma_f32_16x16x32_bf16 v[14:17], v[14:17], v[242:245], v[2:5]
	v_mfma_f32_16x16x32_bf16 v[2:5], v[18:21], v[238:241], v[6:9]
	v_mfma_f32_16x16x32_bf16 v[26:29], v[22:25], v[234:237], v[26:29]
	v_mfma_f32_16x16x32_bf16 v[10:13], v[22:25], v[242:245], v[2:5]
	s_setprio 0
	s_setprio 1
	v_mfma_f32_16x16x32_bf16 v[2:5], v[190:193], v[34:37], v[158:161]
	v_mfma_f32_16x16x32_bf16 v[54:57], v[198:201], v[38:41], v[2:5]
	v_mfma_f32_16x16x32_bf16 v[2:5], v[202:205], v[34:37], v[162:165]
	v_mfma_f32_16x16x32_bf16 v[50:53], v[206:209], v[38:41], v[2:5]
	v_mfma_f32_16x16x32_bf16 v[2:5], v[190:193], v[222:225], v[166:169]
	v_mfma_f32_16x16x32_bf16 v[38:41], v[198:201], v[226:229], v[2:5]
	v_mfma_f32_16x16x32_bf16 v[2:5], v[202:205], v[222:225], v[170:173]
	v_mfma_f32_16x16x32_bf16 v[34:37], v[206:209], v[226:229], v[2:5]
	v_mfma_f32_16x16x32_bf16 v[2:5], v[190:193], v[230:233], v[174:177]
	v_mfma_f32_16x16x32_bf16 v[22:25], v[198:201], v[234:237], v[2:5]
	v_mfma_f32_16x16x32_bf16 v[2:5], v[202:205], v[230:233], v[178:181]
	v_mfma_f32_16x16x32_bf16 v[18:21], v[206:209], v[234:237], v[2:5]
	v_mfma_f32_16x16x32_bf16 v[2:5], v[190:193], v[238:241], v[182:185]
	v_mfma_f32_16x16x32_bf16 v[6:9], v[198:201], v[242:245], v[2:5]
	v_mfma_f32_16x16x32_bf16 v[2:5], v[202:205], v[238:241], v[186:189]
	v_mfma_f32_16x16x32_bf16 v[2:5], v[206:209], v[242:245], v[2:5]
	s_setprio 0
	s_barrier
	s_mov_b32 s97, 0
	s_mov_b64 s[0:1], 0
	v_mov_b32_e32 v131, s68

.LBB0_1068:
	s_or_b64 exec, exec, s[62:63]
	s_add_u32 s88, s12, s0
	ds_read_b128 v[132:135], v214
	ds_read_b128 v[136:139], v214 offset:1024
	ds_read_b128 v[140:143], v214 offset:2048
	ds_read_b128 v[144:147], v214 offset:3072
	ds_read_b128 v[154:157], v215
	ds_read_b128 v[158:161], v215 offset:1024
	ds_read_b128 v[162:165], v215 offset:2048
	ds_read_b128 v[166:169], v215 offset:3072
	s_addc_u32 s89, s13, s1
	s_add_u32 s62, s88, 0x20000
	s_addc_u32 s63, s89, 0
	s_add_u32 s64, s94, s0
	s_addc_u32 s65, s96, s1
	s_cmp_eq_u32 s0, 0x60000
	s_cselect_b32 s68, s53, s62
	s_cselect_b32 s69, s33, s63
	s_cselect_b32 s63, s51, s65
	s_cselect_b32 s62, s95, s64
	s_add_u32 s64, s68, 0x8000
	s_addc_u32 s65, s69, 0
	s_add_u32 s66, s62, 0x8000
	s_addc_u32 s67, s63, 0
	ds_read_b128 v[170:173], v216
	ds_read_b128 v[174:177], v216 offset:1024
	ds_read_b128 v[178:181], v216 offset:2048
	ds_read_b128 v[182:185], v216 offset:3072
	ds_read_b128 v[186:189], v216 offset:4096
	ds_read_b128 v[190:193], v216 offset:5120
	ds_read_b128 v[198:201], v216 offset:6144
	ds_read_b128 v[202:205], v216 offset:7168
	s_add_u32 s88, s88, 0x1c000
	s_addc_u32 s89, s89, 0
	s_mov_b32 m0, s79
	s_nop 0
	global_load_lds_dwordx4 v195, s[88:89]
	s_add_u32 m0, s79, 0x2000
	s_nop 0
	global_load_lds_dwordx4 v212, s[88:89]
	s_waitcnt vmcnt(8)
	s_waitcnt lgkmcnt(0)
	s_barrier
	s_setprio 1
	s_waitcnt lgkmcnt(7)
	v_mfma_f32_16x16x32_bf16 v[126:129], v[132:135], v[170:173], v[126:129]
	v_mfma_f32_16x16x32_bf16 v[122:125], v[140:143], v[170:173], v[122:125]
	s_waitcnt lgkmcnt(5)
	v_mfma_f32_16x16x32_bf16 v[110:113], v[132:135], v[178:181], v[110:113]
	v_mfma_f32_16x16x32_bf16 v[106:109], v[140:143], v[178:181], v[106:109]
	s_waitcnt lgkmcnt(3)
	v_mfma_f32_16x16x32_bf16 v[94:97], v[132:135], v[186:189], v[94:97]
	v_mfma_f32_16x16x32_bf16 v[90:93], v[140:143], v[186:189], v[90:93]
	s_waitcnt lgkmcnt(1)
	v_mfma_f32_16x16x32_bf16 v[78:81], v[132:135], v[198:201], v[78:81]
	v_mfma_f32_16x16x32_bf16 v[74:77], v[140:143], v[198:201], v[74:77]
	v_mfma_f32_16x16x32_bf16 v[126:129], v[136:139], v[174:177], v[126:129]
	v_mfma_f32_16x16x32_bf16 v[122:125], v[144:147], v[174:177], v[122:125]
	v_mfma_f32_16x16x32_bf16 v[110:113], v[136:139], v[182:185], v[110:113]
	v_mfma_f32_16x16x32_bf16 v[106:109], v[144:147], v[182:185], v[106:109]
	v_mfma_f32_16x16x32_bf16 v[94:97], v[136:139], v[190:193], v[94:97]
	v_mfma_f32_16x16x32_bf16 v[90:93], v[144:147], v[190:193], v[90:93]
	s_waitcnt lgkmcnt(0)
	v_mfma_f32_16x16x32_bf16 v[78:81], v[136:139], v[202:205], v[78:81]
	v_mfma_f32_16x16x32_bf16 v[74:77], v[144:147], v[202:205], v[74:77]
	s_setprio 0
	s_setprio 1
	v_mfma_f32_16x16x32_bf16 v[118:121], v[154:157], v[170:173], v[118:121]
	v_mfma_f32_16x16x32_bf16 v[114:117], v[162:165], v[170:173], v[114:117]
	v_mfma_f32_16x16x32_bf16 v[102:105], v[154:157], v[178:181], v[102:105]
	v_mfma_f32_16x16x32_bf16 v[98:101], v[162:165], v[178:181], v[98:101]
	v_mfma_f32_16x16x32_bf16 v[86:89], v[154:157], v[186:189], v[86:89]
	v_mfma_f32_16x16x32_bf16 v[82:85], v[162:165], v[186:189], v[82:85]
	v_mfma_f32_16x16x32_bf16 v[70:73], v[154:157], v[198:201], v[70:73]
	v_mfma_f32_16x16x32_bf16 v[66:69], v[162:165], v[198:201], v[66:69]
	v_mfma_f32_16x16x32_bf16 v[118:121], v[158:161], v[174:177], v[118:121]
	v_mfma_f32_16x16x32_bf16 v[114:117], v[166:169], v[174:177], v[114:117]
	v_mfma_f32_16x16x32_bf16 v[102:105], v[158:161], v[182:185], v[102:105]
	v_mfma_f32_16x16x32_bf16 v[98:101], v[166:169], v[182:185], v[98:101]
	v_mfma_f32_16x16x32_bf16 v[86:89], v[158:161], v[190:193], v[86:89]
	v_mfma_f32_16x16x32_bf16 v[82:85], v[166:169], v[190:193], v[82:85]
	v_mfma_f32_16x16x32_bf16 v[70:73], v[158:161], v[202:205], v[70:73]
	v_mfma_f32_16x16x32_bf16 v[66:69], v[166:169], v[202:205], v[66:69]
	s_setprio 0
	s_barrier
	ds_read_b128 v[170:173], v216 offset:16384
	ds_read_b128 v[174:177], v216 offset:17408
	ds_read_b128 v[178:181], v216 offset:18432
	ds_read_b128 v[182:185], v216 offset:19456
	ds_read_b128 v[186:189], v216 offset:20480
	ds_read_b128 v[190:193], v216 offset:21504
	ds_read_b128 v[198:201], v216 offset:22528
	ds_read_b128 v[202:205], v216 offset:23552
	s_mov_b32 m0, s3
	s_nop 0
	global_load_lds_dwordx4 v195, s[62:63]
	s_add_u32 m0, s3, 0x2000
	s_nop 0
	global_load_lds_dwordx4 v212, s[62:63]
	s_add_u32 s88, s62, 0x4000
	s_addc_u32 s89, s63, 0
	s_mov_b32 m0, s71
	s_nop 0
	global_load_lds_dwordx4 v195, s[88:89]
	s_add_u32 m0, s71, 0x2000
	s_nop 0
	global_load_lds_dwordx4 v212, s[88:89]
	s_nop 0
	s_mov_b32 m0, s70
	s_nop 0
	global_load_lds_dwordx4 v195, s[68:69]
	s_add_u32 m0, s70, 0x2000
	s_nop 0
	global_load_lds_dwordx4 v212, s[68:69]
	s_waitcnt vmcnt(8)
	s_waitcnt lgkmcnt(0)
	s_barrier
	s_setprio 1
	s_waitcnt lgkmcnt(7)
	v_mfma_f32_16x16x32_bf16 v[62:65], v[132:135], v[170:173], v[62:65]
	v_mfma_f32_16x16x32_bf16 v[58:61], v[140:143], v[170:173], v[58:61]
	s_waitcnt lgkmcnt(5)
	v_mfma_f32_16x16x32_bf16 v[46:49], v[132:135], v[178:181], v[46:49]
	v_mfma_f32_16x16x32_bf16 v[42:45], v[140:143], v[178:181], v[42:45]
	s_waitcnt lgkmcnt(3)
	v_mfma_f32_16x16x32_bf16 v[30:33], v[132:135], v[186:189], v[30:33]
	v_mfma_f32_16x16x32_bf16 v[26:29], v[140:143], v[186:189], v[26:29]
	s_waitcnt lgkmcnt(1)
	v_mfma_f32_16x16x32_bf16 v[14:17], v[132:135], v[198:201], v[14:17]
	v_mfma_f32_16x16x32_bf16 v[10:13], v[140:143], v[198:201], v[10:13]
	v_mfma_f32_16x16x32_bf16 v[62:65], v[136:139], v[174:177], v[62:65]
	v_mfma_f32_16x16x32_bf16 v[58:61], v[144:147], v[174:177], v[58:61]
	v_mfma_f32_16x16x32_bf16 v[46:49], v[136:139], v[182:185], v[46:49]
	v_mfma_f32_16x16x32_bf16 v[42:45], v[144:147], v[182:185], v[42:45]
	v_mfma_f32_16x16x32_bf16 v[30:33], v[136:139], v[190:193], v[30:33]
	v_mfma_f32_16x16x32_bf16 v[26:29], v[144:147], v[190:193], v[26:29]
	s_waitcnt lgkmcnt(0)
	v_mfma_f32_16x16x32_bf16 v[14:17], v[136:139], v[202:205], v[14:17]
	v_mfma_f32_16x16x32_bf16 v[10:13], v[144:147], v[202:205], v[10:13]
	s_setprio 0
	s_setprio 1
	v_mfma_f32_16x16x32_bf16 v[54:57], v[154:157], v[170:173], v[54:57]
	v_mfma_f32_16x16x32_bf16 v[50:53], v[162:165], v[170:173], v[50:53]
	v_mfma_f32_16x16x32_bf16 v[38:41], v[154:157], v[178:181], v[38:41]
	v_mfma_f32_16x16x32_bf16 v[34:37], v[162:165], v[178:181], v[34:37]
	v_mfma_f32_16x16x32_bf16 v[22:25], v[154:157], v[186:189], v[22:25]
	v_mfma_f32_16x16x32_bf16 v[18:21], v[162:165], v[186:189], v[18:21]
	v_mfma_f32_16x16x32_bf16 v[6:9], v[154:157], v[198:201], v[6:9]
	v_mfma_f32_16x16x32_bf16 v[2:5], v[162:165], v[198:201], v[2:5]
	v_mfma_f32_16x16x32_bf16 v[54:57], v[158:161], v[174:177], v[54:57]
	v_mfma_f32_16x16x32_bf16 v[50:53], v[166:169], v[174:177], v[50:53]
	v_mfma_f32_16x16x32_bf16 v[38:41], v[158:161], v[182:185], v[38:41]
	v_mfma_f32_16x16x32_bf16 v[34:37], v[166:169], v[182:185], v[34:37]
	v_mfma_f32_16x16x32_bf16 v[22:25], v[158:161], v[190:193], v[22:25]
	v_mfma_f32_16x16x32_bf16 v[18:21], v[166:169], v[190:193], v[18:21]
	v_mfma_f32_16x16x32_bf16 v[6:9], v[158:161], v[202:205], v[6:9]
	v_mfma_f32_16x16x32_bf16 v[2:5], v[166:169], v[202:205], v[2:5]
	s_setprio 0
	s_barrier
	ds_read_b128 v[132:135], v217
	ds_read_b128 v[136:139], v217 offset:1024
	ds_read_b128 v[140:143], v217 offset:2048
	ds_read_b128 v[144:147], v217 offset:3072
	ds_read_b128 v[154:157], v218
	ds_read_b128 v[158:161], v218 offset:1024
	ds_read_b128 v[162:165], v218 offset:2048
	ds_read_b128 v[166:169], v218 offset:3072
	ds_read_b128 v[170:173], v216 offset:32768
	ds_read_b128 v[174:177], v216 offset:33792
	ds_read_b128 v[178:181], v216 offset:34816
	ds_read_b128 v[182:185], v216 offset:35840
	ds_read_b128 v[186:189], v216 offset:36864
	ds_read_b128 v[190:193], v216 offset:37888
	ds_read_b128 v[198:201], v216 offset:38912
	ds_read_b128 v[202:205], v216 offset:39936
	s_add_u32 s68, s68, 0x4000
	s_addc_u32 s69, s69, 0
	s_mov_b32 m0, s72
	s_nop 0
	global_load_lds_dwordx4 v195, s[68:69]
	s_add_u32 m0, s72, 0x2000
	s_nop 0
	global_load_lds_dwordx4 v212, s[68:69]
	s_waitcnt vmcnt(8)
	s_waitcnt lgkmcnt(0)
	s_barrier
	s_setprio 1
	s_waitcnt lgkmcnt(7)
	v_mfma_f32_16x16x32_bf16 v[126:129], v[132:135], v[170:173], v[126:129]
	v_mfma_f32_16x16x32_bf16 v[122:125], v[140:143], v[170:173], v[122:125]
	s_waitcnt lgkmcnt(5)
	v_mfma_f32_16x16x32_bf16 v[110:113], v[132:135], v[178:181], v[110:113]
	v_mfma_f32_16x16x32_bf16 v[106:109], v[140:143], v[178:181], v[106:109]
	s_waitcnt lgkmcnt(3)
	v_mfma_f32_16x16x32_bf16 v[94:97], v[132:135], v[186:189], v[94:97]
	v_mfma_f32_16x16x32_bf16 v[90:93], v[140:143], v[186:189], v[90:93]
	s_waitcnt lgkmcnt(1)
	v_mfma_f32_16x16x32_bf16 v[78:81], v[132:135], v[198:201], v[78:81]
	v_mfma_f32_16x16x32_bf16 v[74:77], v[140:143], v[198:201], v[74:77]
	v_mfma_f32_16x16x32_bf16 v[126:129], v[136:139], v[174:177], v[126:129]
	v_mfma_f32_16x16x32_bf16 v[122:125], v[144:147], v[174:177], v[122:125]
	v_mfma_f32_16x16x32_bf16 v[110:113], v[136:139], v[182:185], v[110:113]
	v_mfma_f32_16x16x32_bf16 v[106:109], v[144:147], v[182:185], v[106:109]
	v_mfma_f32_16x16x32_bf16 v[94:97], v[136:139], v[190:193], v[94:97]
	v_mfma_f32_16x16x32_bf16 v[90:93], v[144:147], v[190:193], v[90:93]
	s_waitcnt lgkmcnt(0)
	v_mfma_f32_16x16x32_bf16 v[78:81], v[136:139], v[202:205], v[78:81]
	v_mfma_f32_16x16x32_bf16 v[74:77], v[144:147], v[202:205], v[74:77]
	s_setprio 0
	s_setprio 1
	v_mfma_f32_16x16x32_bf16 v[118:121], v[154:157], v[170:173], v[118:121]
	v_mfma_f32_16x16x32_bf16 v[114:117], v[162:165], v[170:173], v[114:117]
	v_mfma_f32_16x16x32_bf16 v[102:105], v[154:157], v[178:181], v[102:105]
	v_mfma_f32_16x16x32_bf16 v[98:101], v[162:165], v[178:181], v[98:101]
	v_mfma_f32_16x16x32_bf16 v[86:89], v[154:157], v[186:189], v[86:89]
	v_mfma_f32_16x16x32_bf16 v[82:85], v[162:165], v[186:189], v[82:85]
	v_mfma_f32_16x16x32_bf16 v[70:73], v[154:157], v[198:201], v[70:73]
	v_mfma_f32_16x16x32_bf16 v[66:69], v[162:165], v[198:201], v[66:69]
	v_mfma_f32_16x16x32_bf16 v[118:121], v[158:161], v[174:177], v[118:121]
	v_mfma_f32_16x16x32_bf16 v[114:117], v[166:169], v[174:177], v[114:117]
	v_mfma_f32_16x16x32_bf16 v[102:105], v[158:161], v[182:185], v[102:105]
	v_mfma_f32_16x16x32_bf16 v[98:101], v[166:169], v[182:185], v[98:101]
	v_mfma_f32_16x16x32_bf16 v[86:89], v[158:161], v[190:193], v[86:89]
	v_mfma_f32_16x16x32_bf16 v[82:85], v[166:169], v[190:193], v[82:85]
	v_mfma_f32_16x16x32_bf16 v[70:73], v[158:161], v[202:205], v[70:73]
	v_mfma_f32_16x16x32_bf16 v[66:69], v[166:169], v[202:205], v[66:69]
	s_setprio 0
	s_barrier
	ds_read_b128 v[170:173], v216 offset:49152
	ds_read_b128 v[174:177], v216 offset:50176
	ds_read_b128 v[178:181], v216 offset:51200
	ds_read_b128 v[182:185], v216 offset:52224
	ds_read_b128 v[186:189], v216 offset:53248
	ds_read_b128 v[190:193], v216 offset:54272
	ds_read_b128 v[198:201], v216 offset:55296
	ds_read_b128 v[202:205], v216 offset:56320
	s_mov_b32 m0, s76
	s_nop 0
	global_load_lds_dwordx4 v195, s[66:67]
	s_add_u32 m0, s76, 0x2000
	s_nop 0
	global_load_lds_dwordx4 v212, s[66:67]
	s_add_u32 s62, s62, 0xc000
	s_addc_u32 s63, s63, 0
	s_mov_b32 m0, s78
	s_nop 0
	global_load_lds_dwordx4 v195, s[62:63]
	s_add_u32 m0, s78, 0x2000
	s_nop 0
	global_load_lds_dwordx4 v212, s[62:63]
	s_nop 0
	s_mov_b32 m0, s77
	s_nop 0
	global_load_lds_dwordx4 v195, s[64:65]
	s_add_u32 m0, s77, 0x2000
	s_nop 0
	global_load_lds_dwordx4 v212, s[64:65]
	s_waitcnt vmcnt(8)
	s_waitcnt lgkmcnt(0)
	s_barrier
	s_setprio 1
	s_waitcnt lgkmcnt(7)
	v_mfma_f32_16x16x32_bf16 v[62:65], v[132:135], v[170:173], v[62:65]
	v_mfma_f32_16x16x32_bf16 v[58:61], v[140:143], v[170:173], v[58:61]
	s_waitcnt lgkmcnt(5)
	v_mfma_f32_16x16x32_bf16 v[46:49], v[132:135], v[178:181], v[46:49]
	v_mfma_f32_16x16x32_bf16 v[42:45], v[140:143], v[178:181], v[42:45]
	s_waitcnt lgkmcnt(3)
	v_mfma_f32_16x16x32_bf16 v[30:33], v[132:135], v[186:189], v[30:33]
	v_mfma_f32_16x16x32_bf16 v[26:29], v[140:143], v[186:189], v[26:29]
	s_waitcnt lgkmcnt(1)
	v_mfma_f32_16x16x32_bf16 v[14:17], v[132:135], v[198:201], v[14:17]
	v_mfma_f32_16x16x32_bf16 v[10:13], v[140:143], v[198:201], v[10:13]
	v_mfma_f32_16x16x32_bf16 v[62:65], v[136:139], v[174:177], v[62:65]
	v_mfma_f32_16x16x32_bf16 v[58:61], v[144:147], v[174:177], v[58:61]
	v_mfma_f32_16x16x32_bf16 v[46:49], v[136:139], v[182:185], v[46:49]
	v_mfma_f32_16x16x32_bf16 v[42:45], v[144:147], v[182:185], v[42:45]
	v_mfma_f32_16x16x32_bf16 v[30:33], v[136:139], v[190:193], v[30:33]
	v_mfma_f32_16x16x32_bf16 v[26:29], v[144:147], v[190:193], v[26:29]
	s_waitcnt lgkmcnt(0)
	v_mfma_f32_16x16x32_bf16 v[14:17], v[136:139], v[202:205], v[14:17]
	v_mfma_f32_16x16x32_bf16 v[10:13], v[144:147], v[202:205], v[10:13]
	s_setprio 0
	s_setprio 1
	v_mfma_f32_16x16x32_bf16 v[54:57], v[154:157], v[170:173], v[54:57]
	v_mfma_f32_16x16x32_bf16 v[50:53], v[162:165], v[170:173], v[50:53]
	v_mfma_f32_16x16x32_bf16 v[38:41], v[154:157], v[178:181], v[38:41]
	v_mfma_f32_16x16x32_bf16 v[34:37], v[162:165], v[178:181], v[34:37]
	v_mfma_f32_16x16x32_bf16 v[22:25], v[154:157], v[186:189], v[22:25]
	v_mfma_f32_16x16x32_bf16 v[18:21], v[162:165], v[186:189], v[18:21]
	v_mfma_f32_16x16x32_bf16 v[6:9], v[154:157], v[198:201], v[6:9]
	v_mfma_f32_16x16x32_bf16 v[2:5], v[162:165], v[198:201], v[2:5]
	v_mfma_f32_16x16x32_bf16 v[54:57], v[158:161], v[174:177], v[54:57]
	v_mfma_f32_16x16x32_bf16 v[50:53], v[166:169], v[174:177], v[50:53]
	v_mfma_f32_16x16x32_bf16 v[38:41], v[158:161], v[182:185], v[38:41]
	v_mfma_f32_16x16x32_bf16 v[34:37], v[166:169], v[182:185], v[34:37]
	v_mfma_f32_16x16x32_bf16 v[22:25], v[158:161], v[190:193], v[22:25]
	v_mfma_f32_16x16x32_bf16 v[18:21], v[166:169], v[190:193], v[18:21]
	v_mfma_f32_16x16x32_bf16 v[6:9], v[158:161], v[202:205], v[6:9]
	v_mfma_f32_16x16x32_bf16 v[2:5], v[166:169], v[202:205], v[2:5]
	s_setprio 0
	s_barrier
	s_add_i32 s97, s97, 2
	s_add_u32 s0, s0, 0x10000
	s_addc_u32 s1, s1, 0
	s_cmp_gt_u32 s97, 13
	s_cbranch_scc1 .LBB0_1070
	v_mov_b32_e32 v131, v130
	s_branch .LBB0_1066

.LBB0_1072:
	s_lshl_b32 s0, s92, 8
	v_mov_b32_e32 v225, v210
	v_mov_b32_e32 v222, v213
	s_add_i32 s0, s0, s39
	v_and_b32_e32 v156, 64, v220
	v_add_u32_e32 v182, s0, v222
	v_lshlrev_b32_e32 v130, 2, v225
	v_ashrrev_i32_e32 v131, 31, v130
	v_ashrrev_i32_e32 v183, 31, v182
	v_lshl_add_u64 v[130:131], v[130:131], 2, s[46:47]
	v_lshlrev_b64 v[206:207], 6, v[182:183]
	v_add_u32_e32 v178, 16, v182
	v_lshl_add_u64 v[132:133], v[130:131], 0, v[206:207]
	v_ashrrev_i32_e32 v179, 31, v178
	v_lshl_add_u64 v[250:251], v[132:133], 0, 0
	global_load_dwordx4 v[134:137], v[132:133], off
	v_lshlrev_b64 v[204:205], 6, v[178:179]
	v_add_u32_e32 v174, 32, v182
	v_ashrrev_i32_e32 v175, 31, v174
	s_mov_b32 s98, 0x1000
	s_mov_b32 s99, 0x0
	v_lshl_add_u64 v[252:253], v[250:251], 0, s[98:99]
	global_load_dwordx4 v[138:141], v[252:253], off offset:-3072
	v_lshlrev_b64 v[202:203], 6, v[174:175]
	v_add_u32_e32 v170, 48, v182
	v_ashrrev_i32_e32 v171, 31, v170
	global_load_dwordx4 v[142:145], v[252:253], off offset:-2048
	v_lshlrev_b64 v[200:201], 6, v[170:171]
	v_add_u32_e32 v166, 0x80, v182
	v_ashrrev_i32_e32 v167, 31, v166
	global_load_dwordx4 v[146:149], v[252:253], off offset:-1024
	v_lshlrev_b64 v[198:199], 6, v[166:167]
	v_add_u32_e32 v162, 0x90, v182
	v_ashrrev_i32_e32 v163, 31, v162
	s_mov_b32 s98, 0x3000
	s_mov_b32 s99, 0x0
	v_lshl_add_u64 v[252:253], v[250:251], 0, s[98:99]
	global_load_dwordx4 v[184:187], v[252:253], off offset:-4096
	v_lshlrev_b64 v[192:193], 6, v[162:163]
	v_add_u32_e32 v158, 0xa0, v182
	v_add_u32_e32 v154, 0xb0, v182
	v_ashrrev_i32_e32 v159, 31, v158
	v_ashrrev_i32_e32 v155, 31, v154
	global_load_dwordx4 v[226:229], v[252:253], off offset:-3072
	v_lshlrev_b64 v[190:191], 6, v[158:159]
	v_lshlrev_b64 v[188:189], 6, v[154:155]
	global_load_dwordx4 v[230:233], v[252:253], off offset:-2048
	v_xor_b32_e32 v150, 16, v220
	global_load_dwordx4 v[130:133], v[252:253], off offset:-1024
	v_add_u32_e32 v156, 64, v156
	v_cmp_lt_i32_e32 vcc, v150, v156
	s_add_i32 s51, s2, 6
	s_cmp_gt_u32 s2, -7
	v_cndmask_b32_e32 v150, v220, v150, vcc
	v_lshlrev_b32_e32 v223, 2, v150
	v_xor_b32_e32 v150, 32, v220
	v_cmp_lt_i32_e32 vcc, v150, v156
	s_cselect_b32 s0, 2, 3
	s_cselect_b32 s1, -4, -6
	v_cndmask_b32_e32 v150, v220, v150, vcc
	v_lshlrev_b32_e32 v224, 2, v150
	s_cmp_lt_u32 s51, 4
	s_cselect_b32 s0, 1, s0
	s_cselect_b32 s1, -2, s1
	s_cmp_lt_i32 s2, -4
	s_cselect_b32 s33, 0, s0
	s_cselect_b32 s0, 0, s1
	s_add_i32 s0, s0, s51
	s_cmp_lt_i32 s33, 2
	s_waitcnt vmcnt(7)
	v_add_f32_e32 v134, v134, v135
	v_add_f32_e32 v135, v136, v137
	v_add_f32_e32 v134, v134, v135
	ds_bpermute_b32 v135, v223, v134
	s_waitcnt vmcnt(6)
	v_add_f32_e32 v136, v138, v139
	v_add_f32_e32 v137, v140, v141
	v_add_f32_e32 v136, v136, v137
	ds_bpermute_b32 v137, v223, v136
	s_waitcnt lgkmcnt(1)
	v_add_f32_e32 v134, v134, v135
	s_waitcnt vmcnt(5)
	v_add_f32_e32 v138, v142, v143
	v_add_f32_e32 v139, v144, v145
	v_add_f32_e32 v138, v138, v139
	ds_bpermute_b32 v139, v223, v138
	ds_bpermute_b32 v135, v224, v134
	s_waitcnt vmcnt(4)
	v_add_f32_e32 v140, v146, v147
	v_add_f32_e32 v141, v148, v149
	v_add_f32_e32 v140, v140, v141
	ds_bpermute_b32 v141, v223, v140
	s_waitcnt lgkmcnt(3)
	v_add_f32_e32 v136, v136, v137
	s_waitcnt vmcnt(3)
	v_add_f32_e32 v142, v184, v185
	v_add_f32_e32 v143, v186, v187
	v_add_f32_e32 v142, v142, v143
	ds_bpermute_b32 v137, v224, v136
	ds_bpermute_b32 v143, v223, v142
	s_waitcnt lgkmcnt(4)
	v_add_f32_e32 v138, v138, v139
	ds_bpermute_b32 v139, v224, v138
	s_waitcnt vmcnt(2)
	v_add_f32_e32 v144, v226, v227
	v_add_f32_e32 v145, v228, v229
	v_add_f32_e32 v144, v144, v145
	ds_bpermute_b32 v145, v223, v144
	s_waitcnt lgkmcnt(4)
	v_add_f32_e32 v140, v140, v141
	s_waitcnt vmcnt(1)
	v_add_f32_e32 v146, v230, v231
	v_add_f32_e32 v147, v232, v233
	s_waitcnt vmcnt(0)
	v_add_f32_e32 v130, v130, v131
	v_add_f32_e32 v131, v132, v133
	v_add_f32_e32 v146, v146, v147
	v_add_f32_e32 v130, v130, v131
	v_add_f32_e32 v132, v134, v135
	ds_bpermute_b32 v141, v224, v140
	ds_bpermute_b32 v147, v223, v146
	ds_bpermute_b32 v131, v223, v130
	v_fmamk_f32 v132, v132, 0x3a800000, v221
	s_waitcnt lgkmcnt(5)
	v_add_f32_e32 v142, v142, v143
	v_rsq_f32_e32 v184, v132
	v_add_f32_e32 v132, v136, v137
	ds_bpermute_b32 v143, v224, v142
	v_fmamk_f32 v132, v132, 0x3a800000, v221
	s_waitcnt lgkmcnt(4)
	v_add_f32_e32 v144, v144, v145
	v_rsq_f32_e32 v180, v132
	v_add_f32_e32 v132, v138, v139
	ds_bpermute_b32 v145, v224, v144
	v_fmamk_f32 v132, v132, 0x3a800000, v221
	s_waitcnt lgkmcnt(3)
	v_add_f32_e32 v146, v146, v147
	s_waitcnt lgkmcnt(2)
	v_add_f32_e32 v130, v130, v131
	v_rsq_f32_e32 v176, v132
	v_add_f32_e32 v132, v140, v141
	ds_bpermute_b32 v147, v224, v146
	ds_bpermute_b32 v131, v224, v130
	v_fmamk_f32 v132, v132, 0x3a800000, v221
	v_rsq_f32_e32 v172, v132
	s_waitcnt lgkmcnt(3)
	v_add_f32_e32 v132, v142, v143
	v_fmamk_f32 v132, v132, 0x3a800000, v221
	v_rsq_f32_e32 v168, v132
	s_waitcnt lgkmcnt(2)
	v_add_f32_e32 v132, v144, v145
	v_fmamk_f32 v132, v132, 0x3a800000, v221
	v_rsq_f32_e32 v164, v132
	s_waitcnt lgkmcnt(1)
	v_add_f32_e32 v132, v146, v147
	s_waitcnt lgkmcnt(0)
	v_add_f32_e32 v130, v130, v131
	v_fmamk_f32 v132, v132, 0x3a800000, v221
	v_fmamk_f32 v130, v130, 0x3a800000, v221
	v_rsq_f32_e32 v160, v132
	v_rsq_f32_e32 v156, v130
	v_lshl_add_u32 v148, v225, 3, s17
	v_lshl_add_u32 v186, s0, 8, v148
	s_mov_b64 s[0:1], -1
	s_cbranch_scc1 .LBB0_1158
	s_cmp_gt_i32 s33, 2
	s_cbranch_scc0 .LBB0_1139
	s_mov_b32 s95, s26
	s_mov_b32 s91, s24
	s_mov_b32 s90, s17
	s_mov_b64 s[88:89], s[22:23]
	s_mov_b64 s[68:69], s[20:21]
	s_mov_b64 s[66:67], s[18:19]
	s_mov_b32 s53, s16
	v_readlane_b32 s16, v249, 6
	v_ashrrev_i32_e32 v187, 31, v186
	v_readlane_b32 s24, v249, 14
	v_readlane_b32 s25, v249, 15
	v_lshrrev_b32_e32 v147, 3, v182
	v_lshlrev_b32_e32 v146, 1, v148
	v_lshl_add_u64 v[134:135], v[186:187], 2, s[24:25]
	s_mov_b32 s98, 0x10
	s_mov_b32 s99, 0x0
	v_lshl_add_u64 v[250:251], v[134:135], 0, s[98:99]
	global_load_dwordx4 v[138:141], v[134:135], off offset:16
	s_mov_b32 s98, 0xfffff000
	s_mov_b32 s99, 0xffffffff
	v_lshl_add_u64 v[252:253], v[250:251], 0, s[98:99]
	global_load_dwordx4 v[142:145], v[252:253], off offset:4080
	s_mov_b32 s98, 0x1000
	s_mov_b32 s99, 0x0
	v_lshl_add_u64 v[252:253], v[250:251], 0, s[98:99]
	global_load_dwordx4 v[130:133], v[252:253], off offset:-3584
	s_nop 0
	global_load_dwordx4 v[134:137], v[252:253], off offset:-3600
	v_bfe_u32 v187, v148, 5, 1
	v_and_or_b32 v147, v147, 14, v187
	v_and_b32_e32 v157, 48, v146
	v_ashrrev_i32_e32 v146, 3, v182
	v_lshlrev_b32_e32 v148, 6, v182
	v_lshlrev_b32_e32 v161, 10, v147
	v_lshlrev_b32_e32 v147, 2, v182
	v_and_b32_e32 v165, 0xffffffe0, v146
	v_lshlrev_b32_e32 v146, 7, v182
	v_and_b32_e32 v148, 0x3c0, v148
	v_and_b32_e32 v147, 32, v147
	v_and_b32_e32 v146, 0x4000, v146
	v_bitop3_b32 v147, v157, v147, v148 bitop3:0x36
	v_or3_b32 v150, v146, v147, v161
	v_ashrrev_i32_e32 v226, 6, v186
	s_cmpk_lt_i32 s92, 0x80
	s_cselect_b64 s[0:1], -1, 0
	s_xor_b64 s[62:63], s[36:37], -1
	s_and_b64 s[62:63], s[62:63], s[0:1]
	s_mov_b64 s[64:65], -1
	s_and_b64 vcc, exec, s[62:63]
	v_readlane_b32 s17, v249, 7
	v_readlane_b32 s18, v249, 8
	v_readlane_b32 s19, v249, 9
	v_readlane_b32 s20, v249, 10
	v_readlane_b32 s21, v249, 11
	v_readlane_b32 s22, v249, 12
	v_readlane_b32 s23, v249, 13
	v_readlane_b32 s26, v249, 16
	v_readlane_b32 s27, v249, 17
	v_readlane_b32 s28, v249, 18
	v_readlane_b32 s29, v249, 19
	v_readlane_b32 s30, v249, 20
	v_readlane_b32 s31, v249, 21
	s_waitcnt vmcnt(2)
	v_pk_fma_f32 v[146:147], v[126:127], v[184:185], v[142:143] op_sel_hi:[1,0,1]
	s_nop 0
	v_pk_mul_f32 v[146:147], v[146:147], s[38:39] op_sel_hi:[1,0]
	s_nop 0
	v_exp_f32_e32 v146, v146
	v_exp_f32_e32 v147, v147
	s_nop 0
	v_pk_add_f32 v[146:147], v[146:147], 1.0 op_sel_hi:[1,0]
	s_nop 0
	v_rcp_f32_e32 v148, v146
	v_rcp_f32_e32 v149, v147
	v_pk_fma_f32 v[146:147], v[128:129], v[184:185], v[144:145] op_sel_hi:[1,0,1]
	s_nop 0
	v_pk_mul_f32 v[146:147], v[146:147], s[38:39] op_sel_hi:[1,0]
	s_nop 0
	v_exp_f32_e32 v146, v146
	v_exp_f32_e32 v147, v147
	s_nop 0
	v_pk_add_f32 v[146:147], v[146:147], 1.0 op_sel_hi:[1,0]
	s_nop 0
	v_rcp_f32_e32 v169, v146
	v_rcp_f32_e32 v173, v147
	v_pk_fma_f32 v[146:147], v[122:123], v[184:185], v[138:139] op_sel_hi:[1,0,1]
	s_nop 0
	v_pk_mul_f32 v[146:147], v[146:147], s[38:39] op_sel_hi:[1,0]
	s_nop 0
	v_exp_f32_e32 v146, v146
	v_exp_f32_e32 v147, v147
	s_nop 0
	v_pk_add_f32 v[146:147], v[146:147], 1.0 op_sel_hi:[1,0]
	s_nop 0
	v_rcp_f32_e32 v177, v146
	v_rcp_f32_e32 v181, v147
	v_pk_fma_f32 v[146:147], v[124:125], v[184:185], v[140:141] op_sel_hi:[1,0,1]
	s_nop 0
	v_pk_mul_f32 v[146:147], v[146:147], s[38:39] op_sel_hi:[1,0]
	s_nop 0
	v_exp_f32_e32 v146, v146
	v_exp_f32_e32 v147, v147
	s_nop 0
	v_pk_add_f32 v[146:147], v[146:147], 1.0 op_sel_hi:[1,0]
	s_nop 0
	v_rcp_f32_e32 v185, v146
	v_rcp_f32_e32 v227, v147
	v_add_u32_e32 v146, v226, v165
	v_ashrrev_i32_e32 v147, 31, v146
	v_lshlrev_b64 v[146:147], 15, v[146:147]
	v_lshl_add_u64 v[146:147], s[80:81], 0, v[146:147]
	v_lshl_add_u64 v[208:209], v[146:147], 0, v[150:151]
	v_cvt_pk_bf16_f32 v146, v148, v149
	v_cvt_pk_bf16_f32 v147, v169, v173
	v_cvt_pk_bf16_f32 v148, v177, v181
	v_cvt_pk_bf16_f32 v149, v185, v227
	v_lshl_add_u64 v[250:251], v[208:209], 0, 0
	s_cbranch_vccz .LBB0_1076
	global_store_dwordx4 v[208:209], v[146:149], off
	s_mov_b64 s[64:65], 0
.LBB0_1076:
	s_mov_b32 s98, 0x1000
	s_mov_b32 s99, 0x0
	v_lshl_add_u64 v[252:253], v[250:251], 0, s[98:99]
	s_andn2_b64 vcc, exec, s[64:65]
	s_cbranch_vccnz .LBB0_1078
	global_store_dwordx4 v[252:253], v[146:149], off offset:-4096 sc1
	s_nop 1
.LBB0_1078:
	v_mov_b32_e32 v185, v184
	s_waitcnt vmcnt(0)
	v_pk_fma_f32 v[146:147], v[118:119], v[184:185], v[134:135]
	v_pk_fma_f32 v[148:149], v[120:121], v[184:185], v[136:137]
	v_pk_mul_f32 v[146:147], v[146:147], s[38:39] op_sel_hi:[1,0]
	v_pk_mul_f32 v[148:149], v[148:149], s[38:39] op_sel_hi:[1,0]
	v_exp_f32_e32 v146, v146
	v_exp_f32_e32 v147, v147
	v_exp_f32_e32 v148, v148
	v_exp_f32_e32 v149, v149
	s_andn2_b64 vcc, exec, s[62:63]
	v_pk_add_f32 v[146:147], v[146:147], 1.0 op_sel_hi:[1,0]
	s_mov_b32 s16, s53
	v_rcp_f32_e32 v169, v146
	v_rcp_f32_e32 v173, v147
	v_pk_add_f32 v[146:147], v[148:149], 1.0 op_sel_hi:[1,0]
	v_pk_fma_f32 v[148:149], v[116:117], v[184:185], v[132:133]
	v_rcp_f32_e32 v177, v146
	v_rcp_f32_e32 v181, v147
	v_pk_fma_f32 v[146:147], v[114:115], v[184:185], v[130:131]
	v_pk_mul_f32 v[148:149], v[148:149], s[38:39] op_sel_hi:[1,0]
	v_pk_mul_f32 v[146:147], v[146:147], s[38:39] op_sel_hi:[1,0]
	v_exp_f32_e32 v148, v148
	v_exp_f32_e32 v146, v146
	v_exp_f32_e32 v147, v147
	v_exp_f32_e32 v149, v149
	s_mov_b64 s[18:19], s[66:67]
	s_mov_b64 s[20:21], s[68:69]
	v_pk_add_f32 v[146:147], v[146:147], 1.0 op_sel_hi:[1,0]
	s_mov_b64 s[22:23], s[88:89]
	v_rcp_f32_e32 v227, v146
	v_rcp_f32_e32 v228, v147
	v_pk_add_f32 v[146:147], v[148:149], 1.0 op_sel_hi:[1,0]
	s_mov_b32 s17, s90
	v_rcp_f32_e32 v149, v146
	v_add_u32_e32 v146, 0x80, v186
	v_ashrrev_i32_e32 v185, 6, v146
	s_nop 0
	v_rcp_f32_e32 v229, v147
	s_nop 0
	s_nop 0
	s_nop 0
	s_nop 0
	v_cndmask_b32_e64 v150, 0, 1, s[62:63]
	v_cvt_pk_bf16_f32 v146, v169, v173
	v_cvt_pk_bf16_f32 v147, v177, v181
	v_cvt_pk_bf16_f32 v148, v227, v228
	v_cvt_pk_bf16_f32 v149, v149, v229
	v_cmp_ne_u32_e64 s[0:1], 1, v150
	s_mov_b32 s98, 0x11000
	s_mov_b32 s99, 0x0
	v_lshl_add_u64 v[254:255], v[250:251], 0, s[98:99]
	s_mov_b64 s[62:63], -1
	s_mov_b32 s24, s91
	s_mov_b32 s26, s95
	s_movk_i32 s27, 0xff0
	s_movk_i32 s28, 0xf00f
	s_cbranch_vccnz .LBB0_1080
	s_mov_b64 s[62:63], 0
	global_store_dwordx4 v[254:255], v[146:149], off offset:-4096
.LBB0_1080:
	s_andn2_b64 vcc, exec, s[62:63]
	s_cbranch_vccnz .LBB0_1082
	global_store_dwordx4 v[254:255], v[146:149], off offset:-4096 sc1
	s_nop 1
.LBB0_1082:
	s_nop 0
	s_nop 0
	s_nop 0
	s_nop 0
	v_pk_fma_f32 v[146:147], v[110:111], v[180:181], v[142:143] op_sel_hi:[1,0,1]
	v_pk_fma_f32 v[148:149], v[112:113], v[180:181], v[144:145] op_sel_hi:[1,0,1]
	v_pk_mul_f32 v[146:147], v[146:147], s[38:39] op_sel_hi:[1,0]
	v_pk_mul_f32 v[148:149], v[148:149], s[38:39] op_sel_hi:[1,0]
	v_exp_f32_e32 v146, v146
	v_exp_f32_e32 v147, v147
	v_exp_f32_e32 v148, v148
	v_exp_f32_e32 v149, v149
	s_and_b64 vcc, exec, s[0:1]
	v_pk_add_f32 v[146:147], v[146:147], 1.0 op_sel_hi:[1,0]
	s_mov_b64 s[62:63], -1
	v_rcp_f32_e32 v169, v146
	v_rcp_f32_e32 v173, v147
	v_pk_add_f32 v[146:147], v[148:149], 1.0 op_sel_hi:[1,0]
	s_nop 0
	v_rcp_f32_e32 v181, v147
	v_rcp_f32_e32 v177, v146
	v_pk_fma_f32 v[146:147], v[106:107], v[180:181], v[138:139] op_sel_hi:[1,0,1]
	s_nop 0
	v_pk_mul_f32 v[146:147], v[146:147], s[38:39] op_sel_hi:[1,0]
	v_pk_fma_f32 v[148:149], v[108:109], v[180:181], v[140:141] op_sel_hi:[1,0,1]
	v_exp_f32_e32 v146, v146
	v_exp_f32_e32 v147, v147
	v_pk_mul_f32 v[148:149], v[148:149], s[38:39] op_sel_hi:[1,0]
	v_pk_add_f32 v[146:147], v[146:147], 1.0 op_sel_hi:[1,0]
	v_exp_f32_e32 v148, v148
	v_exp_f32_e32 v149, v149
	v_rcp_f32_e32 v227, v146
	v_rcp_f32_e32 v228, v147
	v_pk_add_f32 v[146:147], v[148:149], 1.0 op_sel_hi:[1,0]
	s_nop 0
	v_rcp_f32_e32 v149, v146
	v_rcp_f32_e32 v229, v147
	s_nop 0
	s_nop 0
	s_nop 0
	s_nop 0
	s_nop 0
	v_cvt_pk_bf16_f32 v146, v169, v173
	v_cvt_pk_bf16_f32 v147, v177, v181
	v_cvt_pk_bf16_f32 v148, v227, v228
	v_cvt_pk_bf16_f32 v149, v149, v229
	s_cbranch_vccnz .LBB0_1084
	s_mov_b64 s[62:63], 0
	global_store_dwordx4 v[252:253], v[146:149], off offset:-2048
.LBB0_1084:
	s_andn2_b64 vcc, exec, s[62:63]
	s_cbranch_vccnz .LBB0_1086
	global_store_dwordx4 v[252:253], v[146:149], off offset:-2048 sc1
	s_nop 1
.LBB0_1086:
	v_mov_b32_e32 v181, v180
	v_pk_fma_f32 v[146:147], v[102:103], v[180:181], v[134:135]
	v_pk_fma_f32 v[148:149], v[104:105], v[180:181], v[136:137]
	v_pk_mul_f32 v[146:147], v[146:147], s[38:39] op_sel_hi:[1,0]
	v_pk_mul_f32 v[148:149], v[148:149], s[38:39] op_sel_hi:[1,0]
	v_exp_f32_e32 v146, v146
	v_exp_f32_e32 v147, v147
	v_exp_f32_e32 v148, v148
	v_exp_f32_e32 v149, v149
	s_and_b64 vcc, exec, s[0:1]
	v_pk_add_f32 v[146:147], v[146:147], 1.0 op_sel_hi:[1,0]
	s_mov_b64 s[62:63], -1
	v_rcp_f32_e32 v169, v146
	v_rcp_f32_e32 v173, v147
	v_pk_add_f32 v[146:147], v[148:149], 1.0 op_sel_hi:[1,0]
	v_pk_fma_f32 v[148:149], v[100:101], v[180:181], v[132:133]
	v_rcp_f32_e32 v177, v146
	v_rcp_f32_e32 v227, v147
	v_pk_fma_f32 v[146:147], v[98:99], v[180:181], v[130:131]
	v_pk_mul_f32 v[148:149], v[148:149], s[38:39] op_sel_hi:[1,0]
	v_pk_mul_f32 v[146:147], v[146:147], s[38:39] op_sel_hi:[1,0]
	v_exp_f32_e32 v148, v148
	v_exp_f32_e32 v146, v146
	v_exp_f32_e32 v147, v147
	v_exp_f32_e32 v149, v149
	v_pk_add_f32 v[146:147], v[146:147], 1.0 op_sel_hi:[1,0]
	s_nop 0
	v_rcp_f32_e32 v181, v146
	v_rcp_f32_e32 v228, v147
	v_pk_add_f32 v[146:147], v[148:149], 1.0 op_sel_hi:[1,0]
	v_cvt_pk_bf16_f32 v148, v181, v228
	v_rcp_f32_e32 v149, v146
	v_rcp_f32_e32 v229, v147
	s_nop 0
	s_nop 0
	s_nop 0
	s_nop 0
	s_nop 0
	v_cvt_pk_bf16_f32 v146, v169, v173
	v_cvt_pk_bf16_f32 v147, v177, v227
	v_cvt_pk_bf16_f32 v149, v149, v229
	s_cbranch_vccnz .LBB0_1088
	s_mov_b64 s[62:63], 0
	global_store_dwordx4 v[254:255], v[146:149], off offset:-2048
.LBB0_1088:
	s_andn2_b64 vcc, exec, s[62:63]
	s_cbranch_vccnz .LBB0_1090
	global_store_dwordx4 v[254:255], v[146:149], off offset:-2048 sc1
	s_nop 1
.LBB0_1090:
	s_nop 0
	s_nop 0
	s_nop 0
	s_nop 0
	v_pk_fma_f32 v[146:147], v[94:95], v[176:177], v[142:143] op_sel_hi:[1,0,1]
	v_pk_fma_f32 v[148:149], v[96:97], v[176:177], v[144:145] op_sel_hi:[1,0,1]
	v_pk_mul_f32 v[146:147], v[146:147], s[38:39] op_sel_hi:[1,0]
	v_pk_mul_f32 v[148:149], v[148:149], s[38:39] op_sel_hi:[1,0]
	v_exp_f32_e32 v146, v146
	v_exp_f32_e32 v147, v147
	v_exp_f32_e32 v148, v148
	v_exp_f32_e32 v149, v149
	s_and_b64 vcc, exec, s[0:1]
	v_pk_add_f32 v[146:147], v[146:147], 1.0 op_sel_hi:[1,0]
	s_mov_b64 s[62:63], -1
	v_rcp_f32_e32 v169, v146
	v_rcp_f32_e32 v173, v147
	v_pk_add_f32 v[146:147], v[148:149], 1.0 op_sel_hi:[1,0]
	s_nop 0
	v_rcp_f32_e32 v177, v146
	v_rcp_f32_e32 v181, v147
	v_pk_fma_f32 v[146:147], v[90:91], v[176:177], v[138:139] op_sel_hi:[1,0,1]
	s_nop 0
	v_pk_mul_f32 v[146:147], v[146:147], s[38:39] op_sel_hi:[1,0]
	v_pk_fma_f32 v[148:149], v[92:93], v[176:177], v[140:141] op_sel_hi:[1,0,1]
	v_exp_f32_e32 v146, v146
	v_exp_f32_e32 v147, v147
	v_pk_mul_f32 v[148:149], v[148:149], s[38:39] op_sel_hi:[1,0]
	v_pk_add_f32 v[146:147], v[146:147], 1.0 op_sel_hi:[1,0]
	v_exp_f32_e32 v148, v148
	v_exp_f32_e32 v149, v149
	v_rcp_f32_e32 v227, v146
	v_rcp_f32_e32 v228, v147
	v_pk_add_f32 v[146:147], v[148:149], 1.0 op_sel_hi:[1,0]
	s_nop 0
	v_rcp_f32_e32 v149, v146
	v_rcp_f32_e32 v229, v147
	s_nop 0
	s_nop 0
	s_nop 0
	s_nop 0
	s_nop 0
	v_cvt_pk_bf16_f32 v146, v169, v173
	v_cvt_pk_bf16_f32 v147, v177, v181
	v_cvt_pk_bf16_f32 v148, v227, v228
	v_cvt_pk_bf16_f32 v149, v149, v229
	s_cbranch_vccnz .LBB0_1092
	s_mov_b64 s[62:63], 0
	global_store_dwordx4 v[252:253], v[146:149], off
.LBB0_1092:
	s_andn2_b64 vcc, exec, s[62:63]
	s_cbranch_vccnz .LBB0_1094
	global_store_dwordx4 v[252:253], v[146:149], off sc1
	s_nop 1
.LBB0_1094:
	v_mov_b32_e32 v177, v176
	v_pk_fma_f32 v[146:147], v[86:87], v[176:177], v[134:135]
	v_pk_fma_f32 v[148:149], v[88:89], v[176:177], v[136:137]
	v_pk_mul_f32 v[146:147], v[146:147], s[38:39] op_sel_hi:[1,0]
	v_pk_mul_f32 v[148:149], v[148:149], s[38:39] op_sel_hi:[1,0]
	v_exp_f32_e32 v146, v146
	v_exp_f32_e32 v147, v147
	v_exp_f32_e32 v148, v148
	v_exp_f32_e32 v149, v149
	s_and_b64 vcc, exec, s[0:1]
	v_pk_add_f32 v[146:147], v[146:147], 1.0 op_sel_hi:[1,0]
	s_mov_b64 s[62:63], -1
	v_rcp_f32_e32 v169, v146
	v_rcp_f32_e32 v173, v147
	v_pk_add_f32 v[146:147], v[148:149], 1.0 op_sel_hi:[1,0]
	v_pk_fma_f32 v[148:149], v[84:85], v[176:177], v[132:133]
	v_rcp_f32_e32 v181, v146
	v_rcp_f32_e32 v227, v147
	v_pk_fma_f32 v[146:147], v[82:83], v[176:177], v[130:131]
	v_pk_mul_f32 v[148:149], v[148:149], s[38:39] op_sel_hi:[1,0]
	v_pk_mul_f32 v[146:147], v[146:147], s[38:39] op_sel_hi:[1,0]
	v_exp_f32_e32 v148, v148
	v_exp_f32_e32 v146, v146
	v_exp_f32_e32 v147, v147
	v_exp_f32_e32 v149, v149
	v_pk_add_f32 v[146:147], v[146:147], 1.0 op_sel_hi:[1,0]
	s_nop 0
	v_rcp_f32_e32 v177, v146
	v_rcp_f32_e32 v228, v147
	v_pk_add_f32 v[146:147], v[148:149], 1.0 op_sel_hi:[1,0]
	v_cvt_pk_bf16_f32 v148, v177, v228
	v_rcp_f32_e32 v149, v146
	v_rcp_f32_e32 v229, v147
	s_nop 0
	s_nop 0
	s_nop 0
	s_nop 0
	s_nop 0
	v_cvt_pk_bf16_f32 v146, v169, v173
	v_cvt_pk_bf16_f32 v147, v181, v227
	v_cvt_pk_bf16_f32 v149, v149, v229
	s_cbranch_vccnz .LBB0_1096
	s_mov_b64 s[62:63], 0
	global_store_dwordx4 v[254:255], v[146:149], off
.LBB0_1096:
	s_andn2_b64 vcc, exec, s[62:63]
	s_cbranch_vccnz .LBB0_1098
	global_store_dwordx4 v[254:255], v[146:149], off sc1
	s_nop 1
.LBB0_1098:
	s_nop 0
	s_nop 0
	s_nop 0
	s_nop 0
	v_pk_fma_f32 v[146:147], v[78:79], v[172:173], v[142:143] op_sel_hi:[1,0,1]
	v_pk_fma_f32 v[148:149], v[80:81], v[172:173], v[144:145] op_sel_hi:[1,0,1]
	v_pk_mul_f32 v[146:147], v[146:147], s[38:39] op_sel_hi:[1,0]
	v_pk_mul_f32 v[148:149], v[148:149], s[38:39] op_sel_hi:[1,0]
	v_exp_f32_e32 v146, v146
	v_exp_f32_e32 v147, v147
	v_exp_f32_e32 v148, v148
	v_exp_f32_e32 v149, v149
	s_and_b64 vcc, exec, s[0:1]
	v_pk_add_f32 v[146:147], v[146:147], 1.0 op_sel_hi:[1,0]
	s_mov_b64 s[62:63], -1
	v_rcp_f32_e32 v173, v147
	v_rcp_f32_e32 v169, v146
	v_pk_add_f32 v[146:147], v[148:149], 1.0 op_sel_hi:[1,0]
	v_pk_fma_f32 v[148:149], v[76:77], v[172:173], v[140:141] op_sel_hi:[1,0,1]
	v_rcp_f32_e32 v177, v146
	v_rcp_f32_e32 v181, v147
	v_pk_fma_f32 v[146:147], v[74:75], v[172:173], v[138:139] op_sel_hi:[1,0,1]
	v_pk_mul_f32 v[148:149], v[148:149], s[38:39] op_sel_hi:[1,0]
	v_pk_mul_f32 v[146:147], v[146:147], s[38:39] op_sel_hi:[1,0]
	v_exp_f32_e32 v148, v148
	v_exp_f32_e32 v146, v146
	v_exp_f32_e32 v147, v147
	v_exp_f32_e32 v149, v149
	v_pk_add_f32 v[146:147], v[146:147], 1.0 op_sel_hi:[1,0]
	s_nop 0
	v_rcp_f32_e32 v227, v146
	v_rcp_f32_e32 v228, v147
	v_pk_add_f32 v[146:147], v[148:149], 1.0 op_sel_hi:[1,0]
	v_cvt_pk_bf16_f32 v148, v227, v228
	v_rcp_f32_e32 v149, v146
	v_rcp_f32_e32 v229, v147
	s_nop 0
	s_nop 0
	s_nop 0
	s_nop 0
	s_nop 0
	v_cvt_pk_bf16_f32 v146, v169, v173
	v_cvt_pk_bf16_f32 v147, v177, v181
	v_cvt_pk_bf16_f32 v149, v149, v229
	s_cbranch_vccnz .LBB0_1100
	s_mov_b64 s[62:63], 0
	global_store_dwordx4 v[252:253], v[146:149], off offset:2048
.LBB0_1100:
	s_andn2_b64 vcc, exec, s[62:63]
	s_cbranch_vccnz .LBB0_1102
	global_store_dwordx4 v[252:253], v[146:149], off offset:2048 sc1
	s_nop 1
.LBB0_1102:
	v_mov_b32_e32 v173, v172
	v_pk_fma_f32 v[146:147], v[70:71], v[172:173], v[134:135]
	v_pk_fma_f32 v[148:149], v[72:73], v[172:173], v[136:137]
	v_pk_mul_f32 v[146:147], v[146:147], s[38:39] op_sel_hi:[1,0]
	v_pk_mul_f32 v[148:149], v[148:149], s[38:39] op_sel_hi:[1,0]
	v_exp_f32_e32 v146, v146
	v_exp_f32_e32 v147, v147
	v_exp_f32_e32 v148, v148
	v_exp_f32_e32 v149, v149
	s_and_b64 vcc, exec, s[0:1]
	v_pk_add_f32 v[146:147], v[146:147], 1.0 op_sel_hi:[1,0]
	s_mov_b64 s[62:63], -1
	v_rcp_f32_e32 v169, v146
	v_rcp_f32_e32 v177, v147
	v_pk_add_f32 v[146:147], v[148:149], 1.0 op_sel_hi:[1,0]
	v_pk_fma_f32 v[148:149], v[68:69], v[172:173], v[132:133]
	v_rcp_f32_e32 v181, v146
	v_rcp_f32_e32 v227, v147
	v_pk_fma_f32 v[146:147], v[66:67], v[172:173], v[130:131]
	v_pk_mul_f32 v[148:149], v[148:149], s[38:39] op_sel_hi:[1,0]
	v_pk_mul_f32 v[146:147], v[146:147], s[38:39] op_sel_hi:[1,0]
	v_exp_f32_e32 v148, v148
	v_exp_f32_e32 v146, v146
	v_exp_f32_e32 v147, v147
	v_exp_f32_e32 v149, v149
	v_pk_add_f32 v[146:147], v[146:147], 1.0 op_sel_hi:[1,0]
	s_nop 0
	v_rcp_f32_e32 v173, v146
	v_rcp_f32_e32 v228, v147
	v_pk_add_f32 v[146:147], v[148:149], 1.0 op_sel_hi:[1,0]
	v_cvt_pk_bf16_f32 v148, v173, v228
	v_rcp_f32_e32 v149, v146
	v_rcp_f32_e32 v229, v147
	s_nop 0
	s_nop 0
	s_nop 0
	s_nop 0
	s_nop 0
	v_cvt_pk_bf16_f32 v146, v169, v177
	v_cvt_pk_bf16_f32 v147, v181, v227
	v_cvt_pk_bf16_f32 v149, v149, v229
	s_cbranch_vccnz .LBB0_1104
	s_mov_b64 s[62:63], 0
	global_store_dwordx4 v[254:255], v[146:149], off offset:2048
.LBB0_1104:
	s_andn2_b64 vcc, exec, s[62:63]
	s_cbranch_vccnz .LBB0_1106
	global_store_dwordx4 v[254:255], v[146:149], off offset:2048 sc1
	s_nop 1
.LBB0_1106:
	v_ashrrev_i32_e32 v146, 3, v166
	s_nop 0
	s_nop 0
	v_and_b32_e32 v165, 0xffffffe0, v146
	v_pk_fma_f32 v[146:147], v[62:63], v[168:169], v[142:143] op_sel_hi:[1,0,1]
	v_pk_fma_f32 v[148:149], v[64:65], v[168:169], v[144:145] op_sel_hi:[1,0,1]
	v_pk_mul_f32 v[146:147], v[146:147], s[38:39] op_sel_hi:[1,0]
	v_pk_mul_f32 v[148:149], v[148:149], s[38:39] op_sel_hi:[1,0]
	v_exp_f32_e32 v146, v146
	v_exp_f32_e32 v147, v147
	v_exp_f32_e32 v148, v148
	v_exp_f32_e32 v149, v149
	s_and_b64 vcc, exec, s[0:1]
	v_pk_add_f32 v[146:147], v[146:147], 1.0 op_sel_hi:[1,0]
	s_mov_b64 s[62:63], -1
	v_rcp_f32_e32 v169, v147
	v_rcp_f32_e32 v161, v146
	v_pk_add_f32 v[146:147], v[148:149], 1.0 op_sel_hi:[1,0]
	v_pk_fma_f32 v[148:149], v[60:61], v[168:169], v[140:141] op_sel_hi:[1,0,1]
	v_rcp_f32_e32 v173, v146
	v_rcp_f32_e32 v177, v147
	v_pk_fma_f32 v[146:147], v[58:59], v[168:169], v[138:139] op_sel_hi:[1,0,1]
	v_pk_mul_f32 v[148:149], v[148:149], s[38:39] op_sel_hi:[1,0]
	v_pk_mul_f32 v[146:147], v[146:147], s[38:39] op_sel_hi:[1,0]
	v_exp_f32_e32 v148, v148
	v_exp_f32_e32 v146, v146
	v_exp_f32_e32 v147, v147
	v_exp_f32_e32 v149, v149
	v_pk_add_f32 v[146:147], v[146:147], 1.0 op_sel_hi:[1,0]
	s_nop 0
	v_rcp_f32_e32 v181, v146
	v_rcp_f32_e32 v227, v147
	v_pk_add_f32 v[146:147], v[148:149], 1.0 op_sel_hi:[1,0]
	v_cvt_pk_bf16_f32 v148, v181, v227
	v_rcp_f32_e32 v149, v146
	v_rcp_f32_e32 v228, v147
	s_nop 0
	s_nop 0
	s_nop 0
	s_nop 0
	s_nop 0
	v_cvt_pk_bf16_f32 v146, v161, v169
	v_cvt_pk_bf16_f32 v147, v173, v177
	v_cvt_pk_bf16_f32 v149, v149, v228
	s_mov_b32 s98, 0x5000
	s_mov_b32 s99, 0x0
	v_lshl_add_u64 v[252:253], v[250:251], 0, s[98:99]
	s_cbranch_vccnz .LBB0_1108
	s_mov_b64 s[62:63], 0
	global_store_dwordx4 v[252:253], v[146:149], off offset:-4096
.LBB0_1108:
	s_andn2_b64 vcc, exec, s[62:63]
	s_cbranch_vccnz .LBB0_1110
	global_store_dwordx4 v[252:253], v[146:149], off offset:-4096 sc1
	s_nop 1
.LBB0_1110:
	v_mov_b32_e32 v169, v168
	v_pk_fma_f32 v[146:147], v[54:55], v[168:169], v[134:135]
	v_pk_fma_f32 v[148:149], v[56:57], v[168:169], v[136:137]
	v_pk_mul_f32 v[146:147], v[146:147], s[38:39] op_sel_hi:[1,0]
	v_pk_mul_f32 v[148:149], v[148:149], s[38:39] op_sel_hi:[1,0]
	v_exp_f32_e32 v146, v146
	v_exp_f32_e32 v147, v147
	v_exp_f32_e32 v148, v148
	v_exp_f32_e32 v149, v149
	s_and_b64 vcc, exec, s[0:1]
	v_pk_add_f32 v[146:147], v[146:147], 1.0 op_sel_hi:[1,0]
	s_mov_b64 s[62:63], -1
	v_rcp_f32_e32 v161, v146
	v_rcp_f32_e32 v173, v147
	v_pk_add_f32 v[146:147], v[148:149], 1.0 op_sel_hi:[1,0]
	v_pk_fma_f32 v[148:149], v[52:53], v[168:169], v[132:133]
	v_rcp_f32_e32 v177, v146
	v_rcp_f32_e32 v181, v147
	v_pk_fma_f32 v[146:147], v[50:51], v[168:169], v[130:131]
	v_pk_mul_f32 v[148:149], v[148:149], s[38:39] op_sel_hi:[1,0]
	v_pk_mul_f32 v[146:147], v[146:147], s[38:39] op_sel_hi:[1,0]
	v_exp_f32_e32 v148, v148
	v_exp_f32_e32 v146, v146
	v_exp_f32_e32 v147, v147
	v_exp_f32_e32 v149, v149
	v_pk_add_f32 v[146:147], v[146:147], 1.0 op_sel_hi:[1,0]
	s_nop 0
	v_rcp_f32_e32 v169, v146
	v_rcp_f32_e32 v227, v147
	v_pk_add_f32 v[146:147], v[148:149], 1.0 op_sel_hi:[1,0]
	v_cvt_pk_bf16_f32 v148, v169, v227
	v_rcp_f32_e32 v149, v146
	v_rcp_f32_e32 v228, v147
	s_nop 0
	s_nop 0
	s_nop 0
	s_nop 0
	s_nop 0
	v_cvt_pk_bf16_f32 v146, v161, v173
	v_cvt_pk_bf16_f32 v147, v177, v181
	v_cvt_pk_bf16_f32 v149, v149, v228
	s_mov_b32 s98, 0x15000
	s_mov_b32 s99, 0x0
	v_lshl_add_u64 v[254:255], v[250:251], 0, s[98:99]
	s_cbranch_vccnz .LBB0_1112
	s_mov_b64 s[62:63], 0
	global_store_dwordx4 v[254:255], v[146:149], off offset:-4096

.LBB0_1114:
	v_ashrrev_i32_e32 v146, 3, v162
	s_nop 0
	s_nop 0
	s_nop 0
	v_and_b32_e32 v161, 0xffffffe0, v146
	v_pk_fma_f32 v[146:147], v[46:47], v[164:165], v[142:143] op_sel_hi:[1,0,1]
	v_pk_fma_f32 v[148:149], v[48:49], v[164:165], v[144:145] op_sel_hi:[1,0,1]
	v_pk_mul_f32 v[146:147], v[146:147], s[38:39] op_sel_hi:[1,0]
	v_pk_mul_f32 v[148:149], v[148:149], s[38:39] op_sel_hi:[1,0]
	v_exp_f32_e32 v146, v146
	v_exp_f32_e32 v147, v147
	v_exp_f32_e32 v148, v148
	v_exp_f32_e32 v149, v149
	s_and_b64 vcc, exec, s[0:1]
	v_pk_add_f32 v[146:147], v[146:147], 1.0 op_sel_hi:[1,0]
	s_mov_b64 s[62:63], -1
	v_rcp_f32_e32 v165, v146
	v_rcp_f32_e32 v169, v147
	v_pk_add_f32 v[146:147], v[148:149], 1.0 op_sel_hi:[1,0]
	v_pk_fma_f32 v[148:149], v[44:45], v[164:165], v[140:141] op_sel_hi:[1,0,1]
	v_rcp_f32_e32 v173, v146
	v_rcp_f32_e32 v177, v147
	v_pk_fma_f32 v[146:147], v[42:43], v[164:165], v[138:139] op_sel_hi:[1,0,1]
	v_pk_mul_f32 v[148:149], v[148:149], s[38:39] op_sel_hi:[1,0]
	v_pk_mul_f32 v[146:147], v[146:147], s[38:39] op_sel_hi:[1,0]
	v_exp_f32_e32 v148, v148
	v_exp_f32_e32 v146, v146
	v_exp_f32_e32 v147, v147
	v_exp_f32_e32 v149, v149
	v_pk_add_f32 v[146:147], v[146:147], 1.0 op_sel_hi:[1,0]
	s_nop 0
	v_rcp_f32_e32 v181, v146
	v_rcp_f32_e32 v227, v147
	v_pk_add_f32 v[146:147], v[148:149], 1.0 op_sel_hi:[1,0]
	v_cvt_pk_bf16_f32 v148, v181, v227
	v_rcp_f32_e32 v149, v146
	v_rcp_f32_e32 v228, v147
	s_nop 0
	s_nop 0
	s_nop 0
	s_nop 0
	s_nop 0
	v_cvt_pk_bf16_f32 v146, v165, v169
	v_cvt_pk_bf16_f32 v147, v173, v177
	v_cvt_pk_bf16_f32 v149, v149, v228
	s_cbranch_vccnz .LBB0_1116
	s_mov_b64 s[62:63], 0
	global_store_dwordx4 v[252:253], v[146:149], off offset:-2048

.LBB0_1118:
	v_mov_b32_e32 v165, v164
	v_pk_fma_f32 v[146:147], v[38:39], v[164:165], v[134:135]
	v_pk_fma_f32 v[148:149], v[40:41], v[164:165], v[136:137]
	v_pk_mul_f32 v[146:147], v[146:147], s[38:39] op_sel_hi:[1,0]
	v_pk_mul_f32 v[148:149], v[148:149], s[38:39] op_sel_hi:[1,0]
	v_exp_f32_e32 v146, v146
	v_exp_f32_e32 v147, v147
	v_exp_f32_e32 v148, v148
	v_exp_f32_e32 v149, v149
	s_and_b64 vcc, exec, s[0:1]
	v_pk_add_f32 v[146:147], v[146:147], 1.0 op_sel_hi:[1,0]
	s_mov_b64 s[62:63], -1
	v_rcp_f32_e32 v169, v146
	v_rcp_f32_e32 v173, v147
	v_pk_add_f32 v[146:147], v[148:149], 1.0 op_sel_hi:[1,0]
	v_pk_fma_f32 v[148:149], v[36:37], v[164:165], v[132:133]
	v_rcp_f32_e32 v177, v146
	v_rcp_f32_e32 v181, v147
	v_pk_fma_f32 v[146:147], v[34:35], v[164:165], v[130:131]
	v_pk_mul_f32 v[148:149], v[148:149], s[38:39] op_sel_hi:[1,0]
	v_pk_mul_f32 v[146:147], v[146:147], s[38:39] op_sel_hi:[1,0]
	v_exp_f32_e32 v148, v148
	v_exp_f32_e32 v146, v146
	v_exp_f32_e32 v147, v147
	v_exp_f32_e32 v149, v149
	v_pk_add_f32 v[146:147], v[146:147], 1.0 op_sel_hi:[1,0]
	s_nop 0
	v_rcp_f32_e32 v165, v146
	v_rcp_f32_e32 v227, v147
	v_pk_add_f32 v[146:147], v[148:149], 1.0 op_sel_hi:[1,0]
	v_cvt_pk_bf16_f32 v148, v165, v227
	v_rcp_f32_e32 v149, v146
	v_rcp_f32_e32 v228, v147
	s_nop 0
	s_nop 0
	s_nop 0
	s_nop 0
	s_nop 0
	v_cvt_pk_bf16_f32 v146, v169, v173
	v_cvt_pk_bf16_f32 v147, v177, v181
	v_cvt_pk_bf16_f32 v149, v149, v228
	s_cbranch_vccnz .LBB0_1120
	s_mov_b64 s[62:63], 0
	global_store_dwordx4 v[254:255], v[146:149], off offset:-2048

.LBB0_1122:
	v_ashrrev_i32_e32 v146, 3, v158
	v_lshrrev_b32_e32 v147, 3, v158
	v_lshlrev_b32_e32 v148, 6, v158
	v_lshlrev_b32_e32 v149, 2, v158
	v_and_b32_e32 v165, 0xffffffe0, v146
	v_lshlrev_b32_e32 v146, 7, v158
	v_and_or_b32 v147, v147, 14, v187
	v_and_b32_e32 v148, 0x3c0, v148
	v_and_b32_e32 v149, 32, v149
	v_and_b32_e32 v146, 0x4000, v146
	v_lshlrev_b32_e32 v147, 10, v147
	v_bitop3_b32 v148, v148, v149, v157 bitop3:0x36
	v_or3_b32 v150, v147, v146, v148
	v_pk_fma_f32 v[146:147], v[30:31], v[160:161], v[142:143] op_sel_hi:[1,0,1]
	v_pk_fma_f32 v[148:149], v[32:33], v[160:161], v[144:145] op_sel_hi:[1,0,1]
	v_pk_mul_f32 v[146:147], v[146:147], s[38:39] op_sel_hi:[1,0]
	v_pk_mul_f32 v[148:149], v[148:149], s[38:39] op_sel_hi:[1,0]
	v_exp_f32_e32 v146, v146
	v_exp_f32_e32 v147, v147
	v_exp_f32_e32 v148, v148
	v_exp_f32_e32 v149, v149
	s_and_b64 vcc, exec, s[0:1]
	v_pk_add_f32 v[146:147], v[146:147], 1.0 op_sel_hi:[1,0]
	s_mov_b64 s[62:63], -1
	v_rcp_f32_e32 v161, v146
	v_rcp_f32_e32 v169, v147
	v_pk_add_f32 v[146:147], v[148:149], 1.0 op_sel_hi:[1,0]
	v_pk_fma_f32 v[148:149], v[28:29], v[160:161], v[140:141] op_sel_hi:[1,0,1]
	v_rcp_f32_e32 v173, v146
	v_rcp_f32_e32 v177, v147
	v_pk_fma_f32 v[146:147], v[26:27], v[160:161], v[138:139] op_sel_hi:[1,0,1]
	v_pk_mul_f32 v[148:149], v[148:149], s[38:39] op_sel_hi:[1,0]
	v_pk_mul_f32 v[146:147], v[146:147], s[38:39] op_sel_hi:[1,0]
	v_exp_f32_e32 v148, v148
	v_exp_f32_e32 v146, v146
	v_exp_f32_e32 v147, v147
	v_exp_f32_e32 v149, v149
	v_pk_add_f32 v[146:147], v[146:147], 1.0 op_sel_hi:[1,0]
	s_nop 0
	v_rcp_f32_e32 v181, v146
	v_rcp_f32_e32 v227, v147
	v_pk_add_f32 v[146:147], v[148:149], 1.0 op_sel_hi:[1,0]
	v_cvt_pk_bf16_f32 v148, v181, v227
	v_rcp_f32_e32 v149, v146
	v_rcp_f32_e32 v228, v147
	s_nop 0
	s_nop 0
	s_nop 0
	s_nop 0
	s_nop 0
	v_cvt_pk_bf16_f32 v146, v161, v169
	v_cvt_pk_bf16_f32 v147, v173, v177
	v_cvt_pk_bf16_f32 v149, v149, v228
	s_cbranch_vccnz .LBB0_1124
	s_mov_b64 s[62:63], 0
	global_store_dwordx4 v[252:253], v[146:149], off

.LBB0_1126:
	v_mov_b32_e32 v161, v160
	v_pk_fma_f32 v[146:147], v[22:23], v[160:161], v[134:135]
	v_pk_fma_f32 v[148:149], v[24:25], v[160:161], v[136:137]
	v_pk_mul_f32 v[146:147], v[146:147], s[38:39] op_sel_hi:[1,0]
	v_pk_mul_f32 v[148:149], v[148:149], s[38:39] op_sel_hi:[1,0]
	v_exp_f32_e32 v146, v146
	v_exp_f32_e32 v147, v147
	v_exp_f32_e32 v148, v148
	v_exp_f32_e32 v149, v149
	s_and_b64 vcc, exec, s[0:1]
	v_pk_add_f32 v[146:147], v[146:147], 1.0 op_sel_hi:[1,0]
	s_mov_b64 s[62:63], -1
	v_rcp_f32_e32 v169, v146
	v_rcp_f32_e32 v173, v147
	v_pk_add_f32 v[146:147], v[148:149], 1.0 op_sel_hi:[1,0]
	v_pk_fma_f32 v[148:149], v[20:21], v[160:161], v[132:133]
	v_rcp_f32_e32 v177, v146
	v_rcp_f32_e32 v181, v147
	v_pk_fma_f32 v[146:147], v[18:19], v[160:161], v[130:131]
	v_pk_mul_f32 v[148:149], v[148:149], s[38:39] op_sel_hi:[1,0]
	v_pk_mul_f32 v[146:147], v[146:147], s[38:39] op_sel_hi:[1,0]
	v_exp_f32_e32 v148, v148
	v_exp_f32_e32 v146, v146
	v_exp_f32_e32 v147, v147
	v_exp_f32_e32 v149, v149
	v_pk_add_f32 v[146:147], v[146:147], 1.0 op_sel_hi:[1,0]
	s_nop 0
	v_rcp_f32_e32 v161, v146
	v_rcp_f32_e32 v227, v147
	v_pk_add_f32 v[146:147], v[148:149], 1.0 op_sel_hi:[1,0]
	v_cvt_pk_bf16_f32 v148, v161, v227
	v_rcp_f32_e32 v149, v146
	v_rcp_f32_e32 v228, v147
	v_add_u32_e32 v146, v185, v165
	v_ashrrev_i32_e32 v147, 31, v146
	v_lshlrev_b64 v[146:147], 15, v[146:147]
	v_lshl_add_u64 v[146:147], s[80:81], 0, v[146:147]
	v_lshl_add_u64 v[208:209], v[146:147], 0, v[150:151]
	v_cvt_pk_bf16_f32 v146, v169, v173
	v_cvt_pk_bf16_f32 v147, v177, v181
	v_cvt_pk_bf16_f32 v149, v149, v228
	s_cbranch_vccnz .LBB0_1128
	s_mov_b64 s[62:63], 0
	global_store_dwordx4 v[254:255], v[146:149], off

.LBB0_1130:
	v_pk_fma_f32 v[142:143], v[14:15], v[156:157], v[142:143] op_sel_hi:[1,0,1]
	v_pk_fma_f32 v[138:139], v[10:11], v[156:157], v[138:139] op_sel_hi:[1,0,1]
	v_pk_mul_f32 v[142:143], v[142:143], s[38:39] op_sel_hi:[1,0]
	v_pk_fma_f32 v[144:145], v[16:17], v[156:157], v[144:145] op_sel_hi:[1,0,1]
	v_pk_mul_f32 v[138:139], v[138:139], s[38:39] op_sel_hi:[1,0]
	v_pk_fma_f32 v[140:141], v[12:13], v[156:157], v[140:141] op_sel_hi:[1,0,1]
	v_exp_f32_e32 v142, v142
	v_exp_f32_e32 v143, v143
	v_pk_mul_f32 v[144:145], v[144:145], s[38:39] op_sel_hi:[1,0]
	v_exp_f32_e32 v138, v138
	v_exp_f32_e32 v139, v139
	v_pk_mul_f32 v[140:141], v[140:141], s[38:39] op_sel_hi:[1,0]
	v_exp_f32_e32 v144, v144
	v_exp_f32_e32 v145, v145
	v_exp_f32_e32 v140, v140
	v_exp_f32_e32 v141, v141
	v_lshrrev_b32_e32 v148, 3, v154
	v_lshlrev_b32_e32 v149, 6, v154
	v_lshlrev_b32_e32 v150, 2, v154
	v_lshlrev_b32_e32 v147, 7, v154
	v_and_or_b32 v148, v148, 14, v187
	v_and_b32_e32 v149, 0x3c0, v149
	v_and_b32_e32 v150, 32, v150
	v_and_b32_e32 v147, 0x4000, v147
	v_lshlrev_b32_e32 v148, 10, v148
	v_bitop3_b32 v149, v149, v150, v157 bitop3:0x36
	v_pk_add_f32 v[142:143], v[142:143], 1.0 op_sel_hi:[1,0]
	v_pk_add_f32 v[138:139], v[138:139], 1.0 op_sel_hi:[1,0]
	v_or3_b32 v150, v148, v147, v149
	v_rcp_f32_e32 v147, v142
	v_rcp_f32_e32 v148, v143
	v_pk_add_f32 v[142:143], v[144:145], 1.0 op_sel_hi:[1,0]
	v_rcp_f32_e32 v149, v138
	v_rcp_f32_e32 v157, v139
	v_pk_add_f32 v[138:139], v[140:141], 1.0 op_sel_hi:[1,0]
	v_rcp_f32_e32 v144, v142
	v_rcp_f32_e32 v145, v143
	v_rcp_f32_e32 v141, v138
	v_rcp_f32_e32 v161, v139
	s_nop 0
	s_nop 0
	s_nop 0
	s_nop 0
	s_nop 0
	v_cvt_pk_bf16_f32 v138, v147, v148
	v_cvt_pk_bf16_f32 v139, v144, v145
	v_cvt_pk_bf16_f32 v140, v149, v157
	v_cvt_pk_bf16_f32 v141, v141, v161
	s_and_b64 vcc, exec, s[0:1]
	s_mov_b64 s[62:63], -1
	s_cbranch_vccnz .LBB0_1132
	s_mov_b64 s[62:63], 0
	global_store_dwordx4 v[252:253], v[138:141], off offset:2048
.LBB0_1132:
	s_andn2_b64 vcc, exec, s[62:63]
	s_cbranch_vccnz .LBB0_1134
	global_store_dwordx4 v[252:253], v[138:141], off offset:2048 sc1
	s_nop 1
.LBB0_1134:
	v_mov_b32_e32 v157, v156
	v_pk_fma_f32 v[134:135], v[6:7], v[156:157], v[134:135]
	v_pk_fma_f32 v[130:131], v[2:3], v[156:157], v[130:131]
	v_pk_mul_f32 v[134:135], v[134:135], s[38:39] op_sel_hi:[1,0]
	v_pk_fma_f32 v[136:137], v[8:9], v[156:157], v[136:137]
	v_pk_mul_f32 v[130:131], v[130:131], s[38:39] op_sel_hi:[1,0]
	v_pk_fma_f32 v[132:133], v[4:5], v[156:157], v[132:133]
	v_exp_f32_e32 v134, v134
	v_exp_f32_e32 v135, v135
	v_pk_mul_f32 v[136:137], v[136:137], s[38:39] op_sel_hi:[1,0]
	v_exp_f32_e32 v130, v130
	v_exp_f32_e32 v131, v131
	v_pk_mul_f32 v[132:133], v[132:133], s[38:39] op_sel_hi:[1,0]
	v_exp_f32_e32 v136, v136
	v_exp_f32_e32 v137, v137
	v_exp_f32_e32 v132, v132
	v_exp_f32_e32 v133, v133
	v_pk_add_f32 v[134:135], v[134:135], 1.0 op_sel_hi:[1,0]
	v_pk_add_f32 v[130:131], v[130:131], 1.0 op_sel_hi:[1,0]
	v_rcp_f32_e32 v138, v134
	v_rcp_f32_e32 v139, v135
	v_pk_add_f32 v[134:135], v[136:137], 1.0 op_sel_hi:[1,0]
	v_rcp_f32_e32 v140, v130
	v_rcp_f32_e32 v141, v131
	v_pk_add_f32 v[130:131], v[132:133], 1.0 op_sel_hi:[1,0]
	v_rcp_f32_e32 v136, v134
	v_rcp_f32_e32 v137, v135
	v_rcp_f32_e32 v133, v130
	v_rcp_f32_e32 v142, v131
	s_nop 0
	s_nop 0
	s_nop 0
	s_nop 0
	s_nop 0
	v_cvt_pk_bf16_f32 v130, v138, v139
	v_cvt_pk_bf16_f32 v131, v136, v137
	v_cvt_pk_bf16_f32 v132, v140, v141
	v_cvt_pk_bf16_f32 v133, v133, v142
	s_and_b64 vcc, exec, s[0:1]
	s_mov_b64 s[0:1], -1
	s_cbranch_vccnz .LBB0_1136
	s_mov_b64 s[0:1], 0
	global_store_dwordx4 v[254:255], v[130:133], off offset:2048

.LBB0_1139:
	s_and_b64 vcc, exec, s[0:1]
	s_cbranch_vccz .LBB0_1157
	v_pk_mul_f32 v[130:131], v[126:127], v[184:185] op_sel_hi:[1,0]
	v_lshlrev_b64 v[134:135], 10, v[182:183]
	v_pk_mul_f32 v[132:133], v[130:131], v[130:131]
	v_ashrrev_i32_e32 v187, 31, v186
	v_pk_fma_f32 v[132:133], v[132:133], s[40:41], 1.0 op_sel_hi:[1,0,0]
	v_lshl_add_u64 v[134:135], s[14:15], 0, v[134:135]
	v_pk_mul_f32 v[132:133], v[130:131], v[132:133]
	v_lshl_add_u64 v[134:135], v[186:187], 1, v[134:135]
	v_pk_mul_f32 v[132:133], v[132:133], s[42:43] op_sel_hi:[1,0]
	s_lshl_b32 s0, s51, 3
	v_pk_mul_f32 v[132:133], v[132:133], s[38:39] op_sel_hi:[1,0]
	v_readlane_b32 s1, v249, 40
	v_exp_f32_e32 v132, v132
	v_exp_f32_e32 v133, v133
	s_add_i32 s0, s1, s0
	v_cmp_eq_u32_e32 vcc, 0, v225
	s_ashr_i32 s1, s0, 31
	v_pk_add_f32 v[132:133], v[132:133], 1.0 op_sel_hi:[1,0]
	s_nop 0
	v_rcp_f32_e32 v132, v132
	v_rcp_f32_e32 v133, v133
	s_nop 0
	v_pk_mul_f32 v[130:131], v[130:131], v[132:133]
	v_pk_mul_f32 v[132:133], v[128:129], v[184:185] op_sel_hi:[1,0]
	v_mov_b32_e32 v139, v131
	v_pk_mul_f32 v[136:137], v[132:133], v[132:133]
	s_nop 0
	v_pk_fma_f32 v[136:137], v[136:137], s[40:41], 1.0 op_sel_hi:[1,0,0]
	s_nop 0
	v_pk_mul_f32 v[136:137], v[132:133], v[136:137]
	s_nop 0
	v_pk_mul_f32 v[136:137], v[136:137], s[42:43] op_sel_hi:[1,0]
	s_nop 0
	v_pk_mul_f32 v[136:137], v[136:137], s[38:39] op_sel_hi:[1,0]
	s_nop 0
	v_exp_f32_e32 v136, v136
	v_exp_f32_e32 v137, v137
	s_nop 0
	v_pk_add_f32 v[136:137], v[136:137], 1.0 op_sel_hi:[1,0]
	s_nop 0
	v_rcp_f32_e32 v136, v136
	v_rcp_f32_e32 v137, v137
	s_nop 0
	v_pk_mul_f32 v[132:133], v[132:133], v[136:137]
	s_nop 0
	v_mov_b32_e32 v136, v132
	v_mov_b32_e32 v137, v130
	v_mov_b32_e32 v138, v133
	v_pk_add_f32 v[136:137], v[136:137], v[138:139]
	v_mov_b32_e32 v138, v131
	v_add_f32_e32 v137, 0, v137
	v_mov_b32_e32 v139, v133
	v_add_f32_e32 v148, v136, v137
	v_mov_b32_e32 v136, v130
	v_mov_b32_e32 v137, v132
	v_pk_mul_f32 v[138:139], v[138:139], v[138:139]
	v_cvt_pk_bf16_f32 v130, v130, v131
	v_pk_fma_f32 v[136:137], v[136:137], v[136:137], v[138:139]
	v_pk_mul_f32 v[138:139], v[122:123], v[184:185] op_sel_hi:[1,0]
	v_cvt_pk_bf16_f32 v131, v132, v133
	v_pk_mul_f32 v[140:141], v[138:139], v[138:139]
	v_pk_add_f32 v[136:137], v[136:137], v[136:137] op_sel:[0,1] op_sel_hi:[1,0]
	v_pk_fma_f32 v[140:141], v[140:141], s[40:41], 1.0 op_sel_hi:[1,0,0]
	s_nop 0
	v_pk_mul_f32 v[140:141], v[138:139], v[140:141]
	s_nop 0
	v_pk_mul_f32 v[140:141], v[140:141], s[42:43] op_sel_hi:[1,0]
	s_nop 0
	v_pk_mul_f32 v[140:141], v[140:141], s[38:39] op_sel_hi:[1,0]
	s_nop 0
	v_exp_f32_e32 v140, v140
	v_exp_f32_e32 v141, v141
	s_nop 0
	v_pk_add_f32 v[140:141], v[140:141], 1.0 op_sel_hi:[1,0]
	s_nop 0
	v_rcp_f32_e32 v140, v140
	v_rcp_f32_e32 v141, v141
	s_nop 0
	v_pk_mul_f32 v[138:139], v[138:139], v[140:141]
	v_pk_mul_f32 v[140:141], v[124:125], v[184:185] op_sel_hi:[1,0]
	v_cvt_pk_bf16_f32 v132, v138, v139
	v_pk_mul_f32 v[142:143], v[140:141], v[140:141]
	v_mov_b32_e32 v145, v139
	v_pk_fma_f32 v[142:143], v[142:143], s[40:41], 1.0 op_sel_hi:[1,0,0]
	s_nop 0
	v_pk_mul_f32 v[142:143], v[140:141], v[142:143]
	s_nop 0
	v_pk_mul_f32 v[142:143], v[142:143], s[42:43] op_sel_hi:[1,0]
	s_nop 0
	v_pk_mul_f32 v[142:143], v[142:143], s[38:39] op_sel_hi:[1,0]
	s_nop 0
	v_exp_f32_e32 v142, v142
	v_exp_f32_e32 v143, v143
	s_nop 0
	v_pk_add_f32 v[142:143], v[142:143], 1.0 op_sel_hi:[1,0]
	s_nop 0
	v_rcp_f32_e32 v142, v142
	v_rcp_f32_e32 v143, v143
	s_nop 0
	v_pk_mul_f32 v[140:141], v[140:141], v[142:143]
	s_nop 0
	v_cvt_pk_bf16_f32 v133, v140, v141
	v_lshl_add_u64 v[250:251], v[134:135], 0, 0
	global_store_dwordx4 v[134:135], v[130:133], off
	v_mov_b32_e32 v143, v138
	v_mov_b32_e32 v142, v140
	v_pk_mul_f32 v[130:131], v[118:119], v[184:185] op_sel_hi:[1,0]
	v_mov_b32_e32 v144, v141
	v_pk_mul_f32 v[132:133], v[130:131], v[130:131]
	v_pk_add_f32 v[146:147], v[142:143], v[144:145]
	v_pk_fma_f32 v[132:133], v[132:133], s[40:41], 1.0 op_sel_hi:[1,0,0]
	v_pk_mul_f32 v[144:145], v[144:145], v[144:145]
	v_pk_mul_f32 v[132:133], v[130:131], v[132:133]
	v_pk_fma_f32 v[142:143], v[142:143], v[142:143], v[144:145]
	v_pk_mul_f32 v[132:133], v[132:133], s[42:43] op_sel_hi:[1,0]
	v_pk_add_f32 v[136:137], v[142:143], v[136:137] op_sel:[1,0] op_sel_hi:[0,1]
	v_pk_mul_f32 v[132:133], v[132:133], s[38:39] op_sel_hi:[1,0]
	v_pk_add_f32 v[136:137], v[142:143], v[136:137]
	v_exp_f32_e32 v132, v132
	v_exp_f32_e32 v133, v133
	v_add_f32_e32 v147, v147, v148
	v_add_f32_e32 v146, v146, v147
	v_pk_add_f32 v[132:133], v[132:133], 1.0 op_sel_hi:[1,0]
	s_nop 0
	v_rcp_f32_e32 v132, v132
	v_rcp_f32_e32 v133, v133
	s_nop 0
	v_pk_mul_f32 v[130:131], v[130:131], v[132:133]
	v_pk_mul_f32 v[132:133], v[120:121], v[184:185] op_sel_hi:[1,0]
	v_mov_b32_e32 v141, v131
	v_pk_mul_f32 v[138:139], v[132:133], v[132:133]
	s_nop 0
	v_pk_fma_f32 v[138:139], v[138:139], s[40:41], 1.0 op_sel_hi:[1,0,0]
	s_nop 0
	v_pk_mul_f32 v[138:139], v[132:133], v[138:139]
	s_nop 0
	v_pk_mul_f32 v[138:139], v[138:139], s[42:43] op_sel_hi:[1,0]
	s_nop 0
	v_pk_mul_f32 v[138:139], v[138:139], s[38:39] op_sel_hi:[1,0]
	s_nop 0
	v_exp_f32_e32 v138, v138
	v_exp_f32_e32 v139, v139
	s_nop 0
	v_pk_add_f32 v[138:139], v[138:139], 1.0 op_sel_hi:[1,0]
	s_nop 0
	v_rcp_f32_e32 v138, v138
	v_rcp_f32_e32 v139, v139
	s_nop 0
	v_pk_mul_f32 v[132:133], v[132:133], v[138:139]
	s_nop 0
	v_mov_b32_e32 v138, v132
	v_mov_b32_e32 v139, v130
	v_mov_b32_e32 v140, v133
	v_pk_add_f32 v[142:143], v[138:139], v[140:141]
	v_pk_mul_f32 v[140:141], v[140:141], v[140:141]
	v_add_f32_e32 v143, v143, v146
	v_pk_fma_f32 v[138:139], v[138:139], v[138:139], v[140:141]
	v_pk_mul_f32 v[146:147], v[116:117], v[184:185] op_sel_hi:[1,0]
	v_pk_add_f32 v[136:137], v[138:139], v[136:137] op_sel:[1,0] op_sel_hi:[0,1]
	v_pk_add_f32 v[136:137], v[138:139], v[136:137]
	v_pk_mul_f32 v[138:139], v[114:115], v[184:185] op_sel_hi:[1,0]
	v_pk_mul_f32 v[148:149], v[146:147], v[146:147]
	v_pk_mul_f32 v[140:141], v[138:139], v[138:139]
	v_pk_fma_f32 v[148:149], v[148:149], s[40:41], 1.0 op_sel_hi:[1,0,0]
	v_pk_fma_f32 v[140:141], v[140:141], s[40:41], 1.0 op_sel_hi:[1,0,0]
	v_pk_mul_f32 v[148:149], v[146:147], v[148:149]
	v_pk_mul_f32 v[140:141], v[138:139], v[140:141]
	v_pk_mul_f32 v[148:149], v[148:149], s[42:43] op_sel_hi:[1,0]
	v_pk_mul_f32 v[140:141], v[140:141], s[42:43] op_sel_hi:[1,0]
	v_pk_mul_f32 v[148:149], v[148:149], s[38:39] op_sel_hi:[1,0]
	v_pk_mul_f32 v[140:141], v[140:141], s[38:39] op_sel_hi:[1,0]
	v_exp_f32_e32 v148, v148
	v_exp_f32_e32 v140, v140
	v_exp_f32_e32 v141, v141
	v_exp_f32_e32 v149, v149
	v_cvt_pk_bf16_f32 v130, v130, v131
	v_cvt_pk_bf16_f32 v131, v132, v133
	v_pk_add_f32 v[140:141], v[140:141], 1.0 op_sel_hi:[1,0]
	v_pk_add_f32 v[148:149], v[148:149], 1.0 op_sel_hi:[1,0]
	v_rcp_f32_e32 v140, v140
	v_rcp_f32_e32 v141, v141
	v_rcp_f32_e32 v148, v148
	v_rcp_f32_e32 v149, v149
	v_add_f32_e32 v142, v142, v143
	v_pk_mul_f32 v[144:145], v[138:139], v[140:141]
	v_pk_mul_f32 v[146:147], v[146:147], v[148:149]
	v_pk_fma_f32 v[138:139], v[138:139], v[140:141], v[144:145] op_sel:[0,0,1] op_sel_hi:[1,1,0]
	v_mul_f32_e32 v140, v144, v144
	v_pk_fma_f32 v[140:141], v[144:145], v[144:145], v[140:141] op_sel_hi:[1,1,0]
	v_pk_mul_f32 v[148:149], v[146:147], v[146:147]
	v_cvt_pk_bf16_f32 v132, v144, v145
	v_cvt_pk_bf16_f32 v133, v146, v147
	s_mov_b32 s98, 0x1000
	s_mov_b32 s99, 0x0
	v_lshl_add_u64 v[252:253], v[250:251], 0, s[98:99]
	global_store_dwordx4 v[252:253], v[130:133], off offset:-3840
	v_mov_b32_e32 v140, v146
	v_mov_b32_e32 v139, v148
	v_pk_mov_b32 v[130:131], v[146:147], v[136:137] op_sel:[1,0]
	v_mov_b32_e32 v143, v149
	v_pk_add_f32 v[130:131], v[140:141], v[130:131]
	v_pk_add_f32 v[132:133], v[138:139], v[142:143]
	s_nop 0
	v_pk_add_f32 v[130:131], v[132:133], v[130:131]
	ds_bpermute_b32 v132, v223, v130
	ds_bpermute_b32 v133, v223, v131
	s_waitcnt lgkmcnt(0)
	v_pk_add_f32 v[130:131], v[130:131], v[132:133]
	ds_bpermute_b32 v132, v224, v130
	ds_bpermute_b32 v133, v224, v131
	s_and_saveexec_b64 s[62:63], vcc
	s_cbranch_execz .LBB0_1142
	v_lshl_add_u64 v[134:135], s[82:83], 0, v[206:207]
	v_lshl_add_u64 v[134:135], s[0:1], 2, v[134:135]
	s_waitcnt lgkmcnt(0)
	v_pk_add_f32 v[130:131], v[130:131], v[132:133]
	global_store_dwordx2 v[134:135], v[130:131], off
.LBB0_1142:
	s_or_b64 exec, exec, s[62:63]
	v_pk_mul_f32 v[130:131], v[110:111], v[180:181] op_sel_hi:[1,0]
	v_lshlrev_b64 v[134:135], 10, v[178:179]
	s_waitcnt lgkmcnt(0)
	v_pk_mul_f32 v[132:133], v[130:131], v[130:131]
	v_lshl_add_u64 v[134:135], s[14:15], 0, v[134:135]
	v_pk_fma_f32 v[132:133], v[132:133], s[40:41], 1.0 op_sel_hi:[1,0,0]
	v_lshl_add_u64 v[134:135], v[186:187], 1, v[134:135]
	v_pk_mul_f32 v[132:133], v[130:131], v[132:133]
	s_nop 0
	v_pk_mul_f32 v[132:133], v[132:133], s[42:43] op_sel_hi:[1,0]
	s_nop 0
	v_pk_mul_f32 v[132:133], v[132:133], s[38:39] op_sel_hi:[1,0]
	s_nop 0
	v_exp_f32_e32 v132, v132
	v_exp_f32_e32 v133, v133
	s_nop 0
	v_pk_add_f32 v[132:133], v[132:133], 1.0 op_sel_hi:[1,0]
	s_nop 0
	v_rcp_f32_e32 v132, v132
	v_rcp_f32_e32 v133, v133
	s_nop 0
	v_pk_mul_f32 v[130:131], v[130:131], v[132:133]
	v_pk_mul_f32 v[132:133], v[112:113], v[180:181] op_sel_hi:[1,0]
	v_mov_b32_e32 v139, v131
	v_pk_mul_f32 v[136:137], v[132:133], v[132:133]
	s_nop 0
	v_pk_fma_f32 v[136:137], v[136:137], s[40:41], 1.0 op_sel_hi:[1,0,0]
	s_nop 0
	v_pk_mul_f32 v[136:137], v[132:133], v[136:137]
	s_nop 0
	v_pk_mul_f32 v[136:137], v[136:137], s[42:43] op_sel_hi:[1,0]
	s_nop 0
	v_pk_mul_f32 v[136:137], v[136:137], s[38:39] op_sel_hi:[1,0]
	s_nop 0
	v_exp_f32_e32 v136, v136
	v_exp_f32_e32 v137, v137
	s_nop 0
	v_pk_add_f32 v[136:137], v[136:137], 1.0 op_sel_hi:[1,0]
	s_nop 0
	v_rcp_f32_e32 v136, v136
	v_rcp_f32_e32 v137, v137
	s_nop 0
	v_pk_mul_f32 v[132:133], v[132:133], v[136:137]
	s_nop 0
	v_mov_b32_e32 v136, v132
	v_mov_b32_e32 v137, v130
	v_mov_b32_e32 v138, v133
	v_pk_add_f32 v[136:137], v[136:137], v[138:139]
	v_mov_b32_e32 v138, v131
	v_add_f32_e32 v137, 0, v137
	v_mov_b32_e32 v139, v133
	v_add_f32_e32 v148, v136, v137
	v_mov_b32_e32 v136, v130
	v_mov_b32_e32 v137, v132
	v_pk_mul_f32 v[138:139], v[138:139], v[138:139]
	v_cvt_pk_bf16_f32 v130, v130, v131
	v_pk_fma_f32 v[136:137], v[136:137], v[136:137], v[138:139]
	v_pk_mul_f32 v[138:139], v[106:107], v[180:181] op_sel_hi:[1,0]
	v_cvt_pk_bf16_f32 v131, v132, v133
	v_pk_mul_f32 v[140:141], v[138:139], v[138:139]
	v_pk_add_f32 v[136:137], v[136:137], v[136:137] op_sel:[0,1] op_sel_hi:[1,0]
	v_pk_fma_f32 v[140:141], v[140:141], s[40:41], 1.0 op_sel_hi:[1,0,0]
	s_nop 0
	v_pk_mul_f32 v[140:141], v[138:139], v[140:141]
	s_nop 0
	v_pk_mul_f32 v[140:141], v[140:141], s[42:43] op_sel_hi:[1,0]
	s_nop 0
	v_pk_mul_f32 v[140:141], v[140:141], s[38:39] op_sel_hi:[1,0]
	s_nop 0
	v_exp_f32_e32 v140, v140
	v_exp_f32_e32 v141, v141
	s_nop 0
	v_pk_add_f32 v[140:141], v[140:141], 1.0 op_sel_hi:[1,0]
	s_nop 0
	v_rcp_f32_e32 v140, v140
	v_rcp_f32_e32 v141, v141
	s_nop 0
	v_pk_mul_f32 v[138:139], v[138:139], v[140:141]
	v_pk_mul_f32 v[140:141], v[108:109], v[180:181] op_sel_hi:[1,0]
	v_cvt_pk_bf16_f32 v132, v138, v139
	v_pk_mul_f32 v[142:143], v[140:141], v[140:141]
	v_mov_b32_e32 v145, v139
	v_pk_fma_f32 v[142:143], v[142:143], s[40:41], 1.0 op_sel_hi:[1,0,0]
	s_nop 0
	v_pk_mul_f32 v[142:143], v[140:141], v[142:143]
	s_nop 0
	v_pk_mul_f32 v[142:143], v[142:143], s[42:43] op_sel_hi:[1,0]
	s_nop 0
	v_pk_mul_f32 v[142:143], v[142:143], s[38:39] op_sel_hi:[1,0]
	s_nop 0
	v_exp_f32_e32 v142, v142
	v_exp_f32_e32 v143, v143
	s_nop 0
	v_pk_add_f32 v[142:143], v[142:143], 1.0 op_sel_hi:[1,0]
	s_nop 0
	v_rcp_f32_e32 v142, v142
	v_rcp_f32_e32 v143, v143
	s_nop 0
	v_pk_mul_f32 v[140:141], v[140:141], v[142:143]
	s_nop 0
	v_cvt_pk_bf16_f32 v133, v140, v141
	s_mov_b32 s98, 0x5000
	s_mov_b32 s99, 0x0
	v_lshl_add_u64 v[252:253], v[250:251], 0, s[98:99]
	global_store_dwordx4 v[252:253], v[130:133], off offset:-4096
	v_mov_b32_e32 v143, v138
	v_mov_b32_e32 v142, v140
	v_pk_mul_f32 v[130:131], v[102:103], v[180:181] op_sel_hi:[1,0]
	v_mov_b32_e32 v144, v141
	v_pk_mul_f32 v[132:133], v[130:131], v[130:131]
	v_pk_add_f32 v[146:147], v[142:143], v[144:145]
	v_pk_fma_f32 v[132:133], v[132:133], s[40:41], 1.0 op_sel_hi:[1,0,0]
	v_pk_mul_f32 v[144:145], v[144:145], v[144:145]
	v_pk_mul_f32 v[132:133], v[130:131], v[132:133]
	v_pk_fma_f32 v[142:143], v[142:143], v[142:143], v[144:145]
	v_pk_mul_f32 v[132:133], v[132:133], s[42:43] op_sel_hi:[1,0]
	v_pk_add_f32 v[136:137], v[142:143], v[136:137] op_sel:[1,0] op_sel_hi:[0,1]
	v_pk_mul_f32 v[132:133], v[132:133], s[38:39] op_sel_hi:[1,0]
	v_pk_add_f32 v[136:137], v[142:143], v[136:137]
	v_exp_f32_e32 v132, v132
	v_exp_f32_e32 v133, v133
	v_add_f32_e32 v147, v147, v148
	v_add_f32_e32 v146, v146, v147
	v_pk_add_f32 v[132:133], v[132:133], 1.0 op_sel_hi:[1,0]
	s_nop 0
	v_rcp_f32_e32 v132, v132
	v_rcp_f32_e32 v133, v133
	s_nop 0
	v_pk_mul_f32 v[130:131], v[130:131], v[132:133]
	v_pk_mul_f32 v[132:133], v[104:105], v[180:181] op_sel_hi:[1,0]
	v_mov_b32_e32 v141, v131
	v_pk_mul_f32 v[138:139], v[132:133], v[132:133]
	s_nop 0
	v_pk_fma_f32 v[138:139], v[138:139], s[40:41], 1.0 op_sel_hi:[1,0,0]
	s_nop 0
	v_pk_mul_f32 v[138:139], v[132:133], v[138:139]
	s_nop 0
	v_pk_mul_f32 v[138:139], v[138:139], s[42:43] op_sel_hi:[1,0]
	s_nop 0
	v_pk_mul_f32 v[138:139], v[138:139], s[38:39] op_sel_hi:[1,0]
	s_nop 0
	v_exp_f32_e32 v138, v138
	v_exp_f32_e32 v139, v139
	s_nop 0
	v_pk_add_f32 v[138:139], v[138:139], 1.0 op_sel_hi:[1,0]
	s_nop 0
	v_rcp_f32_e32 v138, v138
	v_rcp_f32_e32 v139, v139
	s_nop 0
	v_pk_mul_f32 v[132:133], v[132:133], v[138:139]
	s_nop 0
	v_mov_b32_e32 v138, v132
	v_mov_b32_e32 v139, v130
	v_mov_b32_e32 v140, v133
	v_pk_add_f32 v[142:143], v[138:139], v[140:141]
	v_pk_mul_f32 v[140:141], v[140:141], v[140:141]
	v_add_f32_e32 v143, v143, v146
	v_pk_fma_f32 v[138:139], v[138:139], v[138:139], v[140:141]
	v_pk_mul_f32 v[146:147], v[100:101], v[180:181] op_sel_hi:[1,0]
	v_pk_add_f32 v[136:137], v[138:139], v[136:137] op_sel:[1,0] op_sel_hi:[0,1]
	v_pk_add_f32 v[136:137], v[138:139], v[136:137]
	v_pk_mul_f32 v[138:139], v[98:99], v[180:181] op_sel_hi:[1,0]
	v_pk_mul_f32 v[148:149], v[146:147], v[146:147]
	v_pk_mul_f32 v[140:141], v[138:139], v[138:139]
	v_pk_fma_f32 v[148:149], v[148:149], s[40:41], 1.0 op_sel_hi:[1,0,0]
	v_pk_fma_f32 v[140:141], v[140:141], s[40:41], 1.0 op_sel_hi:[1,0,0]
	v_pk_mul_f32 v[148:149], v[146:147], v[148:149]
	v_pk_mul_f32 v[140:141], v[138:139], v[140:141]
	v_pk_mul_f32 v[148:149], v[148:149], s[42:43] op_sel_hi:[1,0]
	v_pk_mul_f32 v[140:141], v[140:141], s[42:43] op_sel_hi:[1,0]
	v_pk_mul_f32 v[148:149], v[148:149], s[38:39] op_sel_hi:[1,0]
	v_pk_mul_f32 v[140:141], v[140:141], s[38:39] op_sel_hi:[1,0]
	v_exp_f32_e32 v148, v148
	v_exp_f32_e32 v140, v140
	v_exp_f32_e32 v141, v141
	v_exp_f32_e32 v149, v149
	v_cvt_pk_bf16_f32 v130, v130, v131
	v_cvt_pk_bf16_f32 v131, v132, v133
	v_pk_add_f32 v[140:141], v[140:141], 1.0 op_sel_hi:[1,0]
	v_pk_add_f32 v[148:149], v[148:149], 1.0 op_sel_hi:[1,0]
	v_rcp_f32_e32 v140, v140
	v_rcp_f32_e32 v141, v141
	v_rcp_f32_e32 v148, v148
	v_rcp_f32_e32 v149, v149
	v_add_f32_e32 v142, v142, v143
	v_pk_mul_f32 v[144:145], v[138:139], v[140:141]
	v_pk_mul_f32 v[146:147], v[146:147], v[148:149]
	v_pk_fma_f32 v[138:139], v[138:139], v[140:141], v[144:145] op_sel:[0,0,1] op_sel_hi:[1,1,0]
	v_mul_f32_e32 v140, v144, v144
	v_pk_fma_f32 v[140:141], v[144:145], v[144:145], v[140:141] op_sel_hi:[1,1,0]
	v_pk_mul_f32 v[148:149], v[146:147], v[146:147]
	v_cvt_pk_bf16_f32 v132, v144, v145
	v_cvt_pk_bf16_f32 v133, v146, v147
	global_store_dwordx4 v[252:253], v[130:133], off offset:-3840
	v_mov_b32_e32 v140, v146
	v_mov_b32_e32 v139, v148
	v_pk_mov_b32 v[130:131], v[146:147], v[136:137] op_sel:[1,0]
	v_mov_b32_e32 v143, v149
	v_pk_add_f32 v[130:131], v[140:141], v[130:131]
	v_pk_add_f32 v[132:133], v[138:139], v[142:143]
	s_nop 0
	v_pk_add_f32 v[130:131], v[132:133], v[130:131]
	ds_bpermute_b32 v132, v223, v130
	ds_bpermute_b32 v133, v223, v131
	s_waitcnt lgkmcnt(0)
	v_pk_add_f32 v[130:131], v[130:131], v[132:133]
	ds_bpermute_b32 v132, v224, v130
	ds_bpermute_b32 v133, v224, v131
	s_and_saveexec_b64 s[62:63], vcc
	s_cbranch_execz .LBB0_1144
	v_lshl_add_u64 v[134:135], s[82:83], 0, v[204:205]
	v_lshl_add_u64 v[134:135], s[0:1], 2, v[134:135]
	s_waitcnt lgkmcnt(0)
	v_pk_add_f32 v[130:131], v[130:131], v[132:133]
	global_store_dwordx2 v[134:135], v[130:131], off
.LBB0_1144:
	s_or_b64 exec, exec, s[62:63]
	v_pk_mul_f32 v[130:131], v[94:95], v[176:177] op_sel_hi:[1,0]
	v_lshlrev_b64 v[134:135], 10, v[174:175]
	s_waitcnt lgkmcnt(0)
	v_pk_mul_f32 v[132:133], v[130:131], v[130:131]
	v_lshl_add_u64 v[134:135], s[14:15], 0, v[134:135]
	v_pk_fma_f32 v[132:133], v[132:133], s[40:41], 1.0 op_sel_hi:[1,0,0]
	v_lshl_add_u64 v[134:135], v[186:187], 1, v[134:135]
	v_pk_mul_f32 v[132:133], v[130:131], v[132:133]
	s_nop 0
	v_pk_mul_f32 v[132:133], v[132:133], s[42:43] op_sel_hi:[1,0]
	s_nop 0
	v_pk_mul_f32 v[132:133], v[132:133], s[38:39] op_sel_hi:[1,0]
	s_nop 0
	v_exp_f32_e32 v132, v132
	v_exp_f32_e32 v133, v133
	s_nop 0
	v_pk_add_f32 v[132:133], v[132:133], 1.0 op_sel_hi:[1,0]
	s_nop 0
	v_rcp_f32_e32 v132, v132
	v_rcp_f32_e32 v133, v133
	s_nop 0
	v_pk_mul_f32 v[130:131], v[130:131], v[132:133]
	v_pk_mul_f32 v[132:133], v[96:97], v[176:177] op_sel_hi:[1,0]
	v_mov_b32_e32 v139, v131
	v_pk_mul_f32 v[136:137], v[132:133], v[132:133]
	s_nop 0
	v_pk_fma_f32 v[136:137], v[136:137], s[40:41], 1.0 op_sel_hi:[1,0,0]
	s_nop 0
	v_pk_mul_f32 v[136:137], v[132:133], v[136:137]
	s_nop 0
	v_pk_mul_f32 v[136:137], v[136:137], s[42:43] op_sel_hi:[1,0]
	s_nop 0
	v_pk_mul_f32 v[136:137], v[136:137], s[38:39] op_sel_hi:[1,0]
	s_nop 0
	v_exp_f32_e32 v136, v136
	v_exp_f32_e32 v137, v137
	s_nop 0
	v_pk_add_f32 v[136:137], v[136:137], 1.0 op_sel_hi:[1,0]
	s_nop 0
	v_rcp_f32_e32 v136, v136
	v_rcp_f32_e32 v137, v137
	s_nop 0
	v_pk_mul_f32 v[132:133], v[132:133], v[136:137]
	s_nop 0
	v_mov_b32_e32 v136, v132
	v_mov_b32_e32 v137, v130
	v_mov_b32_e32 v138, v133
	v_pk_add_f32 v[136:137], v[136:137], v[138:139]
	v_mov_b32_e32 v138, v131
	v_add_f32_e32 v137, 0, v137
	v_mov_b32_e32 v139, v133
	v_add_f32_e32 v148, v136, v137
	v_mov_b32_e32 v136, v130
	v_mov_b32_e32 v137, v132
	v_pk_mul_f32 v[138:139], v[138:139], v[138:139]
	v_cvt_pk_bf16_f32 v130, v130, v131
	v_pk_fma_f32 v[136:137], v[136:137], v[136:137], v[138:139]
	v_pk_mul_f32 v[138:139], v[90:91], v[176:177] op_sel_hi:[1,0]
	v_cvt_pk_bf16_f32 v131, v132, v133
	v_pk_mul_f32 v[140:141], v[138:139], v[138:139]
	v_pk_add_f32 v[136:137], v[136:137], v[136:137] op_sel:[0,1] op_sel_hi:[1,0]
	v_pk_fma_f32 v[140:141], v[140:141], s[40:41], 1.0 op_sel_hi:[1,0,0]
	s_nop 0
	v_pk_mul_f32 v[140:141], v[138:139], v[140:141]
	s_nop 0
	v_pk_mul_f32 v[140:141], v[140:141], s[42:43] op_sel_hi:[1,0]
	s_nop 0
	v_pk_mul_f32 v[140:141], v[140:141], s[38:39] op_sel_hi:[1,0]
	s_nop 0
	v_exp_f32_e32 v140, v140
	v_exp_f32_e32 v141, v141
	s_nop 0
	v_pk_add_f32 v[140:141], v[140:141], 1.0 op_sel_hi:[1,0]
	s_nop 0
	v_rcp_f32_e32 v140, v140
	v_rcp_f32_e32 v141, v141
	s_nop 0
	v_pk_mul_f32 v[138:139], v[138:139], v[140:141]
	v_pk_mul_f32 v[140:141], v[92:93], v[176:177] op_sel_hi:[1,0]
	v_cvt_pk_bf16_f32 v132, v138, v139
	v_pk_mul_f32 v[142:143], v[140:141], v[140:141]
	v_mov_b32_e32 v145, v139
	v_pk_fma_f32 v[142:143], v[142:143], s[40:41], 1.0 op_sel_hi:[1,0,0]
	s_nop 0
	v_pk_mul_f32 v[142:143], v[140:141], v[142:143]
	s_nop 0
	v_pk_mul_f32 v[142:143], v[142:143], s[42:43] op_sel_hi:[1,0]
	s_nop 0
	v_pk_mul_f32 v[142:143], v[142:143], s[38:39] op_sel_hi:[1,0]
	s_nop 0
	v_exp_f32_e32 v142, v142
	v_exp_f32_e32 v143, v143
	s_nop 0
	v_pk_add_f32 v[142:143], v[142:143], 1.0 op_sel_hi:[1,0]
	s_nop 0
	v_rcp_f32_e32 v142, v142
	v_rcp_f32_e32 v143, v143
	s_nop 0
	v_pk_mul_f32 v[140:141], v[140:141], v[142:143]
	s_nop 0
	v_cvt_pk_bf16_f32 v133, v140, v141
	s_mov_b32 s98, 0x9000
	s_mov_b32 s99, 0x0
	v_lshl_add_u64 v[252:253], v[250:251], 0, s[98:99]
	global_store_dwordx4 v[252:253], v[130:133], off offset:-4096
	v_mov_b32_e32 v143, v138
	v_mov_b32_e32 v142, v140
	v_pk_mul_f32 v[130:131], v[86:87], v[176:177] op_sel_hi:[1,0]
	v_mov_b32_e32 v144, v141
	v_pk_mul_f32 v[132:133], v[130:131], v[130:131]
	v_pk_add_f32 v[146:147], v[142:143], v[144:145]
	v_pk_fma_f32 v[132:133], v[132:133], s[40:41], 1.0 op_sel_hi:[1,0,0]
	v_pk_mul_f32 v[144:145], v[144:145], v[144:145]
	v_pk_mul_f32 v[132:133], v[130:131], v[132:133]
	v_pk_fma_f32 v[142:143], v[142:143], v[142:143], v[144:145]
	v_pk_mul_f32 v[132:133], v[132:133], s[42:43] op_sel_hi:[1,0]
	v_pk_add_f32 v[136:137], v[142:143], v[136:137] op_sel:[1,0] op_sel_hi:[0,1]
	v_pk_mul_f32 v[132:133], v[132:133], s[38:39] op_sel_hi:[1,0]
	v_pk_add_f32 v[136:137], v[142:143], v[136:137]
	v_exp_f32_e32 v132, v132
	v_exp_f32_e32 v133, v133
	v_add_f32_e32 v147, v147, v148
	v_add_f32_e32 v146, v146, v147
	v_pk_add_f32 v[132:133], v[132:133], 1.0 op_sel_hi:[1,0]
	s_nop 0
	v_rcp_f32_e32 v132, v132
	v_rcp_f32_e32 v133, v133
	s_nop 0
	v_pk_mul_f32 v[130:131], v[130:131], v[132:133]
	v_pk_mul_f32 v[132:133], v[88:89], v[176:177] op_sel_hi:[1,0]
	v_mov_b32_e32 v141, v131
	v_pk_mul_f32 v[138:139], v[132:133], v[132:133]
	s_nop 0
	v_pk_fma_f32 v[138:139], v[138:139], s[40:41], 1.0 op_sel_hi:[1,0,0]
	s_nop 0
	v_pk_mul_f32 v[138:139], v[132:133], v[138:139]
	s_nop 0
	v_pk_mul_f32 v[138:139], v[138:139], s[42:43] op_sel_hi:[1,0]
	s_nop 0
	v_pk_mul_f32 v[138:139], v[138:139], s[38:39] op_sel_hi:[1,0]
	s_nop 0
	v_exp_f32_e32 v138, v138
	v_exp_f32_e32 v139, v139
	s_nop 0
	v_pk_add_f32 v[138:139], v[138:139], 1.0 op_sel_hi:[1,0]
	s_nop 0
	v_rcp_f32_e32 v138, v138
	v_rcp_f32_e32 v139, v139
	s_nop 0
	v_pk_mul_f32 v[132:133], v[132:133], v[138:139]
	s_nop 0
	v_mov_b32_e32 v138, v132
	v_mov_b32_e32 v139, v130
	v_mov_b32_e32 v140, v133
	v_pk_add_f32 v[142:143], v[138:139], v[140:141]
	v_pk_mul_f32 v[140:141], v[140:141], v[140:141]
	v_add_f32_e32 v143, v143, v146
	v_pk_fma_f32 v[138:139], v[138:139], v[138:139], v[140:141]
	v_pk_mul_f32 v[146:147], v[84:85], v[176:177] op_sel_hi:[1,0]
	v_pk_add_f32 v[136:137], v[138:139], v[136:137] op_sel:[1,0] op_sel_hi:[0,1]
	v_pk_add_f32 v[136:137], v[138:139], v[136:137]
	v_pk_mul_f32 v[138:139], v[82:83], v[176:177] op_sel_hi:[1,0]
	v_pk_mul_f32 v[148:149], v[146:147], v[146:147]
	v_pk_mul_f32 v[140:141], v[138:139], v[138:139]
	v_pk_fma_f32 v[148:149], v[148:149], s[40:41], 1.0 op_sel_hi:[1,0,0]
	v_pk_fma_f32 v[140:141], v[140:141], s[40:41], 1.0 op_sel_hi:[1,0,0]
	v_pk_mul_f32 v[148:149], v[146:147], v[148:149]
	v_pk_mul_f32 v[140:141], v[138:139], v[140:141]
	v_pk_mul_f32 v[148:149], v[148:149], s[42:43] op_sel_hi:[1,0]
	v_pk_mul_f32 v[140:141], v[140:141], s[42:43] op_sel_hi:[1,0]
	v_pk_mul_f32 v[148:149], v[148:149], s[38:39] op_sel_hi:[1,0]
	v_pk_mul_f32 v[140:141], v[140:141], s[38:39] op_sel_hi:[1,0]
	v_exp_f32_e32 v148, v148
	v_exp_f32_e32 v140, v140
	v_exp_f32_e32 v141, v141
	v_exp_f32_e32 v149, v149
	v_cvt_pk_bf16_f32 v130, v130, v131
	v_cvt_pk_bf16_f32 v131, v132, v133
	v_pk_add_f32 v[140:141], v[140:141], 1.0 op_sel_hi:[1,0]
	v_pk_add_f32 v[148:149], v[148:149], 1.0 op_sel_hi:[1,0]
	v_rcp_f32_e32 v140, v140
	v_rcp_f32_e32 v141, v141
	v_rcp_f32_e32 v148, v148
	v_rcp_f32_e32 v149, v149
	v_add_f32_e32 v142, v142, v143
	v_pk_mul_f32 v[144:145], v[138:139], v[140:141]
	v_pk_mul_f32 v[146:147], v[146:147], v[148:149]
	v_pk_fma_f32 v[138:139], v[138:139], v[140:141], v[144:145] op_sel:[0,0,1] op_sel_hi:[1,1,0]
	v_mul_f32_e32 v140, v144, v144
	v_pk_fma_f32 v[140:141], v[144:145], v[144:145], v[140:141] op_sel_hi:[1,1,0]
	v_pk_mul_f32 v[148:149], v[146:147], v[146:147]
	v_cvt_pk_bf16_f32 v132, v144, v145
	v_cvt_pk_bf16_f32 v133, v146, v147
	global_store_dwordx4 v[252:253], v[130:133], off offset:-3840
	v_mov_b32_e32 v140, v146
	v_mov_b32_e32 v139, v148
	v_pk_mov_b32 v[130:131], v[146:147], v[136:137] op_sel:[1,0]
	v_mov_b32_e32 v143, v149
	v_pk_add_f32 v[130:131], v[140:141], v[130:131]
	v_pk_add_f32 v[132:133], v[138:139], v[142:143]
	s_nop 0
	v_pk_add_f32 v[130:131], v[132:133], v[130:131]
	ds_bpermute_b32 v132, v223, v130
	ds_bpermute_b32 v133, v223, v131
	s_waitcnt lgkmcnt(0)
	v_pk_add_f32 v[130:131], v[130:131], v[132:133]
	ds_bpermute_b32 v132, v224, v130
	ds_bpermute_b32 v133, v224, v131
	s_and_saveexec_b64 s[62:63], vcc
	s_cbranch_execz .LBB0_1146
	v_lshl_add_u64 v[134:135], s[82:83], 0, v[202:203]
	v_lshl_add_u64 v[134:135], s[0:1], 2, v[134:135]
	s_waitcnt lgkmcnt(0)
	v_pk_add_f32 v[130:131], v[130:131], v[132:133]
	global_store_dwordx2 v[134:135], v[130:131], off
.LBB0_1146:
	s_or_b64 exec, exec, s[62:63]
	v_pk_mul_f32 v[130:131], v[78:79], v[172:173] op_sel_hi:[1,0]
	v_lshlrev_b64 v[134:135], 10, v[170:171]
	s_waitcnt lgkmcnt(0)
	v_pk_mul_f32 v[132:133], v[130:131], v[130:131]
	v_lshl_add_u64 v[134:135], s[14:15], 0, v[134:135]
	v_pk_fma_f32 v[132:133], v[132:133], s[40:41], 1.0 op_sel_hi:[1,0,0]
	v_lshl_add_u64 v[134:135], v[186:187], 1, v[134:135]
	v_pk_mul_f32 v[132:133], v[130:131], v[132:133]
	s_nop 0
	v_pk_mul_f32 v[132:133], v[132:133], s[42:43] op_sel_hi:[1,0]
	s_nop 0
	v_pk_mul_f32 v[132:133], v[132:133], s[38:39] op_sel_hi:[1,0]
	s_nop 0
	v_exp_f32_e32 v132, v132
	v_exp_f32_e32 v133, v133
	s_nop 0
	v_pk_add_f32 v[132:133], v[132:133], 1.0 op_sel_hi:[1,0]
	s_nop 0
	v_rcp_f32_e32 v132, v132
	v_rcp_f32_e32 v133, v133
	s_nop 0
	v_pk_mul_f32 v[130:131], v[130:131], v[132:133]
	v_pk_mul_f32 v[132:133], v[80:81], v[172:173] op_sel_hi:[1,0]
	v_mov_b32_e32 v139, v131
	v_pk_mul_f32 v[136:137], v[132:133], v[132:133]
	s_nop 0
	v_pk_fma_f32 v[136:137], v[136:137], s[40:41], 1.0 op_sel_hi:[1,0,0]
	s_nop 0
	v_pk_mul_f32 v[136:137], v[132:133], v[136:137]
	s_nop 0
	v_pk_mul_f32 v[136:137], v[136:137], s[42:43] op_sel_hi:[1,0]
	s_nop 0
	v_pk_mul_f32 v[136:137], v[136:137], s[38:39] op_sel_hi:[1,0]
	s_nop 0
	v_exp_f32_e32 v136, v136
	v_exp_f32_e32 v137, v137
	s_nop 0
	v_pk_add_f32 v[136:137], v[136:137], 1.0 op_sel_hi:[1,0]
	s_nop 0
	v_rcp_f32_e32 v136, v136
	v_rcp_f32_e32 v137, v137
	s_nop 0
	v_pk_mul_f32 v[132:133], v[132:133], v[136:137]
	s_nop 0
	v_mov_b32_e32 v136, v132
	v_mov_b32_e32 v137, v130
	v_mov_b32_e32 v138, v133
	v_pk_add_f32 v[136:137], v[136:137], v[138:139]
	v_mov_b32_e32 v138, v131
	v_add_f32_e32 v137, 0, v137
	v_mov_b32_e32 v139, v133
	v_add_f32_e32 v148, v136, v137
	v_mov_b32_e32 v136, v130
	v_mov_b32_e32 v137, v132
	v_pk_mul_f32 v[138:139], v[138:139], v[138:139]
	v_cvt_pk_bf16_f32 v130, v130, v131
	v_pk_fma_f32 v[136:137], v[136:137], v[136:137], v[138:139]
	v_pk_mul_f32 v[138:139], v[74:75], v[172:173] op_sel_hi:[1,0]
	v_cvt_pk_bf16_f32 v131, v132, v133
	v_pk_mul_f32 v[140:141], v[138:139], v[138:139]
	v_pk_add_f32 v[136:137], v[136:137], v[136:137] op_sel:[0,1] op_sel_hi:[1,0]
	v_pk_fma_f32 v[140:141], v[140:141], s[40:41], 1.0 op_sel_hi:[1,0,0]
	s_nop 0
	v_pk_mul_f32 v[140:141], v[138:139], v[140:141]
	s_nop 0
	v_pk_mul_f32 v[140:141], v[140:141], s[42:43] op_sel_hi:[1,0]
	s_nop 0
	v_pk_mul_f32 v[140:141], v[140:141], s[38:39] op_sel_hi:[1,0]
	s_nop 0
	v_exp_f32_e32 v140, v140
	v_exp_f32_e32 v141, v141
	s_nop 0
	v_pk_add_f32 v[140:141], v[140:141], 1.0 op_sel_hi:[1,0]
	s_nop 0
	v_rcp_f32_e32 v140, v140
	v_rcp_f32_e32 v141, v141
	s_nop 0
	v_pk_mul_f32 v[138:139], v[138:139], v[140:141]
	v_pk_mul_f32 v[140:141], v[76:77], v[172:173] op_sel_hi:[1,0]
	v_cvt_pk_bf16_f32 v132, v138, v139
	v_pk_mul_f32 v[142:143], v[140:141], v[140:141]
	v_mov_b32_e32 v145, v139
	v_pk_fma_f32 v[142:143], v[142:143], s[40:41], 1.0 op_sel_hi:[1,0,0]
	s_nop 0
	v_pk_mul_f32 v[142:143], v[140:141], v[142:143]
	s_nop 0
	v_pk_mul_f32 v[142:143], v[142:143], s[42:43] op_sel_hi:[1,0]
	s_nop 0
	v_pk_mul_f32 v[142:143], v[142:143], s[38:39] op_sel_hi:[1,0]
	s_nop 0
	v_exp_f32_e32 v142, v142
	v_exp_f32_e32 v143, v143
	s_nop 0
	v_pk_add_f32 v[142:143], v[142:143], 1.0 op_sel_hi:[1,0]
	s_nop 0
	v_rcp_f32_e32 v142, v142
	v_rcp_f32_e32 v143, v143
	s_nop 0
	v_pk_mul_f32 v[140:141], v[140:141], v[142:143]
	s_nop 0
	v_cvt_pk_bf16_f32 v133, v140, v141
	s_mov_b32 s98, 0xd000
	s_mov_b32 s99, 0x0
	v_lshl_add_u64 v[252:253], v[250:251], 0, s[98:99]
	global_store_dwordx4 v[252:253], v[130:133], off offset:-4096
	v_mov_b32_e32 v143, v138
	v_mov_b32_e32 v142, v140
	v_pk_mul_f32 v[130:131], v[70:71], v[172:173] op_sel_hi:[1,0]
	v_mov_b32_e32 v144, v141
	v_pk_mul_f32 v[132:133], v[130:131], v[130:131]
	v_pk_add_f32 v[146:147], v[142:143], v[144:145]
	v_pk_fma_f32 v[132:133], v[132:133], s[40:41], 1.0 op_sel_hi:[1,0,0]
	v_pk_mul_f32 v[144:145], v[144:145], v[144:145]
	v_pk_mul_f32 v[132:133], v[130:131], v[132:133]
	v_pk_fma_f32 v[142:143], v[142:143], v[142:143], v[144:145]
	v_pk_mul_f32 v[132:133], v[132:133], s[42:43] op_sel_hi:[1,0]
	v_pk_add_f32 v[136:137], v[142:143], v[136:137] op_sel:[1,0] op_sel_hi:[0,1]
	v_pk_mul_f32 v[132:133], v[132:133], s[38:39] op_sel_hi:[1,0]
	v_pk_add_f32 v[136:137], v[142:143], v[136:137]
	v_exp_f32_e32 v132, v132
	v_exp_f32_e32 v133, v133
	v_add_f32_e32 v147, v147, v148
	v_add_f32_e32 v146, v146, v147
	v_pk_add_f32 v[132:133], v[132:133], 1.0 op_sel_hi:[1,0]
	s_nop 0
	v_rcp_f32_e32 v132, v132
	v_rcp_f32_e32 v133, v133
	s_nop 0
	v_pk_mul_f32 v[130:131], v[130:131], v[132:133]
	v_pk_mul_f32 v[132:133], v[72:73], v[172:173] op_sel_hi:[1,0]
	v_mov_b32_e32 v141, v131
	v_pk_mul_f32 v[138:139], v[132:133], v[132:133]
	s_nop 0
	v_pk_fma_f32 v[138:139], v[138:139], s[40:41], 1.0 op_sel_hi:[1,0,0]
	s_nop 0
	v_pk_mul_f32 v[138:139], v[132:133], v[138:139]
	s_nop 0
	v_pk_mul_f32 v[138:139], v[138:139], s[42:43] op_sel_hi:[1,0]
	s_nop 0
	v_pk_mul_f32 v[138:139], v[138:139], s[38:39] op_sel_hi:[1,0]
	s_nop 0
	v_exp_f32_e32 v138, v138
	v_exp_f32_e32 v139, v139
	s_nop 0
	v_pk_add_f32 v[138:139], v[138:139], 1.0 op_sel_hi:[1,0]
	s_nop 0
	v_rcp_f32_e32 v138, v138
	v_rcp_f32_e32 v139, v139
	s_nop 0
	v_pk_mul_f32 v[132:133], v[132:133], v[138:139]
	s_nop 0
	v_mov_b32_e32 v138, v132
	v_mov_b32_e32 v139, v130
	v_mov_b32_e32 v140, v133
	v_pk_add_f32 v[142:143], v[138:139], v[140:141]
	v_pk_mul_f32 v[140:141], v[140:141], v[140:141]
	v_add_f32_e32 v143, v143, v146
	v_pk_fma_f32 v[138:139], v[138:139], v[138:139], v[140:141]
	v_pk_mul_f32 v[146:147], v[68:69], v[172:173] op_sel_hi:[1,0]
	v_pk_add_f32 v[136:137], v[138:139], v[136:137] op_sel:[1,0] op_sel_hi:[0,1]
	v_pk_add_f32 v[136:137], v[138:139], v[136:137]
	v_pk_mul_f32 v[138:139], v[66:67], v[172:173] op_sel_hi:[1,0]
	v_pk_mul_f32 v[148:149], v[146:147], v[146:147]
	v_pk_mul_f32 v[140:141], v[138:139], v[138:139]
	v_pk_fma_f32 v[148:149], v[148:149], s[40:41], 1.0 op_sel_hi:[1,0,0]
	v_pk_fma_f32 v[140:141], v[140:141], s[40:41], 1.0 op_sel_hi:[1,0,0]
	v_pk_mul_f32 v[148:149], v[146:147], v[148:149]
	v_pk_mul_f32 v[140:141], v[138:139], v[140:141]
	v_pk_mul_f32 v[148:149], v[148:149], s[42:43] op_sel_hi:[1,0]
	v_pk_mul_f32 v[140:141], v[140:141], s[42:43] op_sel_hi:[1,0]
	v_pk_mul_f32 v[148:149], v[148:149], s[38:39] op_sel_hi:[1,0]
	v_pk_mul_f32 v[140:141], v[140:141], s[38:39] op_sel_hi:[1,0]
	v_exp_f32_e32 v148, v148
	v_exp_f32_e32 v140, v140
	v_exp_f32_e32 v141, v141
	v_exp_f32_e32 v149, v149
	v_cvt_pk_bf16_f32 v130, v130, v131
	v_cvt_pk_bf16_f32 v131, v132, v133
	v_pk_add_f32 v[140:141], v[140:141], 1.0 op_sel_hi:[1,0]
	v_pk_add_f32 v[148:149], v[148:149], 1.0 op_sel_hi:[1,0]
	v_rcp_f32_e32 v140, v140
	v_rcp_f32_e32 v141, v141
	v_rcp_f32_e32 v148, v148
	v_rcp_f32_e32 v149, v149
	v_add_f32_e32 v142, v142, v143
	v_pk_mul_f32 v[144:145], v[138:139], v[140:141]
	v_pk_mul_f32 v[146:147], v[146:147], v[148:149]
	v_pk_fma_f32 v[138:139], v[138:139], v[140:141], v[144:145] op_sel:[0,0,1] op_sel_hi:[1,1,0]
	v_mul_f32_e32 v140, v144, v144
	v_pk_fma_f32 v[140:141], v[144:145], v[144:145], v[140:141] op_sel_hi:[1,1,0]
	v_pk_mul_f32 v[148:149], v[146:147], v[146:147]
	v_cvt_pk_bf16_f32 v132, v144, v145
	v_cvt_pk_bf16_f32 v133, v146, v147
	global_store_dwordx4 v[252:253], v[130:133], off offset:-3840
	v_mov_b32_e32 v140, v146
	v_mov_b32_e32 v139, v148
	v_pk_mov_b32 v[130:131], v[146:147], v[136:137] op_sel:[1,0]
	v_mov_b32_e32 v143, v149
	v_pk_add_f32 v[130:131], v[140:141], v[130:131]
	v_pk_add_f32 v[132:133], v[138:139], v[142:143]
	s_nop 0
	v_pk_add_f32 v[130:131], v[132:133], v[130:131]
	ds_bpermute_b32 v132, v223, v130
	ds_bpermute_b32 v133, v223, v131
	s_waitcnt lgkmcnt(0)
	v_pk_add_f32 v[130:131], v[130:131], v[132:133]
	ds_bpermute_b32 v132, v224, v130
	ds_bpermute_b32 v133, v224, v131
	s_and_saveexec_b64 s[62:63], vcc
	s_cbranch_execz .LBB0_1148
	v_lshl_add_u64 v[134:135], s[82:83], 0, v[200:201]
	v_lshl_add_u64 v[134:135], s[0:1], 2, v[134:135]
	s_waitcnt lgkmcnt(0)
	v_pk_add_f32 v[130:131], v[130:131], v[132:133]
	global_store_dwordx2 v[134:135], v[130:131], off
.LBB0_1148:
	s_or_b64 exec, exec, s[62:63]
	v_pk_mul_f32 v[130:131], v[62:63], v[168:169] op_sel_hi:[1,0]
	v_lshlrev_b64 v[134:135], 10, v[166:167]
	s_waitcnt lgkmcnt(0)
	v_pk_mul_f32 v[132:133], v[130:131], v[130:131]
	v_lshl_add_u64 v[134:135], s[14:15], 0, v[134:135]
	v_pk_fma_f32 v[132:133], v[132:133], s[40:41], 1.0 op_sel_hi:[1,0,0]
	v_lshl_add_u64 v[134:135], v[186:187], 1, v[134:135]
	v_pk_mul_f32 v[132:133], v[130:131], v[132:133]
	s_nop 0
	v_pk_mul_f32 v[132:133], v[132:133], s[42:43] op_sel_hi:[1,0]
	s_nop 0
	v_pk_mul_f32 v[132:133], v[132:133], s[38:39] op_sel_hi:[1,0]
	s_nop 0
	v_exp_f32_e32 v132, v132
	v_exp_f32_e32 v133, v133
	s_nop 0
	v_pk_add_f32 v[132:133], v[132:133], 1.0 op_sel_hi:[1,0]
	s_nop 0
	v_rcp_f32_e32 v132, v132
	v_rcp_f32_e32 v133, v133
	s_nop 0
	v_pk_mul_f32 v[130:131], v[130:131], v[132:133]
	v_pk_mul_f32 v[132:133], v[64:65], v[168:169] op_sel_hi:[1,0]
	v_mov_b32_e32 v139, v131
	v_pk_mul_f32 v[136:137], v[132:133], v[132:133]
	s_nop 0
	v_pk_fma_f32 v[136:137], v[136:137], s[40:41], 1.0 op_sel_hi:[1,0,0]
	s_nop 0
	v_pk_mul_f32 v[136:137], v[132:133], v[136:137]
	s_nop 0
	v_pk_mul_f32 v[136:137], v[136:137], s[42:43] op_sel_hi:[1,0]
	s_nop 0
	v_pk_mul_f32 v[136:137], v[136:137], s[38:39] op_sel_hi:[1,0]
	s_nop 0
	v_exp_f32_e32 v136, v136
	v_exp_f32_e32 v137, v137
	s_nop 0
	v_pk_add_f32 v[136:137], v[136:137], 1.0 op_sel_hi:[1,0]
	s_nop 0
	v_rcp_f32_e32 v136, v136
	v_rcp_f32_e32 v137, v137
	s_nop 0
	v_pk_mul_f32 v[132:133], v[132:133], v[136:137]
	s_nop 0
	v_mov_b32_e32 v136, v132
	v_mov_b32_e32 v137, v130
	v_mov_b32_e32 v138, v133
	v_pk_add_f32 v[136:137], v[136:137], v[138:139]
	v_mov_b32_e32 v138, v131
	v_add_f32_e32 v137, 0, v137
	v_mov_b32_e32 v139, v133
	v_add_f32_e32 v148, v136, v137
	v_mov_b32_e32 v136, v130
	v_mov_b32_e32 v137, v132
	v_pk_mul_f32 v[138:139], v[138:139], v[138:139]
	v_cvt_pk_bf16_f32 v130, v130, v131
	v_pk_fma_f32 v[136:137], v[136:137], v[136:137], v[138:139]
	v_pk_mul_f32 v[138:139], v[58:59], v[168:169] op_sel_hi:[1,0]
	v_cvt_pk_bf16_f32 v131, v132, v133
	v_pk_mul_f32 v[140:141], v[138:139], v[138:139]
	v_pk_add_f32 v[136:137], v[136:137], v[136:137] op_sel:[0,1] op_sel_hi:[1,0]
	v_pk_fma_f32 v[140:141], v[140:141], s[40:41], 1.0 op_sel_hi:[1,0,0]
	s_nop 0
	v_pk_mul_f32 v[140:141], v[138:139], v[140:141]
	s_nop 0
	v_pk_mul_f32 v[140:141], v[140:141], s[42:43] op_sel_hi:[1,0]
	s_nop 0
	v_pk_mul_f32 v[140:141], v[140:141], s[38:39] op_sel_hi:[1,0]
	s_nop 0
	v_exp_f32_e32 v140, v140
	v_exp_f32_e32 v141, v141
	s_nop 0
	v_pk_add_f32 v[140:141], v[140:141], 1.0 op_sel_hi:[1,0]
	s_nop 0
	v_rcp_f32_e32 v140, v140
	v_rcp_f32_e32 v141, v141
	s_nop 0
	v_pk_mul_f32 v[138:139], v[138:139], v[140:141]
	v_pk_mul_f32 v[140:141], v[60:61], v[168:169] op_sel_hi:[1,0]
	v_cvt_pk_bf16_f32 v132, v138, v139
	v_pk_mul_f32 v[142:143], v[140:141], v[140:141]
	v_mov_b32_e32 v145, v139
	v_pk_fma_f32 v[142:143], v[142:143], s[40:41], 1.0 op_sel_hi:[1,0,0]
	s_nop 0
	v_pk_mul_f32 v[142:143], v[140:141], v[142:143]
	s_nop 0
	v_pk_mul_f32 v[142:143], v[142:143], s[42:43] op_sel_hi:[1,0]
	s_nop 0
	v_pk_mul_f32 v[142:143], v[142:143], s[38:39] op_sel_hi:[1,0]
	s_nop 0
	v_exp_f32_e32 v142, v142
	v_exp_f32_e32 v143, v143
	s_nop 0
	v_pk_add_f32 v[142:143], v[142:143], 1.0 op_sel_hi:[1,0]
	s_nop 0
	v_rcp_f32_e32 v142, v142
	v_rcp_f32_e32 v143, v143
	s_nop 0
	v_pk_mul_f32 v[140:141], v[140:141], v[142:143]
	s_nop 0
	v_cvt_pk_bf16_f32 v133, v140, v141
	s_mov_b32 s98, 0x21000
	s_mov_b32 s99, 0x0
	v_lshl_add_u64 v[252:253], v[250:251], 0, s[98:99]
	global_store_dwordx4 v[252:253], v[130:133], off offset:-4096
	v_mov_b32_e32 v143, v138
	v_mov_b32_e32 v142, v140
	v_pk_mul_f32 v[130:131], v[54:55], v[168:169] op_sel_hi:[1,0]
	v_mov_b32_e32 v144, v141
	v_pk_mul_f32 v[132:133], v[130:131], v[130:131]
	v_pk_add_f32 v[146:147], v[142:143], v[144:145]
	v_pk_fma_f32 v[132:133], v[132:133], s[40:41], 1.0 op_sel_hi:[1,0,0]
	v_pk_mul_f32 v[144:145], v[144:145], v[144:145]
	v_pk_mul_f32 v[132:133], v[130:131], v[132:133]
	v_pk_fma_f32 v[142:143], v[142:143], v[142:143], v[144:145]
	v_pk_mul_f32 v[132:133], v[132:133], s[42:43] op_sel_hi:[1,0]
	v_pk_add_f32 v[136:137], v[142:143], v[136:137] op_sel:[1,0] op_sel_hi:[0,1]
	v_pk_mul_f32 v[132:133], v[132:133], s[38:39] op_sel_hi:[1,0]
	v_pk_add_f32 v[136:137], v[142:143], v[136:137]
	v_exp_f32_e32 v132, v132
	v_exp_f32_e32 v133, v133
	v_add_f32_e32 v147, v147, v148
	v_add_f32_e32 v146, v146, v147
	v_pk_add_f32 v[132:133], v[132:133], 1.0 op_sel_hi:[1,0]
	s_nop 0
	v_rcp_f32_e32 v132, v132
	v_rcp_f32_e32 v133, v133
	s_nop 0
	v_pk_mul_f32 v[130:131], v[130:131], v[132:133]
	v_pk_mul_f32 v[132:133], v[56:57], v[168:169] op_sel_hi:[1,0]
	v_mov_b32_e32 v141, v131
	v_pk_mul_f32 v[138:139], v[132:133], v[132:133]
	s_nop 0
	v_pk_fma_f32 v[138:139], v[138:139], s[40:41], 1.0 op_sel_hi:[1,0,0]
	s_nop 0
	v_pk_mul_f32 v[138:139], v[132:133], v[138:139]
	s_nop 0
	v_pk_mul_f32 v[138:139], v[138:139], s[42:43] op_sel_hi:[1,0]
	s_nop 0
	v_pk_mul_f32 v[138:139], v[138:139], s[38:39] op_sel_hi:[1,0]
	s_nop 0
	v_exp_f32_e32 v138, v138
	v_exp_f32_e32 v139, v139
	s_nop 0
	v_pk_add_f32 v[138:139], v[138:139], 1.0 op_sel_hi:[1,0]
	s_nop 0
	v_rcp_f32_e32 v138, v138
	v_rcp_f32_e32 v139, v139
	s_nop 0
	v_pk_mul_f32 v[132:133], v[132:133], v[138:139]
	s_nop 0
	v_mov_b32_e32 v138, v132
	v_mov_b32_e32 v139, v130
	v_mov_b32_e32 v140, v133
	v_pk_add_f32 v[142:143], v[138:139], v[140:141]
	v_pk_mul_f32 v[140:141], v[140:141], v[140:141]
	v_add_f32_e32 v143, v143, v146
	v_pk_fma_f32 v[138:139], v[138:139], v[138:139], v[140:141]
	v_pk_mul_f32 v[146:147], v[52:53], v[168:169] op_sel_hi:[1,0]
	v_pk_add_f32 v[136:137], v[138:139], v[136:137] op_sel:[1,0] op_sel_hi:[0,1]
	v_pk_add_f32 v[136:137], v[138:139], v[136:137]
	v_pk_mul_f32 v[138:139], v[50:51], v[168:169] op_sel_hi:[1,0]
	v_pk_mul_f32 v[148:149], v[146:147], v[146:147]
	v_pk_mul_f32 v[140:141], v[138:139], v[138:139]
	v_pk_fma_f32 v[148:149], v[148:149], s[40:41], 1.0 op_sel_hi:[1,0,0]
	v_pk_fma_f32 v[140:141], v[140:141], s[40:41], 1.0 op_sel_hi:[1,0,0]
	v_pk_mul_f32 v[148:149], v[146:147], v[148:149]
	v_pk_mul_f32 v[140:141], v[138:139], v[140:141]
	v_pk_mul_f32 v[148:149], v[148:149], s[42:43] op_sel_hi:[1,0]
	v_pk_mul_f32 v[140:141], v[140:141], s[42:43] op_sel_hi:[1,0]
	v_pk_mul_f32 v[148:149], v[148:149], s[38:39] op_sel_hi:[1,0]
	v_pk_mul_f32 v[140:141], v[140:141], s[38:39] op_sel_hi:[1,0]
	v_exp_f32_e32 v148, v148
	v_exp_f32_e32 v140, v140
	v_exp_f32_e32 v141, v141
	v_exp_f32_e32 v149, v149
	v_cvt_pk_bf16_f32 v130, v130, v131
	v_cvt_pk_bf16_f32 v131, v132, v133
	v_pk_add_f32 v[140:141], v[140:141], 1.0 op_sel_hi:[1,0]
	v_pk_add_f32 v[148:149], v[148:149], 1.0 op_sel_hi:[1,0]
	v_rcp_f32_e32 v140, v140
	v_rcp_f32_e32 v141, v141
	v_rcp_f32_e32 v148, v148
	v_rcp_f32_e32 v149, v149
	v_add_f32_e32 v142, v142, v143
	v_pk_mul_f32 v[144:145], v[138:139], v[140:141]
	v_pk_mul_f32 v[146:147], v[146:147], v[148:149]
	v_pk_fma_f32 v[138:139], v[138:139], v[140:141], v[144:145] op_sel:[0,0,1] op_sel_hi:[1,1,0]
	v_mul_f32_e32 v140, v144, v144
	v_pk_fma_f32 v[140:141], v[144:145], v[144:145], v[140:141] op_sel_hi:[1,1,0]
	v_pk_mul_f32 v[148:149], v[146:147], v[146:147]
	v_cvt_pk_bf16_f32 v132, v144, v145
	v_cvt_pk_bf16_f32 v133, v146, v147
	global_store_dwordx4 v[252:253], v[130:133], off offset:-3840
	v_mov_b32_e32 v140, v146
	v_mov_b32_e32 v139, v148
	v_pk_mov_b32 v[130:131], v[146:147], v[136:137] op_sel:[1,0]
	v_mov_b32_e32 v143, v149
	v_pk_add_f32 v[130:131], v[140:141], v[130:131]
	v_pk_add_f32 v[132:133], v[138:139], v[142:143]
	s_nop 0
	v_pk_add_f32 v[130:131], v[132:133], v[130:131]
	ds_bpermute_b32 v132, v223, v130
	ds_bpermute_b32 v133, v223, v131
	s_waitcnt lgkmcnt(0)
	v_pk_add_f32 v[130:131], v[130:131], v[132:133]
	ds_bpermute_b32 v132, v224, v130
	ds_bpermute_b32 v133, v224, v131
	s_and_saveexec_b64 s[62:63], vcc
	s_cbranch_execz .LBB0_1150
	v_lshl_add_u64 v[134:135], s[82:83], 0, v[198:199]
	v_lshl_add_u64 v[134:135], s[0:1], 2, v[134:135]
	s_waitcnt lgkmcnt(0)
	v_pk_add_f32 v[130:131], v[130:131], v[132:133]
	global_store_dwordx2 v[134:135], v[130:131], off
.LBB0_1150:
	s_or_b64 exec, exec, s[62:63]
	v_pk_mul_f32 v[130:131], v[46:47], v[164:165] op_sel_hi:[1,0]
	v_lshlrev_b64 v[134:135], 10, v[162:163]
	s_waitcnt lgkmcnt(0)
	v_pk_mul_f32 v[132:133], v[130:131], v[130:131]
	v_lshl_add_u64 v[134:135], s[14:15], 0, v[134:135]
	v_pk_fma_f32 v[132:133], v[132:133], s[40:41], 1.0 op_sel_hi:[1,0,0]
	v_lshl_add_u64 v[134:135], v[186:187], 1, v[134:135]
	v_pk_mul_f32 v[132:133], v[130:131], v[132:133]
	s_nop 0
	v_pk_mul_f32 v[132:133], v[132:133], s[42:43] op_sel_hi:[1,0]
	s_nop 0
	v_pk_mul_f32 v[132:133], v[132:133], s[38:39] op_sel_hi:[1,0]
	s_nop 0
	v_exp_f32_e32 v132, v132
	v_exp_f32_e32 v133, v133
	s_nop 0
	v_pk_add_f32 v[132:133], v[132:133], 1.0 op_sel_hi:[1,0]
	s_nop 0
	v_rcp_f32_e32 v132, v132
	v_rcp_f32_e32 v133, v133
	s_nop 0
	v_pk_mul_f32 v[130:131], v[130:131], v[132:133]
	v_pk_mul_f32 v[132:133], v[48:49], v[164:165] op_sel_hi:[1,0]
	v_mov_b32_e32 v139, v131
	v_pk_mul_f32 v[136:137], v[132:133], v[132:133]
	s_nop 0
	v_pk_fma_f32 v[136:137], v[136:137], s[40:41], 1.0 op_sel_hi:[1,0,0]
	s_nop 0
	v_pk_mul_f32 v[136:137], v[132:133], v[136:137]
	s_nop 0
	v_pk_mul_f32 v[136:137], v[136:137], s[42:43] op_sel_hi:[1,0]
	s_nop 0
	v_pk_mul_f32 v[136:137], v[136:137], s[38:39] op_sel_hi:[1,0]
	s_nop 0
	v_exp_f32_e32 v136, v136
	v_exp_f32_e32 v137, v137
	s_nop 0
	v_pk_add_f32 v[136:137], v[136:137], 1.0 op_sel_hi:[1,0]
	s_nop 0
	v_rcp_f32_e32 v136, v136
	v_rcp_f32_e32 v137, v137
	s_nop 0
	v_pk_mul_f32 v[132:133], v[132:133], v[136:137]
	s_nop 0
	v_mov_b32_e32 v136, v132
	v_mov_b32_e32 v137, v130
	v_mov_b32_e32 v138, v133
	v_pk_add_f32 v[136:137], v[136:137], v[138:139]
	v_mov_b32_e32 v138, v131
	v_add_f32_e32 v137, 0, v137
	v_mov_b32_e32 v139, v133
	v_add_f32_e32 v148, v136, v137
	v_mov_b32_e32 v136, v130
	v_mov_b32_e32 v137, v132
	v_pk_mul_f32 v[138:139], v[138:139], v[138:139]
	v_cvt_pk_bf16_f32 v130, v130, v131
	v_pk_fma_f32 v[136:137], v[136:137], v[136:137], v[138:139]
	v_pk_mul_f32 v[138:139], v[42:43], v[164:165] op_sel_hi:[1,0]
	v_cvt_pk_bf16_f32 v131, v132, v133
	v_pk_mul_f32 v[140:141], v[138:139], v[138:139]
	v_pk_add_f32 v[136:137], v[136:137], v[136:137] op_sel:[0,1] op_sel_hi:[1,0]
	v_pk_fma_f32 v[140:141], v[140:141], s[40:41], 1.0 op_sel_hi:[1,0,0]
	s_nop 0
	v_pk_mul_f32 v[140:141], v[138:139], v[140:141]
	s_nop 0
	v_pk_mul_f32 v[140:141], v[140:141], s[42:43] op_sel_hi:[1,0]
	s_nop 0
	v_pk_mul_f32 v[140:141], v[140:141], s[38:39] op_sel_hi:[1,0]
	s_nop 0
	v_exp_f32_e32 v140, v140
	v_exp_f32_e32 v141, v141
	s_nop 0
	v_pk_add_f32 v[140:141], v[140:141], 1.0 op_sel_hi:[1,0]
	s_nop 0
	v_rcp_f32_e32 v140, v140
	v_rcp_f32_e32 v141, v141
	s_nop 0
	v_pk_mul_f32 v[138:139], v[138:139], v[140:141]
	v_pk_mul_f32 v[140:141], v[44:45], v[164:165] op_sel_hi:[1,0]
	v_cvt_pk_bf16_f32 v132, v138, v139
	v_pk_mul_f32 v[142:143], v[140:141], v[140:141]
	v_mov_b32_e32 v145, v139
	v_pk_fma_f32 v[142:143], v[142:143], s[40:41], 1.0 op_sel_hi:[1,0,0]
	s_nop 0
	v_pk_mul_f32 v[142:143], v[140:141], v[142:143]
	s_nop 0
	v_pk_mul_f32 v[142:143], v[142:143], s[42:43] op_sel_hi:[1,0]
	s_nop 0
	v_pk_mul_f32 v[142:143], v[142:143], s[38:39] op_sel_hi:[1,0]
	s_nop 0
	v_exp_f32_e32 v142, v142
	v_exp_f32_e32 v143, v143
	s_nop 0
	v_pk_add_f32 v[142:143], v[142:143], 1.0 op_sel_hi:[1,0]
	s_nop 0
	v_rcp_f32_e32 v142, v142
	v_rcp_f32_e32 v143, v143
	s_nop 0
	v_pk_mul_f32 v[140:141], v[140:141], v[142:143]
	s_nop 0
	v_cvt_pk_bf16_f32 v133, v140, v141
	s_mov_b32 s98, 0x25000
	s_mov_b32 s99, 0x0
	v_lshl_add_u64 v[252:253], v[250:251], 0, s[98:99]
	global_store_dwordx4 v[252:253], v[130:133], off offset:-4096
	v_mov_b32_e32 v143, v138
	v_mov_b32_e32 v142, v140
	v_pk_mul_f32 v[130:131], v[38:39], v[164:165] op_sel_hi:[1,0]
	v_mov_b32_e32 v144, v141
	v_pk_mul_f32 v[132:133], v[130:131], v[130:131]
	v_pk_add_f32 v[146:147], v[142:143], v[144:145]
	v_pk_fma_f32 v[132:133], v[132:133], s[40:41], 1.0 op_sel_hi:[1,0,0]
	v_pk_mul_f32 v[144:145], v[144:145], v[144:145]
	v_pk_mul_f32 v[132:133], v[130:131], v[132:133]
	v_pk_fma_f32 v[142:143], v[142:143], v[142:143], v[144:145]
	v_pk_mul_f32 v[132:133], v[132:133], s[42:43] op_sel_hi:[1,0]
	v_pk_add_f32 v[136:137], v[142:143], v[136:137] op_sel:[1,0] op_sel_hi:[0,1]
	v_pk_mul_f32 v[132:133], v[132:133], s[38:39] op_sel_hi:[1,0]
	v_pk_add_f32 v[136:137], v[142:143], v[136:137]
	v_exp_f32_e32 v132, v132
	v_exp_f32_e32 v133, v133
	v_add_f32_e32 v147, v147, v148
	v_add_f32_e32 v146, v146, v147
	v_pk_add_f32 v[132:133], v[132:133], 1.0 op_sel_hi:[1,0]
	s_nop 0
	v_rcp_f32_e32 v132, v132
	v_rcp_f32_e32 v133, v133
	s_nop 0
	v_pk_mul_f32 v[130:131], v[130:131], v[132:133]
	v_pk_mul_f32 v[132:133], v[40:41], v[164:165] op_sel_hi:[1,0]
	v_mov_b32_e32 v141, v131
	v_pk_mul_f32 v[138:139], v[132:133], v[132:133]
	s_nop 0
	v_pk_fma_f32 v[138:139], v[138:139], s[40:41], 1.0 op_sel_hi:[1,0,0]
	s_nop 0
	v_pk_mul_f32 v[138:139], v[132:133], v[138:139]
	s_nop 0
	v_pk_mul_f32 v[138:139], v[138:139], s[42:43] op_sel_hi:[1,0]
	s_nop 0
	v_pk_mul_f32 v[138:139], v[138:139], s[38:39] op_sel_hi:[1,0]
	s_nop 0
	v_exp_f32_e32 v138, v138
	v_exp_f32_e32 v139, v139
	s_nop 0
	v_pk_add_f32 v[138:139], v[138:139], 1.0 op_sel_hi:[1,0]
	s_nop 0
	v_rcp_f32_e32 v138, v138
	v_rcp_f32_e32 v139, v139
	s_nop 0
	v_pk_mul_f32 v[132:133], v[132:133], v[138:139]
	s_nop 0
	v_mov_b32_e32 v138, v132
	v_mov_b32_e32 v139, v130
	v_mov_b32_e32 v140, v133
	v_pk_add_f32 v[142:143], v[138:139], v[140:141]
	v_pk_mul_f32 v[140:141], v[140:141], v[140:141]
	v_add_f32_e32 v143, v143, v146
	v_pk_fma_f32 v[138:139], v[138:139], v[138:139], v[140:141]
	v_pk_mul_f32 v[146:147], v[36:37], v[164:165] op_sel_hi:[1,0]
	v_pk_add_f32 v[136:137], v[138:139], v[136:137] op_sel:[1,0] op_sel_hi:[0,1]
	v_pk_add_f32 v[136:137], v[138:139], v[136:137]
	v_pk_mul_f32 v[138:139], v[34:35], v[164:165] op_sel_hi:[1,0]
	v_pk_mul_f32 v[148:149], v[146:147], v[146:147]
	v_pk_mul_f32 v[140:141], v[138:139], v[138:139]
	v_pk_fma_f32 v[148:149], v[148:149], s[40:41], 1.0 op_sel_hi:[1,0,0]
	v_pk_fma_f32 v[140:141], v[140:141], s[40:41], 1.0 op_sel_hi:[1,0,0]
	v_pk_mul_f32 v[148:149], v[146:147], v[148:149]
	v_pk_mul_f32 v[140:141], v[138:139], v[140:141]
	v_pk_mul_f32 v[148:149], v[148:149], s[42:43] op_sel_hi:[1,0]
	v_pk_mul_f32 v[140:141], v[140:141], s[42:43] op_sel_hi:[1,0]
	v_pk_mul_f32 v[148:149], v[148:149], s[38:39] op_sel_hi:[1,0]
	v_pk_mul_f32 v[140:141], v[140:141], s[38:39] op_sel_hi:[1,0]
	v_exp_f32_e32 v148, v148
	v_exp_f32_e32 v140, v140
	v_exp_f32_e32 v141, v141
	v_exp_f32_e32 v149, v149
	v_cvt_pk_bf16_f32 v130, v130, v131
	v_cvt_pk_bf16_f32 v131, v132, v133
	v_pk_add_f32 v[140:141], v[140:141], 1.0 op_sel_hi:[1,0]
	v_pk_add_f32 v[148:149], v[148:149], 1.0 op_sel_hi:[1,0]
	v_rcp_f32_e32 v140, v140
	v_rcp_f32_e32 v141, v141
	v_rcp_f32_e32 v148, v148
	v_rcp_f32_e32 v149, v149
	v_add_f32_e32 v142, v142, v143
	v_pk_mul_f32 v[144:145], v[138:139], v[140:141]
	v_pk_mul_f32 v[146:147], v[146:147], v[148:149]
	v_pk_fma_f32 v[138:139], v[138:139], v[140:141], v[144:145] op_sel:[0,0,1] op_sel_hi:[1,1,0]
	v_mul_f32_e32 v140, v144, v144
	v_pk_fma_f32 v[140:141], v[144:145], v[144:145], v[140:141] op_sel_hi:[1,1,0]
	v_pk_mul_f32 v[148:149], v[146:147], v[146:147]
	v_cvt_pk_bf16_f32 v132, v144, v145
	v_cvt_pk_bf16_f32 v133, v146, v147
	global_store_dwordx4 v[252:253], v[130:133], off offset:-3840
	v_mov_b32_e32 v140, v146
	v_mov_b32_e32 v139, v148
	v_pk_mov_b32 v[130:131], v[146:147], v[136:137] op_sel:[1,0]
	v_mov_b32_e32 v143, v149
	v_pk_add_f32 v[130:131], v[140:141], v[130:131]
	v_pk_add_f32 v[132:133], v[138:139], v[142:143]
	s_nop 0
	v_pk_add_f32 v[130:131], v[132:133], v[130:131]
	ds_bpermute_b32 v132, v223, v130
	ds_bpermute_b32 v133, v223, v131
	s_waitcnt lgkmcnt(0)
	v_pk_add_f32 v[130:131], v[130:131], v[132:133]
	ds_bpermute_b32 v132, v224, v130
	ds_bpermute_b32 v133, v224, v131
	s_and_saveexec_b64 s[62:63], vcc
	s_cbranch_execz .LBB0_1152
	v_lshl_add_u64 v[134:135], s[82:83], 0, v[192:193]
	v_lshl_add_u64 v[134:135], s[0:1], 2, v[134:135]
	s_waitcnt lgkmcnt(0)
	v_pk_add_f32 v[130:131], v[130:131], v[132:133]
	global_store_dwordx2 v[134:135], v[130:131], off
.LBB0_1152:
	s_or_b64 exec, exec, s[62:63]
	v_pk_mul_f32 v[130:131], v[30:31], v[160:161] op_sel_hi:[1,0]
	v_lshlrev_b64 v[134:135], 10, v[158:159]
	s_waitcnt lgkmcnt(0)
	v_pk_mul_f32 v[132:133], v[130:131], v[130:131]
	v_lshl_add_u64 v[134:135], s[14:15], 0, v[134:135]
	v_pk_fma_f32 v[132:133], v[132:133], s[40:41], 1.0 op_sel_hi:[1,0,0]
	v_lshl_add_u64 v[134:135], v[186:187], 1, v[134:135]
	v_pk_mul_f32 v[132:133], v[130:131], v[132:133]
	s_nop 0
	v_pk_mul_f32 v[132:133], v[132:133], s[42:43] op_sel_hi:[1,0]
	s_nop 0
	v_pk_mul_f32 v[132:133], v[132:133], s[38:39] op_sel_hi:[1,0]
	s_nop 0
	v_exp_f32_e32 v132, v132
	v_exp_f32_e32 v133, v133
	s_nop 0
	v_pk_add_f32 v[132:133], v[132:133], 1.0 op_sel_hi:[1,0]
	s_nop 0
	v_rcp_f32_e32 v132, v132
	v_rcp_f32_e32 v133, v133
	s_nop 0
	v_pk_mul_f32 v[130:131], v[130:131], v[132:133]
	v_pk_mul_f32 v[132:133], v[32:33], v[160:161] op_sel_hi:[1,0]
	v_mov_b32_e32 v139, v131
	v_pk_mul_f32 v[136:137], v[132:133], v[132:133]
	s_nop 0
	v_pk_fma_f32 v[136:137], v[136:137], s[40:41], 1.0 op_sel_hi:[1,0,0]
	s_nop 0
	v_pk_mul_f32 v[136:137], v[132:133], v[136:137]
	s_nop 0
	v_pk_mul_f32 v[136:137], v[136:137], s[42:43] op_sel_hi:[1,0]
	s_nop 0
	v_pk_mul_f32 v[136:137], v[136:137], s[38:39] op_sel_hi:[1,0]
	s_nop 0
	v_exp_f32_e32 v136, v136
	v_exp_f32_e32 v137, v137
	s_nop 0
	v_pk_add_f32 v[136:137], v[136:137], 1.0 op_sel_hi:[1,0]
	s_nop 0
	v_rcp_f32_e32 v136, v136
	v_rcp_f32_e32 v137, v137
	s_nop 0
	v_pk_mul_f32 v[132:133], v[132:133], v[136:137]
	s_nop 0
	v_mov_b32_e32 v136, v132
	v_mov_b32_e32 v137, v130
	v_mov_b32_e32 v138, v133
	v_pk_add_f32 v[136:137], v[136:137], v[138:139]
	v_mov_b32_e32 v138, v131
	v_add_f32_e32 v137, 0, v137
	v_mov_b32_e32 v139, v133
	v_add_f32_e32 v148, v136, v137
	v_mov_b32_e32 v136, v130
	v_mov_b32_e32 v137, v132
	v_pk_mul_f32 v[138:139], v[138:139], v[138:139]
	v_cvt_pk_bf16_f32 v130, v130, v131
	v_pk_fma_f32 v[136:137], v[136:137], v[136:137], v[138:139]
	v_pk_mul_f32 v[138:139], v[26:27], v[160:161] op_sel_hi:[1,0]
	v_cvt_pk_bf16_f32 v131, v132, v133
	v_pk_mul_f32 v[140:141], v[138:139], v[138:139]
	v_pk_add_f32 v[136:137], v[136:137], v[136:137] op_sel:[0,1] op_sel_hi:[1,0]
	v_pk_fma_f32 v[140:141], v[140:141], s[40:41], 1.0 op_sel_hi:[1,0,0]
	s_nop 0
	v_pk_mul_f32 v[140:141], v[138:139], v[140:141]
	s_nop 0
	v_pk_mul_f32 v[140:141], v[140:141], s[42:43] op_sel_hi:[1,0]
	s_nop 0
	v_pk_mul_f32 v[140:141], v[140:141], s[38:39] op_sel_hi:[1,0]
	s_nop 0
	v_exp_f32_e32 v140, v140
	v_exp_f32_e32 v141, v141
	s_nop 0
	v_pk_add_f32 v[140:141], v[140:141], 1.0 op_sel_hi:[1,0]
	s_nop 0
	v_rcp_f32_e32 v140, v140
	v_rcp_f32_e32 v141, v141
	s_nop 0
	v_pk_mul_f32 v[138:139], v[138:139], v[140:141]
	v_pk_mul_f32 v[140:141], v[28:29], v[160:161] op_sel_hi:[1,0]
	v_cvt_pk_bf16_f32 v132, v138, v139
	v_pk_mul_f32 v[142:143], v[140:141], v[140:141]
	v_mov_b32_e32 v145, v139
	v_pk_fma_f32 v[142:143], v[142:143], s[40:41], 1.0 op_sel_hi:[1,0,0]
	s_nop 0
	v_pk_mul_f32 v[142:143], v[140:141], v[142:143]
	s_nop 0
	v_pk_mul_f32 v[142:143], v[142:143], s[42:43] op_sel_hi:[1,0]
	s_nop 0
	v_pk_mul_f32 v[142:143], v[142:143], s[38:39] op_sel_hi:[1,0]
	s_nop 0
	v_exp_f32_e32 v142, v142
	v_exp_f32_e32 v143, v143
	s_nop 0
	v_pk_add_f32 v[142:143], v[142:143], 1.0 op_sel_hi:[1,0]
	s_nop 0
	v_rcp_f32_e32 v142, v142
	v_rcp_f32_e32 v143, v143
	s_nop 0
	v_pk_mul_f32 v[140:141], v[140:141], v[142:143]
	s_nop 0
	v_cvt_pk_bf16_f32 v133, v140, v141
	s_mov_b32 s98, 0x29000
	s_mov_b32 s99, 0x0
	v_lshl_add_u64 v[252:253], v[250:251], 0, s[98:99]
	global_store_dwordx4 v[252:253], v[130:133], off offset:-4096
	v_mov_b32_e32 v143, v138
	v_mov_b32_e32 v142, v140
	v_pk_mul_f32 v[130:131], v[22:23], v[160:161] op_sel_hi:[1,0]
	v_mov_b32_e32 v144, v141
	v_pk_mul_f32 v[132:133], v[130:131], v[130:131]
	v_pk_add_f32 v[146:147], v[142:143], v[144:145]
	v_pk_fma_f32 v[132:133], v[132:133], s[40:41], 1.0 op_sel_hi:[1,0,0]
	v_pk_mul_f32 v[144:145], v[144:145], v[144:145]
	v_pk_mul_f32 v[132:133], v[130:131], v[132:133]
	v_pk_fma_f32 v[142:143], v[142:143], v[142:143], v[144:145]
	v_pk_mul_f32 v[132:133], v[132:133], s[42:43] op_sel_hi:[1,0]
	v_pk_add_f32 v[136:137], v[142:143], v[136:137] op_sel:[1,0] op_sel_hi:[0,1]
	v_pk_mul_f32 v[132:133], v[132:133], s[38:39] op_sel_hi:[1,0]
	v_pk_add_f32 v[136:137], v[142:143], v[136:137]
	v_exp_f32_e32 v132, v132
	v_exp_f32_e32 v133, v133
	v_add_f32_e32 v147, v147, v148
	v_add_f32_e32 v146, v146, v147
	v_pk_add_f32 v[132:133], v[132:133], 1.0 op_sel_hi:[1,0]
	s_nop 0
	v_rcp_f32_e32 v132, v132
	v_rcp_f32_e32 v133, v133
	s_nop 0
	v_pk_mul_f32 v[130:131], v[130:131], v[132:133]
	v_pk_mul_f32 v[132:133], v[24:25], v[160:161] op_sel_hi:[1,0]
	v_mov_b32_e32 v141, v131
	v_pk_mul_f32 v[138:139], v[132:133], v[132:133]
	s_nop 0
	v_pk_fma_f32 v[138:139], v[138:139], s[40:41], 1.0 op_sel_hi:[1,0,0]
	s_nop 0
	v_pk_mul_f32 v[138:139], v[132:133], v[138:139]
	s_nop 0
	v_pk_mul_f32 v[138:139], v[138:139], s[42:43] op_sel_hi:[1,0]
	s_nop 0
	v_pk_mul_f32 v[138:139], v[138:139], s[38:39] op_sel_hi:[1,0]
	s_nop 0
	v_exp_f32_e32 v138, v138
	v_exp_f32_e32 v139, v139
	s_nop 0
	v_pk_add_f32 v[138:139], v[138:139], 1.0 op_sel_hi:[1,0]
	s_nop 0
	v_rcp_f32_e32 v138, v138
	v_rcp_f32_e32 v139, v139
	s_nop 0
	v_pk_mul_f32 v[132:133], v[132:133], v[138:139]
	s_nop 0
	v_mov_b32_e32 v138, v132
	v_mov_b32_e32 v139, v130
	v_mov_b32_e32 v140, v133
	v_pk_add_f32 v[142:143], v[138:139], v[140:141]
	v_pk_mul_f32 v[140:141], v[140:141], v[140:141]
	v_add_f32_e32 v143, v143, v146
	v_pk_fma_f32 v[138:139], v[138:139], v[138:139], v[140:141]
	v_pk_mul_f32 v[146:147], v[20:21], v[160:161] op_sel_hi:[1,0]
	v_pk_add_f32 v[136:137], v[138:139], v[136:137] op_sel:[1,0] op_sel_hi:[0,1]
	v_pk_add_f32 v[136:137], v[138:139], v[136:137]
	v_pk_mul_f32 v[138:139], v[18:19], v[160:161] op_sel_hi:[1,0]
	v_pk_mul_f32 v[148:149], v[146:147], v[146:147]
	v_pk_mul_f32 v[140:141], v[138:139], v[138:139]
	v_pk_fma_f32 v[148:149], v[148:149], s[40:41], 1.0 op_sel_hi:[1,0,0]
	v_pk_fma_f32 v[140:141], v[140:141], s[40:41], 1.0 op_sel_hi:[1,0,0]
	v_pk_mul_f32 v[148:149], v[146:147], v[148:149]
	v_pk_mul_f32 v[140:141], v[138:139], v[140:141]
	v_pk_mul_f32 v[148:149], v[148:149], s[42:43] op_sel_hi:[1,0]
	v_pk_mul_f32 v[140:141], v[140:141], s[42:43] op_sel_hi:[1,0]
	v_pk_mul_f32 v[148:149], v[148:149], s[38:39] op_sel_hi:[1,0]
	v_pk_mul_f32 v[140:141], v[140:141], s[38:39] op_sel_hi:[1,0]
	v_exp_f32_e32 v148, v148
	v_exp_f32_e32 v140, v140
	v_exp_f32_e32 v141, v141
	v_exp_f32_e32 v149, v149
	v_cvt_pk_bf16_f32 v130, v130, v131
	v_cvt_pk_bf16_f32 v131, v132, v133
	v_pk_add_f32 v[140:141], v[140:141], 1.0 op_sel_hi:[1,0]
	v_pk_add_f32 v[148:149], v[148:149], 1.0 op_sel_hi:[1,0]
	v_rcp_f32_e32 v140, v140
	v_rcp_f32_e32 v141, v141
	v_rcp_f32_e32 v148, v148
	v_rcp_f32_e32 v149, v149
	v_add_f32_e32 v142, v142, v143
	v_pk_mul_f32 v[144:145], v[138:139], v[140:141]
	v_pk_mul_f32 v[146:147], v[146:147], v[148:149]
	v_pk_fma_f32 v[138:139], v[138:139], v[140:141], v[144:145] op_sel:[0,0,1] op_sel_hi:[1,1,0]
	v_mul_f32_e32 v140, v144, v144
	v_pk_fma_f32 v[140:141], v[144:145], v[144:145], v[140:141] op_sel_hi:[1,1,0]
	v_pk_mul_f32 v[148:149], v[146:147], v[146:147]
	v_cvt_pk_bf16_f32 v132, v144, v145
	v_cvt_pk_bf16_f32 v133, v146, v147
	global_store_dwordx4 v[252:253], v[130:133], off offset:-3840
	v_mov_b32_e32 v140, v146
	v_mov_b32_e32 v139, v148
	v_pk_mov_b32 v[130:131], v[146:147], v[136:137] op_sel:[1,0]
	v_mov_b32_e32 v143, v149
	v_pk_add_f32 v[130:131], v[140:141], v[130:131]
	v_pk_add_f32 v[132:133], v[138:139], v[142:143]
	s_nop 0
	v_pk_add_f32 v[130:131], v[132:133], v[130:131]
	ds_bpermute_b32 v132, v223, v130
	ds_bpermute_b32 v133, v223, v131
	s_waitcnt lgkmcnt(0)
	v_pk_add_f32 v[130:131], v[130:131], v[132:133]
	ds_bpermute_b32 v132, v224, v130
	ds_bpermute_b32 v133, v224, v131
	s_and_saveexec_b64 s[62:63], vcc
	s_cbranch_execz .LBB0_1154
	v_lshl_add_u64 v[134:135], s[82:83], 0, v[190:191]
	v_lshl_add_u64 v[134:135], s[0:1], 2, v[134:135]
	s_waitcnt lgkmcnt(0)
	v_pk_add_f32 v[130:131], v[130:131], v[132:133]
	global_store_dwordx2 v[134:135], v[130:131], off
.LBB0_1154:
	s_or_b64 exec, exec, s[62:63]
	v_pk_mul_f32 v[130:131], v[14:15], v[156:157] op_sel_hi:[1,0]
	v_lshlrev_b64 v[134:135], 10, v[154:155]
	s_waitcnt lgkmcnt(0)
	v_pk_mul_f32 v[132:133], v[130:131], v[130:131]
	v_lshl_add_u64 v[134:135], s[14:15], 0, v[134:135]
	v_pk_fma_f32 v[132:133], v[132:133], s[40:41], 1.0 op_sel_hi:[1,0,0]
	v_lshl_add_u64 v[134:135], v[186:187], 1, v[134:135]
	v_pk_mul_f32 v[132:133], v[130:131], v[132:133]
	s_nop 0
	v_pk_mul_f32 v[132:133], v[132:133], s[42:43] op_sel_hi:[1,0]
	s_nop 0
	v_pk_mul_f32 v[132:133], v[132:133], s[38:39] op_sel_hi:[1,0]
	s_nop 0
	v_exp_f32_e32 v132, v132
	v_exp_f32_e32 v133, v133
	s_nop 0
	v_pk_add_f32 v[132:133], v[132:133], 1.0 op_sel_hi:[1,0]
	s_nop 0
	v_rcp_f32_e32 v132, v132
	v_rcp_f32_e32 v133, v133
	s_nop 0
	v_pk_mul_f32 v[130:131], v[130:131], v[132:133]
	v_pk_mul_f32 v[132:133], v[16:17], v[156:157] op_sel_hi:[1,0]
	v_mov_b32_e32 v139, v131
	v_pk_mul_f32 v[136:137], v[132:133], v[132:133]
	s_nop 0
	v_pk_fma_f32 v[136:137], v[136:137], s[40:41], 1.0 op_sel_hi:[1,0,0]
	s_nop 0
	v_pk_mul_f32 v[136:137], v[132:133], v[136:137]
	s_nop 0
	v_pk_mul_f32 v[136:137], v[136:137], s[42:43] op_sel_hi:[1,0]
	s_nop 0
	v_pk_mul_f32 v[136:137], v[136:137], s[38:39] op_sel_hi:[1,0]
	s_nop 0
	v_exp_f32_e32 v136, v136
	v_exp_f32_e32 v137, v137
	s_nop 0
	v_pk_add_f32 v[136:137], v[136:137], 1.0 op_sel_hi:[1,0]
	s_nop 0
	v_rcp_f32_e32 v136, v136
	v_rcp_f32_e32 v137, v137
	s_nop 0
	v_pk_mul_f32 v[132:133], v[132:133], v[136:137]
	s_nop 0
	v_mov_b32_e32 v136, v132
	v_mov_b32_e32 v137, v130
	v_mov_b32_e32 v138, v133
	v_pk_add_f32 v[136:137], v[136:137], v[138:139]
	v_mov_b32_e32 v138, v131
	v_add_f32_e32 v137, 0, v137
	v_mov_b32_e32 v139, v133
	v_add_f32_e32 v148, v136, v137
	v_mov_b32_e32 v136, v130
	v_mov_b32_e32 v137, v132
	v_pk_mul_f32 v[138:139], v[138:139], v[138:139]
	v_cvt_pk_bf16_f32 v130, v130, v131
	v_pk_fma_f32 v[136:137], v[136:137], v[136:137], v[138:139]
	v_pk_mul_f32 v[138:139], v[10:11], v[156:157] op_sel_hi:[1,0]
	v_cvt_pk_bf16_f32 v131, v132, v133
	v_pk_mul_f32 v[140:141], v[138:139], v[138:139]
	v_pk_add_f32 v[136:137], v[136:137], v[136:137] op_sel:[0,1] op_sel_hi:[1,0]
	v_pk_fma_f32 v[140:141], v[140:141], s[40:41], 1.0 op_sel_hi:[1,0,0]
	s_nop 0
	v_pk_mul_f32 v[140:141], v[138:139], v[140:141]
	s_nop 0
	v_pk_mul_f32 v[140:141], v[140:141], s[42:43] op_sel_hi:[1,0]
	s_nop 0
	v_pk_mul_f32 v[140:141], v[140:141], s[38:39] op_sel_hi:[1,0]
	s_nop 0
	v_exp_f32_e32 v140, v140
	v_exp_f32_e32 v141, v141
	s_nop 0
	v_pk_add_f32 v[140:141], v[140:141], 1.0 op_sel_hi:[1,0]
	s_nop 0
	v_rcp_f32_e32 v140, v140
	v_rcp_f32_e32 v141, v141
	s_nop 0
	v_pk_mul_f32 v[138:139], v[138:139], v[140:141]
	v_pk_mul_f32 v[140:141], v[12:13], v[156:157] op_sel_hi:[1,0]
	v_cvt_pk_bf16_f32 v132, v138, v139
	v_pk_mul_f32 v[142:143], v[140:141], v[140:141]
	v_mov_b32_e32 v145, v139
	v_pk_fma_f32 v[142:143], v[142:143], s[40:41], 1.0 op_sel_hi:[1,0,0]
	s_nop 0
	v_pk_mul_f32 v[142:143], v[140:141], v[142:143]
	s_nop 0
	v_pk_mul_f32 v[142:143], v[142:143], s[42:43] op_sel_hi:[1,0]
	s_nop 0
	v_pk_mul_f32 v[142:143], v[142:143], s[38:39] op_sel_hi:[1,0]
	s_nop 0
	v_exp_f32_e32 v142, v142
	v_exp_f32_e32 v143, v143
	s_nop 0
	v_pk_add_f32 v[142:143], v[142:143], 1.0 op_sel_hi:[1,0]
	s_nop 0
	v_rcp_f32_e32 v142, v142
	v_rcp_f32_e32 v143, v143
	s_nop 0
	v_pk_mul_f32 v[140:141], v[140:141], v[142:143]
	s_nop 0
	v_cvt_pk_bf16_f32 v133, v140, v141
	s_mov_b32 s98, 0x2d000
	s_mov_b32 s99, 0x0
	v_lshl_add_u64 v[252:253], v[250:251], 0, s[98:99]
	global_store_dwordx4 v[252:253], v[130:133], off offset:-4096
	v_mov_b32_e32 v143, v138
	v_mov_b32_e32 v142, v140
	v_pk_mul_f32 v[130:131], v[6:7], v[156:157] op_sel_hi:[1,0]
	v_mov_b32_e32 v144, v141
	v_pk_mul_f32 v[132:133], v[130:131], v[130:131]
	v_pk_add_f32 v[146:147], v[142:143], v[144:145]
	v_pk_fma_f32 v[132:133], v[132:133], s[40:41], 1.0 op_sel_hi:[1,0,0]
	v_pk_mul_f32 v[144:145], v[144:145], v[144:145]
	v_pk_mul_f32 v[132:133], v[130:131], v[132:133]
	v_pk_fma_f32 v[142:143], v[142:143], v[142:143], v[144:145]
	v_pk_mul_f32 v[132:133], v[132:133], s[42:43] op_sel_hi:[1,0]
	v_pk_add_f32 v[136:137], v[142:143], v[136:137] op_sel:[1,0] op_sel_hi:[0,1]
	v_pk_mul_f32 v[132:133], v[132:133], s[38:39] op_sel_hi:[1,0]
	v_pk_add_f32 v[136:137], v[142:143], v[136:137]
	v_exp_f32_e32 v132, v132
	v_exp_f32_e32 v133, v133
	v_add_f32_e32 v147, v147, v148
	v_add_f32_e32 v146, v146, v147
	v_pk_add_f32 v[132:133], v[132:133], 1.0 op_sel_hi:[1,0]
	s_nop 0
	v_rcp_f32_e32 v132, v132
	v_rcp_f32_e32 v133, v133
	s_nop 0
	v_pk_mul_f32 v[130:131], v[130:131], v[132:133]
	v_pk_mul_f32 v[132:133], v[8:9], v[156:157] op_sel_hi:[1,0]
	v_mov_b32_e32 v141, v131
	v_pk_mul_f32 v[138:139], v[132:133], v[132:133]
	s_nop 0
	v_pk_fma_f32 v[138:139], v[138:139], s[40:41], 1.0 op_sel_hi:[1,0,0]
	s_nop 0
	v_pk_mul_f32 v[138:139], v[132:133], v[138:139]
	s_nop 0
	v_pk_mul_f32 v[138:139], v[138:139], s[42:43] op_sel_hi:[1,0]
	s_nop 0
	v_pk_mul_f32 v[138:139], v[138:139], s[38:39] op_sel_hi:[1,0]
	s_nop 0
	v_exp_f32_e32 v138, v138
	v_exp_f32_e32 v139, v139
	s_nop 0
	v_pk_add_f32 v[138:139], v[138:139], 1.0 op_sel_hi:[1,0]
	s_nop 0
	v_rcp_f32_e32 v138, v138
	v_rcp_f32_e32 v139, v139
	s_nop 0
	v_pk_mul_f32 v[132:133], v[132:133], v[138:139]
	s_nop 0
	v_mov_b32_e32 v138, v132
	v_mov_b32_e32 v139, v130
	v_mov_b32_e32 v140, v133
	v_pk_add_f32 v[142:143], v[138:139], v[140:141]
	v_pk_mul_f32 v[140:141], v[140:141], v[140:141]
	v_add_f32_e32 v143, v143, v146
	v_pk_fma_f32 v[138:139], v[138:139], v[138:139], v[140:141]
	v_pk_mul_f32 v[146:147], v[4:5], v[156:157] op_sel_hi:[1,0]
	v_pk_add_f32 v[136:137], v[138:139], v[136:137] op_sel:[1,0] op_sel_hi:[0,1]
	v_pk_add_f32 v[136:137], v[138:139], v[136:137]
	v_pk_mul_f32 v[138:139], v[2:3], v[156:157] op_sel_hi:[1,0]
	v_pk_mul_f32 v[148:149], v[146:147], v[146:147]
	v_pk_mul_f32 v[140:141], v[138:139], v[138:139]
	v_pk_fma_f32 v[148:149], v[148:149], s[40:41], 1.0 op_sel_hi:[1,0,0]
	v_pk_fma_f32 v[140:141], v[140:141], s[40:41], 1.0 op_sel_hi:[1,0,0]
	v_pk_mul_f32 v[148:149], v[146:147], v[148:149]
	v_pk_mul_f32 v[140:141], v[138:139], v[140:141]
	v_pk_mul_f32 v[148:149], v[148:149], s[42:43] op_sel_hi:[1,0]
	v_pk_mul_f32 v[140:141], v[140:141], s[42:43] op_sel_hi:[1,0]
	v_pk_mul_f32 v[148:149], v[148:149], s[38:39] op_sel_hi:[1,0]
	v_pk_mul_f32 v[140:141], v[140:141], s[38:39] op_sel_hi:[1,0]
	v_exp_f32_e32 v148, v148
	v_exp_f32_e32 v140, v140
	v_exp_f32_e32 v141, v141
	v_exp_f32_e32 v149, v149
	v_cvt_pk_bf16_f32 v130, v130, v131
	v_cvt_pk_bf16_f32 v131, v132, v133
	v_pk_add_f32 v[140:141], v[140:141], 1.0 op_sel_hi:[1,0]
	v_pk_add_f32 v[148:149], v[148:149], 1.0 op_sel_hi:[1,0]
	v_rcp_f32_e32 v140, v140
	v_rcp_f32_e32 v141, v141
	v_rcp_f32_e32 v148, v148
	v_rcp_f32_e32 v149, v149
	v_add_f32_e32 v142, v142, v143
	v_pk_mul_f32 v[144:145], v[138:139], v[140:141]
	v_pk_mul_f32 v[146:147], v[146:147], v[148:149]
	v_pk_fma_f32 v[138:139], v[138:139], v[140:141], v[144:145] op_sel:[0,0,1] op_sel_hi:[1,1,0]
	v_mul_f32_e32 v140, v144, v144
	v_pk_fma_f32 v[140:141], v[144:145], v[144:145], v[140:141] op_sel_hi:[1,1,0]
	v_pk_mul_f32 v[148:149], v[146:147], v[146:147]
	v_cvt_pk_bf16_f32 v132, v144, v145
	v_cvt_pk_bf16_f32 v133, v146, v147
	global_store_dwordx4 v[252:253], v[130:133], off offset:-3840
	v_mov_b32_e32 v140, v146
	v_mov_b32_e32 v139, v148
	v_pk_mov_b32 v[130:131], v[146:147], v[136:137] op_sel:[1,0]
	v_mov_b32_e32 v143, v149
	v_pk_add_f32 v[130:131], v[140:141], v[130:131]
	v_pk_add_f32 v[132:133], v[138:139], v[142:143]
	s_nop 0
	v_pk_add_f32 v[130:131], v[132:133], v[130:131]
	ds_bpermute_b32 v132, v223, v130
	ds_bpermute_b32 v133, v223, v131
	s_waitcnt lgkmcnt(0)
	v_pk_add_f32 v[130:131], v[130:131], v[132:133]
	ds_bpermute_b32 v132, v224, v130
	ds_bpermute_b32 v133, v224, v131
	s_and_saveexec_b64 s[62:63], vcc
	s_cbranch_execz .LBB0_1156
	v_lshl_add_u64 v[134:135], s[82:83], 0, v[188:189]
	v_lshl_add_u64 v[134:135], s[0:1], 2, v[134:135]
	s_waitcnt lgkmcnt(0)
	v_pk_add_f32 v[130:131], v[130:131], v[132:133]
	global_store_dwordx2 v[134:135], v[130:131], off

.LBB0_1168:
	s_or_b64 exec, exec, s[62:63]
	v_lshlrev_b64 v[142:143], 10, v[182:183]
	s_waitcnt lgkmcnt(0)
	v_pk_mul_f32 v[132:133], v[128:129], v[184:185] op_sel_hi:[1,0]
	v_pk_mul_f32 v[130:131], v[126:127], v[184:185] op_sel_hi:[1,0]
	v_pk_mul_f32 v[136:137], v[124:125], v[184:185] op_sel_hi:[1,0]
	v_pk_mul_f32 v[134:135], v[122:123], v[184:185] op_sel_hi:[1,0]
	v_lshl_add_u64 v[142:143], s[44:45], 0, v[142:143]
	v_ashrrev_i32_e32 v187, 31, v186
	v_cmp_ne_u64_e32 vcc, 0, v[140:141]
	v_cvt_pk_bf16_f32 v144, v130, v131
	v_cvt_pk_bf16_f32 v145, v132, v133
	v_cvt_pk_bf16_f32 v146, v134, v135
	v_cvt_pk_bf16_f32 v147, v136, v137
	v_lshl_add_u64 v[142:143], v[186:187], 1, v[142:143]
	v_lshl_add_u64 v[140:141], v[186:187], 2, v[140:141]
	v_lshl_add_u64 v[188:189], v[142:143], 0, 0
	global_store_dwordx4 v[142:143], v[144:147], off
	s_and_saveexec_b64 s[62:63], vcc
	s_cbranch_execz .LBB0_1170
	global_store_dwordx4 v[140:141], v[130:133], off
	global_store_dwordx4 v[140:141], v[134:137], off offset:16
.LBB0_1170:
	s_or_b64 exec, exec, s[62:63]
	v_mov_b32_e32 v185, v184
	v_mov_b32_e32 v134, v184
	v_mov_b32_e32 v135, v184
	v_pk_mul_f32 v[132:133], v[120:121], v[134:135]
	v_pk_mul_f32 v[130:131], v[118:119], v[184:185]
	v_pk_mul_f32 v[136:137], v[116:117], v[134:135]
	v_pk_mul_f32 v[134:135], v[114:115], v[184:185]
	v_cvt_pk_bf16_f32 v144, v130, v131
	v_cvt_pk_bf16_f32 v145, v132, v133
	v_cvt_pk_bf16_f32 v146, v134, v135
	v_cvt_pk_bf16_f32 v147, v136, v137
	s_mov_b32 s98, 0x1000
	s_mov_b32 s99, 0x0
	v_lshl_add_u64 v[190:191], v[188:189], 0, s[98:99]
	global_store_dwordx4 v[190:191], v[144:147], off offset:-3840
	s_and_saveexec_b64 s[62:63], vcc
	s_cbranch_execz .LBB0_1172
	global_store_dwordx4 v[140:141], v[130:133], off offset:512
	global_store_dwordx4 v[140:141], v[134:137], off offset:528

.LBB0_1180:
	s_or_b64 exec, exec, s[62:63]
	v_pk_mul_f32 v[132:133], v[112:113], v[180:181] op_sel_hi:[1,0]
	v_pk_mul_f32 v[130:131], v[110:111], v[180:181] op_sel_hi:[1,0]
	v_pk_mul_f32 v[136:137], v[108:109], v[180:181] op_sel_hi:[1,0]
	v_pk_mul_f32 v[134:135], v[106:107], v[180:181] op_sel_hi:[1,0]
	v_cmp_ne_u64_e32 vcc, 0, v[140:141]
	v_cvt_pk_bf16_f32 v144, v130, v131
	v_cvt_pk_bf16_f32 v145, v132, v133
	v_cvt_pk_bf16_f32 v146, v134, v135
	v_cvt_pk_bf16_f32 v147, v136, v137
	s_nop 0
	v_lshl_add_u64 v[140:141], v[186:187], 2, v[140:141]
	s_mov_b32 s98, 0x5000
	s_mov_b32 s99, 0x0
	v_lshl_add_u64 v[190:191], v[188:189], 0, s[98:99]
	global_store_dwordx4 v[190:191], v[144:147], off offset:-4096
	s_and_saveexec_b64 s[62:63], vcc
	s_cbranch_execz .LBB0_1182
	global_store_dwordx4 v[140:141], v[130:133], off
	global_store_dwordx4 v[140:141], v[134:137], off offset:16
.LBB0_1182:
	s_or_b64 exec, exec, s[62:63]
	v_mov_b32_e32 v181, v180
	v_mov_b32_e32 v134, v180
	v_mov_b32_e32 v135, v180
	v_pk_mul_f32 v[132:133], v[104:105], v[134:135]
	v_pk_mul_f32 v[130:131], v[102:103], v[180:181]
	v_pk_mul_f32 v[136:137], v[100:101], v[134:135]
	v_pk_mul_f32 v[134:135], v[98:99], v[180:181]
	v_cvt_pk_bf16_f32 v144, v130, v131
	v_cvt_pk_bf16_f32 v145, v132, v133
	v_cvt_pk_bf16_f32 v146, v134, v135
	v_cvt_pk_bf16_f32 v147, v136, v137
	global_store_dwordx4 v[190:191], v[144:147], off offset:-3840
	s_and_saveexec_b64 s[62:63], vcc
	s_cbranch_execz .LBB0_1184
	global_store_dwordx4 v[140:141], v[130:133], off offset:512
	global_store_dwordx4 v[140:141], v[134:137], off offset:528

.LBB0_1192:
	s_or_b64 exec, exec, s[62:63]
	v_pk_mul_f32 v[132:133], v[96:97], v[176:177] op_sel_hi:[1,0]
	v_pk_mul_f32 v[130:131], v[94:95], v[176:177] op_sel_hi:[1,0]
	v_pk_mul_f32 v[136:137], v[92:93], v[176:177] op_sel_hi:[1,0]
	v_pk_mul_f32 v[134:135], v[90:91], v[176:177] op_sel_hi:[1,0]
	v_cmp_ne_u64_e32 vcc, 0, v[140:141]
	v_cvt_pk_bf16_f32 v144, v130, v131
	v_cvt_pk_bf16_f32 v145, v132, v133
	v_cvt_pk_bf16_f32 v146, v134, v135
	v_cvt_pk_bf16_f32 v147, v136, v137
	s_nop 0
	v_lshl_add_u64 v[140:141], v[186:187], 2, v[140:141]
	s_mov_b32 s98, 0x9000
	s_mov_b32 s99, 0x0
	v_lshl_add_u64 v[190:191], v[188:189], 0, s[98:99]
	global_store_dwordx4 v[190:191], v[144:147], off offset:-4096
	s_and_saveexec_b64 s[62:63], vcc
	s_cbranch_execz .LBB0_1194
	global_store_dwordx4 v[140:141], v[130:133], off
	global_store_dwordx4 v[140:141], v[134:137], off offset:16
.LBB0_1194:
	s_or_b64 exec, exec, s[62:63]
	v_mov_b32_e32 v177, v176
	v_mov_b32_e32 v134, v176
	v_mov_b32_e32 v135, v176
	v_pk_mul_f32 v[132:133], v[88:89], v[134:135]
	v_pk_mul_f32 v[130:131], v[86:87], v[176:177]
	v_pk_mul_f32 v[136:137], v[84:85], v[134:135]
	v_pk_mul_f32 v[134:135], v[82:83], v[176:177]
	v_cvt_pk_bf16_f32 v144, v130, v131
	v_cvt_pk_bf16_f32 v145, v132, v133
	v_cvt_pk_bf16_f32 v146, v134, v135
	v_cvt_pk_bf16_f32 v147, v136, v137
	global_store_dwordx4 v[190:191], v[144:147], off offset:-3840
	s_and_saveexec_b64 s[62:63], vcc
	s_cbranch_execz .LBB0_1196
	global_store_dwordx4 v[140:141], v[130:133], off offset:512
	global_store_dwordx4 v[140:141], v[134:137], off offset:528

.LBB0_1204:
	s_or_b64 exec, exec, s[62:63]
	v_pk_mul_f32 v[132:133], v[80:81], v[172:173] op_sel_hi:[1,0]
	v_pk_mul_f32 v[130:131], v[78:79], v[172:173] op_sel_hi:[1,0]
	v_pk_mul_f32 v[136:137], v[76:77], v[172:173] op_sel_hi:[1,0]
	v_pk_mul_f32 v[134:135], v[74:75], v[172:173] op_sel_hi:[1,0]
	v_cmp_ne_u64_e32 vcc, 0, v[140:141]
	v_cvt_pk_bf16_f32 v144, v130, v131
	v_cvt_pk_bf16_f32 v145, v132, v133
	v_cvt_pk_bf16_f32 v146, v134, v135
	v_cvt_pk_bf16_f32 v147, v136, v137
	s_nop 0
	v_lshl_add_u64 v[140:141], v[186:187], 2, v[140:141]
	s_mov_b32 s98, 0xd000
	s_mov_b32 s99, 0x0
	v_lshl_add_u64 v[190:191], v[188:189], 0, s[98:99]
	global_store_dwordx4 v[190:191], v[144:147], off offset:-4096
	s_and_saveexec_b64 s[62:63], vcc
	s_cbranch_execz .LBB0_1206
	global_store_dwordx4 v[140:141], v[130:133], off
	global_store_dwordx4 v[140:141], v[134:137], off offset:16
.LBB0_1206:
	s_or_b64 exec, exec, s[62:63]
	v_mov_b32_e32 v173, v172
	v_mov_b32_e32 v134, v172
	v_mov_b32_e32 v135, v172
	v_pk_mul_f32 v[132:133], v[72:73], v[134:135]
	v_pk_mul_f32 v[130:131], v[70:71], v[172:173]
	v_pk_mul_f32 v[136:137], v[68:69], v[134:135]
	v_pk_mul_f32 v[134:135], v[66:67], v[172:173]
	v_cvt_pk_bf16_f32 v144, v130, v131
	v_cvt_pk_bf16_f32 v145, v132, v133
	v_cvt_pk_bf16_f32 v146, v134, v135
	v_cvt_pk_bf16_f32 v147, v136, v137
	global_store_dwordx4 v[190:191], v[144:147], off offset:-3840
	s_and_saveexec_b64 s[62:63], vcc
	s_cbranch_execz .LBB0_1208
	global_store_dwordx4 v[140:141], v[130:133], off offset:512
	global_store_dwordx4 v[140:141], v[134:137], off offset:528

.LBB0_1216:
	s_or_b64 exec, exec, s[62:63]
	v_pk_mul_f32 v[132:133], v[64:65], v[168:169] op_sel_hi:[1,0]
	v_pk_mul_f32 v[130:131], v[62:63], v[168:169] op_sel_hi:[1,0]
	v_pk_mul_f32 v[136:137], v[60:61], v[168:169] op_sel_hi:[1,0]
	v_pk_mul_f32 v[134:135], v[58:59], v[168:169] op_sel_hi:[1,0]
	v_cmp_ne_u64_e32 vcc, 0, v[140:141]
	v_cvt_pk_bf16_f32 v144, v130, v131
	v_cvt_pk_bf16_f32 v145, v132, v133
	v_cvt_pk_bf16_f32 v146, v134, v135
	v_cvt_pk_bf16_f32 v147, v136, v137
	s_nop 0
	v_lshl_add_u64 v[140:141], v[186:187], 2, v[140:141]
	s_mov_b32 s98, 0x21000
	s_mov_b32 s99, 0x0
	v_lshl_add_u64 v[190:191], v[188:189], 0, s[98:99]
	global_store_dwordx4 v[190:191], v[144:147], off offset:-4096
	s_and_saveexec_b64 s[62:63], vcc
	s_cbranch_execz .LBB0_1218
	global_store_dwordx4 v[140:141], v[130:133], off
	global_store_dwordx4 v[140:141], v[134:137], off offset:16
.LBB0_1218:
	s_or_b64 exec, exec, s[62:63]
	v_mov_b32_e32 v169, v168
	v_mov_b32_e32 v134, v168
	v_mov_b32_e32 v135, v168
	v_pk_mul_f32 v[132:133], v[56:57], v[134:135]
	v_pk_mul_f32 v[130:131], v[54:55], v[168:169]
	v_pk_mul_f32 v[136:137], v[52:53], v[134:135]
	v_pk_mul_f32 v[134:135], v[50:51], v[168:169]
	v_cvt_pk_bf16_f32 v144, v130, v131
	v_cvt_pk_bf16_f32 v145, v132, v133
	v_cvt_pk_bf16_f32 v146, v134, v135
	v_cvt_pk_bf16_f32 v147, v136, v137
	global_store_dwordx4 v[190:191], v[144:147], off offset:-3840
	s_and_saveexec_b64 s[62:63], vcc
	s_cbranch_execz .LBB0_1220
	global_store_dwordx4 v[140:141], v[130:133], off offset:512
	global_store_dwordx4 v[140:141], v[134:137], off offset:528

.LBB0_1228:
	s_or_b64 exec, exec, s[62:63]
	v_pk_mul_f32 v[132:133], v[48:49], v[164:165] op_sel_hi:[1,0]
	v_pk_mul_f32 v[130:131], v[46:47], v[164:165] op_sel_hi:[1,0]
	v_pk_mul_f32 v[136:137], v[44:45], v[164:165] op_sel_hi:[1,0]
	v_pk_mul_f32 v[134:135], v[42:43], v[164:165] op_sel_hi:[1,0]
	v_cmp_ne_u64_e32 vcc, 0, v[140:141]
	v_cvt_pk_bf16_f32 v144, v130, v131
	v_cvt_pk_bf16_f32 v145, v132, v133
	v_cvt_pk_bf16_f32 v146, v134, v135
	v_cvt_pk_bf16_f32 v147, v136, v137
	s_nop 0
	v_lshl_add_u64 v[140:141], v[186:187], 2, v[140:141]
	s_mov_b32 s98, 0x25000
	s_mov_b32 s99, 0x0
	v_lshl_add_u64 v[190:191], v[188:189], 0, s[98:99]
	global_store_dwordx4 v[190:191], v[144:147], off offset:-4096
	s_and_saveexec_b64 s[62:63], vcc
	s_cbranch_execz .LBB0_1230
	global_store_dwordx4 v[140:141], v[130:133], off
	global_store_dwordx4 v[140:141], v[134:137], off offset:16
.LBB0_1230:
	s_or_b64 exec, exec, s[62:63]
	v_mov_b32_e32 v165, v164
	v_mov_b32_e32 v134, v164
	v_mov_b32_e32 v135, v164
	v_pk_mul_f32 v[132:133], v[40:41], v[134:135]
	v_pk_mul_f32 v[130:131], v[38:39], v[164:165]
	v_pk_mul_f32 v[136:137], v[36:37], v[134:135]
	v_pk_mul_f32 v[134:135], v[34:35], v[164:165]
	v_cvt_pk_bf16_f32 v144, v130, v131
	v_cvt_pk_bf16_f32 v145, v132, v133
	v_cvt_pk_bf16_f32 v146, v134, v135
	v_cvt_pk_bf16_f32 v147, v136, v137
	global_store_dwordx4 v[190:191], v[144:147], off offset:-3840
	s_and_saveexec_b64 s[62:63], vcc
	s_cbranch_execz .LBB0_1232
	global_store_dwordx4 v[140:141], v[130:133], off offset:512
	global_store_dwordx4 v[140:141], v[134:137], off offset:528

.LBB0_1240:
	s_or_b64 exec, exec, s[62:63]
	v_pk_mul_f32 v[132:133], v[32:33], v[160:161] op_sel_hi:[1,0]
	v_pk_mul_f32 v[130:131], v[30:31], v[160:161] op_sel_hi:[1,0]
	v_pk_mul_f32 v[136:137], v[28:29], v[160:161] op_sel_hi:[1,0]
	v_pk_mul_f32 v[134:135], v[26:27], v[160:161] op_sel_hi:[1,0]
	v_cmp_ne_u64_e32 vcc, 0, v[140:141]
	v_cvt_pk_bf16_f32 v144, v130, v131
	v_cvt_pk_bf16_f32 v145, v132, v133
	v_cvt_pk_bf16_f32 v146, v134, v135
	v_cvt_pk_bf16_f32 v147, v136, v137
	s_nop 0
	v_lshl_add_u64 v[140:141], v[186:187], 2, v[140:141]
	s_mov_b32 s98, 0x29000
	s_mov_b32 s99, 0x0
	v_lshl_add_u64 v[190:191], v[188:189], 0, s[98:99]
	global_store_dwordx4 v[190:191], v[144:147], off offset:-4096
	s_and_saveexec_b64 s[62:63], vcc
	s_cbranch_execz .LBB0_1242
	global_store_dwordx4 v[140:141], v[130:133], off
	global_store_dwordx4 v[140:141], v[134:137], off offset:16
.LBB0_1242:
	s_or_b64 exec, exec, s[62:63]
	v_mov_b32_e32 v161, v160
	v_mov_b32_e32 v134, v160
	v_mov_b32_e32 v135, v160
	v_pk_mul_f32 v[132:133], v[24:25], v[134:135]
	v_pk_mul_f32 v[130:131], v[22:23], v[160:161]
	v_pk_mul_f32 v[136:137], v[20:21], v[134:135]
	v_pk_mul_f32 v[134:135], v[18:19], v[160:161]
	v_cvt_pk_bf16_f32 v144, v130, v131
	v_cvt_pk_bf16_f32 v145, v132, v133
	v_cvt_pk_bf16_f32 v146, v134, v135
	v_cvt_pk_bf16_f32 v147, v136, v137
	global_store_dwordx4 v[190:191], v[144:147], off offset:-3840
	s_and_saveexec_b64 s[62:63], vcc
	s_cbranch_execz .LBB0_1244
	global_store_dwordx4 v[140:141], v[130:133], off offset:512
	global_store_dwordx4 v[140:141], v[134:137], off offset:528

.LBB0_1252:
	s_or_b64 exec, exec, s[0:1]
	v_pk_mul_f32 v[132:133], v[16:17], v[156:157] op_sel_hi:[1,0]
	v_pk_mul_f32 v[130:131], v[14:15], v[156:157] op_sel_hi:[1,0]
	v_pk_mul_f32 v[136:137], v[12:13], v[156:157] op_sel_hi:[1,0]
	v_pk_mul_f32 v[134:135], v[10:11], v[156:157] op_sel_hi:[1,0]
	v_cmp_ne_u64_e32 vcc, 0, v[140:141]
	v_cvt_pk_bf16_f32 v144, v130, v131
	v_cvt_pk_bf16_f32 v145, v132, v133
	v_cvt_pk_bf16_f32 v146, v134, v135
	v_cvt_pk_bf16_f32 v147, v136, v137
	s_nop 0
	v_lshl_add_u64 v[138:139], v[186:187], 2, v[140:141]
	s_mov_b32 s98, 0x2d000
	s_mov_b32 s99, 0x0
	v_lshl_add_u64 v[190:191], v[188:189], 0, s[98:99]
	global_store_dwordx4 v[190:191], v[144:147], off offset:-4096
	s_and_saveexec_b64 s[0:1], vcc
	s_cbranch_execz .LBB0_1254
	global_store_dwordx4 v[138:139], v[130:133], off
	global_store_dwordx4 v[138:139], v[134:137], off offset:16
.LBB0_1254:
	s_or_b64 exec, exec, s[0:1]
	v_mov_b32_e32 v157, v156
	v_mov_b32_e32 v134, v156
	v_mov_b32_e32 v135, v156
	v_pk_mul_f32 v[132:133], v[8:9], v[134:135]
	v_pk_mul_f32 v[130:131], v[6:7], v[156:157]
	v_pk_mul_f32 v[136:137], v[4:5], v[134:135]
	v_pk_mul_f32 v[134:135], v[2:3], v[156:157]
	v_cvt_pk_bf16_f32 v144, v130, v131
	v_cvt_pk_bf16_f32 v145, v132, v133
	v_cvt_pk_bf16_f32 v146, v134, v135
	v_cvt_pk_bf16_f32 v147, v136, v137
	global_store_dwordx4 v[190:191], v[144:147], off offset:-3840
	s_and_saveexec_b64 s[0:1], vcc
	s_cbranch_execz .LBB0_1256
	global_store_dwordx4 v[138:139], v[130:133], off offset:512
	global_store_dwordx4 v[138:139], v[134:137], off offset:528

.LBB0_1257:
	s_and_b64 vcc, exec, s[0:1]
	s_cbranch_vccz .LBB0_1259
	v_pk_mul_f32 v[126:127], v[126:127], v[184:185] op_sel_hi:[1,0]
	v_pk_mul_f32 v[128:129], v[128:129], v[184:185] op_sel_hi:[1,0]
	s_waitcnt lgkmcnt(0)
	v_pk_mul_f32 v[132:133], v[126:127], v[126:127]
	v_pk_mul_f32 v[122:123], v[122:123], v[184:185] op_sel_hi:[1,0]
	v_pk_fma_f32 v[132:133], v[132:133], s[40:41], 1.0 op_sel_hi:[1,0,0]
	v_pk_mul_f32 v[124:125], v[124:125], v[184:185] op_sel_hi:[1,0]
	v_pk_mul_f32 v[132:133], v[126:127], v[132:133]
	v_ashrrev_i32_e32 v187, 31, v186
	v_pk_mul_f32 v[132:133], v[132:133], s[42:43] op_sel_hi:[1,0]
	v_lshlrev_b64 v[130:131], 10, v[182:183]
	v_pk_mul_f32 v[132:133], v[132:133], s[38:39] op_sel_hi:[1,0]
	v_pk_mul_f32 v[118:119], v[118:119], v[184:185] op_sel_hi:[1,0]
	v_exp_f32_e32 v132, v132
	v_exp_f32_e32 v133, v133
	v_pk_mul_f32 v[120:121], v[120:121], v[184:185] op_sel_hi:[1,0]
	v_pk_mul_f32 v[114:115], v[114:115], v[184:185] op_sel_hi:[1,0]
	v_pk_mul_f32 v[110:111], v[110:111], v[180:181] op_sel_hi:[1,0]
	v_pk_add_f32 v[132:133], v[132:133], 1.0 op_sel_hi:[1,0]
	v_pk_mul_f32 v[112:113], v[112:113], v[180:181] op_sel_hi:[1,0]
	v_rcp_f32_e32 v132, v132
	v_rcp_f32_e32 v133, v133
	v_pk_mul_f32 v[106:107], v[106:107], v[180:181] op_sel_hi:[1,0]
	v_pk_mul_f32 v[102:103], v[102:103], v[180:181] op_sel_hi:[1,0]
	v_pk_mul_f32 v[104:105], v[104:105], v[180:181] op_sel_hi:[1,0]
	v_pk_mul_f32 v[126:127], v[126:127], v[132:133]
	v_pk_mul_f32 v[132:133], v[128:129], v[128:129]
	v_pk_mul_f32 v[98:99], v[98:99], v[180:181] op_sel_hi:[1,0]
	v_pk_fma_f32 v[132:133], v[132:133], s[40:41], 1.0 op_sel_hi:[1,0,0]
	v_pk_mul_f32 v[94:95], v[94:95], v[176:177] op_sel_hi:[1,0]
	v_pk_mul_f32 v[132:133], v[128:129], v[132:133]
	v_pk_mul_f32 v[96:97], v[96:97], v[176:177] op_sel_hi:[1,0]
	v_pk_mul_f32 v[132:133], v[132:133], s[42:43] op_sel_hi:[1,0]
	v_pk_mul_f32 v[90:91], v[90:91], v[176:177] op_sel_hi:[1,0]
	v_pk_mul_f32 v[132:133], v[132:133], s[38:39] op_sel_hi:[1,0]
	v_pk_mul_f32 v[86:87], v[86:87], v[176:177] op_sel_hi:[1,0]
	v_exp_f32_e32 v132, v132
	v_exp_f32_e32 v133, v133
	v_pk_mul_f32 v[88:89], v[88:89], v[176:177] op_sel_hi:[1,0]
	v_pk_mul_f32 v[82:83], v[82:83], v[176:177] op_sel_hi:[1,0]
	v_pk_mul_f32 v[78:79], v[78:79], v[172:173] op_sel_hi:[1,0]
	v_pk_add_f32 v[132:133], v[132:133], 1.0 op_sel_hi:[1,0]
	v_pk_mul_f32 v[80:81], v[80:81], v[172:173] op_sel_hi:[1,0]
	v_rcp_f32_e32 v132, v132
	v_rcp_f32_e32 v133, v133
	v_pk_mul_f32 v[74:75], v[74:75], v[172:173] op_sel_hi:[1,0]
	v_pk_mul_f32 v[70:71], v[70:71], v[172:173] op_sel_hi:[1,0]
	v_pk_mul_f32 v[72:73], v[72:73], v[172:173] op_sel_hi:[1,0]
	v_pk_mul_f32 v[128:129], v[128:129], v[132:133]
	v_pk_mul_f32 v[132:133], v[122:123], v[122:123]
	v_pk_mul_f32 v[66:67], v[66:67], v[172:173] op_sel_hi:[1,0]
	v_pk_fma_f32 v[132:133], v[132:133], s[40:41], 1.0 op_sel_hi:[1,0,0]
	v_pk_mul_f32 v[62:63], v[62:63], v[168:169] op_sel_hi:[1,0]
	v_pk_mul_f32 v[132:133], v[122:123], v[132:133]
	v_pk_mul_f32 v[64:65], v[64:65], v[168:169] op_sel_hi:[1,0]
	v_pk_mul_f32 v[132:133], v[132:133], s[42:43] op_sel_hi:[1,0]
	v_pk_mul_f32 v[58:59], v[58:59], v[168:169] op_sel_hi:[1,0]
	v_pk_mul_f32 v[132:133], v[132:133], s[38:39] op_sel_hi:[1,0]
	v_pk_mul_f32 v[54:55], v[54:55], v[168:169] op_sel_hi:[1,0]
	v_exp_f32_e32 v132, v132
	v_exp_f32_e32 v133, v133
	v_pk_mul_f32 v[56:57], v[56:57], v[168:169] op_sel_hi:[1,0]
	v_pk_mul_f32 v[50:51], v[50:51], v[168:169] op_sel_hi:[1,0]
	v_pk_mul_f32 v[46:47], v[46:47], v[164:165] op_sel_hi:[1,0]
	v_pk_add_f32 v[132:133], v[132:133], 1.0 op_sel_hi:[1,0]
	v_pk_mul_f32 v[48:49], v[48:49], v[164:165] op_sel_hi:[1,0]
	v_rcp_f32_e32 v132, v132
	v_rcp_f32_e32 v133, v133
	v_pk_mul_f32 v[42:43], v[42:43], v[164:165] op_sel_hi:[1,0]
	v_pk_mul_f32 v[38:39], v[38:39], v[164:165] op_sel_hi:[1,0]
	v_pk_mul_f32 v[40:41], v[40:41], v[164:165] op_sel_hi:[1,0]
	v_pk_mul_f32 v[122:123], v[122:123], v[132:133]
	v_pk_mul_f32 v[132:133], v[124:125], v[124:125]
	v_pk_mul_f32 v[34:35], v[34:35], v[164:165] op_sel_hi:[1,0]
	v_pk_fma_f32 v[132:133], v[132:133], s[40:41], 1.0 op_sel_hi:[1,0,0]
	v_pk_mul_f32 v[30:31], v[30:31], v[160:161] op_sel_hi:[1,0]
	v_pk_mul_f32 v[132:133], v[124:125], v[132:133]
	v_pk_mul_f32 v[32:33], v[32:33], v[160:161] op_sel_hi:[1,0]
	v_pk_mul_f32 v[132:133], v[132:133], s[42:43] op_sel_hi:[1,0]
	v_pk_mul_f32 v[26:27], v[26:27], v[160:161] op_sel_hi:[1,0]
	v_pk_mul_f32 v[132:133], v[132:133], s[38:39] op_sel_hi:[1,0]
	v_pk_mul_f32 v[22:23], v[22:23], v[160:161] op_sel_hi:[1,0]
	v_exp_f32_e32 v132, v132
	v_exp_f32_e32 v133, v133
	v_pk_mul_f32 v[24:25], v[24:25], v[160:161] op_sel_hi:[1,0]
	v_pk_mul_f32 v[18:19], v[18:19], v[160:161] op_sel_hi:[1,0]
	v_pk_mul_f32 v[14:15], v[14:15], v[156:157] op_sel_hi:[1,0]
	v_pk_add_f32 v[132:133], v[132:133], 1.0 op_sel_hi:[1,0]
	v_pk_mul_f32 v[16:17], v[16:17], v[156:157] op_sel_hi:[1,0]
	v_rcp_f32_e32 v132, v132
	v_rcp_f32_e32 v133, v133
	v_pk_mul_f32 v[10:11], v[10:11], v[156:157] op_sel_hi:[1,0]
	v_pk_mul_f32 v[6:7], v[6:7], v[156:157] op_sel_hi:[1,0]
	v_pk_mul_f32 v[8:9], v[8:9], v[156:157] op_sel_hi:[1,0]
	v_pk_mul_f32 v[132:133], v[124:125], v[132:133]
	v_cvt_pk_bf16_f32 v124, v126, v127
	v_cvt_pk_bf16_f32 v125, v128, v129
	v_cvt_pk_bf16_f32 v126, v122, v123
	v_lshl_add_u64 v[128:129], s[60:61], 0, v[130:131]
	v_lshlrev_b64 v[122:123], 1, v[186:187]
	v_cvt_pk_bf16_f32 v127, v132, v133
	v_lshl_add_u64 v[128:129], v[128:129], 0, v[122:123]
	v_lshl_add_u64 v[134:135], v[128:129], 0, 0
	global_store_dwordx4 v[128:129], v[124:127], off
	v_pk_mul_f32 v[2:3], v[2:3], v[156:157] op_sel_hi:[1,0]
	s_nop 0
	v_pk_mul_f32 v[124:125], v[118:119], v[118:119]
	s_nop 0
	v_pk_fma_f32 v[124:125], v[124:125], s[40:41], 1.0 op_sel_hi:[1,0,0]
	s_nop 0
	v_pk_mul_f32 v[124:125], v[118:119], v[124:125]
	s_nop 0
	v_pk_mul_f32 v[124:125], v[124:125], s[42:43] op_sel_hi:[1,0]
	s_nop 0
	v_pk_mul_f32 v[124:125], v[124:125], s[38:39] op_sel_hi:[1,0]
	s_nop 0
	v_exp_f32_e32 v124, v124
	v_exp_f32_e32 v125, v125
	s_nop 0
	v_pk_add_f32 v[124:125], v[124:125], 1.0 op_sel_hi:[1,0]
	s_nop 0
	v_rcp_f32_e32 v124, v124
	v_rcp_f32_e32 v125, v125
	s_nop 0
	v_pk_mul_f32 v[118:119], v[118:119], v[124:125]
	v_pk_mul_f32 v[124:125], v[120:121], v[120:121]
	s_nop 0
	v_pk_fma_f32 v[124:125], v[124:125], s[40:41], 1.0 op_sel_hi:[1,0,0]
	s_nop 0
	v_pk_mul_f32 v[124:125], v[120:121], v[124:125]
	s_nop 0
	v_pk_mul_f32 v[124:125], v[124:125], s[42:43] op_sel_hi:[1,0]
	s_nop 0
	v_pk_mul_f32 v[124:125], v[124:125], s[38:39] op_sel_hi:[1,0]
	s_nop 0
	v_exp_f32_e32 v124, v124
	v_exp_f32_e32 v125, v125
	s_nop 0
	v_pk_add_f32 v[124:125], v[124:125], 1.0 op_sel_hi:[1,0]
	s_nop 0
	v_rcp_f32_e32 v124, v124
	v_rcp_f32_e32 v125, v125
	s_nop 0
	v_pk_mul_f32 v[120:121], v[120:121], v[124:125]
	v_pk_mul_f32 v[124:125], v[114:115], v[114:115]
	s_nop 0
	v_pk_fma_f32 v[124:125], v[124:125], s[40:41], 1.0 op_sel_hi:[1,0,0]
	s_nop 0
	v_pk_mul_f32 v[124:125], v[114:115], v[124:125]
	s_nop 0
	v_pk_mul_f32 v[124:125], v[124:125], s[42:43] op_sel_hi:[1,0]
	s_nop 0
	v_pk_mul_f32 v[124:125], v[124:125], s[38:39] op_sel_hi:[1,0]
	s_nop 0
	v_exp_f32_e32 v124, v124
	v_exp_f32_e32 v125, v125
	s_nop 0
	v_pk_add_f32 v[124:125], v[124:125], 1.0 op_sel_hi:[1,0]
	s_nop 0
	v_rcp_f32_e32 v124, v124
	v_rcp_f32_e32 v125, v125
	s_nop 0
	v_pk_mul_f32 v[124:125], v[114:115], v[124:125]
	v_pk_mul_f32 v[114:115], v[116:117], v[184:185] op_sel_hi:[1,0]
	s_nop 0
	v_pk_mul_f32 v[116:117], v[114:115], v[114:115]
	s_nop 0
	v_pk_fma_f32 v[116:117], v[116:117], s[40:41], 1.0 op_sel_hi:[1,0,0]
	s_nop 0
	v_pk_mul_f32 v[116:117], v[114:115], v[116:117]
	s_nop 0
	v_pk_mul_f32 v[116:117], v[116:117], s[42:43] op_sel_hi:[1,0]
	s_nop 0
	v_pk_mul_f32 v[116:117], v[116:117], s[38:39] op_sel_hi:[1,0]
	s_nop 0
	v_exp_f32_e32 v116, v116
	v_exp_f32_e32 v117, v117
	s_nop 0
	v_pk_add_f32 v[116:117], v[116:117], 1.0 op_sel_hi:[1,0]
	s_nop 0
	v_rcp_f32_e32 v116, v116
	v_rcp_f32_e32 v117, v117
	s_nop 0
	v_pk_mul_f32 v[126:127], v[114:115], v[116:117]
	v_cvt_pk_bf16_f32 v114, v118, v119
	v_cvt_pk_bf16_f32 v115, v120, v121
	v_cvt_pk_bf16_f32 v116, v124, v125
	v_cvt_pk_bf16_f32 v117, v126, v127
	s_mov_b32 s98, 0x1000
	s_mov_b32 s99, 0x0
	v_lshl_add_u64 v[136:137], v[134:135], 0, s[98:99]
	global_store_dwordx4 v[136:137], v[114:117], off offset:-3840
	s_nop 1
	v_pk_mul_f32 v[116:117], v[110:111], v[110:111]
	s_nop 0
	v_pk_fma_f32 v[116:117], v[116:117], s[40:41], 1.0 op_sel_hi:[1,0,0]
	s_nop 0
	v_pk_mul_f32 v[116:117], v[110:111], v[116:117]
	s_nop 0
	v_pk_mul_f32 v[116:117], v[116:117], s[42:43] op_sel_hi:[1,0]
	s_nop 0
	v_pk_mul_f32 v[116:117], v[116:117], s[38:39] op_sel_hi:[1,0]
	s_nop 0
	v_exp_f32_e32 v116, v116
	v_exp_f32_e32 v117, v117
	s_nop 0
	v_pk_add_f32 v[116:117], v[116:117], 1.0 op_sel_hi:[1,0]
	s_nop 0
	v_rcp_f32_e32 v116, v116
	v_rcp_f32_e32 v117, v117
	s_nop 0
	v_pk_mul_f32 v[110:111], v[110:111], v[116:117]
	v_pk_mul_f32 v[116:117], v[112:113], v[112:113]
	s_nop 0
	v_pk_fma_f32 v[116:117], v[116:117], s[40:41], 1.0 op_sel_hi:[1,0,0]
	s_nop 0
	v_pk_mul_f32 v[116:117], v[112:113], v[116:117]
	s_nop 0
	v_pk_mul_f32 v[116:117], v[116:117], s[42:43] op_sel_hi:[1,0]
	s_nop 0
	v_pk_mul_f32 v[116:117], v[116:117], s[38:39] op_sel_hi:[1,0]
	s_nop 0
	v_exp_f32_e32 v116, v116
	v_exp_f32_e32 v117, v117
	s_nop 0
	v_pk_add_f32 v[116:117], v[116:117], 1.0 op_sel_hi:[1,0]
	s_nop 0
	v_rcp_f32_e32 v116, v116
	v_rcp_f32_e32 v117, v117
	s_nop 0
	v_pk_mul_f32 v[112:113], v[112:113], v[116:117]
	v_pk_mul_f32 v[116:117], v[106:107], v[106:107]
	s_nop 0
	v_pk_fma_f32 v[116:117], v[116:117], s[40:41], 1.0 op_sel_hi:[1,0,0]
	s_nop 0
	v_pk_mul_f32 v[116:117], v[106:107], v[116:117]
	s_nop 0
	v_pk_mul_f32 v[116:117], v[116:117], s[42:43] op_sel_hi:[1,0]
	s_nop 0
	v_pk_mul_f32 v[116:117], v[116:117], s[38:39] op_sel_hi:[1,0]
	s_nop 0
	v_exp_f32_e32 v116, v116
	v_exp_f32_e32 v117, v117
	s_nop 0
	v_pk_add_f32 v[116:117], v[116:117], 1.0 op_sel_hi:[1,0]
	s_nop 0
	v_rcp_f32_e32 v116, v116
	v_rcp_f32_e32 v117, v117
	s_nop 0
	v_pk_mul_f32 v[116:117], v[106:107], v[116:117]
	v_pk_mul_f32 v[106:107], v[108:109], v[180:181] op_sel_hi:[1,0]
	s_nop 0
	v_pk_mul_f32 v[108:109], v[106:107], v[106:107]
	s_nop 0
	v_pk_fma_f32 v[108:109], v[108:109], s[40:41], 1.0 op_sel_hi:[1,0,0]
	s_nop 0
	v_pk_mul_f32 v[108:109], v[106:107], v[108:109]
	s_nop 0
	v_pk_mul_f32 v[108:109], v[108:109], s[42:43] op_sel_hi:[1,0]
	s_nop 0
	v_pk_mul_f32 v[108:109], v[108:109], s[38:39] op_sel_hi:[1,0]
	s_nop 0
	v_exp_f32_e32 v108, v108
	v_exp_f32_e32 v109, v109
	s_nop 0
	v_pk_add_f32 v[108:109], v[108:109], 1.0 op_sel_hi:[1,0]
	s_nop 0
	v_rcp_f32_e32 v108, v108
	v_rcp_f32_e32 v109, v109
	s_nop 0
	v_pk_mul_f32 v[118:119], v[106:107], v[108:109]
	v_cvt_pk_bf16_f32 v106, v110, v111
	s_nop 0
	v_cvt_pk_bf16_f32 v107, v112, v113
	v_cvt_pk_bf16_f32 v108, v116, v117
	v_cvt_pk_bf16_f32 v109, v118, v119
	s_mov_b32 s98, 0x5000
	s_mov_b32 s99, 0x0
	v_lshl_add_u64 v[136:137], v[134:135], 0, s[98:99]
	global_store_dwordx4 v[136:137], v[106:109], off offset:-4096
	s_nop 1
	v_pk_mul_f32 v[106:107], v[102:103], v[102:103]
	s_nop 0
	v_pk_fma_f32 v[106:107], v[106:107], s[40:41], 1.0 op_sel_hi:[1,0,0]
	s_nop 0
	v_pk_mul_f32 v[106:107], v[102:103], v[106:107]
	s_nop 0
	v_pk_mul_f32 v[106:107], v[106:107], s[42:43] op_sel_hi:[1,0]
	s_nop 0
	v_pk_mul_f32 v[106:107], v[106:107], s[38:39] op_sel_hi:[1,0]
	s_nop 0
	v_exp_f32_e32 v106, v106
	v_exp_f32_e32 v107, v107
	s_nop 0
	v_pk_add_f32 v[106:107], v[106:107], 1.0 op_sel_hi:[1,0]
	s_nop 0
	v_rcp_f32_e32 v106, v106
	v_rcp_f32_e32 v107, v107
	s_nop 0
	v_pk_mul_f32 v[102:103], v[102:103], v[106:107]
	v_pk_mul_f32 v[106:107], v[104:105], v[104:105]
	s_nop 0
	v_pk_fma_f32 v[106:107], v[106:107], s[40:41], 1.0 op_sel_hi:[1,0,0]
	s_nop 0
	v_pk_mul_f32 v[106:107], v[104:105], v[106:107]
	s_nop 0
	v_pk_mul_f32 v[106:107], v[106:107], s[42:43] op_sel_hi:[1,0]
	s_nop 0
	v_pk_mul_f32 v[106:107], v[106:107], s[38:39] op_sel_hi:[1,0]
	s_nop 0
	v_exp_f32_e32 v106, v106
	v_exp_f32_e32 v107, v107
	s_nop 0
	v_pk_add_f32 v[106:107], v[106:107], 1.0 op_sel_hi:[1,0]
	s_nop 0
	v_rcp_f32_e32 v106, v106
	v_rcp_f32_e32 v107, v107
	s_nop 0
	v_pk_mul_f32 v[104:105], v[104:105], v[106:107]
	v_pk_mul_f32 v[106:107], v[98:99], v[98:99]
	s_nop 0
	v_pk_fma_f32 v[106:107], v[106:107], s[40:41], 1.0 op_sel_hi:[1,0,0]
	s_nop 0
	v_pk_mul_f32 v[106:107], v[98:99], v[106:107]
	s_nop 0
	v_pk_mul_f32 v[106:107], v[106:107], s[42:43] op_sel_hi:[1,0]
	s_nop 0
	v_pk_mul_f32 v[106:107], v[106:107], s[38:39] op_sel_hi:[1,0]
	s_nop 0
	v_exp_f32_e32 v106, v106
	v_exp_f32_e32 v107, v107
	s_nop 0
	v_pk_add_f32 v[106:107], v[106:107], 1.0 op_sel_hi:[1,0]
	s_nop 0
	v_rcp_f32_e32 v106, v106
	v_rcp_f32_e32 v107, v107
	s_nop 0
	v_pk_mul_f32 v[106:107], v[98:99], v[106:107]
	v_pk_mul_f32 v[98:99], v[100:101], v[180:181] op_sel_hi:[1,0]
	s_nop 0
	v_pk_mul_f32 v[100:101], v[98:99], v[98:99]
	s_nop 0
	v_pk_fma_f32 v[100:101], v[100:101], s[40:41], 1.0 op_sel_hi:[1,0,0]
	s_nop 0
	v_pk_mul_f32 v[100:101], v[98:99], v[100:101]
	s_nop 0
	v_pk_mul_f32 v[100:101], v[100:101], s[42:43] op_sel_hi:[1,0]
	s_nop 0
	v_pk_mul_f32 v[100:101], v[100:101], s[38:39] op_sel_hi:[1,0]
	s_nop 0
	v_exp_f32_e32 v100, v100
	v_exp_f32_e32 v101, v101
	s_nop 0
	v_pk_add_f32 v[100:101], v[100:101], 1.0 op_sel_hi:[1,0]
	s_nop 0
	v_rcp_f32_e32 v100, v100
	v_rcp_f32_e32 v101, v101
	s_nop 0
	v_pk_mul_f32 v[108:109], v[98:99], v[100:101]
	v_cvt_pk_bf16_f32 v98, v102, v103
	v_cvt_pk_bf16_f32 v99, v104, v105
	v_cvt_pk_bf16_f32 v100, v106, v107
	v_cvt_pk_bf16_f32 v101, v108, v109
	global_store_dwordx4 v[136:137], v[98:101], off offset:-3840
	s_nop 1
	v_pk_mul_f32 v[100:101], v[94:95], v[94:95]
	s_nop 0
	v_pk_fma_f32 v[100:101], v[100:101], s[40:41], 1.0 op_sel_hi:[1,0,0]
	s_nop 0
	v_pk_mul_f32 v[100:101], v[94:95], v[100:101]
	s_nop 0
	v_pk_mul_f32 v[100:101], v[100:101], s[42:43] op_sel_hi:[1,0]
	s_nop 0
	v_pk_mul_f32 v[100:101], v[100:101], s[38:39] op_sel_hi:[1,0]
	s_nop 0
	v_exp_f32_e32 v100, v100
	v_exp_f32_e32 v101, v101
	s_nop 0
	v_pk_add_f32 v[100:101], v[100:101], 1.0 op_sel_hi:[1,0]
	s_nop 0
	v_rcp_f32_e32 v100, v100
	v_rcp_f32_e32 v101, v101
	s_nop 0
	v_pk_mul_f32 v[94:95], v[94:95], v[100:101]
	v_pk_mul_f32 v[100:101], v[96:97], v[96:97]
	s_nop 0
	v_pk_fma_f32 v[100:101], v[100:101], s[40:41], 1.0 op_sel_hi:[1,0,0]
	s_nop 0
	v_pk_mul_f32 v[100:101], v[96:97], v[100:101]
	s_nop 0
	v_pk_mul_f32 v[100:101], v[100:101], s[42:43] op_sel_hi:[1,0]
	s_nop 0
	v_pk_mul_f32 v[100:101], v[100:101], s[38:39] op_sel_hi:[1,0]
	s_nop 0
	v_exp_f32_e32 v100, v100
	v_exp_f32_e32 v101, v101
	s_nop 0
	v_pk_add_f32 v[100:101], v[100:101], 1.0 op_sel_hi:[1,0]
	s_nop 0
	v_rcp_f32_e32 v100, v100
	v_rcp_f32_e32 v101, v101
	s_nop 0
	v_pk_mul_f32 v[96:97], v[96:97], v[100:101]
	v_pk_mul_f32 v[100:101], v[90:91], v[90:91]
	s_nop 0
	v_pk_fma_f32 v[100:101], v[100:101], s[40:41], 1.0 op_sel_hi:[1,0,0]
	s_nop 0
	v_pk_mul_f32 v[100:101], v[90:91], v[100:101]
	s_nop 0
	v_pk_mul_f32 v[100:101], v[100:101], s[42:43] op_sel_hi:[1,0]
	s_nop 0
	v_pk_mul_f32 v[100:101], v[100:101], s[38:39] op_sel_hi:[1,0]
	s_nop 0
	v_exp_f32_e32 v100, v100
	v_exp_f32_e32 v101, v101
	s_nop 0
	v_pk_add_f32 v[100:101], v[100:101], 1.0 op_sel_hi:[1,0]
	s_nop 0
	v_rcp_f32_e32 v100, v100
	v_rcp_f32_e32 v101, v101
	s_nop 0
	v_pk_mul_f32 v[100:101], v[90:91], v[100:101]
	v_pk_mul_f32 v[90:91], v[92:93], v[176:177] op_sel_hi:[1,0]
	s_nop 0
	v_pk_mul_f32 v[92:93], v[90:91], v[90:91]
	s_nop 0
	v_pk_fma_f32 v[92:93], v[92:93], s[40:41], 1.0 op_sel_hi:[1,0,0]
	s_nop 0
	v_pk_mul_f32 v[92:93], v[90:91], v[92:93]
	s_nop 0
	v_pk_mul_f32 v[92:93], v[92:93], s[42:43] op_sel_hi:[1,0]
	s_nop 0
	v_pk_mul_f32 v[92:93], v[92:93], s[38:39] op_sel_hi:[1,0]
	s_nop 0
	v_exp_f32_e32 v92, v92
	v_exp_f32_e32 v93, v93
	s_nop 0
	v_pk_add_f32 v[92:93], v[92:93], 1.0 op_sel_hi:[1,0]
	s_nop 0
	v_rcp_f32_e32 v92, v92
	v_rcp_f32_e32 v93, v93
	s_nop 0
	v_pk_mul_f32 v[102:103], v[90:91], v[92:93]
	v_cvt_pk_bf16_f32 v90, v94, v95
	s_nop 0
	v_cvt_pk_bf16_f32 v91, v96, v97
	v_cvt_pk_bf16_f32 v92, v100, v101
	v_cvt_pk_bf16_f32 v93, v102, v103
	s_mov_b32 s98, 0x9000
	s_mov_b32 s99, 0x0
	v_lshl_add_u64 v[136:137], v[134:135], 0, s[98:99]
	global_store_dwordx4 v[136:137], v[90:93], off offset:-4096
	s_nop 1
	v_pk_mul_f32 v[90:91], v[86:87], v[86:87]
	s_nop 0
	v_pk_fma_f32 v[90:91], v[90:91], s[40:41], 1.0 op_sel_hi:[1,0,0]
	s_nop 0
	v_pk_mul_f32 v[90:91], v[86:87], v[90:91]
	s_nop 0
	v_pk_mul_f32 v[90:91], v[90:91], s[42:43] op_sel_hi:[1,0]
	s_nop 0
	v_pk_mul_f32 v[90:91], v[90:91], s[38:39] op_sel_hi:[1,0]
	s_nop 0
	v_exp_f32_e32 v90, v90
	v_exp_f32_e32 v91, v91
	s_nop 0
	v_pk_add_f32 v[90:91], v[90:91], 1.0 op_sel_hi:[1,0]
	s_nop 0
	v_rcp_f32_e32 v90, v90
	v_rcp_f32_e32 v91, v91
	s_nop 0
	v_pk_mul_f32 v[86:87], v[86:87], v[90:91]
	v_pk_mul_f32 v[90:91], v[88:89], v[88:89]
	s_nop 0
	v_pk_fma_f32 v[90:91], v[90:91], s[40:41], 1.0 op_sel_hi:[1,0,0]
	s_nop 0
	v_pk_mul_f32 v[90:91], v[88:89], v[90:91]
	s_nop 0
	v_pk_mul_f32 v[90:91], v[90:91], s[42:43] op_sel_hi:[1,0]
	s_nop 0
	v_pk_mul_f32 v[90:91], v[90:91], s[38:39] op_sel_hi:[1,0]
	s_nop 0
	v_exp_f32_e32 v90, v90
	v_exp_f32_e32 v91, v91
	s_nop 0
	v_pk_add_f32 v[90:91], v[90:91], 1.0 op_sel_hi:[1,0]
	s_nop 0
	v_rcp_f32_e32 v90, v90
	v_rcp_f32_e32 v91, v91
	s_nop 0
	v_pk_mul_f32 v[88:89], v[88:89], v[90:91]
	v_pk_mul_f32 v[90:91], v[82:83], v[82:83]
	s_nop 0
	v_pk_fma_f32 v[90:91], v[90:91], s[40:41], 1.0 op_sel_hi:[1,0,0]
	s_nop 0
	v_pk_mul_f32 v[90:91], v[82:83], v[90:91]
	s_nop 0
	v_pk_mul_f32 v[90:91], v[90:91], s[42:43] op_sel_hi:[1,0]
	s_nop 0
	v_pk_mul_f32 v[90:91], v[90:91], s[38:39] op_sel_hi:[1,0]
	s_nop 0
	v_exp_f32_e32 v90, v90
	v_exp_f32_e32 v91, v91
	s_nop 0
	v_pk_add_f32 v[90:91], v[90:91], 1.0 op_sel_hi:[1,0]
	s_nop 0
	v_rcp_f32_e32 v90, v90
	v_rcp_f32_e32 v91, v91
	s_nop 0
	v_pk_mul_f32 v[90:91], v[82:83], v[90:91]
	v_pk_mul_f32 v[82:83], v[84:85], v[176:177] op_sel_hi:[1,0]
	s_nop 0
	v_pk_mul_f32 v[84:85], v[82:83], v[82:83]
	s_nop 0
	v_pk_fma_f32 v[84:85], v[84:85], s[40:41], 1.0 op_sel_hi:[1,0,0]
	s_nop 0
	v_pk_mul_f32 v[84:85], v[82:83], v[84:85]
	s_nop 0
	v_pk_mul_f32 v[84:85], v[84:85], s[42:43] op_sel_hi:[1,0]
	s_nop 0
	v_pk_mul_f32 v[84:85], v[84:85], s[38:39] op_sel_hi:[1,0]
	s_nop 0
	v_exp_f32_e32 v84, v84
	v_exp_f32_e32 v85, v85
	s_nop 0
	v_pk_add_f32 v[84:85], v[84:85], 1.0 op_sel_hi:[1,0]
	s_nop 0
	v_rcp_f32_e32 v84, v84
	v_rcp_f32_e32 v85, v85
	s_nop 0
	v_pk_mul_f32 v[92:93], v[82:83], v[84:85]
	v_cvt_pk_bf16_f32 v82, v86, v87
	v_cvt_pk_bf16_f32 v83, v88, v89
	v_cvt_pk_bf16_f32 v84, v90, v91
	v_cvt_pk_bf16_f32 v85, v92, v93
	global_store_dwordx4 v[136:137], v[82:85], off offset:-3840
	s_nop 1
	v_pk_mul_f32 v[84:85], v[78:79], v[78:79]
	s_nop 0
	v_pk_fma_f32 v[84:85], v[84:85], s[40:41], 1.0 op_sel_hi:[1,0,0]
	s_nop 0
	v_pk_mul_f32 v[84:85], v[78:79], v[84:85]
	s_nop 0
	v_pk_mul_f32 v[84:85], v[84:85], s[42:43] op_sel_hi:[1,0]
	s_nop 0
	v_pk_mul_f32 v[84:85], v[84:85], s[38:39] op_sel_hi:[1,0]
	s_nop 0
	v_exp_f32_e32 v84, v84
	v_exp_f32_e32 v85, v85
	s_nop 0
	v_pk_add_f32 v[84:85], v[84:85], 1.0 op_sel_hi:[1,0]
	s_nop 0
	v_rcp_f32_e32 v84, v84
	v_rcp_f32_e32 v85, v85
	s_nop 0
	v_pk_mul_f32 v[78:79], v[78:79], v[84:85]
	v_pk_mul_f32 v[84:85], v[80:81], v[80:81]
	s_nop 0
	v_pk_fma_f32 v[84:85], v[84:85], s[40:41], 1.0 op_sel_hi:[1,0,0]
	s_nop 0
	v_pk_mul_f32 v[84:85], v[80:81], v[84:85]
	s_nop 0
	v_pk_mul_f32 v[84:85], v[84:85], s[42:43] op_sel_hi:[1,0]
	s_nop 0
	v_pk_mul_f32 v[84:85], v[84:85], s[38:39] op_sel_hi:[1,0]
	s_nop 0
	v_exp_f32_e32 v84, v84
	v_exp_f32_e32 v85, v85
	s_nop 0
	v_pk_add_f32 v[84:85], v[84:85], 1.0 op_sel_hi:[1,0]
	s_nop 0
	v_rcp_f32_e32 v84, v84
	v_rcp_f32_e32 v85, v85
	s_nop 0
	v_pk_mul_f32 v[80:81], v[80:81], v[84:85]
	v_pk_mul_f32 v[84:85], v[74:75], v[74:75]
	s_nop 0
	v_pk_fma_f32 v[84:85], v[84:85], s[40:41], 1.0 op_sel_hi:[1,0,0]
	s_nop 0
	v_pk_mul_f32 v[84:85], v[74:75], v[84:85]
	s_nop 0
	v_pk_mul_f32 v[84:85], v[84:85], s[42:43] op_sel_hi:[1,0]
	s_nop 0
	v_pk_mul_f32 v[84:85], v[84:85], s[38:39] op_sel_hi:[1,0]
	s_nop 0
	v_exp_f32_e32 v84, v84
	v_exp_f32_e32 v85, v85
	s_nop 0
	v_pk_add_f32 v[84:85], v[84:85], 1.0 op_sel_hi:[1,0]
	s_nop 0
	v_rcp_f32_e32 v84, v84
	v_rcp_f32_e32 v85, v85
	s_nop 0
	v_pk_mul_f32 v[84:85], v[74:75], v[84:85]
	v_pk_mul_f32 v[74:75], v[76:77], v[172:173] op_sel_hi:[1,0]
	s_nop 0
	v_pk_mul_f32 v[76:77], v[74:75], v[74:75]
	s_nop 0
	v_pk_fma_f32 v[76:77], v[76:77], s[40:41], 1.0 op_sel_hi:[1,0,0]
	s_nop 0
	v_pk_mul_f32 v[76:77], v[74:75], v[76:77]
	s_nop 0
	v_pk_mul_f32 v[76:77], v[76:77], s[42:43] op_sel_hi:[1,0]
	s_nop 0
	v_pk_mul_f32 v[76:77], v[76:77], s[38:39] op_sel_hi:[1,0]
	s_nop 0
	v_exp_f32_e32 v76, v76
	v_exp_f32_e32 v77, v77
	s_nop 0
	v_pk_add_f32 v[76:77], v[76:77], 1.0 op_sel_hi:[1,0]
	s_nop 0
	v_rcp_f32_e32 v76, v76
	v_rcp_f32_e32 v77, v77
	s_nop 0
	v_pk_mul_f32 v[86:87], v[74:75], v[76:77]
	v_cvt_pk_bf16_f32 v74, v78, v79
	s_nop 0
	v_cvt_pk_bf16_f32 v75, v80, v81
	v_cvt_pk_bf16_f32 v76, v84, v85
	v_cvt_pk_bf16_f32 v77, v86, v87
	s_mov_b32 s98, 0xd000
	s_mov_b32 s99, 0x0
	v_lshl_add_u64 v[136:137], v[134:135], 0, s[98:99]
	global_store_dwordx4 v[136:137], v[74:77], off offset:-4096
	s_nop 1
	v_pk_mul_f32 v[74:75], v[70:71], v[70:71]
	s_nop 0
	v_pk_fma_f32 v[74:75], v[74:75], s[40:41], 1.0 op_sel_hi:[1,0,0]
	s_nop 0
	v_pk_mul_f32 v[74:75], v[70:71], v[74:75]
	s_nop 0
	v_pk_mul_f32 v[74:75], v[74:75], s[42:43] op_sel_hi:[1,0]
	s_nop 0
	v_pk_mul_f32 v[74:75], v[74:75], s[38:39] op_sel_hi:[1,0]
	s_nop 0
	v_exp_f32_e32 v74, v74
	v_exp_f32_e32 v75, v75
	s_nop 0
	v_pk_add_f32 v[74:75], v[74:75], 1.0 op_sel_hi:[1,0]
	s_nop 0
	v_rcp_f32_e32 v74, v74
	v_rcp_f32_e32 v75, v75
	s_nop 0
	v_pk_mul_f32 v[70:71], v[70:71], v[74:75]
	v_pk_mul_f32 v[74:75], v[72:73], v[72:73]
	s_nop 0
	v_pk_fma_f32 v[74:75], v[74:75], s[40:41], 1.0 op_sel_hi:[1,0,0]
	s_nop 0
	v_pk_mul_f32 v[74:75], v[72:73], v[74:75]
	s_nop 0
	v_pk_mul_f32 v[74:75], v[74:75], s[42:43] op_sel_hi:[1,0]
	s_nop 0
	v_pk_mul_f32 v[74:75], v[74:75], s[38:39] op_sel_hi:[1,0]
	s_nop 0
	v_exp_f32_e32 v74, v74
	v_exp_f32_e32 v75, v75
	s_nop 0
	v_pk_add_f32 v[74:75], v[74:75], 1.0 op_sel_hi:[1,0]
	s_nop 0
	v_rcp_f32_e32 v74, v74
	v_rcp_f32_e32 v75, v75
	s_nop 0
	v_pk_mul_f32 v[72:73], v[72:73], v[74:75]
	v_pk_mul_f32 v[74:75], v[66:67], v[66:67]
	s_nop 0
	v_pk_fma_f32 v[74:75], v[74:75], s[40:41], 1.0 op_sel_hi:[1,0,0]
	s_nop 0
	v_pk_mul_f32 v[74:75], v[66:67], v[74:75]
	s_nop 0
	v_pk_mul_f32 v[74:75], v[74:75], s[42:43] op_sel_hi:[1,0]
	s_nop 0
	v_pk_mul_f32 v[74:75], v[74:75], s[38:39] op_sel_hi:[1,0]
	s_nop 0
	v_exp_f32_e32 v74, v74
	v_exp_f32_e32 v75, v75
	s_nop 0
	v_pk_add_f32 v[74:75], v[74:75], 1.0 op_sel_hi:[1,0]
	s_nop 0
	v_rcp_f32_e32 v74, v74
	v_rcp_f32_e32 v75, v75
	s_nop 0
	v_pk_mul_f32 v[74:75], v[66:67], v[74:75]
	v_pk_mul_f32 v[66:67], v[68:69], v[172:173] op_sel_hi:[1,0]
	s_nop 0
	v_pk_mul_f32 v[68:69], v[66:67], v[66:67]
	s_nop 0
	v_pk_fma_f32 v[68:69], v[68:69], s[40:41], 1.0 op_sel_hi:[1,0,0]
	s_nop 0
	v_pk_mul_f32 v[68:69], v[66:67], v[68:69]
	s_nop 0
	v_pk_mul_f32 v[68:69], v[68:69], s[42:43] op_sel_hi:[1,0]
	s_nop 0
	v_pk_mul_f32 v[68:69], v[68:69], s[38:39] op_sel_hi:[1,0]
	s_nop 0
	v_exp_f32_e32 v68, v68
	v_exp_f32_e32 v69, v69
	s_nop 0
	v_pk_add_f32 v[68:69], v[68:69], 1.0 op_sel_hi:[1,0]
	s_nop 0
	v_rcp_f32_e32 v68, v68
	v_rcp_f32_e32 v69, v69
	s_nop 0
	v_pk_mul_f32 v[76:77], v[66:67], v[68:69]
	v_cvt_pk_bf16_f32 v66, v70, v71
	v_cvt_pk_bf16_f32 v67, v72, v73
	v_cvt_pk_bf16_f32 v68, v74, v75
	v_cvt_pk_bf16_f32 v69, v76, v77
	global_store_dwordx4 v[136:137], v[66:69], off offset:-3840
	s_nop 1
	v_pk_mul_f32 v[68:69], v[62:63], v[62:63]
	s_nop 0
	v_pk_fma_f32 v[68:69], v[68:69], s[40:41], 1.0 op_sel_hi:[1,0,0]
	s_nop 0
	v_pk_mul_f32 v[68:69], v[62:63], v[68:69]
	s_nop 0
	v_pk_mul_f32 v[68:69], v[68:69], s[42:43] op_sel_hi:[1,0]
	s_nop 0
	v_pk_mul_f32 v[68:69], v[68:69], s[38:39] op_sel_hi:[1,0]
	s_nop 0
	v_exp_f32_e32 v68, v68
	v_exp_f32_e32 v69, v69
	s_nop 0
	v_pk_add_f32 v[68:69], v[68:69], 1.0 op_sel_hi:[1,0]
	s_nop 0
	v_rcp_f32_e32 v68, v68
	v_rcp_f32_e32 v69, v69
	s_nop 0
	v_pk_mul_f32 v[62:63], v[62:63], v[68:69]
	v_pk_mul_f32 v[68:69], v[64:65], v[64:65]
	s_nop 0
	v_pk_fma_f32 v[68:69], v[68:69], s[40:41], 1.0 op_sel_hi:[1,0,0]
	s_nop 0
	v_pk_mul_f32 v[68:69], v[64:65], v[68:69]
	s_nop 0
	v_pk_mul_f32 v[68:69], v[68:69], s[42:43] op_sel_hi:[1,0]
	s_nop 0
	v_pk_mul_f32 v[68:69], v[68:69], s[38:39] op_sel_hi:[1,0]
	s_nop 0
	v_exp_f32_e32 v68, v68
	v_exp_f32_e32 v69, v69
	s_nop 0
	v_pk_add_f32 v[68:69], v[68:69], 1.0 op_sel_hi:[1,0]
	s_nop 0
	v_rcp_f32_e32 v68, v68
	v_rcp_f32_e32 v69, v69
	s_nop 0
	v_pk_mul_f32 v[64:65], v[64:65], v[68:69]
	v_pk_mul_f32 v[68:69], v[58:59], v[58:59]
	s_nop 0
	v_pk_fma_f32 v[68:69], v[68:69], s[40:41], 1.0 op_sel_hi:[1,0,0]
	s_nop 0
	v_pk_mul_f32 v[68:69], v[58:59], v[68:69]
	s_nop 0
	v_pk_mul_f32 v[68:69], v[68:69], s[42:43] op_sel_hi:[1,0]
	s_nop 0
	v_pk_mul_f32 v[68:69], v[68:69], s[38:39] op_sel_hi:[1,0]
	s_nop 0
	v_exp_f32_e32 v68, v68
	v_exp_f32_e32 v69, v69
	s_nop 0
	v_pk_add_f32 v[68:69], v[68:69], 1.0 op_sel_hi:[1,0]
	s_nop 0
	v_rcp_f32_e32 v68, v68
	v_rcp_f32_e32 v69, v69
	s_nop 0
	v_pk_mul_f32 v[68:69], v[58:59], v[68:69]
	v_pk_mul_f32 v[58:59], v[60:61], v[168:169] op_sel_hi:[1,0]
	s_nop 0
	v_pk_mul_f32 v[60:61], v[58:59], v[58:59]
	s_nop 0
	v_pk_fma_f32 v[60:61], v[60:61], s[40:41], 1.0 op_sel_hi:[1,0,0]
	s_nop 0
	v_pk_mul_f32 v[60:61], v[58:59], v[60:61]
	s_nop 0
	v_pk_mul_f32 v[60:61], v[60:61], s[42:43] op_sel_hi:[1,0]
	s_nop 0
	v_pk_mul_f32 v[60:61], v[60:61], s[38:39] op_sel_hi:[1,0]
	s_nop 0
	v_exp_f32_e32 v60, v60
	v_exp_f32_e32 v61, v61
	s_nop 0
	v_pk_add_f32 v[60:61], v[60:61], 1.0 op_sel_hi:[1,0]
	s_nop 0
	v_rcp_f32_e32 v60, v60
	v_rcp_f32_e32 v61, v61
	s_nop 0
	v_pk_mul_f32 v[70:71], v[58:59], v[60:61]
	v_cvt_pk_bf16_f32 v58, v62, v63
	s_nop 0
	v_cvt_pk_bf16_f32 v59, v64, v65
	v_cvt_pk_bf16_f32 v60, v68, v69
	v_cvt_pk_bf16_f32 v61, v70, v71
	s_mov_b32 s98, 0x21000
	s_mov_b32 s99, 0x0
	v_lshl_add_u64 v[136:137], v[134:135], 0, s[98:99]
	global_store_dwordx4 v[136:137], v[58:61], off offset:-4096
	s_nop 1
	v_pk_mul_f32 v[58:59], v[54:55], v[54:55]
	s_nop 0
	v_pk_fma_f32 v[58:59], v[58:59], s[40:41], 1.0 op_sel_hi:[1,0,0]
	s_nop 0
	v_pk_mul_f32 v[58:59], v[54:55], v[58:59]
	s_nop 0
	v_pk_mul_f32 v[58:59], v[58:59], s[42:43] op_sel_hi:[1,0]
	s_nop 0
	v_pk_mul_f32 v[58:59], v[58:59], s[38:39] op_sel_hi:[1,0]
	s_nop 0
	v_exp_f32_e32 v58, v58
	v_exp_f32_e32 v59, v59
	s_nop 0
	v_pk_add_f32 v[58:59], v[58:59], 1.0 op_sel_hi:[1,0]
	s_nop 0
	v_rcp_f32_e32 v58, v58
	v_rcp_f32_e32 v59, v59
	s_nop 0
	v_pk_mul_f32 v[54:55], v[54:55], v[58:59]
	v_pk_mul_f32 v[58:59], v[56:57], v[56:57]
	s_nop 0
	v_pk_fma_f32 v[58:59], v[58:59], s[40:41], 1.0 op_sel_hi:[1,0,0]
	s_nop 0
	v_pk_mul_f32 v[58:59], v[56:57], v[58:59]
	s_nop 0
	v_pk_mul_f32 v[58:59], v[58:59], s[42:43] op_sel_hi:[1,0]
	s_nop 0
	v_pk_mul_f32 v[58:59], v[58:59], s[38:39] op_sel_hi:[1,0]
	s_nop 0
	v_exp_f32_e32 v58, v58
	v_exp_f32_e32 v59, v59
	s_nop 0
	v_pk_add_f32 v[58:59], v[58:59], 1.0 op_sel_hi:[1,0]
	s_nop 0
	v_rcp_f32_e32 v58, v58
	v_rcp_f32_e32 v59, v59
	s_nop 0
	v_pk_mul_f32 v[56:57], v[56:57], v[58:59]
	v_pk_mul_f32 v[58:59], v[50:51], v[50:51]
	s_nop 0
	v_pk_fma_f32 v[58:59], v[58:59], s[40:41], 1.0 op_sel_hi:[1,0,0]
	s_nop 0
	v_pk_mul_f32 v[58:59], v[50:51], v[58:59]
	s_nop 0
	v_pk_mul_f32 v[58:59], v[58:59], s[42:43] op_sel_hi:[1,0]
	s_nop 0
	v_pk_mul_f32 v[58:59], v[58:59], s[38:39] op_sel_hi:[1,0]
	s_nop 0
	v_exp_f32_e32 v58, v58
	v_exp_f32_e32 v59, v59
	s_nop 0
	v_pk_add_f32 v[58:59], v[58:59], 1.0 op_sel_hi:[1,0]
	s_nop 0
	v_rcp_f32_e32 v58, v58
	v_rcp_f32_e32 v59, v59
	s_nop 0
	v_pk_mul_f32 v[58:59], v[50:51], v[58:59]
	v_pk_mul_f32 v[50:51], v[52:53], v[168:169] op_sel_hi:[1,0]
	s_nop 0
	v_pk_mul_f32 v[52:53], v[50:51], v[50:51]
	s_nop 0
	v_pk_fma_f32 v[52:53], v[52:53], s[40:41], 1.0 op_sel_hi:[1,0,0]
	s_nop 0
	v_pk_mul_f32 v[52:53], v[50:51], v[52:53]
	s_nop 0
	v_pk_mul_f32 v[52:53], v[52:53], s[42:43] op_sel_hi:[1,0]
	s_nop 0
	v_pk_mul_f32 v[52:53], v[52:53], s[38:39] op_sel_hi:[1,0]
	s_nop 0
	v_exp_f32_e32 v52, v52
	v_exp_f32_e32 v53, v53
	s_nop 0
	v_pk_add_f32 v[52:53], v[52:53], 1.0 op_sel_hi:[1,0]
	s_nop 0
	v_rcp_f32_e32 v52, v52
	v_rcp_f32_e32 v53, v53
	s_nop 0
	v_pk_mul_f32 v[60:61], v[50:51], v[52:53]
	v_cvt_pk_bf16_f32 v50, v54, v55
	v_cvt_pk_bf16_f32 v51, v56, v57
	v_cvt_pk_bf16_f32 v52, v58, v59
	v_cvt_pk_bf16_f32 v53, v60, v61
	global_store_dwordx4 v[136:137], v[50:53], off offset:-3840
	s_nop 1
	v_pk_mul_f32 v[52:53], v[46:47], v[46:47]
	s_nop 0
	v_pk_fma_f32 v[52:53], v[52:53], s[40:41], 1.0 op_sel_hi:[1,0,0]
	s_nop 0
	v_pk_mul_f32 v[52:53], v[46:47], v[52:53]
	s_nop 0
	v_pk_mul_f32 v[52:53], v[52:53], s[42:43] op_sel_hi:[1,0]
	s_nop 0
	v_pk_mul_f32 v[52:53], v[52:53], s[38:39] op_sel_hi:[1,0]
	s_nop 0
	v_exp_f32_e32 v52, v52
	v_exp_f32_e32 v53, v53
	s_nop 0
	v_pk_add_f32 v[52:53], v[52:53], 1.0 op_sel_hi:[1,0]
	s_nop 0
	v_rcp_f32_e32 v52, v52
	v_rcp_f32_e32 v53, v53
	s_nop 0
	v_pk_mul_f32 v[46:47], v[46:47], v[52:53]
	v_pk_mul_f32 v[52:53], v[48:49], v[48:49]
	s_nop 0
	v_pk_fma_f32 v[52:53], v[52:53], s[40:41], 1.0 op_sel_hi:[1,0,0]
	s_nop 0
	v_pk_mul_f32 v[52:53], v[48:49], v[52:53]
	s_nop 0
	v_pk_mul_f32 v[52:53], v[52:53], s[42:43] op_sel_hi:[1,0]
	s_nop 0
	v_pk_mul_f32 v[52:53], v[52:53], s[38:39] op_sel_hi:[1,0]
	s_nop 0
	v_exp_f32_e32 v52, v52
	v_exp_f32_e32 v53, v53
	s_nop 0
	v_pk_add_f32 v[52:53], v[52:53], 1.0 op_sel_hi:[1,0]
	s_nop 0
	v_rcp_f32_e32 v52, v52
	v_rcp_f32_e32 v53, v53
	s_nop 0
	v_pk_mul_f32 v[48:49], v[48:49], v[52:53]
	v_pk_mul_f32 v[52:53], v[42:43], v[42:43]
	s_nop 0
	v_pk_fma_f32 v[52:53], v[52:53], s[40:41], 1.0 op_sel_hi:[1,0,0]
	s_nop 0
	v_pk_mul_f32 v[52:53], v[42:43], v[52:53]
	s_nop 0
	v_pk_mul_f32 v[52:53], v[52:53], s[42:43] op_sel_hi:[1,0]
	s_nop 0
	v_pk_mul_f32 v[52:53], v[52:53], s[38:39] op_sel_hi:[1,0]
	s_nop 0
	v_exp_f32_e32 v52, v52
	v_exp_f32_e32 v53, v53
	s_nop 0
	v_pk_add_f32 v[52:53], v[52:53], 1.0 op_sel_hi:[1,0]
	s_nop 0
	v_rcp_f32_e32 v52, v52
	v_rcp_f32_e32 v53, v53
	s_nop 0
	v_pk_mul_f32 v[52:53], v[42:43], v[52:53]
	v_pk_mul_f32 v[42:43], v[44:45], v[164:165] op_sel_hi:[1,0]
	s_nop 0
	v_pk_mul_f32 v[44:45], v[42:43], v[42:43]
	s_nop 0
	v_pk_fma_f32 v[44:45], v[44:45], s[40:41], 1.0 op_sel_hi:[1,0,0]
	s_nop 0
	v_pk_mul_f32 v[44:45], v[42:43], v[44:45]
	s_nop 0
	v_pk_mul_f32 v[44:45], v[44:45], s[42:43] op_sel_hi:[1,0]
	s_nop 0
	v_pk_mul_f32 v[44:45], v[44:45], s[38:39] op_sel_hi:[1,0]
	s_nop 0
	v_exp_f32_e32 v44, v44
	v_exp_f32_e32 v45, v45
	s_nop 0
	v_pk_add_f32 v[44:45], v[44:45], 1.0 op_sel_hi:[1,0]
	s_nop 0
	v_rcp_f32_e32 v44, v44
	v_rcp_f32_e32 v45, v45
	s_nop 0
	v_pk_mul_f32 v[54:55], v[42:43], v[44:45]
	v_cvt_pk_bf16_f32 v42, v46, v47
	s_nop 0
	v_cvt_pk_bf16_f32 v43, v48, v49
	v_cvt_pk_bf16_f32 v44, v52, v53
	v_cvt_pk_bf16_f32 v45, v54, v55
	s_mov_b32 s98, 0x25000
	s_mov_b32 s99, 0x0
	v_lshl_add_u64 v[136:137], v[134:135], 0, s[98:99]
	global_store_dwordx4 v[136:137], v[42:45], off offset:-4096
	s_nop 1
	v_pk_mul_f32 v[42:43], v[38:39], v[38:39]
	s_nop 0
	v_pk_fma_f32 v[42:43], v[42:43], s[40:41], 1.0 op_sel_hi:[1,0,0]
	s_nop 0
	v_pk_mul_f32 v[42:43], v[38:39], v[42:43]
	s_nop 0
	v_pk_mul_f32 v[42:43], v[42:43], s[42:43] op_sel_hi:[1,0]
	s_nop 0
	v_pk_mul_f32 v[42:43], v[42:43], s[38:39] op_sel_hi:[1,0]
	s_nop 0
	v_exp_f32_e32 v42, v42
	v_exp_f32_e32 v43, v43
	s_nop 0
	v_pk_add_f32 v[42:43], v[42:43], 1.0 op_sel_hi:[1,0]
	s_nop 0
	v_rcp_f32_e32 v42, v42
	v_rcp_f32_e32 v43, v43
	s_nop 0
	v_pk_mul_f32 v[38:39], v[38:39], v[42:43]
	v_pk_mul_f32 v[42:43], v[40:41], v[40:41]
	s_nop 0
	v_pk_fma_f32 v[42:43], v[42:43], s[40:41], 1.0 op_sel_hi:[1,0,0]
	s_nop 0
	v_pk_mul_f32 v[42:43], v[40:41], v[42:43]
	s_nop 0
	v_pk_mul_f32 v[42:43], v[42:43], s[42:43] op_sel_hi:[1,0]
	s_nop 0
	v_pk_mul_f32 v[42:43], v[42:43], s[38:39] op_sel_hi:[1,0]
	s_nop 0
	v_exp_f32_e32 v42, v42
	v_exp_f32_e32 v43, v43
	s_nop 0
	v_pk_add_f32 v[42:43], v[42:43], 1.0 op_sel_hi:[1,0]
	s_nop 0
	v_rcp_f32_e32 v42, v42
	v_rcp_f32_e32 v43, v43
	s_nop 0
	v_pk_mul_f32 v[40:41], v[40:41], v[42:43]
	v_pk_mul_f32 v[42:43], v[34:35], v[34:35]
	s_nop 0
	v_pk_fma_f32 v[42:43], v[42:43], s[40:41], 1.0 op_sel_hi:[1,0,0]
	s_nop 0
	v_pk_mul_f32 v[42:43], v[34:35], v[42:43]
	s_nop 0
	v_pk_mul_f32 v[42:43], v[42:43], s[42:43] op_sel_hi:[1,0]
	s_nop 0
	v_pk_mul_f32 v[42:43], v[42:43], s[38:39] op_sel_hi:[1,0]
	s_nop 0
	v_exp_f32_e32 v42, v42
	v_exp_f32_e32 v43, v43
	s_nop 0
	v_pk_add_f32 v[42:43], v[42:43], 1.0 op_sel_hi:[1,0]
	s_nop 0
	v_rcp_f32_e32 v42, v42
	v_rcp_f32_e32 v43, v43
	s_nop 0
	v_pk_mul_f32 v[42:43], v[34:35], v[42:43]
	v_pk_mul_f32 v[34:35], v[36:37], v[164:165] op_sel_hi:[1,0]
	s_nop 0
	v_pk_mul_f32 v[36:37], v[34:35], v[34:35]
	s_nop 0
	v_pk_fma_f32 v[36:37], v[36:37], s[40:41], 1.0 op_sel_hi:[1,0,0]
	s_nop 0
	v_pk_mul_f32 v[36:37], v[34:35], v[36:37]
	s_nop 0
	v_pk_mul_f32 v[36:37], v[36:37], s[42:43] op_sel_hi:[1,0]
	s_nop 0
	v_pk_mul_f32 v[36:37], v[36:37], s[38:39] op_sel_hi:[1,0]
	s_nop 0
	v_exp_f32_e32 v36, v36
	v_exp_f32_e32 v37, v37
	s_nop 0
	v_pk_add_f32 v[36:37], v[36:37], 1.0 op_sel_hi:[1,0]
	s_nop 0
	v_rcp_f32_e32 v36, v36
	v_rcp_f32_e32 v37, v37
	s_nop 0
	v_pk_mul_f32 v[44:45], v[34:35], v[36:37]
	v_cvt_pk_bf16_f32 v34, v38, v39
	v_cvt_pk_bf16_f32 v35, v40, v41
	v_cvt_pk_bf16_f32 v36, v42, v43
	v_cvt_pk_bf16_f32 v37, v44, v45
	global_store_dwordx4 v[136:137], v[34:37], off offset:-3840
	s_nop 1
	v_pk_mul_f32 v[36:37], v[30:31], v[30:31]
	s_nop 0
	v_pk_fma_f32 v[36:37], v[36:37], s[40:41], 1.0 op_sel_hi:[1,0,0]
	s_nop 0
	v_pk_mul_f32 v[36:37], v[30:31], v[36:37]
	s_nop 0
	v_pk_mul_f32 v[36:37], v[36:37], s[42:43] op_sel_hi:[1,0]
	s_nop 0
	v_pk_mul_f32 v[36:37], v[36:37], s[38:39] op_sel_hi:[1,0]
	s_nop 0
	v_exp_f32_e32 v36, v36
	v_exp_f32_e32 v37, v37
	s_nop 0
	v_pk_add_f32 v[36:37], v[36:37], 1.0 op_sel_hi:[1,0]
	s_nop 0
	v_rcp_f32_e32 v36, v36
	v_rcp_f32_e32 v37, v37
	s_nop 0
	v_pk_mul_f32 v[30:31], v[30:31], v[36:37]
	v_pk_mul_f32 v[36:37], v[32:33], v[32:33]
	s_nop 0
	v_pk_fma_f32 v[36:37], v[36:37], s[40:41], 1.0 op_sel_hi:[1,0,0]
	s_nop 0
	v_pk_mul_f32 v[36:37], v[32:33], v[36:37]
	s_nop 0
	v_pk_mul_f32 v[36:37], v[36:37], s[42:43] op_sel_hi:[1,0]
	s_nop 0
	v_pk_mul_f32 v[36:37], v[36:37], s[38:39] op_sel_hi:[1,0]
	s_nop 0
	v_exp_f32_e32 v36, v36
	v_exp_f32_e32 v37, v37
	s_nop 0
	v_pk_add_f32 v[36:37], v[36:37], 1.0 op_sel_hi:[1,0]
	s_nop 0
	v_rcp_f32_e32 v36, v36
	v_rcp_f32_e32 v37, v37
	s_nop 0
	v_pk_mul_f32 v[32:33], v[32:33], v[36:37]
	v_pk_mul_f32 v[36:37], v[26:27], v[26:27]
	s_nop 0
	v_pk_fma_f32 v[36:37], v[36:37], s[40:41], 1.0 op_sel_hi:[1,0,0]
	s_nop 0
	v_pk_mul_f32 v[36:37], v[26:27], v[36:37]
	s_nop 0
	v_pk_mul_f32 v[36:37], v[36:37], s[42:43] op_sel_hi:[1,0]
	s_nop 0
	v_pk_mul_f32 v[36:37], v[36:37], s[38:39] op_sel_hi:[1,0]
	s_nop 0
	v_exp_f32_e32 v36, v36
	v_exp_f32_e32 v37, v37
	s_nop 0
	v_pk_add_f32 v[36:37], v[36:37], 1.0 op_sel_hi:[1,0]
	s_nop 0
	v_rcp_f32_e32 v36, v36
	v_rcp_f32_e32 v37, v37
	s_nop 0
	v_pk_mul_f32 v[36:37], v[26:27], v[36:37]
	v_pk_mul_f32 v[26:27], v[28:29], v[160:161] op_sel_hi:[1,0]
	s_nop 0
	v_pk_mul_f32 v[28:29], v[26:27], v[26:27]
	s_nop 0
	v_pk_fma_f32 v[28:29], v[28:29], s[40:41], 1.0 op_sel_hi:[1,0,0]
	s_nop 0
	v_pk_mul_f32 v[28:29], v[26:27], v[28:29]
	s_nop 0
	v_pk_mul_f32 v[28:29], v[28:29], s[42:43] op_sel_hi:[1,0]
	s_nop 0
	v_pk_mul_f32 v[28:29], v[28:29], s[38:39] op_sel_hi:[1,0]
	s_nop 0
	v_exp_f32_e32 v28, v28
	v_exp_f32_e32 v29, v29
	s_nop 0
	v_pk_add_f32 v[28:29], v[28:29], 1.0 op_sel_hi:[1,0]
	s_nop 0
	v_rcp_f32_e32 v28, v28
	v_rcp_f32_e32 v29, v29
	s_nop 0
	v_pk_mul_f32 v[38:39], v[26:27], v[28:29]
	v_cvt_pk_bf16_f32 v26, v30, v31
	s_nop 0
	v_cvt_pk_bf16_f32 v27, v32, v33
	v_cvt_pk_bf16_f32 v28, v36, v37
	v_cvt_pk_bf16_f32 v29, v38, v39
	s_mov_b32 s98, 0x29000
	s_mov_b32 s99, 0x0
	v_lshl_add_u64 v[136:137], v[134:135], 0, s[98:99]
	global_store_dwordx4 v[136:137], v[26:29], off offset:-4096
	s_nop 1
	v_pk_mul_f32 v[26:27], v[22:23], v[22:23]
	s_nop 0
	v_pk_fma_f32 v[26:27], v[26:27], s[40:41], 1.0 op_sel_hi:[1,0,0]
	s_nop 0
	v_pk_mul_f32 v[26:27], v[22:23], v[26:27]
	s_nop 0
	v_pk_mul_f32 v[26:27], v[26:27], s[42:43] op_sel_hi:[1,0]
	s_nop 0
	v_pk_mul_f32 v[26:27], v[26:27], s[38:39] op_sel_hi:[1,0]
	s_nop 0
	v_exp_f32_e32 v26, v26
	v_exp_f32_e32 v27, v27
	s_nop 0
	v_pk_add_f32 v[26:27], v[26:27], 1.0 op_sel_hi:[1,0]
	s_nop 0
	v_rcp_f32_e32 v26, v26
	v_rcp_f32_e32 v27, v27
	s_nop 0
	v_pk_mul_f32 v[22:23], v[22:23], v[26:27]
	v_pk_mul_f32 v[26:27], v[24:25], v[24:25]
	s_nop 0
	v_pk_fma_f32 v[26:27], v[26:27], s[40:41], 1.0 op_sel_hi:[1,0,0]
	s_nop 0
	v_pk_mul_f32 v[26:27], v[24:25], v[26:27]
	s_nop 0
	v_pk_mul_f32 v[26:27], v[26:27], s[42:43] op_sel_hi:[1,0]
	s_nop 0
	v_pk_mul_f32 v[26:27], v[26:27], s[38:39] op_sel_hi:[1,0]
	s_nop 0
	v_exp_f32_e32 v26, v26
	v_exp_f32_e32 v27, v27
	s_nop 0
	v_pk_add_f32 v[26:27], v[26:27], 1.0 op_sel_hi:[1,0]
	s_nop 0
	v_rcp_f32_e32 v26, v26
	v_rcp_f32_e32 v27, v27
	s_nop 0
	v_pk_mul_f32 v[24:25], v[24:25], v[26:27]
	v_pk_mul_f32 v[26:27], v[18:19], v[18:19]
	s_nop 0
	v_pk_fma_f32 v[26:27], v[26:27], s[40:41], 1.0 op_sel_hi:[1,0,0]
	s_nop 0
	v_pk_mul_f32 v[26:27], v[18:19], v[26:27]
	s_nop 0
	v_pk_mul_f32 v[26:27], v[26:27], s[42:43] op_sel_hi:[1,0]
	s_nop 0
	v_pk_mul_f32 v[26:27], v[26:27], s[38:39] op_sel_hi:[1,0]
	s_nop 0
	v_exp_f32_e32 v26, v26
	v_exp_f32_e32 v27, v27
	s_nop 0
	v_pk_add_f32 v[26:27], v[26:27], 1.0 op_sel_hi:[1,0]
	s_nop 0
	v_rcp_f32_e32 v26, v26
	v_rcp_f32_e32 v27, v27
	s_nop 0
	v_pk_mul_f32 v[26:27], v[18:19], v[26:27]
	v_pk_mul_f32 v[18:19], v[20:21], v[160:161] op_sel_hi:[1,0]
	s_nop 0
	v_pk_mul_f32 v[20:21], v[18:19], v[18:19]
	s_nop 0
	v_pk_fma_f32 v[20:21], v[20:21], s[40:41], 1.0 op_sel_hi:[1,0,0]
	s_nop 0
	v_pk_mul_f32 v[20:21], v[18:19], v[20:21]
	s_nop 0
	v_pk_mul_f32 v[20:21], v[20:21], s[42:43] op_sel_hi:[1,0]
	s_nop 0
	v_pk_mul_f32 v[20:21], v[20:21], s[38:39] op_sel_hi:[1,0]
	s_nop 0
	v_exp_f32_e32 v20, v20
	v_exp_f32_e32 v21, v21
	s_nop 0
	v_pk_add_f32 v[20:21], v[20:21], 1.0 op_sel_hi:[1,0]
	s_nop 0
	v_rcp_f32_e32 v20, v20
	v_rcp_f32_e32 v21, v21
	s_nop 0
	v_pk_mul_f32 v[28:29], v[18:19], v[20:21]
	v_cvt_pk_bf16_f32 v18, v22, v23
	v_cvt_pk_bf16_f32 v19, v24, v25
	v_cvt_pk_bf16_f32 v20, v26, v27
	v_cvt_pk_bf16_f32 v21, v28, v29
	global_store_dwordx4 v[136:137], v[18:21], off offset:-3840
	s_nop 1
	v_pk_mul_f32 v[20:21], v[14:15], v[14:15]
	s_nop 0
	v_pk_fma_f32 v[20:21], v[20:21], s[40:41], 1.0 op_sel_hi:[1,0,0]
	s_nop 0
	v_pk_mul_f32 v[20:21], v[14:15], v[20:21]
	s_nop 0
	v_pk_mul_f32 v[20:21], v[20:21], s[42:43] op_sel_hi:[1,0]
	s_nop 0
	v_pk_mul_f32 v[20:21], v[20:21], s[38:39] op_sel_hi:[1,0]
	s_nop 0
	v_exp_f32_e32 v20, v20
	v_exp_f32_e32 v21, v21
	s_nop 0
	v_pk_add_f32 v[20:21], v[20:21], 1.0 op_sel_hi:[1,0]
	s_nop 0
	v_rcp_f32_e32 v20, v20
	v_rcp_f32_e32 v21, v21
	s_nop 0
	v_pk_mul_f32 v[14:15], v[14:15], v[20:21]
	v_pk_mul_f32 v[20:21], v[16:17], v[16:17]
	s_nop 0
	v_pk_fma_f32 v[20:21], v[20:21], s[40:41], 1.0 op_sel_hi:[1,0,0]
	s_nop 0
	v_pk_mul_f32 v[20:21], v[16:17], v[20:21]
	s_nop 0
	v_pk_mul_f32 v[20:21], v[20:21], s[42:43] op_sel_hi:[1,0]
	s_nop 0
	v_pk_mul_f32 v[20:21], v[20:21], s[38:39] op_sel_hi:[1,0]
	s_nop 0
	v_exp_f32_e32 v20, v20
	v_exp_f32_e32 v21, v21
	s_nop 0
	v_pk_add_f32 v[20:21], v[20:21], 1.0 op_sel_hi:[1,0]
	s_nop 0
	v_rcp_f32_e32 v20, v20
	v_rcp_f32_e32 v21, v21
	s_nop 0
	v_pk_mul_f32 v[16:17], v[16:17], v[20:21]
	v_pk_mul_f32 v[20:21], v[10:11], v[10:11]
	s_nop 0
	v_pk_fma_f32 v[20:21], v[20:21], s[40:41], 1.0 op_sel_hi:[1,0,0]
	s_nop 0
	v_pk_mul_f32 v[20:21], v[10:11], v[20:21]
	s_nop 0
	v_pk_mul_f32 v[20:21], v[20:21], s[42:43] op_sel_hi:[1,0]
	s_nop 0
	v_pk_mul_f32 v[20:21], v[20:21], s[38:39] op_sel_hi:[1,0]
	s_nop 0
	v_exp_f32_e32 v20, v20
	v_exp_f32_e32 v21, v21
	s_nop 0
	v_pk_add_f32 v[20:21], v[20:21], 1.0 op_sel_hi:[1,0]
	s_nop 0
	v_rcp_f32_e32 v20, v20
	v_rcp_f32_e32 v21, v21
	s_nop 0
	v_pk_mul_f32 v[20:21], v[10:11], v[20:21]
	v_pk_mul_f32 v[10:11], v[12:13], v[156:157] op_sel_hi:[1,0]
	s_nop 0
	v_pk_mul_f32 v[12:13], v[10:11], v[10:11]
	s_nop 0
	v_pk_fma_f32 v[12:13], v[12:13], s[40:41], 1.0 op_sel_hi:[1,0,0]
	s_nop 0
	v_pk_mul_f32 v[12:13], v[10:11], v[12:13]
	s_nop 0
	v_pk_mul_f32 v[12:13], v[12:13], s[42:43] op_sel_hi:[1,0]
	s_nop 0
	v_pk_mul_f32 v[12:13], v[12:13], s[38:39] op_sel_hi:[1,0]
	s_nop 0
	v_exp_f32_e32 v12, v12
	v_exp_f32_e32 v13, v13
	s_nop 0
	v_pk_add_f32 v[12:13], v[12:13], 1.0 op_sel_hi:[1,0]
	s_nop 0
	v_rcp_f32_e32 v12, v12
	v_rcp_f32_e32 v13, v13
	s_nop 0
	v_pk_mul_f32 v[22:23], v[10:11], v[12:13]
	v_cvt_pk_bf16_f32 v10, v14, v15
	s_nop 0
	v_cvt_pk_bf16_f32 v11, v16, v17
	v_cvt_pk_bf16_f32 v12, v20, v21
	v_cvt_pk_bf16_f32 v13, v22, v23
	s_mov_b32 s98, 0x2d000
	s_mov_b32 s99, 0x0
	v_lshl_add_u64 v[136:137], v[134:135], 0, s[98:99]
	global_store_dwordx4 v[136:137], v[10:13], off offset:-4096
	s_nop 1
	v_pk_mul_f32 v[10:11], v[6:7], v[6:7]
	s_nop 0
	v_pk_fma_f32 v[10:11], v[10:11], s[40:41], 1.0 op_sel_hi:[1,0,0]
	s_nop 0
	v_pk_mul_f32 v[10:11], v[6:7], v[10:11]
	s_nop 0
	v_pk_mul_f32 v[10:11], v[10:11], s[42:43] op_sel_hi:[1,0]
	s_nop 0
	v_pk_mul_f32 v[10:11], v[10:11], s[38:39] op_sel_hi:[1,0]
	s_nop 0
	v_exp_f32_e32 v10, v10
	v_exp_f32_e32 v11, v11
	s_nop 0
	v_pk_add_f32 v[10:11], v[10:11], 1.0 op_sel_hi:[1,0]
	s_nop 0
	v_rcp_f32_e32 v10, v10
	v_rcp_f32_e32 v11, v11
	s_nop 0
	v_pk_mul_f32 v[6:7], v[6:7], v[10:11]
	v_pk_mul_f32 v[10:11], v[8:9], v[8:9]
	s_nop 0
	v_pk_fma_f32 v[10:11], v[10:11], s[40:41], 1.0 op_sel_hi:[1,0,0]
	s_nop 0
	v_pk_mul_f32 v[10:11], v[8:9], v[10:11]
	s_nop 0
	v_pk_mul_f32 v[10:11], v[10:11], s[42:43] op_sel_hi:[1,0]
	s_nop 0
	v_pk_mul_f32 v[10:11], v[10:11], s[38:39] op_sel_hi:[1,0]
	s_nop 0
	v_exp_f32_e32 v10, v10
	v_exp_f32_e32 v11, v11
	s_nop 0
	v_pk_add_f32 v[10:11], v[10:11], 1.0 op_sel_hi:[1,0]
	s_nop 0
	v_rcp_f32_e32 v10, v10
	v_rcp_f32_e32 v11, v11
	s_nop 0
	v_pk_mul_f32 v[8:9], v[8:9], v[10:11]
	v_pk_mul_f32 v[10:11], v[2:3], v[2:3]
	s_nop 0
	v_pk_fma_f32 v[10:11], v[10:11], s[40:41], 1.0 op_sel_hi:[1,0,0]
	s_nop 0
	v_pk_mul_f32 v[10:11], v[2:3], v[10:11]
	s_nop 0
	v_pk_mul_f32 v[10:11], v[10:11], s[42:43] op_sel_hi:[1,0]
	s_nop 0
	v_pk_mul_f32 v[10:11], v[10:11], s[38:39] op_sel_hi:[1,0]
	s_nop 0
	v_exp_f32_e32 v10, v10
	v_exp_f32_e32 v11, v11
	s_nop 0
	v_pk_add_f32 v[10:11], v[10:11], 1.0 op_sel_hi:[1,0]
	s_nop 0
	v_rcp_f32_e32 v10, v10
	v_rcp_f32_e32 v11, v11
	s_nop 0
	v_pk_mul_f32 v[10:11], v[2:3], v[10:11]
	v_pk_mul_f32 v[2:3], v[4:5], v[156:157] op_sel_hi:[1,0]
	s_nop 0
	v_pk_mul_f32 v[4:5], v[2:3], v[2:3]
	s_nop 0
	v_pk_fma_f32 v[4:5], v[4:5], s[40:41], 1.0 op_sel_hi:[1,0,0]
	s_nop 0
	v_pk_mul_f32 v[4:5], v[2:3], v[4:5]
	s_nop 0
	v_pk_mul_f32 v[4:5], v[4:5], s[42:43] op_sel_hi:[1,0]
	s_nop 0
	v_pk_mul_f32 v[4:5], v[4:5], s[38:39] op_sel_hi:[1,0]
	s_nop 0
	v_exp_f32_e32 v4, v4
	v_exp_f32_e32 v5, v5
	s_nop 0
	v_pk_add_f32 v[4:5], v[4:5], 1.0 op_sel_hi:[1,0]
	s_nop 0
	v_rcp_f32_e32 v4, v4
	v_rcp_f32_e32 v5, v5
	s_nop 0
	v_pk_mul_f32 v[12:13], v[2:3], v[4:5]
	v_cvt_pk_bf16_f32 v2, v6, v7
	v_cvt_pk_bf16_f32 v3, v8, v9
	v_cvt_pk_bf16_f32 v4, v10, v11
	v_cvt_pk_bf16_f32 v5, v12, v13
	global_store_dwordx4 v[136:137], v[2:5], off offset:-3840

.LBB0_1336:
	s_add_u32 s50, s46, 0x10000
	s_addc_u32 s51, s47, 0
	s_and_b64 s[46:47], s[42:43], exec
	s_cselect_b32 s47, s51, s23
	s_cselect_b32 s46, s50, s75
	s_add_u32 s13, s16, s13
	s_addc_u32 s50, s17, 0
	s_add_u32 s13, s13, 0x10000
	s_waitcnt vmcnt(8)
	s_addc_u32 s50, s50, 0
	s_waitcnt lgkmcnt(0)
	s_and_b64 s[42:43], s[42:43], exec
	s_cselect_b32 s43, s50, s25
	s_cselect_b32 s42, s13, s76
	s_barrier
	s_setprio 1
	s_waitcnt lgkmcnt(7)
	v_mfma_f32_16x16x32_bf16 v[126:129], v[146:149], v[186:189], v[126:129]
	v_mfma_f32_16x16x32_bf16 v[122:125], v[154:157], v[186:189], v[122:125]
	s_waitcnt lgkmcnt(5)
	v_mfma_f32_16x16x32_bf16 v[118:121], v[146:149], v[178:181], v[118:121]
	v_mfma_f32_16x16x32_bf16 v[114:117], v[154:157], v[178:181], v[114:117]
	s_waitcnt lgkmcnt(3)
	v_mfma_f32_16x16x32_bf16 v[110:113], v[146:149], v[170:173], v[110:113]
	v_mfma_f32_16x16x32_bf16 v[106:109], v[154:157], v[170:173], v[106:109]
	s_waitcnt lgkmcnt(1)
	v_mfma_f32_16x16x32_bf16 v[102:105], v[146:149], v[162:165], v[102:105]
	v_mfma_f32_16x16x32_bf16 v[98:101], v[154:157], v[162:165], v[98:101]
	v_mfma_f32_16x16x32_bf16 v[126:129], v[150:153], v[190:193], v[126:129]
	v_mfma_f32_16x16x32_bf16 v[122:125], v[158:161], v[190:193], v[122:125]
	v_mfma_f32_16x16x32_bf16 v[118:121], v[150:153], v[182:185], v[118:121]
	v_mfma_f32_16x16x32_bf16 v[114:117], v[158:161], v[182:185], v[114:117]
	v_mfma_f32_16x16x32_bf16 v[110:113], v[150:153], v[174:177], v[110:113]
	v_mfma_f32_16x16x32_bf16 v[106:109], v[158:161], v[174:177], v[106:109]
	s_waitcnt lgkmcnt(0)
	v_mfma_f32_16x16x32_bf16 v[102:105], v[150:153], v[166:169], v[102:105]
	v_mfma_f32_16x16x32_bf16 v[98:101], v[158:161], v[166:169], v[98:101]
	s_setprio 0
	s_setprio 1
	v_mfma_f32_16x16x32_bf16 v[94:97], v[130:133], v[186:189], v[94:97]
	v_mfma_f32_16x16x32_bf16 v[90:93], v[138:141], v[186:189], v[90:93]
	v_mfma_f32_16x16x32_bf16 v[86:89], v[130:133], v[178:181], v[86:89]
	v_mfma_f32_16x16x32_bf16 v[82:85], v[138:141], v[178:181], v[82:85]
	v_mfma_f32_16x16x32_bf16 v[78:81], v[130:133], v[170:173], v[78:81]
	v_mfma_f32_16x16x32_bf16 v[74:77], v[138:141], v[170:173], v[74:77]
	v_mfma_f32_16x16x32_bf16 v[70:73], v[130:133], v[162:165], v[70:73]
	v_mfma_f32_16x16x32_bf16 v[66:69], v[138:141], v[162:165], v[66:69]
	v_mfma_f32_16x16x32_bf16 v[94:97], v[134:137], v[190:193], v[94:97]
	v_mfma_f32_16x16x32_bf16 v[90:93], v[142:145], v[190:193], v[90:93]
	v_mfma_f32_16x16x32_bf16 v[86:89], v[134:137], v[182:185], v[86:89]
	v_mfma_f32_16x16x32_bf16 v[82:85], v[142:145], v[182:185], v[82:85]
	v_mfma_f32_16x16x32_bf16 v[78:81], v[134:137], v[174:177], v[78:81]
	v_mfma_f32_16x16x32_bf16 v[74:77], v[142:145], v[174:177], v[74:77]
	v_mfma_f32_16x16x32_bf16 v[70:73], v[134:137], v[166:169], v[70:73]
	v_mfma_f32_16x16x32_bf16 v[66:69], v[142:145], v[166:169], v[66:69]
	s_setprio 0
	s_barrier
	ds_read_b128 v[186:189], v208 offset:16384
	ds_read_b128 v[190:193], v208 offset:17408
	ds_read_b128 v[178:181], v208 offset:18432
	ds_read_b128 v[182:185], v208 offset:19456
	ds_read_b128 v[170:173], v208 offset:20480
	ds_read_b128 v[174:177], v208 offset:21504
	ds_read_b128 v[162:165], v208 offset:22528
	ds_read_b128 v[166:169], v208 offset:23552
	s_mov_b32 m0, s58
	s_nop 0
	global_load_lds_dwordx4 v202, s[42:43]
	s_add_u32 m0, s58, 0x2000
	s_nop 0
	global_load_lds_dwordx4 v203, s[42:43]
	s_add_u32 s50, s42, 0x4000
	s_addc_u32 s51, s43, 0
	s_mov_b32 m0, s59
	s_nop 0
	global_load_lds_dwordx4 v202, s[50:51]
	s_add_u32 m0, s59, 0x2000
	s_nop 0
	global_load_lds_dwordx4 v203, s[50:51]
	s_andn2_b64 vcc, exec, s[48:49]
	s_mov_b32 m0, s7
	s_nop 0
	global_load_lds_dwordx4 v202, s[46:47]
	s_add_u32 m0, s7, 0x2000
	s_nop 0
	global_load_lds_dwordx4 v203, s[46:47]
	s_cbranch_vccnz .LBB0_1338
	v_mov_b32_e32 v2, 0
	v_mov_b32_e32 v3, v2
	v_mov_b32_e32 v4, v2
	v_mov_b32_e32 v5, v2
	v_mov_b32_e32 v6, v2
	v_mov_b32_e32 v7, v2
	v_mov_b32_e32 v8, v2
	v_mov_b32_e32 v9, v2
	v_mov_b32_e32 v10, v2
	v_mov_b32_e32 v11, v2
	v_mov_b32_e32 v12, v2
	v_mov_b32_e32 v13, v2
	v_mov_b32_e32 v14, v2
	v_mov_b32_e32 v15, v2
	v_mov_b32_e32 v16, v2
	v_mov_b32_e32 v17, v2
	v_mov_b32_e32 v18, v2
	v_mov_b32_e32 v19, v2
	v_mov_b32_e32 v20, v2
	v_mov_b32_e32 v21, v2
	v_mov_b32_e32 v22, v2
	v_mov_b32_e32 v23, v2
	v_mov_b32_e32 v24, v2
	v_mov_b32_e32 v25, v2
	v_mov_b32_e32 v26, v2
	v_mov_b32_e32 v27, v2
	v_mov_b32_e32 v28, v2
	v_mov_b32_e32 v29, v2
	v_mov_b32_e32 v30, v2
	v_mov_b32_e32 v31, v2
	v_mov_b32_e32 v32, v2
	v_mov_b32_e32 v33, v2
	v_mov_b32_e32 v34, v2
	v_mov_b32_e32 v35, v2
	v_mov_b32_e32 v36, v2
	v_mov_b32_e32 v37, v2
	v_mov_b32_e32 v38, v2
	v_mov_b32_e32 v39, v2
	v_mov_b32_e32 v40, v2
	v_mov_b32_e32 v41, v2
	v_mov_b32_e32 v42, v2
	v_mov_b32_e32 v43, v2
	v_mov_b32_e32 v44, v2
	v_mov_b32_e32 v45, v2
	v_mov_b32_e32 v46, v2
	v_mov_b32_e32 v47, v2
	v_mov_b32_e32 v48, v2
	v_mov_b32_e32 v49, v2
	v_mov_b32_e32 v50, v2
	v_mov_b32_e32 v51, v2
	v_mov_b32_e32 v52, v2
	v_mov_b32_e32 v53, v2
	v_mov_b32_e32 v54, v2
	v_mov_b32_e32 v55, v2
	v_mov_b32_e32 v56, v2
	v_mov_b32_e32 v57, v2
	v_mov_b32_e32 v58, v2
	v_mov_b32_e32 v59, v2
	v_mov_b32_e32 v60, v2
	v_mov_b32_e32 v61, v2
	v_mov_b32_e32 v62, v2
	v_mov_b32_e32 v63, v2
	v_mov_b32_e32 v64, v2
	v_mov_b32_e32 v65, v2
.LBB0_1338:
	s_waitcnt vmcnt(8)
	s_add_u32 s48, s46, 0x8000
	s_waitcnt lgkmcnt(0)
	s_addc_u32 s49, s47, 0
	s_add_u32 s50, s42, 0x8000
	s_addc_u32 s51, s43, 0
	s_barrier
	s_setprio 1
	s_waitcnt lgkmcnt(7)
	v_mfma_f32_16x16x32_bf16 v[62:65], v[146:149], v[186:189], v[62:65]
	v_mfma_f32_16x16x32_bf16 v[58:61], v[154:157], v[186:189], v[58:61]
	s_waitcnt lgkmcnt(5)
	v_mfma_f32_16x16x32_bf16 v[54:57], v[146:149], v[178:181], v[54:57]
	v_mfma_f32_16x16x32_bf16 v[50:53], v[154:157], v[178:181], v[50:53]
	s_waitcnt lgkmcnt(3)
	v_mfma_f32_16x16x32_bf16 v[46:49], v[146:149], v[170:173], v[46:49]
	v_mfma_f32_16x16x32_bf16 v[42:45], v[154:157], v[170:173], v[42:45]
	s_waitcnt lgkmcnt(1)
	v_mfma_f32_16x16x32_bf16 v[38:41], v[146:149], v[162:165], v[38:41]
	v_mfma_f32_16x16x32_bf16 v[34:37], v[154:157], v[162:165], v[34:37]
	v_mfma_f32_16x16x32_bf16 v[62:65], v[150:153], v[190:193], v[62:65]
	v_mfma_f32_16x16x32_bf16 v[58:61], v[158:161], v[190:193], v[58:61]
	v_mfma_f32_16x16x32_bf16 v[54:57], v[150:153], v[182:185], v[54:57]
	v_mfma_f32_16x16x32_bf16 v[50:53], v[158:161], v[182:185], v[50:53]
	v_mfma_f32_16x16x32_bf16 v[46:49], v[150:153], v[174:177], v[46:49]
	v_mfma_f32_16x16x32_bf16 v[42:45], v[158:161], v[174:177], v[42:45]
	s_waitcnt lgkmcnt(0)
	v_mfma_f32_16x16x32_bf16 v[38:41], v[150:153], v[166:169], v[38:41]
	v_mfma_f32_16x16x32_bf16 v[34:37], v[158:161], v[166:169], v[34:37]
	s_setprio 0
	s_setprio 1
	v_mfma_f32_16x16x32_bf16 v[30:33], v[130:133], v[186:189], v[30:33]
	v_mfma_f32_16x16x32_bf16 v[26:29], v[138:141], v[186:189], v[26:29]
	v_mfma_f32_16x16x32_bf16 v[22:25], v[130:133], v[178:181], v[22:25]
	v_mfma_f32_16x16x32_bf16 v[18:21], v[138:141], v[178:181], v[18:21]
	v_mfma_f32_16x16x32_bf16 v[14:17], v[130:133], v[170:173], v[14:17]
	v_mfma_f32_16x16x32_bf16 v[10:13], v[138:141], v[170:173], v[10:13]
	v_mfma_f32_16x16x32_bf16 v[6:9], v[130:133], v[162:165], v[6:9]
	v_mfma_f32_16x16x32_bf16 v[2:5], v[138:141], v[162:165], v[2:5]
	v_mfma_f32_16x16x32_bf16 v[30:33], v[134:137], v[190:193], v[30:33]
	v_mfma_f32_16x16x32_bf16 v[26:29], v[142:145], v[190:193], v[26:29]
	v_mfma_f32_16x16x32_bf16 v[22:25], v[134:137], v[182:185], v[22:25]
	v_mfma_f32_16x16x32_bf16 v[18:21], v[142:145], v[182:185], v[18:21]
	v_mfma_f32_16x16x32_bf16 v[14:17], v[134:137], v[174:177], v[14:17]
	v_mfma_f32_16x16x32_bf16 v[10:13], v[142:145], v[174:177], v[10:13]
	v_mfma_f32_16x16x32_bf16 v[6:9], v[134:137], v[166:169], v[6:9]
	v_mfma_f32_16x16x32_bf16 v[2:5], v[142:145], v[166:169], v[2:5]
	s_setprio 0
	s_barrier
	v_add_u32_e32 v142, 0x18000, v207
	v_add_u32_e32 v158, 0x1c000, v207
	ds_read_b128 v[130:133], v142
	ds_read_b128 v[134:137], v142 offset:1024
	ds_read_b128 v[138:141], v142 offset:2048
	ds_read_b128 v[142:145], v142 offset:3072
	ds_read_b128 v[146:149], v158
	ds_read_b128 v[150:153], v158 offset:1024
	ds_read_b128 v[154:157], v158 offset:2048
	ds_read_b128 v[158:161], v158 offset:3072
	ds_read_b128 v[162:165], v208 offset:32768
	ds_read_b128 v[166:169], v208 offset:33792
	ds_read_b128 v[170:173], v208 offset:34816
	ds_read_b128 v[174:177], v208 offset:35840
	ds_read_b128 v[178:181], v208 offset:36864
	ds_read_b128 v[182:185], v208 offset:37888
	ds_read_b128 v[186:189], v208 offset:38912
	ds_read_b128 v[190:193], v208 offset:39936
	s_add_u32 s46, s46, 0x4000
	s_addc_u32 s47, s47, 0
	s_mov_b32 m0, s60
	s_nop 0
	global_load_lds_dwordx4 v202, s[46:47]
	s_add_u32 m0, s60, 0x2000
	s_nop 0
	global_load_lds_dwordx4 v203, s[46:47]
	s_waitcnt vmcnt(8)
	s_waitcnt lgkmcnt(0)
	s_barrier
	s_setprio 1
	s_waitcnt lgkmcnt(7)
	v_mfma_f32_16x16x32_bf16 v[126:129], v[130:133], v[162:165], v[126:129]
	v_mfma_f32_16x16x32_bf16 v[122:125], v[138:141], v[162:165], v[122:125]
	s_waitcnt lgkmcnt(5)
	v_mfma_f32_16x16x32_bf16 v[118:121], v[130:133], v[170:173], v[118:121]
	v_mfma_f32_16x16x32_bf16 v[114:117], v[138:141], v[170:173], v[114:117]
	s_waitcnt lgkmcnt(3)
	v_mfma_f32_16x16x32_bf16 v[110:113], v[130:133], v[178:181], v[110:113]
	v_mfma_f32_16x16x32_bf16 v[106:109], v[138:141], v[178:181], v[106:109]
	s_waitcnt lgkmcnt(1)
	v_mfma_f32_16x16x32_bf16 v[102:105], v[130:133], v[186:189], v[102:105]
	v_mfma_f32_16x16x32_bf16 v[98:101], v[138:141], v[186:189], v[98:101]
	v_mfma_f32_16x16x32_bf16 v[126:129], v[134:137], v[166:169], v[126:129]
	v_mfma_f32_16x16x32_bf16 v[122:125], v[142:145], v[166:169], v[122:125]
	v_mfma_f32_16x16x32_bf16 v[118:121], v[134:137], v[174:177], v[118:121]
	v_mfma_f32_16x16x32_bf16 v[114:117], v[142:145], v[174:177], v[114:117]
	v_mfma_f32_16x16x32_bf16 v[110:113], v[134:137], v[182:185], v[110:113]
	v_mfma_f32_16x16x32_bf16 v[106:109], v[142:145], v[182:185], v[106:109]
	s_waitcnt lgkmcnt(0)
	v_mfma_f32_16x16x32_bf16 v[102:105], v[134:137], v[190:193], v[102:105]
	v_mfma_f32_16x16x32_bf16 v[98:101], v[142:145], v[190:193], v[98:101]
	s_setprio 0
	s_setprio 1
	v_mfma_f32_16x16x32_bf16 v[94:97], v[146:149], v[162:165], v[94:97]
	v_mfma_f32_16x16x32_bf16 v[90:93], v[154:157], v[162:165], v[90:93]
	v_mfma_f32_16x16x32_bf16 v[86:89], v[146:149], v[170:173], v[86:89]
	v_mfma_f32_16x16x32_bf16 v[82:85], v[154:157], v[170:173], v[82:85]
	v_mfma_f32_16x16x32_bf16 v[78:81], v[146:149], v[178:181], v[78:81]
	v_mfma_f32_16x16x32_bf16 v[74:77], v[154:157], v[178:181], v[74:77]
	v_mfma_f32_16x16x32_bf16 v[70:73], v[146:149], v[186:189], v[70:73]
	v_mfma_f32_16x16x32_bf16 v[66:69], v[154:157], v[186:189], v[66:69]
	v_mfma_f32_16x16x32_bf16 v[94:97], v[150:153], v[166:169], v[94:97]
	v_mfma_f32_16x16x32_bf16 v[90:93], v[158:161], v[166:169], v[90:93]
	v_mfma_f32_16x16x32_bf16 v[86:89], v[150:153], v[174:177], v[86:89]
	v_mfma_f32_16x16x32_bf16 v[82:85], v[158:161], v[174:177], v[82:85]
	v_mfma_f32_16x16x32_bf16 v[78:81], v[150:153], v[182:185], v[78:81]
	v_mfma_f32_16x16x32_bf16 v[74:77], v[158:161], v[182:185], v[74:77]
	v_mfma_f32_16x16x32_bf16 v[70:73], v[150:153], v[190:193], v[70:73]
	v_mfma_f32_16x16x32_bf16 v[66:69], v[158:161], v[190:193], v[66:69]
	s_setprio 0
	s_barrier
	ds_read_b128 v[162:165], v208 offset:49152
	ds_read_b128 v[166:169], v208 offset:50176
	ds_read_b128 v[170:173], v208 offset:51200
	ds_read_b128 v[174:177], v208 offset:52224
	ds_read_b128 v[178:181], v208 offset:53248
	ds_read_b128 v[182:185], v208 offset:54272
	ds_read_b128 v[186:189], v208 offset:55296
	ds_read_b128 v[190:193], v208 offset:56320
	s_mov_b32 m0, s64
	s_nop 0
	global_load_lds_dwordx4 v202, s[50:51]
	s_add_u32 m0, s64, 0x2000
	s_nop 0
	global_load_lds_dwordx4 v203, s[50:51]
	s_add_u32 s42, s42, 0xc000
	s_addc_u32 s43, s43, 0
	s_mov_b32 m0, s66
	s_nop 0
	global_load_lds_dwordx4 v202, s[42:43]
	s_add_u32 m0, s66, 0x2000
	s_nop 0
	global_load_lds_dwordx4 v203, s[42:43]
	s_nop 0
	s_mov_b32 m0, s65
	s_nop 0
	global_load_lds_dwordx4 v202, s[48:49]
	s_add_u32 m0, s65, 0x2000
	s_nop 0
	global_load_lds_dwordx4 v203, s[48:49]
	s_waitcnt vmcnt(8)
	s_waitcnt lgkmcnt(0)
	s_barrier
	s_setprio 1
	s_waitcnt lgkmcnt(7)
	v_mfma_f32_16x16x32_bf16 v[62:65], v[130:133], v[162:165], v[62:65]
	v_mfma_f32_16x16x32_bf16 v[58:61], v[138:141], v[162:165], v[58:61]
	s_waitcnt lgkmcnt(5)
	v_mfma_f32_16x16x32_bf16 v[54:57], v[130:133], v[170:173], v[54:57]
	v_mfma_f32_16x16x32_bf16 v[50:53], v[138:141], v[170:173], v[50:53]
	s_waitcnt lgkmcnt(3)
	v_mfma_f32_16x16x32_bf16 v[46:49], v[130:133], v[178:181], v[46:49]
	v_mfma_f32_16x16x32_bf16 v[42:45], v[138:141], v[178:181], v[42:45]
	s_waitcnt lgkmcnt(1)
	v_mfma_f32_16x16x32_bf16 v[38:41], v[130:133], v[186:189], v[38:41]
	v_mfma_f32_16x16x32_bf16 v[34:37], v[138:141], v[186:189], v[34:37]
	v_mfma_f32_16x16x32_bf16 v[62:65], v[134:137], v[166:169], v[62:65]
	v_mfma_f32_16x16x32_bf16 v[58:61], v[142:145], v[166:169], v[58:61]
	v_mfma_f32_16x16x32_bf16 v[54:57], v[134:137], v[174:177], v[54:57]
	v_mfma_f32_16x16x32_bf16 v[50:53], v[142:145], v[174:177], v[50:53]
	v_mfma_f32_16x16x32_bf16 v[46:49], v[134:137], v[182:185], v[46:49]
	v_mfma_f32_16x16x32_bf16 v[42:45], v[142:145], v[182:185], v[42:45]
	s_waitcnt lgkmcnt(0)
	v_mfma_f32_16x16x32_bf16 v[38:41], v[134:137], v[190:193], v[38:41]
	v_mfma_f32_16x16x32_bf16 v[34:37], v[142:145], v[190:193], v[34:37]
	s_setprio 0
	s_setprio 1
	v_mfma_f32_16x16x32_bf16 v[30:33], v[146:149], v[162:165], v[30:33]
	v_mfma_f32_16x16x32_bf16 v[26:29], v[154:157], v[162:165], v[26:29]
	v_mfma_f32_16x16x32_bf16 v[22:25], v[146:149], v[170:173], v[22:25]
	v_mfma_f32_16x16x32_bf16 v[18:21], v[154:157], v[170:173], v[18:21]
	v_mfma_f32_16x16x32_bf16 v[14:17], v[146:149], v[178:181], v[14:17]
	v_mfma_f32_16x16x32_bf16 v[10:13], v[154:157], v[178:181], v[10:13]
	v_mfma_f32_16x16x32_bf16 v[6:9], v[146:149], v[186:189], v[6:9]
	v_mfma_f32_16x16x32_bf16 v[2:5], v[154:157], v[186:189], v[2:5]
	v_mfma_f32_16x16x32_bf16 v[30:33], v[150:153], v[166:169], v[30:33]
	v_mfma_f32_16x16x32_bf16 v[26:29], v[158:161], v[166:169], v[26:29]
	v_mfma_f32_16x16x32_bf16 v[22:25], v[150:153], v[174:177], v[22:25]
	v_mfma_f32_16x16x32_bf16 v[18:21], v[158:161], v[174:177], v[18:21]
	v_mfma_f32_16x16x32_bf16 v[14:17], v[150:153], v[182:185], v[14:17]
	v_mfma_f32_16x16x32_bf16 v[10:13], v[158:161], v[182:185], v[10:13]
	v_mfma_f32_16x16x32_bf16 v[6:9], v[150:153], v[190:193], v[6:9]
	v_mfma_f32_16x16x32_bf16 v[2:5], v[158:161], v[190:193], v[2:5]
	s_setprio 0
	s_barrier
	s_add_i32 s13, s77, 2
	s_cmp_gt_u32 s77, 5
	s_cbranch_scc1 .LBB0_1340
	s_mov_b32 s77, s13
	s_branch .LBB0_1317

.LBB0_1342:
	s_lshl_b32 s13, s73, 8
	v_mov_b32_e32 v130, v195
	v_mov_b32_e32 v131, v210
	s_add_i32 s13, s13, s61
	v_add_u32_e32 v134, s13, v130
	s_lshl_b32 s13, s6, 8
	s_or_b32 s13, s13, s62
	v_lshl_add_u32 v130, v131, 3, s13
	v_bfe_u32 v133, v130, 5, 1
	v_lshrrev_b32_e32 v137, 3, v134
	v_and_or_b32 v137, v137, 14, v133
	v_lshlrev_b32_e32 v131, 1, v130
	v_lshlrev_b32_e32 v138, 6, v134
	v_lshlrev_b32_e32 v166, 10, v137
	v_lshlrev_b32_e32 v137, 2, v134
	v_and_b32_e32 v132, 48, v131
	v_ashrrev_i32_e32 v135, 3, v134
	v_lshlrev_b32_e32 v136, 7, v134
	v_and_b32_e32 v138, 0x3c0, v138
	v_and_b32_e32 v137, 32, v137
	v_ashrrev_i32_e32 v131, 6, v130
	v_and_b32_e32 v135, 0xffffffe0, v135
	v_and_b32_e32 v136, 0x4000, v136
	v_bitop3_b32 v137, v132, v137, v138 bitop3:0x36
	v_or3_b32 v198, v136, v137, v166
	v_add_u32_e32 v136, v131, v135
	v_ashrrev_i32_e32 v137, 31, v136
	v_add_u32_e32 v130, 0x80, v130
	v_lshl_add_u64 v[140:141], s[2:3], 0, v[198:199]
	v_lshlrev_b64 v[136:137], 15, v[136:137]
	v_ashrrev_i32_e32 v130, 6, v130
	v_lshl_add_u64 v[136:137], v[140:141], 0, v[136:137]
	v_lshl_add_u64 v[168:169], v[136:137], 0, 0
	global_load_dwordx4 v[136:139], v[136:137], off
	s_mov_b32 s98, 0x11000
	s_mov_b32 s99, 0x0
	v_lshl_add_u64 v[170:171], v[168:169], 0, s[98:99]
	global_load_dwordx4 v[140:143], v[170:171], off offset:-4096
	s_mov_b32 s98, 0x1000
	s_mov_b32 s99, 0x0
	v_lshl_add_u64 v[172:173], v[168:169], 0, s[98:99]
	global_load_dwordx4 v[144:147], v[172:173], off offset:-2048
	global_load_dwordx4 v[148:151], v[170:171], off offset:-2048
	v_ashrrev_i32_e32 v154, 4, v134
	v_and_b32_e32 v167, -16, v154
	v_add_u32_e32 v154, v131, v167
	v_ashrrev_i32_e32 v155, 31, v154
	v_lshlrev_b64 v[154:155], 15, v[154:155]
	v_lshl_add_u64 v[154:155], s[10:11], 0, v[154:155]
	v_lshl_add_u64 v[154:155], v[154:155], 0, v[198:199]
	s_andn2_b64 vcc, exec, s[38:39]
	s_waitcnt vmcnt(3)
	v_lshlrev_b32_e32 v156, 16, v136
	v_and_b32_e32 v157, 0xffff0000, v136
	v_lshlrev_b32_e32 v136, 16, v137
	v_and_b32_e32 v137, 0xffff0000, v137
	v_lshlrev_b32_e32 v158, 16, v138
	v_and_b32_e32 v159, 0xffff0000, v138
	v_lshlrev_b32_e32 v138, 16, v139
	v_and_b32_e32 v139, 0xffff0000, v139
	v_pk_mul_f32 v[156:157], v[126:127], v[156:157]
	v_pk_mul_f32 v[162:163], v[128:129], v[136:137]
	v_pk_mul_f32 v[158:159], v[122:123], v[158:159]
	v_pk_mul_f32 v[164:165], v[124:125], v[138:139]
	v_cvt_pk_bf16_f32 v136, v156, v157
	v_cvt_pk_bf16_f32 v137, v162, v163
	v_cvt_pk_bf16_f32 v138, v158, v159
	v_cvt_pk_bf16_f32 v139, v164, v165
	s_waitcnt vmcnt(2)
	v_lshlrev_b32_e32 v160, 16, v140
	v_and_b32_e32 v161, 0xffff0000, v140
	v_lshlrev_b32_e32 v140, 16, v141
	v_lshl_add_u64 v[174:175], v[154:155], 0, 0
	global_store_dwordx4 v[154:155], v[136:139], off
	v_and_b32_e32 v141, 0xffff0000, v141
	v_pk_mul_f32 v[160:161], v[94:95], v[160:161]
	v_lshlrev_b32_e32 v136, 16, v142
	v_and_b32_e32 v137, 0xffff0000, v142
	v_pk_mul_f32 v[138:139], v[96:97], v[140:141]
	v_pk_mul_f32 v[140:141], v[90:91], v[136:137]
	v_lshlrev_b32_e32 v136, 16, v143
	v_and_b32_e32 v137, 0xffff0000, v143
	v_pk_mul_f32 v[142:143], v[92:93], v[136:137]
	v_cvt_pk_bf16_f32 v136, v160, v161
	v_cvt_pk_bf16_f32 v137, v138, v139
	v_cvt_pk_bf16_f32 v138, v140, v141
	v_cvt_pk_bf16_f32 v139, v142, v143
	s_mov_b32 s98, 0x11000
	s_mov_b32 s99, 0x0
	v_lshl_add_u64 v[176:177], v[174:175], 0, s[98:99]
	global_store_dwordx4 v[176:177], v[136:139], off offset:-4096
	s_waitcnt vmcnt(3)
	v_lshlrev_b32_e32 v140, 16, v146
	v_and_b32_e32 v141, 0xffff0000, v146
	v_lshlrev_b32_e32 v136, 16, v144
	v_and_b32_e32 v137, 0xffff0000, v144
	v_lshlrev_b32_e32 v138, 16, v145
	v_and_b32_e32 v139, 0xffff0000, v145
	v_lshlrev_b32_e32 v142, 16, v147
	v_and_b32_e32 v143, 0xffff0000, v147
	v_pk_mul_f32 v[136:137], v[118:119], v[136:137]
	v_pk_mul_f32 v[138:139], v[120:121], v[138:139]
	v_pk_mul_f32 v[140:141], v[114:115], v[140:141]
	v_pk_mul_f32 v[142:143], v[116:117], v[142:143]
	v_cvt_pk_bf16_f32 v136, v136, v137
	v_cvt_pk_bf16_f32 v137, v138, v139
	v_cvt_pk_bf16_f32 v138, v140, v141
	v_cvt_pk_bf16_f32 v139, v142, v143
	s_mov_b32 s98, 0x1000
	s_mov_b32 s99, 0x0
	v_lshl_add_u64 v[178:179], v[174:175], 0, s[98:99]
	global_store_dwordx4 v[178:179], v[136:139], off offset:-2048
	s_nop 0
	s_nop 0
	s_waitcnt vmcnt(3)
	v_lshlrev_b32_e32 v136, 16, v148
	v_and_b32_e32 v137, 0xffff0000, v148
	v_lshlrev_b32_e32 v138, 16, v149
	v_and_b32_e32 v139, 0xffff0000, v149
	v_lshlrev_b32_e32 v140, 16, v150
	v_and_b32_e32 v141, 0xffff0000, v150
	v_lshlrev_b32_e32 v142, 16, v151
	v_and_b32_e32 v143, 0xffff0000, v151
	v_pk_mul_f32 v[136:137], v[86:87], v[136:137]
	v_pk_mul_f32 v[138:139], v[88:89], v[138:139]
	v_pk_mul_f32 v[140:141], v[82:83], v[140:141]
	v_pk_mul_f32 v[142:143], v[84:85], v[142:143]
	v_cvt_pk_bf16_f32 v136, v136, v137
	v_cvt_pk_bf16_f32 v137, v138, v139
	v_cvt_pk_bf16_f32 v138, v140, v141
	v_cvt_pk_bf16_f32 v139, v142, v143
	global_store_dwordx4 v[176:177], v[136:139], off offset:-2048
	s_nop 0
	s_nop 0
	s_nop 0
	s_nop 0
	s_nop 0
	global_load_dwordx4 v[136:139], v[172:173], off
	global_load_dwordx4 v[140:143], v[170:171], off
	global_load_dwordx4 v[144:147], v[172:173], off offset:2048
	global_load_dwordx4 v[148:151], v[170:171], off offset:2048
	s_waitcnt vmcnt(3)
	v_lshlrev_b32_e32 v154, 16, v136
	v_and_b32_e32 v155, 0xffff0000, v136
	v_lshlrev_b32_e32 v136, 16, v137
	v_and_b32_e32 v137, 0xffff0000, v137
	v_pk_mul_f32 v[156:157], v[112:113], v[136:137]
	v_lshlrev_b32_e32 v136, 16, v138
	v_and_b32_e32 v137, 0xffff0000, v138
	v_pk_mul_f32 v[158:159], v[106:107], v[136:137]
	v_lshlrev_b32_e32 v136, 16, v139
	v_and_b32_e32 v137, 0xffff0000, v139
	v_pk_mul_f32 v[160:161], v[108:109], v[136:137]
	v_pk_mul_f32 v[154:155], v[110:111], v[154:155]
	v_cvt_pk_bf16_f32 v136, v154, v155
	v_cvt_pk_bf16_f32 v137, v156, v157
	v_cvt_pk_bf16_f32 v138, v158, v159
	v_cvt_pk_bf16_f32 v139, v160, v161
	global_store_dwordx4 v[178:179], v[136:139], off
	s_nop 0
	s_nop 0
	s_waitcnt vmcnt(3)
	v_lshlrev_b32_e32 v136, 16, v140
	v_and_b32_e32 v137, 0xffff0000, v140
	v_lshlrev_b32_e32 v138, 16, v141
	v_and_b32_e32 v139, 0xffff0000, v141
	v_lshlrev_b32_e32 v140, 16, v142
	v_and_b32_e32 v141, 0xffff0000, v142
	v_lshlrev_b32_e32 v142, 16, v143
	v_and_b32_e32 v143, 0xffff0000, v143
	v_pk_mul_f32 v[136:137], v[78:79], v[136:137]
	v_pk_mul_f32 v[138:139], v[80:81], v[138:139]
	v_pk_mul_f32 v[140:141], v[74:75], v[140:141]
	v_pk_mul_f32 v[142:143], v[76:77], v[142:143]
	v_cvt_pk_bf16_f32 v136, v136, v137
	v_cvt_pk_bf16_f32 v137, v138, v139
	v_cvt_pk_bf16_f32 v138, v140, v141
	v_cvt_pk_bf16_f32 v139, v142, v143
	global_store_dwordx4 v[176:177], v[136:139], off
	s_waitcnt vmcnt(3)
	v_lshlrev_b32_e32 v140, 16, v146
	v_and_b32_e32 v141, 0xffff0000, v146
	v_lshlrev_b32_e32 v136, 16, v144
	v_and_b32_e32 v137, 0xffff0000, v144
	v_lshlrev_b32_e32 v138, 16, v145
	v_and_b32_e32 v139, 0xffff0000, v145
	v_lshlrev_b32_e32 v142, 16, v147
	v_and_b32_e32 v143, 0xffff0000, v147
	v_pk_mul_f32 v[136:137], v[102:103], v[136:137]
	v_pk_mul_f32 v[138:139], v[104:105], v[138:139]
	v_pk_mul_f32 v[140:141], v[98:99], v[140:141]
	v_pk_mul_f32 v[142:143], v[100:101], v[142:143]
	v_cvt_pk_bf16_f32 v136, v136, v137
	v_cvt_pk_bf16_f32 v137, v138, v139
	v_cvt_pk_bf16_f32 v138, v140, v141
	v_cvt_pk_bf16_f32 v139, v142, v143
	global_store_dwordx4 v[178:179], v[136:139], off offset:2048
	s_nop 0
	s_nop 0
	s_waitcnt vmcnt(3)
	v_lshlrev_b32_e32 v136, 16, v148
	v_and_b32_e32 v137, 0xffff0000, v148
	v_lshlrev_b32_e32 v138, 16, v149
	v_and_b32_e32 v139, 0xffff0000, v149
	v_lshlrev_b32_e32 v140, 16, v150
	v_and_b32_e32 v141, 0xffff0000, v150
	v_lshlrev_b32_e32 v142, 16, v151
	v_and_b32_e32 v143, 0xffff0000, v151
	v_pk_mul_f32 v[136:137], v[70:71], v[136:137]
	v_pk_mul_f32 v[138:139], v[72:73], v[138:139]
	v_pk_mul_f32 v[140:141], v[66:67], v[140:141]
	v_pk_mul_f32 v[142:143], v[68:69], v[142:143]
	v_cvt_pk_bf16_f32 v136, v136, v137
	v_cvt_pk_bf16_f32 v137, v138, v139
	v_cvt_pk_bf16_f32 v138, v140, v141
	v_cvt_pk_bf16_f32 v139, v142, v143
	v_add_u32_e32 v135, 0x80, v134
	global_store_dwordx4 v[176:177], v[136:139], off offset:2048
	v_add_u32_e32 v164, 0x90, v134
	s_nop 0
	s_nop 0
	v_lshlrev_b32_e32 v137, 6, v135
	v_lshlrev_b32_e32 v138, 2, v135
	v_lshlrev_b32_e32 v136, 7, v135
	v_and_b32_e32 v137, 0x3c0, v137
	v_and_b32_e32 v138, 32, v138
	v_and_b32_e32 v136, 0x4000, v136
	v_bitop3_b32 v137, v137, v138, v132 bitop3:0x36
	v_or3_b32 v198, v136, v137, v166
	s_mov_b32 s98, 0x5000
	s_mov_b32 s99, 0x0
	v_lshl_add_u64 v[170:171], v[168:169], 0, s[98:99]
	global_load_dwordx4 v[136:139], v[170:171], off offset:-4096
	s_mov_b32 s98, 0x15000
	s_mov_b32 s99, 0x0
	v_lshl_add_u64 v[172:173], v[168:169], 0, s[98:99]
	global_load_dwordx4 v[140:143], v[172:173], off offset:-4096
	global_load_dwordx4 v[144:147], v[170:171], off offset:-2048
	global_load_dwordx4 v[148:151], v[172:173], off offset:-2048
	v_ashrrev_i32_e32 v135, 4, v135
	v_and_b32_e32 v135, -16, v135
	s_waitcnt vmcnt(3)
	v_lshlrev_b32_e32 v154, 16, v136
	v_and_b32_e32 v155, 0xffff0000, v136
	v_lshlrev_b32_e32 v136, 16, v137
	v_and_b32_e32 v137, 0xffff0000, v137
	v_pk_mul_f32 v[156:157], v[64:65], v[136:137]
	v_lshlrev_b32_e32 v136, 16, v138
	v_and_b32_e32 v137, 0xffff0000, v138
	v_pk_mul_f32 v[158:159], v[58:59], v[136:137]
	v_lshlrev_b32_e32 v136, 16, v139
	v_and_b32_e32 v137, 0xffff0000, v139
	v_pk_mul_f32 v[160:161], v[60:61], v[136:137]
	v_add_u32_e32 v136, v135, v131
	v_ashrrev_i32_e32 v137, 31, v136
	v_lshlrev_b64 v[136:137], 15, v[136:137]
	v_pk_mul_f32 v[154:155], v[62:63], v[154:155]
	v_lshl_add_u64 v[136:137], s[10:11], 0, v[136:137]
	v_lshl_add_u64 v[162:163], v[136:137], 0, v[198:199]
	v_cvt_pk_bf16_f32 v136, v154, v155
	v_cvt_pk_bf16_f32 v137, v156, v157
	v_cvt_pk_bf16_f32 v138, v158, v159
	v_cvt_pk_bf16_f32 v139, v160, v161
	s_mov_b32 s98, 0x5000
	s_mov_b32 s99, 0x0
	v_lshl_add_u64 v[168:169], v[174:175], 0, s[98:99]
	global_store_dwordx4 v[168:169], v[136:139], off offset:-4096
	s_nop 0
	s_nop 0
	s_waitcnt vmcnt(3)
	v_lshlrev_b32_e32 v136, 16, v140
	v_and_b32_e32 v137, 0xffff0000, v140
	v_lshlrev_b32_e32 v138, 16, v141
	v_and_b32_e32 v139, 0xffff0000, v141
	v_lshlrev_b32_e32 v140, 16, v142
	v_and_b32_e32 v141, 0xffff0000, v142
	v_lshlrev_b32_e32 v142, 16, v143
	v_and_b32_e32 v143, 0xffff0000, v143
	v_pk_mul_f32 v[136:137], v[30:31], v[136:137]
	v_pk_mul_f32 v[138:139], v[32:33], v[138:139]
	v_pk_mul_f32 v[140:141], v[26:27], v[140:141]
	v_pk_mul_f32 v[142:143], v[28:29], v[142:143]
	v_cvt_pk_bf16_f32 v136, v136, v137
	v_cvt_pk_bf16_f32 v137, v138, v139
	v_cvt_pk_bf16_f32 v138, v140, v141
	v_cvt_pk_bf16_f32 v139, v142, v143
	s_mov_b32 s98, 0x15000
	s_mov_b32 s99, 0x0
	v_lshl_add_u64 v[176:177], v[174:175], 0, s[98:99]
	global_store_dwordx4 v[176:177], v[136:139], off offset:-4096
	s_waitcnt vmcnt(3)
	v_lshlrev_b32_e32 v140, 16, v146
	v_and_b32_e32 v141, 0xffff0000, v146
	v_lshlrev_b32_e32 v136, 16, v144
	v_and_b32_e32 v137, 0xffff0000, v144
	v_lshlrev_b32_e32 v138, 16, v145
	v_and_b32_e32 v139, 0xffff0000, v145
	v_lshlrev_b32_e32 v142, 16, v147
	v_and_b32_e32 v143, 0xffff0000, v147
	v_pk_mul_f32 v[136:137], v[54:55], v[136:137]
	v_pk_mul_f32 v[138:139], v[56:57], v[138:139]
	v_pk_mul_f32 v[140:141], v[50:51], v[140:141]
	v_pk_mul_f32 v[142:143], v[52:53], v[142:143]
	v_cvt_pk_bf16_f32 v136, v136, v137
	v_cvt_pk_bf16_f32 v137, v138, v139
	v_cvt_pk_bf16_f32 v138, v140, v141
	v_cvt_pk_bf16_f32 v139, v142, v143
	global_store_dwordx4 v[168:169], v[136:139], off offset:-2048
	s_nop 0
	s_nop 0
	s_waitcnt vmcnt(3)
	v_lshlrev_b32_e32 v136, 16, v148
	v_and_b32_e32 v137, 0xffff0000, v148
	v_lshlrev_b32_e32 v138, 16, v149
	v_and_b32_e32 v139, 0xffff0000, v149
	v_lshlrev_b32_e32 v140, 16, v150
	v_and_b32_e32 v141, 0xffff0000, v150
	v_lshlrev_b32_e32 v142, 16, v151
	v_and_b32_e32 v143, 0xffff0000, v151
	v_pk_mul_f32 v[136:137], v[22:23], v[136:137]
	v_pk_mul_f32 v[138:139], v[24:25], v[138:139]
	v_pk_mul_f32 v[140:141], v[18:19], v[140:141]
	v_pk_mul_f32 v[142:143], v[20:21], v[142:143]
	v_cvt_pk_bf16_f32 v136, v136, v137
	v_cvt_pk_bf16_f32 v137, v138, v139
	v_cvt_pk_bf16_f32 v138, v140, v141
	v_cvt_pk_bf16_f32 v139, v142, v143
	v_add_u32_e32 v150, 0xa0, v134
	global_store_dwordx4 v[176:177], v[136:139], off offset:-2048
	s_nop 0
	s_nop 0
	v_lshrrev_b32_e32 v137, 3, v150
	v_lshlrev_b32_e32 v138, 6, v150
	v_lshlrev_b32_e32 v139, 2, v150
	v_lshlrev_b32_e32 v136, 7, v150
	v_and_or_b32 v137, v137, 14, v133
	v_and_b32_e32 v138, 0x3c0, v138
	v_and_b32_e32 v139, 32, v139
	v_and_b32_e32 v136, 0x4000, v136
	v_lshlrev_b32_e32 v137, 10, v137
	v_bitop3_b32 v138, v138, v139, v132 bitop3:0x36
	v_or3_b32 v198, v137, v136, v138
	global_load_dwordx4 v[136:139], v[170:171], off
	v_add_u32_e32 v160, 0xb0, v134
	v_lshrrev_b32_e32 v135, 3, v160
	v_and_or_b32 v133, v135, 14, v133
	v_lshlrev_b32_e32 v135, 6, v160
	v_lshlrev_b32_e32 v144, 2, v160
	v_lshlrev_b32_e32 v134, 7, v160
	v_and_b32_e32 v135, 0x3c0, v135
	v_and_b32_e32 v144, 32, v144
	v_and_b32_e32 v134, 0x4000, v134
	v_lshlrev_b32_e32 v133, 10, v133
	v_bitop3_b32 v132, v135, v144, v132 bitop3:0x36
	global_load_dwordx4 v[140:143], v[172:173], off
	v_or3_b32 v148, v133, v134, v132
	v_mov_b32_e32 v149, v199
	global_load_dwordx4 v[132:135], v[170:171], off offset:2048
	global_load_dwordx4 v[144:147], v[172:173], off offset:2048
	v_ashrrev_i32_e32 v150, 4, v150
	v_and_b32_e32 v161, -16, v150
	s_waitcnt vmcnt(3)
	v_lshlrev_b32_e32 v150, 16, v136
	v_and_b32_e32 v151, 0xffff0000, v136
	v_lshlrev_b32_e32 v136, 16, v137
	v_and_b32_e32 v137, 0xffff0000, v137
	v_pk_mul_f32 v[152:153], v[48:49], v[136:137]
	v_lshlrev_b32_e32 v136, 16, v138
	v_and_b32_e32 v137, 0xffff0000, v138
	v_pk_mul_f32 v[154:155], v[42:43], v[136:137]
	v_lshlrev_b32_e32 v136, 16, v139
	v_and_b32_e32 v137, 0xffff0000, v139
	v_pk_mul_f32 v[156:157], v[44:45], v[136:137]
	v_add_u32_e32 v136, v161, v131
	v_ashrrev_i32_e32 v137, 31, v136
	v_lshlrev_b64 v[136:137], 15, v[136:137]
	v_pk_mul_f32 v[150:151], v[46:47], v[150:151]
	v_lshl_add_u64 v[136:137], s[10:11], 0, v[136:137]
	v_lshl_add_u64 v[158:159], v[136:137], 0, v[198:199]
	v_cvt_pk_bf16_f32 v136, v150, v151
	v_cvt_pk_bf16_f32 v137, v152, v153
	v_cvt_pk_bf16_f32 v138, v154, v155
	v_cvt_pk_bf16_f32 v139, v156, v157
	global_store_dwordx4 v[168:169], v[136:139], off
	s_nop 0
	s_nop 0
	s_waitcnt vmcnt(3)
	v_lshlrev_b32_e32 v136, 16, v140
	v_and_b32_e32 v137, 0xffff0000, v140
	v_lshlrev_b32_e32 v138, 16, v141
	v_and_b32_e32 v139, 0xffff0000, v141
	v_lshlrev_b32_e32 v140, 16, v142
	v_and_b32_e32 v141, 0xffff0000, v142
	v_lshlrev_b32_e32 v142, 16, v143
	v_and_b32_e32 v143, 0xffff0000, v143
	v_pk_mul_f32 v[136:137], v[14:15], v[136:137]
	v_pk_mul_f32 v[138:139], v[16:17], v[138:139]
	v_pk_mul_f32 v[140:141], v[10:11], v[140:141]
	v_pk_mul_f32 v[142:143], v[12:13], v[142:143]
	v_cvt_pk_bf16_f32 v136, v136, v137
	v_cvt_pk_bf16_f32 v137, v138, v139
	v_cvt_pk_bf16_f32 v138, v140, v141
	v_cvt_pk_bf16_f32 v139, v142, v143
	global_store_dwordx4 v[176:177], v[136:139], off
	s_nop 1
	v_ashrrev_i32_e32 v136, 4, v160
	v_and_b32_e32 v152, -16, v136
	s_waitcnt vmcnt(3)
	v_lshlrev_b32_e32 v136, 16, v132
	v_and_b32_e32 v137, 0xffff0000, v132
	v_lshlrev_b32_e32 v132, 16, v133
	v_and_b32_e32 v133, 0xffff0000, v133
	v_pk_mul_f32 v[138:139], v[40:41], v[132:133]
	v_lshlrev_b32_e32 v132, 16, v134
	v_and_b32_e32 v133, 0xffff0000, v134
	v_pk_mul_f32 v[140:141], v[34:35], v[132:133]
	v_lshlrev_b32_e32 v132, 16, v135
	v_and_b32_e32 v133, 0xffff0000, v135
	v_pk_mul_f32 v[142:143], v[36:37], v[132:133]
	v_add_u32_e32 v132, v152, v131
	v_ashrrev_i32_e32 v133, 31, v132
	v_lshlrev_b64 v[132:133], 15, v[132:133]
	v_pk_mul_f32 v[136:137], v[38:39], v[136:137]
	v_lshl_add_u64 v[132:133], s[10:11], 0, v[132:133]
	v_add_u32_e32 v130, v130, v152
	v_lshl_add_u64 v[150:151], v[132:133], 0, v[148:149]
	v_cvt_pk_bf16_f32 v132, v136, v137
	v_cvt_pk_bf16_f32 v133, v138, v139
	v_cvt_pk_bf16_f32 v134, v140, v141
	v_cvt_pk_bf16_f32 v135, v142, v143
	v_ashrrev_i32_e32 v131, 31, v130
	global_store_dwordx4 v[168:169], v[132:135], off offset:2048
	s_waitcnt vmcnt(3)
	v_lshlrev_b32_e32 v136, 16, v146
	v_and_b32_e32 v137, 0xffff0000, v146
	v_lshlrev_b32_e32 v132, 16, v144
	v_and_b32_e32 v133, 0xffff0000, v144
	v_lshlrev_b32_e32 v134, 16, v145
	v_and_b32_e32 v135, 0xffff0000, v145
	v_lshlrev_b32_e32 v138, 16, v147
	v_and_b32_e32 v139, 0xffff0000, v147
	v_lshlrev_b64 v[130:131], 15, v[130:131]
	v_pk_mul_f32 v[132:133], v[6:7], v[132:133]
	v_pk_mul_f32 v[134:135], v[8:9], v[134:135]
	v_pk_mul_f32 v[136:137], v[2:3], v[136:137]
	v_pk_mul_f32 v[138:139], v[4:5], v[138:139]
	v_lshl_add_u64 v[130:131], s[10:11], 0, v[130:131]
	v_lshl_add_u64 v[140:141], v[130:131], 0, v[148:149]
	v_cvt_pk_bf16_f32 v130, v132, v133
	v_cvt_pk_bf16_f32 v131, v134, v135
	v_cvt_pk_bf16_f32 v132, v136, v137
	v_cvt_pk_bf16_f32 v133, v138, v139
	global_store_dwordx4 v[176:177], v[130:133], off offset:2048
	s_cbranch_vccnz .LBB0_1303
	s_andn2_b64 vcc, exec, s[18:19]
	s_cbranch_vccnz .LBB0_1302
	s_barrier
	s_branch .LBB0_1302

.LBB0_1371:
	s_xor_b64 s[28:29], s[22:23], -1
	s_add_u32 s71, s6, 0x20000
	s_addc_u32 s72, s7, 0
	s_ashr_i32 s27, s26, 31
	s_lshl_b64 s[30:31], s[26:27], 18
	s_add_u32 s30, s33, s30
	s_addc_u32 s31, s50, s31
	s_and_b64 s[38:39], s[22:23], exec
	s_cselect_b32 s27, s31, s17
	s_cselect_b32 s73, s30, s16
	s_ashr_i32 s25, s24, 31
	s_lshl_b64 s[38:39], s[24:25], 18
	ds_read_b128 v[2:5], v168
	ds_read_b128 v[6:9], v168 offset:1024
	ds_read_b128 v[10:13], v168 offset:2048
	ds_read_b128 v[14:17], v168 offset:3072
	ds_read_b128 v[18:21], v169
	ds_read_b128 v[22:25], v169 offset:1024
	ds_read_b128 v[26:29], v169 offset:2048
	ds_read_b128 v[30:33], v169 offset:3072
	s_add_u32 s38, s51, s38
	s_addc_u32 s39, s53, s39
	s_and_b64 s[40:41], s[22:23], exec
	s_cselect_b32 s25, s39, s7
	s_cselect_b32 s74, s38, s6
	s_add_u32 s46, s16, 0x10000
	s_addc_u32 s47, s17, 0
	s_add_u32 s76, s6, 0x10000
	s_addc_u32 s77, s7, 0
	s_add_u32 s40, s16, 0x18000
	s_addc_u32 s41, s17, 0
	s_add_u32 s42, s6, 0x18000
	s_addc_u32 s43, s7, 0
	ds_read_b128 v[34:37], v170
	ds_read_b128 v[38:41], v170 offset:1024
	ds_read_b128 v[42:45], v170 offset:2048
	ds_read_b128 v[46:49], v170 offset:3072
	ds_read_b128 v[50:53], v170 offset:4096
	ds_read_b128 v[54:57], v170 offset:5120
	ds_read_b128 v[58:61], v170 offset:6144
	ds_read_b128 v[62:65], v170 offset:7168
	s_add_u32 s78, s16, 0xc000
	s_addc_u32 s79, s17, 0
	s_mov_b32 m0, s63
	s_nop 0
	global_load_lds_dwordx4 v202, s[78:79]
	s_add_u32 m0, s63, 0x2000
	s_nop 0
	global_load_lds_dwordx4 v203, s[78:79]
	s_waitcnt vmcnt(8)
	s_waitcnt lgkmcnt(0)
	s_barrier
	s_setprio 1
	s_waitcnt lgkmcnt(1)
	v_mfma_f32_16x16x32_bf16 v[90:93], v[2:5], v[58:61], 0
	v_mfma_f32_16x16x32_bf16 v[66:69], v[2:5], v[34:37], 0
	v_mfma_f32_16x16x32_bf16 v[70:73], v[10:13], v[34:37], 0
	v_mfma_f32_16x16x32_bf16 v[74:77], v[2:5], v[42:45], 0
	v_mfma_f32_16x16x32_bf16 v[78:81], v[10:13], v[42:45], 0
	v_mfma_f32_16x16x32_bf16 v[82:85], v[2:5], v[50:53], 0
	v_mfma_f32_16x16x32_bf16 v[86:89], v[10:13], v[50:53], 0
	s_waitcnt lgkmcnt(0)
	v_mfma_f32_16x16x32_bf16 v[98:101], v[6:9], v[62:65], v[90:93]
	v_mfma_f32_16x16x32_bf16 v[90:93], v[10:13], v[58:61], 0
	v_mfma_f32_16x16x32_bf16 v[66:69], v[6:9], v[38:41], v[66:69]
	v_mfma_f32_16x16x32_bf16 v[70:73], v[14:17], v[38:41], v[70:73]
	v_mfma_f32_16x16x32_bf16 v[74:77], v[6:9], v[46:49], v[74:77]
	v_mfma_f32_16x16x32_bf16 v[78:81], v[14:17], v[46:49], v[78:81]
	v_mfma_f32_16x16x32_bf16 v[82:85], v[6:9], v[54:57], v[82:85]
	v_mfma_f32_16x16x32_bf16 v[86:89], v[14:17], v[54:57], v[86:89]
	v_mfma_f32_16x16x32_bf16 v[102:105], v[14:17], v[62:65], v[90:93]
	s_setprio 0
	s_setprio 1
	v_mfma_f32_16x16x32_bf16 v[90:93], v[18:21], v[34:37], 0
	v_mfma_f32_16x16x32_bf16 v[34:37], v[26:29], v[34:37], 0
	v_mfma_f32_16x16x32_bf16 v[114:117], v[22:25], v[38:41], v[90:93]
	v_mfma_f32_16x16x32_bf16 v[34:37], v[30:33], v[38:41], v[34:37]
	v_mfma_f32_16x16x32_bf16 v[38:41], v[18:21], v[42:45], 0
	v_mfma_f32_16x16x32_bf16 v[42:45], v[26:29], v[42:45], 0
	v_mfma_f32_16x16x32_bf16 v[38:41], v[22:25], v[46:49], v[38:41]
	v_mfma_f32_16x16x32_bf16 v[42:45], v[30:33], v[46:49], v[42:45]
	v_mfma_f32_16x16x32_bf16 v[46:49], v[18:21], v[50:53], 0
	v_mfma_f32_16x16x32_bf16 v[50:53], v[26:29], v[50:53], 0
	v_mfma_f32_16x16x32_bf16 v[46:49], v[22:25], v[54:57], v[46:49]
	v_mfma_f32_16x16x32_bf16 v[50:53], v[30:33], v[54:57], v[50:53]
	v_mfma_f32_16x16x32_bf16 v[54:57], v[18:21], v[58:61], 0
	v_mfma_f32_16x16x32_bf16 v[58:61], v[26:29], v[58:61], 0
	v_mfma_f32_16x16x32_bf16 v[54:57], v[22:25], v[62:65], v[54:57]
	v_mfma_f32_16x16x32_bf16 v[58:61], v[30:33], v[62:65], v[58:61]
	s_setprio 0
	s_barrier
	ds_read_b128 v[62:65], v170 offset:16384
	ds_read_b128 v[90:93], v170 offset:17408
	ds_read_b128 v[94:97], v170 offset:18432
	ds_read_b128 v[106:109], v170 offset:19456
	ds_read_b128 v[110:113], v170 offset:20480
	ds_read_b128 v[118:121], v170 offset:21504
	ds_read_b128 v[122:125], v170 offset:22528
	ds_read_b128 v[126:129], v170 offset:23552
	s_mov_b32 m0, s13
	s_nop 0
	global_load_lds_dwordx4 v202, s[76:77]
	s_add_u32 m0, s13, 0x2000
	s_nop 0
	global_load_lds_dwordx4 v203, s[76:77]
	s_add_u32 s76, s6, 0x14000
	s_addc_u32 s77, s7, 0
	s_mov_b32 m0, s55
	s_nop 0
	global_load_lds_dwordx4 v202, s[76:77]
	s_add_u32 m0, s55, 0x2000
	s_nop 0
	global_load_lds_dwordx4 v203, s[76:77]
	s_nop 0
	s_mov_b32 m0, s54
	s_nop 0
	global_load_lds_dwordx4 v202, s[46:47]
	s_add_u32 m0, s54, 0x2000
	s_nop 0
	global_load_lds_dwordx4 v203, s[46:47]
	s_waitcnt vmcnt(8)
	s_waitcnt lgkmcnt(0)
	s_barrier
	s_setprio 1
	s_waitcnt lgkmcnt(7)
	v_mfma_f32_16x16x32_bf16 v[130:133], v[2:5], v[62:65], 0
	s_waitcnt lgkmcnt(5)
	v_mfma_f32_16x16x32_bf16 v[138:141], v[2:5], v[94:97], 0
	s_waitcnt lgkmcnt(3)
	v_mfma_f32_16x16x32_bf16 v[146:149], v[2:5], v[110:113], 0
	s_waitcnt lgkmcnt(1)
	v_mfma_f32_16x16x32_bf16 v[2:5], v[2:5], v[122:125], 0
	v_mfma_f32_16x16x32_bf16 v[130:133], v[6:9], v[90:93], v[130:133]
	v_mfma_f32_16x16x32_bf16 v[138:141], v[6:9], v[106:109], v[138:141]
	v_mfma_f32_16x16x32_bf16 v[146:149], v[6:9], v[118:121], v[146:149]
	s_waitcnt lgkmcnt(0)
	v_mfma_f32_16x16x32_bf16 v[2:5], v[6:9], v[126:129], v[2:5]
	v_mfma_f32_16x16x32_bf16 v[6:9], v[10:13], v[122:125], 0
	v_mfma_f32_16x16x32_bf16 v[134:137], v[10:13], v[62:65], 0
	v_mfma_f32_16x16x32_bf16 v[142:145], v[10:13], v[94:97], 0
	v_mfma_f32_16x16x32_bf16 v[150:153], v[10:13], v[110:113], 0
	v_mfma_f32_16x16x32_bf16 v[6:9], v[14:17], v[126:129], v[6:9]
	v_mfma_f32_16x16x32_bf16 v[134:137], v[14:17], v[90:93], v[134:137]
	v_mfma_f32_16x16x32_bf16 v[142:145], v[14:17], v[106:109], v[142:145]
	v_mfma_f32_16x16x32_bf16 v[150:153], v[14:17], v[118:121], v[150:153]
	s_setprio 0
	s_setprio 1
	v_mfma_f32_16x16x32_bf16 v[10:13], v[18:21], v[62:65], 0
	v_mfma_f32_16x16x32_bf16 v[158:161], v[22:25], v[90:93], v[10:13]
	v_mfma_f32_16x16x32_bf16 v[10:13], v[26:29], v[62:65], 0
	v_mfma_f32_16x16x32_bf16 v[162:165], v[30:33], v[90:93], v[10:13]
	v_mfma_f32_16x16x32_bf16 v[10:13], v[18:21], v[94:97], 0
	v_mfma_f32_16x16x32_bf16 v[174:177], v[22:25], v[106:109], v[10:13]
	v_mfma_f32_16x16x32_bf16 v[10:13], v[26:29], v[94:97], 0
	v_mfma_f32_16x16x32_bf16 v[178:181], v[30:33], v[106:109], v[10:13]
	v_mfma_f32_16x16x32_bf16 v[10:13], v[18:21], v[110:113], 0
	v_mfma_f32_16x16x32_bf16 v[182:185], v[22:25], v[118:121], v[10:13]
	v_mfma_f32_16x16x32_bf16 v[10:13], v[26:29], v[110:113], 0
	v_mfma_f32_16x16x32_bf16 v[186:189], v[30:33], v[118:121], v[10:13]
	v_mfma_f32_16x16x32_bf16 v[10:13], v[18:21], v[122:125], 0
	v_mfma_f32_16x16x32_bf16 v[190:193], v[22:25], v[126:129], v[10:13]
	v_mfma_f32_16x16x32_bf16 v[10:13], v[26:29], v[122:125], 0
	v_mfma_f32_16x16x32_bf16 v[198:201], v[30:33], v[126:129], v[10:13]
	s_setprio 0
	s_barrier
	s_nop 4
	ds_read_b128 v[10:13], v171
	ds_read_b128 v[14:17], v171 offset:1024
	ds_read_b128 v[18:21], v171 offset:2048
	ds_read_b128 v[22:25], v171 offset:3072
	ds_read_b128 v[204:207], v172
	ds_read_b128 v[212:215], v172 offset:1024
	ds_read_b128 v[216:219], v172 offset:2048
	ds_read_b128 v[220:223], v172 offset:3072
	ds_read_b128 v[26:29], v170 offset:32768
	ds_read_b128 v[30:33], v170 offset:33792
	ds_read_b128 v[62:65], v170 offset:34816
	ds_read_b128 v[224:227], v170 offset:35840
	ds_read_b128 v[228:231], v170 offset:36864
	ds_read_b128 v[232:235], v170 offset:37888
	ds_read_b128 v[236:239], v170 offset:38912
	ds_read_b128 v[240:243], v170 offset:39936
	s_add_u32 s46, s16, 0x14000
	s_addc_u32 s47, s17, 0
	s_mov_b32 m0, s56
	s_nop 0
	global_load_lds_dwordx4 v202, s[46:47]
	s_add_u32 m0, s56, 0x2000
	s_nop 0
	global_load_lds_dwordx4 v203, s[46:47]
	s_waitcnt vmcnt(8)
	s_waitcnt lgkmcnt(0)
	s_barrier
	s_setprio 1
	s_waitcnt lgkmcnt(7)
	v_mfma_f32_16x16x32_bf16 v[66:69], v[10:13], v[26:29], v[66:69]
	s_waitcnt lgkmcnt(6)
	v_mfma_f32_16x16x32_bf16 v[126:129], v[14:17], v[30:33], v[66:69]
	v_mfma_f32_16x16x32_bf16 v[66:69], v[18:21], v[26:29], v[70:73]
	v_mfma_f32_16x16x32_bf16 v[122:125], v[22:25], v[30:33], v[66:69]
	s_waitcnt lgkmcnt(5)
	v_mfma_f32_16x16x32_bf16 v[66:69], v[10:13], v[62:65], v[74:77]
	s_waitcnt lgkmcnt(4)
	v_mfma_f32_16x16x32_bf16 v[110:113], v[14:17], v[224:227], v[66:69]
	v_mfma_f32_16x16x32_bf16 v[66:69], v[18:21], v[62:65], v[78:81]
	v_mfma_f32_16x16x32_bf16 v[106:109], v[22:25], v[224:227], v[66:69]
	s_waitcnt lgkmcnt(3)
	v_mfma_f32_16x16x32_bf16 v[66:69], v[10:13], v[228:231], v[82:85]
	s_waitcnt lgkmcnt(2)
	v_mfma_f32_16x16x32_bf16 v[94:97], v[14:17], v[232:235], v[66:69]
	v_mfma_f32_16x16x32_bf16 v[66:69], v[18:21], v[228:231], v[86:89]
	v_mfma_f32_16x16x32_bf16 v[90:93], v[22:25], v[232:235], v[66:69]
	s_waitcnt lgkmcnt(1)
	v_mfma_f32_16x16x32_bf16 v[66:69], v[10:13], v[236:239], v[98:101]
	s_waitcnt lgkmcnt(0)
	v_mfma_f32_16x16x32_bf16 v[78:81], v[14:17], v[240:243], v[66:69]
	v_mfma_f32_16x16x32_bf16 v[66:69], v[18:21], v[236:239], v[102:105]
	v_mfma_f32_16x16x32_bf16 v[74:77], v[22:25], v[240:243], v[66:69]
	s_setprio 0
	s_setprio 1
	v_mfma_f32_16x16x32_bf16 v[66:69], v[204:207], v[26:29], v[114:117]
	v_mfma_f32_16x16x32_bf16 v[26:29], v[216:219], v[26:29], v[34:37]
	v_mfma_f32_16x16x32_bf16 v[114:117], v[220:223], v[30:33], v[26:29]
	v_mfma_f32_16x16x32_bf16 v[26:29], v[204:207], v[62:65], v[38:41]
	v_mfma_f32_16x16x32_bf16 v[102:105], v[212:215], v[224:227], v[26:29]
	v_mfma_f32_16x16x32_bf16 v[26:29], v[216:219], v[62:65], v[42:45]
	v_mfma_f32_16x16x32_bf16 v[98:101], v[220:223], v[224:227], v[26:29]
	v_mfma_f32_16x16x32_bf16 v[26:29], v[204:207], v[228:231], v[46:49]
	v_mfma_f32_16x16x32_bf16 v[86:89], v[212:215], v[232:235], v[26:29]
	v_mfma_f32_16x16x32_bf16 v[26:29], v[216:219], v[228:231], v[50:53]
	v_mfma_f32_16x16x32_bf16 v[82:85], v[220:223], v[232:235], v[26:29]
	v_mfma_f32_16x16x32_bf16 v[26:29], v[204:207], v[236:239], v[54:57]
	v_mfma_f32_16x16x32_bf16 v[70:73], v[212:215], v[240:243], v[26:29]
	v_mfma_f32_16x16x32_bf16 v[26:29], v[216:219], v[236:239], v[58:61]
	v_mfma_f32_16x16x32_bf16 v[118:121], v[212:215], v[30:33], v[66:69]
	v_mfma_f32_16x16x32_bf16 v[66:69], v[220:223], v[240:243], v[26:29]
	s_setprio 0
	s_barrier
	ds_read_b128 v[34:37], v170 offset:49152
	ds_read_b128 v[38:41], v170 offset:50176
	ds_read_b128 v[224:227], v170 offset:51200
	ds_read_b128 v[228:231], v170 offset:52224
	ds_read_b128 v[232:235], v170 offset:53248
	ds_read_b128 v[236:239], v170 offset:54272
	ds_read_b128 v[240:243], v170 offset:55296
	ds_read_b128 v[244:247], v170 offset:56320
	s_mov_b32 m0, s59
	s_nop 0
	global_load_lds_dwordx4 v202, s[42:43]
	s_add_u32 m0, s59, 0x2000
	s_nop 0
	global_load_lds_dwordx4 v203, s[42:43]
	s_add_u32 s6, s6, 0x1c000
	s_addc_u32 s7, s7, 0
	s_mov_b32 m0, s62
	s_nop 0
	global_load_lds_dwordx4 v202, s[6:7]
	s_add_u32 m0, s62, 0x2000
	s_nop 0
	global_load_lds_dwordx4 v203, s[6:7]
	s_nop 0
	s_mov_b32 m0, s61
	s_nop 0
	global_load_lds_dwordx4 v202, s[40:41]
	s_add_u32 m0, s61, 0x2000
	s_nop 0
	global_load_lds_dwordx4 v203, s[40:41]
	s_waitcnt vmcnt(8)
	s_waitcnt lgkmcnt(0)
	s_barrier
	s_setprio 1
	s_waitcnt lgkmcnt(7)
	v_mfma_f32_16x16x32_bf16 v[26:29], v[10:13], v[34:37], v[130:133]
	s_waitcnt lgkmcnt(6)
	v_mfma_f32_16x16x32_bf16 v[62:65], v[14:17], v[38:41], v[26:29]
	v_mfma_f32_16x16x32_bf16 v[26:29], v[18:21], v[34:37], v[134:137]
	v_mfma_f32_16x16x32_bf16 v[58:61], v[22:25], v[38:41], v[26:29]
	s_waitcnt lgkmcnt(5)
	v_mfma_f32_16x16x32_bf16 v[26:29], v[10:13], v[224:227], v[138:141]
	s_waitcnt lgkmcnt(4)
	v_mfma_f32_16x16x32_bf16 v[46:49], v[14:17], v[228:231], v[26:29]
	v_mfma_f32_16x16x32_bf16 v[26:29], v[18:21], v[224:227], v[142:145]
	v_mfma_f32_16x16x32_bf16 v[42:45], v[22:25], v[228:231], v[26:29]
	s_waitcnt lgkmcnt(3)
	v_mfma_f32_16x16x32_bf16 v[26:29], v[10:13], v[232:235], v[146:149]
	s_waitcnt lgkmcnt(1)
	v_mfma_f32_16x16x32_bf16 v[2:5], v[10:13], v[240:243], v[2:5]
	v_mfma_f32_16x16x32_bf16 v[30:33], v[14:17], v[236:239], v[26:29]
	v_mfma_f32_16x16x32_bf16 v[26:29], v[18:21], v[232:235], v[150:153]
	s_waitcnt lgkmcnt(0)
	v_mfma_f32_16x16x32_bf16 v[14:17], v[14:17], v[244:247], v[2:5]
	v_mfma_f32_16x16x32_bf16 v[2:5], v[18:21], v[240:243], v[6:9]
	v_mfma_f32_16x16x32_bf16 v[26:29], v[22:25], v[236:239], v[26:29]
	v_mfma_f32_16x16x32_bf16 v[10:13], v[22:25], v[244:247], v[2:5]
	s_setprio 0
	s_setprio 1
	v_mfma_f32_16x16x32_bf16 v[2:5], v[204:207], v[34:37], v[158:161]
	v_mfma_f32_16x16x32_bf16 v[54:57], v[212:215], v[38:41], v[2:5]
	v_mfma_f32_16x16x32_bf16 v[2:5], v[216:219], v[34:37], v[162:165]
	v_mfma_f32_16x16x32_bf16 v[50:53], v[220:223], v[38:41], v[2:5]
	v_mfma_f32_16x16x32_bf16 v[2:5], v[204:207], v[224:227], v[174:177]
	v_mfma_f32_16x16x32_bf16 v[38:41], v[212:215], v[228:231], v[2:5]
	v_mfma_f32_16x16x32_bf16 v[2:5], v[216:219], v[224:227], v[178:181]
	v_mfma_f32_16x16x32_bf16 v[34:37], v[220:223], v[228:231], v[2:5]
	v_mfma_f32_16x16x32_bf16 v[2:5], v[204:207], v[232:235], v[182:185]
	v_mfma_f32_16x16x32_bf16 v[22:25], v[212:215], v[236:239], v[2:5]
	v_mfma_f32_16x16x32_bf16 v[2:5], v[216:219], v[232:235], v[186:189]
	v_mfma_f32_16x16x32_bf16 v[18:21], v[220:223], v[236:239], v[2:5]
	v_mfma_f32_16x16x32_bf16 v[2:5], v[204:207], v[240:243], v[190:193]
	v_mfma_f32_16x16x32_bf16 v[6:9], v[212:215], v[244:247], v[2:5]
	v_mfma_f32_16x16x32_bf16 v[2:5], v[216:219], v[240:243], v[198:201]
	v_mfma_f32_16x16x32_bf16 v[2:5], v[220:223], v[244:247], v[2:5]
	s_setprio 0
	s_barrier
	s_mov_b32 s75, 0
	s_mov_b64 s[6:7], 0
	v_mov_b32_e32 v131, s48

.LBB0_1374:
	s_or_b64 exec, exec, s[40:41]
	s_add_u32 s76, s16, s6
	ds_read_b128 v[132:135], v168
	ds_read_b128 v[136:139], v168 offset:1024
	ds_read_b128 v[140:143], v168 offset:2048
	ds_read_b128 v[144:147], v168 offset:3072
	ds_read_b128 v[148:151], v169
	ds_read_b128 v[158:161], v169 offset:1024
	ds_read_b128 v[162:165], v169 offset:2048
	ds_read_b128 v[174:177], v169 offset:3072
	s_addc_u32 s77, s17, s7
	s_add_u32 s40, s76, 0x20000
	s_addc_u32 s41, s77, 0
	s_add_u32 s42, s71, s6
	s_addc_u32 s43, s72, s7
	s_cmp_eq_u32 s6, 0x20000
	s_cselect_b32 s48, s73, s40
	s_cselect_b32 s49, s27, s41
	s_cselect_b32 s41, s25, s43
	s_cselect_b32 s40, s74, s42
	s_add_u32 s42, s48, 0x8000
	s_addc_u32 s43, s49, 0
	s_add_u32 s46, s40, 0x8000
	s_addc_u32 s47, s41, 0
	ds_read_b128 v[178:181], v170
	ds_read_b128 v[182:185], v170 offset:1024
	ds_read_b128 v[186:189], v170 offset:2048
	ds_read_b128 v[190:193], v170 offset:3072
	ds_read_b128 v[198:201], v170 offset:4096
	ds_read_b128 v[204:207], v170 offset:5120
	ds_read_b128 v[212:215], v170 offset:6144
	ds_read_b128 v[216:219], v170 offset:7168
	s_add_u32 s76, s76, 0x1c000
	s_addc_u32 s77, s77, 0
	s_mov_b32 m0, s63
	s_nop 0
	global_load_lds_dwordx4 v202, s[76:77]
	s_add_u32 m0, s63, 0x2000
	s_nop 0
	global_load_lds_dwordx4 v203, s[76:77]
	s_waitcnt vmcnt(8)
	s_waitcnt lgkmcnt(0)
	s_barrier
	s_setprio 1
	s_waitcnt lgkmcnt(7)
	v_mfma_f32_16x16x32_bf16 v[126:129], v[132:135], v[178:181], v[126:129]
	v_mfma_f32_16x16x32_bf16 v[122:125], v[140:143], v[178:181], v[122:125]
	s_waitcnt lgkmcnt(5)
	v_mfma_f32_16x16x32_bf16 v[110:113], v[132:135], v[186:189], v[110:113]
	v_mfma_f32_16x16x32_bf16 v[106:109], v[140:143], v[186:189], v[106:109]
	s_waitcnt lgkmcnt(3)
	v_mfma_f32_16x16x32_bf16 v[94:97], v[132:135], v[198:201], v[94:97]
	v_mfma_f32_16x16x32_bf16 v[90:93], v[140:143], v[198:201], v[90:93]
	s_waitcnt lgkmcnt(1)
	v_mfma_f32_16x16x32_bf16 v[78:81], v[132:135], v[212:215], v[78:81]
	v_mfma_f32_16x16x32_bf16 v[74:77], v[140:143], v[212:215], v[74:77]
	v_mfma_f32_16x16x32_bf16 v[126:129], v[136:139], v[182:185], v[126:129]
	v_mfma_f32_16x16x32_bf16 v[122:125], v[144:147], v[182:185], v[122:125]
	v_mfma_f32_16x16x32_bf16 v[110:113], v[136:139], v[190:193], v[110:113]
	v_mfma_f32_16x16x32_bf16 v[106:109], v[144:147], v[190:193], v[106:109]
	v_mfma_f32_16x16x32_bf16 v[94:97], v[136:139], v[204:207], v[94:97]
	v_mfma_f32_16x16x32_bf16 v[90:93], v[144:147], v[204:207], v[90:93]
	s_waitcnt lgkmcnt(0)
	v_mfma_f32_16x16x32_bf16 v[78:81], v[136:139], v[216:219], v[78:81]
	v_mfma_f32_16x16x32_bf16 v[74:77], v[144:147], v[216:219], v[74:77]
	s_setprio 0
	s_setprio 1
	v_mfma_f32_16x16x32_bf16 v[118:121], v[148:151], v[178:181], v[118:121]
	v_mfma_f32_16x16x32_bf16 v[114:117], v[162:165], v[178:181], v[114:117]
	v_mfma_f32_16x16x32_bf16 v[102:105], v[148:151], v[186:189], v[102:105]
	v_mfma_f32_16x16x32_bf16 v[98:101], v[162:165], v[186:189], v[98:101]
	v_mfma_f32_16x16x32_bf16 v[86:89], v[148:151], v[198:201], v[86:89]
	v_mfma_f32_16x16x32_bf16 v[82:85], v[162:165], v[198:201], v[82:85]
	v_mfma_f32_16x16x32_bf16 v[70:73], v[148:151], v[212:215], v[70:73]
	v_mfma_f32_16x16x32_bf16 v[66:69], v[162:165], v[212:215], v[66:69]
	v_mfma_f32_16x16x32_bf16 v[118:121], v[158:161], v[182:185], v[118:121]
	v_mfma_f32_16x16x32_bf16 v[114:117], v[174:177], v[182:185], v[114:117]
	v_mfma_f32_16x16x32_bf16 v[102:105], v[158:161], v[190:193], v[102:105]
	v_mfma_f32_16x16x32_bf16 v[98:101], v[174:177], v[190:193], v[98:101]
	v_mfma_f32_16x16x32_bf16 v[86:89], v[158:161], v[204:207], v[86:89]
	v_mfma_f32_16x16x32_bf16 v[82:85], v[174:177], v[204:207], v[82:85]
	v_mfma_f32_16x16x32_bf16 v[70:73], v[158:161], v[216:219], v[70:73]
	v_mfma_f32_16x16x32_bf16 v[66:69], v[174:177], v[216:219], v[66:69]
	s_setprio 0
	s_barrier
	ds_read_b128 v[178:181], v170 offset:16384
	ds_read_b128 v[182:185], v170 offset:17408
	ds_read_b128 v[186:189], v170 offset:18432
	ds_read_b128 v[190:193], v170 offset:19456
	ds_read_b128 v[198:201], v170 offset:20480
	ds_read_b128 v[204:207], v170 offset:21504
	ds_read_b128 v[212:215], v170 offset:22528
	ds_read_b128 v[216:219], v170 offset:23552
	s_mov_b32 m0, s13
	s_nop 0
	global_load_lds_dwordx4 v202, s[40:41]
	s_add_u32 m0, s13, 0x2000
	s_nop 0
	global_load_lds_dwordx4 v203, s[40:41]
	s_add_u32 s76, s40, 0x4000
	s_addc_u32 s77, s41, 0
	s_mov_b32 m0, s55
	s_nop 0
	global_load_lds_dwordx4 v202, s[76:77]
	s_add_u32 m0, s55, 0x2000
	s_nop 0
	global_load_lds_dwordx4 v203, s[76:77]
	s_nop 0
	s_mov_b32 m0, s54
	s_nop 0
	global_load_lds_dwordx4 v202, s[48:49]
	s_add_u32 m0, s54, 0x2000
	s_nop 0
	global_load_lds_dwordx4 v203, s[48:49]
	s_waitcnt vmcnt(8)
	s_waitcnt lgkmcnt(0)
	s_barrier
	s_setprio 1
	s_waitcnt lgkmcnt(7)
	v_mfma_f32_16x16x32_bf16 v[62:65], v[132:135], v[178:181], v[62:65]
	v_mfma_f32_16x16x32_bf16 v[58:61], v[140:143], v[178:181], v[58:61]
	s_waitcnt lgkmcnt(5)
	v_mfma_f32_16x16x32_bf16 v[46:49], v[132:135], v[186:189], v[46:49]
	v_mfma_f32_16x16x32_bf16 v[42:45], v[140:143], v[186:189], v[42:45]
	s_waitcnt lgkmcnt(3)
	v_mfma_f32_16x16x32_bf16 v[30:33], v[132:135], v[198:201], v[30:33]
	v_mfma_f32_16x16x32_bf16 v[26:29], v[140:143], v[198:201], v[26:29]
	s_waitcnt lgkmcnt(1)
	v_mfma_f32_16x16x32_bf16 v[14:17], v[132:135], v[212:215], v[14:17]
	v_mfma_f32_16x16x32_bf16 v[10:13], v[140:143], v[212:215], v[10:13]
	v_mfma_f32_16x16x32_bf16 v[62:65], v[136:139], v[182:185], v[62:65]
	v_mfma_f32_16x16x32_bf16 v[58:61], v[144:147], v[182:185], v[58:61]
	v_mfma_f32_16x16x32_bf16 v[46:49], v[136:139], v[190:193], v[46:49]
	v_mfma_f32_16x16x32_bf16 v[42:45], v[144:147], v[190:193], v[42:45]
	v_mfma_f32_16x16x32_bf16 v[30:33], v[136:139], v[204:207], v[30:33]
	v_mfma_f32_16x16x32_bf16 v[26:29], v[144:147], v[204:207], v[26:29]
	s_waitcnt lgkmcnt(0)
	v_mfma_f32_16x16x32_bf16 v[14:17], v[136:139], v[216:219], v[14:17]
	v_mfma_f32_16x16x32_bf16 v[10:13], v[144:147], v[216:219], v[10:13]
	s_setprio 0
	s_setprio 1
	v_mfma_f32_16x16x32_bf16 v[54:57], v[148:151], v[178:181], v[54:57]
	v_mfma_f32_16x16x32_bf16 v[50:53], v[162:165], v[178:181], v[50:53]
	v_mfma_f32_16x16x32_bf16 v[38:41], v[148:151], v[186:189], v[38:41]
	v_mfma_f32_16x16x32_bf16 v[34:37], v[162:165], v[186:189], v[34:37]
	v_mfma_f32_16x16x32_bf16 v[22:25], v[148:151], v[198:201], v[22:25]
	v_mfma_f32_16x16x32_bf16 v[18:21], v[162:165], v[198:201], v[18:21]
	v_mfma_f32_16x16x32_bf16 v[6:9], v[148:151], v[212:215], v[6:9]
	v_mfma_f32_16x16x32_bf16 v[2:5], v[162:165], v[212:215], v[2:5]
	v_mfma_f32_16x16x32_bf16 v[54:57], v[158:161], v[182:185], v[54:57]
	v_mfma_f32_16x16x32_bf16 v[50:53], v[174:177], v[182:185], v[50:53]
	v_mfma_f32_16x16x32_bf16 v[38:41], v[158:161], v[190:193], v[38:41]
	v_mfma_f32_16x16x32_bf16 v[34:37], v[174:177], v[190:193], v[34:37]
	v_mfma_f32_16x16x32_bf16 v[22:25], v[158:161], v[204:207], v[22:25]
	v_mfma_f32_16x16x32_bf16 v[18:21], v[174:177], v[204:207], v[18:21]
	v_mfma_f32_16x16x32_bf16 v[6:9], v[158:161], v[216:219], v[6:9]
	v_mfma_f32_16x16x32_bf16 v[2:5], v[174:177], v[216:219], v[2:5]
	s_setprio 0
	s_barrier
	ds_read_b128 v[132:135], v171
	ds_read_b128 v[136:139], v171 offset:1024
	ds_read_b128 v[140:143], v171 offset:2048
	ds_read_b128 v[144:147], v171 offset:3072
	ds_read_b128 v[148:151], v172
	ds_read_b128 v[158:161], v172 offset:1024
	ds_read_b128 v[162:165], v172 offset:2048
	ds_read_b128 v[174:177], v172 offset:3072
	ds_read_b128 v[178:181], v170 offset:32768
	ds_read_b128 v[182:185], v170 offset:33792
	ds_read_b128 v[186:189], v170 offset:34816
	ds_read_b128 v[190:193], v170 offset:35840
	ds_read_b128 v[198:201], v170 offset:36864
	ds_read_b128 v[204:207], v170 offset:37888
	ds_read_b128 v[212:215], v170 offset:38912
	ds_read_b128 v[216:219], v170 offset:39936
	s_add_u32 s48, s48, 0x4000
	s_addc_u32 s49, s49, 0
	s_mov_b32 m0, s56
	s_nop 0
	global_load_lds_dwordx4 v202, s[48:49]
	s_add_u32 m0, s56, 0x2000
	s_nop 0
	global_load_lds_dwordx4 v203, s[48:49]
	s_waitcnt vmcnt(8)
	s_waitcnt lgkmcnt(0)
	s_barrier
	s_setprio 1
	s_waitcnt lgkmcnt(7)
	v_mfma_f32_16x16x32_bf16 v[126:129], v[132:135], v[178:181], v[126:129]
	v_mfma_f32_16x16x32_bf16 v[122:125], v[140:143], v[178:181], v[122:125]
	s_waitcnt lgkmcnt(5)
	v_mfma_f32_16x16x32_bf16 v[110:113], v[132:135], v[186:189], v[110:113]
	v_mfma_f32_16x16x32_bf16 v[106:109], v[140:143], v[186:189], v[106:109]
	s_waitcnt lgkmcnt(3)
	v_mfma_f32_16x16x32_bf16 v[94:97], v[132:135], v[198:201], v[94:97]
	v_mfma_f32_16x16x32_bf16 v[90:93], v[140:143], v[198:201], v[90:93]
	s_waitcnt lgkmcnt(1)
	v_mfma_f32_16x16x32_bf16 v[78:81], v[132:135], v[212:215], v[78:81]
	v_mfma_f32_16x16x32_bf16 v[74:77], v[140:143], v[212:215], v[74:77]
	v_mfma_f32_16x16x32_bf16 v[126:129], v[136:139], v[182:185], v[126:129]
	v_mfma_f32_16x16x32_bf16 v[122:125], v[144:147], v[182:185], v[122:125]
	v_mfma_f32_16x16x32_bf16 v[110:113], v[136:139], v[190:193], v[110:113]
	v_mfma_f32_16x16x32_bf16 v[106:109], v[144:147], v[190:193], v[106:109]
	v_mfma_f32_16x16x32_bf16 v[94:97], v[136:139], v[204:207], v[94:97]
	v_mfma_f32_16x16x32_bf16 v[90:93], v[144:147], v[204:207], v[90:93]
	s_waitcnt lgkmcnt(0)
	v_mfma_f32_16x16x32_bf16 v[78:81], v[136:139], v[216:219], v[78:81]
	v_mfma_f32_16x16x32_bf16 v[74:77], v[144:147], v[216:219], v[74:77]
	s_setprio 0
	s_setprio 1
	v_mfma_f32_16x16x32_bf16 v[118:121], v[148:151], v[178:181], v[118:121]
	v_mfma_f32_16x16x32_bf16 v[114:117], v[162:165], v[178:181], v[114:117]
	v_mfma_f32_16x16x32_bf16 v[102:105], v[148:151], v[186:189], v[102:105]
	v_mfma_f32_16x16x32_bf16 v[98:101], v[162:165], v[186:189], v[98:101]
	v_mfma_f32_16x16x32_bf16 v[86:89], v[148:151], v[198:201], v[86:89]
	v_mfma_f32_16x16x32_bf16 v[82:85], v[162:165], v[198:201], v[82:85]
	v_mfma_f32_16x16x32_bf16 v[70:73], v[148:151], v[212:215], v[70:73]
	v_mfma_f32_16x16x32_bf16 v[66:69], v[162:165], v[212:215], v[66:69]
	v_mfma_f32_16x16x32_bf16 v[118:121], v[158:161], v[182:185], v[118:121]
	v_mfma_f32_16x16x32_bf16 v[114:117], v[174:177], v[182:185], v[114:117]
	v_mfma_f32_16x16x32_bf16 v[102:105], v[158:161], v[190:193], v[102:105]
	v_mfma_f32_16x16x32_bf16 v[98:101], v[174:177], v[190:193], v[98:101]
	v_mfma_f32_16x16x32_bf16 v[86:89], v[158:161], v[204:207], v[86:89]
	v_mfma_f32_16x16x32_bf16 v[82:85], v[174:177], v[204:207], v[82:85]
	v_mfma_f32_16x16x32_bf16 v[70:73], v[158:161], v[216:219], v[70:73]
	v_mfma_f32_16x16x32_bf16 v[66:69], v[174:177], v[216:219], v[66:69]
	s_setprio 0
	s_barrier
	ds_read_b128 v[178:181], v170 offset:49152
	ds_read_b128 v[182:185], v170 offset:50176
	ds_read_b128 v[186:189], v170 offset:51200
	ds_read_b128 v[190:193], v170 offset:52224
	ds_read_b128 v[198:201], v170 offset:53248
	ds_read_b128 v[204:207], v170 offset:54272
	ds_read_b128 v[212:215], v170 offset:55296
	ds_read_b128 v[216:219], v170 offset:56320
	s_mov_b32 m0, s59
	s_nop 0
	global_load_lds_dwordx4 v202, s[46:47]
	s_add_u32 m0, s59, 0x2000
	s_nop 0
	global_load_lds_dwordx4 v203, s[46:47]
	s_add_u32 s40, s40, 0xc000
	s_addc_u32 s41, s41, 0
	s_mov_b32 m0, s62
	s_nop 0
	global_load_lds_dwordx4 v202, s[40:41]
	s_add_u32 m0, s62, 0x2000
	s_nop 0
	global_load_lds_dwordx4 v203, s[40:41]
	s_nop 0
	s_mov_b32 m0, s61
	s_nop 0
	global_load_lds_dwordx4 v202, s[42:43]
	s_add_u32 m0, s61, 0x2000
	s_nop 0
	global_load_lds_dwordx4 v203, s[42:43]
	s_waitcnt vmcnt(8)
	s_waitcnt lgkmcnt(0)
	s_barrier
	s_setprio 1
	s_waitcnt lgkmcnt(7)
	v_mfma_f32_16x16x32_bf16 v[62:65], v[132:135], v[178:181], v[62:65]
	v_mfma_f32_16x16x32_bf16 v[58:61], v[140:143], v[178:181], v[58:61]
	s_waitcnt lgkmcnt(5)
	v_mfma_f32_16x16x32_bf16 v[46:49], v[132:135], v[186:189], v[46:49]
	v_mfma_f32_16x16x32_bf16 v[42:45], v[140:143], v[186:189], v[42:45]
	s_waitcnt lgkmcnt(3)
	v_mfma_f32_16x16x32_bf16 v[30:33], v[132:135], v[198:201], v[30:33]
	v_mfma_f32_16x16x32_bf16 v[26:29], v[140:143], v[198:201], v[26:29]
	s_waitcnt lgkmcnt(1)
	v_mfma_f32_16x16x32_bf16 v[14:17], v[132:135], v[212:215], v[14:17]
	v_mfma_f32_16x16x32_bf16 v[10:13], v[140:143], v[212:215], v[10:13]
	v_mfma_f32_16x16x32_bf16 v[62:65], v[136:139], v[182:185], v[62:65]
	v_mfma_f32_16x16x32_bf16 v[58:61], v[144:147], v[182:185], v[58:61]
	v_mfma_f32_16x16x32_bf16 v[46:49], v[136:139], v[190:193], v[46:49]
	v_mfma_f32_16x16x32_bf16 v[42:45], v[144:147], v[190:193], v[42:45]
	v_mfma_f32_16x16x32_bf16 v[30:33], v[136:139], v[204:207], v[30:33]
	v_mfma_f32_16x16x32_bf16 v[26:29], v[144:147], v[204:207], v[26:29]
	s_waitcnt lgkmcnt(0)
	v_mfma_f32_16x16x32_bf16 v[14:17], v[136:139], v[216:219], v[14:17]
	v_mfma_f32_16x16x32_bf16 v[10:13], v[144:147], v[216:219], v[10:13]
	s_setprio 0
	s_setprio 1
	v_mfma_f32_16x16x32_bf16 v[54:57], v[148:151], v[178:181], v[54:57]
	v_mfma_f32_16x16x32_bf16 v[50:53], v[162:165], v[178:181], v[50:53]
	v_mfma_f32_16x16x32_bf16 v[38:41], v[148:151], v[186:189], v[38:41]
	v_mfma_f32_16x16x32_bf16 v[34:37], v[162:165], v[186:189], v[34:37]
	v_mfma_f32_16x16x32_bf16 v[22:25], v[148:151], v[198:201], v[22:25]
	v_mfma_f32_16x16x32_bf16 v[18:21], v[162:165], v[198:201], v[18:21]
	v_mfma_f32_16x16x32_bf16 v[6:9], v[148:151], v[212:215], v[6:9]
	v_mfma_f32_16x16x32_bf16 v[2:5], v[162:165], v[212:215], v[2:5]
	v_mfma_f32_16x16x32_bf16 v[54:57], v[158:161], v[182:185], v[54:57]
	v_mfma_f32_16x16x32_bf16 v[50:53], v[174:177], v[182:185], v[50:53]
	v_mfma_f32_16x16x32_bf16 v[38:41], v[158:161], v[190:193], v[38:41]
	v_mfma_f32_16x16x32_bf16 v[34:37], v[174:177], v[190:193], v[34:37]
	v_mfma_f32_16x16x32_bf16 v[22:25], v[158:161], v[204:207], v[22:25]
	v_mfma_f32_16x16x32_bf16 v[18:21], v[174:177], v[204:207], v[18:21]
	v_mfma_f32_16x16x32_bf16 v[6:9], v[158:161], v[216:219], v[6:9]
	v_mfma_f32_16x16x32_bf16 v[2:5], v[174:177], v[216:219], v[2:5]
	s_setprio 0
	s_barrier
	s_add_i32 s75, s75, 2
	s_add_u32 s6, s6, 0x10000
	s_addc_u32 s7, s7, 0
	s_cmp_gt_u32 s75, 5
	s_cbranch_scc1 .LBB0_1376
	v_mov_b32_e32 v131, v130
	s_branch .LBB0_1372

.LBB0_1378:
	s_lshl_b32 s6, s69, 8
	v_mov_b32_e32 v130, v210
	v_mov_b32_e32 v131, v195
	s_add_i32 s6, s6, s57
	v_add_u32_e32 v177, s6, v131
	s_lshl_b32 s6, s12, 8
	s_or_b32 s6, s6, s58
	v_lshl_add_u32 v138, v130, 3, s6
	v_bfe_u32 v176, v138, 5, 1
	v_lshrrev_b32_e32 v131, 3, v177
	v_lshlrev_b32_e32 v130, 1, v138
	v_and_or_b32 v131, v131, 14, v176
	v_and_b32_e32 v175, 48, v130
	v_add_u32_e32 v130, 0x400, v138
	v_lshlrev_b32_e32 v132, 6, v177
	v_lshlrev_b32_e32 v181, 10, v131
	v_lshlrev_b32_e32 v131, 2, v177
	v_ashrrev_i32_e32 v174, 6, v130
	v_ashrrev_i32_e32 v130, 3, v177
	v_and_b32_e32 v132, 0x3c0, v132
	v_and_b32_e32 v131, 32, v131
	v_and_b32_e32 v139, 0xffffffe0, v130
	v_lshlrev_b32_e32 v130, 7, v177
	v_bitop3_b32 v131, v175, v131, v132 bitop3:0x36
	v_ashrrev_i32_e32 v132, 4, v177
	v_and_b32_e32 v130, 0x4000, v130
	v_and_b32_e32 v140, -16, v132
	v_add_u32_e32 v134, v174, v139
	v_ashrrev_i32_e32 v178, 6, v138
	v_or3_b32 v154, v130, v131, v181
	v_ashrrev_i32_e32 v135, 31, v134
	v_add_u32_e32 v136, v178, v140
	v_lshl_add_u64 v[130:131], s[2:3], 0, v[154:155]
	v_lshlrev_b64 v[134:135], 15, v[134:135]
	v_ashrrev_i32_e32 v137, 31, v136
	v_lshl_add_u64 v[132:133], s[10:11], 0, v[154:155]
	v_lshl_add_u64 v[134:135], v[130:131], 0, v[134:135]
	v_lshlrev_b64 v[166:167], 15, v[136:137]
	v_lshl_add_u64 v[136:137], v[132:133], 0, v[166:167]
	v_lshl_add_u64 v[158:159], v[134:135], 0, 0
	global_load_dwordx4 v[182:185], v[134:135], off
	v_lshl_add_u64 v[160:161], v[136:137], 0, 0
	global_load_dwordx4 v[186:189], v[136:137], off
	s_mov_b32 s98, 0x11000
	s_mov_b32 s99, 0x0
	v_lshl_add_u64 v[162:163], v[158:159], 0, s[98:99]
	global_load_dwordx4 v[150:153], v[162:163], off offset:-4096
	s_mov_b32 s98, 0x11000
	s_mov_b32 s99, 0x0
	v_lshl_add_u64 v[164:165], v[160:161], 0, s[98:99]
	global_load_dwordx4 v[146:149], v[164:165], off offset:-4096
	s_mov_b32 s98, 0x1000
	s_mov_b32 s99, 0x0
	v_lshl_add_u64 v[198:199], v[158:159], 0, s[98:99]
	global_load_dwordx4 v[142:145], v[198:199], off offset:-2048
	s_mov_b32 s98, 0x1000
	s_mov_b32 s99, 0x0
	v_lshl_add_u64 v[200:201], v[160:161], 0, s[98:99]
	global_load_dwordx4 v[138:141], v[200:201], off offset:-2048
	global_load_dwordx4 v[134:137], v[162:163], off offset:-2048
	s_nop 0
	global_load_dwordx4 v[130:133], v[164:165], off offset:-2048
	s_cmpk_lt_i32 s69, 0x80
	s_cselect_b64 s[40:41], -1, 0
	s_xor_b64 s[42:43], s[36:37], -1
	v_lshl_add_u64 v[166:167], s[10:11], 0, v[166:167]
	s_and_b64 s[40:41], s[42:43], s[40:41]
	v_lshl_add_u64 v[166:167], v[166:167], 0, v[154:155]
	s_mov_b64 s[6:7], -1
	s_and_b64 vcc, exec, s[40:41]
	s_waitcnt vmcnt(7)
	v_lshlrev_b32_e32 v190, 16, v182
	v_and_b32_e32 v191, 0xffff0000, v182
	s_waitcnt vmcnt(6)
	v_lshlrev_b32_e32 v192, 16, v186
	v_and_b32_e32 v193, 0xffff0000, v186
	v_lshlrev_b32_e32 v182, 16, v183
	v_and_b32_e32 v183, 0xffff0000, v183
	v_lshlrev_b32_e32 v186, 16, v187
	v_and_b32_e32 v187, 0xffff0000, v187
	v_pk_fma_f32 v[128:129], v[128:129], v[182:183], v[186:187]
	v_lshlrev_b32_e32 v182, 16, v184
	v_and_b32_e32 v183, 0xffff0000, v184
	v_lshlrev_b32_e32 v186, 16, v188
	v_and_b32_e32 v187, 0xffff0000, v188
	v_pk_fma_f32 v[182:183], v[122:123], v[182:183], v[186:187]
	v_lshlrev_b32_e32 v122, 16, v185
	v_and_b32_e32 v123, 0xffff0000, v185
	v_lshlrev_b32_e32 v184, 16, v189
	v_and_b32_e32 v185, 0xffff0000, v189
	v_pk_fma_f32 v[126:127], v[126:127], v[190:191], v[192:193]
	v_pk_fma_f32 v[184:185], v[124:125], v[122:123], v[184:185]
	v_cvt_pk_bf16_f32 v122, v126, v127
	v_cvt_pk_bf16_f32 v123, v128, v129
	v_cvt_pk_bf16_f32 v124, v182, v183
	v_cvt_pk_bf16_f32 v125, v184, v185
	s_cbranch_vccz .LBB0_1380
	global_store_dwordx4 v[200:201], v[122:125], off offset:-4096
	s_mov_b64 s[6:7], 0
.LBB0_1380:
	s_andn2_b64 vcc, exec, s[6:7]
	s_cbranch_vccnz .LBB0_1382
	global_store_dwordx4 v[200:201], v[122:125], off offset:-4096 sc1
	s_nop 1
.LBB0_1382:
	s_waitcnt vmcnt(5)
	v_lshlrev_b32_e32 v124, 16, v150
	v_and_b32_e32 v125, 0xffff0000, v150
	s_waitcnt vmcnt(4)
	v_lshlrev_b32_e32 v126, 16, v146
	v_and_b32_e32 v127, 0xffff0000, v146
	v_pk_fma_f32 v[118:119], v[118:119], v[124:125], v[126:127]
	v_lshlrev_b32_e32 v124, 16, v151
	v_and_b32_e32 v125, 0xffff0000, v151
	v_lshlrev_b32_e32 v126, 16, v147
	v_and_b32_e32 v127, 0xffff0000, v147
	v_pk_fma_f32 v[120:121], v[120:121], v[124:125], v[126:127]
	v_lshlrev_b32_e32 v124, 16, v152
	v_and_b32_e32 v125, 0xffff0000, v152
	v_lshlrev_b32_e32 v126, 16, v148
	v_and_b32_e32 v127, 0xffff0000, v148
	v_pk_fma_f32 v[124:125], v[114:115], v[124:125], v[126:127]
	v_lshlrev_b32_e32 v114, 16, v153
	v_and_b32_e32 v115, 0xffff0000, v153
	v_lshlrev_b32_e32 v126, 16, v149
	v_and_b32_e32 v127, 0xffff0000, v149
	s_nop 0
	v_pk_fma_f32 v[126:127], v[116:117], v[114:115], v[126:127]
	v_cvt_pk_bf16_f32 v114, v118, v119
	v_cndmask_b32_e64 v118, 0, 1, s[40:41]
	v_cvt_pk_bf16_f32 v115, v120, v121
	v_cvt_pk_bf16_f32 v116, v124, v125
	v_cvt_pk_bf16_f32 v117, v126, v127
	v_cmp_ne_u32_e64 s[6:7], 1, v118
	s_andn2_b64 vcc, exec, s[40:41]
	s_mov_b64 s[40:41], -1
	s_cbranch_vccnz .LBB0_1384
	s_mov_b64 s[40:41], 0
	global_store_dwordx4 v[164:165], v[114:117], off offset:-4096
.LBB0_1384:
	s_andn2_b64 vcc, exec, s[40:41]
	s_cbranch_vccnz .LBB0_1386
	global_store_dwordx4 v[164:165], v[114:117], off offset:-4096 sc1
	s_nop 1
.LBB0_1386:
	s_waitcnt vmcnt(3)
	v_lshlrev_b32_e32 v116, 16, v142
	v_and_b32_e32 v117, 0xffff0000, v142
	s_waitcnt vmcnt(2)
	v_lshlrev_b32_e32 v118, 16, v138
	v_and_b32_e32 v119, 0xffff0000, v138
	v_pk_fma_f32 v[110:111], v[110:111], v[116:117], v[118:119]
	v_lshlrev_b32_e32 v116, 16, v143
	v_and_b32_e32 v117, 0xffff0000, v143
	v_lshlrev_b32_e32 v118, 16, v139
	v_and_b32_e32 v119, 0xffff0000, v139
	v_pk_fma_f32 v[112:113], v[112:113], v[116:117], v[118:119]
	v_lshlrev_b32_e32 v116, 16, v144
	v_and_b32_e32 v117, 0xffff0000, v144
	v_lshlrev_b32_e32 v118, 16, v140
	v_and_b32_e32 v119, 0xffff0000, v140
	v_pk_fma_f32 v[116:117], v[106:107], v[116:117], v[118:119]
	v_lshlrev_b32_e32 v106, 16, v145
	v_and_b32_e32 v107, 0xffff0000, v145
	v_lshlrev_b32_e32 v118, 16, v141
	v_and_b32_e32 v119, 0xffff0000, v141
	v_pk_fma_f32 v[118:119], v[108:109], v[106:107], v[118:119]
	v_cvt_pk_bf16_f32 v106, v110, v111
	v_cvt_pk_bf16_f32 v107, v112, v113
	v_cvt_pk_bf16_f32 v108, v116, v117
	v_cvt_pk_bf16_f32 v109, v118, v119
	s_and_b64 vcc, exec, s[6:7]
	s_mov_b64 s[40:41], -1
	s_cbranch_vccnz .LBB0_1388
	s_mov_b64 s[40:41], 0
	global_store_dwordx4 v[200:201], v[106:109], off offset:-2048
.LBB0_1388:
	s_andn2_b64 vcc, exec, s[40:41]
	s_cbranch_vccnz .LBB0_1390
	global_store_dwordx4 v[200:201], v[106:109], off offset:-2048 sc1
	s_nop 1
.LBB0_1390:
	s_waitcnt vmcnt(1)
	v_lshlrev_b32_e32 v108, 16, v134
	v_and_b32_e32 v109, 0xffff0000, v134
	s_waitcnt vmcnt(0)
	v_lshlrev_b32_e32 v110, 16, v130
	v_and_b32_e32 v111, 0xffff0000, v130
	v_pk_fma_f32 v[102:103], v[102:103], v[108:109], v[110:111]
	v_lshlrev_b32_e32 v108, 16, v135
	v_and_b32_e32 v109, 0xffff0000, v135
	v_lshlrev_b32_e32 v110, 16, v131
	v_and_b32_e32 v111, 0xffff0000, v131
	v_pk_fma_f32 v[104:105], v[104:105], v[108:109], v[110:111]
	v_lshlrev_b32_e32 v108, 16, v136
	v_and_b32_e32 v109, 0xffff0000, v136
	v_lshlrev_b32_e32 v110, 16, v132
	v_and_b32_e32 v111, 0xffff0000, v132
	v_pk_fma_f32 v[108:109], v[98:99], v[108:109], v[110:111]
	v_lshlrev_b32_e32 v98, 16, v137
	v_and_b32_e32 v99, 0xffff0000, v137
	v_lshlrev_b32_e32 v110, 16, v133
	v_and_b32_e32 v111, 0xffff0000, v133
	v_pk_fma_f32 v[110:111], v[100:101], v[98:99], v[110:111]
	v_cvt_pk_bf16_f32 v98, v102, v103
	v_cvt_pk_bf16_f32 v99, v104, v105
	v_cvt_pk_bf16_f32 v100, v108, v109
	v_cvt_pk_bf16_f32 v101, v110, v111
	s_and_b64 vcc, exec, s[6:7]
	s_mov_b64 s[40:41], -1
	s_cbranch_vccnz .LBB0_1392
	s_mov_b64 s[40:41], 0
	global_store_dwordx4 v[164:165], v[98:101], off offset:-2048
.LBB0_1392:
	s_andn2_b64 vcc, exec, s[40:41]
	s_cbranch_vccnz .LBB0_1394
	global_store_dwordx4 v[164:165], v[98:101], off offset:-2048 sc1
	s_nop 1
.LBB0_1394:
	v_add_u32_e32 v100, 32, v177
	s_nop 0
	v_lshrrev_b32_e32 v99, 3, v100
	v_lshlrev_b32_e32 v101, 6, v100
	v_lshlrev_b32_e32 v102, 2, v100
	v_lshlrev_b32_e32 v98, 7, v100
	v_and_or_b32 v99, v99, 14, v176
	v_and_b32_e32 v101, 0x3c0, v101
	v_and_b32_e32 v102, 32, v102
	v_ashrrev_i32_e32 v100, 4, v100
	v_and_b32_e32 v98, 0x4000, v98
	v_lshlrev_b32_e32 v99, 10, v99
	v_bitop3_b32 v101, v101, v102, v175 bitop3:0x36
	v_and_b32_e32 v107, -16, v100
	v_or3_b32 v154, v99, v98, v101
	v_add_u32_e32 v104, v107, v178
	v_ashrrev_i32_e32 v105, 31, v104
	v_lshlrev_b64 v[130:131], 15, v[104:105]
	global_load_dwordx4 v[132:135], v[198:199], off
	global_load_dwordx4 v[136:139], v[200:201], off
	global_load_dwordx4 v[118:121], v[162:163], off
	global_load_dwordx4 v[114:117], v[164:165], off
	global_load_dwordx4 v[110:113], v[198:199], off offset:2048
	global_load_dwordx4 v[106:109], v[200:201], off offset:2048
	global_load_dwordx4 v[102:105], v[162:163], off offset:2048
	s_nop 0
	global_load_dwordx4 v[98:101], v[164:165], off offset:2048
	v_lshl_add_u64 v[130:131], s[10:11], 0, v[130:131]
	v_lshl_add_u64 v[130:131], v[130:131], 0, v[154:155]
	s_and_b64 vcc, exec, s[6:7]
	s_mov_b64 s[40:41], -1
	s_waitcnt vmcnt(7)
	v_lshlrev_b32_e32 v140, 16, v132
	v_and_b32_e32 v141, 0xffff0000, v132
	s_waitcnt vmcnt(6)
	v_lshlrev_b32_e32 v142, 16, v136
	v_and_b32_e32 v143, 0xffff0000, v136
	v_lshlrev_b32_e32 v132, 16, v133
	v_and_b32_e32 v133, 0xffff0000, v133
	v_lshlrev_b32_e32 v136, 16, v137
	v_and_b32_e32 v137, 0xffff0000, v137
	v_pk_fma_f32 v[96:97], v[96:97], v[132:133], v[136:137]
	v_lshlrev_b32_e32 v132, 16, v134
	v_and_b32_e32 v133, 0xffff0000, v134
	v_lshlrev_b32_e32 v136, 16, v138
	v_and_b32_e32 v137, 0xffff0000, v138
	v_pk_fma_f32 v[132:133], v[90:91], v[132:133], v[136:137]
	v_lshlrev_b32_e32 v90, 16, v135
	v_and_b32_e32 v91, 0xffff0000, v135
	v_lshlrev_b32_e32 v134, 16, v139
	v_and_b32_e32 v135, 0xffff0000, v139
	v_pk_fma_f32 v[94:95], v[94:95], v[140:141], v[142:143]
	v_pk_fma_f32 v[134:135], v[92:93], v[90:91], v[134:135]
	v_cvt_pk_bf16_f32 v90, v94, v95
	v_cvt_pk_bf16_f32 v91, v96, v97
	v_cvt_pk_bf16_f32 v92, v132, v133
	v_cvt_pk_bf16_f32 v93, v134, v135
	s_cbranch_vccnz .LBB0_1396
	s_mov_b64 s[40:41], 0
	global_store_dwordx4 v[200:201], v[90:93], off
.LBB0_1396:
	s_andn2_b64 vcc, exec, s[40:41]
	s_cbranch_vccnz .LBB0_1398
	global_store_dwordx4 v[200:201], v[90:93], off sc1
	s_nop 1
.LBB0_1398:
	s_waitcnt vmcnt(5)
	v_lshlrev_b32_e32 v92, 16, v118
	v_and_b32_e32 v93, 0xffff0000, v118
	s_waitcnt vmcnt(4)
	v_lshlrev_b32_e32 v94, 16, v114
	v_and_b32_e32 v95, 0xffff0000, v114
	v_pk_fma_f32 v[86:87], v[86:87], v[92:93], v[94:95]
	v_lshlrev_b32_e32 v92, 16, v119
	v_and_b32_e32 v93, 0xffff0000, v119
	v_lshlrev_b32_e32 v94, 16, v115
	v_and_b32_e32 v95, 0xffff0000, v115
	v_pk_fma_f32 v[88:89], v[88:89], v[92:93], v[94:95]
	v_lshlrev_b32_e32 v92, 16, v120
	v_and_b32_e32 v93, 0xffff0000, v120
	v_lshlrev_b32_e32 v94, 16, v116
	v_and_b32_e32 v95, 0xffff0000, v116
	v_pk_fma_f32 v[92:93], v[82:83], v[92:93], v[94:95]
	v_lshlrev_b32_e32 v82, 16, v121
	v_and_b32_e32 v83, 0xffff0000, v121
	v_lshlrev_b32_e32 v94, 16, v117
	v_and_b32_e32 v95, 0xffff0000, v117
	v_pk_fma_f32 v[94:95], v[84:85], v[82:83], v[94:95]
	v_cvt_pk_bf16_f32 v82, v86, v87
	v_cvt_pk_bf16_f32 v83, v88, v89
	v_cvt_pk_bf16_f32 v84, v92, v93
	v_cvt_pk_bf16_f32 v85, v94, v95
	s_and_b64 vcc, exec, s[6:7]
	s_mov_b64 s[40:41], -1
	s_cbranch_vccnz .LBB0_1400
	s_mov_b64 s[40:41], 0
	global_store_dwordx4 v[164:165], v[82:85], off
.LBB0_1400:
	s_andn2_b64 vcc, exec, s[40:41]
	s_cbranch_vccnz .LBB0_1402
	global_store_dwordx4 v[164:165], v[82:85], off sc1
	s_nop 1
.LBB0_1402:
	s_waitcnt vmcnt(3)
	v_lshlrev_b32_e32 v84, 16, v110
	v_and_b32_e32 v85, 0xffff0000, v110
	s_waitcnt vmcnt(2)
	v_lshlrev_b32_e32 v86, 16, v106
	v_and_b32_e32 v87, 0xffff0000, v106
	v_pk_fma_f32 v[78:79], v[78:79], v[84:85], v[86:87]
	v_lshlrev_b32_e32 v84, 16, v111
	v_and_b32_e32 v85, 0xffff0000, v111
	v_lshlrev_b32_e32 v86, 16, v107
	v_and_b32_e32 v87, 0xffff0000, v107
	v_pk_fma_f32 v[80:81], v[80:81], v[84:85], v[86:87]
	v_lshlrev_b32_e32 v84, 16, v112
	v_and_b32_e32 v85, 0xffff0000, v112
	v_lshlrev_b32_e32 v86, 16, v108
	v_and_b32_e32 v87, 0xffff0000, v108
	v_pk_fma_f32 v[84:85], v[74:75], v[84:85], v[86:87]
	v_lshlrev_b32_e32 v74, 16, v113
	v_and_b32_e32 v75, 0xffff0000, v113
	v_lshlrev_b32_e32 v86, 16, v109
	v_and_b32_e32 v87, 0xffff0000, v109
	v_pk_fma_f32 v[86:87], v[76:77], v[74:75], v[86:87]
	v_cvt_pk_bf16_f32 v74, v78, v79
	v_cvt_pk_bf16_f32 v75, v80, v81
	v_cvt_pk_bf16_f32 v76, v84, v85
	v_cvt_pk_bf16_f32 v77, v86, v87
	s_and_b64 vcc, exec, s[6:7]
	s_mov_b64 s[40:41], -1
	s_cbranch_vccnz .LBB0_1404
	s_mov_b64 s[40:41], 0
	global_store_dwordx4 v[200:201], v[74:77], off offset:2048
.LBB0_1404:
	s_andn2_b64 vcc, exec, s[40:41]
	s_cbranch_vccnz .LBB0_1406
	global_store_dwordx4 v[200:201], v[74:77], off offset:2048 sc1
	s_nop 1
.LBB0_1406:
	s_waitcnt vmcnt(1)
	v_lshlrev_b32_e32 v76, 16, v102
	v_and_b32_e32 v77, 0xffff0000, v102
	s_waitcnt vmcnt(0)
	v_lshlrev_b32_e32 v78, 16, v98
	v_and_b32_e32 v79, 0xffff0000, v98
	v_pk_fma_f32 v[70:71], v[70:71], v[76:77], v[78:79]
	v_lshlrev_b32_e32 v76, 16, v103
	v_and_b32_e32 v77, 0xffff0000, v103
	v_lshlrev_b32_e32 v78, 16, v99
	v_and_b32_e32 v79, 0xffff0000, v99
	v_pk_fma_f32 v[72:73], v[72:73], v[76:77], v[78:79]
	v_lshlrev_b32_e32 v76, 16, v104
	v_and_b32_e32 v77, 0xffff0000, v104
	v_lshlrev_b32_e32 v78, 16, v100
	v_and_b32_e32 v79, 0xffff0000, v100
	v_pk_fma_f32 v[76:77], v[66:67], v[76:77], v[78:79]
	v_lshlrev_b32_e32 v66, 16, v105
	v_and_b32_e32 v67, 0xffff0000, v105
	v_lshlrev_b32_e32 v78, 16, v101
	v_and_b32_e32 v79, 0xffff0000, v101
	v_pk_fma_f32 v[78:79], v[68:69], v[66:67], v[78:79]
	v_cvt_pk_bf16_f32 v66, v70, v71
	v_cvt_pk_bf16_f32 v67, v72, v73
	v_cvt_pk_bf16_f32 v68, v76, v77
	v_cvt_pk_bf16_f32 v69, v78, v79
	s_and_b64 vcc, exec, s[6:7]
	s_mov_b64 s[40:41], -1
	s_cbranch_vccnz .LBB0_1408
	s_mov_b64 s[40:41], 0
	global_store_dwordx4 v[164:165], v[66:69], off offset:2048
.LBB0_1408:
	s_andn2_b64 vcc, exec, s[40:41]
	s_cbranch_vccnz .LBB0_1410
	global_store_dwordx4 v[164:165], v[66:69], off offset:2048 sc1
	s_nop 1
.LBB0_1410:
	s_nop 0
	s_nop 0
	s_nop 0
	s_nop 0
	s_mov_b32 s98, 0x5000
	s_mov_b32 s99, 0x0
	v_lshl_add_u64 v[162:163], v[158:159], 0, s[98:99]
	global_load_dwordx4 v[100:103], v[162:163], off offset:-4096
	s_mov_b32 s98, 0x5000
	s_mov_b32 s99, 0x0
	v_lshl_add_u64 v[164:165], v[160:161], 0, s[98:99]
	global_load_dwordx4 v[104:107], v[164:165], off offset:-4096
	s_mov_b32 s98, 0x15000
	s_mov_b32 s99, 0x0
	v_lshl_add_u64 v[198:199], v[158:159], 0, s[98:99]
	global_load_dwordx4 v[86:89], v[198:199], off offset:-4096
	s_mov_b32 s98, 0x15000
	s_mov_b32 s99, 0x0
	v_lshl_add_u64 v[158:159], v[160:161], 0, s[98:99]
	global_load_dwordx4 v[82:85], v[158:159], off offset:-4096
	global_load_dwordx4 v[78:81], v[162:163], off offset:-2048
	global_load_dwordx4 v[74:77], v[164:165], off offset:-2048
	global_load_dwordx4 v[70:73], v[198:199], off offset:-2048
	s_nop 0
	global_load_dwordx4 v[66:69], v[158:159], off offset:-2048
	s_and_b64 vcc, exec, s[6:7]
	s_mov_b64 s[40:41], -1
	s_waitcnt vmcnt(7)
	v_lshlrev_b32_e32 v108, 16, v100
	v_and_b32_e32 v109, 0xffff0000, v100
	s_waitcnt vmcnt(6)
	v_lshlrev_b32_e32 v110, 16, v104
	v_and_b32_e32 v111, 0xffff0000, v104
	v_lshlrev_b32_e32 v100, 16, v101
	v_and_b32_e32 v101, 0xffff0000, v101
	v_lshlrev_b32_e32 v104, 16, v105
	v_and_b32_e32 v105, 0xffff0000, v105
	v_lshlrev_b32_e32 v112, 16, v102
	v_and_b32_e32 v113, 0xffff0000, v102
	v_pk_fma_f32 v[64:65], v[64:65], v[100:101], v[104:105]
	v_lshlrev_b32_e32 v100, 16, v106
	v_and_b32_e32 v101, 0xffff0000, v106
	v_pk_fma_f32 v[100:101], v[58:59], v[112:113], v[100:101]
	v_lshlrev_b32_e32 v58, 16, v103
	v_and_b32_e32 v59, 0xffff0000, v103
	v_lshlrev_b32_e32 v102, 16, v107
	v_and_b32_e32 v103, 0xffff0000, v107
	v_pk_fma_f32 v[62:63], v[62:63], v[108:109], v[110:111]
	v_pk_fma_f32 v[102:103], v[60:61], v[58:59], v[102:103]
	v_cvt_pk_bf16_f32 v58, v62, v63
	v_cvt_pk_bf16_f32 v59, v64, v65
	v_cvt_pk_bf16_f32 v60, v100, v101
	v_cvt_pk_bf16_f32 v61, v102, v103
	s_cbranch_vccnz .LBB0_1412
	s_mov_b64 s[40:41], 0
	global_store_dwordx4 v[164:165], v[58:61], off offset:-4096
.LBB0_1412:
	s_andn2_b64 vcc, exec, s[40:41]
	s_cbranch_vccnz .LBB0_1414
	global_store_dwordx4 v[164:165], v[58:61], off offset:-4096 sc1
	s_nop 1
.LBB0_1414:
	s_waitcnt vmcnt(5)
	v_lshlrev_b32_e32 v60, 16, v86
	v_and_b32_e32 v61, 0xffff0000, v86
	s_waitcnt vmcnt(4)
	v_lshlrev_b32_e32 v62, 16, v82
	v_and_b32_e32 v63, 0xffff0000, v82
	v_pk_fma_f32 v[54:55], v[54:55], v[60:61], v[62:63]
	v_lshlrev_b32_e32 v60, 16, v87
	v_and_b32_e32 v61, 0xffff0000, v87
	v_lshlrev_b32_e32 v62, 16, v83
	v_and_b32_e32 v63, 0xffff0000, v83
	v_pk_fma_f32 v[56:57], v[56:57], v[60:61], v[62:63]
	v_lshlrev_b32_e32 v60, 16, v88
	v_and_b32_e32 v61, 0xffff0000, v88
	v_lshlrev_b32_e32 v62, 16, v84
	v_and_b32_e32 v63, 0xffff0000, v84
	v_pk_fma_f32 v[60:61], v[50:51], v[60:61], v[62:63]
	v_lshlrev_b32_e32 v50, 16, v89
	v_and_b32_e32 v51, 0xffff0000, v89
	v_lshlrev_b32_e32 v62, 16, v85
	v_and_b32_e32 v63, 0xffff0000, v85
	v_pk_fma_f32 v[62:63], v[52:53], v[50:51], v[62:63]
	v_cvt_pk_bf16_f32 v50, v54, v55
	v_cvt_pk_bf16_f32 v51, v56, v57
	v_cvt_pk_bf16_f32 v52, v60, v61
	v_cvt_pk_bf16_f32 v53, v62, v63
	s_and_b64 vcc, exec, s[6:7]
	s_mov_b64 s[40:41], -1
	s_cbranch_vccnz .LBB0_1416
	s_mov_b64 s[40:41], 0
	global_store_dwordx4 v[158:159], v[50:53], off offset:-4096
.LBB0_1416:
	s_andn2_b64 vcc, exec, s[40:41]
	s_cbranch_vccnz .LBB0_1418
	global_store_dwordx4 v[158:159], v[50:53], off offset:-4096 sc1
	s_nop 1
.LBB0_1418:
	s_waitcnt vmcnt(3)
	v_lshlrev_b32_e32 v52, 16, v78
	v_and_b32_e32 v53, 0xffff0000, v78
	s_waitcnt vmcnt(2)
	v_lshlrev_b32_e32 v54, 16, v74
	v_and_b32_e32 v55, 0xffff0000, v74
	v_pk_fma_f32 v[46:47], v[46:47], v[52:53], v[54:55]
	v_lshlrev_b32_e32 v52, 16, v79
	v_and_b32_e32 v53, 0xffff0000, v79
	v_lshlrev_b32_e32 v54, 16, v75
	v_and_b32_e32 v55, 0xffff0000, v75
	v_pk_fma_f32 v[48:49], v[48:49], v[52:53], v[54:55]
	v_lshlrev_b32_e32 v52, 16, v80
	v_and_b32_e32 v53, 0xffff0000, v80
	v_lshlrev_b32_e32 v54, 16, v76
	v_and_b32_e32 v55, 0xffff0000, v76
	v_pk_fma_f32 v[52:53], v[42:43], v[52:53], v[54:55]
	v_lshlrev_b32_e32 v42, 16, v81
	v_and_b32_e32 v43, 0xffff0000, v81
	v_lshlrev_b32_e32 v54, 16, v77
	v_and_b32_e32 v55, 0xffff0000, v77
	v_pk_fma_f32 v[54:55], v[44:45], v[42:43], v[54:55]
	v_cvt_pk_bf16_f32 v42, v46, v47
	v_cvt_pk_bf16_f32 v43, v48, v49
	v_cvt_pk_bf16_f32 v44, v52, v53
	v_cvt_pk_bf16_f32 v45, v54, v55
	s_and_b64 vcc, exec, s[6:7]
	s_mov_b64 s[40:41], -1
	s_cbranch_vccnz .LBB0_1420
	s_mov_b64 s[40:41], 0
	global_store_dwordx4 v[164:165], v[42:45], off offset:-2048
.LBB0_1420:
	s_andn2_b64 vcc, exec, s[40:41]
	s_cbranch_vccnz .LBB0_1422
	global_store_dwordx4 v[164:165], v[42:45], off offset:-2048 sc1
	s_nop 1
.LBB0_1422:
	s_waitcnt vmcnt(1)
	v_lshlrev_b32_e32 v44, 16, v70
	v_and_b32_e32 v45, 0xffff0000, v70
	s_waitcnt vmcnt(0)
	v_lshlrev_b32_e32 v46, 16, v66
	v_and_b32_e32 v47, 0xffff0000, v66
	v_pk_fma_f32 v[38:39], v[38:39], v[44:45], v[46:47]
	v_lshlrev_b32_e32 v44, 16, v71
	v_and_b32_e32 v45, 0xffff0000, v71
	v_lshlrev_b32_e32 v46, 16, v67
	v_and_b32_e32 v47, 0xffff0000, v67
	v_pk_fma_f32 v[40:41], v[40:41], v[44:45], v[46:47]
	v_lshlrev_b32_e32 v44, 16, v72
	v_and_b32_e32 v45, 0xffff0000, v72
	v_lshlrev_b32_e32 v46, 16, v68
	v_and_b32_e32 v47, 0xffff0000, v68
	v_pk_fma_f32 v[44:45], v[34:35], v[44:45], v[46:47]
	v_lshlrev_b32_e32 v34, 16, v73
	v_and_b32_e32 v35, 0xffff0000, v73
	v_lshlrev_b32_e32 v46, 16, v69
	v_and_b32_e32 v47, 0xffff0000, v69
	v_pk_fma_f32 v[46:47], v[36:37], v[34:35], v[46:47]
	v_cvt_pk_bf16_f32 v34, v38, v39
	v_cvt_pk_bf16_f32 v35, v40, v41
	v_cvt_pk_bf16_f32 v36, v44, v45
	v_cvt_pk_bf16_f32 v37, v46, v47
	s_and_b64 vcc, exec, s[6:7]
	s_mov_b64 s[40:41], -1
	s_cbranch_vccnz .LBB0_1424
	s_mov_b64 s[40:41], 0
	global_store_dwordx4 v[158:159], v[34:37], off offset:-2048
.LBB0_1424:
	s_andn2_b64 vcc, exec, s[40:41]
	s_cbranch_vccnz .LBB0_1426
	global_store_dwordx4 v[158:159], v[34:37], off offset:-2048 sc1
	s_nop 1
.LBB0_1426:
	v_add_u32_e32 v36, 0xa0, v177
	s_nop 0
	v_lshrrev_b32_e32 v35, 3, v36
	v_lshlrev_b32_e32 v37, 6, v36
	v_lshlrev_b32_e32 v38, 2, v36
	v_lshlrev_b32_e32 v34, 7, v36
	v_and_or_b32 v35, v35, 14, v176
	v_and_b32_e32 v37, 0x3c0, v37
	v_and_b32_e32 v38, 32, v38
	v_and_b32_e32 v34, 0x4000, v34
	v_lshlrev_b32_e32 v35, 10, v35
	v_bitop3_b32 v37, v37, v38, v175 bitop3:0x36
	v_or3_b32 v154, v35, v34, v37
	global_load_dwordx4 v[68:71], v[162:163], off
	global_load_dwordx4 v[72:75], v[164:165], off
	global_load_dwordx4 v[54:57], v[198:199], off
	global_load_dwordx4 v[50:53], v[158:159], off
	global_load_dwordx4 v[46:49], v[162:163], off offset:2048
	global_load_dwordx4 v[42:45], v[164:165], off offset:2048
	global_load_dwordx4 v[38:41], v[198:199], off offset:2048
	s_nop 0
	global_load_dwordx4 v[34:37], v[158:159], off offset:2048
	s_and_b64 vcc, exec, s[6:7]
	s_mov_b64 s[40:41], -1
	s_waitcnt vmcnt(7)
	v_lshlrev_b32_e32 v76, 16, v68
	v_and_b32_e32 v77, 0xffff0000, v68
	s_waitcnt vmcnt(6)
	v_lshlrev_b32_e32 v78, 16, v72
	v_and_b32_e32 v79, 0xffff0000, v72
	v_lshlrev_b32_e32 v68, 16, v69
	v_and_b32_e32 v69, 0xffff0000, v69
	v_lshlrev_b32_e32 v72, 16, v73
	v_and_b32_e32 v73, 0xffff0000, v73
	v_pk_fma_f32 v[32:33], v[32:33], v[68:69], v[72:73]
	v_lshlrev_b32_e32 v68, 16, v70
	v_and_b32_e32 v69, 0xffff0000, v70
	v_lshlrev_b32_e32 v72, 16, v74
	v_and_b32_e32 v73, 0xffff0000, v74
	v_pk_fma_f32 v[68:69], v[26:27], v[68:69], v[72:73]
	v_lshlrev_b32_e32 v26, 16, v71
	v_and_b32_e32 v27, 0xffff0000, v71
	v_lshlrev_b32_e32 v70, 16, v75
	v_and_b32_e32 v71, 0xffff0000, v75
	v_pk_fma_f32 v[30:31], v[30:31], v[76:77], v[78:79]
	v_pk_fma_f32 v[70:71], v[28:29], v[26:27], v[70:71]
	v_cvt_pk_bf16_f32 v26, v30, v31
	v_cvt_pk_bf16_f32 v27, v32, v33
	v_cvt_pk_bf16_f32 v28, v68, v69
	v_cvt_pk_bf16_f32 v29, v70, v71
	s_cbranch_vccnz .LBB0_1428
	s_mov_b64 s[40:41], 0
	global_store_dwordx4 v[164:165], v[26:29], off
.LBB0_1428:
	s_andn2_b64 vcc, exec, s[40:41]
	s_cbranch_vccnz .LBB0_1430
	global_store_dwordx4 v[164:165], v[26:29], off sc1
	s_nop 1
.LBB0_1430:
	s_waitcnt vmcnt(5)
	v_lshlrev_b32_e32 v28, 16, v54
	v_and_b32_e32 v29, 0xffff0000, v54
	s_waitcnt vmcnt(4)
	v_lshlrev_b32_e32 v30, 16, v50
	v_and_b32_e32 v31, 0xffff0000, v50
	v_pk_fma_f32 v[22:23], v[22:23], v[28:29], v[30:31]
	v_lshlrev_b32_e32 v28, 16, v55
	v_and_b32_e32 v29, 0xffff0000, v55
	v_lshlrev_b32_e32 v30, 16, v51
	v_and_b32_e32 v31, 0xffff0000, v51
	v_pk_fma_f32 v[24:25], v[24:25], v[28:29], v[30:31]
	v_lshlrev_b32_e32 v28, 16, v56
	v_and_b32_e32 v29, 0xffff0000, v56
	v_lshlrev_b32_e32 v30, 16, v52
	v_and_b32_e32 v31, 0xffff0000, v52
	v_pk_fma_f32 v[28:29], v[18:19], v[28:29], v[30:31]
	v_lshlrev_b32_e32 v18, 16, v57
	v_and_b32_e32 v19, 0xffff0000, v57
	v_lshlrev_b32_e32 v30, 16, v53
	v_and_b32_e32 v31, 0xffff0000, v53
	v_pk_fma_f32 v[30:31], v[20:21], v[18:19], v[30:31]
	v_cvt_pk_bf16_f32 v18, v22, v23
	v_cvt_pk_bf16_f32 v19, v24, v25
	v_cvt_pk_bf16_f32 v20, v28, v29
	v_cvt_pk_bf16_f32 v21, v30, v31
	s_and_b64 vcc, exec, s[6:7]
	s_mov_b64 s[40:41], -1
	s_cbranch_vccnz .LBB0_1432
	s_mov_b64 s[40:41], 0
	global_store_dwordx4 v[158:159], v[18:21], off
.LBB0_1432:
	s_andn2_b64 vcc, exec, s[40:41]
	s_cbranch_vccnz .LBB0_1434
	global_store_dwordx4 v[158:159], v[18:21], off sc1
	s_nop 1
.LBB0_1434:
	s_waitcnt vmcnt(3)
	v_lshlrev_b32_e32 v20, 16, v46
	v_and_b32_e32 v21, 0xffff0000, v46
	s_waitcnt vmcnt(2)
	v_lshlrev_b32_e32 v22, 16, v42
	v_and_b32_e32 v23, 0xffff0000, v42
	v_pk_fma_f32 v[14:15], v[14:15], v[20:21], v[22:23]
	v_lshlrev_b32_e32 v20, 16, v47
	v_and_b32_e32 v21, 0xffff0000, v47
	v_lshlrev_b32_e32 v22, 16, v43
	v_and_b32_e32 v23, 0xffff0000, v43
	v_pk_fma_f32 v[16:17], v[16:17], v[20:21], v[22:23]
	v_lshlrev_b32_e32 v20, 16, v48
	v_and_b32_e32 v21, 0xffff0000, v48
	v_lshlrev_b32_e32 v22, 16, v44
	v_and_b32_e32 v23, 0xffff0000, v44
	v_pk_fma_f32 v[20:21], v[10:11], v[20:21], v[22:23]
	v_lshlrev_b32_e32 v10, 16, v49
	v_and_b32_e32 v11, 0xffff0000, v49
	v_lshlrev_b32_e32 v22, 16, v45
	v_and_b32_e32 v23, 0xffff0000, v45
	v_pk_fma_f32 v[22:23], v[12:13], v[10:11], v[22:23]
	v_cvt_pk_bf16_f32 v10, v14, v15
	v_cvt_pk_bf16_f32 v11, v16, v17
	v_cvt_pk_bf16_f32 v12, v20, v21
	v_cvt_pk_bf16_f32 v13, v22, v23
	s_and_b64 vcc, exec, s[6:7]
	s_mov_b64 s[40:41], -1
	s_cbranch_vccnz .LBB0_1436
	s_mov_b64 s[40:41], 0
	global_store_dwordx4 v[164:165], v[10:13], off offset:2048
.LBB0_1436:
	s_andn2_b64 vcc, exec, s[40:41]
	s_cbranch_vccnz .LBB0_1438
	global_store_dwordx4 v[164:165], v[10:13], off offset:2048 sc1
	s_nop 1
.LBB0_1438:
	s_waitcnt vmcnt(1)
	v_lshlrev_b32_e32 v12, 16, v38
	v_and_b32_e32 v13, 0xffff0000, v38
	s_waitcnt vmcnt(0)
	v_lshlrev_b32_e32 v14, 16, v34
	v_and_b32_e32 v15, 0xffff0000, v34
	v_pk_fma_f32 v[6:7], v[6:7], v[12:13], v[14:15]
	v_lshlrev_b32_e32 v12, 16, v39
	v_and_b32_e32 v13, 0xffff0000, v39
	v_lshlrev_b32_e32 v14, 16, v35
	v_and_b32_e32 v15, 0xffff0000, v35
	v_pk_fma_f32 v[8:9], v[8:9], v[12:13], v[14:15]
	v_lshlrev_b32_e32 v12, 16, v40
	v_and_b32_e32 v13, 0xffff0000, v40
	v_lshlrev_b32_e32 v14, 16, v36
	v_and_b32_e32 v15, 0xffff0000, v36
	v_pk_fma_f32 v[12:13], v[2:3], v[12:13], v[14:15]
	v_lshlrev_b32_e32 v2, 16, v41
	v_and_b32_e32 v3, 0xffff0000, v41
	v_lshlrev_b32_e32 v14, 16, v37
	v_and_b32_e32 v15, 0xffff0000, v37
	v_pk_fma_f32 v[14:15], v[4:5], v[2:3], v[14:15]
	v_cvt_pk_bf16_f32 v2, v6, v7
	v_cvt_pk_bf16_f32 v3, v8, v9
	v_cvt_pk_bf16_f32 v4, v12, v13
	v_cvt_pk_bf16_f32 v5, v14, v15
	s_and_b64 vcc, exec, s[6:7]
	s_mov_b64 s[6:7], -1
	s_cbranch_vccnz .LBB0_1440
	s_mov_b64 s[6:7], 0
	global_store_dwordx4 v[158:159], v[2:5], off offset:2048
.LBB0_1440:
	s_andn2_b64 vcc, exec, s[6:7]
	s_cbranch_vccnz .LBB0_1442
	global_store_dwordx4 v[158:159], v[2:5], off offset:2048 sc1
	s_nop 1

.LBB0_1519:
	s_add_i32 s26, s58, 2
	s_lshl_b64 s[54:55], s[26:27], 15
	s_add_u32 s17, s18, s54
	s_addc_u32 s59, s19, s55
	s_and_b64 s[50:51], s[12:13], exec
	s_cselect_b32 s51, s59, s41
	s_cselect_b32 s50, s17, s56
	s_add_u32 s17, s20, s54
	s_waitcnt vmcnt(8)
	s_addc_u32 s54, s21, s55
	s_waitcnt lgkmcnt(0)
	s_and_b64 s[12:13], s[12:13], exec
	s_cselect_b32 s13, s54, s39
	s_cselect_b32 s12, s17, s57
	s_barrier
	s_setprio 1
	s_waitcnt lgkmcnt(7)
	v_mfma_f32_16x16x32_bf16 v[126:129], v[146:149], v[186:189], v[126:129]
	v_mfma_f32_16x16x32_bf16 v[122:125], v[154:157], v[186:189], v[122:125]
	s_waitcnt lgkmcnt(5)
	v_mfma_f32_16x16x32_bf16 v[118:121], v[146:149], v[178:181], v[118:121]
	v_mfma_f32_16x16x32_bf16 v[114:117], v[154:157], v[178:181], v[114:117]
	s_waitcnt lgkmcnt(3)
	v_mfma_f32_16x16x32_bf16 v[110:113], v[146:149], v[170:173], v[110:113]
	v_mfma_f32_16x16x32_bf16 v[106:109], v[154:157], v[170:173], v[106:109]
	s_waitcnt lgkmcnt(1)
	v_mfma_f32_16x16x32_bf16 v[102:105], v[146:149], v[162:165], v[102:105]
	v_mfma_f32_16x16x32_bf16 v[98:101], v[154:157], v[162:165], v[98:101]
	v_mfma_f32_16x16x32_bf16 v[126:129], v[150:153], v[190:193], v[126:129]
	v_mfma_f32_16x16x32_bf16 v[122:125], v[158:161], v[190:193], v[122:125]
	v_mfma_f32_16x16x32_bf16 v[118:121], v[150:153], v[182:185], v[118:121]
	v_mfma_f32_16x16x32_bf16 v[114:117], v[158:161], v[182:185], v[114:117]
	v_mfma_f32_16x16x32_bf16 v[110:113], v[150:153], v[174:177], v[110:113]
	v_mfma_f32_16x16x32_bf16 v[106:109], v[158:161], v[174:177], v[106:109]
	s_waitcnt lgkmcnt(0)
	v_mfma_f32_16x16x32_bf16 v[102:105], v[150:153], v[166:169], v[102:105]
	v_mfma_f32_16x16x32_bf16 v[98:101], v[158:161], v[166:169], v[98:101]
	s_setprio 0
	s_setprio 1
	v_mfma_f32_16x16x32_bf16 v[94:97], v[130:133], v[186:189], v[94:97]
	v_mfma_f32_16x16x32_bf16 v[90:93], v[138:141], v[186:189], v[90:93]
	v_mfma_f32_16x16x32_bf16 v[86:89], v[130:133], v[178:181], v[86:89]
	v_mfma_f32_16x16x32_bf16 v[82:85], v[138:141], v[178:181], v[82:85]
	v_mfma_f32_16x16x32_bf16 v[78:81], v[130:133], v[170:173], v[78:81]
	v_mfma_f32_16x16x32_bf16 v[74:77], v[138:141], v[170:173], v[74:77]
	v_mfma_f32_16x16x32_bf16 v[70:73], v[130:133], v[162:165], v[70:73]
	v_mfma_f32_16x16x32_bf16 v[66:69], v[138:141], v[162:165], v[66:69]
	v_mfma_f32_16x16x32_bf16 v[94:97], v[134:137], v[190:193], v[94:97]
	v_mfma_f32_16x16x32_bf16 v[90:93], v[142:145], v[190:193], v[90:93]
	v_mfma_f32_16x16x32_bf16 v[86:89], v[134:137], v[182:185], v[86:89]
	v_mfma_f32_16x16x32_bf16 v[82:85], v[142:145], v[182:185], v[82:85]
	v_mfma_f32_16x16x32_bf16 v[78:81], v[134:137], v[174:177], v[78:81]
	v_mfma_f32_16x16x32_bf16 v[74:77], v[142:145], v[174:177], v[74:77]
	v_mfma_f32_16x16x32_bf16 v[70:73], v[134:137], v[166:169], v[70:73]
	v_mfma_f32_16x16x32_bf16 v[66:69], v[142:145], v[166:169], v[66:69]
	s_setprio 0
	s_barrier
	ds_read_b128 v[186:189], v217 offset:16384
	ds_read_b128 v[190:193], v217 offset:17408
	ds_read_b128 v[178:181], v217 offset:18432
	ds_read_b128 v[182:185], v217 offset:19456
	ds_read_b128 v[170:173], v217 offset:20480
	ds_read_b128 v[174:177], v217 offset:21504
	ds_read_b128 v[162:165], v217 offset:22528
	ds_read_b128 v[166:169], v217 offset:23552
	s_mov_b32 m0, s66
	s_nop 0
	global_load_lds_dwordx4 v195, s[12:13]
	s_add_u32 m0, s66, 0x2000
	s_nop 0
	global_load_lds_dwordx4 v212, s[12:13]
	s_add_u32 s54, s12, 0x4000
	s_addc_u32 s55, s13, 0
	s_mov_b32 m0, s67
	s_nop 0
	global_load_lds_dwordx4 v195, s[54:55]
	s_add_u32 m0, s67, 0x2000
	s_nop 0
	global_load_lds_dwordx4 v212, s[54:55]
	s_andn2_b64 vcc, exec, s[52:53]
	s_mov_b32 m0, s15
	s_nop 0
	global_load_lds_dwordx4 v195, s[50:51]
	s_add_u32 m0, s15, 0x2000
	s_nop 0
	global_load_lds_dwordx4 v212, s[50:51]
	s_cbranch_vccnz .LBB0_1521
	v_mov_b32_e32 v2, 0
	v_mov_b32_e32 v3, v2
	v_mov_b32_e32 v4, v2
	v_mov_b32_e32 v5, v2
	v_mov_b32_e32 v6, v2
	v_mov_b32_e32 v7, v2
	v_mov_b32_e32 v8, v2
	v_mov_b32_e32 v9, v2
	v_mov_b32_e32 v10, v2
	v_mov_b32_e32 v11, v2
	v_mov_b32_e32 v12, v2
	v_mov_b32_e32 v13, v2
	v_mov_b32_e32 v14, v2
	v_mov_b32_e32 v15, v2
	v_mov_b32_e32 v16, v2
	v_mov_b32_e32 v17, v2
	v_mov_b32_e32 v18, v2
	v_mov_b32_e32 v19, v2
	v_mov_b32_e32 v20, v2
	v_mov_b32_e32 v21, v2
	v_mov_b32_e32 v22, v2
	v_mov_b32_e32 v23, v2
	v_mov_b32_e32 v24, v2
	v_mov_b32_e32 v25, v2
	v_mov_b32_e32 v26, v2
	v_mov_b32_e32 v27, v2
	v_mov_b32_e32 v28, v2
	v_mov_b32_e32 v29, v2
	v_mov_b32_e32 v30, v2
	v_mov_b32_e32 v31, v2
	v_mov_b32_e32 v32, v2
	v_mov_b32_e32 v33, v2
	v_mov_b32_e32 v34, v2
	v_mov_b32_e32 v35, v2
	v_mov_b32_e32 v36, v2
	v_mov_b32_e32 v37, v2
	v_mov_b32_e32 v38, v2
	v_mov_b32_e32 v39, v2
	v_mov_b32_e32 v40, v2
	v_mov_b32_e32 v41, v2
	v_mov_b32_e32 v42, v2
	v_mov_b32_e32 v43, v2
	v_mov_b32_e32 v44, v2
	v_mov_b32_e32 v45, v2
	v_mov_b32_e32 v46, v2
	v_mov_b32_e32 v47, v2
	v_mov_b32_e32 v48, v2
	v_mov_b32_e32 v49, v2
	v_mov_b32_e32 v50, v2
	v_mov_b32_e32 v51, v2
	v_mov_b32_e32 v52, v2
	v_mov_b32_e32 v53, v2
	v_mov_b32_e32 v54, v2
	v_mov_b32_e32 v55, v2
	v_mov_b32_e32 v56, v2
	v_mov_b32_e32 v57, v2
	v_mov_b32_e32 v58, v2
	v_mov_b32_e32 v59, v2
	v_mov_b32_e32 v60, v2
	v_mov_b32_e32 v61, v2
	v_mov_b32_e32 v62, v2
	v_mov_b32_e32 v63, v2
	v_mov_b32_e32 v64, v2
	v_mov_b32_e32 v65, v2
.LBB0_1521:
	s_waitcnt vmcnt(8)
	s_add_u32 s52, s50, 0x8000
	s_waitcnt lgkmcnt(0)
	s_addc_u32 s53, s51, 0
	s_add_u32 s54, s12, 0x8000
	s_addc_u32 s55, s13, 0
	s_barrier
	s_setprio 1
	s_waitcnt lgkmcnt(7)
	v_mfma_f32_16x16x32_bf16 v[62:65], v[146:149], v[186:189], v[62:65]
	v_mfma_f32_16x16x32_bf16 v[58:61], v[154:157], v[186:189], v[58:61]
	s_waitcnt lgkmcnt(5)
	v_mfma_f32_16x16x32_bf16 v[54:57], v[146:149], v[178:181], v[54:57]
	v_mfma_f32_16x16x32_bf16 v[50:53], v[154:157], v[178:181], v[50:53]
	s_waitcnt lgkmcnt(3)
	v_mfma_f32_16x16x32_bf16 v[46:49], v[146:149], v[170:173], v[46:49]
	v_mfma_f32_16x16x32_bf16 v[42:45], v[154:157], v[170:173], v[42:45]
	s_waitcnt lgkmcnt(1)
	v_mfma_f32_16x16x32_bf16 v[38:41], v[146:149], v[162:165], v[38:41]
	v_mfma_f32_16x16x32_bf16 v[34:37], v[154:157], v[162:165], v[34:37]
	v_mfma_f32_16x16x32_bf16 v[62:65], v[150:153], v[190:193], v[62:65]
	v_mfma_f32_16x16x32_bf16 v[58:61], v[158:161], v[190:193], v[58:61]
	v_mfma_f32_16x16x32_bf16 v[54:57], v[150:153], v[182:185], v[54:57]
	v_mfma_f32_16x16x32_bf16 v[50:53], v[158:161], v[182:185], v[50:53]
	v_mfma_f32_16x16x32_bf16 v[46:49], v[150:153], v[174:177], v[46:49]
	v_mfma_f32_16x16x32_bf16 v[42:45], v[158:161], v[174:177], v[42:45]
	s_waitcnt lgkmcnt(0)
	v_mfma_f32_16x16x32_bf16 v[38:41], v[150:153], v[166:169], v[38:41]
	v_mfma_f32_16x16x32_bf16 v[34:37], v[158:161], v[166:169], v[34:37]
	s_setprio 0
	s_setprio 1
	v_mfma_f32_16x16x32_bf16 v[30:33], v[130:133], v[186:189], v[30:33]
	v_mfma_f32_16x16x32_bf16 v[26:29], v[138:141], v[186:189], v[26:29]
	v_mfma_f32_16x16x32_bf16 v[22:25], v[130:133], v[178:181], v[22:25]
	v_mfma_f32_16x16x32_bf16 v[18:21], v[138:141], v[178:181], v[18:21]
	v_mfma_f32_16x16x32_bf16 v[14:17], v[130:133], v[170:173], v[14:17]
	v_mfma_f32_16x16x32_bf16 v[10:13], v[138:141], v[170:173], v[10:13]
	v_mfma_f32_16x16x32_bf16 v[6:9], v[130:133], v[162:165], v[6:9]
	v_mfma_f32_16x16x32_bf16 v[2:5], v[138:141], v[162:165], v[2:5]
	v_mfma_f32_16x16x32_bf16 v[30:33], v[134:137], v[190:193], v[30:33]
	v_mfma_f32_16x16x32_bf16 v[26:29], v[142:145], v[190:193], v[26:29]
	v_mfma_f32_16x16x32_bf16 v[22:25], v[134:137], v[182:185], v[22:25]
	v_mfma_f32_16x16x32_bf16 v[18:21], v[142:145], v[182:185], v[18:21]
	v_mfma_f32_16x16x32_bf16 v[14:17], v[134:137], v[174:177], v[14:17]
	v_mfma_f32_16x16x32_bf16 v[10:13], v[142:145], v[174:177], v[10:13]
	v_mfma_f32_16x16x32_bf16 v[6:9], v[134:137], v[166:169], v[6:9]
	v_mfma_f32_16x16x32_bf16 v[2:5], v[142:145], v[166:169], v[2:5]
	s_setprio 0
	s_barrier
	v_add_u32_e32 v142, 0x18000, v216
	v_add_u32_e32 v158, 0x1c000, v216
	ds_read_b128 v[130:133], v142
	ds_read_b128 v[134:137], v142 offset:1024
	ds_read_b128 v[138:141], v142 offset:2048
	ds_read_b128 v[142:145], v142 offset:3072
	ds_read_b128 v[146:149], v158
	ds_read_b128 v[150:153], v158 offset:1024
	ds_read_b128 v[154:157], v158 offset:2048
	ds_read_b128 v[158:161], v158 offset:3072
	ds_read_b128 v[162:165], v217 offset:32768
	ds_read_b128 v[166:169], v217 offset:33792
	ds_read_b128 v[170:173], v217 offset:34816
	ds_read_b128 v[174:177], v217 offset:35840
	ds_read_b128 v[178:181], v217 offset:36864
	ds_read_b128 v[182:185], v217 offset:37888
	ds_read_b128 v[186:189], v217 offset:38912
	ds_read_b128 v[190:193], v217 offset:39936
	s_add_u32 s50, s50, 0x4000
	s_addc_u32 s51, s51, 0
	s_mov_b32 m0, s68
	s_nop 0
	global_load_lds_dwordx4 v195, s[50:51]
	s_add_u32 m0, s68, 0x2000
	s_nop 0
	global_load_lds_dwordx4 v212, s[50:51]
	s_waitcnt vmcnt(8)
	s_waitcnt lgkmcnt(0)
	s_barrier
	s_setprio 1
	s_waitcnt lgkmcnt(7)
	v_mfma_f32_16x16x32_bf16 v[126:129], v[130:133], v[162:165], v[126:129]
	v_mfma_f32_16x16x32_bf16 v[122:125], v[138:141], v[162:165], v[122:125]
	s_waitcnt lgkmcnt(5)
	v_mfma_f32_16x16x32_bf16 v[118:121], v[130:133], v[170:173], v[118:121]
	v_mfma_f32_16x16x32_bf16 v[114:117], v[138:141], v[170:173], v[114:117]
	s_waitcnt lgkmcnt(3)
	v_mfma_f32_16x16x32_bf16 v[110:113], v[130:133], v[178:181], v[110:113]
	v_mfma_f32_16x16x32_bf16 v[106:109], v[138:141], v[178:181], v[106:109]
	s_waitcnt lgkmcnt(1)
	v_mfma_f32_16x16x32_bf16 v[102:105], v[130:133], v[186:189], v[102:105]
	v_mfma_f32_16x16x32_bf16 v[98:101], v[138:141], v[186:189], v[98:101]
	v_mfma_f32_16x16x32_bf16 v[126:129], v[134:137], v[166:169], v[126:129]
	v_mfma_f32_16x16x32_bf16 v[122:125], v[142:145], v[166:169], v[122:125]
	v_mfma_f32_16x16x32_bf16 v[118:121], v[134:137], v[174:177], v[118:121]
	v_mfma_f32_16x16x32_bf16 v[114:117], v[142:145], v[174:177], v[114:117]
	v_mfma_f32_16x16x32_bf16 v[110:113], v[134:137], v[182:185], v[110:113]
	v_mfma_f32_16x16x32_bf16 v[106:109], v[142:145], v[182:185], v[106:109]
	s_waitcnt lgkmcnt(0)
	v_mfma_f32_16x16x32_bf16 v[102:105], v[134:137], v[190:193], v[102:105]
	v_mfma_f32_16x16x32_bf16 v[98:101], v[142:145], v[190:193], v[98:101]
	s_setprio 0
	s_setprio 1
	v_mfma_f32_16x16x32_bf16 v[94:97], v[146:149], v[162:165], v[94:97]
	v_mfma_f32_16x16x32_bf16 v[90:93], v[154:157], v[162:165], v[90:93]
	v_mfma_f32_16x16x32_bf16 v[86:89], v[146:149], v[170:173], v[86:89]
	v_mfma_f32_16x16x32_bf16 v[82:85], v[154:157], v[170:173], v[82:85]
	v_mfma_f32_16x16x32_bf16 v[78:81], v[146:149], v[178:181], v[78:81]
	v_mfma_f32_16x16x32_bf16 v[74:77], v[154:157], v[178:181], v[74:77]
	v_mfma_f32_16x16x32_bf16 v[70:73], v[146:149], v[186:189], v[70:73]
	v_mfma_f32_16x16x32_bf16 v[66:69], v[154:157], v[186:189], v[66:69]
	v_mfma_f32_16x16x32_bf16 v[94:97], v[150:153], v[166:169], v[94:97]
	v_mfma_f32_16x16x32_bf16 v[90:93], v[158:161], v[166:169], v[90:93]
	v_mfma_f32_16x16x32_bf16 v[86:89], v[150:153], v[174:177], v[86:89]
	v_mfma_f32_16x16x32_bf16 v[82:85], v[158:161], v[174:177], v[82:85]
	v_mfma_f32_16x16x32_bf16 v[78:81], v[150:153], v[182:185], v[78:81]
	v_mfma_f32_16x16x32_bf16 v[74:77], v[158:161], v[182:185], v[74:77]
	v_mfma_f32_16x16x32_bf16 v[70:73], v[150:153], v[190:193], v[70:73]
	v_mfma_f32_16x16x32_bf16 v[66:69], v[158:161], v[190:193], v[66:69]
	s_setprio 0
	s_barrier
	ds_read_b128 v[162:165], v217 offset:49152
	ds_read_b128 v[166:169], v217 offset:50176
	ds_read_b128 v[170:173], v217 offset:51200
	ds_read_b128 v[174:177], v217 offset:52224
	ds_read_b128 v[178:181], v217 offset:53248
	ds_read_b128 v[182:185], v217 offset:54272
	ds_read_b128 v[186:189], v217 offset:55296
	ds_read_b128 v[190:193], v217 offset:56320
	s_mov_b32 m0, s72
	s_nop 0
	global_load_lds_dwordx4 v195, s[54:55]
	s_add_u32 m0, s72, 0x2000
	s_nop 0
	global_load_lds_dwordx4 v212, s[54:55]
	s_add_u32 s12, s12, 0xc000
	s_addc_u32 s13, s13, 0
	s_mov_b32 m0, s74
	s_nop 0
	global_load_lds_dwordx4 v195, s[12:13]
	s_add_u32 m0, s74, 0x2000
	s_nop 0
	global_load_lds_dwordx4 v212, s[12:13]
	s_nop 0
	s_mov_b32 m0, s73
	s_nop 0
	global_load_lds_dwordx4 v195, s[52:53]
	s_add_u32 m0, s73, 0x2000
	s_nop 0
	global_load_lds_dwordx4 v212, s[52:53]
	s_waitcnt vmcnt(8)
	s_waitcnt lgkmcnt(0)
	s_barrier
	s_setprio 1
	s_waitcnt lgkmcnt(7)
	v_mfma_f32_16x16x32_bf16 v[62:65], v[130:133], v[162:165], v[62:65]
	v_mfma_f32_16x16x32_bf16 v[58:61], v[138:141], v[162:165], v[58:61]
	s_waitcnt lgkmcnt(5)
	v_mfma_f32_16x16x32_bf16 v[54:57], v[130:133], v[170:173], v[54:57]
	v_mfma_f32_16x16x32_bf16 v[50:53], v[138:141], v[170:173], v[50:53]
	s_waitcnt lgkmcnt(3)
	v_mfma_f32_16x16x32_bf16 v[46:49], v[130:133], v[178:181], v[46:49]
	v_mfma_f32_16x16x32_bf16 v[42:45], v[138:141], v[178:181], v[42:45]
	s_waitcnt lgkmcnt(1)
	v_mfma_f32_16x16x32_bf16 v[38:41], v[130:133], v[186:189], v[38:41]
	v_mfma_f32_16x16x32_bf16 v[34:37], v[138:141], v[186:189], v[34:37]
	v_mfma_f32_16x16x32_bf16 v[62:65], v[134:137], v[166:169], v[62:65]
	v_mfma_f32_16x16x32_bf16 v[58:61], v[142:145], v[166:169], v[58:61]
	v_mfma_f32_16x16x32_bf16 v[54:57], v[134:137], v[174:177], v[54:57]
	v_mfma_f32_16x16x32_bf16 v[50:53], v[142:145], v[174:177], v[50:53]
	v_mfma_f32_16x16x32_bf16 v[46:49], v[134:137], v[182:185], v[46:49]
	v_mfma_f32_16x16x32_bf16 v[42:45], v[142:145], v[182:185], v[42:45]
	s_waitcnt lgkmcnt(0)
	v_mfma_f32_16x16x32_bf16 v[38:41], v[134:137], v[190:193], v[38:41]
	v_mfma_f32_16x16x32_bf16 v[34:37], v[142:145], v[190:193], v[34:37]
	s_setprio 0
	s_setprio 1
	v_mfma_f32_16x16x32_bf16 v[30:33], v[146:149], v[162:165], v[30:33]
	v_mfma_f32_16x16x32_bf16 v[26:29], v[154:157], v[162:165], v[26:29]
	v_mfma_f32_16x16x32_bf16 v[22:25], v[146:149], v[170:173], v[22:25]
	v_mfma_f32_16x16x32_bf16 v[18:21], v[154:157], v[170:173], v[18:21]
	v_mfma_f32_16x16x32_bf16 v[14:17], v[146:149], v[178:181], v[14:17]
	v_mfma_f32_16x16x32_bf16 v[10:13], v[154:157], v[178:181], v[10:13]
	v_mfma_f32_16x16x32_bf16 v[6:9], v[146:149], v[186:189], v[6:9]
	v_mfma_f32_16x16x32_bf16 v[2:5], v[154:157], v[186:189], v[2:5]
	v_mfma_f32_16x16x32_bf16 v[30:33], v[150:153], v[166:169], v[30:33]
	v_mfma_f32_16x16x32_bf16 v[26:29], v[158:161], v[166:169], v[26:29]
	v_mfma_f32_16x16x32_bf16 v[22:25], v[150:153], v[174:177], v[22:25]
	v_mfma_f32_16x16x32_bf16 v[18:21], v[158:161], v[174:177], v[18:21]
	v_mfma_f32_16x16x32_bf16 v[14:17], v[150:153], v[182:185], v[14:17]
	v_mfma_f32_16x16x32_bf16 v[10:13], v[158:161], v[182:185], v[10:13]
	v_mfma_f32_16x16x32_bf16 v[6:9], v[150:153], v[190:193], v[6:9]
	v_mfma_f32_16x16x32_bf16 v[2:5], v[158:161], v[190:193], v[2:5]
	s_setprio 0
	s_barrier
	s_cmp_gt_u32 s58, 13
	s_cbranch_scc1 .LBB0_1523
	v_mov_b32_e32 v130, v198
	s_mov_b32 s58, s26
	s_branch .LBB0_1498

.LBB0_1525:
	s_lshl_b32 s10, s82, 8
	v_mov_b32_e32 v130, v213
	v_mov_b32_e32 v163, v210
	s_add_i32 s10, s10, s70
	v_add_u32_e32 v162, s10, v130
	s_lshl_b32 s10, s14, 8
	s_or_b32 s10, s10, s71
	v_lshl_add_u32 v134, v163, 3, s10
	v_bfe_u32 v222, v134, 5, 1
	v_lshrrev_b32_e32 v131, 3, v162
	v_lshlrev_b32_e32 v130, 1, v134
	v_and_or_b32 v131, v131, 14, v222
	v_and_b32_e32 v221, 48, v130
	v_ashrrev_i32_e32 v220, 6, v134
	v_ashrrev_i32_e32 v130, 4, v162
	v_lshlrev_b32_e32 v132, 6, v162
	v_lshlrev_b32_e32 v224, 10, v131
	v_lshlrev_b32_e32 v131, 2, v162
	v_add_u32_e32 v134, 0x80, v134
	v_and_b32_e32 v135, -16, v130
	v_lshlrev_b32_e32 v130, 7, v162
	v_and_b32_e32 v132, 0x3c0, v132
	v_and_b32_e32 v131, 32, v131
	v_ashrrev_i32_e32 v223, 6, v134
	v_and_b32_e32 v130, 0x4000, v130
	v_bitop3_b32 v131, v221, v131, v132 bitop3:0x36
	v_add_u32_e32 v132, v220, v135
	v_or3_b32 v198, v130, v131, v224
	v_ashrrev_i32_e32 v133, 31, v132
	v_lshl_add_u64 v[130:131], s[34:35], 0, v[198:199]
	v_lshlrev_b64 v[190:191], 15, v[132:133]
	v_lshl_add_u64 v[132:133], v[130:131], 0, v[190:191]
	v_add_u32_e32 v178, 16, v162
	v_lshl_add_u64 v[166:167], v[132:133], 0, 0
	global_load_dwordx4 v[158:161], v[132:133], off
	s_mov_b32 s98, 0x11000
	s_mov_b32 s99, 0x0
	v_lshl_add_u64 v[172:173], v[166:167], 0, s[98:99]
	global_load_dwordx4 v[154:157], v[172:173], off offset:-4096
	v_add_u32_e32 v170, 32, v162
	s_mov_b32 s98, 0x1000
	s_mov_b32 s99, 0x0
	v_lshl_add_u64 v[174:175], v[166:167], 0, s[98:99]
	global_load_dwordx4 v[150:153], v[174:175], off offset:-2048
	global_load_dwordx4 v[146:149], v[172:173], off offset:-2048
	v_ashrrev_i32_e32 v130, 4, v170
	v_and_b32_e32 v134, -16, v130
	v_add_u32_e32 v134, v223, v134
	v_ashrrev_i32_e32 v135, 31, v134
	v_lshlrev_b64 v[176:177], 15, v[134:135]
	v_add_u32_e32 v164, 48, v162
	global_load_dwordx4 v[142:145], v[174:175], off
	global_load_dwordx4 v[138:141], v[172:173], off
	global_load_dwordx4 v[134:137], v[174:175], off offset:2048
	s_nop 0
	global_load_dwordx4 v[130:133], v[172:173], off offset:2048
	s_cmpk_gt_i32 s82, 0x7f
	s_cselect_b64 s[50:51], -1, 0
	s_nor_b64 s[54:55], s[36:37], s[50:51]
	s_waitcnt vmcnt(7)
	v_lshlrev_b32_e32 v190, 16, v158
	v_and_b32_e32 v191, 0xffff0000, v158
	v_lshlrev_b32_e32 v158, 16, v159
	v_and_b32_e32 v159, 0xffff0000, v159
	v_pk_add_f32 v[192:193], v[128:129], v[158:159]
	v_lshlrev_b32_e32 v158, 16, v160
	v_and_b32_e32 v159, 0xffff0000, v160
	v_pk_add_f32 v[202:203], v[122:123], v[158:159]
	v_lshlrev_b32_e32 v158, 16, v161
	v_and_b32_e32 v159, 0xffff0000, v161
	v_pk_add_f32 v[190:191], v[126:127], v[190:191]
	v_pk_add_f32 v[204:205], v[124:125], v[158:159]
	v_cvt_pk_bf16_f32 v158, v190, v191
	v_cvt_pk_bf16_f32 v159, v192, v193
	v_cvt_pk_bf16_f32 v160, v202, v203
	v_cvt_pk_bf16_f32 v161, v204, v205
	s_mov_b64 s[10:11], -1
	s_and_b64 vcc, exec, s[54:55]
	s_cbranch_vccz .LBB0_1527
	global_store_dwordx4 v[174:175], v[158:161], off offset:-4096
	s_mov_b64 s[10:11], 0
.LBB0_1527:
	s_andn2_b64 vcc, exec, s[10:11]
	s_cbranch_vccnz .LBB0_1529
	global_store_dwordx4 v[174:175], v[158:161], off offset:-4096 sc1
	s_nop 1
.LBB0_1529:
	s_nop 0
	s_nop 0
	s_waitcnt vmcnt(6)
	v_lshlrev_b32_e32 v158, 16, v154
	v_and_b32_e32 v159, 0xffff0000, v154
	v_lshlrev_b32_e32 v154, 16, v155
	v_and_b32_e32 v155, 0xffff0000, v155
	v_pk_add_f32 v[160:161], v[96:97], v[154:155]
	v_lshlrev_b32_e32 v154, 16, v156
	v_and_b32_e32 v155, 0xffff0000, v156
	v_pk_add_f32 v[206:207], v[90:91], v[154:155]
	v_lshlrev_b32_e32 v154, 16, v157
	v_and_b32_e32 v155, 0xffff0000, v157
	v_pk_add_f32 v[158:159], v[94:95], v[158:159]
	v_pk_add_f32 v[208:209], v[92:93], v[154:155]
	v_cndmask_b32_e64 v165, 0, 1, s[54:55]
	v_cvt_pk_bf16_f32 v154, v158, v159
	v_cvt_pk_bf16_f32 v155, v160, v161
	v_cvt_pk_bf16_f32 v156, v206, v207
	v_cvt_pk_bf16_f32 v157, v208, v209
	v_cmp_ne_u32_e64 s[10:11], 1, v165
	s_andn2_b64 vcc, exec, s[54:55]
	s_mov_b64 s[12:13], -1
	s_cbranch_vccnz .LBB0_1531
	s_mov_b64 s[12:13], 0
	global_store_dwordx4 v[172:173], v[154:157], off offset:-4096
.LBB0_1531:
	s_andn2_b64 vcc, exec, s[12:13]
	s_cbranch_vccnz .LBB0_1533
	global_store_dwordx4 v[172:173], v[154:157], off offset:-4096 sc1
	s_nop 1

.LBB0_1539:
	s_or_b64 exec, exec, s[56:57]
	s_waitcnt lgkmcnt(0)
	s_waitcnt vmcnt(5)
	v_lshlrev_b32_e32 v154, 16, v150
	v_and_b32_e32 v155, 0xffff0000, v150
	v_lshlrev_b32_e32 v150, 16, v151
	v_and_b32_e32 v151, 0xffff0000, v151
	v_pk_add_f32 v[156:157], v[120:121], v[150:151]
	v_lshlrev_b32_e32 v150, 16, v152
	v_and_b32_e32 v151, 0xffff0000, v152
	v_pk_add_f32 v[158:159], v[114:115], v[150:151]
	v_lshlrev_b32_e32 v150, 16, v153
	v_and_b32_e32 v151, 0xffff0000, v153
	v_pk_add_f32 v[154:155], v[118:119], v[154:155]
	v_pk_add_f32 v[160:161], v[116:117], v[150:151]
	v_cvt_pk_bf16_f32 v150, v154, v155
	v_cvt_pk_bf16_f32 v151, v156, v157
	v_cvt_pk_bf16_f32 v152, v158, v159
	v_cvt_pk_bf16_f32 v153, v160, v161
	s_nor_b64 s[54:55], s[58:59], s[50:51]
	s_and_saveexec_b64 s[56:57], s[54:55]
	s_xor_b64 s[54:55], exec, s[56:57]
	s_cbranch_execz .LBB0_1541
	global_store_dwordx4 v[174:175], v[150:153], off offset:-2048

.LBB0_1543:
	s_or_b64 exec, exec, s[54:55]
	s_nop 0
	s_nop 0
	s_waitcnt vmcnt(4)
	v_lshlrev_b32_e32 v150, 16, v146
	v_and_b32_e32 v151, 0xffff0000, v146
	v_lshlrev_b32_e32 v146, 16, v147
	v_and_b32_e32 v147, 0xffff0000, v147
	v_pk_add_f32 v[182:183], v[88:89], v[146:147]
	v_lshlrev_b32_e32 v146, 16, v148
	v_and_b32_e32 v147, 0xffff0000, v148
	v_pk_add_f32 v[184:185], v[82:83], v[146:147]
	v_lshlrev_b32_e32 v146, 16, v149
	v_and_b32_e32 v147, 0xffff0000, v149
	v_pk_add_f32 v[150:151], v[86:87], v[150:151]
	v_pk_add_f32 v[186:187], v[84:85], v[146:147]
	v_cvt_pk_bf16_f32 v146, v150, v151
	v_cvt_pk_bf16_f32 v147, v182, v183
	v_cvt_pk_bf16_f32 v148, v184, v185
	v_cvt_pk_bf16_f32 v149, v186, v187
	s_and_b64 vcc, exec, s[10:11]
	s_mov_b64 s[54:55], -1
	s_cbranch_vccnz .LBB0_1545
	s_mov_b64 s[54:55], 0
	global_store_dwordx4 v[172:173], v[146:149], off offset:-2048

.LBB0_1553:
	s_or_b64 exec, exec, s[54:55]
	s_waitcnt lgkmcnt(0)
	s_waitcnt vmcnt(3)
	v_lshlrev_b32_e32 v146, 16, v142
	v_and_b32_e32 v147, 0xffff0000, v142
	v_lshlrev_b32_e32 v142, 16, v143
	v_and_b32_e32 v143, 0xffff0000, v143
	v_pk_add_f32 v[148:149], v[112:113], v[142:143]
	v_lshlrev_b32_e32 v142, 16, v144
	v_and_b32_e32 v143, 0xffff0000, v144
	v_pk_add_f32 v[150:151], v[106:107], v[142:143]
	v_lshlrev_b32_e32 v142, 16, v145
	v_and_b32_e32 v143, 0xffff0000, v145
	v_pk_add_f32 v[146:147], v[110:111], v[146:147]
	v_pk_add_f32 v[152:153], v[108:109], v[142:143]
	v_cvt_pk_bf16_f32 v142, v146, v147
	v_cvt_pk_bf16_f32 v143, v148, v149
	v_cvt_pk_bf16_f32 v144, v150, v151
	v_cvt_pk_bf16_f32 v145, v152, v153
	s_nor_b64 s[54:55], s[56:57], s[50:51]
	s_and_saveexec_b64 s[56:57], s[54:55]
	s_xor_b64 s[54:55], exec, s[56:57]
	s_cbranch_execz .LBB0_1555
	global_store_dwordx4 v[174:175], v[142:145], off

.LBB0_1557:
	s_or_b64 exec, exec, s[54:55]
	s_nop 0
	s_nop 0
	s_waitcnt vmcnt(2)
	v_lshlrev_b32_e32 v142, 16, v138
	v_and_b32_e32 v143, 0xffff0000, v138
	v_lshlrev_b32_e32 v138, 16, v139
	v_and_b32_e32 v139, 0xffff0000, v139
	v_pk_add_f32 v[154:155], v[80:81], v[138:139]
	v_lshlrev_b32_e32 v138, 16, v140
	v_and_b32_e32 v139, 0xffff0000, v140
	v_pk_add_f32 v[156:157], v[74:75], v[138:139]
	v_lshlrev_b32_e32 v138, 16, v141
	v_and_b32_e32 v139, 0xffff0000, v141
	v_pk_add_f32 v[142:143], v[78:79], v[142:143]
	v_pk_add_f32 v[158:159], v[76:77], v[138:139]
	v_cvt_pk_bf16_f32 v138, v142, v143
	v_cvt_pk_bf16_f32 v139, v154, v155
	v_cvt_pk_bf16_f32 v140, v156, v157
	v_cvt_pk_bf16_f32 v141, v158, v159
	s_and_b64 vcc, exec, s[10:11]
	s_mov_b64 s[54:55], -1
	s_cbranch_vccnz .LBB0_1559
	s_mov_b64 s[54:55], 0
	global_store_dwordx4 v[172:173], v[138:141], off

.LBB0_1567:
	s_or_b64 exec, exec, s[54:55]
	s_waitcnt lgkmcnt(0)
	s_waitcnt vmcnt(1)
	v_lshlrev_b32_e32 v138, 16, v134
	v_and_b32_e32 v139, 0xffff0000, v134
	v_lshlrev_b32_e32 v134, 16, v135
	v_and_b32_e32 v135, 0xffff0000, v135
	v_pk_add_f32 v[140:141], v[104:105], v[134:135]
	v_lshlrev_b32_e32 v134, 16, v136
	v_and_b32_e32 v135, 0xffff0000, v136
	v_pk_add_f32 v[142:143], v[98:99], v[134:135]
	v_lshlrev_b32_e32 v134, 16, v137
	v_and_b32_e32 v135, 0xffff0000, v137
	v_pk_add_f32 v[138:139], v[102:103], v[138:139]
	v_pk_add_f32 v[144:145], v[100:101], v[134:135]
	v_cvt_pk_bf16_f32 v134, v138, v139
	v_cvt_pk_bf16_f32 v135, v140, v141
	v_cvt_pk_bf16_f32 v136, v142, v143
	v_cvt_pk_bf16_f32 v137, v144, v145
	s_nor_b64 s[54:55], s[56:57], s[50:51]
	s_and_saveexec_b64 s[56:57], s[54:55]
	s_xor_b64 s[54:55], exec, s[56:57]
	s_cbranch_execz .LBB0_1569
	global_store_dwordx4 v[174:175], v[134:137], off offset:2048

.LBB0_1571:
	s_or_b64 exec, exec, s[54:55]
	s_nop 0
	s_nop 0
	s_waitcnt vmcnt(0)
	v_lshlrev_b32_e32 v134, 16, v130
	v_and_b32_e32 v135, 0xffff0000, v130
	v_lshlrev_b32_e32 v130, 16, v131
	v_and_b32_e32 v131, 0xffff0000, v131
	v_pk_add_f32 v[146:147], v[72:73], v[130:131]
	v_lshlrev_b32_e32 v130, 16, v132
	v_and_b32_e32 v131, 0xffff0000, v132
	v_pk_add_f32 v[148:149], v[66:67], v[130:131]
	v_lshlrev_b32_e32 v130, 16, v133
	v_and_b32_e32 v131, 0xffff0000, v133
	v_pk_add_f32 v[134:135], v[70:71], v[134:135]
	v_pk_add_f32 v[150:151], v[68:69], v[130:131]
	v_cvt_pk_bf16_f32 v130, v134, v135
	v_cvt_pk_bf16_f32 v131, v146, v147
	v_cvt_pk_bf16_f32 v132, v148, v149
	v_cvt_pk_bf16_f32 v133, v150, v151
	s_and_b64 vcc, exec, s[10:11]
	s_mov_b64 s[54:55], -1
	s_cbranch_vccnz .LBB0_1573
	s_mov_b64 s[54:55], 0
	global_store_dwordx4 v[172:173], v[130:133], off offset:2048

.LBB0_1580:
	s_or_b64 exec, exec, s[54:55]
	v_add_u32_e32 v184, 0x80, v162
	s_waitcnt lgkmcnt(0)
	v_lshlrev_b32_e32 v131, 6, v184
	v_lshlrev_b32_e32 v132, 2, v184
	v_lshlrev_b32_e32 v130, 7, v184
	v_and_b32_e32 v131, 0x3c0, v131
	v_and_b32_e32 v132, 32, v132
	v_and_b32_e32 v130, 0x4000, v130
	v_bitop3_b32 v131, v131, v132, v221 bitop3:0x36
	v_or3_b32 v198, v130, v131, v224
	v_add_u32_e32 v176, 0x90, v162
	s_mov_b32 s98, 0x5000
	s_mov_b32 s99, 0x0
	v_lshl_add_u64 v[172:173], v[166:167], 0, s[98:99]
	global_load_dwordx4 v[158:161], v[172:173], off offset:-4096
	s_mov_b32 s98, 0x15000
	s_mov_b32 s99, 0x0
	v_lshl_add_u64 v[174:175], v[166:167], 0, s[98:99]
	global_load_dwordx4 v[154:157], v[174:175], off offset:-4096
	v_add_u32_e32 v168, 0xa0, v162
	global_load_dwordx4 v[150:153], v[172:173], off offset:-2048
	global_load_dwordx4 v[146:149], v[174:175], off offset:-2048
	v_add_u32_e32 v162, 0xb0, v162
	global_load_dwordx4 v[142:145], v[172:173], off
	global_load_dwordx4 v[138:141], v[174:175], off
	global_load_dwordx4 v[134:137], v[172:173], off offset:2048
	s_nop 0
	global_load_dwordx4 v[130:133], v[174:175], off offset:2048
	s_and_b64 vcc, exec, s[10:11]
	s_mov_b64 s[54:55], -1
	s_waitcnt vmcnt(7)
	v_lshlrev_b32_e32 v190, 16, v158
	v_and_b32_e32 v191, 0xffff0000, v158
	v_lshlrev_b32_e32 v158, 16, v159
	v_and_b32_e32 v159, 0xffff0000, v159
	v_pk_add_f32 v[192:193], v[64:65], v[158:159]
	v_lshlrev_b32_e32 v158, 16, v160
	v_and_b32_e32 v159, 0xffff0000, v160
	v_pk_add_f32 v[202:203], v[58:59], v[158:159]
	v_lshlrev_b32_e32 v158, 16, v161
	v_and_b32_e32 v159, 0xffff0000, v161
	v_pk_add_f32 v[190:191], v[62:63], v[190:191]
	v_pk_add_f32 v[204:205], v[60:61], v[158:159]
	v_cvt_pk_bf16_f32 v158, v190, v191
	v_cvt_pk_bf16_f32 v159, v192, v193
	v_cvt_pk_bf16_f32 v160, v202, v203
	v_cvt_pk_bf16_f32 v161, v204, v205
	s_cbranch_vccnz .LBB0_1582
	s_mov_b64 s[54:55], 0
	global_store_dwordx4 v[172:173], v[158:161], off offset:-4096

.LBB0_1584:
	s_nop 0
	s_nop 0
	s_waitcnt vmcnt(6)
	v_lshlrev_b32_e32 v158, 16, v154
	v_and_b32_e32 v159, 0xffff0000, v154
	v_lshlrev_b32_e32 v154, 16, v155
	v_and_b32_e32 v155, 0xffff0000, v155
	v_pk_add_f32 v[188:189], v[32:33], v[154:155]
	v_lshlrev_b32_e32 v154, 16, v156
	v_and_b32_e32 v155, 0xffff0000, v156
	v_pk_add_f32 v[206:207], v[26:27], v[154:155]
	v_lshlrev_b32_e32 v154, 16, v157
	v_and_b32_e32 v155, 0xffff0000, v157
	v_pk_add_f32 v[158:159], v[30:31], v[158:159]
	v_pk_add_f32 v[208:209], v[28:29], v[154:155]
	v_cvt_pk_bf16_f32 v154, v158, v159
	v_cvt_pk_bf16_f32 v155, v188, v189
	v_cvt_pk_bf16_f32 v156, v206, v207
	v_cvt_pk_bf16_f32 v157, v208, v209
	s_and_b64 vcc, exec, s[10:11]
	s_mov_b64 s[54:55], -1
	s_cbranch_vccnz .LBB0_1586
	s_mov_b64 s[54:55], 0
	global_store_dwordx4 v[174:175], v[154:157], off offset:-4096

.LBB0_1594:
	s_or_b64 exec, exec, s[54:55]
	s_waitcnt lgkmcnt(0)
	s_waitcnt vmcnt(5)
	v_lshlrev_b32_e32 v154, 16, v150
	v_and_b32_e32 v155, 0xffff0000, v150
	v_lshlrev_b32_e32 v150, 16, v151
	v_and_b32_e32 v151, 0xffff0000, v151
	v_pk_add_f32 v[156:157], v[56:57], v[150:151]
	v_lshlrev_b32_e32 v150, 16, v152
	v_and_b32_e32 v151, 0xffff0000, v152
	v_pk_add_f32 v[158:159], v[50:51], v[150:151]
	v_lshlrev_b32_e32 v150, 16, v153
	v_and_b32_e32 v151, 0xffff0000, v153
	v_pk_add_f32 v[154:155], v[54:55], v[154:155]
	v_pk_add_f32 v[160:161], v[52:53], v[150:151]
	v_cvt_pk_bf16_f32 v150, v154, v155
	v_cvt_pk_bf16_f32 v151, v156, v157
	v_cvt_pk_bf16_f32 v152, v158, v159
	v_cvt_pk_bf16_f32 v153, v160, v161
	s_nor_b64 s[54:55], s[56:57], s[50:51]
	s_and_saveexec_b64 s[56:57], s[54:55]
	s_xor_b64 s[54:55], exec, s[56:57]
	s_cbranch_execz .LBB0_1596
	global_store_dwordx4 v[172:173], v[150:153], off offset:-2048

.LBB0_1598:
	s_or_b64 exec, exec, s[54:55]
	s_nop 0
	s_nop 0
	s_waitcnt vmcnt(4)
	v_lshlrev_b32_e32 v150, 16, v146
	v_and_b32_e32 v151, 0xffff0000, v146
	v_lshlrev_b32_e32 v146, 16, v147
	v_and_b32_e32 v147, 0xffff0000, v147
	v_pk_add_f32 v[180:181], v[24:25], v[146:147]
	v_lshlrev_b32_e32 v146, 16, v148
	v_and_b32_e32 v147, 0xffff0000, v148
	v_pk_add_f32 v[182:183], v[18:19], v[146:147]
	v_lshlrev_b32_e32 v146, 16, v149
	v_and_b32_e32 v147, 0xffff0000, v149
	v_pk_add_f32 v[150:151], v[22:23], v[150:151]
	v_pk_add_f32 v[184:185], v[20:21], v[146:147]
	v_cvt_pk_bf16_f32 v146, v150, v151
	v_cvt_pk_bf16_f32 v147, v180, v181
	v_cvt_pk_bf16_f32 v148, v182, v183
	v_cvt_pk_bf16_f32 v149, v184, v185
	s_and_b64 vcc, exec, s[10:11]
	s_mov_b64 s[54:55], -1
	s_cbranch_vccnz .LBB0_1600
	s_mov_b64 s[54:55], 0
	global_store_dwordx4 v[174:175], v[146:149], off offset:-2048

.LBB0_1608:
	s_or_b64 exec, exec, s[54:55]
	s_waitcnt lgkmcnt(0)
	s_waitcnt vmcnt(3)
	v_lshlrev_b32_e32 v146, 16, v142
	v_and_b32_e32 v147, 0xffff0000, v142
	v_lshlrev_b32_e32 v142, 16, v143
	v_and_b32_e32 v143, 0xffff0000, v143
	v_pk_add_f32 v[148:149], v[48:49], v[142:143]
	v_lshlrev_b32_e32 v142, 16, v144
	v_and_b32_e32 v143, 0xffff0000, v144
	v_pk_add_f32 v[150:151], v[42:43], v[142:143]
	v_lshlrev_b32_e32 v142, 16, v145
	v_and_b32_e32 v143, 0xffff0000, v145
	v_pk_add_f32 v[146:147], v[46:47], v[146:147]
	v_pk_add_f32 v[152:153], v[44:45], v[142:143]
	v_cvt_pk_bf16_f32 v142, v146, v147
	v_cvt_pk_bf16_f32 v143, v148, v149
	v_cvt_pk_bf16_f32 v144, v150, v151
	v_cvt_pk_bf16_f32 v145, v152, v153
	s_nor_b64 s[54:55], s[56:57], s[50:51]
	s_and_saveexec_b64 s[56:57], s[54:55]
	s_xor_b64 s[54:55], exec, s[56:57]
	s_cbranch_execz .LBB0_1610
	global_store_dwordx4 v[172:173], v[142:145], off

.LBB0_1612:
	s_or_b64 exec, exec, s[54:55]
	s_nop 0
	s_nop 0
	s_waitcnt vmcnt(2)
	v_lshlrev_b32_e32 v142, 16, v138
	v_and_b32_e32 v143, 0xffff0000, v138
	v_lshlrev_b32_e32 v138, 16, v139
	v_and_b32_e32 v139, 0xffff0000, v139
	v_pk_add_f32 v[154:155], v[16:17], v[138:139]
	v_lshlrev_b32_e32 v138, 16, v140
	v_and_b32_e32 v139, 0xffff0000, v140
	v_pk_add_f32 v[156:157], v[10:11], v[138:139]
	v_lshlrev_b32_e32 v138, 16, v141
	v_and_b32_e32 v139, 0xffff0000, v141
	v_pk_add_f32 v[142:143], v[14:15], v[142:143]
	v_pk_add_f32 v[158:159], v[12:13], v[138:139]
	v_cvt_pk_bf16_f32 v138, v142, v143
	v_cvt_pk_bf16_f32 v139, v154, v155
	v_cvt_pk_bf16_f32 v140, v156, v157
	v_cvt_pk_bf16_f32 v141, v158, v159
	s_and_b64 vcc, exec, s[10:11]
	s_mov_b64 s[54:55], -1
	s_cbranch_vccnz .LBB0_1614
	s_mov_b64 s[54:55], 0
	global_store_dwordx4 v[174:175], v[138:141], off

.LBB0_1622:
	s_or_b64 exec, exec, s[54:55]
	s_waitcnt lgkmcnt(0)
	s_waitcnt vmcnt(1)
	v_lshlrev_b32_e32 v138, 16, v134
	v_and_b32_e32 v139, 0xffff0000, v134
	v_lshlrev_b32_e32 v134, 16, v135
	v_and_b32_e32 v135, 0xffff0000, v135
	v_pk_add_f32 v[140:141], v[40:41], v[134:135]
	v_lshlrev_b32_e32 v134, 16, v136
	v_and_b32_e32 v135, 0xffff0000, v136
	v_pk_add_f32 v[142:143], v[34:35], v[134:135]
	v_lshlrev_b32_e32 v134, 16, v137
	v_and_b32_e32 v135, 0xffff0000, v137
	v_pk_add_f32 v[138:139], v[38:39], v[138:139]
	v_pk_add_f32 v[144:145], v[36:37], v[134:135]
	v_cvt_pk_bf16_f32 v134, v138, v139
	v_cvt_pk_bf16_f32 v135, v140, v141
	v_cvt_pk_bf16_f32 v136, v142, v143
	v_cvt_pk_bf16_f32 v137, v144, v145
	s_nor_b64 s[50:51], s[56:57], s[50:51]
	s_and_saveexec_b64 s[54:55], s[50:51]
	s_xor_b64 s[50:51], exec, s[54:55]
	s_cbranch_execz .LBB0_1624
	global_store_dwordx4 v[172:173], v[134:137], off offset:2048

.LBB0_1626:
	s_or_b64 exec, exec, s[50:51]
	s_nop 0
	s_nop 0
	s_waitcnt vmcnt(0)
	v_lshlrev_b32_e32 v134, 16, v130
	v_and_b32_e32 v135, 0xffff0000, v130
	v_lshlrev_b32_e32 v130, 16, v131
	v_and_b32_e32 v131, 0xffff0000, v131
	v_pk_add_f32 v[146:147], v[8:9], v[130:131]
	v_lshlrev_b32_e32 v130, 16, v132
	v_and_b32_e32 v131, 0xffff0000, v132
	v_pk_add_f32 v[148:149], v[2:3], v[130:131]
	v_lshlrev_b32_e32 v130, 16, v133
	v_and_b32_e32 v131, 0xffff0000, v133
	v_pk_add_f32 v[134:135], v[6:7], v[134:135]
	v_pk_add_f32 v[150:151], v[4:5], v[130:131]
	v_cvt_pk_bf16_f32 v130, v134, v135
	v_cvt_pk_bf16_f32 v131, v146, v147
	v_cvt_pk_bf16_f32 v132, v148, v149
	v_cvt_pk_bf16_f32 v133, v150, v151
	s_and_b64 vcc, exec, s[10:11]
	s_mov_b64 s[50:51], -1
	s_cbranch_vccnz .LBB0_1628
	s_mov_b64 s[50:51], 0
	global_store_dwordx4 v[174:175], v[130:133], off offset:2048

.LBB0_1712:
	s_add_u32 s52, s48, 0x10000
	s_addc_u32 s53, s49, 0
	s_and_b64 s[48:49], s[46:47], exec
	s_cselect_b32 s49, s53, s25
	s_cselect_b32 s48, s52, s75
	s_add_u32 s13, s16, s13
	s_addc_u32 s52, s17, 0
	s_add_u32 s13, s13, 0x10000
	s_waitcnt vmcnt(8)
	s_addc_u32 s52, s52, 0
	s_waitcnt lgkmcnt(0)
	s_and_b64 s[46:47], s[46:47], exec
	s_cselect_b32 s47, s52, s27
	s_cselect_b32 s46, s13, s76
	s_barrier
	s_setprio 1
	s_waitcnt lgkmcnt(7)
	v_mfma_f32_16x16x32_bf16 v[126:129], v[146:149], v[186:189], v[126:129]
	v_mfma_f32_16x16x32_bf16 v[122:125], v[154:157], v[186:189], v[122:125]
	s_waitcnt lgkmcnt(5)
	v_mfma_f32_16x16x32_bf16 v[118:121], v[146:149], v[178:181], v[118:121]
	v_mfma_f32_16x16x32_bf16 v[114:117], v[154:157], v[178:181], v[114:117]
	s_waitcnt lgkmcnt(3)
	v_mfma_f32_16x16x32_bf16 v[110:113], v[146:149], v[170:173], v[110:113]
	v_mfma_f32_16x16x32_bf16 v[106:109], v[154:157], v[170:173], v[106:109]
	s_waitcnt lgkmcnt(1)
	v_mfma_f32_16x16x32_bf16 v[102:105], v[146:149], v[162:165], v[102:105]
	v_mfma_f32_16x16x32_bf16 v[98:101], v[154:157], v[162:165], v[98:101]
	v_mfma_f32_16x16x32_bf16 v[126:129], v[150:153], v[190:193], v[126:129]
	v_mfma_f32_16x16x32_bf16 v[122:125], v[158:161], v[190:193], v[122:125]
	v_mfma_f32_16x16x32_bf16 v[118:121], v[150:153], v[182:185], v[118:121]
	v_mfma_f32_16x16x32_bf16 v[114:117], v[158:161], v[182:185], v[114:117]
	v_mfma_f32_16x16x32_bf16 v[110:113], v[150:153], v[174:177], v[110:113]
	v_mfma_f32_16x16x32_bf16 v[106:109], v[158:161], v[174:177], v[106:109]
	s_waitcnt lgkmcnt(0)
	v_mfma_f32_16x16x32_bf16 v[102:105], v[150:153], v[166:169], v[102:105]
	v_mfma_f32_16x16x32_bf16 v[98:101], v[158:161], v[166:169], v[98:101]
	s_setprio 0
	s_setprio 1
	v_mfma_f32_16x16x32_bf16 v[94:97], v[130:133], v[186:189], v[94:97]
	v_mfma_f32_16x16x32_bf16 v[90:93], v[138:141], v[186:189], v[90:93]
	v_mfma_f32_16x16x32_bf16 v[86:89], v[130:133], v[178:181], v[86:89]
	v_mfma_f32_16x16x32_bf16 v[82:85], v[138:141], v[178:181], v[82:85]
	v_mfma_f32_16x16x32_bf16 v[78:81], v[130:133], v[170:173], v[78:81]
	v_mfma_f32_16x16x32_bf16 v[74:77], v[138:141], v[170:173], v[74:77]
	v_mfma_f32_16x16x32_bf16 v[70:73], v[130:133], v[162:165], v[70:73]
	v_mfma_f32_16x16x32_bf16 v[66:69], v[138:141], v[162:165], v[66:69]
	v_mfma_f32_16x16x32_bf16 v[94:97], v[134:137], v[190:193], v[94:97]
	v_mfma_f32_16x16x32_bf16 v[90:93], v[142:145], v[190:193], v[90:93]
	v_mfma_f32_16x16x32_bf16 v[86:89], v[134:137], v[182:185], v[86:89]
	v_mfma_f32_16x16x32_bf16 v[82:85], v[142:145], v[182:185], v[82:85]
	v_mfma_f32_16x16x32_bf16 v[78:81], v[134:137], v[174:177], v[78:81]
	v_mfma_f32_16x16x32_bf16 v[74:77], v[142:145], v[174:177], v[74:77]
	v_mfma_f32_16x16x32_bf16 v[70:73], v[134:137], v[166:169], v[70:73]
	v_mfma_f32_16x16x32_bf16 v[66:69], v[142:145], v[166:169], v[66:69]
	s_setprio 0
	s_barrier
	ds_read_b128 v[186:189], v209 offset:16384
	ds_read_b128 v[190:193], v209 offset:17408
	ds_read_b128 v[178:181], v209 offset:18432
	ds_read_b128 v[182:185], v209 offset:19456
	ds_read_b128 v[170:173], v209 offset:20480
	ds_read_b128 v[174:177], v209 offset:21504
	ds_read_b128 v[162:165], v209 offset:22528
	ds_read_b128 v[166:169], v209 offset:23552
	s_mov_b32 m0, s58
	s_nop 0
	global_load_lds_dwordx4 v195, s[46:47]
	s_add_u32 m0, s58, 0x2000
	s_nop 0
	global_load_lds_dwordx4 v203, s[46:47]
	s_add_u32 s52, s46, 0x4000
	s_addc_u32 s53, s47, 0
	s_mov_b32 m0, s59
	s_nop 0
	global_load_lds_dwordx4 v195, s[52:53]
	s_add_u32 m0, s59, 0x2000
	s_nop 0
	global_load_lds_dwordx4 v203, s[52:53]
	s_andn2_b64 vcc, exec, s[50:51]
	s_mov_b32 m0, s11
	s_nop 0
	global_load_lds_dwordx4 v195, s[48:49]
	s_add_u32 m0, s11, 0x2000
	s_nop 0
	global_load_lds_dwordx4 v203, s[48:49]
	s_cbranch_vccnz .LBB0_1714
	v_mov_b32_e32 v2, 0
	v_mov_b32_e32 v3, v2
	v_mov_b32_e32 v4, v2
	v_mov_b32_e32 v5, v2
	v_mov_b32_e32 v6, v2
	v_mov_b32_e32 v7, v2
	v_mov_b32_e32 v8, v2
	v_mov_b32_e32 v9, v2
	v_mov_b32_e32 v10, v2
	v_mov_b32_e32 v11, v2
	v_mov_b32_e32 v12, v2
	v_mov_b32_e32 v13, v2
	v_mov_b32_e32 v14, v2
	v_mov_b32_e32 v15, v2
	v_mov_b32_e32 v16, v2
	v_mov_b32_e32 v17, v2
	v_mov_b32_e32 v18, v2
	v_mov_b32_e32 v19, v2
	v_mov_b32_e32 v20, v2
	v_mov_b32_e32 v21, v2
	v_mov_b32_e32 v22, v2
	v_mov_b32_e32 v23, v2
	v_mov_b32_e32 v24, v2
	v_mov_b32_e32 v25, v2
	v_mov_b32_e32 v26, v2
	v_mov_b32_e32 v27, v2
	v_mov_b32_e32 v28, v2
	v_mov_b32_e32 v29, v2
	v_mov_b32_e32 v30, v2
	v_mov_b32_e32 v31, v2
	v_mov_b32_e32 v32, v2
	v_mov_b32_e32 v33, v2
	v_mov_b32_e32 v34, v2
	v_mov_b32_e32 v35, v2
	v_mov_b32_e32 v36, v2
	v_mov_b32_e32 v37, v2
	v_mov_b32_e32 v38, v2
	v_mov_b32_e32 v39, v2
	v_mov_b32_e32 v40, v2
	v_mov_b32_e32 v41, v2
	v_mov_b32_e32 v42, v2
	v_mov_b32_e32 v43, v2
	v_mov_b32_e32 v44, v2
	v_mov_b32_e32 v45, v2
	v_mov_b32_e32 v46, v2
	v_mov_b32_e32 v47, v2
	v_mov_b32_e32 v48, v2
	v_mov_b32_e32 v49, v2
	v_mov_b32_e32 v50, v2
	v_mov_b32_e32 v51, v2
	v_mov_b32_e32 v52, v2
	v_mov_b32_e32 v53, v2
	v_mov_b32_e32 v54, v2
	v_mov_b32_e32 v55, v2
	v_mov_b32_e32 v56, v2
	v_mov_b32_e32 v57, v2
	v_mov_b32_e32 v58, v2
	v_mov_b32_e32 v59, v2
	v_mov_b32_e32 v60, v2
	v_mov_b32_e32 v61, v2
	v_mov_b32_e32 v62, v2
	v_mov_b32_e32 v63, v2
	v_mov_b32_e32 v64, v2
	v_mov_b32_e32 v65, v2
.LBB0_1714:
	s_waitcnt vmcnt(8)
	s_add_u32 s50, s48, 0x8000
	s_waitcnt lgkmcnt(0)
	s_addc_u32 s51, s49, 0
	s_add_u32 s52, s46, 0x8000
	s_addc_u32 s53, s47, 0
	s_barrier
	s_setprio 1
	s_waitcnt lgkmcnt(7)
	v_mfma_f32_16x16x32_bf16 v[62:65], v[146:149], v[186:189], v[62:65]
	v_mfma_f32_16x16x32_bf16 v[58:61], v[154:157], v[186:189], v[58:61]
	s_waitcnt lgkmcnt(5)
	v_mfma_f32_16x16x32_bf16 v[54:57], v[146:149], v[178:181], v[54:57]
	v_mfma_f32_16x16x32_bf16 v[50:53], v[154:157], v[178:181], v[50:53]
	s_waitcnt lgkmcnt(3)
	v_mfma_f32_16x16x32_bf16 v[46:49], v[146:149], v[170:173], v[46:49]
	v_mfma_f32_16x16x32_bf16 v[42:45], v[154:157], v[170:173], v[42:45]
	s_waitcnt lgkmcnt(1)
	v_mfma_f32_16x16x32_bf16 v[38:41], v[146:149], v[162:165], v[38:41]
	v_mfma_f32_16x16x32_bf16 v[34:37], v[154:157], v[162:165], v[34:37]
	v_mfma_f32_16x16x32_bf16 v[62:65], v[150:153], v[190:193], v[62:65]
	v_mfma_f32_16x16x32_bf16 v[58:61], v[158:161], v[190:193], v[58:61]
	v_mfma_f32_16x16x32_bf16 v[54:57], v[150:153], v[182:185], v[54:57]
	v_mfma_f32_16x16x32_bf16 v[50:53], v[158:161], v[182:185], v[50:53]
	v_mfma_f32_16x16x32_bf16 v[46:49], v[150:153], v[174:177], v[46:49]
	v_mfma_f32_16x16x32_bf16 v[42:45], v[158:161], v[174:177], v[42:45]
	s_waitcnt lgkmcnt(0)
	v_mfma_f32_16x16x32_bf16 v[38:41], v[150:153], v[166:169], v[38:41]
	v_mfma_f32_16x16x32_bf16 v[34:37], v[158:161], v[166:169], v[34:37]
	s_setprio 0
	s_setprio 1
	v_mfma_f32_16x16x32_bf16 v[30:33], v[130:133], v[186:189], v[30:33]
	v_mfma_f32_16x16x32_bf16 v[26:29], v[138:141], v[186:189], v[26:29]
	v_mfma_f32_16x16x32_bf16 v[22:25], v[130:133], v[178:181], v[22:25]
	v_mfma_f32_16x16x32_bf16 v[18:21], v[138:141], v[178:181], v[18:21]
	v_mfma_f32_16x16x32_bf16 v[14:17], v[130:133], v[170:173], v[14:17]
	v_mfma_f32_16x16x32_bf16 v[10:13], v[138:141], v[170:173], v[10:13]
	v_mfma_f32_16x16x32_bf16 v[6:9], v[130:133], v[162:165], v[6:9]
	v_mfma_f32_16x16x32_bf16 v[2:5], v[138:141], v[162:165], v[2:5]
	v_mfma_f32_16x16x32_bf16 v[30:33], v[134:137], v[190:193], v[30:33]
	v_mfma_f32_16x16x32_bf16 v[26:29], v[142:145], v[190:193], v[26:29]
	v_mfma_f32_16x16x32_bf16 v[22:25], v[134:137], v[182:185], v[22:25]
	v_mfma_f32_16x16x32_bf16 v[18:21], v[142:145], v[182:185], v[18:21]
	v_mfma_f32_16x16x32_bf16 v[14:17], v[134:137], v[174:177], v[14:17]
	v_mfma_f32_16x16x32_bf16 v[10:13], v[142:145], v[174:177], v[10:13]
	v_mfma_f32_16x16x32_bf16 v[6:9], v[134:137], v[166:169], v[6:9]
	v_mfma_f32_16x16x32_bf16 v[2:5], v[142:145], v[166:169], v[2:5]
	s_setprio 0
	s_barrier
	v_add_u32_e32 v142, 0x18000, v208
	v_add_u32_e32 v158, 0x1c000, v208
	ds_read_b128 v[130:133], v142
	ds_read_b128 v[134:137], v142 offset:1024
	ds_read_b128 v[138:141], v142 offset:2048
	ds_read_b128 v[142:145], v142 offset:3072
	ds_read_b128 v[146:149], v158
	ds_read_b128 v[150:153], v158 offset:1024
	ds_read_b128 v[154:157], v158 offset:2048
	ds_read_b128 v[158:161], v158 offset:3072
	ds_read_b128 v[162:165], v209 offset:32768
	ds_read_b128 v[166:169], v209 offset:33792
	ds_read_b128 v[170:173], v209 offset:34816
	ds_read_b128 v[174:177], v209 offset:35840
	ds_read_b128 v[178:181], v209 offset:36864
	ds_read_b128 v[182:185], v209 offset:37888
	ds_read_b128 v[186:189], v209 offset:38912
	ds_read_b128 v[190:193], v209 offset:39936
	s_add_u32 s48, s48, 0x4000
	s_addc_u32 s49, s49, 0
	s_mov_b32 m0, s60
	s_nop 0
	global_load_lds_dwordx4 v195, s[48:49]
	s_add_u32 m0, s60, 0x2000
	s_nop 0
	global_load_lds_dwordx4 v203, s[48:49]
	s_waitcnt vmcnt(8)
	s_waitcnt lgkmcnt(0)
	s_barrier
	s_setprio 1
	s_waitcnt lgkmcnt(7)
	v_mfma_f32_16x16x32_bf16 v[126:129], v[130:133], v[162:165], v[126:129]
	v_mfma_f32_16x16x32_bf16 v[122:125], v[138:141], v[162:165], v[122:125]
	s_waitcnt lgkmcnt(5)
	v_mfma_f32_16x16x32_bf16 v[118:121], v[130:133], v[170:173], v[118:121]
	v_mfma_f32_16x16x32_bf16 v[114:117], v[138:141], v[170:173], v[114:117]
	s_waitcnt lgkmcnt(3)
	v_mfma_f32_16x16x32_bf16 v[110:113], v[130:133], v[178:181], v[110:113]
	v_mfma_f32_16x16x32_bf16 v[106:109], v[138:141], v[178:181], v[106:109]
	s_waitcnt lgkmcnt(1)
	v_mfma_f32_16x16x32_bf16 v[102:105], v[130:133], v[186:189], v[102:105]
	v_mfma_f32_16x16x32_bf16 v[98:101], v[138:141], v[186:189], v[98:101]
	v_mfma_f32_16x16x32_bf16 v[126:129], v[134:137], v[166:169], v[126:129]
	v_mfma_f32_16x16x32_bf16 v[122:125], v[142:145], v[166:169], v[122:125]
	v_mfma_f32_16x16x32_bf16 v[118:121], v[134:137], v[174:177], v[118:121]
	v_mfma_f32_16x16x32_bf16 v[114:117], v[142:145], v[174:177], v[114:117]
	v_mfma_f32_16x16x32_bf16 v[110:113], v[134:137], v[182:185], v[110:113]
	v_mfma_f32_16x16x32_bf16 v[106:109], v[142:145], v[182:185], v[106:109]
	s_waitcnt lgkmcnt(0)
	v_mfma_f32_16x16x32_bf16 v[102:105], v[134:137], v[190:193], v[102:105]
	v_mfma_f32_16x16x32_bf16 v[98:101], v[142:145], v[190:193], v[98:101]
	s_setprio 0
	s_setprio 1
	v_mfma_f32_16x16x32_bf16 v[94:97], v[146:149], v[162:165], v[94:97]
	v_mfma_f32_16x16x32_bf16 v[90:93], v[154:157], v[162:165], v[90:93]
	v_mfma_f32_16x16x32_bf16 v[86:89], v[146:149], v[170:173], v[86:89]
	v_mfma_f32_16x16x32_bf16 v[82:85], v[154:157], v[170:173], v[82:85]
	v_mfma_f32_16x16x32_bf16 v[78:81], v[146:149], v[178:181], v[78:81]
	v_mfma_f32_16x16x32_bf16 v[74:77], v[154:157], v[178:181], v[74:77]
	v_mfma_f32_16x16x32_bf16 v[70:73], v[146:149], v[186:189], v[70:73]
	v_mfma_f32_16x16x32_bf16 v[66:69], v[154:157], v[186:189], v[66:69]
	v_mfma_f32_16x16x32_bf16 v[94:97], v[150:153], v[166:169], v[94:97]
	v_mfma_f32_16x16x32_bf16 v[90:93], v[158:161], v[166:169], v[90:93]
	v_mfma_f32_16x16x32_bf16 v[86:89], v[150:153], v[174:177], v[86:89]
	v_mfma_f32_16x16x32_bf16 v[82:85], v[158:161], v[174:177], v[82:85]
	v_mfma_f32_16x16x32_bf16 v[78:81], v[150:153], v[182:185], v[78:81]
	v_mfma_f32_16x16x32_bf16 v[74:77], v[158:161], v[182:185], v[74:77]
	v_mfma_f32_16x16x32_bf16 v[70:73], v[150:153], v[190:193], v[70:73]
	v_mfma_f32_16x16x32_bf16 v[66:69], v[158:161], v[190:193], v[66:69]
	s_setprio 0
	s_barrier
	ds_read_b128 v[162:165], v209 offset:49152
	ds_read_b128 v[166:169], v209 offset:50176
	ds_read_b128 v[170:173], v209 offset:51200
	ds_read_b128 v[174:177], v209 offset:52224
	ds_read_b128 v[178:181], v209 offset:53248
	ds_read_b128 v[182:185], v209 offset:54272
	ds_read_b128 v[186:189], v209 offset:55296
	ds_read_b128 v[190:193], v209 offset:56320
	s_mov_b32 m0, s64
	s_nop 0
	global_load_lds_dwordx4 v195, s[52:53]
	s_add_u32 m0, s64, 0x2000
	s_nop 0
	global_load_lds_dwordx4 v203, s[52:53]
	s_add_u32 s46, s46, 0xc000
	s_addc_u32 s47, s47, 0
	s_mov_b32 m0, s66
	s_nop 0
	global_load_lds_dwordx4 v195, s[46:47]
	s_add_u32 m0, s66, 0x2000
	s_nop 0
	global_load_lds_dwordx4 v203, s[46:47]
	s_nop 0
	s_mov_b32 m0, s65
	s_nop 0
	global_load_lds_dwordx4 v195, s[50:51]
	s_add_u32 m0, s65, 0x2000
	s_nop 0
	global_load_lds_dwordx4 v203, s[50:51]
	s_waitcnt vmcnt(8)
	s_waitcnt lgkmcnt(0)
	s_barrier
	s_setprio 1
	s_waitcnt lgkmcnt(7)
	v_mfma_f32_16x16x32_bf16 v[62:65], v[130:133], v[162:165], v[62:65]
	v_mfma_f32_16x16x32_bf16 v[58:61], v[138:141], v[162:165], v[58:61]
	s_waitcnt lgkmcnt(5)
	v_mfma_f32_16x16x32_bf16 v[54:57], v[130:133], v[170:173], v[54:57]
	v_mfma_f32_16x16x32_bf16 v[50:53], v[138:141], v[170:173], v[50:53]
	s_waitcnt lgkmcnt(3)
	v_mfma_f32_16x16x32_bf16 v[46:49], v[130:133], v[178:181], v[46:49]
	v_mfma_f32_16x16x32_bf16 v[42:45], v[138:141], v[178:181], v[42:45]
	s_waitcnt lgkmcnt(1)
	v_mfma_f32_16x16x32_bf16 v[38:41], v[130:133], v[186:189], v[38:41]
	v_mfma_f32_16x16x32_bf16 v[34:37], v[138:141], v[186:189], v[34:37]
	v_mfma_f32_16x16x32_bf16 v[62:65], v[134:137], v[166:169], v[62:65]
	v_mfma_f32_16x16x32_bf16 v[58:61], v[142:145], v[166:169], v[58:61]
	v_mfma_f32_16x16x32_bf16 v[54:57], v[134:137], v[174:177], v[54:57]
	v_mfma_f32_16x16x32_bf16 v[50:53], v[142:145], v[174:177], v[50:53]
	v_mfma_f32_16x16x32_bf16 v[46:49], v[134:137], v[182:185], v[46:49]
	v_mfma_f32_16x16x32_bf16 v[42:45], v[142:145], v[182:185], v[42:45]
	s_waitcnt lgkmcnt(0)
	v_mfma_f32_16x16x32_bf16 v[38:41], v[134:137], v[190:193], v[38:41]
	v_mfma_f32_16x16x32_bf16 v[34:37], v[142:145], v[190:193], v[34:37]
	s_setprio 0
	s_setprio 1
	v_mfma_f32_16x16x32_bf16 v[30:33], v[146:149], v[162:165], v[30:33]
	v_mfma_f32_16x16x32_bf16 v[26:29], v[154:157], v[162:165], v[26:29]
	v_mfma_f32_16x16x32_bf16 v[22:25], v[146:149], v[170:173], v[22:25]
	v_mfma_f32_16x16x32_bf16 v[18:21], v[154:157], v[170:173], v[18:21]
	v_mfma_f32_16x16x32_bf16 v[14:17], v[146:149], v[178:181], v[14:17]
	v_mfma_f32_16x16x32_bf16 v[10:13], v[154:157], v[178:181], v[10:13]
	v_mfma_f32_16x16x32_bf16 v[6:9], v[146:149], v[186:189], v[6:9]
	v_mfma_f32_16x16x32_bf16 v[2:5], v[154:157], v[186:189], v[2:5]
	v_mfma_f32_16x16x32_bf16 v[30:33], v[150:153], v[166:169], v[30:33]
	v_mfma_f32_16x16x32_bf16 v[26:29], v[158:161], v[166:169], v[26:29]
	v_mfma_f32_16x16x32_bf16 v[22:25], v[150:153], v[174:177], v[22:25]
	v_mfma_f32_16x16x32_bf16 v[18:21], v[158:161], v[174:177], v[18:21]
	v_mfma_f32_16x16x32_bf16 v[14:17], v[150:153], v[182:185], v[14:17]
	v_mfma_f32_16x16x32_bf16 v[10:13], v[158:161], v[182:185], v[10:13]
	v_mfma_f32_16x16x32_bf16 v[6:9], v[150:153], v[190:193], v[6:9]
	v_mfma_f32_16x16x32_bf16 v[2:5], v[158:161], v[190:193], v[2:5]
	s_setprio 0
	s_barrier
	s_add_i32 s13, s77, 2
	s_cmp_gt_u32 s77, 13
	s_cbranch_scc1 .LBB0_1716
	s_mov_b32 s77, s13
	s_branch .LBB0_1693

.LBB0_1718:
	v_mov_b32_e32 v130, v204
	v_mov_b32_e32 v178, v210
	s_lshl_b32 s13, s73, 8
	s_add_i32 s13, s13, s61
	v_add_u32_e32 v144, s13, v130
	v_lshlrev_b32_e32 v130, 2, v178
	v_ashrrev_i32_e32 v131, 31, v130
	v_ashrrev_i32_e32 v145, 31, v144
	v_lshl_add_u64 v[174:175], v[130:131], 2, s[2:3]
	v_lshlrev_b64 v[130:131], 6, v[144:145]
	v_lshl_add_u64 v[130:131], v[174:175], 0, v[130:131]
	v_add_u32_e32 v138, 48, v144
	v_lshl_add_u64 v[180:181], v[130:131], 0, 0
	global_load_dwordx4 v[146:149], v[130:131], off
	s_mov_b32 s98, 0x1000
	s_mov_b32 s99, 0x0
	v_lshl_add_u64 v[182:183], v[180:181], 0, s[98:99]
	global_load_dwordx4 v[150:153], v[182:183], off offset:-3072
	v_ashrrev_i32_e32 v139, 31, v138
	global_load_dwordx4 v[154:157], v[182:183], off offset:-2048
	global_load_dwordx4 v[158:161], v[182:183], off offset:-1024
	s_mov_b32 s98, 0x3000
	s_mov_b32 s99, 0x0
	v_lshl_add_u64 v[182:183], v[180:181], 0, s[98:99]
	global_load_dwordx4 v[162:165], v[182:183], off offset:-4096
	global_load_dwordx4 v[166:169], v[182:183], off offset:-3072
	v_add_u32_e32 v132, 0xa0, v144
	global_load_dwordx4 v[170:173], v[182:183], off offset:-2048
	v_add_u32_e32 v130, 0xb0, v144
	global_load_dwordx4 v[174:177], v[182:183], off offset:-1024
	s_lshl_b32 s13, s10, 8
	v_and_b32_e32 v133, 64, v206
	v_xor_b32_e32 v135, 16, v206
	s_or_b32 s13, s13, s63
	v_add_u32_e32 v133, 64, v133
	v_lshl_add_u32 v137, v178, 3, s13
	v_cmp_lt_i32_e32 vcc, v135, v133
	v_xor_b32_e32 v131, 32, v206
	s_waitcnt vmcnt(7)
	v_mov_b32_e32 v178, v147
	v_mov_b32_e32 v179, v148
	v_mov_b32_e32 v147, v149
	v_cndmask_b32_e32 v135, v206, v135, vcc
	v_pk_add_f32 v[146:147], v[178:179], v[146:147]
	s_waitcnt vmcnt(6)
	v_mov_b32_e32 v148, v151
	v_mov_b32_e32 v149, v152
	v_mov_b32_e32 v151, v153
	s_waitcnt vmcnt(5)
	v_mov_b32_e32 v152, v155
	v_mov_b32_e32 v153, v156
	v_mov_b32_e32 v155, v157
	v_cmp_lt_i32_e32 vcc, v131, v133
	v_lshlrev_b32_e32 v133, 2, v135
	v_add_f32_e32 v135, v146, v147
	v_pk_add_f32 v[146:147], v[148:149], v[150:151]
	v_pk_add_f32 v[148:149], v[152:153], v[154:155]
	v_add_f32_e32 v141, v146, v147
	v_add_f32_e32 v143, v148, v149
	ds_bpermute_b32 v139, v133, v135
	ds_bpermute_b32 v146, v133, v141
	ds_bpermute_b32 v147, v133, v143
	v_cndmask_b32_e32 v131, v206, v131, vcc
	s_waitcnt vmcnt(4)
	v_mov_b32_e32 v156, v159
	v_mov_b32_e32 v157, v160
	v_mov_b32_e32 v159, v161
	v_lshlrev_b32_e32 v131, 2, v131
	v_pk_add_f32 v[150:151], v[156:157], v[158:159]
	s_waitcnt lgkmcnt(2)
	v_add_f32_e32 v135, v135, v139
	s_waitcnt lgkmcnt(1)
	v_add_f32_e32 v141, v141, v146
	s_waitcnt lgkmcnt(0)
	v_add_f32_e32 v143, v143, v147
	v_add_f32_e32 v145, v150, v151
	ds_bpermute_b32 v139, v131, v135
	ds_bpermute_b32 v146, v131, v141
	ds_bpermute_b32 v147, v131, v143
	ds_bpermute_b32 v148, v133, v145
	s_waitcnt vmcnt(3)
	v_mov_b32_e32 v160, v163
	v_mov_b32_e32 v161, v164
	v_mov_b32_e32 v163, v165
	v_pk_add_f32 v[152:153], v[160:161], v[162:163]
	s_waitcnt lgkmcnt(3)
	v_add_f32_e32 v135, v135, v139
	s_waitcnt lgkmcnt(2)
	v_add_f32_e32 v139, v141, v146
	s_waitcnt lgkmcnt(1)
	v_add_f32_e32 v141, v143, v147
	v_add_f32_e32 v143, v152, v153
	s_waitcnt lgkmcnt(0)
	v_add_f32_e32 v145, v145, v148
	ds_bpermute_b32 v146, v133, v143
	ds_bpermute_b32 v148, v131, v145
	s_waitcnt vmcnt(2)
	v_mov_b32_e32 v147, v168
	v_fmamk_f32 v135, v135, 0x3a800000, v207
	v_rsq_f32_e32 v135, v135
	s_waitcnt lgkmcnt(1)
	v_add_f32_e32 v143, v143, v146
	v_mov_b32_e32 v146, v167
	v_mov_b32_e32 v167, v169
	s_waitcnt lgkmcnt(0)
	v_add_f32_e32 v145, v145, v148
	ds_bpermute_b32 v148, v131, v143
	v_pk_add_f32 v[146:147], v[146:147], v[166:167]
	v_fmamk_f32 v145, v145, 0x3a800000, v207
	v_add_f32_e32 v146, v146, v147
	ds_bpermute_b32 v147, v133, v146
	s_waitcnt lgkmcnt(1)
	v_add_f32_e32 v143, v143, v148
	v_fmamk_f32 v143, v143, 0x3a800000, v207
	v_rsq_f32_e32 v155, v143
	v_rsq_f32_e32 v154, v145
	s_waitcnt lgkmcnt(0)
	v_add_f32_e32 v143, v146, v147
	s_waitcnt vmcnt(1)
	v_mov_b32_e32 v146, v171
	v_mov_b32_e32 v147, v172
	v_mov_b32_e32 v171, v173
	v_pk_add_f32 v[146:147], v[146:147], v[170:171]
	ds_bpermute_b32 v145, v131, v143
	v_add_f32_e32 v148, v146, v147
	ds_bpermute_b32 v149, v133, v148
	s_waitcnt vmcnt(0)
	v_mov_b32_e32 v146, v175
	v_mov_b32_e32 v147, v176
	v_mov_b32_e32 v175, v177
	v_pk_add_f32 v[146:147], v[146:147], v[174:175]
	s_waitcnt lgkmcnt(1)
	v_add_f32_e32 v143, v143, v145
	v_add_f32_e32 v146, v146, v147
	ds_bpermute_b32 v133, v133, v146
	s_waitcnt lgkmcnt(1)
	v_add_f32_e32 v145, v148, v149
	ds_bpermute_b32 v147, v131, v145
	v_fmamk_f32 v143, v143, 0x3a800000, v207
	v_rsq_f32_e32 v156, v143
	s_waitcnt lgkmcnt(1)
	v_add_f32_e32 v133, v146, v133
	ds_bpermute_b32 v131, v131, v133
	s_waitcnt lgkmcnt(1)
	v_add_f32_e32 v143, v145, v147
	v_fmamk_f32 v143, v143, 0x3a800000, v207
	v_rsq_f32_e32 v157, v143
	v_bfe_u32 v158, v137, 5, 1
	v_lshrrev_b32_e32 v143, 3, v144
	v_and_or_b32 v143, v143, 14, v158
	s_waitcnt lgkmcnt(0)
	v_add_f32_e32 v131, v133, v131
	v_lshlrev_b32_e32 v133, 1, v137
	v_lshlrev_b32_e32 v145, 6, v144
	v_lshlrev_b32_e32 v160, 10, v143
	v_lshlrev_b32_e32 v143, 2, v144
	v_and_b32_e32 v159, 48, v133
	v_mul_f32_e32 v148, 0x3db8aa3b, v135
	v_and_b32_e32 v145, 0x3c0, v145
	v_and_b32_e32 v143, 32, v143
	v_ashrrev_i32_e32 v133, 4, v144
	v_lshlrev_b32_e32 v135, 7, v144
	v_bitop3_b32 v143, v159, v143, v145 bitop3:0x36
	v_pk_mul_f32 v[146:147], v[128:129], v[148:149] op_sel_hi:[1,0]
	v_pk_mul_f32 v[144:145], v[126:127], v[148:149] op_sel_hi:[1,0]
	v_pk_mul_f32 v[152:153], v[122:123], v[148:149] op_sel_hi:[1,0]
	v_and_b32_e32 v133, -16, v133
	v_pk_mul_f32 v[150:151], v[124:125], v[148:149] op_sel_hi:[1,0]
	v_cvt_pk_bf16_f32 v144, v144, v145
	v_cvt_pk_bf16_f32 v145, v146, v147
	v_cvt_pk_bf16_f32 v146, v152, v153
	v_ashrrev_i32_e32 v152, 6, v137
	v_cvt_pk_bf16_f32 v147, v150, v151
	v_add_u32_e32 v150, v152, v133
	v_ashrrev_i32_e32 v151, 31, v150
	v_and_b32_e32 v135, 0x4000, v135
	v_lshlrev_b64 v[150:151], 15, v[150:151]
	v_or3_b32 v198, v135, v143, v160
	v_lshl_add_u64 v[150:151], s[20:21], 0, v[150:151]
	v_lshl_add_u64 v[150:151], v[150:151], 0, v[198:199]
	v_add_u32_e32 v135, 0x80, v137
	v_lshl_add_u64 v[180:181], v[150:151], 0, 0
	global_store_dwordx4 v[150:151], v[144:147], off
	v_pk_mul_f32 v[150:151], v[92:93], v[148:149] op_sel_hi:[1,0]
	v_ashrrev_i32_e32 v153, 6, v135
	v_pk_mul_f32 v[146:147], v[96:97], v[148:149] op_sel_hi:[1,0]
	v_pk_mul_f32 v[144:145], v[94:95], v[148:149] op_sel_hi:[1,0]
	v_pk_mul_f32 v[148:149], v[90:91], v[148:149] op_sel_hi:[1,0]
	v_fmamk_f32 v139, v139, 0x3a800000, v207
	v_cvt_pk_bf16_f32 v144, v144, v145
	v_cvt_pk_bf16_f32 v145, v146, v147
	v_cvt_pk_bf16_f32 v146, v148, v149
	v_rsq_f32_e32 v139, v139
	s_nop 0
	s_nop 0
	s_nop 0
	v_cvt_pk_bf16_f32 v147, v150, v151
	s_nop 0
	s_mov_b32 s98, 0x11000
	s_mov_b32 s99, 0x0
	v_lshl_add_u64 v[182:183], v[180:181], 0, s[98:99]
	global_store_dwordx4 v[182:183], v[144:147], off offset:-4096
	s_nop 0
	s_nop 0
	v_mul_f32_e32 v146, 0x3db8aa3b, v139
	s_nop 0
	s_nop 0
	v_pk_mul_f32 v[144:145], v[120:121], v[146:147] op_sel_hi:[1,0]
	v_pk_mul_f32 v[142:143], v[118:119], v[146:147] op_sel_hi:[1,0]
	v_pk_mul_f32 v[148:149], v[116:117], v[146:147] op_sel_hi:[1,0]
	v_cvt_pk_bf16_f32 v142, v142, v143
	v_cvt_pk_bf16_f32 v143, v144, v145
	v_cvt_pk_bf16_f32 v145, v148, v149
	v_pk_mul_f32 v[150:151], v[114:115], v[146:147] op_sel_hi:[1,0]
	v_cvt_pk_bf16_f32 v144, v150, v151
	s_mov_b32 s98, 0x1000
	s_mov_b32 s99, 0x0
	v_lshl_add_u64 v[184:185], v[180:181], 0, s[98:99]
	global_store_dwordx4 v[184:185], v[142:145], off offset:-2048
	v_pk_mul_f32 v[148:149], v[84:85], v[146:147] op_sel_hi:[1,0]
	v_fmamk_f32 v141, v141, 0x3a800000, v207
	v_pk_mul_f32 v[144:145], v[88:89], v[146:147] op_sel_hi:[1,0]
	v_pk_mul_f32 v[142:143], v[86:87], v[146:147] op_sel_hi:[1,0]
	v_pk_mul_f32 v[146:147], v[82:83], v[146:147] op_sel_hi:[1,0]
	v_cvt_pk_bf16_f32 v142, v142, v143
	v_cvt_pk_bf16_f32 v143, v144, v145
	v_cvt_pk_bf16_f32 v144, v146, v147
	v_rsq_f32_e32 v141, v141
	s_nop 0
	s_nop 0
	s_nop 0
	v_cvt_pk_bf16_f32 v145, v148, v149
	s_nop 0
	global_store_dwordx4 v[182:183], v[142:145], off offset:-2048
	s_nop 0
	s_nop 0
	v_mul_f32_e32 v144, 0x3db8aa3b, v141
	s_nop 0
	s_nop 0
	v_pk_mul_f32 v[142:143], v[112:113], v[144:145] op_sel_hi:[1,0]
	v_pk_mul_f32 v[140:141], v[110:111], v[144:145] op_sel_hi:[1,0]
	v_pk_mul_f32 v[146:147], v[108:109], v[144:145] op_sel_hi:[1,0]
	v_cvt_pk_bf16_f32 v140, v140, v141
	v_cvt_pk_bf16_f32 v141, v142, v143
	v_cvt_pk_bf16_f32 v143, v146, v147
	v_pk_mul_f32 v[148:149], v[106:107], v[144:145] op_sel_hi:[1,0]
	v_cvt_pk_bf16_f32 v142, v148, v149
	global_store_dwordx4 v[184:185], v[140:143], off
	v_pk_mul_f32 v[146:147], v[76:77], v[144:145] op_sel_hi:[1,0]
	s_nop 0
	v_pk_mul_f32 v[142:143], v[80:81], v[144:145] op_sel_hi:[1,0]
	v_pk_mul_f32 v[140:141], v[78:79], v[144:145] op_sel_hi:[1,0]
	v_pk_mul_f32 v[144:145], v[74:75], v[144:145] op_sel_hi:[1,0]
	v_cvt_pk_bf16_f32 v140, v140, v141
	v_cvt_pk_bf16_f32 v141, v142, v143
	v_cvt_pk_bf16_f32 v142, v144, v145
	v_cvt_pk_bf16_f32 v143, v146, v147
	global_store_dwordx4 v[182:183], v[140:143], off
	s_nop 0
	s_nop 0
	v_mul_f32_e32 v142, 0x3db8aa3b, v154
	s_nop 0
	s_nop 0
	v_pk_mul_f32 v[140:141], v[104:105], v[142:143] op_sel_hi:[1,0]
	v_pk_mul_f32 v[138:139], v[102:103], v[142:143] op_sel_hi:[1,0]
	v_pk_mul_f32 v[144:145], v[100:101], v[142:143] op_sel_hi:[1,0]
	v_cvt_pk_bf16_f32 v138, v138, v139
	v_cvt_pk_bf16_f32 v139, v140, v141
	v_cvt_pk_bf16_f32 v141, v144, v145
	v_pk_mul_f32 v[146:147], v[98:99], v[142:143] op_sel_hi:[1,0]
	v_cvt_pk_bf16_f32 v140, v146, v147
	global_store_dwordx4 v[184:185], v[138:141], off offset:2048
	v_pk_mul_f32 v[144:145], v[68:69], v[142:143] op_sel_hi:[1,0]
	s_nop 0
	v_pk_mul_f32 v[140:141], v[72:73], v[142:143] op_sel_hi:[1,0]
	v_pk_mul_f32 v[138:139], v[70:71], v[142:143] op_sel_hi:[1,0]
	v_pk_mul_f32 v[142:143], v[66:67], v[142:143] op_sel_hi:[1,0]
	v_cvt_pk_bf16_f32 v138, v138, v139
	v_cvt_pk_bf16_f32 v139, v140, v141
	v_cvt_pk_bf16_f32 v140, v142, v143
	v_cvt_pk_bf16_f32 v141, v144, v145
	global_store_dwordx4 v[182:183], v[138:141], off offset:2048
	s_nop 0
	s_nop 0
	v_mul_f32_e32 v140, 0x3db8aa3b, v155
	s_nop 0
	s_nop 0
	v_pk_mul_f32 v[138:139], v[64:65], v[140:141] op_sel_hi:[1,0]
	v_pk_mul_f32 v[136:137], v[62:63], v[140:141] op_sel_hi:[1,0]
	v_pk_mul_f32 v[142:143], v[60:61], v[140:141] op_sel_hi:[1,0]
	v_cvt_pk_bf16_f32 v136, v136, v137
	v_cvt_pk_bf16_f32 v137, v138, v139
	v_cvt_pk_bf16_f32 v139, v142, v143
	v_pk_mul_f32 v[144:145], v[58:59], v[140:141] op_sel_hi:[1,0]
	v_cvt_pk_bf16_f32 v138, v144, v145
	s_mov_b32 s98, 0x5000
	s_mov_b32 s99, 0x0
	v_lshl_add_u64 v[182:183], v[180:181], 0, s[98:99]
	global_store_dwordx4 v[182:183], v[136:139], off offset:-4096
	v_pk_mul_f32 v[142:143], v[28:29], v[140:141] op_sel_hi:[1,0]
	s_nop 0
	v_pk_mul_f32 v[138:139], v[32:33], v[140:141] op_sel_hi:[1,0]
	v_pk_mul_f32 v[136:137], v[30:31], v[140:141] op_sel_hi:[1,0]
	v_pk_mul_f32 v[140:141], v[26:27], v[140:141] op_sel_hi:[1,0]
	v_cvt_pk_bf16_f32 v136, v136, v137
	v_cvt_pk_bf16_f32 v137, v138, v139
	v_cvt_pk_bf16_f32 v138, v140, v141
	v_cvt_pk_bf16_f32 v139, v142, v143
	s_mov_b32 s98, 0x15000
	s_mov_b32 s99, 0x0
	v_lshl_add_u64 v[184:185], v[180:181], 0, s[98:99]
	global_store_dwordx4 v[184:185], v[136:139], off offset:-4096
	s_nop 0
	s_nop 0
	s_nop 0
	s_nop 0
	s_nop 0
	v_mul_f32_e32 v138, 0x3db8aa3b, v156
	v_pk_mul_f32 v[136:137], v[56:57], v[138:139] op_sel_hi:[1,0]
	v_pk_mul_f32 v[134:135], v[54:55], v[138:139] op_sel_hi:[1,0]
	v_pk_mul_f32 v[140:141], v[52:53], v[138:139] op_sel_hi:[1,0]
	v_cvt_pk_bf16_f32 v134, v134, v135
	v_cvt_pk_bf16_f32 v135, v136, v137
	v_cvt_pk_bf16_f32 v137, v140, v141
	v_pk_mul_f32 v[142:143], v[50:51], v[138:139] op_sel_hi:[1,0]
	v_cvt_pk_bf16_f32 v136, v142, v143
	global_store_dwordx4 v[182:183], v[134:137], off offset:-2048
	v_pk_mul_f32 v[140:141], v[20:21], v[138:139] op_sel_hi:[1,0]
	v_fmamk_f32 v131, v131, 0x3a800000, v207
	v_pk_mul_f32 v[136:137], v[24:25], v[138:139] op_sel_hi:[1,0]
	v_pk_mul_f32 v[134:135], v[22:23], v[138:139] op_sel_hi:[1,0]
	v_pk_mul_f32 v[138:139], v[18:19], v[138:139] op_sel_hi:[1,0]
	v_cvt_pk_bf16_f32 v134, v134, v135
	v_cvt_pk_bf16_f32 v135, v136, v137
	v_cvt_pk_bf16_f32 v136, v138, v139
	v_cvt_pk_bf16_f32 v137, v140, v141
	v_ashrrev_i32_e32 v133, 4, v132
	global_store_dwordx4 v[184:185], v[134:137], off offset:-2048
	v_and_b32_e32 v142, -16, v133
	s_nop 0
	s_nop 0
	s_nop 0
	s_nop 0
	v_mul_f32_e32 v136, 0x3db8aa3b, v157
	v_pk_mul_f32 v[134:135], v[48:49], v[136:137] op_sel_hi:[1,0]
	v_pk_mul_f32 v[132:133], v[46:47], v[136:137] op_sel_hi:[1,0]
	v_pk_mul_f32 v[138:139], v[44:45], v[136:137] op_sel_hi:[1,0]
	v_cvt_pk_bf16_f32 v132, v132, v133
	v_cvt_pk_bf16_f32 v133, v134, v135
	v_cvt_pk_bf16_f32 v135, v138, v139
	v_pk_mul_f32 v[140:141], v[42:43], v[136:137] op_sel_hi:[1,0]
	v_cvt_pk_bf16_f32 v134, v140, v141
	global_store_dwordx4 v[182:183], v[132:135], off
	v_pk_mul_f32 v[138:139], v[12:13], v[136:137] op_sel_hi:[1,0]
	v_rsq_f32_e32 v131, v131
	v_pk_mul_f32 v[134:135], v[16:17], v[136:137] op_sel_hi:[1,0]
	v_pk_mul_f32 v[132:133], v[14:15], v[136:137] op_sel_hi:[1,0]
	v_pk_mul_f32 v[136:137], v[10:11], v[136:137] op_sel_hi:[1,0]
	v_cvt_pk_bf16_f32 v132, v132, v133
	v_cvt_pk_bf16_f32 v133, v134, v135
	v_cvt_pk_bf16_f32 v134, v136, v137
	v_cvt_pk_bf16_f32 v135, v138, v139
	global_store_dwordx4 v[184:185], v[132:135], off
	s_andn2_b64 vcc, exec, s[40:41]
	s_nop 0
	v_mul_f32_e32 v134, 0x3db8aa3b, v131
	v_ashrrev_i32_e32 v131, 4, v130
	v_and_b32_e32 v140, -16, v131
	v_lshlrev_b32_e32 v131, 7, v130
	v_lshrrev_b32_e32 v132, 3, v130
	v_lshlrev_b32_e32 v133, 6, v130
	v_lshlrev_b32_e32 v130, 2, v130
	v_and_or_b32 v132, v132, 14, v158
	v_and_b32_e32 v133, 0x3c0, v133
	v_and_b32_e32 v130, 32, v130
	v_and_b32_e32 v131, 0x4000, v131
	v_lshlrev_b32_e32 v132, 10, v132
	v_bitop3_b32 v130, v133, v130, v159 bitop3:0x36
	v_or3_b32 v198, v132, v131, v130
	v_pk_mul_f32 v[132:133], v[40:41], v[134:135] op_sel_hi:[1,0]
	v_pk_mul_f32 v[130:131], v[38:39], v[134:135] op_sel_hi:[1,0]
	v_pk_mul_f32 v[136:137], v[36:37], v[134:135] op_sel_hi:[1,0]
	v_cvt_pk_bf16_f32 v130, v130, v131
	v_cvt_pk_bf16_f32 v131, v132, v133
	v_cvt_pk_bf16_f32 v133, v136, v137
	v_pk_mul_f32 v[138:139], v[34:35], v[134:135] op_sel_hi:[1,0]
	v_cvt_pk_bf16_f32 v132, v138, v139
	global_store_dwordx4 v[182:183], v[130:133], off offset:2048
	v_pk_mul_f32 v[136:137], v[4:5], v[134:135] op_sel_hi:[1,0]
	s_nop 0
	v_pk_mul_f32 v[132:133], v[8:9], v[134:135] op_sel_hi:[1,0]
	v_pk_mul_f32 v[130:131], v[6:7], v[134:135] op_sel_hi:[1,0]
	v_pk_mul_f32 v[134:135], v[2:3], v[134:135] op_sel_hi:[1,0]
	v_cvt_pk_bf16_f32 v130, v130, v131
	v_cvt_pk_bf16_f32 v131, v132, v133
	v_cvt_pk_bf16_f32 v132, v134, v135
	v_add_u32_e32 v134, v153, v140
	v_ashrrev_i32_e32 v135, 31, v134
	v_lshlrev_b64 v[134:135], 15, v[134:135]
	v_lshl_add_u64 v[134:135], s[20:21], 0, v[134:135]
	v_cvt_pk_bf16_f32 v133, v136, v137
	v_lshl_add_u64 v[134:135], v[134:135], 0, v[198:199]
	global_store_dwordx4 v[184:185], v[130:133], off offset:2048
	s_cbranch_vccnz .LBB0_1679
	s_andn2_b64 vcc, exec, s[18:19]
	s_cbranch_vccnz .LBB0_1678
	s_barrier
	s_branch .LBB0_1678

.LBB0_1918:
	s_xor_b64 s[30:31], s[24:25], -1
	s_add_u32 s75, s6, 0x20000
	s_addc_u32 s76, s7, 0
	s_ashr_i32 s29, s28, 31
	s_lshl_b64 s[10:11], s[28:29], 19
	s_add_u32 s38, s52, s10
	s_addc_u32 s39, s53, s11
	s_and_b64 s[10:11], s[24:25], exec
	s_cselect_b32 s20, s39, s17
	s_cselect_b32 s29, s38, s16
	s_ashr_i32 s27, s26, 31
	s_lshl_b64 s[10:11], s[26:27], 19
	s_waitcnt lgkmcnt(0)
	ds_read_b128 v[2:5], v201
	ds_read_b128 v[6:9], v201 offset:1024
	ds_read_b128 v[10:13], v201 offset:2048
	ds_read_b128 v[14:17], v201 offset:3072
	ds_read_b128 v[18:21], v202
	ds_read_b128 v[22:25], v202 offset:1024
	ds_read_b128 v[26:29], v202 offset:2048
	ds_read_b128 v[30:33], v202 offset:3072
	s_add_u32 s40, s54, s10
	s_addc_u32 s41, s55, s11
	s_and_b64 s[10:11], s[24:25], exec
	s_cselect_b32 s27, s41, s7
	s_cselect_b32 s48, s40, s6
	s_add_u32 s44, s16, 0x10000
	s_addc_u32 s45, s17, 0
	s_add_u32 s50, s6, 0x10000
	s_addc_u32 s51, s7, 0
	s_add_u32 s10, s16, 0x18000
	s_addc_u32 s11, s17, 0
	s_add_u32 s42, s6, 0x18000
	s_addc_u32 s43, s7, 0
	ds_read_b128 v[34:37], v203
	ds_read_b128 v[38:41], v203 offset:1024
	ds_read_b128 v[42:45], v203 offset:2048
	ds_read_b128 v[46:49], v203 offset:3072
	ds_read_b128 v[50:53], v203 offset:4096
	ds_read_b128 v[54:57], v203 offset:5120
	ds_read_b128 v[58:61], v203 offset:6144
	ds_read_b128 v[62:65], v203 offset:7168
	s_add_u32 s78, s16, 0xc000
	s_addc_u32 s79, s17, 0
	s_mov_b32 m0, s65
	s_nop 0
	global_load_lds_dwordx4 v195, s[78:79]
	s_add_u32 m0, s65, 0x2000
	s_nop 0
	global_load_lds_dwordx4 v197, s[78:79]
	s_waitcnt vmcnt(8)
	s_waitcnt lgkmcnt(0)
	s_barrier
	s_setprio 1
	s_waitcnt lgkmcnt(1)
	v_mfma_f32_16x16x32_bf16 v[90:93], v[2:5], v[58:61], 0
	v_mfma_f32_16x16x32_bf16 v[66:69], v[2:5], v[34:37], 0
	v_mfma_f32_16x16x32_bf16 v[70:73], v[10:13], v[34:37], 0
	v_mfma_f32_16x16x32_bf16 v[74:77], v[2:5], v[42:45], 0
	v_mfma_f32_16x16x32_bf16 v[78:81], v[10:13], v[42:45], 0
	v_mfma_f32_16x16x32_bf16 v[82:85], v[2:5], v[50:53], 0
	v_mfma_f32_16x16x32_bf16 v[86:89], v[10:13], v[50:53], 0
	s_waitcnt lgkmcnt(0)
	v_mfma_f32_16x16x32_bf16 v[98:101], v[6:9], v[62:65], v[90:93]
	v_mfma_f32_16x16x32_bf16 v[90:93], v[10:13], v[58:61], 0
	v_mfma_f32_16x16x32_bf16 v[66:69], v[6:9], v[38:41], v[66:69]
	v_mfma_f32_16x16x32_bf16 v[70:73], v[14:17], v[38:41], v[70:73]
	v_mfma_f32_16x16x32_bf16 v[74:77], v[6:9], v[46:49], v[74:77]
	v_mfma_f32_16x16x32_bf16 v[78:81], v[14:17], v[46:49], v[78:81]
	v_mfma_f32_16x16x32_bf16 v[82:85], v[6:9], v[54:57], v[82:85]
	v_mfma_f32_16x16x32_bf16 v[86:89], v[14:17], v[54:57], v[86:89]
	v_mfma_f32_16x16x32_bf16 v[102:105], v[14:17], v[62:65], v[90:93]
	s_setprio 0
	s_setprio 1
	v_mfma_f32_16x16x32_bf16 v[90:93], v[18:21], v[34:37], 0
	v_mfma_f32_16x16x32_bf16 v[34:37], v[26:29], v[34:37], 0
	v_mfma_f32_16x16x32_bf16 v[114:117], v[22:25], v[38:41], v[90:93]
	v_mfma_f32_16x16x32_bf16 v[34:37], v[30:33], v[38:41], v[34:37]
	v_mfma_f32_16x16x32_bf16 v[38:41], v[18:21], v[42:45], 0
	v_mfma_f32_16x16x32_bf16 v[42:45], v[26:29], v[42:45], 0
	v_mfma_f32_16x16x32_bf16 v[38:41], v[22:25], v[46:49], v[38:41]
	v_mfma_f32_16x16x32_bf16 v[42:45], v[30:33], v[46:49], v[42:45]
	v_mfma_f32_16x16x32_bf16 v[46:49], v[18:21], v[50:53], 0
	v_mfma_f32_16x16x32_bf16 v[50:53], v[26:29], v[50:53], 0
	v_mfma_f32_16x16x32_bf16 v[46:49], v[22:25], v[54:57], v[46:49]
	v_mfma_f32_16x16x32_bf16 v[50:53], v[30:33], v[54:57], v[50:53]
	v_mfma_f32_16x16x32_bf16 v[54:57], v[18:21], v[58:61], 0
	v_mfma_f32_16x16x32_bf16 v[58:61], v[26:29], v[58:61], 0
	v_mfma_f32_16x16x32_bf16 v[54:57], v[22:25], v[62:65], v[54:57]
	v_mfma_f32_16x16x32_bf16 v[58:61], v[30:33], v[62:65], v[58:61]
	s_setprio 0
	s_barrier
	ds_read_b128 v[62:65], v203 offset:16384
	ds_read_b128 v[90:93], v203 offset:17408
	ds_read_b128 v[94:97], v203 offset:18432
	ds_read_b128 v[106:109], v203 offset:19456
	ds_read_b128 v[110:113], v203 offset:20480
	ds_read_b128 v[118:121], v203 offset:21504
	ds_read_b128 v[122:125], v203 offset:22528
	ds_read_b128 v[126:129], v203 offset:23552
	s_mov_b32 m0, s13
	s_nop 0
	global_load_lds_dwordx4 v195, s[50:51]
	s_add_u32 m0, s13, 0x2000
	s_nop 0
	global_load_lds_dwordx4 v197, s[50:51]
	s_add_u32 s50, s6, 0x14000
	s_addc_u32 s51, s7, 0
	s_mov_b32 m0, s57
	s_nop 0
	global_load_lds_dwordx4 v195, s[50:51]
	s_add_u32 m0, s57, 0x2000
	s_nop 0
	global_load_lds_dwordx4 v197, s[50:51]
	s_nop 0
	s_mov_b32 m0, s56
	s_nop 0
	global_load_lds_dwordx4 v195, s[44:45]
	s_add_u32 m0, s56, 0x2000
	s_nop 0
	global_load_lds_dwordx4 v197, s[44:45]
	s_waitcnt vmcnt(8)
	s_waitcnt lgkmcnt(0)
	s_barrier
	s_setprio 1
	s_waitcnt lgkmcnt(7)
	v_mfma_f32_16x16x32_bf16 v[130:133], v[2:5], v[62:65], 0
	s_waitcnt lgkmcnt(6)
	v_mfma_f32_16x16x32_bf16 v[134:137], v[6:9], v[90:93], v[130:133]
	v_mfma_f32_16x16x32_bf16 v[130:133], v[10:13], v[62:65], 0
	v_mfma_f32_16x16x32_bf16 v[138:141], v[14:17], v[90:93], v[130:133]
	s_waitcnt lgkmcnt(5)
	v_mfma_f32_16x16x32_bf16 v[130:133], v[2:5], v[94:97], 0
	s_waitcnt lgkmcnt(4)
	v_mfma_f32_16x16x32_bf16 v[142:145], v[6:9], v[106:109], v[130:133]
	v_mfma_f32_16x16x32_bf16 v[130:133], v[10:13], v[94:97], 0
	v_mfma_f32_16x16x32_bf16 v[146:149], v[14:17], v[106:109], v[130:133]
	s_waitcnt lgkmcnt(3)
	v_mfma_f32_16x16x32_bf16 v[130:133], v[2:5], v[110:113], 0
	s_waitcnt lgkmcnt(1)
	v_mfma_f32_16x16x32_bf16 v[2:5], v[2:5], v[122:125], 0
	v_mfma_f32_16x16x32_bf16 v[150:153], v[6:9], v[118:121], v[130:133]
	s_waitcnt lgkmcnt(0)
	v_mfma_f32_16x16x32_bf16 v[2:5], v[6:9], v[126:129], v[2:5]
	v_mfma_f32_16x16x32_bf16 v[6:9], v[10:13], v[122:125], 0
	v_mfma_f32_16x16x32_bf16 v[130:133], v[10:13], v[110:113], 0
	v_mfma_f32_16x16x32_bf16 v[6:9], v[14:17], v[126:129], v[6:9]
	v_mfma_f32_16x16x32_bf16 v[154:157], v[14:17], v[118:121], v[130:133]
	s_setprio 0
	s_setprio 1
	v_mfma_f32_16x16x32_bf16 v[10:13], v[18:21], v[62:65], 0
	v_mfma_f32_16x16x32_bf16 v[162:165], v[22:25], v[90:93], v[10:13]
	v_mfma_f32_16x16x32_bf16 v[10:13], v[26:29], v[62:65], 0
	v_mfma_f32_16x16x32_bf16 v[166:169], v[30:33], v[90:93], v[10:13]
	v_mfma_f32_16x16x32_bf16 v[10:13], v[18:21], v[94:97], 0
	v_mfma_f32_16x16x32_bf16 v[170:173], v[22:25], v[106:109], v[10:13]
	v_mfma_f32_16x16x32_bf16 v[10:13], v[26:29], v[94:97], 0
	v_mfma_f32_16x16x32_bf16 v[174:177], v[30:33], v[106:109], v[10:13]
	v_mfma_f32_16x16x32_bf16 v[10:13], v[18:21], v[110:113], 0
	v_mfma_f32_16x16x32_bf16 v[178:181], v[22:25], v[118:121], v[10:13]
	v_mfma_f32_16x16x32_bf16 v[10:13], v[26:29], v[110:113], 0
	v_mfma_f32_16x16x32_bf16 v[182:185], v[30:33], v[118:121], v[10:13]
	v_mfma_f32_16x16x32_bf16 v[10:13], v[18:21], v[122:125], 0
	v_mfma_f32_16x16x32_bf16 v[186:189], v[22:25], v[126:129], v[10:13]
	v_mfma_f32_16x16x32_bf16 v[10:13], v[26:29], v[122:125], 0
	v_mfma_f32_16x16x32_bf16 v[190:193], v[30:33], v[126:129], v[10:13]
	s_setprio 0
	s_barrier
	s_nop 4
	ds_read_b128 v[10:13], v204
	ds_read_b128 v[14:17], v204 offset:1024
	ds_read_b128 v[18:21], v204 offset:2048
	ds_read_b128 v[22:25], v204 offset:3072
	ds_read_b128 v[212:215], v205
	ds_read_b128 v[216:219], v205 offset:1024
	ds_read_b128 v[220:223], v205 offset:2048
	ds_read_b128 v[224:227], v205 offset:3072
	ds_read_b128 v[26:29], v203 offset:32768
	ds_read_b128 v[30:33], v203 offset:33792
	ds_read_b128 v[62:65], v203 offset:34816
	ds_read_b128 v[228:231], v203 offset:35840
	ds_read_b128 v[232:235], v203 offset:36864
	ds_read_b128 v[236:239], v203 offset:37888
	ds_read_b128 v[240:243], v203 offset:38912
	ds_read_b128 v[244:247], v203 offset:39936
	s_add_u32 s44, s16, 0x14000
	s_addc_u32 s45, s17, 0
	s_mov_b32 m0, s58
	s_nop 0
	global_load_lds_dwordx4 v195, s[44:45]
	s_add_u32 m0, s58, 0x2000
	s_nop 0
	global_load_lds_dwordx4 v197, s[44:45]
	s_waitcnt vmcnt(8)
	s_waitcnt lgkmcnt(0)
	s_barrier
	s_setprio 1
	s_waitcnt lgkmcnt(7)
	v_mfma_f32_16x16x32_bf16 v[66:69], v[10:13], v[26:29], v[66:69]
	s_waitcnt lgkmcnt(6)
	v_mfma_f32_16x16x32_bf16 v[130:133], v[14:17], v[30:33], v[66:69]
	v_mfma_f32_16x16x32_bf16 v[66:69], v[18:21], v[26:29], v[70:73]
	v_mfma_f32_16x16x32_bf16 v[126:129], v[22:25], v[30:33], v[66:69]
	s_waitcnt lgkmcnt(5)
	v_mfma_f32_16x16x32_bf16 v[66:69], v[10:13], v[62:65], v[74:77]
	s_waitcnt lgkmcnt(4)
	v_mfma_f32_16x16x32_bf16 v[110:113], v[14:17], v[228:231], v[66:69]
	v_mfma_f32_16x16x32_bf16 v[66:69], v[18:21], v[62:65], v[78:81]
	v_mfma_f32_16x16x32_bf16 v[106:109], v[22:25], v[228:231], v[66:69]
	s_waitcnt lgkmcnt(3)
	v_mfma_f32_16x16x32_bf16 v[66:69], v[10:13], v[232:235], v[82:85]
	s_waitcnt lgkmcnt(2)
	v_mfma_f32_16x16x32_bf16 v[94:97], v[14:17], v[236:239], v[66:69]
	v_mfma_f32_16x16x32_bf16 v[66:69], v[18:21], v[232:235], v[86:89]
	v_mfma_f32_16x16x32_bf16 v[90:93], v[22:25], v[236:239], v[66:69]
	s_waitcnt lgkmcnt(1)
	v_mfma_f32_16x16x32_bf16 v[66:69], v[10:13], v[240:243], v[98:101]
	s_waitcnt lgkmcnt(0)
	v_mfma_f32_16x16x32_bf16 v[78:81], v[14:17], v[244:247], v[66:69]
	v_mfma_f32_16x16x32_bf16 v[66:69], v[18:21], v[240:243], v[102:105]
	v_mfma_f32_16x16x32_bf16 v[74:77], v[22:25], v[244:247], v[66:69]
	s_setprio 0
	s_setprio 1
	v_mfma_f32_16x16x32_bf16 v[66:69], v[212:215], v[26:29], v[114:117]
	v_mfma_f32_16x16x32_bf16 v[26:29], v[220:223], v[26:29], v[34:37]
	v_mfma_f32_16x16x32_bf16 v[118:121], v[224:227], v[30:33], v[26:29]
	v_mfma_f32_16x16x32_bf16 v[26:29], v[212:215], v[62:65], v[38:41]
	v_mfma_f32_16x16x32_bf16 v[102:105], v[216:219], v[228:231], v[26:29]
	v_mfma_f32_16x16x32_bf16 v[26:29], v[220:223], v[62:65], v[42:45]
	v_mfma_f32_16x16x32_bf16 v[98:101], v[224:227], v[228:231], v[26:29]
	v_mfma_f32_16x16x32_bf16 v[26:29], v[212:215], v[232:235], v[46:49]
	v_mfma_f32_16x16x32_bf16 v[86:89], v[216:219], v[236:239], v[26:29]
	v_mfma_f32_16x16x32_bf16 v[26:29], v[220:223], v[232:235], v[50:53]
	v_mfma_f32_16x16x32_bf16 v[82:85], v[224:227], v[236:239], v[26:29]
	v_mfma_f32_16x16x32_bf16 v[26:29], v[212:215], v[240:243], v[54:57]
	v_mfma_f32_16x16x32_bf16 v[70:73], v[216:219], v[244:247], v[26:29]
	v_mfma_f32_16x16x32_bf16 v[26:29], v[220:223], v[240:243], v[58:61]
	v_mfma_f32_16x16x32_bf16 v[122:125], v[216:219], v[30:33], v[66:69]
	v_mfma_f32_16x16x32_bf16 v[66:69], v[224:227], v[244:247], v[26:29]
	s_setprio 0
	s_barrier
	ds_read_b128 v[34:37], v203 offset:49152
	ds_read_b128 v[38:41], v203 offset:50176
	ds_read_b128 v[114:117], v203 offset:51200
	ds_read_b128 v[228:231], v203 offset:52224
	ds_read_b128 v[232:235], v203 offset:53248
	ds_read_b128 v[236:239], v203 offset:54272
	ds_read_b128 v[240:243], v203 offset:55296
	ds_read_b128 v[244:247], v203 offset:56320
	s_mov_b32 m0, s62
	s_nop 0
	global_load_lds_dwordx4 v195, s[42:43]
	s_add_u32 m0, s62, 0x2000
	s_nop 0
	global_load_lds_dwordx4 v197, s[42:43]
	s_add_u32 s6, s6, 0x1c000
	s_addc_u32 s7, s7, 0
	s_mov_b32 m0, s64
	s_nop 0
	global_load_lds_dwordx4 v195, s[6:7]
	s_add_u32 m0, s64, 0x2000
	s_nop 0
	global_load_lds_dwordx4 v197, s[6:7]
	s_nop 0
	s_mov_b32 m0, s63
	s_nop 0
	global_load_lds_dwordx4 v195, s[10:11]
	s_add_u32 m0, s63, 0x2000
	s_nop 0
	global_load_lds_dwordx4 v197, s[10:11]
	s_waitcnt vmcnt(8)
	s_waitcnt lgkmcnt(0)
	s_barrier
	s_setprio 1
	s_waitcnt lgkmcnt(7)
	v_mfma_f32_16x16x32_bf16 v[26:29], v[10:13], v[34:37], v[134:137]
	s_waitcnt lgkmcnt(6)
	v_mfma_f32_16x16x32_bf16 v[62:65], v[14:17], v[38:41], v[26:29]
	v_mfma_f32_16x16x32_bf16 v[26:29], v[18:21], v[34:37], v[138:141]
	v_mfma_f32_16x16x32_bf16 v[58:61], v[22:25], v[38:41], v[26:29]
	s_waitcnt lgkmcnt(5)
	v_mfma_f32_16x16x32_bf16 v[26:29], v[10:13], v[114:117], v[142:145]
	s_waitcnt lgkmcnt(4)
	v_mfma_f32_16x16x32_bf16 v[46:49], v[14:17], v[228:231], v[26:29]
	v_mfma_f32_16x16x32_bf16 v[26:29], v[18:21], v[114:117], v[146:149]
	v_mfma_f32_16x16x32_bf16 v[42:45], v[22:25], v[228:231], v[26:29]
	s_waitcnt lgkmcnt(3)
	v_mfma_f32_16x16x32_bf16 v[26:29], v[10:13], v[232:235], v[150:153]
	s_waitcnt lgkmcnt(1)
	v_mfma_f32_16x16x32_bf16 v[2:5], v[10:13], v[240:243], v[2:5]
	v_mfma_f32_16x16x32_bf16 v[30:33], v[14:17], v[236:239], v[26:29]
	v_mfma_f32_16x16x32_bf16 v[26:29], v[18:21], v[232:235], v[154:157]
	s_waitcnt lgkmcnt(0)
	v_mfma_f32_16x16x32_bf16 v[14:17], v[14:17], v[244:247], v[2:5]
	v_mfma_f32_16x16x32_bf16 v[2:5], v[18:21], v[240:243], v[6:9]
	v_mfma_f32_16x16x32_bf16 v[26:29], v[22:25], v[236:239], v[26:29]
	v_mfma_f32_16x16x32_bf16 v[10:13], v[22:25], v[244:247], v[2:5]
	s_setprio 0
	s_setprio 1
	v_mfma_f32_16x16x32_bf16 v[2:5], v[212:215], v[34:37], v[162:165]
	v_mfma_f32_16x16x32_bf16 v[54:57], v[216:219], v[38:41], v[2:5]
	v_mfma_f32_16x16x32_bf16 v[2:5], v[220:223], v[34:37], v[166:169]
	v_mfma_f32_16x16x32_bf16 v[50:53], v[224:227], v[38:41], v[2:5]
	v_mfma_f32_16x16x32_bf16 v[2:5], v[212:215], v[114:117], v[170:173]
	v_mfma_f32_16x16x32_bf16 v[38:41], v[216:219], v[228:231], v[2:5]
	v_mfma_f32_16x16x32_bf16 v[2:5], v[220:223], v[114:117], v[174:177]
	v_mfma_f32_16x16x32_bf16 v[34:37], v[224:227], v[228:231], v[2:5]
	v_mfma_f32_16x16x32_bf16 v[2:5], v[212:215], v[232:235], v[178:181]
	v_mfma_f32_16x16x32_bf16 v[22:25], v[216:219], v[236:239], v[2:5]
	v_mfma_f32_16x16x32_bf16 v[2:5], v[220:223], v[232:235], v[182:185]
	v_mfma_f32_16x16x32_bf16 v[18:21], v[224:227], v[236:239], v[2:5]
	v_mfma_f32_16x16x32_bf16 v[2:5], v[212:215], v[240:243], v[186:189]
	v_mfma_f32_16x16x32_bf16 v[6:9], v[216:219], v[244:247], v[2:5]
	v_mfma_f32_16x16x32_bf16 v[2:5], v[220:223], v[240:243], v[190:193]
	v_mfma_f32_16x16x32_bf16 v[2:5], v[224:227], v[244:247], v[2:5]
	s_setprio 0
	s_barrier
	s_mov_b32 s49, 0
	s_mov_b64 s[6:7], 0
	v_mov_b32_e32 v115, s46
	s_branch .LBB0_1920
.LBB0_1919:
	s_or_b64 exec, exec, s[10:11]
	s_add_u32 s50, s16, s6
	ds_read_b128 v[134:137], v201
	ds_read_b128 v[138:141], v201 offset:1024
	ds_read_b128 v[142:145], v201 offset:2048
	ds_read_b128 v[146:149], v201 offset:3072
	ds_read_b128 v[150:153], v202
	ds_read_b128 v[154:157], v202 offset:1024
	ds_read_b128 v[162:165], v202 offset:2048
	ds_read_b128 v[166:169], v202 offset:3072
	s_addc_u32 s51, s17, s7
	s_add_u32 s10, s50, 0x20000
	s_addc_u32 s11, s51, 0
	s_add_u32 s42, s75, s6
	s_addc_u32 s43, s76, s7
	s_cmp_eq_u32 s6, 0x60000
	s_cselect_b32 s46, s29, s10
	s_cselect_b32 s47, s20, s11
	s_cselect_b32 s11, s27, s43
	s_cselect_b32 s10, s48, s42
	s_add_u32 s42, s46, 0x8000
	s_addc_u32 s43, s47, 0
	s_add_u32 s44, s10, 0x8000
	s_addc_u32 s45, s11, 0
	ds_read_b128 v[170:173], v203
	ds_read_b128 v[174:177], v203 offset:1024
	ds_read_b128 v[178:181], v203 offset:2048
	ds_read_b128 v[182:185], v203 offset:3072
	ds_read_b128 v[186:189], v203 offset:4096
	ds_read_b128 v[190:193], v203 offset:5120
	ds_read_b128 v[212:215], v203 offset:6144
	ds_read_b128 v[216:219], v203 offset:7168
	s_add_u32 s50, s50, 0x1c000
	s_addc_u32 s51, s51, 0
	s_mov_b32 m0, s65
	s_nop 0
	global_load_lds_dwordx4 v195, s[50:51]
	s_add_u32 m0, s65, 0x2000
	s_nop 0
	global_load_lds_dwordx4 v197, s[50:51]
	s_waitcnt vmcnt(8)
	s_waitcnt lgkmcnt(0)
	s_barrier
	s_setprio 1
	s_waitcnt lgkmcnt(7)
	v_mfma_f32_16x16x32_bf16 v[130:133], v[134:137], v[170:173], v[130:133]
	v_mfma_f32_16x16x32_bf16 v[126:129], v[142:145], v[170:173], v[126:129]
	s_waitcnt lgkmcnt(5)
	v_mfma_f32_16x16x32_bf16 v[110:113], v[134:137], v[178:181], v[110:113]
	v_mfma_f32_16x16x32_bf16 v[106:109], v[142:145], v[178:181], v[106:109]
	s_waitcnt lgkmcnt(3)
	v_mfma_f32_16x16x32_bf16 v[94:97], v[134:137], v[186:189], v[94:97]
	v_mfma_f32_16x16x32_bf16 v[90:93], v[142:145], v[186:189], v[90:93]
	s_waitcnt lgkmcnt(1)
	v_mfma_f32_16x16x32_bf16 v[78:81], v[134:137], v[212:215], v[78:81]
	v_mfma_f32_16x16x32_bf16 v[74:77], v[142:145], v[212:215], v[74:77]
	v_mfma_f32_16x16x32_bf16 v[130:133], v[138:141], v[174:177], v[130:133]
	v_mfma_f32_16x16x32_bf16 v[126:129], v[146:149], v[174:177], v[126:129]
	v_mfma_f32_16x16x32_bf16 v[110:113], v[138:141], v[182:185], v[110:113]
	v_mfma_f32_16x16x32_bf16 v[106:109], v[146:149], v[182:185], v[106:109]
	v_mfma_f32_16x16x32_bf16 v[94:97], v[138:141], v[190:193], v[94:97]
	v_mfma_f32_16x16x32_bf16 v[90:93], v[146:149], v[190:193], v[90:93]
	s_waitcnt lgkmcnt(0)
	v_mfma_f32_16x16x32_bf16 v[78:81], v[138:141], v[216:219], v[78:81]
	v_mfma_f32_16x16x32_bf16 v[74:77], v[146:149], v[216:219], v[74:77]
	s_setprio 0
	s_setprio 1
	v_mfma_f32_16x16x32_bf16 v[122:125], v[150:153], v[170:173], v[122:125]
	v_mfma_f32_16x16x32_bf16 v[116:119], v[162:165], v[170:173], v[118:121]
	v_mfma_f32_16x16x32_bf16 v[102:105], v[150:153], v[178:181], v[102:105]
	v_mfma_f32_16x16x32_bf16 v[98:101], v[162:165], v[178:181], v[98:101]
	v_mfma_f32_16x16x32_bf16 v[86:89], v[150:153], v[186:189], v[86:89]
	v_mfma_f32_16x16x32_bf16 v[82:85], v[162:165], v[186:189], v[82:85]
	v_mfma_f32_16x16x32_bf16 v[70:73], v[150:153], v[212:215], v[70:73]
	v_mfma_f32_16x16x32_bf16 v[66:69], v[162:165], v[212:215], v[66:69]
	v_mfma_f32_16x16x32_bf16 v[122:125], v[154:157], v[174:177], v[122:125]
	v_mfma_f32_16x16x32_bf16 v[116:119], v[166:169], v[174:177], v[116:119]
	v_mfma_f32_16x16x32_bf16 v[102:105], v[154:157], v[182:185], v[102:105]
	v_mfma_f32_16x16x32_bf16 v[98:101], v[166:169], v[182:185], v[98:101]
	v_mfma_f32_16x16x32_bf16 v[86:89], v[154:157], v[190:193], v[86:89]
	v_mfma_f32_16x16x32_bf16 v[82:85], v[166:169], v[190:193], v[82:85]
	v_mfma_f32_16x16x32_bf16 v[70:73], v[154:157], v[216:219], v[70:73]
	v_mfma_f32_16x16x32_bf16 v[66:69], v[166:169], v[216:219], v[66:69]
	s_setprio 0
	s_barrier
	ds_read_b128 v[170:173], v203 offset:16384
	ds_read_b128 v[174:177], v203 offset:17408
	ds_read_b128 v[178:181], v203 offset:18432
	ds_read_b128 v[182:185], v203 offset:19456
	ds_read_b128 v[186:189], v203 offset:20480
	ds_read_b128 v[190:193], v203 offset:21504
	ds_read_b128 v[212:215], v203 offset:22528
	ds_read_b128 v[216:219], v203 offset:23552
	s_mov_b32 m0, s13
	s_nop 0
	global_load_lds_dwordx4 v195, s[10:11]
	s_add_u32 m0, s13, 0x2000
	s_nop 0
	global_load_lds_dwordx4 v197, s[10:11]
	s_add_u32 s50, s10, 0x4000
	s_addc_u32 s51, s11, 0
	s_mov_b32 m0, s57
	s_nop 0
	global_load_lds_dwordx4 v195, s[50:51]
	s_add_u32 m0, s57, 0x2000
	s_nop 0
	global_load_lds_dwordx4 v197, s[50:51]
	s_nop 0
	s_mov_b32 m0, s56
	s_nop 0
	global_load_lds_dwordx4 v195, s[46:47]
	s_add_u32 m0, s56, 0x2000
	s_nop 0
	global_load_lds_dwordx4 v197, s[46:47]
	s_waitcnt vmcnt(8)
	s_waitcnt lgkmcnt(0)
	s_barrier
	s_setprio 1
	s_waitcnt lgkmcnt(7)
	v_mfma_f32_16x16x32_bf16 v[62:65], v[134:137], v[170:173], v[62:65]
	v_mfma_f32_16x16x32_bf16 v[58:61], v[142:145], v[170:173], v[58:61]
	s_waitcnt lgkmcnt(5)
	v_mfma_f32_16x16x32_bf16 v[46:49], v[134:137], v[178:181], v[46:49]
	v_mfma_f32_16x16x32_bf16 v[42:45], v[142:145], v[178:181], v[42:45]
	s_waitcnt lgkmcnt(3)
	v_mfma_f32_16x16x32_bf16 v[30:33], v[134:137], v[186:189], v[30:33]
	v_mfma_f32_16x16x32_bf16 v[26:29], v[142:145], v[186:189], v[26:29]
	s_waitcnt lgkmcnt(1)
	v_mfma_f32_16x16x32_bf16 v[14:17], v[134:137], v[212:215], v[14:17]
	v_mfma_f32_16x16x32_bf16 v[10:13], v[142:145], v[212:215], v[10:13]
	v_mfma_f32_16x16x32_bf16 v[62:65], v[138:141], v[174:177], v[62:65]
	v_mfma_f32_16x16x32_bf16 v[58:61], v[146:149], v[174:177], v[58:61]
	v_mfma_f32_16x16x32_bf16 v[46:49], v[138:141], v[182:185], v[46:49]
	v_mfma_f32_16x16x32_bf16 v[42:45], v[146:149], v[182:185], v[42:45]
	v_mfma_f32_16x16x32_bf16 v[30:33], v[138:141], v[190:193], v[30:33]
	v_mfma_f32_16x16x32_bf16 v[26:29], v[146:149], v[190:193], v[26:29]
	s_waitcnt lgkmcnt(0)
	v_mfma_f32_16x16x32_bf16 v[14:17], v[138:141], v[216:219], v[14:17]
	v_mfma_f32_16x16x32_bf16 v[10:13], v[146:149], v[216:219], v[10:13]
	s_setprio 0
	s_setprio 1
	v_mfma_f32_16x16x32_bf16 v[54:57], v[150:153], v[170:173], v[54:57]
	v_mfma_f32_16x16x32_bf16 v[50:53], v[162:165], v[170:173], v[50:53]
	v_mfma_f32_16x16x32_bf16 v[38:41], v[150:153], v[178:181], v[38:41]
	v_mfma_f32_16x16x32_bf16 v[34:37], v[162:165], v[178:181], v[34:37]
	v_mfma_f32_16x16x32_bf16 v[22:25], v[150:153], v[186:189], v[22:25]
	v_mfma_f32_16x16x32_bf16 v[18:21], v[162:165], v[186:189], v[18:21]
	v_mfma_f32_16x16x32_bf16 v[6:9], v[150:153], v[212:215], v[6:9]
	v_mfma_f32_16x16x32_bf16 v[2:5], v[162:165], v[212:215], v[2:5]
	v_mfma_f32_16x16x32_bf16 v[54:57], v[154:157], v[174:177], v[54:57]
	v_mfma_f32_16x16x32_bf16 v[50:53], v[166:169], v[174:177], v[50:53]
	v_mfma_f32_16x16x32_bf16 v[38:41], v[154:157], v[182:185], v[38:41]
	v_mfma_f32_16x16x32_bf16 v[34:37], v[166:169], v[182:185], v[34:37]
	v_mfma_f32_16x16x32_bf16 v[22:25], v[154:157], v[190:193], v[22:25]
	v_mfma_f32_16x16x32_bf16 v[18:21], v[166:169], v[190:193], v[18:21]
	v_mfma_f32_16x16x32_bf16 v[6:9], v[154:157], v[216:219], v[6:9]
	v_mfma_f32_16x16x32_bf16 v[2:5], v[166:169], v[216:219], v[2:5]
	s_setprio 0
	s_barrier
	ds_read_b128 v[134:137], v204
	ds_read_b128 v[138:141], v204 offset:1024
	ds_read_b128 v[142:145], v204 offset:2048
	ds_read_b128 v[146:149], v204 offset:3072
	ds_read_b128 v[150:153], v205
	ds_read_b128 v[154:157], v205 offset:1024
	ds_read_b128 v[162:165], v205 offset:2048
	ds_read_b128 v[166:169], v205 offset:3072
	ds_read_b128 v[170:173], v203 offset:32768
	ds_read_b128 v[174:177], v203 offset:33792
	ds_read_b128 v[178:181], v203 offset:34816
	ds_read_b128 v[182:185], v203 offset:35840
	ds_read_b128 v[186:189], v203 offset:36864
	ds_read_b128 v[190:193], v203 offset:37888
	ds_read_b128 v[212:215], v203 offset:38912
	ds_read_b128 v[216:219], v203 offset:39936
	s_add_u32 s46, s46, 0x4000
	s_addc_u32 s47, s47, 0
	s_mov_b32 m0, s58
	s_nop 0
	global_load_lds_dwordx4 v195, s[46:47]
	s_add_u32 m0, s58, 0x2000
	s_nop 0
	global_load_lds_dwordx4 v197, s[46:47]
	s_waitcnt vmcnt(8)
	s_waitcnt lgkmcnt(0)
	s_barrier
	s_setprio 1
	s_waitcnt lgkmcnt(7)
	v_mfma_f32_16x16x32_bf16 v[130:133], v[134:137], v[170:173], v[130:133]
	v_mfma_f32_16x16x32_bf16 v[126:129], v[142:145], v[170:173], v[126:129]
	s_waitcnt lgkmcnt(5)
	v_mfma_f32_16x16x32_bf16 v[110:113], v[134:137], v[178:181], v[110:113]
	v_mfma_f32_16x16x32_bf16 v[106:109], v[142:145], v[178:181], v[106:109]
	s_waitcnt lgkmcnt(3)
	v_mfma_f32_16x16x32_bf16 v[94:97], v[134:137], v[186:189], v[94:97]
	v_mfma_f32_16x16x32_bf16 v[90:93], v[142:145], v[186:189], v[90:93]
	s_waitcnt lgkmcnt(1)
	v_mfma_f32_16x16x32_bf16 v[78:81], v[134:137], v[212:215], v[78:81]
	v_mfma_f32_16x16x32_bf16 v[74:77], v[142:145], v[212:215], v[74:77]
	v_mfma_f32_16x16x32_bf16 v[130:133], v[138:141], v[174:177], v[130:133]
	v_mfma_f32_16x16x32_bf16 v[126:129], v[146:149], v[174:177], v[126:129]
	v_mfma_f32_16x16x32_bf16 v[110:113], v[138:141], v[182:185], v[110:113]
	v_mfma_f32_16x16x32_bf16 v[106:109], v[146:149], v[182:185], v[106:109]
	v_mfma_f32_16x16x32_bf16 v[94:97], v[138:141], v[190:193], v[94:97]
	v_mfma_f32_16x16x32_bf16 v[90:93], v[146:149], v[190:193], v[90:93]
	s_waitcnt lgkmcnt(0)
	v_mfma_f32_16x16x32_bf16 v[78:81], v[138:141], v[216:219], v[78:81]
	v_mfma_f32_16x16x32_bf16 v[74:77], v[146:149], v[216:219], v[74:77]
	s_setprio 0
	s_setprio 1
	v_mfma_f32_16x16x32_bf16 v[120:123], v[150:153], v[170:173], v[122:125]
	v_mfma_f32_16x16x32_bf16 v[116:119], v[162:165], v[170:173], v[116:119]
	v_mfma_f32_16x16x32_bf16 v[102:105], v[150:153], v[178:181], v[102:105]
	v_mfma_f32_16x16x32_bf16 v[98:101], v[162:165], v[178:181], v[98:101]
	v_mfma_f32_16x16x32_bf16 v[86:89], v[150:153], v[186:189], v[86:89]
	v_mfma_f32_16x16x32_bf16 v[82:85], v[162:165], v[186:189], v[82:85]
	v_mfma_f32_16x16x32_bf16 v[70:73], v[150:153], v[212:215], v[70:73]
	v_mfma_f32_16x16x32_bf16 v[66:69], v[162:165], v[212:215], v[66:69]
	v_mfma_f32_16x16x32_bf16 v[122:125], v[154:157], v[174:177], v[120:123]
	v_mfma_f32_16x16x32_bf16 v[118:121], v[166:169], v[174:177], v[116:119]
	v_mfma_f32_16x16x32_bf16 v[102:105], v[154:157], v[182:185], v[102:105]
	v_mfma_f32_16x16x32_bf16 v[98:101], v[166:169], v[182:185], v[98:101]
	v_mfma_f32_16x16x32_bf16 v[86:89], v[154:157], v[190:193], v[86:89]
	v_mfma_f32_16x16x32_bf16 v[82:85], v[166:169], v[190:193], v[82:85]
	v_mfma_f32_16x16x32_bf16 v[70:73], v[154:157], v[216:219], v[70:73]
	v_mfma_f32_16x16x32_bf16 v[66:69], v[166:169], v[216:219], v[66:69]
	s_setprio 0
	s_barrier
	ds_read_b128 v[170:173], v203 offset:49152
	ds_read_b128 v[174:177], v203 offset:50176
	ds_read_b128 v[178:181], v203 offset:51200
	ds_read_b128 v[182:185], v203 offset:52224
	ds_read_b128 v[186:189], v203 offset:53248
	ds_read_b128 v[190:193], v203 offset:54272
	ds_read_b128 v[212:215], v203 offset:55296
	ds_read_b128 v[216:219], v203 offset:56320
	s_mov_b32 m0, s62
	s_nop 0
	global_load_lds_dwordx4 v195, s[44:45]
	s_add_u32 m0, s62, 0x2000
	s_nop 0
	global_load_lds_dwordx4 v197, s[44:45]
	s_add_u32 s10, s10, 0xc000
	s_addc_u32 s11, s11, 0
	s_mov_b32 m0, s64
	s_nop 0
	global_load_lds_dwordx4 v195, s[10:11]
	s_add_u32 m0, s64, 0x2000
	s_nop 0
	global_load_lds_dwordx4 v197, s[10:11]
	s_nop 0
	s_mov_b32 m0, s63
	s_nop 0
	global_load_lds_dwordx4 v195, s[42:43]
	s_add_u32 m0, s63, 0x2000
	s_nop 0
	global_load_lds_dwordx4 v197, s[42:43]
	s_waitcnt vmcnt(8)
	s_waitcnt lgkmcnt(0)
	s_barrier
	s_setprio 1
	s_waitcnt lgkmcnt(7)
	v_mfma_f32_16x16x32_bf16 v[62:65], v[134:137], v[170:173], v[62:65]
	v_mfma_f32_16x16x32_bf16 v[58:61], v[142:145], v[170:173], v[58:61]
	s_waitcnt lgkmcnt(5)
	v_mfma_f32_16x16x32_bf16 v[46:49], v[134:137], v[178:181], v[46:49]
	v_mfma_f32_16x16x32_bf16 v[42:45], v[142:145], v[178:181], v[42:45]
	s_waitcnt lgkmcnt(3)
	v_mfma_f32_16x16x32_bf16 v[30:33], v[134:137], v[186:189], v[30:33]
	v_mfma_f32_16x16x32_bf16 v[26:29], v[142:145], v[186:189], v[26:29]
	s_waitcnt lgkmcnt(1)
	v_mfma_f32_16x16x32_bf16 v[14:17], v[134:137], v[212:215], v[14:17]
	v_mfma_f32_16x16x32_bf16 v[10:13], v[142:145], v[212:215], v[10:13]
	v_mfma_f32_16x16x32_bf16 v[62:65], v[138:141], v[174:177], v[62:65]
	v_mfma_f32_16x16x32_bf16 v[58:61], v[146:149], v[174:177], v[58:61]
	v_mfma_f32_16x16x32_bf16 v[46:49], v[138:141], v[182:185], v[46:49]
	v_mfma_f32_16x16x32_bf16 v[42:45], v[146:149], v[182:185], v[42:45]
	v_mfma_f32_16x16x32_bf16 v[30:33], v[138:141], v[190:193], v[30:33]
	v_mfma_f32_16x16x32_bf16 v[26:29], v[146:149], v[190:193], v[26:29]
	s_waitcnt lgkmcnt(0)
	v_mfma_f32_16x16x32_bf16 v[14:17], v[138:141], v[216:219], v[14:17]
	v_mfma_f32_16x16x32_bf16 v[10:13], v[146:149], v[216:219], v[10:13]
	s_setprio 0
	s_setprio 1
	v_mfma_f32_16x16x32_bf16 v[54:57], v[150:153], v[170:173], v[54:57]
	v_mfma_f32_16x16x32_bf16 v[50:53], v[162:165], v[170:173], v[50:53]
	v_mfma_f32_16x16x32_bf16 v[38:41], v[150:153], v[178:181], v[38:41]
	v_mfma_f32_16x16x32_bf16 v[34:37], v[162:165], v[178:181], v[34:37]
	v_mfma_f32_16x16x32_bf16 v[22:25], v[150:153], v[186:189], v[22:25]
	v_mfma_f32_16x16x32_bf16 v[18:21], v[162:165], v[186:189], v[18:21]
	v_mfma_f32_16x16x32_bf16 v[6:9], v[150:153], v[212:215], v[6:9]
	v_mfma_f32_16x16x32_bf16 v[2:5], v[162:165], v[212:215], v[2:5]
	v_mfma_f32_16x16x32_bf16 v[54:57], v[154:157], v[174:177], v[54:57]
	v_mfma_f32_16x16x32_bf16 v[50:53], v[166:169], v[174:177], v[50:53]
	v_mfma_f32_16x16x32_bf16 v[38:41], v[154:157], v[182:185], v[38:41]
	v_mfma_f32_16x16x32_bf16 v[34:37], v[166:169], v[182:185], v[34:37]
	v_mfma_f32_16x16x32_bf16 v[22:25], v[154:157], v[190:193], v[22:25]
	v_mfma_f32_16x16x32_bf16 v[18:21], v[166:169], v[190:193], v[18:21]
	v_mfma_f32_16x16x32_bf16 v[6:9], v[154:157], v[216:219], v[6:9]
	v_mfma_f32_16x16x32_bf16 v[2:5], v[166:169], v[216:219], v[2:5]
	s_setprio 0
	s_barrier
	s_add_i32 s49, s49, 2
	s_add_u32 s6, s6, 0x10000
	s_addc_u32 s7, s7, 0
	s_cmp_gt_u32 s49, 13
	v_mov_b32_e32 v115, v114
	s_cbranch_scc1 .LBB0_1922

.LBB0_1924:
	s_lshl_b32 s6, s72, 8
	v_mov_b32_e32 v114, v200
	v_mov_b32_e32 v163, v210
	s_add_i32 s6, s6, s60
	v_add_u32_e32 v162, s6, v114
	s_lshl_b32 s6, s12, 8
	s_or_b32 s6, s6, s61
	v_lshl_add_u32 v134, v163, 3, s6
	v_bfe_u32 v212, v134, 5, 1
	v_lshrrev_b32_e32 v115, 3, v162
	v_lshlrev_b32_e32 v114, 1, v134
	v_and_or_b32 v115, v115, 14, v212
	v_and_b32_e32 v209, 48, v114
	v_ashrrev_i32_e32 v208, 6, v134
	v_ashrrev_i32_e32 v114, 4, v162
	v_lshlrev_b32_e32 v116, 6, v162
	v_lshlrev_b32_e32 v214, 10, v115
	v_lshlrev_b32_e32 v115, 2, v162
	v_add_u32_e32 v134, 0x80, v134
	v_and_b32_e32 v135, -16, v114
	v_lshlrev_b32_e32 v114, 7, v162
	v_and_b32_e32 v116, 0x3c0, v116
	v_and_b32_e32 v115, 32, v115
	v_ashrrev_i32_e32 v213, 6, v134
	v_and_b32_e32 v114, 0x4000, v114
	v_bitop3_b32 v115, v209, v115, v116 bitop3:0x36
	v_add_u32_e32 v116, v208, v135
	v_or3_b32 v158, v114, v115, v214
	v_ashrrev_i32_e32 v117, 31, v116
	v_lshl_add_u64 v[114:115], s[34:35], 0, v[158:159]
	v_lshlrev_b64 v[198:199], 15, v[116:117]
	v_lshl_add_u64 v[116:117], v[114:115], 0, v[198:199]
	v_add_u32_e32 v178, 16, v162
	v_lshl_add_u64 v[166:167], v[116:117], 0, 0
	global_load_dwordx4 v[190:193], v[116:117], off
	s_mov_b32 s98, 0x11000
	s_mov_b32 s99, 0x0
	v_lshl_add_u64 v[168:169], v[166:167], 0, s[98:99]
	global_load_dwordx4 v[154:157], v[168:169], off offset:-4096
	v_add_u32_e32 v170, 32, v162
	s_mov_b32 s98, 0x1000
	s_mov_b32 s99, 0x0
	v_lshl_add_u64 v[172:173], v[166:167], 0, s[98:99]
	global_load_dwordx4 v[150:153], v[172:173], off offset:-2048
	global_load_dwordx4 v[146:149], v[168:169], off offset:-2048
	v_add_u32_e32 v164, 48, v162
	global_load_dwordx4 v[142:145], v[172:173], off
	global_load_dwordx4 v[138:141], v[168:169], off
	global_load_dwordx4 v[134:137], v[172:173], off offset:2048
	s_nop 0
	global_load_dwordx4 v[114:117], v[168:169], off offset:2048
	s_cmpk_gt_i32 s72, 0x7f
	s_cselect_b64 s[42:43], -1, 0
	v_lshl_add_u64 v[198:199], s[34:35], 0, v[198:199]
	s_nor_b64 s[46:47], s[36:37], s[42:43]
	v_lshl_add_u64 v[198:199], v[198:199], 0, v[158:159]
	s_waitcnt vmcnt(7)
	v_lshlrev_b32_e32 v216, 16, v190
	v_and_b32_e32 v217, 0xffff0000, v190
	v_lshlrev_b32_e32 v190, 16, v191
	v_and_b32_e32 v191, 0xffff0000, v191
	v_pk_add_f32 v[132:133], v[132:133], v[190:191]
	v_lshlrev_b32_e32 v190, 16, v192
	v_and_b32_e32 v191, 0xffff0000, v192
	v_pk_add_f32 v[190:191], v[126:127], v[190:191]
	v_lshlrev_b32_e32 v126, 16, v193
	v_and_b32_e32 v127, 0xffff0000, v193
	v_pk_add_f32 v[130:131], v[130:131], v[216:217]
	v_pk_add_f32 v[192:193], v[128:129], v[126:127]
	v_cvt_pk_bf16_f32 v126, v130, v131
	v_cvt_pk_bf16_f32 v127, v132, v133
	v_cvt_pk_bf16_f32 v128, v190, v191
	v_cvt_pk_bf16_f32 v129, v192, v193
	s_mov_b64 s[6:7], -1
	s_and_b64 vcc, exec, s[46:47]
	s_cbranch_vccz .LBB0_1926
	global_store_dwordx4 v[172:173], v[126:129], off offset:-4096
	s_mov_b64 s[6:7], 0
.LBB0_1926:
	s_andn2_b64 vcc, exec, s[6:7]
	s_cbranch_vccnz .LBB0_1928
	global_store_dwordx4 v[172:173], v[126:129], off offset:-4096 sc1
	s_nop 1
.LBB0_1928:
	s_waitcnt vmcnt(6)
	v_lshlrev_b32_e32 v128, 16, v154
	v_and_b32_e32 v129, 0xffff0000, v154
	v_pk_add_f32 v[122:123], v[122:123], v[128:129]
	v_lshlrev_b32_e32 v128, 16, v155
	v_and_b32_e32 v129, 0xffff0000, v155
	v_pk_add_f32 v[124:125], v[124:125], v[128:129]
	v_lshlrev_b32_e32 v128, 16, v156
	v_and_b32_e32 v129, 0xffff0000, v156
	v_pk_add_f32 v[128:129], v[118:119], v[128:129]
	v_lshlrev_b32_e32 v118, 16, v157
	v_and_b32_e32 v119, 0xffff0000, v157
	s_nop 0
	v_pk_add_f32 v[154:155], v[120:121], v[118:119]
	v_cndmask_b32_e64 v156, 0, 1, s[46:47]
	v_cvt_pk_bf16_f32 v118, v122, v123
	v_cvt_pk_bf16_f32 v119, v124, v125
	v_cvt_pk_bf16_f32 v120, v128, v129
	v_cvt_pk_bf16_f32 v121, v154, v155
	v_cmp_ne_u32_e64 s[6:7], 1, v156
	s_andn2_b64 vcc, exec, s[46:47]
	s_mov_b64 s[10:11], -1
	s_cbranch_vccnz .LBB0_1930
	s_mov_b64 s[10:11], 0
	global_store_dwordx4 v[168:169], v[118:121], off offset:-4096
.LBB0_1930:
	s_andn2_b64 vcc, exec, s[10:11]
	s_cbranch_vccnz .LBB0_1932
	global_store_dwordx4 v[168:169], v[118:121], off offset:-4096 sc1
	s_nop 1

.LBB0_1938:
	s_or_b64 exec, exec, s[48:49]
	s_waitcnt lgkmcnt(0)
	s_waitcnt vmcnt(5)
	v_lshlrev_b32_e32 v118, 16, v150
	v_and_b32_e32 v119, 0xffff0000, v150
	v_pk_add_f32 v[110:111], v[110:111], v[118:119]
	v_lshlrev_b32_e32 v118, 16, v151
	v_and_b32_e32 v119, 0xffff0000, v151
	v_pk_add_f32 v[112:113], v[112:113], v[118:119]
	v_lshlrev_b32_e32 v118, 16, v152
	v_and_b32_e32 v119, 0xffff0000, v152
	v_pk_add_f32 v[118:119], v[106:107], v[118:119]
	v_lshlrev_b32_e32 v106, 16, v153
	v_and_b32_e32 v107, 0xffff0000, v153
	v_pk_add_f32 v[120:121], v[108:109], v[106:107]
	v_cvt_pk_bf16_f32 v106, v110, v111
	v_cvt_pk_bf16_f32 v107, v112, v113
	v_cvt_pk_bf16_f32 v108, v118, v119
	v_cvt_pk_bf16_f32 v109, v120, v121
	s_nor_b64 s[46:47], s[50:51], s[42:43]
	s_and_saveexec_b64 s[48:49], s[46:47]
	s_xor_b64 s[46:47], exec, s[48:49]
	s_cbranch_execz .LBB0_1940
	global_store_dwordx4 v[172:173], v[106:109], off offset:-2048
.LBB0_1940:
	s_andn2_saveexec_b64 s[46:47], s[46:47]
	s_cbranch_execz .LBB0_1942
	global_store_dwordx4 v[172:173], v[106:109], off offset:-2048 sc1
	s_nop 1
.LBB0_1942:
	s_or_b64 exec, exec, s[46:47]
	s_waitcnt vmcnt(4)
	v_lshlrev_b32_e32 v108, 16, v146
	v_and_b32_e32 v109, 0xffff0000, v146
	v_pk_add_f32 v[102:103], v[102:103], v[108:109]
	v_lshlrev_b32_e32 v108, 16, v147
	v_and_b32_e32 v109, 0xffff0000, v147
	v_pk_add_f32 v[104:105], v[104:105], v[108:109]
	v_lshlrev_b32_e32 v108, 16, v148
	v_and_b32_e32 v109, 0xffff0000, v148
	v_pk_add_f32 v[108:109], v[98:99], v[108:109]
	v_lshlrev_b32_e32 v98, 16, v149
	v_and_b32_e32 v99, 0xffff0000, v149
	v_pk_add_f32 v[122:123], v[100:101], v[98:99]
	v_cvt_pk_bf16_f32 v98, v102, v103
	v_cvt_pk_bf16_f32 v99, v104, v105
	v_cvt_pk_bf16_f32 v100, v108, v109
	v_cvt_pk_bf16_f32 v101, v122, v123
	s_and_b64 vcc, exec, s[6:7]
	s_mov_b64 s[46:47], -1
	s_cbranch_vccnz .LBB0_1944
	s_mov_b64 s[46:47], 0
	global_store_dwordx4 v[168:169], v[98:101], off offset:-2048
.LBB0_1944:
	s_andn2_b64 vcc, exec, s[46:47]
	s_cbranch_vccnz .LBB0_1946
	global_store_dwordx4 v[168:169], v[98:101], off offset:-2048 sc1
	s_nop 1

.LBB0_1952:
	s_or_b64 exec, exec, s[46:47]
	s_waitcnt lgkmcnt(0)
	s_waitcnt vmcnt(3)
	v_lshlrev_b32_e32 v98, 16, v142
	v_and_b32_e32 v99, 0xffff0000, v142
	v_pk_add_f32 v[94:95], v[94:95], v[98:99]
	v_lshlrev_b32_e32 v98, 16, v143
	v_and_b32_e32 v99, 0xffff0000, v143
	v_pk_add_f32 v[96:97], v[96:97], v[98:99]
	v_lshlrev_b32_e32 v98, 16, v144
	v_and_b32_e32 v99, 0xffff0000, v144
	v_pk_add_f32 v[98:99], v[90:91], v[98:99]
	v_lshlrev_b32_e32 v90, 16, v145
	v_and_b32_e32 v91, 0xffff0000, v145
	v_pk_add_f32 v[100:101], v[92:93], v[90:91]
	v_cvt_pk_bf16_f32 v90, v94, v95
	v_cvt_pk_bf16_f32 v91, v96, v97
	v_cvt_pk_bf16_f32 v92, v98, v99
	v_cvt_pk_bf16_f32 v93, v100, v101
	s_nor_b64 s[46:47], s[48:49], s[42:43]
	s_and_saveexec_b64 s[48:49], s[46:47]
	s_xor_b64 s[46:47], exec, s[48:49]
	s_cbranch_execz .LBB0_1954
	global_store_dwordx4 v[172:173], v[90:93], off
.LBB0_1954:
	s_andn2_saveexec_b64 s[46:47], s[46:47]
	s_cbranch_execz .LBB0_1956
	global_store_dwordx4 v[172:173], v[90:93], off sc1
	s_nop 1
.LBB0_1956:
	s_or_b64 exec, exec, s[46:47]
	s_waitcnt vmcnt(2)
	v_lshlrev_b32_e32 v92, 16, v138
	v_and_b32_e32 v93, 0xffff0000, v138
	v_pk_add_f32 v[86:87], v[86:87], v[92:93]
	v_lshlrev_b32_e32 v92, 16, v139
	v_and_b32_e32 v93, 0xffff0000, v139
	v_pk_add_f32 v[88:89], v[88:89], v[92:93]
	v_lshlrev_b32_e32 v92, 16, v140
	v_and_b32_e32 v93, 0xffff0000, v140
	v_pk_add_f32 v[92:93], v[82:83], v[92:93]
	v_lshlrev_b32_e32 v82, 16, v141
	v_and_b32_e32 v83, 0xffff0000, v141
	v_pk_add_f32 v[102:103], v[84:85], v[82:83]
	v_cvt_pk_bf16_f32 v82, v86, v87
	v_cvt_pk_bf16_f32 v83, v88, v89
	v_cvt_pk_bf16_f32 v84, v92, v93
	v_cvt_pk_bf16_f32 v85, v102, v103
	s_and_b64 vcc, exec, s[6:7]
	s_mov_b64 s[46:47], -1
	s_cbranch_vccnz .LBB0_1958
	s_mov_b64 s[46:47], 0
	global_store_dwordx4 v[168:169], v[82:85], off
.LBB0_1958:
	s_andn2_b64 vcc, exec, s[46:47]
	s_cbranch_vccnz .LBB0_1960
	global_store_dwordx4 v[168:169], v[82:85], off sc1
	s_nop 1

.LBB0_1966:
	s_or_b64 exec, exec, s[46:47]
	s_waitcnt lgkmcnt(0)
	s_waitcnt vmcnt(1)
	v_lshlrev_b32_e32 v82, 16, v134
	v_and_b32_e32 v83, 0xffff0000, v134
	v_pk_add_f32 v[78:79], v[78:79], v[82:83]
	v_lshlrev_b32_e32 v82, 16, v135
	v_and_b32_e32 v83, 0xffff0000, v135
	v_pk_add_f32 v[80:81], v[80:81], v[82:83]
	v_lshlrev_b32_e32 v82, 16, v136
	v_and_b32_e32 v83, 0xffff0000, v136
	v_pk_add_f32 v[82:83], v[74:75], v[82:83]
	v_lshlrev_b32_e32 v74, 16, v137
	v_and_b32_e32 v75, 0xffff0000, v137
	v_pk_add_f32 v[84:85], v[76:77], v[74:75]
	v_cvt_pk_bf16_f32 v74, v78, v79
	v_cvt_pk_bf16_f32 v75, v80, v81
	v_cvt_pk_bf16_f32 v76, v82, v83
	v_cvt_pk_bf16_f32 v77, v84, v85
	s_nor_b64 s[46:47], s[48:49], s[42:43]
	s_and_saveexec_b64 s[48:49], s[46:47]
	s_xor_b64 s[46:47], exec, s[48:49]
	s_cbranch_execz .LBB0_1968
	global_store_dwordx4 v[172:173], v[74:77], off offset:2048
.LBB0_1968:
	s_andn2_saveexec_b64 s[46:47], s[46:47]
	s_cbranch_execz .LBB0_1970
	global_store_dwordx4 v[172:173], v[74:77], off offset:2048 sc1
	s_nop 1
.LBB0_1970:
	s_or_b64 exec, exec, s[46:47]
	s_waitcnt vmcnt(0)
	v_lshlrev_b32_e32 v76, 16, v114
	v_and_b32_e32 v77, 0xffff0000, v114
	v_pk_add_f32 v[70:71], v[70:71], v[76:77]
	v_lshlrev_b32_e32 v76, 16, v115
	v_and_b32_e32 v77, 0xffff0000, v115
	v_pk_add_f32 v[72:73], v[72:73], v[76:77]
	v_lshlrev_b32_e32 v76, 16, v116
	v_and_b32_e32 v77, 0xffff0000, v116
	v_pk_add_f32 v[76:77], v[66:67], v[76:77]
	v_lshlrev_b32_e32 v66, 16, v117
	v_and_b32_e32 v67, 0xffff0000, v117
	v_pk_add_f32 v[86:87], v[68:69], v[66:67]
	v_cvt_pk_bf16_f32 v66, v70, v71
	v_cvt_pk_bf16_f32 v67, v72, v73
	v_cvt_pk_bf16_f32 v68, v76, v77
	v_cvt_pk_bf16_f32 v69, v86, v87
	s_and_b64 vcc, exec, s[6:7]
	s_mov_b64 s[46:47], -1
	s_cbranch_vccnz .LBB0_1972
	s_mov_b64 s[46:47], 0
	global_store_dwordx4 v[168:169], v[66:69], off offset:2048
.LBB0_1972:
	s_andn2_b64 vcc, exec, s[46:47]
	s_cbranch_vccnz .LBB0_1974
	global_store_dwordx4 v[168:169], v[66:69], off offset:2048 sc1
	s_nop 1

.LBB0_1979:
	s_or_b64 exec, exec, s[46:47]
	v_add_u32_e32 v116, 0x80, v162
	s_waitcnt lgkmcnt(0)
	v_lshlrev_b32_e32 v67, 6, v116
	v_lshlrev_b32_e32 v68, 2, v116
	v_lshlrev_b32_e32 v66, 7, v116
	v_and_b32_e32 v67, 0x3c0, v67
	v_and_b32_e32 v68, 32, v68
	v_and_b32_e32 v66, 0x4000, v66
	v_bitop3_b32 v67, v67, v68, v209 bitop3:0x36
	v_or3_b32 v158, v66, v67, v214
	v_add_u32_e32 v108, 0x90, v162
	s_mov_b32 s98, 0x5000
	s_mov_b32 s99, 0x0
	v_lshl_add_u64 v[168:169], v[166:167], 0, s[98:99]
	global_load_dwordx4 v[122:125], v[168:169], off offset:-4096
	s_mov_b32 s98, 0x15000
	s_mov_b32 s99, 0x0
	v_lshl_add_u64 v[172:173], v[166:167], 0, s[98:99]
	global_load_dwordx4 v[90:93], v[172:173], off offset:-4096
	v_ashrrev_i32_e32 v66, 4, v108
	v_and_b32_e32 v70, -16, v66
	v_add_u32_e32 v70, v213, v70
	v_ashrrev_i32_e32 v71, 31, v70
	v_lshlrev_b64 v[114:115], 15, v[70:71]
	v_add_u32_e32 v100, 0xa0, v162
	global_load_dwordx4 v[86:89], v[168:169], off offset:-2048
	global_load_dwordx4 v[82:85], v[172:173], off offset:-2048
	v_add_u32_e32 v94, 0xb0, v162
	global_load_dwordx4 v[78:81], v[168:169], off
	global_load_dwordx4 v[74:77], v[172:173], off
	global_load_dwordx4 v[70:73], v[168:169], off offset:2048
	s_nop 0
	global_load_dwordx4 v[66:69], v[172:173], off offset:2048
	s_and_b64 vcc, exec, s[6:7]
	s_mov_b64 s[46:47], -1
	s_waitcnt vmcnt(7)
	v_lshlrev_b32_e32 v130, 16, v122
	v_and_b32_e32 v131, 0xffff0000, v122
	v_lshlrev_b32_e32 v122, 16, v123
	v_and_b32_e32 v123, 0xffff0000, v123
	v_pk_add_f32 v[64:65], v[64:65], v[122:123]
	v_lshlrev_b32_e32 v122, 16, v124
	v_and_b32_e32 v123, 0xffff0000, v124
	v_pk_add_f32 v[122:123], v[58:59], v[122:123]
	v_lshlrev_b32_e32 v58, 16, v125
	v_and_b32_e32 v59, 0xffff0000, v125
	v_pk_add_f32 v[62:63], v[62:63], v[130:131]
	v_pk_add_f32 v[124:125], v[60:61], v[58:59]
	v_cvt_pk_bf16_f32 v58, v62, v63
	v_cvt_pk_bf16_f32 v59, v64, v65
	v_cvt_pk_bf16_f32 v60, v122, v123
	v_cvt_pk_bf16_f32 v61, v124, v125
	s_cbranch_vccnz .LBB0_1981
	s_mov_b64 s[46:47], 0
	global_store_dwordx4 v[168:169], v[58:61], off offset:-4096
.LBB0_1981:
	s_andn2_b64 vcc, exec, s[46:47]
	s_cbranch_vccnz .LBB0_1983
	global_store_dwordx4 v[168:169], v[58:61], off offset:-4096 sc1
	s_nop 1
.LBB0_1983:
	s_waitcnt vmcnt(6)
	v_lshlrev_b32_e32 v60, 16, v90
	v_and_b32_e32 v61, 0xffff0000, v90
	v_pk_add_f32 v[54:55], v[54:55], v[60:61]
	v_lshlrev_b32_e32 v60, 16, v91
	v_and_b32_e32 v61, 0xffff0000, v91
	v_pk_add_f32 v[56:57], v[56:57], v[60:61]
	v_lshlrev_b32_e32 v60, 16, v92
	v_and_b32_e32 v61, 0xffff0000, v92
	v_pk_add_f32 v[60:61], v[50:51], v[60:61]
	v_lshlrev_b32_e32 v50, 16, v93
	v_and_b32_e32 v51, 0xffff0000, v93
	v_pk_add_f32 v[90:91], v[52:53], v[50:51]
	v_cvt_pk_bf16_f32 v50, v54, v55
	v_cvt_pk_bf16_f32 v51, v56, v57
	v_cvt_pk_bf16_f32 v52, v60, v61
	v_cvt_pk_bf16_f32 v53, v90, v91
	s_and_b64 vcc, exec, s[6:7]
	s_mov_b64 s[46:47], -1
	s_cbranch_vccnz .LBB0_1985
	s_mov_b64 s[46:47], 0
	global_store_dwordx4 v[172:173], v[50:53], off offset:-4096
.LBB0_1985:
	s_andn2_b64 vcc, exec, s[46:47]
	s_cbranch_vccnz .LBB0_1987
	global_store_dwordx4 v[172:173], v[50:53], off offset:-4096 sc1
	s_nop 1

.LBB0_1993:
	s_or_b64 exec, exec, s[46:47]
	s_waitcnt lgkmcnt(0)
	s_waitcnt vmcnt(5)
	v_lshlrev_b32_e32 v50, 16, v86
	v_and_b32_e32 v51, 0xffff0000, v86
	v_pk_add_f32 v[46:47], v[46:47], v[50:51]
	v_lshlrev_b32_e32 v50, 16, v87
	v_and_b32_e32 v51, 0xffff0000, v87
	v_pk_add_f32 v[48:49], v[48:49], v[50:51]
	v_lshlrev_b32_e32 v50, 16, v88
	v_and_b32_e32 v51, 0xffff0000, v88
	v_pk_add_f32 v[50:51], v[42:43], v[50:51]
	v_lshlrev_b32_e32 v42, 16, v89
	v_and_b32_e32 v43, 0xffff0000, v89
	v_pk_add_f32 v[52:53], v[44:45], v[42:43]
	v_cvt_pk_bf16_f32 v42, v46, v47
	v_cvt_pk_bf16_f32 v43, v48, v49
	v_cvt_pk_bf16_f32 v44, v50, v51
	v_cvt_pk_bf16_f32 v45, v52, v53
	s_nor_b64 s[46:47], s[48:49], s[42:43]
	s_and_saveexec_b64 s[48:49], s[46:47]
	s_xor_b64 s[46:47], exec, s[48:49]
	s_cbranch_execz .LBB0_1995
	global_store_dwordx4 v[168:169], v[42:45], off offset:-2048
.LBB0_1995:
	s_andn2_saveexec_b64 s[46:47], s[46:47]
	s_cbranch_execz .LBB0_1997
	global_store_dwordx4 v[168:169], v[42:45], off offset:-2048 sc1
	s_nop 1
.LBB0_1997:
	s_or_b64 exec, exec, s[46:47]
	s_waitcnt vmcnt(4)
	v_lshlrev_b32_e32 v44, 16, v82
	v_and_b32_e32 v45, 0xffff0000, v82
	v_pk_add_f32 v[38:39], v[38:39], v[44:45]
	v_lshlrev_b32_e32 v44, 16, v83
	v_and_b32_e32 v45, 0xffff0000, v83
	v_pk_add_f32 v[40:41], v[40:41], v[44:45]
	v_lshlrev_b32_e32 v44, 16, v84
	v_and_b32_e32 v45, 0xffff0000, v84
	v_pk_add_f32 v[44:45], v[34:35], v[44:45]
	v_lshlrev_b32_e32 v34, 16, v85
	v_and_b32_e32 v35, 0xffff0000, v85
	v_pk_add_f32 v[54:55], v[36:37], v[34:35]
	v_cvt_pk_bf16_f32 v34, v38, v39
	v_cvt_pk_bf16_f32 v35, v40, v41
	v_cvt_pk_bf16_f32 v36, v44, v45
	v_cvt_pk_bf16_f32 v37, v54, v55
	s_and_b64 vcc, exec, s[6:7]
	s_mov_b64 s[46:47], -1
	s_cbranch_vccnz .LBB0_1999
	s_mov_b64 s[46:47], 0
	global_store_dwordx4 v[172:173], v[34:37], off offset:-2048
.LBB0_1999:
	s_andn2_b64 vcc, exec, s[46:47]
	s_cbranch_vccnz .LBB0_2001
	global_store_dwordx4 v[172:173], v[34:37], off offset:-2048 sc1
	s_nop 1

.LBB0_2007:
	s_or_b64 exec, exec, s[46:47]
	s_waitcnt lgkmcnt(0)
	s_waitcnt vmcnt(3)
	v_lshlrev_b32_e32 v34, 16, v78
	v_and_b32_e32 v35, 0xffff0000, v78
	v_pk_add_f32 v[30:31], v[30:31], v[34:35]
	v_lshlrev_b32_e32 v34, 16, v79
	v_and_b32_e32 v35, 0xffff0000, v79
	v_pk_add_f32 v[32:33], v[32:33], v[34:35]
	v_lshlrev_b32_e32 v34, 16, v80
	v_and_b32_e32 v35, 0xffff0000, v80
	v_pk_add_f32 v[34:35], v[26:27], v[34:35]
	v_lshlrev_b32_e32 v26, 16, v81
	v_and_b32_e32 v27, 0xffff0000, v81
	v_pk_add_f32 v[36:37], v[28:29], v[26:27]
	v_cvt_pk_bf16_f32 v26, v30, v31
	v_cvt_pk_bf16_f32 v27, v32, v33
	v_cvt_pk_bf16_f32 v28, v34, v35
	v_cvt_pk_bf16_f32 v29, v36, v37
	s_nor_b64 s[46:47], s[48:49], s[42:43]
	s_and_saveexec_b64 s[48:49], s[46:47]
	s_xor_b64 s[46:47], exec, s[48:49]
	s_cbranch_execz .LBB0_2009
	global_store_dwordx4 v[168:169], v[26:29], off
.LBB0_2009:
	s_andn2_saveexec_b64 s[46:47], s[46:47]
	s_cbranch_execz .LBB0_2011
	global_store_dwordx4 v[168:169], v[26:29], off sc1
	s_nop 1
.LBB0_2011:
	s_or_b64 exec, exec, s[46:47]
	s_waitcnt vmcnt(2)
	v_lshlrev_b32_e32 v28, 16, v74
	v_and_b32_e32 v29, 0xffff0000, v74
	v_pk_add_f32 v[22:23], v[22:23], v[28:29]
	v_lshlrev_b32_e32 v28, 16, v75
	v_and_b32_e32 v29, 0xffff0000, v75
	v_pk_add_f32 v[24:25], v[24:25], v[28:29]
	v_lshlrev_b32_e32 v28, 16, v76
	v_and_b32_e32 v29, 0xffff0000, v76
	v_pk_add_f32 v[28:29], v[18:19], v[28:29]
	v_lshlrev_b32_e32 v18, 16, v77
	v_and_b32_e32 v19, 0xffff0000, v77
	v_pk_add_f32 v[38:39], v[20:21], v[18:19]
	v_cvt_pk_bf16_f32 v18, v22, v23
	v_cvt_pk_bf16_f32 v19, v24, v25
	v_cvt_pk_bf16_f32 v20, v28, v29
	v_cvt_pk_bf16_f32 v21, v38, v39
	s_and_b64 vcc, exec, s[6:7]
	s_mov_b64 s[46:47], -1
	s_cbranch_vccnz .LBB0_2013
	s_mov_b64 s[46:47], 0
	global_store_dwordx4 v[172:173], v[18:21], off
.LBB0_2013:
	s_andn2_b64 vcc, exec, s[46:47]
	s_cbranch_vccnz .LBB0_2015
	global_store_dwordx4 v[172:173], v[18:21], off sc1
	s_nop 1

.LBB0_2021:
	s_or_b64 exec, exec, s[46:47]
	s_waitcnt lgkmcnt(0)
	s_waitcnt vmcnt(1)
	v_lshlrev_b32_e32 v18, 16, v70
	v_and_b32_e32 v19, 0xffff0000, v70
	v_pk_add_f32 v[14:15], v[14:15], v[18:19]
	v_lshlrev_b32_e32 v18, 16, v71
	v_and_b32_e32 v19, 0xffff0000, v71
	v_pk_add_f32 v[16:17], v[16:17], v[18:19]
	v_lshlrev_b32_e32 v18, 16, v72
	v_and_b32_e32 v19, 0xffff0000, v72
	v_pk_add_f32 v[18:19], v[10:11], v[18:19]
	v_lshlrev_b32_e32 v10, 16, v73
	v_and_b32_e32 v11, 0xffff0000, v73
	v_pk_add_f32 v[20:21], v[12:13], v[10:11]
	v_cvt_pk_bf16_f32 v10, v14, v15
	v_cvt_pk_bf16_f32 v11, v16, v17
	v_cvt_pk_bf16_f32 v12, v18, v19
	v_cvt_pk_bf16_f32 v13, v20, v21
	s_nor_b64 s[42:43], s[48:49], s[42:43]
	s_and_saveexec_b64 s[46:47], s[42:43]
	s_xor_b64 s[42:43], exec, s[46:47]
	s_cbranch_execz .LBB0_2023
	global_store_dwordx4 v[168:169], v[10:13], off offset:2048
.LBB0_2023:
	s_andn2_saveexec_b64 s[42:43], s[42:43]
	s_cbranch_execz .LBB0_2025
	global_store_dwordx4 v[168:169], v[10:13], off offset:2048 sc1
	s_nop 1
.LBB0_2025:
	s_or_b64 exec, exec, s[42:43]
	s_waitcnt vmcnt(0)
	v_lshlrev_b32_e32 v12, 16, v66
	v_and_b32_e32 v13, 0xffff0000, v66
	v_pk_add_f32 v[6:7], v[6:7], v[12:13]
	v_lshlrev_b32_e32 v12, 16, v67
	v_and_b32_e32 v13, 0xffff0000, v67
	v_pk_add_f32 v[8:9], v[8:9], v[12:13]
	v_lshlrev_b32_e32 v12, 16, v68
	v_and_b32_e32 v13, 0xffff0000, v68
	v_pk_add_f32 v[12:13], v[2:3], v[12:13]
	v_lshlrev_b32_e32 v2, 16, v69
	v_and_b32_e32 v3, 0xffff0000, v69
	v_pk_add_f32 v[22:23], v[4:5], v[2:3]
	v_cvt_pk_bf16_f32 v2, v6, v7
	v_cvt_pk_bf16_f32 v3, v8, v9
	v_cvt_pk_bf16_f32 v4, v12, v13
	v_cvt_pk_bf16_f32 v5, v22, v23
	s_and_b64 vcc, exec, s[6:7]
	s_mov_b64 s[42:43], -1
	s_cbranch_vccnz .LBB0_2027
	s_mov_b64 s[42:43], 0
	global_store_dwordx4 v[172:173], v[2:5], off offset:2048
.LBB0_2027:
	s_andn2_b64 vcc, exec, s[42:43]
	s_cbranch_vccnz .LBB0_2029
	global_store_dwordx4 v[172:173], v[2:5], off offset:2048 sc1
	s_nop 1

.LBB0_2120:
	s_add_u32 s56, s52, 0x10000
	s_addc_u32 s57, s53, 0
	s_and_b64 s[52:53], s[50:51], exec
	s_cselect_b32 s53, s57, s43
	s_cselect_b32 s52, s56, s88
	s_add_u32 s15, s18, s15
	s_addc_u32 s56, s19, 0
	s_add_u32 s15, s15, 0x10000
	s_waitcnt vmcnt(8)
	s_addc_u32 s56, s56, 0
	s_waitcnt lgkmcnt(0)
	s_and_b64 s[50:51], s[50:51], exec
	s_cselect_b32 s51, s56, s41
	s_cselect_b32 s50, s15, s89
	s_barrier
	s_setprio 1
	s_waitcnt lgkmcnt(7)
	v_mfma_f32_16x16x32_bf16 v[126:129], v[146:149], v[186:189], v[126:129]
	v_mfma_f32_16x16x32_bf16 v[122:125], v[154:157], v[186:189], v[122:125]
	s_waitcnt lgkmcnt(5)
	v_mfma_f32_16x16x32_bf16 v[118:121], v[146:149], v[178:181], v[118:121]
	v_mfma_f32_16x16x32_bf16 v[114:117], v[154:157], v[178:181], v[114:117]
	s_waitcnt lgkmcnt(3)
	v_mfma_f32_16x16x32_bf16 v[110:113], v[146:149], v[170:173], v[110:113]
	v_mfma_f32_16x16x32_bf16 v[106:109], v[154:157], v[170:173], v[106:109]
	s_waitcnt lgkmcnt(1)
	v_mfma_f32_16x16x32_bf16 v[102:105], v[146:149], v[162:165], v[102:105]
	v_mfma_f32_16x16x32_bf16 v[98:101], v[154:157], v[162:165], v[98:101]
	v_mfma_f32_16x16x32_bf16 v[126:129], v[150:153], v[190:193], v[126:129]
	v_mfma_f32_16x16x32_bf16 v[122:125], v[158:161], v[190:193], v[122:125]
	v_mfma_f32_16x16x32_bf16 v[118:121], v[150:153], v[182:185], v[118:121]
	v_mfma_f32_16x16x32_bf16 v[114:117], v[158:161], v[182:185], v[114:117]
	v_mfma_f32_16x16x32_bf16 v[110:113], v[150:153], v[174:177], v[110:113]
	v_mfma_f32_16x16x32_bf16 v[106:109], v[158:161], v[174:177], v[106:109]
	s_waitcnt lgkmcnt(0)
	v_mfma_f32_16x16x32_bf16 v[102:105], v[150:153], v[166:169], v[102:105]
	v_mfma_f32_16x16x32_bf16 v[98:101], v[158:161], v[166:169], v[98:101]
	s_setprio 0
	s_setprio 1
	v_mfma_f32_16x16x32_bf16 v[94:97], v[130:133], v[186:189], v[94:97]
	v_mfma_f32_16x16x32_bf16 v[90:93], v[138:141], v[186:189], v[90:93]
	v_mfma_f32_16x16x32_bf16 v[86:89], v[130:133], v[178:181], v[86:89]
	v_mfma_f32_16x16x32_bf16 v[82:85], v[138:141], v[178:181], v[82:85]
	v_mfma_f32_16x16x32_bf16 v[78:81], v[130:133], v[170:173], v[78:81]
	v_mfma_f32_16x16x32_bf16 v[74:77], v[138:141], v[170:173], v[74:77]
	v_mfma_f32_16x16x32_bf16 v[70:73], v[130:133], v[162:165], v[70:73]
	v_mfma_f32_16x16x32_bf16 v[66:69], v[138:141], v[162:165], v[66:69]
	v_mfma_f32_16x16x32_bf16 v[94:97], v[134:137], v[190:193], v[94:97]
	v_mfma_f32_16x16x32_bf16 v[90:93], v[142:145], v[190:193], v[90:93]
	v_mfma_f32_16x16x32_bf16 v[86:89], v[134:137], v[182:185], v[86:89]
	v_mfma_f32_16x16x32_bf16 v[82:85], v[142:145], v[182:185], v[82:85]
	v_mfma_f32_16x16x32_bf16 v[78:81], v[134:137], v[174:177], v[78:81]
	v_mfma_f32_16x16x32_bf16 v[74:77], v[142:145], v[174:177], v[74:77]
	v_mfma_f32_16x16x32_bf16 v[70:73], v[134:137], v[166:169], v[70:73]
	v_mfma_f32_16x16x32_bf16 v[66:69], v[142:145], v[166:169], v[66:69]
	s_setprio 0
	s_barrier
	ds_read_b128 v[186:189], v207 offset:16384
	ds_read_b128 v[190:193], v207 offset:17408
	ds_read_b128 v[178:181], v207 offset:18432
	ds_read_b128 v[182:185], v207 offset:19456
	ds_read_b128 v[170:173], v207 offset:20480
	ds_read_b128 v[174:177], v207 offset:21504
	ds_read_b128 v[162:165], v207 offset:22528
	ds_read_b128 v[166:169], v207 offset:23552
	s_mov_b32 m0, s62
	s_nop 0
	global_load_lds_dwordx4 v195, s[50:51]
	s_add_u32 m0, s62, 0x2000
	s_nop 0
	global_load_lds_dwordx4 v197, s[50:51]
	s_add_u32 s56, s50, 0x4000
	s_addc_u32 s57, s51, 0
	s_mov_b32 m0, s63
	s_nop 0
	global_load_lds_dwordx4 v195, s[56:57]
	s_add_u32 m0, s63, 0x2000
	s_nop 0
	global_load_lds_dwordx4 v197, s[56:57]
	s_andn2_b64 vcc, exec, s[54:55]
	s_mov_b32 m0, s61
	s_nop 0
	global_load_lds_dwordx4 v195, s[52:53]
	s_add_u32 m0, s61, 0x2000
	s_nop 0
	global_load_lds_dwordx4 v197, s[52:53]
	s_cbranch_vccnz .LBB0_2122
	v_mov_b32_e32 v2, 0
	v_mov_b32_e32 v3, v2
	v_mov_b32_e32 v4, v2
	v_mov_b32_e32 v5, v2
	v_mov_b32_e32 v6, v2
	v_mov_b32_e32 v7, v2
	v_mov_b32_e32 v8, v2
	v_mov_b32_e32 v9, v2
	v_mov_b32_e32 v10, v2
	v_mov_b32_e32 v11, v2
	v_mov_b32_e32 v12, v2
	v_mov_b32_e32 v13, v2
	v_mov_b32_e32 v14, v2
	v_mov_b32_e32 v15, v2
	v_mov_b32_e32 v16, v2
	v_mov_b32_e32 v17, v2
	v_mov_b32_e32 v18, v2
	v_mov_b32_e32 v19, v2
	v_mov_b32_e32 v20, v2
	v_mov_b32_e32 v21, v2
	v_mov_b32_e32 v22, v2
	v_mov_b32_e32 v23, v2
	v_mov_b32_e32 v24, v2
	v_mov_b32_e32 v25, v2
	v_mov_b32_e32 v26, v2
	v_mov_b32_e32 v27, v2
	v_mov_b32_e32 v28, v2
	v_mov_b32_e32 v29, v2
	v_mov_b32_e32 v30, v2
	v_mov_b32_e32 v31, v2
	v_mov_b32_e32 v32, v2
	v_mov_b32_e32 v33, v2
	v_mov_b32_e32 v34, v2
	v_mov_b32_e32 v35, v2
	v_mov_b32_e32 v36, v2
	v_mov_b32_e32 v37, v2
	v_mov_b32_e32 v38, v2
	v_mov_b32_e32 v39, v2
	v_mov_b32_e32 v40, v2
	v_mov_b32_e32 v41, v2
	v_mov_b32_e32 v42, v2
	v_mov_b32_e32 v43, v2
	v_mov_b32_e32 v44, v2
	v_mov_b32_e32 v45, v2
	v_mov_b32_e32 v46, v2
	v_mov_b32_e32 v47, v2
	v_mov_b32_e32 v48, v2
	v_mov_b32_e32 v49, v2
	v_mov_b32_e32 v50, v2
	v_mov_b32_e32 v51, v2
	v_mov_b32_e32 v52, v2
	v_mov_b32_e32 v53, v2
	v_mov_b32_e32 v54, v2
	v_mov_b32_e32 v55, v2
	v_mov_b32_e32 v56, v2
	v_mov_b32_e32 v57, v2
	v_mov_b32_e32 v58, v2
	v_mov_b32_e32 v59, v2
	v_mov_b32_e32 v60, v2
	v_mov_b32_e32 v61, v2
	v_mov_b32_e32 v62, v2
	v_mov_b32_e32 v63, v2
	v_mov_b32_e32 v64, v2
	v_mov_b32_e32 v65, v2
.LBB0_2122:
	s_waitcnt vmcnt(8)
	s_add_u32 s54, s52, 0x8000
	s_waitcnt lgkmcnt(0)
	s_addc_u32 s55, s53, 0
	s_add_u32 s56, s50, 0x8000
	s_addc_u32 s57, s51, 0
	s_barrier
	s_setprio 1
	s_waitcnt lgkmcnt(7)
	v_mfma_f32_16x16x32_bf16 v[62:65], v[146:149], v[186:189], v[62:65]
	v_mfma_f32_16x16x32_bf16 v[58:61], v[154:157], v[186:189], v[58:61]
	s_waitcnt lgkmcnt(5)
	v_mfma_f32_16x16x32_bf16 v[54:57], v[146:149], v[178:181], v[54:57]
	v_mfma_f32_16x16x32_bf16 v[50:53], v[154:157], v[178:181], v[50:53]
	s_waitcnt lgkmcnt(3)
	v_mfma_f32_16x16x32_bf16 v[46:49], v[146:149], v[170:173], v[46:49]
	v_mfma_f32_16x16x32_bf16 v[42:45], v[154:157], v[170:173], v[42:45]
	s_waitcnt lgkmcnt(1)
	v_mfma_f32_16x16x32_bf16 v[38:41], v[146:149], v[162:165], v[38:41]
	v_mfma_f32_16x16x32_bf16 v[34:37], v[154:157], v[162:165], v[34:37]
	v_mfma_f32_16x16x32_bf16 v[62:65], v[150:153], v[190:193], v[62:65]
	v_mfma_f32_16x16x32_bf16 v[58:61], v[158:161], v[190:193], v[58:61]
	v_mfma_f32_16x16x32_bf16 v[54:57], v[150:153], v[182:185], v[54:57]
	v_mfma_f32_16x16x32_bf16 v[50:53], v[158:161], v[182:185], v[50:53]
	v_mfma_f32_16x16x32_bf16 v[46:49], v[150:153], v[174:177], v[46:49]
	v_mfma_f32_16x16x32_bf16 v[42:45], v[158:161], v[174:177], v[42:45]
	s_waitcnt lgkmcnt(0)
	v_mfma_f32_16x16x32_bf16 v[38:41], v[150:153], v[166:169], v[38:41]
	v_mfma_f32_16x16x32_bf16 v[34:37], v[158:161], v[166:169], v[34:37]
	s_setprio 0
	s_setprio 1
	v_mfma_f32_16x16x32_bf16 v[30:33], v[130:133], v[186:189], v[30:33]
	v_mfma_f32_16x16x32_bf16 v[26:29], v[138:141], v[186:189], v[26:29]
	v_mfma_f32_16x16x32_bf16 v[22:25], v[130:133], v[178:181], v[22:25]
	v_mfma_f32_16x16x32_bf16 v[18:21], v[138:141], v[178:181], v[18:21]
	v_mfma_f32_16x16x32_bf16 v[14:17], v[130:133], v[170:173], v[14:17]
	v_mfma_f32_16x16x32_bf16 v[10:13], v[138:141], v[170:173], v[10:13]
	v_mfma_f32_16x16x32_bf16 v[6:9], v[130:133], v[162:165], v[6:9]
	v_mfma_f32_16x16x32_bf16 v[2:5], v[138:141], v[162:165], v[2:5]
	v_mfma_f32_16x16x32_bf16 v[30:33], v[134:137], v[190:193], v[30:33]
	v_mfma_f32_16x16x32_bf16 v[26:29], v[142:145], v[190:193], v[26:29]
	v_mfma_f32_16x16x32_bf16 v[22:25], v[134:137], v[182:185], v[22:25]
	v_mfma_f32_16x16x32_bf16 v[18:21], v[142:145], v[182:185], v[18:21]
	v_mfma_f32_16x16x32_bf16 v[14:17], v[134:137], v[174:177], v[14:17]
	v_mfma_f32_16x16x32_bf16 v[10:13], v[142:145], v[174:177], v[10:13]
	v_mfma_f32_16x16x32_bf16 v[6:9], v[134:137], v[166:169], v[6:9]
	v_mfma_f32_16x16x32_bf16 v[2:5], v[142:145], v[166:169], v[2:5]
	s_setprio 0
	s_barrier
	v_add_u32_e32 v142, 0x18000, v206
	v_add_u32_e32 v158, 0x1c000, v206
	ds_read_b128 v[130:133], v142
	ds_read_b128 v[134:137], v142 offset:1024
	ds_read_b128 v[138:141], v142 offset:2048
	ds_read_b128 v[142:145], v142 offset:3072
	ds_read_b128 v[146:149], v158
	ds_read_b128 v[150:153], v158 offset:1024
	ds_read_b128 v[154:157], v158 offset:2048
	ds_read_b128 v[158:161], v158 offset:3072
	ds_read_b128 v[162:165], v207 offset:32768
	ds_read_b128 v[166:169], v207 offset:33792
	ds_read_b128 v[170:173], v207 offset:34816
	ds_read_b128 v[174:177], v207 offset:35840
	ds_read_b128 v[178:181], v207 offset:36864
	ds_read_b128 v[182:185], v207 offset:37888
	ds_read_b128 v[186:189], v207 offset:38912
	ds_read_b128 v[190:193], v207 offset:39936
	s_add_u32 s52, s52, 0x4000
	s_addc_u32 s53, s53, 0
	s_mov_b32 m0, s64
	s_nop 0
	global_load_lds_dwordx4 v195, s[52:53]
	s_add_u32 m0, s64, 0x2000
	s_nop 0
	global_load_lds_dwordx4 v197, s[52:53]
	s_waitcnt vmcnt(8)
	s_waitcnt lgkmcnt(0)
	s_barrier
	s_setprio 1
	s_waitcnt lgkmcnt(7)
	v_mfma_f32_16x16x32_bf16 v[126:129], v[130:133], v[162:165], v[126:129]
	v_mfma_f32_16x16x32_bf16 v[122:125], v[138:141], v[162:165], v[122:125]
	s_waitcnt lgkmcnt(5)
	v_mfma_f32_16x16x32_bf16 v[118:121], v[130:133], v[170:173], v[118:121]
	v_mfma_f32_16x16x32_bf16 v[114:117], v[138:141], v[170:173], v[114:117]
	s_waitcnt lgkmcnt(3)
	v_mfma_f32_16x16x32_bf16 v[110:113], v[130:133], v[178:181], v[110:113]
	v_mfma_f32_16x16x32_bf16 v[106:109], v[138:141], v[178:181], v[106:109]
	s_waitcnt lgkmcnt(1)
	v_mfma_f32_16x16x32_bf16 v[102:105], v[130:133], v[186:189], v[102:105]
	v_mfma_f32_16x16x32_bf16 v[98:101], v[138:141], v[186:189], v[98:101]
	v_mfma_f32_16x16x32_bf16 v[126:129], v[134:137], v[166:169], v[126:129]
	v_mfma_f32_16x16x32_bf16 v[122:125], v[142:145], v[166:169], v[122:125]
	v_mfma_f32_16x16x32_bf16 v[118:121], v[134:137], v[174:177], v[118:121]
	v_mfma_f32_16x16x32_bf16 v[114:117], v[142:145], v[174:177], v[114:117]
	v_mfma_f32_16x16x32_bf16 v[110:113], v[134:137], v[182:185], v[110:113]
	v_mfma_f32_16x16x32_bf16 v[106:109], v[142:145], v[182:185], v[106:109]
	s_waitcnt lgkmcnt(0)
	v_mfma_f32_16x16x32_bf16 v[102:105], v[134:137], v[190:193], v[102:105]
	v_mfma_f32_16x16x32_bf16 v[98:101], v[142:145], v[190:193], v[98:101]
	s_setprio 0
	s_setprio 1
	v_mfma_f32_16x16x32_bf16 v[94:97], v[146:149], v[162:165], v[94:97]
	v_mfma_f32_16x16x32_bf16 v[90:93], v[154:157], v[162:165], v[90:93]
	v_mfma_f32_16x16x32_bf16 v[86:89], v[146:149], v[170:173], v[86:89]
	v_mfma_f32_16x16x32_bf16 v[82:85], v[154:157], v[170:173], v[82:85]
	v_mfma_f32_16x16x32_bf16 v[78:81], v[146:149], v[178:181], v[78:81]
	v_mfma_f32_16x16x32_bf16 v[74:77], v[154:157], v[178:181], v[74:77]
	v_mfma_f32_16x16x32_bf16 v[70:73], v[146:149], v[186:189], v[70:73]
	v_mfma_f32_16x16x32_bf16 v[66:69], v[154:157], v[186:189], v[66:69]
	v_mfma_f32_16x16x32_bf16 v[94:97], v[150:153], v[166:169], v[94:97]
	v_mfma_f32_16x16x32_bf16 v[90:93], v[158:161], v[166:169], v[90:93]
	v_mfma_f32_16x16x32_bf16 v[86:89], v[150:153], v[174:177], v[86:89]
	v_mfma_f32_16x16x32_bf16 v[82:85], v[158:161], v[174:177], v[82:85]
	v_mfma_f32_16x16x32_bf16 v[78:81], v[150:153], v[182:185], v[78:81]
	v_mfma_f32_16x16x32_bf16 v[74:77], v[158:161], v[182:185], v[74:77]
	v_mfma_f32_16x16x32_bf16 v[70:73], v[150:153], v[190:193], v[70:73]
	v_mfma_f32_16x16x32_bf16 v[66:69], v[158:161], v[190:193], v[66:69]
	s_setprio 0
	s_barrier
	ds_read_b128 v[162:165], v207 offset:49152
	ds_read_b128 v[166:169], v207 offset:50176
	ds_read_b128 v[170:173], v207 offset:51200
	ds_read_b128 v[174:177], v207 offset:52224
	ds_read_b128 v[178:181], v207 offset:53248
	ds_read_b128 v[182:185], v207 offset:54272
	ds_read_b128 v[186:189], v207 offset:55296
	ds_read_b128 v[190:193], v207 offset:56320
	s_mov_b32 m0, s70
	s_nop 0
	global_load_lds_dwordx4 v195, s[56:57]
	s_add_u32 m0, s70, 0x2000
	s_nop 0
	global_load_lds_dwordx4 v197, s[56:57]
	s_add_u32 s50, s50, 0xc000
	s_addc_u32 s51, s51, 0
	s_mov_b32 m0, s72
	s_nop 0
	global_load_lds_dwordx4 v195, s[50:51]
	s_add_u32 m0, s72, 0x2000
	s_nop 0
	global_load_lds_dwordx4 v197, s[50:51]
	s_nop 0
	s_mov_b32 m0, s71
	s_nop 0
	global_load_lds_dwordx4 v195, s[54:55]
	s_add_u32 m0, s71, 0x2000
	s_nop 0
	global_load_lds_dwordx4 v197, s[54:55]
	s_waitcnt vmcnt(8)
	s_waitcnt lgkmcnt(0)
	s_barrier
	s_setprio 1
	s_waitcnt lgkmcnt(7)
	v_mfma_f32_16x16x32_bf16 v[62:65], v[130:133], v[162:165], v[62:65]
	v_mfma_f32_16x16x32_bf16 v[58:61], v[138:141], v[162:165], v[58:61]
	s_waitcnt lgkmcnt(5)
	v_mfma_f32_16x16x32_bf16 v[54:57], v[130:133], v[170:173], v[54:57]
	v_mfma_f32_16x16x32_bf16 v[50:53], v[138:141], v[170:173], v[50:53]
	s_waitcnt lgkmcnt(3)
	v_mfma_f32_16x16x32_bf16 v[46:49], v[130:133], v[178:181], v[46:49]
	v_mfma_f32_16x16x32_bf16 v[42:45], v[138:141], v[178:181], v[42:45]
	s_waitcnt lgkmcnt(1)
	v_mfma_f32_16x16x32_bf16 v[38:41], v[130:133], v[186:189], v[38:41]
	v_mfma_f32_16x16x32_bf16 v[34:37], v[138:141], v[186:189], v[34:37]
	v_mfma_f32_16x16x32_bf16 v[62:65], v[134:137], v[166:169], v[62:65]
	v_mfma_f32_16x16x32_bf16 v[58:61], v[142:145], v[166:169], v[58:61]
	v_mfma_f32_16x16x32_bf16 v[54:57], v[134:137], v[174:177], v[54:57]
	v_mfma_f32_16x16x32_bf16 v[50:53], v[142:145], v[174:177], v[50:53]
	v_mfma_f32_16x16x32_bf16 v[46:49], v[134:137], v[182:185], v[46:49]
	v_mfma_f32_16x16x32_bf16 v[42:45], v[142:145], v[182:185], v[42:45]
	s_waitcnt lgkmcnt(0)
	v_mfma_f32_16x16x32_bf16 v[38:41], v[134:137], v[190:193], v[38:41]
	v_mfma_f32_16x16x32_bf16 v[34:37], v[142:145], v[190:193], v[34:37]
	s_setprio 0
	s_setprio 1
	v_mfma_f32_16x16x32_bf16 v[30:33], v[146:149], v[162:165], v[30:33]
	v_mfma_f32_16x16x32_bf16 v[26:29], v[154:157], v[162:165], v[26:29]
	v_mfma_f32_16x16x32_bf16 v[22:25], v[146:149], v[170:173], v[22:25]
	v_mfma_f32_16x16x32_bf16 v[18:21], v[154:157], v[170:173], v[18:21]
	v_mfma_f32_16x16x32_bf16 v[14:17], v[146:149], v[178:181], v[14:17]
	v_mfma_f32_16x16x32_bf16 v[10:13], v[154:157], v[178:181], v[10:13]
	v_mfma_f32_16x16x32_bf16 v[6:9], v[146:149], v[186:189], v[6:9]
	v_mfma_f32_16x16x32_bf16 v[2:5], v[154:157], v[186:189], v[2:5]
	v_mfma_f32_16x16x32_bf16 v[30:33], v[150:153], v[166:169], v[30:33]
	v_mfma_f32_16x16x32_bf16 v[26:29], v[158:161], v[166:169], v[26:29]
	v_mfma_f32_16x16x32_bf16 v[22:25], v[150:153], v[174:177], v[22:25]
	v_mfma_f32_16x16x32_bf16 v[18:21], v[158:161], v[174:177], v[18:21]
	v_mfma_f32_16x16x32_bf16 v[14:17], v[150:153], v[182:185], v[14:17]
	v_mfma_f32_16x16x32_bf16 v[10:13], v[158:161], v[182:185], v[10:13]
	v_mfma_f32_16x16x32_bf16 v[6:9], v[150:153], v[190:193], v[6:9]
	v_mfma_f32_16x16x32_bf16 v[2:5], v[158:161], v[190:193], v[2:5]
	s_setprio 0
	s_barrier
	s_add_i32 s15, s90, 2
	s_cmp_gt_u32 s90, 13
	s_cbranch_scc1 .LBB0_2124
	v_mov_b32_e32 v130, v198
	s_mov_b32 s90, s15
	s_branch .LBB0_2099

.LBB0_2126:
	v_mov_b32_e32 v137, v210
	v_mov_b32_e32 v130, v202
	v_xor_b32_e32 v138, 32, v204
	v_add_u32_e32 v136, s68, v130
	v_lshl_add_u32 v130, s82, 8, v136
	v_lshlrev_b32_e32 v132, 2, v137
	v_ashrrev_i32_e32 v133, 31, v132
	v_ashrrev_i32_e32 v131, 31, v130
	v_lshl_add_u64 v[132:133], v[132:133], 2, s[2:3]
	v_lshlrev_b64 v[130:131], 6, v[130:131]
	v_lshl_add_u64 v[134:135], v[132:133], 0, v[130:131]
	v_lshl_add_u64 v[170:171], v[134:135], 0, 0
	global_load_dwordx4 v[130:133], v[134:135], off
	s_mov_b32 s98, 0x1000
	s_mov_b32 s99, 0x0
	v_lshl_add_u64 v[172:173], v[170:171], 0, s[98:99]
	global_load_dwordx4 v[140:143], v[172:173], off offset:-3072
	global_load_dwordx4 v[144:147], v[172:173], off offset:-2048
	global_load_dwordx4 v[148:151], v[172:173], off offset:-1024
	v_add_co_u32_e32 v134, vcc, s13, v134
	s_mul_i32 s10, s82, 44
	s_nop 0
	v_addc_co_u32_e32 v135, vcc, 0, v135, vcc
	global_load_dwordx4 v[152:155], v[134:135], off
	global_load_dwordx4 v[156:159], v[134:135], off offset:1024
	global_load_dwordx4 v[160:163], v[134:135], off offset:2048
	global_load_dwordx4 v[164:167], v[134:135], off offset:3072
	v_and_b32_e32 v135, 64, v204
	v_xor_b32_e32 v134, 16, v204
	v_add_u32_e32 v135, 64, v135
	v_cmp_lt_i32_e32 vcc, v134, v135
	s_lshl_b32 s11, s12, 1
	s_add_i32 s10, s10, s11
	v_cndmask_b32_e32 v134, v204, v134, vcc
	v_cmp_lt_i32_e32 vcc, v138, v135
	v_lshlrev_b32_e32 v139, 2, v134
	s_or_b32 s10, s10, s74
	v_cndmask_b32_e32 v135, v204, v138, vcc
	v_lshlrev_b32_e32 v168, 2, v135
	s_ashr_i32 s11, s10, 31
	v_lshl_add_u32 v138, v137, 3, s75
	s_lshl_b64 s[10:11], s[10:11], 15
	v_lshlrev_b32_e32 v137, 4, v137
	v_ashrrev_i32_e32 v138, 5, v138
	s_add_u32 s50, s65, s10
	v_and_b32_e32 v137, 48, v137
	s_addc_u32 s51, s66, s11
	s_cmpk_lt_i32 s82, 0x80
	s_cselect_b64 s[52:53], -1, 0
	s_xor_b64 s[54:55], s[36:37], -1
	s_and_b64 s[52:53], s[54:55], s[52:53]
	s_mov_b64 s[10:11], -1
	s_and_b64 vcc, exec, s[52:53]
	s_waitcnt vmcnt(7)
	v_mov_b32_e32 v134, v131
	v_mov_b32_e32 v135, v132
	v_mov_b32_e32 v131, v133
	s_waitcnt vmcnt(6)
	v_add_f32_e32 v132, v140, v141
	v_add_f32_e32 v133, v142, v143
	s_waitcnt vmcnt(5)
	v_add_f32_e32 v140, v144, v145
	v_add_f32_e32 v141, v146, v147
	s_waitcnt vmcnt(4)
	v_add_f32_e32 v142, v148, v149
	v_add_f32_e32 v143, v150, v151
	v_pk_add_f32 v[130:131], v[134:135], v[130:131]
	v_add_f32_e32 v132, v132, v133
	v_add_f32_e32 v133, v140, v141
	v_add_f32_e32 v134, v142, v143
	s_waitcnt vmcnt(3)
	v_add_f32_e32 v135, v152, v153
	v_add_f32_e32 v140, v154, v155
	s_waitcnt vmcnt(2)
	v_add_f32_e32 v141, v156, v157
	v_add_f32_e32 v142, v158, v159
	s_waitcnt vmcnt(1)
	v_add_f32_e32 v143, v160, v161
	v_add_f32_e32 v144, v162, v163
	v_add_f32_e32 v130, v130, v131
	v_add_f32_e32 v135, v135, v140
	v_add_f32_e32 v140, v141, v142
	v_add_f32_e32 v141, v143, v144
	ds_bpermute_b32 v143, v139, v130
	ds_bpermute_b32 v131, v139, v132
	ds_bpermute_b32 v148, v139, v134
	ds_bpermute_b32 v144, v139, v135
	ds_bpermute_b32 v147, v139, v133
	s_waitcnt lgkmcnt(4)
	v_add_f32_e32 v130, v130, v143
	s_waitcnt lgkmcnt(3)
	v_add_f32_e32 v152, v132, v131
	ds_bpermute_b32 v131, v168, v130
	ds_bpermute_b32 v154, v139, v141
	s_waitcnt vmcnt(0)
	v_add_f32_e32 v145, v164, v165
	v_add_f32_e32 v146, v166, v167
	v_add_f32_e32 v142, v145, v146
	s_waitcnt lgkmcnt(1)
	v_add_f32_e32 v130, v130, v131
	v_fmamk_f32 v130, v130, 0x3a800000, v205
	v_rsq_f32_e32 v130, v130
	v_add_f32_e32 v148, v134, v148
	v_add_f32_e32 v145, v135, v144
	v_add_f32_e32 v150, v133, v147
	v_pk_mul_f32 v[134:135], v[128:129], v[130:131] op_sel_hi:[1,0]
	v_pk_mul_f32 v[132:133], v[126:127], v[130:131] op_sel_hi:[1,0]
	v_pk_mul_f32 v[156:157], v[134:135], s[30:31] op_sel_hi:[1,0]
	s_waitcnt lgkmcnt(0)
	v_add_f32_e32 v141, v141, v154
	v_pk_mul_f32 v[154:155], v[132:133], s[30:31] op_sel_hi:[1,0]
	v_exp_f32_e32 v156, v156
	v_exp_f32_e32 v157, v157
	v_exp_f32_e32 v154, v154
	v_exp_f32_e32 v155, v155
	v_pk_mul_f32 v[160:161], v[96:97], v[130:131] op_sel_hi:[1,0]
	v_pk_add_f32 v[156:157], v[156:157], 1.0 op_sel_hi:[1,0]
	v_pk_mul_f32 v[162:163], v[122:123], v[130:131] op_sel_hi:[1,0]
	v_pk_add_f32 v[154:155], v[154:155], 1.0 op_sel_hi:[1,0]
	v_rcp_f32_e32 v156, v156
	v_rcp_f32_e32 v157, v157
	v_rcp_f32_e32 v154, v154
	v_rcp_f32_e32 v155, v155
	v_pk_mul_f32 v[158:159], v[94:95], v[130:131] op_sel_hi:[1,0]
	v_pk_mul_f32 v[134:135], v[134:135], v[156:157]
	v_pk_mul_f32 v[156:157], v[124:125], v[130:131] op_sel_hi:[1,0]
	v_pk_mul_f32 v[132:133], v[132:133], v[154:155]
	v_pk_mul_f32 v[154:155], v[160:161], v[134:135]
	v_pk_mul_f32 v[134:135], v[162:163], s[30:31] op_sel_hi:[1,0]
	v_pk_mul_f32 v[132:133], v[158:159], v[132:133]
	v_exp_f32_e32 v134, v134
	v_exp_f32_e32 v135, v135
	v_pk_mul_f32 v[158:159], v[156:157], s[30:31] op_sel_hi:[1,0]
	ds_bpermute_b32 v146, v139, v140
	v_exp_f32_e32 v158, v158
	v_exp_f32_e32 v159, v159
	v_pk_add_f32 v[134:135], v[134:135], 1.0 op_sel_hi:[1,0]
	ds_bpermute_b32 v139, v139, v142
	v_rcp_f32_e32 v134, v134
	v_rcp_f32_e32 v135, v135
	v_pk_add_f32 v[158:159], v[158:159], 1.0 op_sel_hi:[1,0]
	v_pk_mul_f32 v[164:165], v[90:91], v[130:131] op_sel_hi:[1,0]
	v_rcp_f32_e32 v158, v158
	v_rcp_f32_e32 v159, v159
	v_pk_mul_f32 v[134:135], v[162:163], v[134:135]
	v_pk_mul_f32 v[130:131], v[92:93], v[130:131] op_sel_hi:[1,0]
	v_pk_mul_f32 v[160:161], v[164:165], v[134:135]
	v_pk_mul_f32 v[134:135], v[156:157], v[158:159]
	s_waitcnt lgkmcnt(1)
	v_add_f32_e32 v143, v140, v146
	v_pk_mul_f32 v[156:157], v[130:131], v[134:135]
	v_lshrrev_b32_e32 v131, 3, v136
	s_waitcnt lgkmcnt(0)
	v_add_f32_e32 v139, v142, v139
	v_lshlrev_b32_e32 v130, 7, v136
	v_and_b32_e32 v131, 14, v131
	ds_bpermute_b32 v153, v168, v152
	ds_bpermute_b32 v151, v168, v150
	ds_bpermute_b32 v149, v168, v148
	ds_bpermute_b32 v146, v168, v145
	ds_bpermute_b32 v144, v168, v143
	ds_bpermute_b32 v142, v168, v141
	ds_bpermute_b32 v140, v168, v139
	v_and_b32_e32 v130, 0xffffc000, v130
	v_lshlrev_b32_e32 v134, 6, v136
	v_add_lshl_u32 v147, v131, v138, 10
	v_lshlrev_b32_e32 v131, 2, v136
	v_and_or_b32 v134, v134, s69, v137
	v_and_b32_e32 v131, 32, v131
	v_add_u32_e32 v130, v147, v130
	v_bitop3_b32 v130, v130, v134, v131 bitop3:0xf6
	v_ashrrev_i32_e32 v131, 31, v130
	v_lshl_add_u64 v[134:135], s[50:51], 0, v[130:131]
	v_cvt_pk_bf16_f32 v130, v132, v133
	v_cvt_pk_bf16_f32 v131, v154, v155
	v_cvt_pk_bf16_f32 v132, v160, v161
	v_cvt_pk_bf16_f32 v133, v156, v157
	v_lshl_add_u64 v[170:171], v[134:135], 0, 0
	s_cbranch_vccz .LBB0_2128
	global_store_dwordx4 v[134:135], v[130:133], off
	s_mov_b64 s[10:11], 0
.LBB0_2128:
	s_mov_b32 s98, 0x1000
	s_mov_b32 s99, 0x0
	v_lshl_add_u64 v[172:173], v[170:171], 0, s[98:99]
	s_andn2_b64 vcc, exec, s[10:11]
	s_cbranch_vccnz .LBB0_2130
	global_store_dwordx4 v[172:173], v[130:133], off offset:-4096 sc1
	s_nop 1
.LBB0_2130:
	s_waitcnt lgkmcnt(6)
	v_add_f32_e32 v130, v152, v153
	v_fmamk_f32 v130, v130, 0x3a800000, v205
	v_rsq_f32_e32 v130, v130
	s_andn2_b64 vcc, exec, s[52:53]
	v_pk_mul_f32 v[132:133], v[118:119], v[130:131] op_sel_hi:[1,0]
	s_nop 0
	v_pk_mul_f32 v[152:153], v[132:133], s[30:31] op_sel_hi:[1,0]
	v_pk_mul_f32 v[154:155], v[120:121], v[130:131] op_sel_hi:[1,0]
	v_exp_f32_e32 v152, v152
	v_exp_f32_e32 v153, v153
	v_pk_mul_f32 v[156:157], v[154:155], s[30:31] op_sel_hi:[1,0]
	v_pk_mul_f32 v[134:135], v[86:87], v[130:131] op_sel_hi:[1,0]
	v_exp_f32_e32 v156, v156
	v_exp_f32_e32 v157, v157
	v_pk_add_f32 v[152:153], v[152:153], 1.0 op_sel_hi:[1,0]
	v_pk_mul_f32 v[158:159], v[116:117], v[130:131] op_sel_hi:[1,0]
	v_rcp_f32_e32 v152, v152
	v_rcp_f32_e32 v153, v153
	v_pk_add_f32 v[156:157], v[156:157], 1.0 op_sel_hi:[1,0]
	v_pk_mul_f32 v[160:161], v[158:159], s[30:31] op_sel_hi:[1,0]
	v_rcp_f32_e32 v156, v156
	v_rcp_f32_e32 v157, v157
	v_pk_mul_f32 v[132:133], v[132:133], v[152:153]
	v_exp_f32_e32 v160, v160
	v_pk_mul_f32 v[132:133], v[134:135], v[132:133]
	v_pk_mul_f32 v[134:135], v[88:89], v[130:131] op_sel_hi:[1,0]
	v_pk_mul_f32 v[152:153], v[154:155], v[156:157]
	v_exp_f32_e32 v161, v161
	v_pk_mul_f32 v[152:153], v[134:135], v[152:153]
	v_pk_mul_f32 v[134:135], v[114:115], v[130:131] op_sel_hi:[1,0]
	v_pk_mul_f32 v[154:155], v[82:83], v[130:131] op_sel_hi:[1,0]
	v_pk_mul_f32 v[156:157], v[134:135], s[30:31] op_sel_hi:[1,0]
	v_pk_add_f32 v[160:161], v[160:161], 1.0 op_sel_hi:[1,0]
	v_exp_f32_e32 v156, v156
	v_exp_f32_e32 v157, v157
	v_rcp_f32_e32 v160, v160
	v_rcp_f32_e32 v161, v161
	v_pk_mul_f32 v[130:131], v[84:85], v[130:131] op_sel_hi:[1,0]
	v_pk_add_f32 v[156:157], v[156:157], 1.0 op_sel_hi:[1,0]
	s_nop 0
	v_rcp_f32_e32 v156, v156
	v_rcp_f32_e32 v157, v157
	s_nop 0
	v_pk_mul_f32 v[134:135], v[134:135], v[156:157]
	s_nop 0
	v_pk_mul_f32 v[154:155], v[154:155], v[134:135]
	v_pk_mul_f32 v[134:135], v[158:159], v[160:161]
	s_nop 0
	v_pk_mul_f32 v[156:157], v[130:131], v[134:135]
	s_nop 0
	s_nop 0
	s_nop 0
	s_nop 0
	v_cvt_pk_bf16_f32 v131, v152, v153
	v_cndmask_b32_e64 v152, 0, 1, s[52:53]
	v_cvt_pk_bf16_f32 v130, v132, v133
	v_cvt_pk_bf16_f32 v132, v154, v155
	v_cvt_pk_bf16_f32 v133, v156, v157
	v_cmp_ne_u32_e64 s[10:11], 1, v152
	s_mov_b64 s[52:53], -1
	s_cbranch_vccnz .LBB0_2132
	s_mov_b64 s[52:53], 0
	global_store_dwordx4 v[172:173], v[130:133], off offset:-2048
.LBB0_2132:
	s_andn2_b64 vcc, exec, s[52:53]
	s_cbranch_vccnz .LBB0_2134
	global_store_dwordx4 v[172:173], v[130:133], off offset:-2048 sc1
	s_nop 1
.LBB0_2134:
	s_waitcnt lgkmcnt(5)
	v_add_f32_e32 v130, v150, v151
	v_fmamk_f32 v130, v130, 0x3a800000, v205
	v_rsq_f32_e32 v130, v130
	s_and_b64 vcc, exec, s[10:11]
	s_mov_b64 s[52:53], -1
	v_pk_mul_f32 v[132:133], v[110:111], v[130:131] op_sel_hi:[1,0]
	v_pk_mul_f32 v[152:153], v[112:113], v[130:131] op_sel_hi:[1,0]
	v_pk_mul_f32 v[150:151], v[132:133], s[30:31] op_sel_hi:[1,0]
	v_pk_mul_f32 v[154:155], v[152:153], s[30:31] op_sel_hi:[1,0]
	v_exp_f32_e32 v150, v150
	v_exp_f32_e32 v151, v151
	v_exp_f32_e32 v154, v154
	v_exp_f32_e32 v155, v155
	v_pk_mul_f32 v[134:135], v[78:79], v[130:131] op_sel_hi:[1,0]
	v_pk_add_f32 v[150:151], v[150:151], 1.0 op_sel_hi:[1,0]
	v_pk_mul_f32 v[156:157], v[108:109], v[130:131] op_sel_hi:[1,0]
	v_rcp_f32_e32 v150, v150
	v_rcp_f32_e32 v151, v151
	v_pk_add_f32 v[154:155], v[154:155], 1.0 op_sel_hi:[1,0]
	v_pk_mul_f32 v[158:159], v[156:157], s[30:31] op_sel_hi:[1,0]
	v_rcp_f32_e32 v154, v154
	v_rcp_f32_e32 v155, v155
	v_pk_mul_f32 v[132:133], v[132:133], v[150:151]
	v_exp_f32_e32 v158, v158
	v_pk_mul_f32 v[132:133], v[134:135], v[132:133]
	v_pk_mul_f32 v[134:135], v[80:81], v[130:131] op_sel_hi:[1,0]
	v_pk_mul_f32 v[150:151], v[152:153], v[154:155]
	v_exp_f32_e32 v159, v159
	v_pk_mul_f32 v[150:151], v[134:135], v[150:151]
	v_pk_mul_f32 v[134:135], v[106:107], v[130:131] op_sel_hi:[1,0]
	v_pk_mul_f32 v[152:153], v[74:75], v[130:131] op_sel_hi:[1,0]
	v_pk_mul_f32 v[154:155], v[134:135], s[30:31] op_sel_hi:[1,0]
	v_pk_add_f32 v[158:159], v[158:159], 1.0 op_sel_hi:[1,0]
	v_exp_f32_e32 v154, v154
	v_exp_f32_e32 v155, v155
	v_rcp_f32_e32 v158, v158
	v_rcp_f32_e32 v159, v159
	v_pk_mul_f32 v[130:131], v[76:77], v[130:131] op_sel_hi:[1,0]
	v_pk_add_f32 v[154:155], v[154:155], 1.0 op_sel_hi:[1,0]
	s_nop 0
	v_rcp_f32_e32 v154, v154
	v_rcp_f32_e32 v155, v155
	s_nop 0
	v_pk_mul_f32 v[134:135], v[134:135], v[154:155]
	s_nop 0
	v_pk_mul_f32 v[152:153], v[152:153], v[134:135]
	v_pk_mul_f32 v[134:135], v[156:157], v[158:159]
	s_nop 0
	v_pk_mul_f32 v[154:155], v[130:131], v[134:135]
	v_cvt_pk_bf16_f32 v130, v132, v133
	v_cvt_pk_bf16_f32 v131, v150, v151
	v_cvt_pk_bf16_f32 v132, v152, v153
	v_cvt_pk_bf16_f32 v133, v154, v155
	s_cbranch_vccnz .LBB0_2136
	s_mov_b64 s[52:53], 0
	global_store_dwordx4 v[172:173], v[130:133], off
.LBB0_2136:
	s_andn2_b64 vcc, exec, s[52:53]
	s_cbranch_vccnz .LBB0_2138
	global_store_dwordx4 v[172:173], v[130:133], off sc1
	s_nop 1
.LBB0_2138:
	s_waitcnt lgkmcnt(4)
	v_add_f32_e32 v130, v148, v149
	v_fmamk_f32 v130, v130, 0x3a800000, v205
	v_rsq_f32_e32 v130, v130
	s_and_b64 vcc, exec, s[10:11]
	s_mov_b64 s[52:53], -1
	v_pk_mul_f32 v[132:133], v[102:103], v[130:131] op_sel_hi:[1,0]
	v_pk_mul_f32 v[150:151], v[104:105], v[130:131] op_sel_hi:[1,0]
	v_pk_mul_f32 v[148:149], v[132:133], s[30:31] op_sel_hi:[1,0]
	v_pk_mul_f32 v[152:153], v[150:151], s[30:31] op_sel_hi:[1,0]
	v_exp_f32_e32 v148, v148
	v_exp_f32_e32 v149, v149
	v_exp_f32_e32 v152, v152
	v_exp_f32_e32 v153, v153
	v_pk_mul_f32 v[134:135], v[70:71], v[130:131] op_sel_hi:[1,0]
	v_pk_add_f32 v[148:149], v[148:149], 1.0 op_sel_hi:[1,0]
	v_pk_mul_f32 v[154:155], v[100:101], v[130:131] op_sel_hi:[1,0]
	v_rcp_f32_e32 v148, v148
	v_rcp_f32_e32 v149, v149
	v_pk_add_f32 v[152:153], v[152:153], 1.0 op_sel_hi:[1,0]
	v_pk_mul_f32 v[156:157], v[154:155], s[30:31] op_sel_hi:[1,0]
	v_rcp_f32_e32 v152, v152
	v_rcp_f32_e32 v153, v153
	v_pk_mul_f32 v[132:133], v[132:133], v[148:149]
	v_exp_f32_e32 v156, v156
	v_pk_mul_f32 v[132:133], v[134:135], v[132:133]
	v_pk_mul_f32 v[134:135], v[72:73], v[130:131] op_sel_hi:[1,0]
	v_pk_mul_f32 v[148:149], v[150:151], v[152:153]
	v_exp_f32_e32 v157, v157
	v_pk_mul_f32 v[148:149], v[134:135], v[148:149]
	v_pk_mul_f32 v[134:135], v[98:99], v[130:131] op_sel_hi:[1,0]
	v_pk_mul_f32 v[150:151], v[66:67], v[130:131] op_sel_hi:[1,0]
	v_pk_mul_f32 v[152:153], v[134:135], s[30:31] op_sel_hi:[1,0]
	v_pk_add_f32 v[156:157], v[156:157], 1.0 op_sel_hi:[1,0]
	v_exp_f32_e32 v152, v152
	v_exp_f32_e32 v153, v153
	v_rcp_f32_e32 v156, v156
	v_rcp_f32_e32 v157, v157
	v_pk_mul_f32 v[130:131], v[68:69], v[130:131] op_sel_hi:[1,0]
	v_pk_add_f32 v[152:153], v[152:153], 1.0 op_sel_hi:[1,0]
	s_nop 0
	v_rcp_f32_e32 v152, v152
	v_rcp_f32_e32 v153, v153
	s_nop 0
	v_pk_mul_f32 v[134:135], v[134:135], v[152:153]
	s_nop 0
	v_pk_mul_f32 v[150:151], v[150:151], v[134:135]
	v_pk_mul_f32 v[134:135], v[154:155], v[156:157]
	s_nop 0
	v_pk_mul_f32 v[152:153], v[130:131], v[134:135]
	v_cvt_pk_bf16_f32 v130, v132, v133
	v_cvt_pk_bf16_f32 v131, v148, v149
	v_cvt_pk_bf16_f32 v132, v150, v151
	v_cvt_pk_bf16_f32 v133, v152, v153
	s_cbranch_vccnz .LBB0_2140
	s_mov_b64 s[52:53], 0
	global_store_dwordx4 v[172:173], v[130:133], off offset:2048
.LBB0_2140:
	s_andn2_b64 vcc, exec, s[52:53]
	s_cbranch_vccnz .LBB0_2142
	global_store_dwordx4 v[172:173], v[130:133], off offset:2048 sc1
	s_nop 1
.LBB0_2142:
	s_waitcnt lgkmcnt(3)
	v_add_f32_e32 v130, v145, v146
	v_fmamk_f32 v130, v130, 0x3a800000, v205
	v_rsq_f32_e32 v130, v130
	s_nop 0
	s_and_b64 vcc, exec, s[10:11]
	v_pk_mul_f32 v[132:133], v[62:63], v[130:131] op_sel_hi:[1,0]
	v_pk_mul_f32 v[150:151], v[64:65], v[130:131] op_sel_hi:[1,0]
	v_pk_mul_f32 v[148:149], v[132:133], s[30:31] op_sel_hi:[1,0]
	v_pk_mul_f32 v[152:153], v[150:151], s[30:31] op_sel_hi:[1,0]
	v_exp_f32_e32 v148, v148
	v_exp_f32_e32 v149, v149
	v_exp_f32_e32 v152, v152
	v_exp_f32_e32 v153, v153
	v_pk_mul_f32 v[134:135], v[30:31], v[130:131] op_sel_hi:[1,0]
	v_pk_add_f32 v[148:149], v[148:149], 1.0 op_sel_hi:[1,0]
	v_pk_mul_f32 v[154:155], v[60:61], v[130:131] op_sel_hi:[1,0]
	v_rcp_f32_e32 v148, v148
	v_rcp_f32_e32 v149, v149
	v_pk_add_f32 v[152:153], v[152:153], 1.0 op_sel_hi:[1,0]
	v_pk_mul_f32 v[156:157], v[154:155], s[30:31] op_sel_hi:[1,0]
	v_rcp_f32_e32 v152, v152
	v_rcp_f32_e32 v153, v153
	v_pk_mul_f32 v[132:133], v[132:133], v[148:149]
	v_exp_f32_e32 v156, v156
	v_pk_mul_f32 v[132:133], v[134:135], v[132:133]
	v_pk_mul_f32 v[134:135], v[32:33], v[130:131] op_sel_hi:[1,0]
	v_pk_mul_f32 v[148:149], v[150:151], v[152:153]
	v_exp_f32_e32 v157, v157
	v_pk_mul_f32 v[148:149], v[134:135], v[148:149]
	v_pk_mul_f32 v[134:135], v[58:59], v[130:131] op_sel_hi:[1,0]
	v_pk_mul_f32 v[150:151], v[26:27], v[130:131] op_sel_hi:[1,0]
	v_pk_mul_f32 v[152:153], v[134:135], s[30:31] op_sel_hi:[1,0]
	v_pk_add_f32 v[156:157], v[156:157], 1.0 op_sel_hi:[1,0]
	v_exp_f32_e32 v152, v152
	v_exp_f32_e32 v153, v153
	v_rcp_f32_e32 v156, v156
	v_rcp_f32_e32 v157, v157
	v_pk_mul_f32 v[130:131], v[28:29], v[130:131] op_sel_hi:[1,0]
	v_pk_add_f32 v[152:153], v[152:153], 1.0 op_sel_hi:[1,0]
	s_mov_b64 s[52:53], -1
	v_rcp_f32_e32 v152, v152
	v_rcp_f32_e32 v153, v153
	s_nop 0
	v_pk_mul_f32 v[134:135], v[134:135], v[152:153]
	s_nop 0
	v_pk_mul_f32 v[150:151], v[150:151], v[134:135]
	v_pk_mul_f32 v[134:135], v[154:155], v[156:157]
	s_nop 0
	v_pk_mul_f32 v[152:153], v[130:131], v[134:135]
	v_cvt_pk_bf16_f32 v130, v132, v133
	v_cvt_pk_bf16_f32 v131, v148, v149
	v_cvt_pk_bf16_f32 v132, v150, v151
	v_cvt_pk_bf16_f32 v133, v152, v153
	s_mov_b32 s98, 0x5000
	s_mov_b32 s99, 0x0
	v_lshl_add_u64 v[172:173], v[170:171], 0, s[98:99]
	s_cbranch_vccnz .LBB0_2144
	s_mov_b64 s[52:53], 0
	global_store_dwordx4 v[172:173], v[130:133], off offset:-4096
.LBB0_2144:
	s_andn2_b64 vcc, exec, s[52:53]
	s_cbranch_vccnz .LBB0_2146
	global_store_dwordx4 v[172:173], v[130:133], off offset:-4096 sc1
	s_nop 1
.LBB0_2146:
	s_waitcnt lgkmcnt(2)
	v_add_f32_e32 v130, v143, v144
	v_fmamk_f32 v130, v130, 0x3a800000, v205
	v_rsq_f32_e32 v130, v130
	s_and_b64 vcc, exec, s[10:11]
	s_mov_b64 s[52:53], -1
	v_pk_mul_f32 v[132:133], v[54:55], v[130:131] op_sel_hi:[1,0]
	v_pk_mul_f32 v[146:147], v[56:57], v[130:131] op_sel_hi:[1,0]
	v_pk_mul_f32 v[144:145], v[132:133], s[30:31] op_sel_hi:[1,0]
	v_pk_mul_f32 v[148:149], v[146:147], s[30:31] op_sel_hi:[1,0]
	v_exp_f32_e32 v144, v144
	v_exp_f32_e32 v145, v145
	v_exp_f32_e32 v148, v148
	v_exp_f32_e32 v149, v149
	v_pk_mul_f32 v[134:135], v[22:23], v[130:131] op_sel_hi:[1,0]
	v_pk_add_f32 v[144:145], v[144:145], 1.0 op_sel_hi:[1,0]
	v_pk_mul_f32 v[150:151], v[52:53], v[130:131] op_sel_hi:[1,0]
	v_rcp_f32_e32 v144, v144
	v_rcp_f32_e32 v145, v145
	v_pk_add_f32 v[148:149], v[148:149], 1.0 op_sel_hi:[1,0]
	v_pk_mul_f32 v[152:153], v[150:151], s[30:31] op_sel_hi:[1,0]
	v_rcp_f32_e32 v148, v148
	v_rcp_f32_e32 v149, v149
	v_pk_mul_f32 v[132:133], v[132:133], v[144:145]
	v_exp_f32_e32 v152, v152
	v_pk_mul_f32 v[132:133], v[134:135], v[132:133]
	v_pk_mul_f32 v[134:135], v[24:25], v[130:131] op_sel_hi:[1,0]
	v_pk_mul_f32 v[144:145], v[146:147], v[148:149]
	v_exp_f32_e32 v153, v153
	v_pk_mul_f32 v[144:145], v[134:135], v[144:145]
	v_pk_mul_f32 v[134:135], v[50:51], v[130:131] op_sel_hi:[1,0]
	v_pk_mul_f32 v[146:147], v[18:19], v[130:131] op_sel_hi:[1,0]
	v_pk_mul_f32 v[148:149], v[134:135], s[30:31] op_sel_hi:[1,0]
	v_pk_add_f32 v[152:153], v[152:153], 1.0 op_sel_hi:[1,0]
	v_exp_f32_e32 v148, v148
	v_exp_f32_e32 v149, v149
	v_rcp_f32_e32 v152, v152
	v_rcp_f32_e32 v153, v153
	v_pk_mul_f32 v[130:131], v[20:21], v[130:131] op_sel_hi:[1,0]
	v_pk_add_f32 v[148:149], v[148:149], 1.0 op_sel_hi:[1,0]
	s_nop 0
	v_rcp_f32_e32 v148, v148
	v_rcp_f32_e32 v149, v149
	s_nop 0
	v_pk_mul_f32 v[134:135], v[134:135], v[148:149]
	s_nop 0
	v_pk_mul_f32 v[146:147], v[146:147], v[134:135]
	v_pk_mul_f32 v[134:135], v[150:151], v[152:153]
	s_nop 0
	v_pk_mul_f32 v[148:149], v[130:131], v[134:135]
	v_cvt_pk_bf16_f32 v130, v132, v133
	v_cvt_pk_bf16_f32 v131, v144, v145
	v_cvt_pk_bf16_f32 v132, v146, v147
	v_cvt_pk_bf16_f32 v133, v148, v149
	s_cbranch_vccnz .LBB0_2148
	s_mov_b64 s[52:53], 0
	global_store_dwordx4 v[172:173], v[130:133], off offset:-2048

.LBB0_2150:
	s_waitcnt lgkmcnt(1)
	v_add_f32_e32 v130, v141, v142
	v_fmamk_f32 v130, v130, 0x3a800000, v205
	v_rsq_f32_e32 v130, v130
	s_and_b64 vcc, exec, s[10:11]
	s_mov_b64 s[52:53], -1
	v_pk_mul_f32 v[132:133], v[46:47], v[130:131] op_sel_hi:[1,0]
	v_pk_mul_f32 v[144:145], v[48:49], v[130:131] op_sel_hi:[1,0]
	v_pk_mul_f32 v[142:143], v[132:133], s[30:31] op_sel_hi:[1,0]
	v_pk_mul_f32 v[146:147], v[144:145], s[30:31] op_sel_hi:[1,0]
	v_exp_f32_e32 v142, v142
	v_exp_f32_e32 v143, v143
	v_exp_f32_e32 v146, v146
	v_exp_f32_e32 v147, v147
	v_pk_mul_f32 v[134:135], v[14:15], v[130:131] op_sel_hi:[1,0]
	v_pk_add_f32 v[142:143], v[142:143], 1.0 op_sel_hi:[1,0]
	v_pk_mul_f32 v[148:149], v[44:45], v[130:131] op_sel_hi:[1,0]
	v_rcp_f32_e32 v142, v142
	v_rcp_f32_e32 v143, v143
	v_pk_add_f32 v[146:147], v[146:147], 1.0 op_sel_hi:[1,0]
	v_pk_mul_f32 v[150:151], v[148:149], s[30:31] op_sel_hi:[1,0]
	v_rcp_f32_e32 v146, v146
	v_rcp_f32_e32 v147, v147
	v_pk_mul_f32 v[132:133], v[132:133], v[142:143]
	v_exp_f32_e32 v150, v150
	v_pk_mul_f32 v[132:133], v[134:135], v[132:133]
	v_pk_mul_f32 v[134:135], v[16:17], v[130:131] op_sel_hi:[1,0]
	v_pk_mul_f32 v[142:143], v[144:145], v[146:147]
	v_exp_f32_e32 v151, v151
	v_pk_mul_f32 v[142:143], v[134:135], v[142:143]
	v_pk_mul_f32 v[134:135], v[42:43], v[130:131] op_sel_hi:[1,0]
	v_pk_mul_f32 v[144:145], v[10:11], v[130:131] op_sel_hi:[1,0]
	v_pk_mul_f32 v[146:147], v[134:135], s[30:31] op_sel_hi:[1,0]
	v_pk_add_f32 v[150:151], v[150:151], 1.0 op_sel_hi:[1,0]
	v_exp_f32_e32 v146, v146
	v_exp_f32_e32 v147, v147
	v_rcp_f32_e32 v150, v150
	v_rcp_f32_e32 v151, v151
	v_pk_mul_f32 v[130:131], v[12:13], v[130:131] op_sel_hi:[1,0]
	v_pk_add_f32 v[146:147], v[146:147], 1.0 op_sel_hi:[1,0]
	s_nop 0
	v_rcp_f32_e32 v146, v146
	v_rcp_f32_e32 v147, v147
	s_nop 0
	v_pk_mul_f32 v[134:135], v[134:135], v[146:147]
	s_nop 0
	v_pk_mul_f32 v[144:145], v[144:145], v[134:135]
	v_pk_mul_f32 v[134:135], v[148:149], v[150:151]
	s_nop 0
	v_pk_mul_f32 v[146:147], v[130:131], v[134:135]
	v_cvt_pk_bf16_f32 v130, v132, v133
	v_cvt_pk_bf16_f32 v131, v142, v143
	v_cvt_pk_bf16_f32 v132, v144, v145
	v_cvt_pk_bf16_f32 v133, v146, v147
	s_cbranch_vccnz .LBB0_2152
	s_mov_b64 s[52:53], 0
	global_store_dwordx4 v[172:173], v[130:133], off

.LBB0_2154:
	s_waitcnt lgkmcnt(0)
	v_add_f32_e32 v130, v139, v140
	v_fmamk_f32 v130, v130, 0x3a800000, v205
	v_rsq_f32_e32 v130, v130
	s_and_b64 vcc, exec, s[10:11]
	s_mov_b64 s[10:11], -1
	v_pk_mul_f32 v[132:133], v[38:39], v[130:131] op_sel_hi:[1,0]
	v_pk_mul_f32 v[142:143], v[40:41], v[130:131] op_sel_hi:[1,0]
	v_pk_mul_f32 v[140:141], v[132:133], s[30:31] op_sel_hi:[1,0]
	v_pk_mul_f32 v[144:145], v[142:143], s[30:31] op_sel_hi:[1,0]
	v_exp_f32_e32 v140, v140
	v_exp_f32_e32 v141, v141
	v_exp_f32_e32 v144, v144
	v_exp_f32_e32 v145, v145
	v_pk_mul_f32 v[134:135], v[6:7], v[130:131] op_sel_hi:[1,0]
	v_pk_add_f32 v[140:141], v[140:141], 1.0 op_sel_hi:[1,0]
	v_pk_mul_f32 v[146:147], v[36:37], v[130:131] op_sel_hi:[1,0]
	v_rcp_f32_e32 v140, v140
	v_rcp_f32_e32 v141, v141
	v_pk_add_f32 v[144:145], v[144:145], 1.0 op_sel_hi:[1,0]
	v_pk_mul_f32 v[148:149], v[146:147], s[30:31] op_sel_hi:[1,0]
	v_rcp_f32_e32 v144, v144
	v_rcp_f32_e32 v145, v145
	v_pk_mul_f32 v[132:133], v[132:133], v[140:141]
	v_exp_f32_e32 v148, v148
	v_pk_mul_f32 v[132:133], v[134:135], v[132:133]
	v_pk_mul_f32 v[134:135], v[8:9], v[130:131] op_sel_hi:[1,0]
	v_pk_mul_f32 v[140:141], v[142:143], v[144:145]
	v_exp_f32_e32 v149, v149
	v_pk_mul_f32 v[140:141], v[134:135], v[140:141]
	v_pk_mul_f32 v[134:135], v[34:35], v[130:131] op_sel_hi:[1,0]
	v_pk_mul_f32 v[142:143], v[2:3], v[130:131] op_sel_hi:[1,0]
	v_pk_mul_f32 v[144:145], v[134:135], s[30:31] op_sel_hi:[1,0]
	v_pk_add_f32 v[148:149], v[148:149], 1.0 op_sel_hi:[1,0]
	v_exp_f32_e32 v144, v144
	v_exp_f32_e32 v145, v145
	v_rcp_f32_e32 v148, v148
	v_rcp_f32_e32 v149, v149
	v_pk_mul_f32 v[130:131], v[4:5], v[130:131] op_sel_hi:[1,0]
	v_pk_add_f32 v[144:145], v[144:145], 1.0 op_sel_hi:[1,0]
	s_nop 0
	v_rcp_f32_e32 v144, v144
	v_rcp_f32_e32 v145, v145
	s_nop 0
	v_pk_mul_f32 v[134:135], v[134:135], v[144:145]
	s_nop 0
	v_pk_mul_f32 v[142:143], v[142:143], v[134:135]
	v_pk_mul_f32 v[134:135], v[146:147], v[148:149]
	s_nop 0
	v_pk_mul_f32 v[144:145], v[130:131], v[134:135]
	v_cvt_pk_bf16_f32 v130, v132, v133
	v_cvt_pk_bf16_f32 v131, v140, v141
	v_cvt_pk_bf16_f32 v132, v142, v143
	v_cvt_pk_bf16_f32 v133, v144, v145
	s_cbranch_vccnz .LBB0_2156
	s_mov_b64 s[10:11], 0
	global_store_dwordx4 v[172:173], v[130:133], off offset:2048
.LBB0_2156:
	s_andn2_b64 vcc, exec, s[10:11]
	s_cbranch_vccnz .LBB0_2158
	global_store_dwordx4 v[172:173], v[130:133], off offset:2048 sc1
	s_nop 1

.LBB0_2229:
	s_add_i32 s22, s46, 2
	s_lshl_b64 s[42:43], s[22:23], 15
	s_add_u32 s44, s2, s42
	s_addc_u32 s45, s3, s43
	s_and_b64 s[38:39], s[14:15], exec
	s_cselect_b32 s39, s45, s29
	s_cselect_b32 s38, s44, s28
	s_add_u32 s42, s16, s42
	s_waitcnt vmcnt(8)
	s_addc_u32 s43, s17, s43
	s_waitcnt lgkmcnt(0)
	s_and_b64 s[14:15], s[14:15], exec
	s_cselect_b32 s15, s43, s31
	s_cselect_b32 s14, s42, s30
	s_barrier
	s_setprio 1
	s_waitcnt lgkmcnt(7)
	v_mfma_f32_16x16x32_bf16 v[126:129], v[146:149], v[186:189], v[126:129]
	v_mfma_f32_16x16x32_bf16 v[122:125], v[154:157], v[186:189], v[122:125]
	s_waitcnt lgkmcnt(5)
	v_mfma_f32_16x16x32_bf16 v[118:121], v[146:149], v[178:181], v[118:121]
	v_mfma_f32_16x16x32_bf16 v[114:117], v[154:157], v[178:181], v[114:117]
	s_waitcnt lgkmcnt(3)
	v_mfma_f32_16x16x32_bf16 v[110:113], v[146:149], v[170:173], v[110:113]
	v_mfma_f32_16x16x32_bf16 v[106:109], v[154:157], v[170:173], v[106:109]
	s_waitcnt lgkmcnt(1)
	v_mfma_f32_16x16x32_bf16 v[102:105], v[146:149], v[162:165], v[102:105]
	v_mfma_f32_16x16x32_bf16 v[98:101], v[154:157], v[162:165], v[98:101]
	v_mfma_f32_16x16x32_bf16 v[126:129], v[150:153], v[190:193], v[126:129]
	v_mfma_f32_16x16x32_bf16 v[122:125], v[158:161], v[190:193], v[122:125]
	v_mfma_f32_16x16x32_bf16 v[118:121], v[150:153], v[182:185], v[118:121]
	v_mfma_f32_16x16x32_bf16 v[114:117], v[158:161], v[182:185], v[114:117]
	v_mfma_f32_16x16x32_bf16 v[110:113], v[150:153], v[174:177], v[110:113]
	v_mfma_f32_16x16x32_bf16 v[106:109], v[158:161], v[174:177], v[106:109]
	s_waitcnt lgkmcnt(0)
	v_mfma_f32_16x16x32_bf16 v[102:105], v[150:153], v[166:169], v[102:105]
	v_mfma_f32_16x16x32_bf16 v[98:101], v[158:161], v[166:169], v[98:101]
	s_setprio 0
	s_setprio 1
	v_mfma_f32_16x16x32_bf16 v[94:97], v[130:133], v[186:189], v[94:97]
	v_mfma_f32_16x16x32_bf16 v[90:93], v[138:141], v[186:189], v[90:93]
	v_mfma_f32_16x16x32_bf16 v[86:89], v[130:133], v[178:181], v[86:89]
	v_mfma_f32_16x16x32_bf16 v[82:85], v[138:141], v[178:181], v[82:85]
	v_mfma_f32_16x16x32_bf16 v[78:81], v[130:133], v[170:173], v[78:81]
	v_mfma_f32_16x16x32_bf16 v[74:77], v[138:141], v[170:173], v[74:77]
	v_mfma_f32_16x16x32_bf16 v[70:73], v[130:133], v[162:165], v[70:73]
	v_mfma_f32_16x16x32_bf16 v[66:69], v[138:141], v[162:165], v[66:69]
	v_mfma_f32_16x16x32_bf16 v[94:97], v[134:137], v[190:193], v[94:97]
	v_mfma_f32_16x16x32_bf16 v[90:93], v[142:145], v[190:193], v[90:93]
	v_mfma_f32_16x16x32_bf16 v[86:89], v[134:137], v[182:185], v[86:89]
	v_mfma_f32_16x16x32_bf16 v[82:85], v[142:145], v[182:185], v[82:85]
	v_mfma_f32_16x16x32_bf16 v[78:81], v[134:137], v[174:177], v[78:81]
	v_mfma_f32_16x16x32_bf16 v[74:77], v[142:145], v[174:177], v[74:77]
	v_mfma_f32_16x16x32_bf16 v[70:73], v[134:137], v[166:169], v[70:73]
	v_mfma_f32_16x16x32_bf16 v[66:69], v[142:145], v[166:169], v[66:69]
	s_setprio 0
	s_barrier
	ds_read_b128 v[186:189], v215 offset:16384
	ds_read_b128 v[190:193], v215 offset:17408
	ds_read_b128 v[178:181], v215 offset:18432
	ds_read_b128 v[182:185], v215 offset:19456
	ds_read_b128 v[170:173], v215 offset:20480
	ds_read_b128 v[174:177], v215 offset:21504
	ds_read_b128 v[162:165], v215 offset:22528
	ds_read_b128 v[166:169], v215 offset:23552
	s_mov_b32 m0, s57
	s_nop 0
	global_load_lds_dwordx4 v195, s[14:15]
	s_add_u32 m0, s57, 0x2000
	s_nop 0
	global_load_lds_dwordx4 v208, s[14:15]
	s_add_u32 s42, s14, 0x4000
	s_addc_u32 s43, s15, 0
	s_mov_b32 m0, s58
	s_nop 0
	global_load_lds_dwordx4 v195, s[42:43]
	s_add_u32 m0, s58, 0x2000
	s_nop 0
	global_load_lds_dwordx4 v208, s[42:43]
	s_andn2_b64 vcc, exec, s[40:41]
	s_mov_b32 m0, s56
	s_nop 0
	global_load_lds_dwordx4 v195, s[38:39]
	s_add_u32 m0, s56, 0x2000
	s_nop 0
	global_load_lds_dwordx4 v208, s[38:39]
	s_cbranch_vccnz .LBB0_2231
	v_mov_b32_e32 v2, 0
	v_mov_b32_e32 v3, v2
	v_mov_b32_e32 v4, v2
	v_mov_b32_e32 v5, v2
	v_mov_b32_e32 v6, v2
	v_mov_b32_e32 v7, v2
	v_mov_b32_e32 v8, v2
	v_mov_b32_e32 v9, v2
	v_mov_b32_e32 v10, v2
	v_mov_b32_e32 v11, v2
	v_mov_b32_e32 v12, v2
	v_mov_b32_e32 v13, v2
	v_mov_b32_e32 v14, v2
	v_mov_b32_e32 v15, v2
	v_mov_b32_e32 v16, v2
	v_mov_b32_e32 v17, v2
	v_mov_b32_e32 v18, v2
	v_mov_b32_e32 v19, v2
	v_mov_b32_e32 v20, v2
	v_mov_b32_e32 v21, v2
	v_mov_b32_e32 v22, v2
	v_mov_b32_e32 v23, v2
	v_mov_b32_e32 v24, v2
	v_mov_b32_e32 v25, v2
	v_mov_b32_e32 v26, v2
	v_mov_b32_e32 v27, v2
	v_mov_b32_e32 v28, v2
	v_mov_b32_e32 v29, v2
	v_mov_b32_e32 v30, v2
	v_mov_b32_e32 v31, v2
	v_mov_b32_e32 v32, v2
	v_mov_b32_e32 v33, v2
	v_mov_b32_e32 v34, v2
	v_mov_b32_e32 v35, v2
	v_mov_b32_e32 v36, v2
	v_mov_b32_e32 v37, v2
	v_mov_b32_e32 v38, v2
	v_mov_b32_e32 v39, v2
	v_mov_b32_e32 v40, v2
	v_mov_b32_e32 v41, v2
	v_mov_b32_e32 v42, v2
	v_mov_b32_e32 v43, v2
	v_mov_b32_e32 v44, v2
	v_mov_b32_e32 v45, v2
	v_mov_b32_e32 v46, v2
	v_mov_b32_e32 v47, v2
	v_mov_b32_e32 v48, v2
	v_mov_b32_e32 v49, v2
	v_mov_b32_e32 v50, v2
	v_mov_b32_e32 v51, v2
	v_mov_b32_e32 v52, v2
	v_mov_b32_e32 v53, v2
	v_mov_b32_e32 v54, v2
	v_mov_b32_e32 v55, v2
	v_mov_b32_e32 v56, v2
	v_mov_b32_e32 v57, v2
	v_mov_b32_e32 v58, v2
	v_mov_b32_e32 v59, v2
	v_mov_b32_e32 v60, v2
	v_mov_b32_e32 v61, v2
	v_mov_b32_e32 v62, v2
	v_mov_b32_e32 v63, v2
	v_mov_b32_e32 v64, v2
	v_mov_b32_e32 v65, v2
.LBB0_2231:
	s_waitcnt vmcnt(8)
	s_add_u32 s40, s38, 0x8000
	s_waitcnt lgkmcnt(0)
	s_addc_u32 s41, s39, 0
	s_add_u32 s42, s14, 0x8000
	s_addc_u32 s43, s15, 0
	s_barrier
	s_setprio 1
	s_waitcnt lgkmcnt(7)
	v_mfma_f32_16x16x32_bf16 v[62:65], v[146:149], v[186:189], v[62:65]
	v_mfma_f32_16x16x32_bf16 v[58:61], v[154:157], v[186:189], v[58:61]
	s_waitcnt lgkmcnt(5)
	v_mfma_f32_16x16x32_bf16 v[54:57], v[146:149], v[178:181], v[54:57]
	v_mfma_f32_16x16x32_bf16 v[50:53], v[154:157], v[178:181], v[50:53]
	s_waitcnt lgkmcnt(3)
	v_mfma_f32_16x16x32_bf16 v[46:49], v[146:149], v[170:173], v[46:49]
	v_mfma_f32_16x16x32_bf16 v[42:45], v[154:157], v[170:173], v[42:45]
	s_waitcnt lgkmcnt(1)
	v_mfma_f32_16x16x32_bf16 v[38:41], v[146:149], v[162:165], v[38:41]
	v_mfma_f32_16x16x32_bf16 v[34:37], v[154:157], v[162:165], v[34:37]
	v_mfma_f32_16x16x32_bf16 v[62:65], v[150:153], v[190:193], v[62:65]
	v_mfma_f32_16x16x32_bf16 v[58:61], v[158:161], v[190:193], v[58:61]
	v_mfma_f32_16x16x32_bf16 v[54:57], v[150:153], v[182:185], v[54:57]
	v_mfma_f32_16x16x32_bf16 v[50:53], v[158:161], v[182:185], v[50:53]
	v_mfma_f32_16x16x32_bf16 v[46:49], v[150:153], v[174:177], v[46:49]
	v_mfma_f32_16x16x32_bf16 v[42:45], v[158:161], v[174:177], v[42:45]
	s_waitcnt lgkmcnt(0)
	v_mfma_f32_16x16x32_bf16 v[38:41], v[150:153], v[166:169], v[38:41]
	v_mfma_f32_16x16x32_bf16 v[34:37], v[158:161], v[166:169], v[34:37]
	s_setprio 0
	s_setprio 1
	v_mfma_f32_16x16x32_bf16 v[30:33], v[130:133], v[186:189], v[30:33]
	v_mfma_f32_16x16x32_bf16 v[26:29], v[138:141], v[186:189], v[26:29]
	v_mfma_f32_16x16x32_bf16 v[22:25], v[130:133], v[178:181], v[22:25]
	v_mfma_f32_16x16x32_bf16 v[18:21], v[138:141], v[178:181], v[18:21]
	v_mfma_f32_16x16x32_bf16 v[14:17], v[130:133], v[170:173], v[14:17]
	v_mfma_f32_16x16x32_bf16 v[10:13], v[138:141], v[170:173], v[10:13]
	v_mfma_f32_16x16x32_bf16 v[6:9], v[130:133], v[162:165], v[6:9]
	v_mfma_f32_16x16x32_bf16 v[2:5], v[138:141], v[162:165], v[2:5]
	v_mfma_f32_16x16x32_bf16 v[30:33], v[134:137], v[190:193], v[30:33]
	v_mfma_f32_16x16x32_bf16 v[26:29], v[142:145], v[190:193], v[26:29]
	v_mfma_f32_16x16x32_bf16 v[22:25], v[134:137], v[182:185], v[22:25]
	v_mfma_f32_16x16x32_bf16 v[18:21], v[142:145], v[182:185], v[18:21]
	v_mfma_f32_16x16x32_bf16 v[14:17], v[134:137], v[174:177], v[14:17]
	v_mfma_f32_16x16x32_bf16 v[10:13], v[142:145], v[174:177], v[10:13]
	v_mfma_f32_16x16x32_bf16 v[6:9], v[134:137], v[166:169], v[6:9]
	v_mfma_f32_16x16x32_bf16 v[2:5], v[142:145], v[166:169], v[2:5]
	s_setprio 0
	s_barrier
	v_add_u32_e32 v142, 0x18000, v214
	v_add_u32_e32 v158, 0x1c000, v214
	ds_read_b128 v[130:133], v142
	ds_read_b128 v[134:137], v142 offset:1024
	ds_read_b128 v[138:141], v142 offset:2048
	ds_read_b128 v[142:145], v142 offset:3072
	ds_read_b128 v[146:149], v158
	ds_read_b128 v[150:153], v158 offset:1024
	ds_read_b128 v[154:157], v158 offset:2048
	ds_read_b128 v[158:161], v158 offset:3072
	ds_read_b128 v[162:165], v215 offset:32768
	ds_read_b128 v[166:169], v215 offset:33792
	ds_read_b128 v[170:173], v215 offset:34816
	ds_read_b128 v[174:177], v215 offset:35840
	ds_read_b128 v[178:181], v215 offset:36864
	ds_read_b128 v[182:185], v215 offset:37888
	ds_read_b128 v[186:189], v215 offset:38912
	ds_read_b128 v[190:193], v215 offset:39936
	s_add_u32 s38, s38, 0x4000
	s_addc_u32 s39, s39, 0
	s_mov_b32 m0, s59
	s_nop 0
	global_load_lds_dwordx4 v195, s[38:39]
	s_add_u32 m0, s59, 0x2000
	s_nop 0
	global_load_lds_dwordx4 v208, s[38:39]
	s_waitcnt vmcnt(8)
	s_waitcnt lgkmcnt(0)
	s_barrier
	s_setprio 1
	s_waitcnt lgkmcnt(7)
	v_mfma_f32_16x16x32_bf16 v[126:129], v[130:133], v[162:165], v[126:129]
	v_mfma_f32_16x16x32_bf16 v[122:125], v[138:141], v[162:165], v[122:125]
	s_waitcnt lgkmcnt(5)
	v_mfma_f32_16x16x32_bf16 v[118:121], v[130:133], v[170:173], v[118:121]
	v_mfma_f32_16x16x32_bf16 v[114:117], v[138:141], v[170:173], v[114:117]
	s_waitcnt lgkmcnt(3)
	v_mfma_f32_16x16x32_bf16 v[110:113], v[130:133], v[178:181], v[110:113]
	v_mfma_f32_16x16x32_bf16 v[106:109], v[138:141], v[178:181], v[106:109]
	s_waitcnt lgkmcnt(1)
	v_mfma_f32_16x16x32_bf16 v[102:105], v[130:133], v[186:189], v[102:105]
	v_mfma_f32_16x16x32_bf16 v[98:101], v[138:141], v[186:189], v[98:101]
	v_mfma_f32_16x16x32_bf16 v[126:129], v[134:137], v[166:169], v[126:129]
	v_mfma_f32_16x16x32_bf16 v[122:125], v[142:145], v[166:169], v[122:125]
	v_mfma_f32_16x16x32_bf16 v[118:121], v[134:137], v[174:177], v[118:121]
	v_mfma_f32_16x16x32_bf16 v[114:117], v[142:145], v[174:177], v[114:117]
	v_mfma_f32_16x16x32_bf16 v[110:113], v[134:137], v[182:185], v[110:113]
	v_mfma_f32_16x16x32_bf16 v[106:109], v[142:145], v[182:185], v[106:109]
	s_waitcnt lgkmcnt(0)
	v_mfma_f32_16x16x32_bf16 v[102:105], v[134:137], v[190:193], v[102:105]
	v_mfma_f32_16x16x32_bf16 v[98:101], v[142:145], v[190:193], v[98:101]
	s_setprio 0
	s_setprio 1
	v_mfma_f32_16x16x32_bf16 v[94:97], v[146:149], v[162:165], v[94:97]
	v_mfma_f32_16x16x32_bf16 v[90:93], v[154:157], v[162:165], v[90:93]
	v_mfma_f32_16x16x32_bf16 v[86:89], v[146:149], v[170:173], v[86:89]
	v_mfma_f32_16x16x32_bf16 v[82:85], v[154:157], v[170:173], v[82:85]
	v_mfma_f32_16x16x32_bf16 v[78:81], v[146:149], v[178:181], v[78:81]
	v_mfma_f32_16x16x32_bf16 v[74:77], v[154:157], v[178:181], v[74:77]
	v_mfma_f32_16x16x32_bf16 v[70:73], v[146:149], v[186:189], v[70:73]
	v_mfma_f32_16x16x32_bf16 v[66:69], v[154:157], v[186:189], v[66:69]
	v_mfma_f32_16x16x32_bf16 v[94:97], v[150:153], v[166:169], v[94:97]
	v_mfma_f32_16x16x32_bf16 v[90:93], v[158:161], v[166:169], v[90:93]
	v_mfma_f32_16x16x32_bf16 v[86:89], v[150:153], v[174:177], v[86:89]
	v_mfma_f32_16x16x32_bf16 v[82:85], v[158:161], v[174:177], v[82:85]
	v_mfma_f32_16x16x32_bf16 v[78:81], v[150:153], v[182:185], v[78:81]
	v_mfma_f32_16x16x32_bf16 v[74:77], v[158:161], v[182:185], v[74:77]
	v_mfma_f32_16x16x32_bf16 v[70:73], v[150:153], v[190:193], v[70:73]
	v_mfma_f32_16x16x32_bf16 v[66:69], v[158:161], v[190:193], v[66:69]
	s_setprio 0
	s_barrier
	ds_read_b128 v[162:165], v215 offset:49152
	ds_read_b128 v[166:169], v215 offset:50176
	ds_read_b128 v[170:173], v215 offset:51200
	ds_read_b128 v[174:177], v215 offset:52224
	ds_read_b128 v[178:181], v215 offset:53248
	ds_read_b128 v[182:185], v215 offset:54272
	ds_read_b128 v[186:189], v215 offset:55296
	ds_read_b128 v[190:193], v215 offset:56320
	s_mov_b32 m0, s63
	s_nop 0
	global_load_lds_dwordx4 v195, s[42:43]
	s_add_u32 m0, s63, 0x2000
	s_nop 0
	global_load_lds_dwordx4 v208, s[42:43]
	s_add_u32 s14, s14, 0xc000
	s_addc_u32 s15, s15, 0
	s_mov_b32 m0, s65
	s_nop 0
	global_load_lds_dwordx4 v195, s[14:15]
	s_add_u32 m0, s65, 0x2000
	s_nop 0
	global_load_lds_dwordx4 v208, s[14:15]
	s_nop 0
	s_mov_b32 m0, s64
	s_nop 0
	global_load_lds_dwordx4 v195, s[40:41]
	s_add_u32 m0, s64, 0x2000
	s_nop 0
	global_load_lds_dwordx4 v208, s[40:41]
	s_waitcnt vmcnt(8)
	s_waitcnt lgkmcnt(0)
	s_barrier
	s_setprio 1
	s_waitcnt lgkmcnt(7)
	v_mfma_f32_16x16x32_bf16 v[62:65], v[130:133], v[162:165], v[62:65]
	v_mfma_f32_16x16x32_bf16 v[58:61], v[138:141], v[162:165], v[58:61]
	s_waitcnt lgkmcnt(5)
	v_mfma_f32_16x16x32_bf16 v[54:57], v[130:133], v[170:173], v[54:57]
	v_mfma_f32_16x16x32_bf16 v[50:53], v[138:141], v[170:173], v[50:53]
	s_waitcnt lgkmcnt(3)
	v_mfma_f32_16x16x32_bf16 v[46:49], v[130:133], v[178:181], v[46:49]
	v_mfma_f32_16x16x32_bf16 v[42:45], v[138:141], v[178:181], v[42:45]
	s_waitcnt lgkmcnt(1)
	v_mfma_f32_16x16x32_bf16 v[38:41], v[130:133], v[186:189], v[38:41]
	v_mfma_f32_16x16x32_bf16 v[34:37], v[138:141], v[186:189], v[34:37]
	v_mfma_f32_16x16x32_bf16 v[62:65], v[134:137], v[166:169], v[62:65]
	v_mfma_f32_16x16x32_bf16 v[58:61], v[142:145], v[166:169], v[58:61]
	v_mfma_f32_16x16x32_bf16 v[54:57], v[134:137], v[174:177], v[54:57]
	v_mfma_f32_16x16x32_bf16 v[50:53], v[142:145], v[174:177], v[50:53]
	v_mfma_f32_16x16x32_bf16 v[46:49], v[134:137], v[182:185], v[46:49]
	v_mfma_f32_16x16x32_bf16 v[42:45], v[142:145], v[182:185], v[42:45]
	s_waitcnt lgkmcnt(0)
	v_mfma_f32_16x16x32_bf16 v[38:41], v[134:137], v[190:193], v[38:41]
	v_mfma_f32_16x16x32_bf16 v[34:37], v[142:145], v[190:193], v[34:37]
	s_setprio 0
	s_setprio 1
	v_mfma_f32_16x16x32_bf16 v[30:33], v[146:149], v[162:165], v[30:33]
	v_mfma_f32_16x16x32_bf16 v[26:29], v[154:157], v[162:165], v[26:29]
	v_mfma_f32_16x16x32_bf16 v[22:25], v[146:149], v[170:173], v[22:25]
	v_mfma_f32_16x16x32_bf16 v[18:21], v[154:157], v[170:173], v[18:21]
	v_mfma_f32_16x16x32_bf16 v[14:17], v[146:149], v[178:181], v[14:17]
	v_mfma_f32_16x16x32_bf16 v[10:13], v[154:157], v[178:181], v[10:13]
	v_mfma_f32_16x16x32_bf16 v[6:9], v[146:149], v[186:189], v[6:9]
	v_mfma_f32_16x16x32_bf16 v[2:5], v[154:157], v[186:189], v[2:5]
	v_mfma_f32_16x16x32_bf16 v[30:33], v[150:153], v[166:169], v[30:33]
	v_mfma_f32_16x16x32_bf16 v[26:29], v[158:161], v[166:169], v[26:29]
	v_mfma_f32_16x16x32_bf16 v[22:25], v[150:153], v[174:177], v[22:25]
	v_mfma_f32_16x16x32_bf16 v[18:21], v[158:161], v[174:177], v[18:21]
	v_mfma_f32_16x16x32_bf16 v[14:17], v[150:153], v[182:185], v[14:17]
	v_mfma_f32_16x16x32_bf16 v[10:13], v[158:161], v[182:185], v[10:13]
	v_mfma_f32_16x16x32_bf16 v[6:9], v[150:153], v[190:193], v[6:9]
	v_mfma_f32_16x16x32_bf16 v[2:5], v[158:161], v[190:193], v[2:5]
	s_setprio 0
	s_barrier
	s_cmp_gt_u32 s46, 41
	s_cbranch_scc1 .LBB0_2233
	v_mov_b32_e32 v130, v196
	s_mov_b32 s46, s22
	s_branch .LBB0_2208

.LBB0_2235:
	s_lshl_b32 s12, s74, 8
	v_mov_b32_e32 v163, v210
	v_mov_b32_e32 v130, v209
	s_add_i32 s12, s12, s61
	v_add_u32_e32 v162, s12, v130
	s_lshl_b32 s12, s48, 8
	s_or_b32 s12, s12, s62
	v_lshl_add_u32 v134, v163, 3, s12
	v_bfe_u32 v220, v134, 5, 1
	v_lshrrev_b32_e32 v131, 3, v162
	v_lshlrev_b32_e32 v130, 1, v134
	v_and_or_b32 v131, v131, 14, v220
	v_and_b32_e32 v219, 48, v130
	v_ashrrev_i32_e32 v218, 6, v134
	v_ashrrev_i32_e32 v130, 4, v162
	v_lshlrev_b32_e32 v132, 6, v162
	v_lshlrev_b32_e32 v222, 10, v131
	v_lshlrev_b32_e32 v131, 2, v162
	v_add_u32_e32 v134, 0x80, v134
	v_and_b32_e32 v135, -16, v130
	v_lshlrev_b32_e32 v130, 7, v162
	v_and_b32_e32 v132, 0x3c0, v132
	v_and_b32_e32 v131, 32, v131
	v_ashrrev_i32_e32 v221, 6, v134
	v_and_b32_e32 v130, 0x4000, v130
	v_bitop3_b32 v131, v219, v131, v132 bitop3:0x36
	v_add_u32_e32 v132, v218, v135
	v_or3_b32 v196, v130, v131, v222
	v_ashrrev_i32_e32 v133, 31, v132
	v_lshl_add_u64 v[130:131], s[34:35], 0, v[196:197]
	v_lshlrev_b64 v[190:191], 15, v[132:133]
	v_lshl_add_u64 v[132:133], v[130:131], 0, v[190:191]
	v_add_u32_e32 v178, 16, v162
	v_lshl_add_u64 v[166:167], v[132:133], 0, 0
	global_load_dwordx4 v[158:161], v[132:133], off
	s_mov_b32 s98, 0x11000
	s_mov_b32 s99, 0x0
	v_lshl_add_u64 v[172:173], v[166:167], 0, s[98:99]
	global_load_dwordx4 v[154:157], v[172:173], off offset:-4096
	v_add_u32_e32 v170, 32, v162
	s_mov_b32 s98, 0x1000
	s_mov_b32 s99, 0x0
	v_lshl_add_u64 v[174:175], v[166:167], 0, s[98:99]
	global_load_dwordx4 v[150:153], v[174:175], off offset:-2048
	global_load_dwordx4 v[146:149], v[172:173], off offset:-2048
	v_ashrrev_i32_e32 v130, 4, v170
	v_and_b32_e32 v134, -16, v130
	v_add_u32_e32 v134, v221, v134
	v_ashrrev_i32_e32 v135, 31, v134
	v_lshlrev_b64 v[176:177], 15, v[134:135]
	v_add_u32_e32 v164, 48, v162
	global_load_dwordx4 v[142:145], v[174:175], off
	global_load_dwordx4 v[138:141], v[172:173], off
	global_load_dwordx4 v[134:137], v[174:175], off offset:2048
	s_nop 0
	global_load_dwordx4 v[130:133], v[172:173], off offset:2048
	s_cmpk_gt_i32 s74, 0x7f
	s_cselect_b64 s[38:39], -1, 0
	s_nor_b64 s[42:43], s[36:37], s[38:39]
	s_waitcnt vmcnt(7)
	v_lshlrev_b32_e32 v190, 16, v158
	v_and_b32_e32 v191, 0xffff0000, v158
	v_lshlrev_b32_e32 v158, 16, v159
	v_and_b32_e32 v159, 0xffff0000, v159
	v_pk_fma_f32 v[192:193], v[128:129], 0.5, v[158:159] op_sel_hi:[1,0,1]
	v_lshlrev_b32_e32 v158, 16, v160
	v_and_b32_e32 v159, 0xffff0000, v160
	v_pk_fma_f32 v[200:201], v[122:123], 0.5, v[158:159] op_sel_hi:[1,0,1]
	v_lshlrev_b32_e32 v158, 16, v161
	v_and_b32_e32 v159, 0xffff0000, v161
	v_pk_fma_f32 v[190:191], v[126:127], 0.5, v[190:191] op_sel_hi:[1,0,1]
	v_pk_fma_f32 v[202:203], v[124:125], 0.5, v[158:159] op_sel_hi:[1,0,1]
	v_cvt_pk_bf16_f32 v158, v190, v191
	v_cvt_pk_bf16_f32 v159, v192, v193
	v_cvt_pk_bf16_f32 v160, v200, v201
	v_cvt_pk_bf16_f32 v161, v202, v203
	s_mov_b64 s[12:13], -1
	s_and_b64 vcc, exec, s[42:43]
	s_cbranch_vccz .LBB0_2237
	global_store_dwordx4 v[174:175], v[158:161], off offset:-4096
	s_mov_b64 s[12:13], 0

.LBB0_2239:
	s_nop 0
	s_nop 0
	s_waitcnt vmcnt(6)
	v_lshlrev_b32_e32 v158, 16, v154
	v_and_b32_e32 v159, 0xffff0000, v154
	v_lshlrev_b32_e32 v154, 16, v155
	v_and_b32_e32 v155, 0xffff0000, v155
	v_pk_fma_f32 v[188:189], v[96:97], 0.5, v[154:155] op_sel_hi:[1,0,1]
	v_lshlrev_b32_e32 v154, 16, v156
	v_and_b32_e32 v155, 0xffff0000, v156
	v_pk_fma_f32 v[204:205], v[90:91], 0.5, v[154:155] op_sel_hi:[1,0,1]
	v_lshlrev_b32_e32 v154, 16, v157
	v_and_b32_e32 v155, 0xffff0000, v157
	v_pk_fma_f32 v[158:159], v[94:95], 0.5, v[158:159] op_sel_hi:[1,0,1]
	v_pk_fma_f32 v[206:207], v[92:93], 0.5, v[154:155] op_sel_hi:[1,0,1]
	v_cndmask_b32_e64 v165, 0, 1, s[42:43]
	v_cvt_pk_bf16_f32 v154, v158, v159
	v_cvt_pk_bf16_f32 v155, v188, v189
	v_cvt_pk_bf16_f32 v156, v204, v205
	v_cvt_pk_bf16_f32 v157, v206, v207
	v_cmp_ne_u32_e64 s[12:13], 1, v165
	s_andn2_b64 vcc, exec, s[42:43]
	s_mov_b64 s[14:15], -1
	s_cbranch_vccnz .LBB0_2241
	s_mov_b64 s[14:15], 0
	global_store_dwordx4 v[172:173], v[154:157], off offset:-4096

.LBB0_2249:
	s_or_b64 exec, exec, s[44:45]
	s_waitcnt lgkmcnt(0)
	s_waitcnt vmcnt(5)
	v_lshlrev_b32_e32 v154, 16, v150
	v_and_b32_e32 v155, 0xffff0000, v150
	v_lshlrev_b32_e32 v150, 16, v151
	v_and_b32_e32 v151, 0xffff0000, v151
	v_pk_fma_f32 v[156:157], v[120:121], 0.5, v[150:151] op_sel_hi:[1,0,1]
	v_lshlrev_b32_e32 v150, 16, v152
	v_and_b32_e32 v151, 0xffff0000, v152
	v_pk_fma_f32 v[158:159], v[114:115], 0.5, v[150:151] op_sel_hi:[1,0,1]
	v_lshlrev_b32_e32 v150, 16, v153
	v_and_b32_e32 v151, 0xffff0000, v153
	v_pk_fma_f32 v[154:155], v[118:119], 0.5, v[154:155] op_sel_hi:[1,0,1]
	v_pk_fma_f32 v[160:161], v[116:117], 0.5, v[150:151] op_sel_hi:[1,0,1]
	v_cvt_pk_bf16_f32 v150, v154, v155
	v_cvt_pk_bf16_f32 v151, v156, v157
	v_cvt_pk_bf16_f32 v152, v158, v159
	v_cvt_pk_bf16_f32 v153, v160, v161
	s_nor_b64 s[42:43], s[46:47], s[38:39]
	s_and_saveexec_b64 s[44:45], s[42:43]
	s_xor_b64 s[42:43], exec, s[44:45]
	s_cbranch_execz .LBB0_2251
	global_store_dwordx4 v[174:175], v[150:153], off offset:-2048
.LBB0_2251:
	s_andn2_saveexec_b64 s[42:43], s[42:43]
	s_cbranch_execz .LBB0_2253
	global_store_dwordx4 v[174:175], v[150:153], off offset:-2048 sc1
	s_nop 1
.LBB0_2253:
	s_or_b64 exec, exec, s[42:43]
	s_nop 0
	s_waitcnt vmcnt(4)
	v_lshlrev_b32_e32 v152, 16, v146
	v_and_b32_e32 v153, 0xffff0000, v146
	v_lshlrev_b32_e32 v146, 16, v147
	v_and_b32_e32 v147, 0xffff0000, v147
	v_pk_fma_f32 v[182:183], v[88:89], 0.5, v[146:147] op_sel_hi:[1,0,1]
	v_lshlrev_b32_e32 v146, 16, v148
	v_and_b32_e32 v147, 0xffff0000, v148
	v_pk_fma_f32 v[184:185], v[82:83], 0.5, v[146:147] op_sel_hi:[1,0,1]
	v_lshlrev_b32_e32 v146, 16, v149
	v_and_b32_e32 v147, 0xffff0000, v149
	v_pk_fma_f32 v[152:153], v[86:87], 0.5, v[152:153] op_sel_hi:[1,0,1]
	v_pk_fma_f32 v[186:187], v[84:85], 0.5, v[146:147] op_sel_hi:[1,0,1]
	v_cvt_pk_bf16_f32 v146, v152, v153
	v_cvt_pk_bf16_f32 v147, v182, v183
	v_cvt_pk_bf16_f32 v148, v184, v185
	v_cvt_pk_bf16_f32 v149, v186, v187
	s_and_b64 vcc, exec, s[12:13]
	s_mov_b64 s[42:43], -1
	s_cbranch_vccnz .LBB0_2255
	s_mov_b64 s[42:43], 0
	global_store_dwordx4 v[172:173], v[146:149], off offset:-2048
.LBB0_2255:
	s_andn2_b64 vcc, exec, s[42:43]
	s_cbranch_vccnz .LBB0_2257
	global_store_dwordx4 v[172:173], v[146:149], off offset:-2048 sc1
	s_nop 1

.LBB0_2263:
	s_or_b64 exec, exec, s[42:43]
	s_waitcnt lgkmcnt(0)
	s_waitcnt vmcnt(3)
	v_lshlrev_b32_e32 v146, 16, v142
	v_and_b32_e32 v147, 0xffff0000, v142
	v_lshlrev_b32_e32 v142, 16, v143
	v_and_b32_e32 v143, 0xffff0000, v143
	v_pk_fma_f32 v[148:149], v[112:113], 0.5, v[142:143] op_sel_hi:[1,0,1]
	v_lshlrev_b32_e32 v142, 16, v144
	v_and_b32_e32 v143, 0xffff0000, v144
	v_pk_fma_f32 v[150:151], v[106:107], 0.5, v[142:143] op_sel_hi:[1,0,1]
	v_lshlrev_b32_e32 v142, 16, v145
	v_and_b32_e32 v143, 0xffff0000, v145
	v_pk_fma_f32 v[146:147], v[110:111], 0.5, v[146:147] op_sel_hi:[1,0,1]
	v_pk_fma_f32 v[152:153], v[108:109], 0.5, v[142:143] op_sel_hi:[1,0,1]
	v_cvt_pk_bf16_f32 v142, v146, v147
	v_cvt_pk_bf16_f32 v143, v148, v149
	v_cvt_pk_bf16_f32 v144, v150, v151
	v_cvt_pk_bf16_f32 v145, v152, v153
	s_nor_b64 s[42:43], s[44:45], s[38:39]
	s_and_saveexec_b64 s[44:45], s[42:43]
	s_xor_b64 s[42:43], exec, s[44:45]
	s_cbranch_execz .LBB0_2265
	global_store_dwordx4 v[174:175], v[142:145], off
.LBB0_2265:
	s_andn2_saveexec_b64 s[42:43], s[42:43]
	s_cbranch_execz .LBB0_2267
	global_store_dwordx4 v[174:175], v[142:145], off sc1
	s_nop 1
.LBB0_2267:
	s_or_b64 exec, exec, s[42:43]
	s_waitcnt vmcnt(2)
	v_lshlrev_b32_e32 v144, 16, v138
	v_and_b32_e32 v145, 0xffff0000, v138
	v_lshlrev_b32_e32 v138, 16, v139
	v_and_b32_e32 v139, 0xffff0000, v139
	v_pk_fma_f32 v[154:155], v[80:81], 0.5, v[138:139] op_sel_hi:[1,0,1]
	v_lshlrev_b32_e32 v138, 16, v140
	v_and_b32_e32 v139, 0xffff0000, v140
	v_pk_fma_f32 v[156:157], v[74:75], 0.5, v[138:139] op_sel_hi:[1,0,1]
	v_lshlrev_b32_e32 v138, 16, v141
	v_and_b32_e32 v139, 0xffff0000, v141
	v_pk_fma_f32 v[144:145], v[78:79], 0.5, v[144:145] op_sel_hi:[1,0,1]
	v_pk_fma_f32 v[158:159], v[76:77], 0.5, v[138:139] op_sel_hi:[1,0,1]
	v_cvt_pk_bf16_f32 v138, v144, v145
	v_cvt_pk_bf16_f32 v139, v154, v155
	v_cvt_pk_bf16_f32 v140, v156, v157
	v_cvt_pk_bf16_f32 v141, v158, v159
	s_and_b64 vcc, exec, s[12:13]
	s_mov_b64 s[42:43], -1
	s_cbranch_vccnz .LBB0_2269
	s_mov_b64 s[42:43], 0
	global_store_dwordx4 v[172:173], v[138:141], off
.LBB0_2269:
	s_andn2_b64 vcc, exec, s[42:43]
	s_cbranch_vccnz .LBB0_2271
	global_store_dwordx4 v[172:173], v[138:141], off sc1
	s_nop 1

.LBB0_2277:
	s_or_b64 exec, exec, s[42:43]
	s_waitcnt lgkmcnt(0)
	s_waitcnt vmcnt(1)
	v_lshlrev_b32_e32 v138, 16, v134
	v_and_b32_e32 v139, 0xffff0000, v134
	v_lshlrev_b32_e32 v134, 16, v135
	v_and_b32_e32 v135, 0xffff0000, v135
	v_pk_fma_f32 v[140:141], v[104:105], 0.5, v[134:135] op_sel_hi:[1,0,1]
	v_lshlrev_b32_e32 v134, 16, v136
	v_and_b32_e32 v135, 0xffff0000, v136
	v_pk_fma_f32 v[142:143], v[98:99], 0.5, v[134:135] op_sel_hi:[1,0,1]
	v_lshlrev_b32_e32 v134, 16, v137
	v_and_b32_e32 v135, 0xffff0000, v137
	v_pk_fma_f32 v[138:139], v[102:103], 0.5, v[138:139] op_sel_hi:[1,0,1]
	v_pk_fma_f32 v[144:145], v[100:101], 0.5, v[134:135] op_sel_hi:[1,0,1]
	v_cvt_pk_bf16_f32 v134, v138, v139
	v_cvt_pk_bf16_f32 v135, v140, v141
	v_cvt_pk_bf16_f32 v136, v142, v143
	v_cvt_pk_bf16_f32 v137, v144, v145
	s_nor_b64 s[42:43], s[44:45], s[38:39]
	s_and_saveexec_b64 s[44:45], s[42:43]
	s_xor_b64 s[42:43], exec, s[44:45]
	s_cbranch_execz .LBB0_2279
	global_store_dwordx4 v[174:175], v[134:137], off offset:2048
.LBB0_2279:
	s_andn2_saveexec_b64 s[42:43], s[42:43]
	s_cbranch_execz .LBB0_2281
	global_store_dwordx4 v[174:175], v[134:137], off offset:2048 sc1
	s_nop 1
.LBB0_2281:
	s_or_b64 exec, exec, s[42:43]
	s_waitcnt vmcnt(0)
	v_lshlrev_b32_e32 v136, 16, v130
	v_and_b32_e32 v137, 0xffff0000, v130
	v_lshlrev_b32_e32 v130, 16, v131
	v_and_b32_e32 v131, 0xffff0000, v131
	v_pk_fma_f32 v[146:147], v[72:73], 0.5, v[130:131] op_sel_hi:[1,0,1]
	v_lshlrev_b32_e32 v130, 16, v132
	v_and_b32_e32 v131, 0xffff0000, v132
	v_pk_fma_f32 v[148:149], v[66:67], 0.5, v[130:131] op_sel_hi:[1,0,1]
	v_lshlrev_b32_e32 v130, 16, v133
	v_and_b32_e32 v131, 0xffff0000, v133
	v_pk_fma_f32 v[136:137], v[70:71], 0.5, v[136:137] op_sel_hi:[1,0,1]
	v_pk_fma_f32 v[150:151], v[68:69], 0.5, v[130:131] op_sel_hi:[1,0,1]
	v_cvt_pk_bf16_f32 v130, v136, v137
	v_cvt_pk_bf16_f32 v131, v146, v147
	v_cvt_pk_bf16_f32 v132, v148, v149
	v_cvt_pk_bf16_f32 v133, v150, v151
	s_and_b64 vcc, exec, s[12:13]
	s_mov_b64 s[42:43], -1
	s_cbranch_vccnz .LBB0_2283
	s_mov_b64 s[42:43], 0
	global_store_dwordx4 v[172:173], v[130:133], off offset:2048
.LBB0_2283:
	s_andn2_b64 vcc, exec, s[42:43]
	s_cbranch_vccnz .LBB0_2285
	global_store_dwordx4 v[172:173], v[130:133], off offset:2048 sc1
	s_nop 1

.LBB0_2290:
	s_or_b64 exec, exec, s[42:43]
	v_add_u32_e32 v184, 0x80, v162
	s_waitcnt lgkmcnt(0)
	v_lshlrev_b32_e32 v131, 6, v184
	v_lshlrev_b32_e32 v132, 2, v184
	v_lshlrev_b32_e32 v130, 7, v184
	v_and_b32_e32 v131, 0x3c0, v131
	v_and_b32_e32 v132, 32, v132
	v_and_b32_e32 v130, 0x4000, v130
	v_bitop3_b32 v131, v131, v132, v219 bitop3:0x36
	v_or3_b32 v196, v130, v131, v222
	v_add_u32_e32 v176, 0x90, v162
	s_mov_b32 s98, 0x5000
	s_mov_b32 s99, 0x0
	v_lshl_add_u64 v[172:173], v[166:167], 0, s[98:99]
	global_load_dwordx4 v[158:161], v[172:173], off offset:-4096
	s_mov_b32 s98, 0x15000
	s_mov_b32 s99, 0x0
	v_lshl_add_u64 v[174:175], v[166:167], 0, s[98:99]
	global_load_dwordx4 v[154:157], v[174:175], off offset:-4096
	v_add_u32_e32 v168, 0xa0, v162
	global_load_dwordx4 v[150:153], v[172:173], off offset:-2048
	global_load_dwordx4 v[146:149], v[174:175], off offset:-2048
	v_add_u32_e32 v162, 0xb0, v162
	global_load_dwordx4 v[142:145], v[172:173], off
	global_load_dwordx4 v[138:141], v[174:175], off
	global_load_dwordx4 v[134:137], v[172:173], off offset:2048
	s_nop 0
	global_load_dwordx4 v[130:133], v[174:175], off offset:2048
	s_and_b64 vcc, exec, s[12:13]
	s_mov_b64 s[42:43], -1
	s_waitcnt vmcnt(7)
	v_lshlrev_b32_e32 v190, 16, v158
	v_and_b32_e32 v191, 0xffff0000, v158
	v_lshlrev_b32_e32 v158, 16, v159
	v_and_b32_e32 v159, 0xffff0000, v159
	v_pk_fma_f32 v[192:193], v[64:65], 0.5, v[158:159] op_sel_hi:[1,0,1]
	v_lshlrev_b32_e32 v158, 16, v160
	v_and_b32_e32 v159, 0xffff0000, v160
	v_pk_fma_f32 v[200:201], v[58:59], 0.5, v[158:159] op_sel_hi:[1,0,1]
	v_lshlrev_b32_e32 v158, 16, v161
	v_and_b32_e32 v159, 0xffff0000, v161
	v_pk_fma_f32 v[190:191], v[62:63], 0.5, v[190:191] op_sel_hi:[1,0,1]
	v_pk_fma_f32 v[202:203], v[60:61], 0.5, v[158:159] op_sel_hi:[1,0,1]
	v_cvt_pk_bf16_f32 v158, v190, v191
	v_cvt_pk_bf16_f32 v159, v192, v193
	v_cvt_pk_bf16_f32 v160, v200, v201
	v_cvt_pk_bf16_f32 v161, v202, v203
	s_cbranch_vccnz .LBB0_2292
	s_mov_b64 s[42:43], 0
	global_store_dwordx4 v[172:173], v[158:161], off offset:-4096
.LBB0_2292:
	s_andn2_b64 vcc, exec, s[42:43]
	s_cbranch_vccnz .LBB0_2294
	global_store_dwordx4 v[172:173], v[158:161], off offset:-4096 sc1
	s_nop 1
.LBB0_2294:
	s_waitcnt vmcnt(6)
	v_lshlrev_b32_e32 v160, 16, v154
	v_and_b32_e32 v161, 0xffff0000, v154
	v_lshlrev_b32_e32 v154, 16, v155
	v_and_b32_e32 v155, 0xffff0000, v155
	v_pk_fma_f32 v[188:189], v[32:33], 0.5, v[154:155] op_sel_hi:[1,0,1]
	v_lshlrev_b32_e32 v154, 16, v156
	v_and_b32_e32 v155, 0xffff0000, v156
	v_pk_fma_f32 v[204:205], v[26:27], 0.5, v[154:155] op_sel_hi:[1,0,1]
	v_lshlrev_b32_e32 v154, 16, v157
	v_and_b32_e32 v155, 0xffff0000, v157
	v_pk_fma_f32 v[160:161], v[30:31], 0.5, v[160:161] op_sel_hi:[1,0,1]
	v_pk_fma_f32 v[206:207], v[28:29], 0.5, v[154:155] op_sel_hi:[1,0,1]
	v_cvt_pk_bf16_f32 v154, v160, v161
	v_cvt_pk_bf16_f32 v155, v188, v189
	v_cvt_pk_bf16_f32 v156, v204, v205
	v_cvt_pk_bf16_f32 v157, v206, v207
	s_and_b64 vcc, exec, s[12:13]
	s_mov_b64 s[42:43], -1
	s_cbranch_vccnz .LBB0_2296
	s_mov_b64 s[42:43], 0
	global_store_dwordx4 v[174:175], v[154:157], off offset:-4096
.LBB0_2296:
	s_andn2_b64 vcc, exec, s[42:43]
	s_cbranch_vccnz .LBB0_2298
	global_store_dwordx4 v[174:175], v[154:157], off offset:-4096 sc1
	s_nop 1

.LBB0_2304:
	s_or_b64 exec, exec, s[42:43]
	s_waitcnt lgkmcnt(0)
	s_waitcnt vmcnt(5)
	v_lshlrev_b32_e32 v154, 16, v150
	v_and_b32_e32 v155, 0xffff0000, v150
	v_lshlrev_b32_e32 v150, 16, v151
	v_and_b32_e32 v151, 0xffff0000, v151
	v_pk_fma_f32 v[156:157], v[56:57], 0.5, v[150:151] op_sel_hi:[1,0,1]
	v_lshlrev_b32_e32 v150, 16, v152
	v_and_b32_e32 v151, 0xffff0000, v152
	v_pk_fma_f32 v[158:159], v[50:51], 0.5, v[150:151] op_sel_hi:[1,0,1]
	v_lshlrev_b32_e32 v150, 16, v153
	v_and_b32_e32 v151, 0xffff0000, v153
	v_pk_fma_f32 v[154:155], v[54:55], 0.5, v[154:155] op_sel_hi:[1,0,1]
	v_pk_fma_f32 v[160:161], v[52:53], 0.5, v[150:151] op_sel_hi:[1,0,1]
	v_cvt_pk_bf16_f32 v150, v154, v155
	v_cvt_pk_bf16_f32 v151, v156, v157
	v_cvt_pk_bf16_f32 v152, v158, v159
	v_cvt_pk_bf16_f32 v153, v160, v161
	s_nor_b64 s[42:43], s[44:45], s[38:39]
	s_and_saveexec_b64 s[44:45], s[42:43]
	s_xor_b64 s[42:43], exec, s[44:45]
	s_cbranch_execz .LBB0_2306
	global_store_dwordx4 v[172:173], v[150:153], off offset:-2048
.LBB0_2306:
	s_andn2_saveexec_b64 s[42:43], s[42:43]
	s_cbranch_execz .LBB0_2308
	global_store_dwordx4 v[172:173], v[150:153], off offset:-2048 sc1
	s_nop 1
.LBB0_2308:
	s_or_b64 exec, exec, s[42:43]
	s_nop 0
	s_waitcnt vmcnt(4)
	v_lshlrev_b32_e32 v152, 16, v146
	v_and_b32_e32 v153, 0xffff0000, v146
	v_lshlrev_b32_e32 v146, 16, v147
	v_and_b32_e32 v147, 0xffff0000, v147
	v_pk_fma_f32 v[180:181], v[24:25], 0.5, v[146:147] op_sel_hi:[1,0,1]
	v_lshlrev_b32_e32 v146, 16, v148
	v_and_b32_e32 v147, 0xffff0000, v148
	v_pk_fma_f32 v[182:183], v[18:19], 0.5, v[146:147] op_sel_hi:[1,0,1]
	v_lshlrev_b32_e32 v146, 16, v149
	v_and_b32_e32 v147, 0xffff0000, v149
	v_pk_fma_f32 v[152:153], v[22:23], 0.5, v[152:153] op_sel_hi:[1,0,1]
	v_pk_fma_f32 v[184:185], v[20:21], 0.5, v[146:147] op_sel_hi:[1,0,1]
	v_cvt_pk_bf16_f32 v146, v152, v153
	v_cvt_pk_bf16_f32 v147, v180, v181
	v_cvt_pk_bf16_f32 v148, v182, v183
	v_cvt_pk_bf16_f32 v149, v184, v185
	s_and_b64 vcc, exec, s[12:13]
	s_mov_b64 s[42:43], -1
	s_cbranch_vccnz .LBB0_2310
	s_mov_b64 s[42:43], 0
	global_store_dwordx4 v[174:175], v[146:149], off offset:-2048
.LBB0_2310:
	s_andn2_b64 vcc, exec, s[42:43]
	s_cbranch_vccnz .LBB0_2312
	global_store_dwordx4 v[174:175], v[146:149], off offset:-2048 sc1
	s_nop 1

.LBB0_2318:
	s_or_b64 exec, exec, s[42:43]
	s_waitcnt lgkmcnt(0)
	s_waitcnt vmcnt(3)
	v_lshlrev_b32_e32 v146, 16, v142
	v_and_b32_e32 v147, 0xffff0000, v142
	v_lshlrev_b32_e32 v142, 16, v143
	v_and_b32_e32 v143, 0xffff0000, v143
	v_pk_fma_f32 v[148:149], v[48:49], 0.5, v[142:143] op_sel_hi:[1,0,1]
	v_lshlrev_b32_e32 v142, 16, v144
	v_and_b32_e32 v143, 0xffff0000, v144
	v_pk_fma_f32 v[150:151], v[42:43], 0.5, v[142:143] op_sel_hi:[1,0,1]
	v_lshlrev_b32_e32 v142, 16, v145
	v_and_b32_e32 v143, 0xffff0000, v145
	v_pk_fma_f32 v[146:147], v[46:47], 0.5, v[146:147] op_sel_hi:[1,0,1]
	v_pk_fma_f32 v[152:153], v[44:45], 0.5, v[142:143] op_sel_hi:[1,0,1]
	v_cvt_pk_bf16_f32 v142, v146, v147
	v_cvt_pk_bf16_f32 v143, v148, v149
	v_cvt_pk_bf16_f32 v144, v150, v151
	v_cvt_pk_bf16_f32 v145, v152, v153
	s_nor_b64 s[42:43], s[44:45], s[38:39]
	s_and_saveexec_b64 s[44:45], s[42:43]
	s_xor_b64 s[42:43], exec, s[44:45]
	s_cbranch_execz .LBB0_2320
	global_store_dwordx4 v[172:173], v[142:145], off
.LBB0_2320:
	s_andn2_saveexec_b64 s[42:43], s[42:43]
	s_cbranch_execz .LBB0_2322
	global_store_dwordx4 v[172:173], v[142:145], off sc1
	s_nop 1
.LBB0_2322:
	s_or_b64 exec, exec, s[42:43]
	s_waitcnt vmcnt(2)
	v_lshlrev_b32_e32 v144, 16, v138
	v_and_b32_e32 v145, 0xffff0000, v138
	v_lshlrev_b32_e32 v138, 16, v139
	v_and_b32_e32 v139, 0xffff0000, v139
	v_pk_fma_f32 v[154:155], v[16:17], 0.5, v[138:139] op_sel_hi:[1,0,1]
	v_lshlrev_b32_e32 v138, 16, v140
	v_and_b32_e32 v139, 0xffff0000, v140
	v_pk_fma_f32 v[156:157], v[10:11], 0.5, v[138:139] op_sel_hi:[1,0,1]
	v_lshlrev_b32_e32 v138, 16, v141
	v_and_b32_e32 v139, 0xffff0000, v141
	v_pk_fma_f32 v[144:145], v[14:15], 0.5, v[144:145] op_sel_hi:[1,0,1]
	v_pk_fma_f32 v[158:159], v[12:13], 0.5, v[138:139] op_sel_hi:[1,0,1]
	v_cvt_pk_bf16_f32 v138, v144, v145
	v_cvt_pk_bf16_f32 v139, v154, v155
	v_cvt_pk_bf16_f32 v140, v156, v157
	v_cvt_pk_bf16_f32 v141, v158, v159
	s_and_b64 vcc, exec, s[12:13]
	s_mov_b64 s[42:43], -1
	s_cbranch_vccnz .LBB0_2324
	s_mov_b64 s[42:43], 0
	global_store_dwordx4 v[174:175], v[138:141], off
.LBB0_2324:
	s_andn2_b64 vcc, exec, s[42:43]
	s_cbranch_vccnz .LBB0_2326
	global_store_dwordx4 v[174:175], v[138:141], off sc1
	s_nop 1

.LBB0_2332:
	s_or_b64 exec, exec, s[42:43]
	s_waitcnt lgkmcnt(0)
	s_waitcnt vmcnt(1)
	v_lshlrev_b32_e32 v138, 16, v134
	v_and_b32_e32 v139, 0xffff0000, v134
	v_lshlrev_b32_e32 v134, 16, v135
	v_and_b32_e32 v135, 0xffff0000, v135
	v_pk_fma_f32 v[140:141], v[40:41], 0.5, v[134:135] op_sel_hi:[1,0,1]
	v_lshlrev_b32_e32 v134, 16, v136
	v_and_b32_e32 v135, 0xffff0000, v136
	v_pk_fma_f32 v[142:143], v[34:35], 0.5, v[134:135] op_sel_hi:[1,0,1]
	v_lshlrev_b32_e32 v134, 16, v137
	v_and_b32_e32 v135, 0xffff0000, v137
	v_pk_fma_f32 v[138:139], v[38:39], 0.5, v[138:139] op_sel_hi:[1,0,1]
	v_pk_fma_f32 v[144:145], v[36:37], 0.5, v[134:135] op_sel_hi:[1,0,1]
	v_cvt_pk_bf16_f32 v134, v138, v139
	v_cvt_pk_bf16_f32 v135, v140, v141
	v_cvt_pk_bf16_f32 v136, v142, v143
	v_cvt_pk_bf16_f32 v137, v144, v145
	s_nor_b64 s[38:39], s[44:45], s[38:39]
	s_and_saveexec_b64 s[42:43], s[38:39]
	s_xor_b64 s[38:39], exec, s[42:43]
	s_cbranch_execz .LBB0_2334
	global_store_dwordx4 v[172:173], v[134:137], off offset:2048
.LBB0_2334:
	s_andn2_saveexec_b64 s[38:39], s[38:39]
	s_cbranch_execz .LBB0_2336
	global_store_dwordx4 v[172:173], v[134:137], off offset:2048 sc1
	s_nop 1
.LBB0_2336:
	s_or_b64 exec, exec, s[38:39]
	s_waitcnt vmcnt(0)
	v_lshlrev_b32_e32 v136, 16, v130
	v_and_b32_e32 v137, 0xffff0000, v130
	v_lshlrev_b32_e32 v130, 16, v131
	v_and_b32_e32 v131, 0xffff0000, v131
	v_pk_fma_f32 v[146:147], v[8:9], 0.5, v[130:131] op_sel_hi:[1,0,1]
	v_lshlrev_b32_e32 v130, 16, v132
	v_and_b32_e32 v131, 0xffff0000, v132
	v_pk_fma_f32 v[148:149], v[2:3], 0.5, v[130:131] op_sel_hi:[1,0,1]
	v_lshlrev_b32_e32 v130, 16, v133
	v_and_b32_e32 v131, 0xffff0000, v133
	v_pk_fma_f32 v[136:137], v[6:7], 0.5, v[136:137] op_sel_hi:[1,0,1]
	v_pk_fma_f32 v[150:151], v[4:5], 0.5, v[130:131] op_sel_hi:[1,0,1]
	v_cvt_pk_bf16_f32 v130, v136, v137
	v_cvt_pk_bf16_f32 v131, v146, v147
	v_cvt_pk_bf16_f32 v132, v148, v149
	v_cvt_pk_bf16_f32 v133, v150, v151
	s_and_b64 vcc, exec, s[12:13]
	s_mov_b64 s[38:39], -1
	s_cbranch_vccnz .LBB0_2338
	s_mov_b64 s[38:39], 0
	global_store_dwordx4 v[174:175], v[130:133], off offset:2048
.LBB0_2338:
	s_andn2_b64 vcc, exec, s[38:39]
	s_cbranch_vccnz .LBB0_2340
	global_store_dwordx4 v[174:175], v[130:133], off offset:2048 sc1
	s_nop 1

	.amdhsa_kernel _Z10fwd_kernel4Args
		.amdhsa_group_segment_fixed_size 0
		.amdhsa_private_segment_fixed_size 0
		.amdhsa_kernarg_size 536
		.amdhsa_user_sgpr_count 2
		.amdhsa_user_sgpr_dispatch_ptr 0
		.amdhsa_user_sgpr_queue_ptr 0
		.amdhsa_user_sgpr_kernarg_segment_ptr 1
		.amdhsa_user_sgpr_dispatch_id 0
		.amdhsa_user_sgpr_kernarg_preload_length 0
		.amdhsa_user_sgpr_kernarg_preload_offset 0
		.amdhsa_user_sgpr_private_segment_size 0
		.amdhsa_uses_dynamic_stack 0
		.amdhsa_enable_private_segment 0
		.amdhsa_system_sgpr_workgroup_id_x 1
		.amdhsa_system_sgpr_workgroup_id_y 0
		.amdhsa_system_sgpr_workgroup_id_z 0
		.amdhsa_system_sgpr_workgroup_info 0
		.amdhsa_system_vgpr_workitem_id 0
		.amdhsa_next_free_vgpr 256
		.amdhsa_next_free_sgpr 102
		.amdhsa_accum_offset 256
		.amdhsa_reserve_vcc 1
		.amdhsa_float_round_mode_32 0
		.amdhsa_float_round_mode_16_64 0
		.amdhsa_float_denorm_mode_32 3
		.amdhsa_float_denorm_mode_16_64 3
		.amdhsa_dx10_clamp 1
		.amdhsa_ieee_mode 1
		.amdhsa_fp16_overflow 0
		.amdhsa_tg_split 0
		.amdhsa_exception_fp_ieee_invalid_op 0
		.amdhsa_exception_fp_denorm_src 0
		.amdhsa_exception_fp_ieee_div_zero 0
		.amdhsa_exception_fp_ieee_overflow 0
		.amdhsa_exception_fp_ieee_underflow 0
		.amdhsa_exception_fp_ieee_inexact 0
		.amdhsa_exception_int_div_zero 0
	.end_amdhsa_kernel

amdhsa.kernels:
  - .agpr_count:     0
    .args:
      - .offset:         0
        .size:           280
        .value_kind:     by_value
      - .offset:         280
        .size:           4
        .value_kind:     hidden_block_count_x
      - .offset:         284
        .size:           4
        .value_kind:     hidden_block_count_y
      - .offset:         288
        .size:           4
        .value_kind:     hidden_block_count_z
      - .offset:         292
        .size:           2
        .value_kind:     hidden_group_size_x
      - .offset:         294
        .size:           2
        .value_kind:     hidden_group_size_y
      - .offset:         296
        .size:           2
        .value_kind:     hidden_group_size_z
      - .offset:         298
        .size:           2
        .value_kind:     hidden_remainder_x
      - .offset:         300
        .size:           2
        .value_kind:     hidden_remainder_y
      - .offset:         302
        .size:           2
        .value_kind:     hidden_remainder_z
      - .offset:         320
        .size:           8
        .value_kind:     hidden_global_offset_x
      - .offset:         328
        .size:           8
        .value_kind:     hidden_global_offset_y
      - .offset:         336
        .size:           8
        .value_kind:     hidden_global_offset_z
      - .offset:         344
        .size:           2
        .value_kind:     hidden_grid_dims
      - .offset:         400
        .size:           4
        .value_kind:     hidden_dynamic_lds_size
    .group_segment_fixed_size: 0
    .kernarg_segment_align: 8
    .kernarg_segment_size: 536
    .language:       OpenCL C
    .language_version:
      - 2
      - 0
    .max_flat_workgroup_size: 512
    .name:           _Z10fwd_kernel4Args
    .private_segment_fixed_size: 0
    .sgpr_count:     108
    .sgpr_spill_count: 99
    .symbol:         _Z10fwd_kernel4Args.kd
    .uniform_work_group_size: 1
    .uses_dynamic_stack: false
    .vgpr_count:     256
    .vgpr_spill_count: 0
    .wavefront_size: 64
